# dil loop: next group's LDS round trip (vmcnt wait, K write/readback, V write) issued right after the current group's V transpose reads
# speedup vs baseline: 1.0010x; 1.0010x over previous
; #define LAS __attribute__((address_space(3)))
; #define GAS __attribute__((address_space(1)))
; __device__ __forceinline__ void dil_unit(LAS unsigned char* lds, bf16_t* proj, int seq, int hd, int T0, int rho) {
;     int tid_ = threadIdx.x; asm volatile("" : "+v"(tid_));
;     const int tid = tid_, lane = tid & 63, r32 = lane & 31, hi = lane >> 5, wid = __builtin_amdgcn_readfirstlane(tid >> 6);
;     bf16_t* base = proj + (size_t)seq * SEQ * NIN;
;     LAS unsigned char* wbuf = lds + wid * 4096;
;     const LAS unsigned char* vp = wbuf + ((lane >> 4) & 1) * 32 + (lane & 3) * 8 + (4 * hi + ((lane & 15) >> 2)) * 64;
;     const int P0 = T0 + rho;
;     bf16x8 qr[4];
; #pragma unroll
;     for (int ks = 0; ks < 4; ++ks) qr[ks] = *(const GAS bf16x8*)(base + (size_t)(P0 + 16 * r32) * NIN + PC_LQ + hd * 64 + 16 * ks + 8 * hi);
;     f32x16 o0 = {}, o1 = {}; float l = 0.f;
;     const bool bound = (T0 < 1024) || (T0 >= 15360);
; __device__ __forceinline__ void attn_phase(unsigned char* ws, int l, LAS unsigned char* lds, int G) {
;     ...
;     for (int bu = vb; bu < 1152; bu += G) {
;         const int sh = bu >> 6, rem = bu & 63, T0 = (rem >> 1) * 512, rho = (rem & 1) * 8 + wid;
;         dil_unit(lds, proj, sh / 6, sh % 6, T0, rho);
.LBB0_554:
	s_lshr_b32 s82, s33, 8
	s_mul_i32 s82, s82, 13
	s_add_i32 s82, s82, s33
	s_ashr_i32 s2, s33, 6
	s_mul_hi_i32 s7, s2, 0x2aaaaaab
	s_lshl_b32 s3, s82, 8
	s_lshr_b32 s8, s7, 31
	s_and_b32 s6, s3, 0x3e00
	s_lshl_b32 s3, s82, 3
	s_add_i32 s7, s7, s8
	s_and_b32 s3, s3, 8
	s_mul_i32 s8, s7, 6
	s_add_i32 s3, s3, s64
	s_sub_i32 s8, s2, s8
	s_mul_hi_i32 s2, s7, 0x6000000
	s_mul_i32 s7, s7, 0x6000000
	v_mov_b32_e32 v2, v154
	s_add_u32 s56, s48, s7
	s_addc_u32 s57, s49, s2
	v_and_b32_e32 v105, 31, v2
	s_add_i32 s76, s3, s6
	v_lshl_add_u32 v3, v105, 4, s76
	v_mov_b64_e32 v[0:1], s[56:57]
	s_lshl_b32 s58, s8, 6
	v_bfe_u32 v106, v2, 5, 1
	v_mad_u64_u32 v[0:1], s[2:3], v3, s65, v[0:1]
	s_ashr_i32 s59, s58, 31
	v_lshl_add_u64 v[0:1], s[58:59], 1, v[0:1]
	v_lshlrev_b32_e32 v80, 4, v106
	v_lshl_add_u64 v[0:1], v[0:1], 0, v[80:81]
	global_load_dwordx4 v[48:51], v[0:1], off offset:1280
	global_load_dwordx4 v[52:55], v[0:1], off offset:1312
	global_load_dwordx4 v[56:59], v[0:1], off offset:1344
	global_load_dwordx4 v[60:63], v[0:1], off offset:1376
	v_readfirstlane_b32 s2, v2
	s_lshl_b32 s2, s2, 6
	s_and_b32 s2, s2, 0xfffff000
	v_lshlrev_b32_e32 v0, 1, v2
	v_lshlrev_b32_e32 v104, 3, v2
	v_lshlrev_b32_e32 v107, 2, v106
	v_lshrrev_b32_e32 v1, 2, v2
	v_and_b32_e32 v103, 63, v2
	v_and_b32_e32 v0, 32, v0
	v_and_b32_e32 v98, 24, v104
	v_and_or_b32 v1, v1, 3, v107
	s_add_i32 s77, s2, 0
	v_lshlrev_b32_e32 v108, 6, v1
	v_lshlrev_b32_e32 v1, 3, v106
	v_add3_u32 v109, s77, v0, v98
	s_addk_i32 s6, 0xc400
	v_lshrrev_b32_e32 v110, 2, v103
	v_lshlrev_b32_e32 v0, 4, v103
	s_mov_b64 s[2:3], -1
	s_cmp_gt_u32 s6, 0xffffc7ff
	v_lshlrev_b32_e32 v100, 1, v98
	s_mul_i32 s6, s8, 0x1c00
	v_lshlrev_b32_e32 v82, 1, v1
	v_or_b32_e32 v111, 16, v110
	v_add_u32_e32 v112, s77, v0
	s_cbranch_scc0 .LBB0_558
	s_movk_i32 s100, 0x1800
	s_add_i32 s101, s6, 0x15c00
	s_lshl_b32 s90, s58, 1
	s_add_u32 s82, s56, s90
	s_addc_u32 s83, s57, 0
	s_add_u32 s82, s82, 0x1200
	s_addc_u32 s83, s83, 0
	s_sub_i32 s90, s76, 64
	s_mul_i32 s90, s90, 0x1800
	s_add_u32 s84, s82, s90
	s_addc_u32 s85, s83, 0
	s_sub_i32 s90, s76, 256
	s_mul_i32 s90, s90, 0x1800
	s_add_u32 s86, s82, s90
	s_addc_u32 s87, s83, 0
	s_sub_i32 s90, s76, 1024
	s_mul_i32 s90, s90, 0x1800
	s_add_u32 s88, s82, s90
	s_addc_u32 s89, s83, 0
	v_lshlrev_b32_e32 v153, 1, v98
	v_mad_u32_u24 v80, v105, s100, v82
	v_mad_u32_u24 v100, v110, s100, v153
	v_add_u32_e32 v149, 0x18000, v100
	v_lshlrev_b32_e32 v83, 2, v105
	v_mad_u32_u24 v83, v83, s100, v82
	v_lshlrev_b32_e32 v101, 2, v110
	v_mad_u32_u24 v101, v101, s100, v153
	v_add_u32_e32 v150, 0x60000, v101
	v_lshlrev_b32_e32 v99, 4, v105
	v_mad_u32_u24 v99, v99, s100, v82
	v_lshlrev_b32_e32 v148, 4, v110
	v_mad_u32_u24 v148, v148, s100, v153
	v_add_u32_e32 v151, 0x180000, v148
	v_lshrrev_b32_e32 v249, 3, v103
	v_and_b32_e32 v250, 7, v103
	v_lshlrev_b32_e32 v250, 4, v250
	v_add_u32_e32 v235, 0, v249
	v_mad_u32_u24 v235, v235, s100, v250
	v_add_u32_e32 v236, 8, v249
	v_mad_u32_u24 v236, v236, s100, v250
	v_add_u32_e32 v237, 16, v249
	v_mad_u32_u24 v237, v237, s100, v250
	v_add_u32_e32 v238, 24, v249
	v_mad_u32_u24 v238, v238, s100, v250
	v_add_u32_e32 v239, 0, v249
	v_lshlrev_b32_e32 v239, 2, v239
	v_mad_u32_u24 v239, v239, s100, v250
	v_add_u32_e32 v240, 8, v249
	v_lshlrev_b32_e32 v240, 2, v240
	v_mad_u32_u24 v240, v240, s100, v250
	v_add_u32_e32 v241, 16, v249
	v_lshlrev_b32_e32 v241, 2, v241
	v_mad_u32_u24 v241, v241, s100, v250
	v_add_u32_e32 v242, 24, v249
	v_lshlrev_b32_e32 v242, 2, v242
	v_mad_u32_u24 v242, v242, s100, v250
	v_add_u32_e32 v243, 0, v249
	v_lshlrev_b32_e32 v243, 4, v243
	v_mad_u32_u24 v243, v243, s100, v250
	v_add_u32_e32 v244, 8, v249
	v_lshlrev_b32_e32 v244, 4, v244
	v_mad_u32_u24 v244, v244, s100, v250
	v_add_u32_e32 v245, 16, v249
	v_lshlrev_b32_e32 v245, 4, v245
	v_mad_u32_u24 v245, v245, s100, v250
	v_add_u32_e32 v246, 24, v249
	v_lshlrev_b32_e32 v246, 4, v246
	v_mad_u32_u24 v246, v246, s100, v250
	v_and_b32_e32 v247, 7, v249
	v_lshlrev_b32_e32 v247, 4, v247
	v_xor_b32_e32 v247, v247, v112
	v_and_b32_e32 v153, 7, v105
	v_or_b32_e32 v248, 0, v106
	v_xor_b32_e32 v248, v248, v153
	v_lshlrev_b32_e32 v248, 4, v248
	v_lshl_add_u32 v248, v105, 7, v248
	v_add_u32_e32 v248, s77, v248
	v_or_b32_e32 v249, 2, v106
	v_xor_b32_e32 v249, v249, v153
	v_lshlrev_b32_e32 v249, 4, v249
	v_lshl_add_u32 v249, v105, 7, v249
	v_add_u32_e32 v249, s77, v249
	v_or_b32_e32 v250, 4, v106
	v_xor_b32_e32 v250, v250, v153
	v_lshlrev_b32_e32 v250, 4, v250
	v_lshl_add_u32 v250, v105, 7, v250
	v_add_u32_e32 v250, s77, v250
	v_or_b32_e32 v251, 6, v106
	v_xor_b32_e32 v251, v251, v153
	v_lshlrev_b32_e32 v251, 4, v251
	v_lshl_add_u32 v251, v105, 7, v251
	v_add_u32_e32 v251, s77, v251
	v_lshlrev_b32_e32 v153, 1, v98
	v_mul_u32_u24_e32 v228, 17, v105
	v_sub_u32_e32 v228, v107, v228
	s_mul_i32 s90, s58, 153
	s_lshr_b32 s90, s90, 1
	s_add_i32 s90, s90, 34876
	v_lshl_add_u32 v228, v228, 2, s90
	v_lshlrev_b32_e32 v229, 2, v105
	v_sub_u32_e32 v229, v107, v229
	s_add_i32 s90, s101, 5104
	v_lshl_add_u32 v229, v229, 2, s90
	v_sub_u32_e32 v230, v107, v105
	s_add_i32 s90, s101, 6364
	v_lshl_add_u32 v230, v230, 2, s90
	v_add_u32_e32 v231, v109, v108
	v_mov_b64_e32 v[232:233], 0
	v_mov_b64_e32 v[0:1], 0
	v_mov_b64_e32 v[2:3], 0
	v_mov_b64_e32 v[4:5], 0
	v_mov_b64_e32 v[6:7], 0
	v_mov_b64_e32 v[8:9], 0
	v_mov_b64_e32 v[10:11], 0
	v_mov_b64_e32 v[12:13], 0
	v_mov_b64_e32 v[14:15], 0
	v_mov_b64_e32 v[16:17], 0
	v_mov_b64_e32 v[18:19], 0
	v_mov_b64_e32 v[20:21], 0
	v_mov_b64_e32 v[22:23], 0
	v_mov_b64_e32 v[24:25], 0
	v_mov_b64_e32 v[26:27], 0
	v_mov_b64_e32 v[28:29], 0
	v_mov_b64_e32 v[30:31], 0
	global_load_dwordx4 v[116:119], v235, s[84:85]
	global_load_dwordx4 v[120:123], v236, s[84:85]
	global_load_dwordx4 v[124:127], v237, s[84:85]
	global_load_dwordx4 v[128:131], v238, s[84:85]
	global_load_dwordx4 v[132:135], v100, s[84:85] offset:768
	global_load_dwordx4 v[136:139], v149, s[84:85] offset:768
	global_load_dwordx4 v[140:143], v100, s[84:85] offset:832
	global_load_dwordx4 v[144:147], v149, s[84:85] offset:832
	s_add_u32 s84, s84, 0x30000
	s_addc_u32 s85, s85, 0
	global_load_dwordx4 v[156:159], v235, s[84:85]
	global_load_dwordx4 v[160:163], v236, s[84:85]
	global_load_dwordx4 v[164:167], v237, s[84:85]
	global_load_dwordx4 v[168:171], v238, s[84:85]
	global_load_dwordx4 v[172:175], v100, s[84:85] offset:768
	global_load_dwordx4 v[176:179], v149, s[84:85] offset:768
	global_load_dwordx4 v[180:183], v100, s[84:85] offset:832
	global_load_dwordx4 v[184:187], v149, s[84:85] offset:832
	s_add_u32 s84, s84, 0x30000
	s_addc_u32 s85, s85, 0
	global_load_dwordx4 v[188:191], v235, s[84:85]
	global_load_dwordx4 v[192:195], v236, s[84:85]
	global_load_dwordx4 v[196:199], v237, s[84:85]
	global_load_dwordx4 v[200:203], v238, s[84:85]
	global_load_dwordx4 v[204:207], v100, s[84:85] offset:768
	global_load_dwordx4 v[208:211], v149, s[84:85] offset:768
	global_load_dwordx4 v[212:215], v100, s[84:85] offset:832
	global_load_dwordx4 v[216:219], v149, s[84:85] offset:832
	s_add_u32 s84, s84, 0x30000
	s_addc_u32 s85, s85, 0
	s_waitcnt vmcnt(16)
	ds_write_b128 v247, v[116:119]
	ds_write_b128 v247, v[120:123] offset:1024
	ds_write_b128 v247, v[124:127] offset:2048
	ds_write_b128 v247, v[128:131] offset:3072
	ds_read_b128 v[116:119], v248
	ds_read_b128 v[120:123], v249
	ds_read_b128 v[124:127], v250
	ds_read_b128 v[128:131], v251
	ds_write_b128 v112, v[132:135]
	ds_write_b128 v112, v[136:139] offset:1024
	ds_write_b128 v112, v[140:143] offset:2048
	ds_write_b128 v112, v[144:147] offset:3072
	v_mov_b32_e32 v115, v228
	ds_read2_b32 v[32:33], v115 offset0:0 offset1:1
	ds_read2_b32 v[34:35], v115 offset0:2 offset1:3
	ds_read2_b32 v[36:37], v115 offset0:8 offset1:9
	ds_read2_b32 v[38:39], v115 offset0:10 offset1:11
	ds_read2_b32 v[40:41], v115 offset0:17 offset1:18
	ds_read2_b32 v[42:43], v115 offset0:19 offset1:20
	ds_read2_b32 v[44:45], v115 offset0:25 offset1:26
	ds_read2_b32 v[46:47], v115 offset0:27 offset1:28
	s_waitcnt lgkmcnt(0)
	v_mfma_f32_32x32x16_bf16 v[32:47], v[116:119], v[48:51], v[32:47]
	ds_read_b64_tr_b16 v[72:73], v231
	ds_read_b64_tr_b16 v[74:75], v231 offset:512
	ds_read_b64_tr_b16 v[76:77], v231 offset:2048
	ds_read_b64_tr_b16 v[78:79], v231 offset:2560
	ds_read_b64_tr_b16 v[220:221], v231 offset:1024
	ds_read_b64_tr_b16 v[222:223], v231 offset:1536
	ds_read_b64_tr_b16 v[224:225], v231 offset:3072
	ds_read_b64_tr_b16 v[226:227], v231 offset:3584
	s_waitcnt vmcnt(8)
	ds_write_b128 v247, v[156:159]
	ds_write_b128 v247, v[160:163] offset:1024
	ds_write_b128 v247, v[164:167] offset:2048
	ds_write_b128 v247, v[168:171] offset:3072
	ds_read_b128 v[156:159], v248
	ds_read_b128 v[160:163], v249
	ds_read_b128 v[164:167], v250
	ds_read_b128 v[168:171], v251
	ds_write_b128 v112, v[172:175]
	ds_write_b128 v112, v[176:179] offset:1024
	ds_write_b128 v112, v[180:183] offset:2048
	ds_write_b128 v112, v[184:187] offset:3072
	v_mfma_f32_32x32x16_bf16 v[32:47], v[120:123], v[52:55], v[32:47]
	v_mfma_f32_32x32x16_bf16 v[32:47], v[124:127], v[56:59], v[32:47]
	v_mfma_f32_32x32x16_bf16 v[32:47], v[128:131], v[60:63], v[32:47]
	s_nop 11
	v_exp_f32_e32 v32, v32
	v_exp_f32_e32 v33, v33
	v_exp_f32_e32 v34, v34
	v_exp_f32_e32 v35, v35
	v_exp_f32_e32 v36, v36
	v_exp_f32_e32 v37, v37
	v_exp_f32_e32 v38, v38
	v_exp_f32_e32 v39, v39
	v_exp_f32_e32 v40, v40
	v_exp_f32_e32 v41, v41
	v_exp_f32_e32 v42, v42
	v_exp_f32_e32 v43, v43
	v_exp_f32_e32 v44, v44
	v_exp_f32_e32 v45, v45
	v_exp_f32_e32 v46, v46
	v_exp_f32_e32 v47, v47
	v_cvt_pk_bf16_f32 v64, v32, v33
	v_cvt_pk_bf16_f32 v65, v34, v35
	v_cvt_pk_bf16_f32 v66, v36, v37
	v_cvt_pk_bf16_f32 v67, v38, v39
	v_cvt_pk_bf16_f32 v68, v40, v41
	v_cvt_pk_bf16_f32 v69, v42, v43
	v_cvt_pk_bf16_f32 v70, v44, v45
	v_cvt_pk_bf16_f32 v71, v46, v47
	v_pk_add_f32 v[232:233], v[232:233], v[32:33]
	v_pk_add_f32 v[232:233], v[232:233], v[34:35]
	v_pk_add_f32 v[232:233], v[232:233], v[36:37]
	v_pk_add_f32 v[232:233], v[232:233], v[38:39]
	v_pk_add_f32 v[232:233], v[232:233], v[40:41]
	v_pk_add_f32 v[232:233], v[232:233], v[42:43]
	v_pk_add_f32 v[232:233], v[232:233], v[44:45]
	v_pk_add_f32 v[232:233], v[232:233], v[46:47]
	s_waitcnt lgkmcnt(12)
	v_mfma_f32_32x32x16_bf16 v[0:15], v[64:67], v[72:75], v[0:15]
	v_mfma_f32_32x32x16_bf16 v[16:31], v[64:67], v[76:79], v[16:31]
	v_mfma_f32_32x32x16_bf16 v[0:15], v[68:71], v[220:223], v[0:15]
	v_mfma_f32_32x32x16_bf16 v[16:31], v[68:71], v[224:227], v[16:31]
	global_load_dwordx4 v[116:119], v235, s[84:85]
	global_load_dwordx4 v[120:123], v236, s[84:85]
	global_load_dwordx4 v[124:127], v237, s[84:85]
	global_load_dwordx4 v[128:131], v238, s[84:85]
	global_load_dwordx4 v[132:135], v100, s[84:85] offset:768
	global_load_dwordx4 v[136:139], v149, s[84:85] offset:768
	global_load_dwordx4 v[140:143], v100, s[84:85] offset:832
	global_load_dwordx4 v[144:147], v149, s[84:85] offset:832
	s_add_u32 s84, s84, 0x30000
	s_addc_u32 s85, s85, 0
	ds_read2_b32 v[32:33], v115 offset0:34 offset1:35
	ds_read2_b32 v[34:35], v115 offset0:36 offset1:37
	ds_read2_b32 v[36:37], v115 offset0:42 offset1:43
	ds_read2_b32 v[38:39], v115 offset0:44 offset1:45
	ds_read2_b32 v[40:41], v115 offset0:51 offset1:52
	ds_read2_b32 v[42:43], v115 offset0:53 offset1:54
	ds_read2_b32 v[44:45], v115 offset0:59 offset1:60
	ds_read2_b32 v[46:47], v115 offset0:61 offset1:62
	s_waitcnt lgkmcnt(0)
	v_mfma_f32_32x32x16_bf16 v[32:47], v[156:159], v[48:51], v[32:47]
	ds_read_b64_tr_b16 v[72:73], v231
	ds_read_b64_tr_b16 v[74:75], v231 offset:512
	ds_read_b64_tr_b16 v[76:77], v231 offset:2048
	ds_read_b64_tr_b16 v[78:79], v231 offset:2560
	ds_read_b64_tr_b16 v[220:221], v231 offset:1024
	ds_read_b64_tr_b16 v[222:223], v231 offset:1536
	ds_read_b64_tr_b16 v[224:225], v231 offset:3072
	ds_read_b64_tr_b16 v[226:227], v231 offset:3584
	s_waitcnt vmcnt(8)
	ds_write_b128 v247, v[188:191]
	ds_write_b128 v247, v[192:195] offset:1024
	ds_write_b128 v247, v[196:199] offset:2048
	ds_write_b128 v247, v[200:203] offset:3072
	ds_read_b128 v[188:191], v248
	ds_read_b128 v[192:195], v249
	ds_read_b128 v[196:199], v250
	ds_read_b128 v[200:203], v251
	ds_write_b128 v112, v[204:207]
	ds_write_b128 v112, v[208:211] offset:1024
	ds_write_b128 v112, v[212:215] offset:2048
	ds_write_b128 v112, v[216:219] offset:3072
	v_mfma_f32_32x32x16_bf16 v[32:47], v[160:163], v[52:55], v[32:47]
	v_mfma_f32_32x32x16_bf16 v[32:47], v[164:167], v[56:59], v[32:47]
	v_mfma_f32_32x32x16_bf16 v[32:47], v[168:171], v[60:63], v[32:47]
	s_nop 11
	v_exp_f32_e32 v32, v32
	v_exp_f32_e32 v33, v33
	v_exp_f32_e32 v34, v34
	v_exp_f32_e32 v35, v35
	v_exp_f32_e32 v36, v36
	v_exp_f32_e32 v37, v37
	v_exp_f32_e32 v38, v38
	v_exp_f32_e32 v39, v39
	v_exp_f32_e32 v40, v40
	v_exp_f32_e32 v41, v41
	v_exp_f32_e32 v42, v42
	v_exp_f32_e32 v43, v43
	v_exp_f32_e32 v44, v44
	v_exp_f32_e32 v45, v45
	v_exp_f32_e32 v46, v46
	v_exp_f32_e32 v47, v47
	v_cvt_pk_bf16_f32 v64, v32, v33
	v_cvt_pk_bf16_f32 v65, v34, v35
	v_cvt_pk_bf16_f32 v66, v36, v37
	v_cvt_pk_bf16_f32 v67, v38, v39
	v_cvt_pk_bf16_f32 v68, v40, v41
	v_cvt_pk_bf16_f32 v69, v42, v43
	v_cvt_pk_bf16_f32 v70, v44, v45
	v_cvt_pk_bf16_f32 v71, v46, v47
	v_pk_add_f32 v[232:233], v[232:233], v[32:33]
	v_pk_add_f32 v[232:233], v[232:233], v[34:35]
	v_pk_add_f32 v[232:233], v[232:233], v[36:37]
	v_pk_add_f32 v[232:233], v[232:233], v[38:39]
	v_pk_add_f32 v[232:233], v[232:233], v[40:41]
	v_pk_add_f32 v[232:233], v[232:233], v[42:43]
	v_pk_add_f32 v[232:233], v[232:233], v[44:45]
	v_pk_add_f32 v[232:233], v[232:233], v[46:47]
	s_waitcnt lgkmcnt(12)
	v_mfma_f32_32x32x16_bf16 v[0:15], v[64:67], v[72:75], v[0:15]
	v_mfma_f32_32x32x16_bf16 v[16:31], v[64:67], v[76:79], v[16:31]
	v_mfma_f32_32x32x16_bf16 v[0:15], v[68:71], v[220:223], v[0:15]
	v_mfma_f32_32x32x16_bf16 v[16:31], v[68:71], v[224:227], v[16:31]
	global_load_dwordx4 v[156:159], v235, s[84:85]
	global_load_dwordx4 v[160:163], v236, s[84:85]
	global_load_dwordx4 v[164:167], v237, s[84:85]
	global_load_dwordx4 v[168:171], v238, s[84:85]
	global_load_dwordx4 v[172:175], v100, s[84:85] offset:768
	global_load_dwordx4 v[176:179], v149, s[84:85] offset:768
	global_load_dwordx4 v[180:183], v100, s[84:85] offset:832
	global_load_dwordx4 v[184:187], v149, s[84:85] offset:832
	s_add_u32 s84, s84, 0x30000
	s_addc_u32 s85, s85, 0
	ds_read2_b32 v[32:33], v115 offset0:68 offset1:69
	ds_read2_b32 v[34:35], v115 offset0:70 offset1:71
	ds_read2_b32 v[36:37], v115 offset0:76 offset1:77
	ds_read2_b32 v[38:39], v115 offset0:78 offset1:79
	ds_read2_b32 v[40:41], v115 offset0:85 offset1:86
	ds_read2_b32 v[42:43], v115 offset0:87 offset1:88
	ds_read2_b32 v[44:45], v115 offset0:93 offset1:94
	ds_read2_b32 v[46:47], v115 offset0:95 offset1:96
	s_waitcnt lgkmcnt(0)
	v_mfma_f32_32x32x16_bf16 v[32:47], v[188:191], v[48:51], v[32:47]
	ds_read_b64_tr_b16 v[72:73], v231
	ds_read_b64_tr_b16 v[74:75], v231 offset:512
	ds_read_b64_tr_b16 v[76:77], v231 offset:2048
	ds_read_b64_tr_b16 v[78:79], v231 offset:2560
	ds_read_b64_tr_b16 v[220:221], v231 offset:1024
	ds_read_b64_tr_b16 v[222:223], v231 offset:1536
	ds_read_b64_tr_b16 v[224:225], v231 offset:3072
	ds_read_b64_tr_b16 v[226:227], v231 offset:3584
	s_waitcnt vmcnt(8)
	ds_write_b128 v247, v[116:119]
	ds_write_b128 v247, v[120:123] offset:1024
	ds_write_b128 v247, v[124:127] offset:2048
	ds_write_b128 v247, v[128:131] offset:3072
	ds_read_b128 v[116:119], v248
	ds_read_b128 v[120:123], v249
	ds_read_b128 v[124:127], v250
	ds_read_b128 v[128:131], v251
	ds_write_b128 v112, v[132:135]
	ds_write_b128 v112, v[136:139] offset:1024
	ds_write_b128 v112, v[140:143] offset:2048
	ds_write_b128 v112, v[144:147] offset:3072
	v_mfma_f32_32x32x16_bf16 v[32:47], v[192:195], v[52:55], v[32:47]
	v_mfma_f32_32x32x16_bf16 v[32:47], v[196:199], v[56:59], v[32:47]
	v_mfma_f32_32x32x16_bf16 v[32:47], v[200:203], v[60:63], v[32:47]
	s_nop 11
	v_exp_f32_e32 v32, v32
	v_exp_f32_e32 v33, v33
	v_exp_f32_e32 v34, v34
	v_exp_f32_e32 v35, v35
	v_exp_f32_e32 v36, v36
	v_exp_f32_e32 v37, v37
	v_exp_f32_e32 v38, v38
	v_exp_f32_e32 v39, v39
	v_exp_f32_e32 v40, v40
	v_exp_f32_e32 v41, v41
	v_exp_f32_e32 v42, v42
	v_exp_f32_e32 v43, v43
	v_exp_f32_e32 v44, v44
	v_exp_f32_e32 v45, v45
	v_exp_f32_e32 v46, v46
	v_exp_f32_e32 v47, v47
	v_cvt_pk_bf16_f32 v64, v32, v33
	v_cvt_pk_bf16_f32 v65, v34, v35
	v_cvt_pk_bf16_f32 v66, v36, v37
	v_cvt_pk_bf16_f32 v67, v38, v39
	v_cvt_pk_bf16_f32 v68, v40, v41
	v_cvt_pk_bf16_f32 v69, v42, v43
	v_cvt_pk_bf16_f32 v70, v44, v45
	v_cvt_pk_bf16_f32 v71, v46, v47
	v_pk_add_f32 v[232:233], v[232:233], v[32:33]
	v_pk_add_f32 v[232:233], v[232:233], v[34:35]
	v_pk_add_f32 v[232:233], v[232:233], v[36:37]
	v_pk_add_f32 v[232:233], v[232:233], v[38:39]
	v_pk_add_f32 v[232:233], v[232:233], v[40:41]
	v_pk_add_f32 v[232:233], v[232:233], v[42:43]
	v_pk_add_f32 v[232:233], v[232:233], v[44:45]
	v_pk_add_f32 v[232:233], v[232:233], v[46:47]
	s_waitcnt lgkmcnt(12)
	v_mfma_f32_32x32x16_bf16 v[0:15], v[64:67], v[72:75], v[0:15]
	v_mfma_f32_32x32x16_bf16 v[16:31], v[64:67], v[76:79], v[16:31]
	v_mfma_f32_32x32x16_bf16 v[0:15], v[68:71], v[220:223], v[0:15]
	v_mfma_f32_32x32x16_bf16 v[16:31], v[68:71], v[224:227], v[16:31]
	global_load_dwordx4 v[188:191], v235, s[84:85]
	global_load_dwordx4 v[192:195], v236, s[84:85]
	global_load_dwordx4 v[196:199], v237, s[84:85]
	global_load_dwordx4 v[200:203], v238, s[84:85]
	global_load_dwordx4 v[204:207], v100, s[84:85] offset:768
	global_load_dwordx4 v[208:211], v149, s[84:85] offset:768
	global_load_dwordx4 v[212:215], v100, s[84:85] offset:832
	global_load_dwordx4 v[216:219], v149, s[84:85] offset:832
	s_add_u32 s84, s84, 0x30000
	s_addc_u32 s85, s85, 0
	ds_read2_b32 v[32:33], v115 offset0:102 offset1:103
	ds_read2_b32 v[34:35], v115 offset0:104 offset1:105
	ds_read2_b32 v[36:37], v115 offset0:110 offset1:111
	ds_read2_b32 v[38:39], v115 offset0:112 offset1:113
	ds_read2_b32 v[40:41], v115 offset0:119 offset1:120
	ds_read2_b32 v[42:43], v115 offset0:121 offset1:122
	ds_read2_b32 v[44:45], v115 offset0:127 offset1:128
	ds_read2_b32 v[46:47], v115 offset0:129 offset1:130
	s_waitcnt lgkmcnt(0)
	v_mfma_f32_32x32x16_bf16 v[32:47], v[116:119], v[48:51], v[32:47]
	ds_read_b64_tr_b16 v[72:73], v231
	ds_read_b64_tr_b16 v[74:75], v231 offset:512
	ds_read_b64_tr_b16 v[76:77], v231 offset:2048
	ds_read_b64_tr_b16 v[78:79], v231 offset:2560
	ds_read_b64_tr_b16 v[220:221], v231 offset:1024
	ds_read_b64_tr_b16 v[222:223], v231 offset:1536
	ds_read_b64_tr_b16 v[224:225], v231 offset:3072
	ds_read_b64_tr_b16 v[226:227], v231 offset:3584
	s_waitcnt vmcnt(8)
	ds_write_b128 v247, v[156:159]
	ds_write_b128 v247, v[160:163] offset:1024
	ds_write_b128 v247, v[164:167] offset:2048
	ds_write_b128 v247, v[168:171] offset:3072
	ds_read_b128 v[156:159], v248
	ds_read_b128 v[160:163], v249
	ds_read_b128 v[164:167], v250
	ds_read_b128 v[168:171], v251
	ds_write_b128 v112, v[172:175]
	ds_write_b128 v112, v[176:179] offset:1024
	ds_write_b128 v112, v[180:183] offset:2048
	ds_write_b128 v112, v[184:187] offset:3072
	v_mfma_f32_32x32x16_bf16 v[32:47], v[120:123], v[52:55], v[32:47]
	v_mfma_f32_32x32x16_bf16 v[32:47], v[124:127], v[56:59], v[32:47]
	v_mfma_f32_32x32x16_bf16 v[32:47], v[128:131], v[60:63], v[32:47]
	s_nop 11
	v_exp_f32_e32 v32, v32
	v_exp_f32_e32 v33, v33
	v_exp_f32_e32 v34, v34
	v_exp_f32_e32 v35, v35
	v_exp_f32_e32 v36, v36
	v_exp_f32_e32 v37, v37
	v_exp_f32_e32 v38, v38
	v_exp_f32_e32 v39, v39
	v_exp_f32_e32 v40, v40
	v_exp_f32_e32 v41, v41
	v_exp_f32_e32 v42, v42
	v_exp_f32_e32 v43, v43
	v_exp_f32_e32 v44, v44
	v_exp_f32_e32 v45, v45
	v_exp_f32_e32 v46, v46
	v_exp_f32_e32 v47, v47
	v_cvt_pk_bf16_f32 v64, v32, v33
	v_cvt_pk_bf16_f32 v65, v34, v35
	v_cvt_pk_bf16_f32 v66, v36, v37
	v_cvt_pk_bf16_f32 v67, v38, v39
	v_cvt_pk_bf16_f32 v68, v40, v41
	v_cvt_pk_bf16_f32 v69, v42, v43
	v_cvt_pk_bf16_f32 v70, v44, v45
	v_cvt_pk_bf16_f32 v71, v46, v47
	v_pk_add_f32 v[232:233], v[232:233], v[32:33]
	v_pk_add_f32 v[232:233], v[232:233], v[34:35]
	v_pk_add_f32 v[232:233], v[232:233], v[36:37]
	v_pk_add_f32 v[232:233], v[232:233], v[38:39]
	v_pk_add_f32 v[232:233], v[232:233], v[40:41]
	v_pk_add_f32 v[232:233], v[232:233], v[42:43]
	v_pk_add_f32 v[232:233], v[232:233], v[44:45]
	v_pk_add_f32 v[232:233], v[232:233], v[46:47]
	s_waitcnt lgkmcnt(12)
	v_mfma_f32_32x32x16_bf16 v[0:15], v[64:67], v[72:75], v[0:15]
	v_mfma_f32_32x32x16_bf16 v[16:31], v[64:67], v[76:79], v[16:31]
	v_mfma_f32_32x32x16_bf16 v[0:15], v[68:71], v[220:223], v[0:15]
	v_mfma_f32_32x32x16_bf16 v[16:31], v[68:71], v[224:227], v[16:31]
	global_load_dwordx4 v[116:119], v235, s[84:85]
	global_load_dwordx4 v[120:123], v236, s[84:85]
	global_load_dwordx4 v[124:127], v237, s[84:85]
	global_load_dwordx4 v[128:131], v238, s[84:85]
	global_load_dwordx4 v[132:135], v100, s[84:85] offset:768
	global_load_dwordx4 v[136:139], v149, s[84:85] offset:768
	global_load_dwordx4 v[140:143], v100, s[84:85] offset:832
	global_load_dwordx4 v[144:147], v149, s[84:85] offset:832
	s_add_u32 s84, s84, 0x30000
	s_addc_u32 s85, s85, 0
	ds_read2_b32 v[32:33], v115 offset0:136 offset1:137
	ds_read2_b32 v[34:35], v115 offset0:138 offset1:139
	ds_read2_b32 v[36:37], v115 offset0:144 offset1:145
	ds_read2_b32 v[38:39], v115 offset0:146 offset1:147
	ds_read2_b32 v[40:41], v115 offset0:153 offset1:154
	ds_read2_b32 v[42:43], v115 offset0:155 offset1:156
	ds_read2_b32 v[44:45], v115 offset0:161 offset1:162
	ds_read2_b32 v[46:47], v115 offset0:163 offset1:164
	s_waitcnt lgkmcnt(0)
	v_mfma_f32_32x32x16_bf16 v[32:47], v[156:159], v[48:51], v[32:47]
	ds_read_b64_tr_b16 v[72:73], v231
	ds_read_b64_tr_b16 v[74:75], v231 offset:512
	ds_read_b64_tr_b16 v[76:77], v231 offset:2048
	ds_read_b64_tr_b16 v[78:79], v231 offset:2560
	ds_read_b64_tr_b16 v[220:221], v231 offset:1024
	ds_read_b64_tr_b16 v[222:223], v231 offset:1536
	ds_read_b64_tr_b16 v[224:225], v231 offset:3072
	ds_read_b64_tr_b16 v[226:227], v231 offset:3584
	s_waitcnt vmcnt(8)
	ds_write_b128 v247, v[188:191]
	ds_write_b128 v247, v[192:195] offset:1024
	ds_write_b128 v247, v[196:199] offset:2048
	ds_write_b128 v247, v[200:203] offset:3072
	ds_read_b128 v[188:191], v248
	ds_read_b128 v[192:195], v249
	ds_read_b128 v[196:199], v250
	ds_read_b128 v[200:203], v251
	ds_write_b128 v112, v[204:207]
	ds_write_b128 v112, v[208:211] offset:1024
	ds_write_b128 v112, v[212:215] offset:2048
	ds_write_b128 v112, v[216:219] offset:3072
	v_mfma_f32_32x32x16_bf16 v[32:47], v[160:163], v[52:55], v[32:47]
	v_mfma_f32_32x32x16_bf16 v[32:47], v[164:167], v[56:59], v[32:47]
	v_mfma_f32_32x32x16_bf16 v[32:47], v[168:171], v[60:63], v[32:47]
	s_nop 11
	v_exp_f32_e32 v32, v32
	v_exp_f32_e32 v33, v33
	v_exp_f32_e32 v34, v34
	v_exp_f32_e32 v35, v35
	v_exp_f32_e32 v36, v36
	v_exp_f32_e32 v37, v37
	v_exp_f32_e32 v38, v38
	v_exp_f32_e32 v39, v39
	v_exp_f32_e32 v40, v40
	v_exp_f32_e32 v41, v41
	v_exp_f32_e32 v42, v42
	v_exp_f32_e32 v43, v43
	v_exp_f32_e32 v44, v44
	v_exp_f32_e32 v45, v45
	v_exp_f32_e32 v46, v46
	v_exp_f32_e32 v47, v47
	v_cvt_pk_bf16_f32 v64, v32, v33
	v_cvt_pk_bf16_f32 v65, v34, v35
	v_cvt_pk_bf16_f32 v66, v36, v37
	v_cvt_pk_bf16_f32 v67, v38, v39
	v_cvt_pk_bf16_f32 v68, v40, v41
	v_cvt_pk_bf16_f32 v69, v42, v43
	v_cvt_pk_bf16_f32 v70, v44, v45
	v_cvt_pk_bf16_f32 v71, v46, v47
	v_pk_add_f32 v[232:233], v[232:233], v[32:33]
	v_pk_add_f32 v[232:233], v[232:233], v[34:35]
	v_pk_add_f32 v[232:233], v[232:233], v[36:37]
	v_pk_add_f32 v[232:233], v[232:233], v[38:39]
	v_pk_add_f32 v[232:233], v[232:233], v[40:41]
	v_pk_add_f32 v[232:233], v[232:233], v[42:43]
	v_pk_add_f32 v[232:233], v[232:233], v[44:45]
	v_pk_add_f32 v[232:233], v[232:233], v[46:47]
	s_waitcnt lgkmcnt(12)
	v_mfma_f32_32x32x16_bf16 v[0:15], v[64:67], v[72:75], v[0:15]
	v_mfma_f32_32x32x16_bf16 v[16:31], v[64:67], v[76:79], v[16:31]
	v_mfma_f32_32x32x16_bf16 v[0:15], v[68:71], v[220:223], v[0:15]
	v_mfma_f32_32x32x16_bf16 v[16:31], v[68:71], v[224:227], v[16:31]
	global_load_dwordx4 v[156:159], v235, s[84:85]
	global_load_dwordx4 v[160:163], v236, s[84:85]
	global_load_dwordx4 v[164:167], v237, s[84:85]
	global_load_dwordx4 v[168:171], v238, s[84:85]
	global_load_dwordx4 v[172:175], v100, s[84:85] offset:768
	global_load_dwordx4 v[176:179], v149, s[84:85] offset:768
	global_load_dwordx4 v[180:183], v100, s[84:85] offset:832
	global_load_dwordx4 v[184:187], v149, s[84:85] offset:832
	s_add_u32 s84, s84, 0x30000
	s_addc_u32 s85, s85, 0
	ds_read2_b32 v[32:33], v115 offset0:170 offset1:171
	ds_read2_b32 v[34:35], v115 offset0:172 offset1:173
	ds_read2_b32 v[36:37], v115 offset0:178 offset1:179
	ds_read2_b32 v[38:39], v115 offset0:180 offset1:181
	ds_read2_b32 v[40:41], v115 offset0:187 offset1:188
	ds_read2_b32 v[42:43], v115 offset0:189 offset1:190
	ds_read2_b32 v[44:45], v115 offset0:195 offset1:196
	ds_read2_b32 v[46:47], v115 offset0:197 offset1:198
	s_waitcnt lgkmcnt(0)
	v_mfma_f32_32x32x16_bf16 v[32:47], v[188:191], v[48:51], v[32:47]
	ds_read_b64_tr_b16 v[72:73], v231
	ds_read_b64_tr_b16 v[74:75], v231 offset:512
	ds_read_b64_tr_b16 v[76:77], v231 offset:2048
	ds_read_b64_tr_b16 v[78:79], v231 offset:2560
	ds_read_b64_tr_b16 v[220:221], v231 offset:1024
	ds_read_b64_tr_b16 v[222:223], v231 offset:1536
	ds_read_b64_tr_b16 v[224:225], v231 offset:3072
	ds_read_b64_tr_b16 v[226:227], v231 offset:3584
	s_waitcnt vmcnt(8)
	ds_write_b128 v247, v[116:119]
	ds_write_b128 v247, v[120:123] offset:1024
	ds_write_b128 v247, v[124:127] offset:2048
	ds_write_b128 v247, v[128:131] offset:3072
	ds_read_b128 v[116:119], v248
	ds_read_b128 v[120:123], v249
	ds_read_b128 v[124:127], v250
	ds_read_b128 v[128:131], v251
	ds_write_b128 v112, v[132:135]
	ds_write_b128 v112, v[136:139] offset:1024
	ds_write_b128 v112, v[140:143] offset:2048
	ds_write_b128 v112, v[144:147] offset:3072
	v_mfma_f32_32x32x16_bf16 v[32:47], v[192:195], v[52:55], v[32:47]
	v_mfma_f32_32x32x16_bf16 v[32:47], v[196:199], v[56:59], v[32:47]
	v_mfma_f32_32x32x16_bf16 v[32:47], v[200:203], v[60:63], v[32:47]
	s_nop 11
	v_exp_f32_e32 v32, v32
	v_exp_f32_e32 v33, v33
	v_exp_f32_e32 v34, v34
	v_exp_f32_e32 v35, v35
	v_exp_f32_e32 v36, v36
	v_exp_f32_e32 v37, v37
	v_exp_f32_e32 v38, v38
	v_exp_f32_e32 v39, v39
	v_exp_f32_e32 v40, v40
	v_exp_f32_e32 v41, v41
	v_exp_f32_e32 v42, v42
	v_exp_f32_e32 v43, v43
	v_exp_f32_e32 v44, v44
	v_exp_f32_e32 v45, v45
	v_exp_f32_e32 v46, v46
	v_exp_f32_e32 v47, v47
	v_cvt_pk_bf16_f32 v64, v32, v33
	v_cvt_pk_bf16_f32 v65, v34, v35
	v_cvt_pk_bf16_f32 v66, v36, v37
	v_cvt_pk_bf16_f32 v67, v38, v39
	v_cvt_pk_bf16_f32 v68, v40, v41
	v_cvt_pk_bf16_f32 v69, v42, v43
	v_cvt_pk_bf16_f32 v70, v44, v45
	v_cvt_pk_bf16_f32 v71, v46, v47
	v_pk_add_f32 v[232:233], v[232:233], v[32:33]
	v_pk_add_f32 v[232:233], v[232:233], v[34:35]
	v_pk_add_f32 v[232:233], v[232:233], v[36:37]
	v_pk_add_f32 v[232:233], v[232:233], v[38:39]
	v_pk_add_f32 v[232:233], v[232:233], v[40:41]
	v_pk_add_f32 v[232:233], v[232:233], v[42:43]
	v_pk_add_f32 v[232:233], v[232:233], v[44:45]
	v_pk_add_f32 v[232:233], v[232:233], v[46:47]
	s_waitcnt lgkmcnt(12)
	v_mfma_f32_32x32x16_bf16 v[0:15], v[64:67], v[72:75], v[0:15]
	v_mfma_f32_32x32x16_bf16 v[16:31], v[64:67], v[76:79], v[16:31]
	v_mfma_f32_32x32x16_bf16 v[0:15], v[68:71], v[220:223], v[0:15]
	v_mfma_f32_32x32x16_bf16 v[16:31], v[68:71], v[224:227], v[16:31]
	global_load_dwordx4 v[188:191], v235, s[84:85]
	global_load_dwordx4 v[192:195], v236, s[84:85]
	global_load_dwordx4 v[196:199], v237, s[84:85]
	global_load_dwordx4 v[200:203], v238, s[84:85]
	global_load_dwordx4 v[204:207], v100, s[84:85] offset:768
	global_load_dwordx4 v[208:211], v149, s[84:85] offset:768
	global_load_dwordx4 v[212:215], v100, s[84:85] offset:832
	global_load_dwordx4 v[216:219], v149, s[84:85] offset:832
	s_add_u32 s84, s84, 0x30000
	s_addc_u32 s85, s85, 0
	ds_read2_b32 v[32:33], v115 offset0:204 offset1:205
	ds_read2_b32 v[34:35], v115 offset0:206 offset1:207
	ds_read2_b32 v[36:37], v115 offset0:212 offset1:213
	ds_read2_b32 v[38:39], v115 offset0:214 offset1:215
	ds_read2_b32 v[40:41], v115 offset0:221 offset1:222
	ds_read2_b32 v[42:43], v115 offset0:223 offset1:224
	ds_read2_b32 v[44:45], v115 offset0:229 offset1:230
	ds_read2_b32 v[46:47], v115 offset0:231 offset1:232
	s_waitcnt lgkmcnt(0)
	v_mfma_f32_32x32x16_bf16 v[32:47], v[116:119], v[48:51], v[32:47]
	ds_read_b64_tr_b16 v[72:73], v231
	ds_read_b64_tr_b16 v[74:75], v231 offset:512
	ds_read_b64_tr_b16 v[76:77], v231 offset:2048
	ds_read_b64_tr_b16 v[78:79], v231 offset:2560
	ds_read_b64_tr_b16 v[220:221], v231 offset:1024
	ds_read_b64_tr_b16 v[222:223], v231 offset:1536
	ds_read_b64_tr_b16 v[224:225], v231 offset:3072
	ds_read_b64_tr_b16 v[226:227], v231 offset:3584
	s_waitcnt vmcnt(8)
	ds_write_b128 v247, v[156:159]
	ds_write_b128 v247, v[160:163] offset:1024
	ds_write_b128 v247, v[164:167] offset:2048
	ds_write_b128 v247, v[168:171] offset:3072
	ds_read_b128 v[156:159], v248
	ds_read_b128 v[160:163], v249
	ds_read_b128 v[164:167], v250
	ds_read_b128 v[168:171], v251
	ds_write_b128 v112, v[172:175]
	ds_write_b128 v112, v[176:179] offset:1024
	ds_write_b128 v112, v[180:183] offset:2048
	ds_write_b128 v112, v[184:187] offset:3072
	v_mfma_f32_32x32x16_bf16 v[32:47], v[120:123], v[52:55], v[32:47]
	v_mfma_f32_32x32x16_bf16 v[32:47], v[124:127], v[56:59], v[32:47]
	v_mfma_f32_32x32x16_bf16 v[32:47], v[128:131], v[60:63], v[32:47]
	s_nop 11
	v_exp_f32_e32 v32, v32
	v_exp_f32_e32 v33, v33
	v_exp_f32_e32 v34, v34
	v_exp_f32_e32 v35, v35
	v_exp_f32_e32 v36, v36
	v_exp_f32_e32 v37, v37
	v_exp_f32_e32 v38, v38
	v_exp_f32_e32 v39, v39
	v_exp_f32_e32 v40, v40
	v_exp_f32_e32 v41, v41
	v_exp_f32_e32 v42, v42
	v_exp_f32_e32 v43, v43
	v_exp_f32_e32 v44, v44
	v_exp_f32_e32 v45, v45
	v_exp_f32_e32 v46, v46
	v_exp_f32_e32 v47, v47
	v_cvt_pk_bf16_f32 v64, v32, v33
	v_cvt_pk_bf16_f32 v65, v34, v35
	v_cvt_pk_bf16_f32 v66, v36, v37
	v_cvt_pk_bf16_f32 v67, v38, v39
	v_cvt_pk_bf16_f32 v68, v40, v41
	v_cvt_pk_bf16_f32 v69, v42, v43
	v_cvt_pk_bf16_f32 v70, v44, v45
	v_cvt_pk_bf16_f32 v71, v46, v47
	v_pk_add_f32 v[232:233], v[232:233], v[32:33]
	v_pk_add_f32 v[232:233], v[232:233], v[34:35]
	v_pk_add_f32 v[232:233], v[232:233], v[36:37]
	v_pk_add_f32 v[232:233], v[232:233], v[38:39]
	v_pk_add_f32 v[232:233], v[232:233], v[40:41]
	v_pk_add_f32 v[232:233], v[232:233], v[42:43]
	v_pk_add_f32 v[232:233], v[232:233], v[44:45]
	v_pk_add_f32 v[232:233], v[232:233], v[46:47]
	s_waitcnt lgkmcnt(12)
	v_mfma_f32_32x32x16_bf16 v[0:15], v[64:67], v[72:75], v[0:15]
	v_mfma_f32_32x32x16_bf16 v[16:31], v[64:67], v[76:79], v[16:31]
	v_mfma_f32_32x32x16_bf16 v[0:15], v[68:71], v[220:223], v[0:15]
	v_mfma_f32_32x32x16_bf16 v[16:31], v[68:71], v[224:227], v[16:31]
	global_load_dwordx4 v[116:119], v235, s[84:85]
	global_load_dwordx4 v[120:123], v236, s[84:85]
	global_load_dwordx4 v[124:127], v237, s[84:85]
	global_load_dwordx4 v[128:131], v238, s[84:85]
	global_load_dwordx4 v[132:135], v100, s[84:85] offset:768
	global_load_dwordx4 v[136:139], v149, s[84:85] offset:768
	global_load_dwordx4 v[140:143], v100, s[84:85] offset:832
	global_load_dwordx4 v[144:147], v149, s[84:85] offset:832
	s_add_u32 s84, s84, 0x30000
	s_addc_u32 s85, s85, 0
	v_add_u32_e32 v115, 952, v115
	ds_read2_b32 v[32:33], v115 offset0:0 offset1:1
	ds_read2_b32 v[34:35], v115 offset0:2 offset1:3
	ds_read2_b32 v[36:37], v115 offset0:8 offset1:9
	ds_read2_b32 v[38:39], v115 offset0:10 offset1:11
	ds_read2_b32 v[40:41], v115 offset0:17 offset1:18
	ds_read2_b32 v[42:43], v115 offset0:19 offset1:20
	ds_read2_b32 v[44:45], v115 offset0:25 offset1:26
	ds_read2_b32 v[46:47], v115 offset0:27 offset1:28
	s_waitcnt lgkmcnt(0)
	v_mfma_f32_32x32x16_bf16 v[32:47], v[156:159], v[48:51], v[32:47]
	ds_read_b64_tr_b16 v[72:73], v231
	ds_read_b64_tr_b16 v[74:75], v231 offset:512
	ds_read_b64_tr_b16 v[76:77], v231 offset:2048
	ds_read_b64_tr_b16 v[78:79], v231 offset:2560
	ds_read_b64_tr_b16 v[220:221], v231 offset:1024
	ds_read_b64_tr_b16 v[222:223], v231 offset:1536
	ds_read_b64_tr_b16 v[224:225], v231 offset:3072
	ds_read_b64_tr_b16 v[226:227], v231 offset:3584
	s_waitcnt vmcnt(8)
	ds_write_b128 v247, v[188:191]
	ds_write_b128 v247, v[192:195] offset:1024
	ds_write_b128 v247, v[196:199] offset:2048
	ds_write_b128 v247, v[200:203] offset:3072
	ds_read_b128 v[188:191], v248
	ds_read_b128 v[192:195], v249
	ds_read_b128 v[196:199], v250
	ds_read_b128 v[200:203], v251
	ds_write_b128 v112, v[204:207]
	ds_write_b128 v112, v[208:211] offset:1024
	ds_write_b128 v112, v[212:215] offset:2048
	ds_write_b128 v112, v[216:219] offset:3072
	v_mfma_f32_32x32x16_bf16 v[32:47], v[160:163], v[52:55], v[32:47]
	v_mfma_f32_32x32x16_bf16 v[32:47], v[164:167], v[56:59], v[32:47]
	v_mfma_f32_32x32x16_bf16 v[32:47], v[168:171], v[60:63], v[32:47]
	s_nop 11
	v_exp_f32_e32 v32, v32
	v_exp_f32_e32 v33, v33
	v_exp_f32_e32 v34, v34
	v_exp_f32_e32 v35, v35
	v_exp_f32_e32 v36, v36
	v_exp_f32_e32 v37, v37
	v_exp_f32_e32 v38, v38
	v_exp_f32_e32 v39, v39
	v_exp_f32_e32 v40, v40
	v_exp_f32_e32 v41, v41
	v_exp_f32_e32 v42, v42
	v_exp_f32_e32 v43, v43
	v_exp_f32_e32 v44, v44
	v_exp_f32_e32 v45, v45
	v_exp_f32_e32 v46, v46
	v_exp_f32_e32 v47, v47
	v_cvt_pk_bf16_f32 v64, v32, v33
	v_cvt_pk_bf16_f32 v65, v34, v35
	v_cvt_pk_bf16_f32 v66, v36, v37
	v_cvt_pk_bf16_f32 v67, v38, v39
	v_cvt_pk_bf16_f32 v68, v40, v41
	v_cvt_pk_bf16_f32 v69, v42, v43
	v_cvt_pk_bf16_f32 v70, v44, v45
	v_cvt_pk_bf16_f32 v71, v46, v47
	v_pk_add_f32 v[232:233], v[232:233], v[32:33]
	v_pk_add_f32 v[232:233], v[232:233], v[34:35]
	v_pk_add_f32 v[232:233], v[232:233], v[36:37]
	v_pk_add_f32 v[232:233], v[232:233], v[38:39]
	v_pk_add_f32 v[232:233], v[232:233], v[40:41]
	v_pk_add_f32 v[232:233], v[232:233], v[42:43]
	v_pk_add_f32 v[232:233], v[232:233], v[44:45]
	v_pk_add_f32 v[232:233], v[232:233], v[46:47]
	s_waitcnt lgkmcnt(12)
	v_mfma_f32_32x32x16_bf16 v[0:15], v[64:67], v[72:75], v[0:15]
	v_mfma_f32_32x32x16_bf16 v[16:31], v[64:67], v[76:79], v[16:31]
	v_mfma_f32_32x32x16_bf16 v[0:15], v[68:71], v[220:223], v[0:15]
	v_mfma_f32_32x32x16_bf16 v[16:31], v[68:71], v[224:227], v[16:31]
	global_load_dwordx4 v[156:159], v235, s[84:85]
	global_load_dwordx4 v[160:163], v236, s[84:85]
	global_load_dwordx4 v[164:167], v237, s[84:85]
	global_load_dwordx4 v[168:171], v238, s[84:85]
	global_load_dwordx4 v[172:175], v100, s[84:85] offset:768
	global_load_dwordx4 v[176:179], v149, s[84:85] offset:768
	global_load_dwordx4 v[180:183], v100, s[84:85] offset:832
	global_load_dwordx4 v[184:187], v149, s[84:85] offset:832
	s_add_u32 s84, s84, 0x30000
	s_addc_u32 s85, s85, 0
	ds_read2_b32 v[32:33], v115 offset0:34 offset1:35
	ds_read2_b32 v[34:35], v115 offset0:36 offset1:37
	ds_read2_b32 v[36:37], v115 offset0:42 offset1:43
	ds_read2_b32 v[38:39], v115 offset0:44 offset1:45
	ds_read2_b32 v[40:41], v115 offset0:51 offset1:52
	ds_read2_b32 v[42:43], v115 offset0:53 offset1:54
	ds_read2_b32 v[44:45], v115 offset0:59 offset1:60
	ds_read2_b32 v[46:47], v115 offset0:61 offset1:62
	s_waitcnt lgkmcnt(0)
	v_mfma_f32_32x32x16_bf16 v[32:47], v[188:191], v[48:51], v[32:47]
	ds_read_b64_tr_b16 v[72:73], v231
	ds_read_b64_tr_b16 v[74:75], v231 offset:512
	ds_read_b64_tr_b16 v[76:77], v231 offset:2048
	ds_read_b64_tr_b16 v[78:79], v231 offset:2560
	ds_read_b64_tr_b16 v[220:221], v231 offset:1024
	ds_read_b64_tr_b16 v[222:223], v231 offset:1536
	ds_read_b64_tr_b16 v[224:225], v231 offset:3072
	ds_read_b64_tr_b16 v[226:227], v231 offset:3584
	s_waitcnt vmcnt(8)
	ds_write_b128 v247, v[116:119]
	ds_write_b128 v247, v[120:123] offset:1024
	ds_write_b128 v247, v[124:127] offset:2048
	ds_write_b128 v247, v[128:131] offset:3072
	ds_read_b128 v[116:119], v248
	ds_read_b128 v[120:123], v249
	ds_read_b128 v[124:127], v250
	ds_read_b128 v[128:131], v251
	ds_write_b128 v112, v[132:135]
	ds_write_b128 v112, v[136:139] offset:1024
	ds_write_b128 v112, v[140:143] offset:2048
	ds_write_b128 v112, v[144:147] offset:3072
	v_mfma_f32_32x32x16_bf16 v[32:47], v[192:195], v[52:55], v[32:47]
	v_mfma_f32_32x32x16_bf16 v[32:47], v[196:199], v[56:59], v[32:47]
	v_mfma_f32_32x32x16_bf16 v[32:47], v[200:203], v[60:63], v[32:47]
	s_nop 11
	v_exp_f32_e32 v32, v32
	v_exp_f32_e32 v33, v33
	v_exp_f32_e32 v34, v34
	v_exp_f32_e32 v35, v35
	v_exp_f32_e32 v36, v36
	v_exp_f32_e32 v37, v37
	v_exp_f32_e32 v38, v38
	v_exp_f32_e32 v39, v39
	v_exp_f32_e32 v40, v40
	v_exp_f32_e32 v41, v41
	v_exp_f32_e32 v42, v42
	v_exp_f32_e32 v43, v43
	v_exp_f32_e32 v44, v44
	v_exp_f32_e32 v45, v45
	v_exp_f32_e32 v46, v46
	v_exp_f32_e32 v47, v47
	v_cvt_pk_bf16_f32 v64, v32, v33
	v_cvt_pk_bf16_f32 v65, v34, v35
	v_cvt_pk_bf16_f32 v66, v36, v37
	v_cvt_pk_bf16_f32 v67, v38, v39
	v_cvt_pk_bf16_f32 v68, v40, v41
	v_cvt_pk_bf16_f32 v69, v42, v43
	v_cvt_pk_bf16_f32 v70, v44, v45
	v_cvt_pk_bf16_f32 v71, v46, v47
	v_pk_add_f32 v[232:233], v[232:233], v[32:33]
	v_pk_add_f32 v[232:233], v[232:233], v[34:35]
	v_pk_add_f32 v[232:233], v[232:233], v[36:37]
	v_pk_add_f32 v[232:233], v[232:233], v[38:39]
	v_pk_add_f32 v[232:233], v[232:233], v[40:41]
	v_pk_add_f32 v[232:233], v[232:233], v[42:43]
	v_pk_add_f32 v[232:233], v[232:233], v[44:45]
	v_pk_add_f32 v[232:233], v[232:233], v[46:47]
	s_waitcnt lgkmcnt(12)
	v_mfma_f32_32x32x16_bf16 v[0:15], v[64:67], v[72:75], v[0:15]
	v_mfma_f32_32x32x16_bf16 v[16:31], v[64:67], v[76:79], v[16:31]
	v_mfma_f32_32x32x16_bf16 v[0:15], v[68:71], v[220:223], v[0:15]
	v_mfma_f32_32x32x16_bf16 v[16:31], v[68:71], v[224:227], v[16:31]
	global_load_dwordx4 v[188:191], v235, s[84:85]
	global_load_dwordx4 v[192:195], v236, s[84:85]
	global_load_dwordx4 v[196:199], v237, s[84:85]
	global_load_dwordx4 v[200:203], v238, s[84:85]
	global_load_dwordx4 v[204:207], v100, s[84:85] offset:768
	global_load_dwordx4 v[208:211], v149, s[84:85] offset:768
	global_load_dwordx4 v[212:215], v100, s[84:85] offset:832
	global_load_dwordx4 v[216:219], v149, s[84:85] offset:832
	s_add_u32 s84, s84, 0x30000
	s_addc_u32 s85, s85, 0
	ds_read2_b32 v[32:33], v115 offset0:68 offset1:69
	ds_read2_b32 v[34:35], v115 offset0:70 offset1:71
	ds_read2_b32 v[36:37], v115 offset0:76 offset1:77
	ds_read2_b32 v[38:39], v115 offset0:78 offset1:79
	ds_read2_b32 v[40:41], v115 offset0:85 offset1:86
	ds_read2_b32 v[42:43], v115 offset0:87 offset1:88
	ds_read2_b32 v[44:45], v115 offset0:93 offset1:94
	ds_read2_b32 v[46:47], v115 offset0:95 offset1:96
	s_waitcnt lgkmcnt(0)
	v_mfma_f32_32x32x16_bf16 v[32:47], v[116:119], v[48:51], v[32:47]
	ds_read_b64_tr_b16 v[72:73], v231
	ds_read_b64_tr_b16 v[74:75], v231 offset:512
	ds_read_b64_tr_b16 v[76:77], v231 offset:2048
	ds_read_b64_tr_b16 v[78:79], v231 offset:2560
	ds_read_b64_tr_b16 v[220:221], v231 offset:1024
	ds_read_b64_tr_b16 v[222:223], v231 offset:1536
	ds_read_b64_tr_b16 v[224:225], v231 offset:3072
	ds_read_b64_tr_b16 v[226:227], v231 offset:3584
	s_waitcnt vmcnt(8)
	ds_write_b128 v247, v[156:159]
	ds_write_b128 v247, v[160:163] offset:1024
	ds_write_b128 v247, v[164:167] offset:2048
	ds_write_b128 v247, v[168:171] offset:3072
	ds_read_b128 v[156:159], v248
	ds_read_b128 v[160:163], v249
	ds_read_b128 v[164:167], v250
	ds_read_b128 v[168:171], v251
	ds_write_b128 v112, v[172:175]
	ds_write_b128 v112, v[176:179] offset:1024
	ds_write_b128 v112, v[180:183] offset:2048
	ds_write_b128 v112, v[184:187] offset:3072
	v_mfma_f32_32x32x16_bf16 v[32:47], v[120:123], v[52:55], v[32:47]
	v_mfma_f32_32x32x16_bf16 v[32:47], v[124:127], v[56:59], v[32:47]
	v_mfma_f32_32x32x16_bf16 v[32:47], v[128:131], v[60:63], v[32:47]
	s_nop 11
	v_exp_f32_e32 v32, v32
	v_exp_f32_e32 v33, v33
	v_exp_f32_e32 v34, v34
	v_exp_f32_e32 v35, v35
	v_exp_f32_e32 v36, v36
	v_exp_f32_e32 v37, v37
	v_exp_f32_e32 v38, v38
	v_exp_f32_e32 v39, v39
	v_exp_f32_e32 v40, v40
	v_exp_f32_e32 v41, v41
	v_exp_f32_e32 v42, v42
	v_exp_f32_e32 v43, v43
	v_exp_f32_e32 v44, v44
	v_exp_f32_e32 v45, v45
	v_exp_f32_e32 v46, v46
	v_exp_f32_e32 v47, v47
	v_cvt_pk_bf16_f32 v64, v32, v33
	v_cvt_pk_bf16_f32 v65, v34, v35
	v_cvt_pk_bf16_f32 v66, v36, v37
	v_cvt_pk_bf16_f32 v67, v38, v39
	v_cvt_pk_bf16_f32 v68, v40, v41
	v_cvt_pk_bf16_f32 v69, v42, v43
	v_cvt_pk_bf16_f32 v70, v44, v45
	v_cvt_pk_bf16_f32 v71, v46, v47
	v_pk_add_f32 v[232:233], v[232:233], v[32:33]
	v_pk_add_f32 v[232:233], v[232:233], v[34:35]
	v_pk_add_f32 v[232:233], v[232:233], v[36:37]
	v_pk_add_f32 v[232:233], v[232:233], v[38:39]
	v_pk_add_f32 v[232:233], v[232:233], v[40:41]
	v_pk_add_f32 v[232:233], v[232:233], v[42:43]
	v_pk_add_f32 v[232:233], v[232:233], v[44:45]
	v_pk_add_f32 v[232:233], v[232:233], v[46:47]
	s_waitcnt lgkmcnt(12)
	v_mfma_f32_32x32x16_bf16 v[0:15], v[64:67], v[72:75], v[0:15]
	v_mfma_f32_32x32x16_bf16 v[16:31], v[64:67], v[76:79], v[16:31]
	v_mfma_f32_32x32x16_bf16 v[0:15], v[68:71], v[220:223], v[0:15]
	v_mfma_f32_32x32x16_bf16 v[16:31], v[68:71], v[224:227], v[16:31]
	global_load_dwordx4 v[116:119], v235, s[84:85]
	global_load_dwordx4 v[120:123], v236, s[84:85]
	global_load_dwordx4 v[124:127], v237, s[84:85]
	global_load_dwordx4 v[128:131], v238, s[84:85]
	global_load_dwordx4 v[132:135], v100, s[84:85] offset:768
	global_load_dwordx4 v[136:139], v149, s[84:85] offset:768
	global_load_dwordx4 v[140:143], v100, s[84:85] offset:832
	global_load_dwordx4 v[144:147], v149, s[84:85] offset:832
	s_add_u32 s84, s84, 0x30000
	s_addc_u32 s85, s85, 0
	ds_read2_b32 v[32:33], v115 offset0:102 offset1:103
	ds_read2_b32 v[34:35], v115 offset0:104 offset1:105
	ds_read2_b32 v[36:37], v115 offset0:110 offset1:111
	ds_read2_b32 v[38:39], v115 offset0:112 offset1:113
	ds_read2_b32 v[40:41], v115 offset0:119 offset1:120
	ds_read2_b32 v[42:43], v115 offset0:121 offset1:122
	ds_read2_b32 v[44:45], v115 offset0:127 offset1:128
	ds_read2_b32 v[46:47], v115 offset0:129 offset1:130
	s_waitcnt lgkmcnt(0)
	v_mfma_f32_32x32x16_bf16 v[32:47], v[156:159], v[48:51], v[32:47]
	ds_read_b64_tr_b16 v[72:73], v231
	ds_read_b64_tr_b16 v[74:75], v231 offset:512
	ds_read_b64_tr_b16 v[76:77], v231 offset:2048
	ds_read_b64_tr_b16 v[78:79], v231 offset:2560
	ds_read_b64_tr_b16 v[220:221], v231 offset:1024
	ds_read_b64_tr_b16 v[222:223], v231 offset:1536
	ds_read_b64_tr_b16 v[224:225], v231 offset:3072
	ds_read_b64_tr_b16 v[226:227], v231 offset:3584
	s_waitcnt vmcnt(8)
	ds_write_b128 v247, v[188:191]
	ds_write_b128 v247, v[192:195] offset:1024
	ds_write_b128 v247, v[196:199] offset:2048
	ds_write_b128 v247, v[200:203] offset:3072
	ds_read_b128 v[188:191], v248
	ds_read_b128 v[192:195], v249
	ds_read_b128 v[196:199], v250
	ds_read_b128 v[200:203], v251
	ds_write_b128 v112, v[204:207]
	ds_write_b128 v112, v[208:211] offset:1024
	ds_write_b128 v112, v[212:215] offset:2048
	ds_write_b128 v112, v[216:219] offset:3072
	v_mfma_f32_32x32x16_bf16 v[32:47], v[160:163], v[52:55], v[32:47]
	v_mfma_f32_32x32x16_bf16 v[32:47], v[164:167], v[56:59], v[32:47]
	v_mfma_f32_32x32x16_bf16 v[32:47], v[168:171], v[60:63], v[32:47]
	s_nop 11
	v_exp_f32_e32 v32, v32
	v_exp_f32_e32 v33, v33
	v_exp_f32_e32 v34, v34
	v_exp_f32_e32 v35, v35
	v_exp_f32_e32 v36, v36
	v_exp_f32_e32 v37, v37
	v_exp_f32_e32 v38, v38
	v_exp_f32_e32 v39, v39
	v_exp_f32_e32 v40, v40
	v_exp_f32_e32 v41, v41
	v_exp_f32_e32 v42, v42
	v_exp_f32_e32 v43, v43
	v_exp_f32_e32 v44, v44
	v_exp_f32_e32 v45, v45
	v_exp_f32_e32 v46, v46
	v_exp_f32_e32 v47, v47
	v_cvt_pk_bf16_f32 v64, v32, v33
	v_cvt_pk_bf16_f32 v65, v34, v35
	v_cvt_pk_bf16_f32 v66, v36, v37
	v_cvt_pk_bf16_f32 v67, v38, v39
	v_cvt_pk_bf16_f32 v68, v40, v41
	v_cvt_pk_bf16_f32 v69, v42, v43
	v_cvt_pk_bf16_f32 v70, v44, v45
	v_cvt_pk_bf16_f32 v71, v46, v47
	v_pk_add_f32 v[232:233], v[232:233], v[32:33]
	v_pk_add_f32 v[232:233], v[232:233], v[34:35]
	v_pk_add_f32 v[232:233], v[232:233], v[36:37]
	v_pk_add_f32 v[232:233], v[232:233], v[38:39]
	v_pk_add_f32 v[232:233], v[232:233], v[40:41]
	v_pk_add_f32 v[232:233], v[232:233], v[42:43]
	v_pk_add_f32 v[232:233], v[232:233], v[44:45]
	v_pk_add_f32 v[232:233], v[232:233], v[46:47]
	s_waitcnt lgkmcnt(12)
	v_mfma_f32_32x32x16_bf16 v[0:15], v[64:67], v[72:75], v[0:15]
	v_mfma_f32_32x32x16_bf16 v[16:31], v[64:67], v[76:79], v[16:31]
	v_mfma_f32_32x32x16_bf16 v[0:15], v[68:71], v[220:223], v[0:15]
	v_mfma_f32_32x32x16_bf16 v[16:31], v[68:71], v[224:227], v[16:31]
	global_load_dwordx4 v[156:159], v235, s[84:85]
	global_load_dwordx4 v[160:163], v236, s[84:85]
	global_load_dwordx4 v[164:167], v237, s[84:85]
	global_load_dwordx4 v[168:171], v238, s[84:85]
	global_load_dwordx4 v[172:175], v100, s[84:85] offset:768
	global_load_dwordx4 v[176:179], v149, s[84:85] offset:768
	global_load_dwordx4 v[180:183], v100, s[84:85] offset:832
	global_load_dwordx4 v[184:187], v149, s[84:85] offset:832
	s_add_u32 s84, s84, 0x30000
	s_addc_u32 s85, s85, 0
	ds_read2_b32 v[32:33], v115 offset0:136 offset1:137
	ds_read2_b32 v[34:35], v115 offset0:138 offset1:139
	ds_read2_b32 v[36:37], v115 offset0:144 offset1:145
	ds_read2_b32 v[38:39], v115 offset0:146 offset1:147
	ds_read2_b32 v[40:41], v115 offset0:153 offset1:154
	ds_read2_b32 v[42:43], v115 offset0:155 offset1:156
	ds_read2_b32 v[44:45], v115 offset0:161 offset1:162
	ds_read2_b32 v[46:47], v115 offset0:163 offset1:164
	s_waitcnt lgkmcnt(0)
	v_mfma_f32_32x32x16_bf16 v[32:47], v[188:191], v[48:51], v[32:47]
	ds_read_b64_tr_b16 v[72:73], v231
	ds_read_b64_tr_b16 v[74:75], v231 offset:512
	ds_read_b64_tr_b16 v[76:77], v231 offset:2048
	ds_read_b64_tr_b16 v[78:79], v231 offset:2560
	ds_read_b64_tr_b16 v[220:221], v231 offset:1024
	ds_read_b64_tr_b16 v[222:223], v231 offset:1536
	ds_read_b64_tr_b16 v[224:225], v231 offset:3072
	ds_read_b64_tr_b16 v[226:227], v231 offset:3584
	s_waitcnt vmcnt(8)
	ds_write_b128 v247, v[116:119]
	ds_write_b128 v247, v[120:123] offset:1024
	ds_write_b128 v247, v[124:127] offset:2048
	ds_write_b128 v247, v[128:131] offset:3072
	ds_read_b128 v[116:119], v248
	ds_read_b128 v[120:123], v249
	ds_read_b128 v[124:127], v250
	ds_read_b128 v[128:131], v251
	ds_write_b128 v112, v[132:135]
	ds_write_b128 v112, v[136:139] offset:1024
	ds_write_b128 v112, v[140:143] offset:2048
	ds_write_b128 v112, v[144:147] offset:3072
	v_mfma_f32_32x32x16_bf16 v[32:47], v[192:195], v[52:55], v[32:47]
	v_mfma_f32_32x32x16_bf16 v[32:47], v[196:199], v[56:59], v[32:47]
	v_mfma_f32_32x32x16_bf16 v[32:47], v[200:203], v[60:63], v[32:47]
	s_nop 11
	v_exp_f32_e32 v32, v32
	v_exp_f32_e32 v33, v33
	v_exp_f32_e32 v34, v34
	v_exp_f32_e32 v35, v35
	v_exp_f32_e32 v36, v36
	v_exp_f32_e32 v37, v37
	v_exp_f32_e32 v38, v38
	v_exp_f32_e32 v39, v39
	v_exp_f32_e32 v40, v40
	v_exp_f32_e32 v41, v41
	v_exp_f32_e32 v42, v42
	v_exp_f32_e32 v43, v43
	v_exp_f32_e32 v44, v44
	v_exp_f32_e32 v45, v45
	v_exp_f32_e32 v46, v46
	v_exp_f32_e32 v47, v47
	v_cvt_pk_bf16_f32 v64, v32, v33
	v_cvt_pk_bf16_f32 v65, v34, v35
	v_cvt_pk_bf16_f32 v66, v36, v37
	v_cvt_pk_bf16_f32 v67, v38, v39
	v_cvt_pk_bf16_f32 v68, v40, v41
	v_cvt_pk_bf16_f32 v69, v42, v43
	v_cvt_pk_bf16_f32 v70, v44, v45
	v_cvt_pk_bf16_f32 v71, v46, v47
	v_pk_add_f32 v[232:233], v[232:233], v[32:33]
	v_pk_add_f32 v[232:233], v[232:233], v[34:35]
	v_pk_add_f32 v[232:233], v[232:233], v[36:37]
	v_pk_add_f32 v[232:233], v[232:233], v[38:39]
	v_pk_add_f32 v[232:233], v[232:233], v[40:41]
	v_pk_add_f32 v[232:233], v[232:233], v[42:43]
	v_pk_add_f32 v[232:233], v[232:233], v[44:45]
	v_pk_add_f32 v[232:233], v[232:233], v[46:47]
	s_waitcnt lgkmcnt(12)
	v_mfma_f32_32x32x16_bf16 v[0:15], v[64:67], v[72:75], v[0:15]
	v_mfma_f32_32x32x16_bf16 v[16:31], v[64:67], v[76:79], v[16:31]
	v_mfma_f32_32x32x16_bf16 v[0:15], v[68:71], v[220:223], v[0:15]
	v_mfma_f32_32x32x16_bf16 v[16:31], v[68:71], v[224:227], v[16:31]
	global_load_dwordx4 v[188:191], v235, s[84:85]
	global_load_dwordx4 v[192:195], v236, s[84:85]
	global_load_dwordx4 v[196:199], v237, s[84:85]
	global_load_dwordx4 v[200:203], v238, s[84:85]
	global_load_dwordx4 v[204:207], v100, s[84:85] offset:768
	global_load_dwordx4 v[208:211], v149, s[84:85] offset:768
	global_load_dwordx4 v[212:215], v100, s[84:85] offset:832
	global_load_dwordx4 v[216:219], v149, s[84:85] offset:832
	s_add_u32 s84, s84, 0x30000
	s_addc_u32 s85, s85, 0
	ds_read2_b32 v[32:33], v115 offset0:170 offset1:171
	ds_read2_b32 v[34:35], v115 offset0:172 offset1:173
	ds_read2_b32 v[36:37], v115 offset0:178 offset1:179
	ds_read2_b32 v[38:39], v115 offset0:180 offset1:181
	ds_read2_b32 v[40:41], v115 offset0:187 offset1:188
	ds_read2_b32 v[42:43], v115 offset0:189 offset1:190
	ds_read2_b32 v[44:45], v115 offset0:195 offset1:196
	ds_read2_b32 v[46:47], v115 offset0:197 offset1:198
	s_waitcnt lgkmcnt(0)
	v_mfma_f32_32x32x16_bf16 v[32:47], v[116:119], v[48:51], v[32:47]
	ds_read_b64_tr_b16 v[72:73], v231
	ds_read_b64_tr_b16 v[74:75], v231 offset:512
	ds_read_b64_tr_b16 v[76:77], v231 offset:2048
	ds_read_b64_tr_b16 v[78:79], v231 offset:2560
	ds_read_b64_tr_b16 v[220:221], v231 offset:1024
	ds_read_b64_tr_b16 v[222:223], v231 offset:1536
	ds_read_b64_tr_b16 v[224:225], v231 offset:3072
	ds_read_b64_tr_b16 v[226:227], v231 offset:3584
	s_waitcnt vmcnt(8)
	ds_write_b128 v247, v[156:159]
	ds_write_b128 v247, v[160:163] offset:1024
	ds_write_b128 v247, v[164:167] offset:2048
	ds_write_b128 v247, v[168:171] offset:3072
	ds_read_b128 v[156:159], v248
	ds_read_b128 v[160:163], v249
	ds_read_b128 v[164:167], v250
	ds_read_b128 v[168:171], v251
	ds_write_b128 v112, v[172:175]
	ds_write_b128 v112, v[176:179] offset:1024
	ds_write_b128 v112, v[180:183] offset:2048
	ds_write_b128 v112, v[184:187] offset:3072
	v_mfma_f32_32x32x16_bf16 v[32:47], v[120:123], v[52:55], v[32:47]
	v_mfma_f32_32x32x16_bf16 v[32:47], v[124:127], v[56:59], v[32:47]
	v_mfma_f32_32x32x16_bf16 v[32:47], v[128:131], v[60:63], v[32:47]
	s_nop 11
	v_exp_f32_e32 v32, v32
	v_exp_f32_e32 v33, v33
	v_exp_f32_e32 v34, v34
	v_exp_f32_e32 v35, v35
	v_exp_f32_e32 v36, v36
	v_exp_f32_e32 v37, v37
	v_exp_f32_e32 v38, v38
	v_exp_f32_e32 v39, v39
	v_exp_f32_e32 v40, v40
	v_exp_f32_e32 v41, v41
	v_exp_f32_e32 v42, v42
	v_exp_f32_e32 v43, v43
	v_exp_f32_e32 v44, v44
	v_exp_f32_e32 v45, v45
	v_exp_f32_e32 v46, v46
	v_exp_f32_e32 v47, v47
	v_cvt_pk_bf16_f32 v64, v32, v33
	v_cvt_pk_bf16_f32 v65, v34, v35
	v_cvt_pk_bf16_f32 v66, v36, v37
	v_cvt_pk_bf16_f32 v67, v38, v39
	v_cvt_pk_bf16_f32 v68, v40, v41
	v_cvt_pk_bf16_f32 v69, v42, v43
	v_cvt_pk_bf16_f32 v70, v44, v45
	v_cvt_pk_bf16_f32 v71, v46, v47
	v_pk_add_f32 v[232:233], v[232:233], v[32:33]
	v_pk_add_f32 v[232:233], v[232:233], v[34:35]
	v_pk_add_f32 v[232:233], v[232:233], v[36:37]
	v_pk_add_f32 v[232:233], v[232:233], v[38:39]
	v_pk_add_f32 v[232:233], v[232:233], v[40:41]
	v_pk_add_f32 v[232:233], v[232:233], v[42:43]
	v_pk_add_f32 v[232:233], v[232:233], v[44:45]
	v_pk_add_f32 v[232:233], v[232:233], v[46:47]
	s_waitcnt lgkmcnt(12)
	v_mfma_f32_32x32x16_bf16 v[0:15], v[64:67], v[72:75], v[0:15]
	v_mfma_f32_32x32x16_bf16 v[16:31], v[64:67], v[76:79], v[16:31]
	v_mfma_f32_32x32x16_bf16 v[0:15], v[68:71], v[220:223], v[0:15]
	v_mfma_f32_32x32x16_bf16 v[16:31], v[68:71], v[224:227], v[16:31]
	global_load_dwordx4 v[116:119], v235, s[84:85]
	global_load_dwordx4 v[120:123], v236, s[84:85]
	global_load_dwordx4 v[124:127], v237, s[84:85]
	global_load_dwordx4 v[128:131], v238, s[84:85]
	global_load_dwordx4 v[132:135], v100, s[84:85] offset:768
	global_load_dwordx4 v[136:139], v149, s[84:85] offset:768
	global_load_dwordx4 v[140:143], v100, s[84:85] offset:832
	global_load_dwordx4 v[144:147], v149, s[84:85] offset:832
	s_add_u32 s84, s84, 0x30000
	s_addc_u32 s85, s85, 0
	ds_read2_b32 v[32:33], v115 offset0:204 offset1:205
	ds_read2_b32 v[34:35], v115 offset0:206 offset1:207
	ds_read2_b32 v[36:37], v115 offset0:212 offset1:213
	ds_read2_b32 v[38:39], v115 offset0:214 offset1:215
	ds_read2_b32 v[40:41], v115 offset0:221 offset1:222
	ds_read2_b32 v[42:43], v115 offset0:223 offset1:224
	ds_read2_b32 v[44:45], v115 offset0:229 offset1:230
	ds_read2_b32 v[46:47], v115 offset0:231 offset1:232
	s_waitcnt lgkmcnt(0)
	v_mfma_f32_32x32x16_bf16 v[32:47], v[156:159], v[48:51], v[32:47]
	ds_read_b64_tr_b16 v[72:73], v231
	ds_read_b64_tr_b16 v[74:75], v231 offset:512
	ds_read_b64_tr_b16 v[76:77], v231 offset:2048
	ds_read_b64_tr_b16 v[78:79], v231 offset:2560
	ds_read_b64_tr_b16 v[220:221], v231 offset:1024
	ds_read_b64_tr_b16 v[222:223], v231 offset:1536
	ds_read_b64_tr_b16 v[224:225], v231 offset:3072
	ds_read_b64_tr_b16 v[226:227], v231 offset:3584
	s_waitcnt vmcnt(8)
	ds_write_b128 v247, v[188:191]
	ds_write_b128 v247, v[192:195] offset:1024
	ds_write_b128 v247, v[196:199] offset:2048
	ds_write_b128 v247, v[200:203] offset:3072
	ds_read_b128 v[188:191], v248
	ds_read_b128 v[192:195], v249
	ds_read_b128 v[196:199], v250
	ds_read_b128 v[200:203], v251
	ds_write_b128 v112, v[204:207]
	ds_write_b128 v112, v[208:211] offset:1024
	ds_write_b128 v112, v[212:215] offset:2048
	ds_write_b128 v112, v[216:219] offset:3072
	v_mfma_f32_32x32x16_bf16 v[32:47], v[160:163], v[52:55], v[32:47]
	v_mfma_f32_32x32x16_bf16 v[32:47], v[164:167], v[56:59], v[32:47]
	v_mfma_f32_32x32x16_bf16 v[32:47], v[168:171], v[60:63], v[32:47]
	s_nop 11
	v_exp_f32_e32 v32, v32
	v_exp_f32_e32 v33, v33
	v_exp_f32_e32 v34, v34
	v_exp_f32_e32 v35, v35
	v_exp_f32_e32 v36, v36
	v_exp_f32_e32 v37, v37
	v_exp_f32_e32 v38, v38
	v_exp_f32_e32 v39, v39
	v_exp_f32_e32 v40, v40
	v_exp_f32_e32 v41, v41
	v_exp_f32_e32 v42, v42
	v_exp_f32_e32 v43, v43
	v_exp_f32_e32 v44, v44
	v_exp_f32_e32 v45, v45
	v_exp_f32_e32 v46, v46
	v_exp_f32_e32 v47, v47
	v_cvt_pk_bf16_f32 v64, v32, v33
	v_cvt_pk_bf16_f32 v65, v34, v35
	v_cvt_pk_bf16_f32 v66, v36, v37
	v_cvt_pk_bf16_f32 v67, v38, v39
	v_cvt_pk_bf16_f32 v68, v40, v41
	v_cvt_pk_bf16_f32 v69, v42, v43
	v_cvt_pk_bf16_f32 v70, v44, v45
	v_cvt_pk_bf16_f32 v71, v46, v47
	v_pk_add_f32 v[232:233], v[232:233], v[32:33]
	v_pk_add_f32 v[232:233], v[232:233], v[34:35]
	v_pk_add_f32 v[232:233], v[232:233], v[36:37]
	v_pk_add_f32 v[232:233], v[232:233], v[38:39]
	v_pk_add_f32 v[232:233], v[232:233], v[40:41]
	v_pk_add_f32 v[232:233], v[232:233], v[42:43]
	v_pk_add_f32 v[232:233], v[232:233], v[44:45]
	v_pk_add_f32 v[232:233], v[232:233], v[46:47]
	s_waitcnt lgkmcnt(12)
	v_mfma_f32_32x32x16_bf16 v[0:15], v[64:67], v[72:75], v[0:15]
	v_mfma_f32_32x32x16_bf16 v[16:31], v[64:67], v[76:79], v[16:31]
	v_mfma_f32_32x32x16_bf16 v[0:15], v[68:71], v[220:223], v[0:15]
	v_mfma_f32_32x32x16_bf16 v[16:31], v[68:71], v[224:227], v[16:31]
	global_load_dwordx4 v[156:159], v235, s[84:85]
	global_load_dwordx4 v[160:163], v236, s[84:85]
	global_load_dwordx4 v[164:167], v237, s[84:85]
	global_load_dwordx4 v[168:171], v238, s[84:85]
	global_load_dwordx4 v[172:175], v100, s[84:85] offset:768
	global_load_dwordx4 v[176:179], v149, s[84:85] offset:768
	global_load_dwordx4 v[180:183], v100, s[84:85] offset:832
	global_load_dwordx4 v[184:187], v149, s[84:85] offset:832
	s_add_u32 s84, s84, 0x30000
	s_addc_u32 s85, s85, 0
	v_add_u32_e32 v115, 952, v115
	ds_read2_b32 v[32:33], v115 offset0:0 offset1:1
	ds_read2_b32 v[34:35], v115 offset0:2 offset1:3
	ds_read2_b32 v[36:37], v115 offset0:8 offset1:9
	ds_read2_b32 v[38:39], v115 offset0:10 offset1:11
	ds_read2_b32 v[40:41], v115 offset0:17 offset1:18
	ds_read2_b32 v[42:43], v115 offset0:19 offset1:20
	ds_read2_b32 v[44:45], v115 offset0:25 offset1:26
	ds_read2_b32 v[46:47], v115 offset0:27 offset1:28
	s_waitcnt lgkmcnt(0)
	v_mfma_f32_32x32x16_bf16 v[32:47], v[188:191], v[48:51], v[32:47]
	ds_read_b64_tr_b16 v[72:73], v231
	ds_read_b64_tr_b16 v[74:75], v231 offset:512
	ds_read_b64_tr_b16 v[76:77], v231 offset:2048
	ds_read_b64_tr_b16 v[78:79], v231 offset:2560
	ds_read_b64_tr_b16 v[220:221], v231 offset:1024
	ds_read_b64_tr_b16 v[222:223], v231 offset:1536
	ds_read_b64_tr_b16 v[224:225], v231 offset:3072
	ds_read_b64_tr_b16 v[226:227], v231 offset:3584
	s_waitcnt vmcnt(8)
	ds_write_b128 v247, v[116:119]
	ds_write_b128 v247, v[120:123] offset:1024
	ds_write_b128 v247, v[124:127] offset:2048
	ds_write_b128 v247, v[128:131] offset:3072
	ds_read_b128 v[116:119], v248
	ds_read_b128 v[120:123], v249
	ds_read_b128 v[124:127], v250
	ds_read_b128 v[128:131], v251
	ds_write_b128 v112, v[132:135]
	ds_write_b128 v112, v[136:139] offset:1024
	ds_write_b128 v112, v[140:143] offset:2048
	ds_write_b128 v112, v[144:147] offset:3072
	v_mfma_f32_32x32x16_bf16 v[32:47], v[192:195], v[52:55], v[32:47]
	v_mfma_f32_32x32x16_bf16 v[32:47], v[196:199], v[56:59], v[32:47]
	v_mfma_f32_32x32x16_bf16 v[32:47], v[200:203], v[60:63], v[32:47]
	s_nop 11
	v_exp_f32_e32 v32, v32
	v_exp_f32_e32 v33, v33
	v_exp_f32_e32 v34, v34
	v_exp_f32_e32 v35, v35
	v_exp_f32_e32 v36, v36
	v_exp_f32_e32 v37, v37
	v_exp_f32_e32 v38, v38
	v_exp_f32_e32 v39, v39
	v_exp_f32_e32 v40, v40
	v_exp_f32_e32 v41, v41
	v_exp_f32_e32 v42, v42
	v_exp_f32_e32 v43, v43
	v_exp_f32_e32 v44, v44
	v_exp_f32_e32 v45, v45
	v_exp_f32_e32 v46, v46
	v_exp_f32_e32 v47, v47
	v_cvt_pk_bf16_f32 v64, v32, v33
	v_cvt_pk_bf16_f32 v65, v34, v35
	v_cvt_pk_bf16_f32 v66, v36, v37
	v_cvt_pk_bf16_f32 v67, v38, v39
	v_cvt_pk_bf16_f32 v68, v40, v41
	v_cvt_pk_bf16_f32 v69, v42, v43
	v_cvt_pk_bf16_f32 v70, v44, v45
	v_cvt_pk_bf16_f32 v71, v46, v47
	v_pk_add_f32 v[232:233], v[232:233], v[32:33]
	v_pk_add_f32 v[232:233], v[232:233], v[34:35]
	v_pk_add_f32 v[232:233], v[232:233], v[36:37]
	v_pk_add_f32 v[232:233], v[232:233], v[38:39]
	v_pk_add_f32 v[232:233], v[232:233], v[40:41]
	v_pk_add_f32 v[232:233], v[232:233], v[42:43]
	v_pk_add_f32 v[232:233], v[232:233], v[44:45]
	v_pk_add_f32 v[232:233], v[232:233], v[46:47]
	s_waitcnt lgkmcnt(12)
	v_mfma_f32_32x32x16_bf16 v[0:15], v[64:67], v[72:75], v[0:15]
	v_mfma_f32_32x32x16_bf16 v[16:31], v[64:67], v[76:79], v[16:31]
	v_mfma_f32_32x32x16_bf16 v[0:15], v[68:71], v[220:223], v[0:15]
	v_mfma_f32_32x32x16_bf16 v[16:31], v[68:71], v[224:227], v[16:31]
	global_load_dwordx4 v[188:191], v235, s[84:85]
	global_load_dwordx4 v[192:195], v236, s[84:85]
	global_load_dwordx4 v[196:199], v237, s[84:85]
	global_load_dwordx4 v[200:203], v238, s[84:85]
	global_load_dwordx4 v[204:207], v100, s[84:85] offset:768
	global_load_dwordx4 v[208:211], v149, s[84:85] offset:768
	global_load_dwordx4 v[212:215], v100, s[84:85] offset:832
	global_load_dwordx4 v[216:219], v149, s[84:85] offset:832
	s_add_u32 s84, s84, 0x30000
	s_addc_u32 s85, s85, 0
	ds_read2_b32 v[32:33], v115 offset0:34 offset1:35
	ds_read2_b32 v[34:35], v115 offset0:36 offset1:37
	ds_read2_b32 v[36:37], v115 offset0:42 offset1:43
	ds_read2_b32 v[38:39], v115 offset0:44 offset1:45
	ds_read2_b32 v[40:41], v115 offset0:51 offset1:52
	ds_read2_b32 v[42:43], v115 offset0:53 offset1:54
	ds_read2_b32 v[44:45], v115 offset0:59 offset1:60
	ds_read2_b32 v[46:47], v115 offset0:61 offset1:62
	s_waitcnt lgkmcnt(0)
	v_mfma_f32_32x32x16_bf16 v[32:47], v[116:119], v[48:51], v[32:47]
	ds_read_b64_tr_b16 v[72:73], v231
	ds_read_b64_tr_b16 v[74:75], v231 offset:512
	ds_read_b64_tr_b16 v[76:77], v231 offset:2048
	ds_read_b64_tr_b16 v[78:79], v231 offset:2560
	ds_read_b64_tr_b16 v[220:221], v231 offset:1024
	ds_read_b64_tr_b16 v[222:223], v231 offset:1536
	ds_read_b64_tr_b16 v[224:225], v231 offset:3072
	ds_read_b64_tr_b16 v[226:227], v231 offset:3584
	s_waitcnt vmcnt(8)
	ds_write_b128 v247, v[156:159]
	ds_write_b128 v247, v[160:163] offset:1024
	ds_write_b128 v247, v[164:167] offset:2048
	ds_write_b128 v247, v[168:171] offset:3072
	ds_read_b128 v[156:159], v248
	ds_read_b128 v[160:163], v249
	ds_read_b128 v[164:167], v250
	ds_read_b128 v[168:171], v251
	ds_write_b128 v112, v[172:175]
	ds_write_b128 v112, v[176:179] offset:1024
	ds_write_b128 v112, v[180:183] offset:2048
	ds_write_b128 v112, v[184:187] offset:3072
	v_mfma_f32_32x32x16_bf16 v[32:47], v[120:123], v[52:55], v[32:47]
	v_mfma_f32_32x32x16_bf16 v[32:47], v[124:127], v[56:59], v[32:47]
	v_mfma_f32_32x32x16_bf16 v[32:47], v[128:131], v[60:63], v[32:47]
	s_nop 11
	v_exp_f32_e32 v32, v32
	v_exp_f32_e32 v33, v33
	v_exp_f32_e32 v34, v34
	v_exp_f32_e32 v35, v35
	v_exp_f32_e32 v36, v36
	v_exp_f32_e32 v37, v37
	v_exp_f32_e32 v38, v38
	v_exp_f32_e32 v39, v39
	v_exp_f32_e32 v40, v40
	v_exp_f32_e32 v41, v41
	v_exp_f32_e32 v42, v42
	v_exp_f32_e32 v43, v43
	v_exp_f32_e32 v44, v44
	v_exp_f32_e32 v45, v45
	v_exp_f32_e32 v46, v46
	v_exp_f32_e32 v47, v47
	v_cvt_pk_bf16_f32 v64, v32, v33
	v_cvt_pk_bf16_f32 v65, v34, v35
	v_cvt_pk_bf16_f32 v66, v36, v37
	v_cvt_pk_bf16_f32 v67, v38, v39
	v_cvt_pk_bf16_f32 v68, v40, v41
	v_cvt_pk_bf16_f32 v69, v42, v43
	v_cvt_pk_bf16_f32 v70, v44, v45
	v_cvt_pk_bf16_f32 v71, v46, v47
	v_pk_add_f32 v[232:233], v[232:233], v[32:33]
	v_pk_add_f32 v[232:233], v[232:233], v[34:35]
	v_pk_add_f32 v[232:233], v[232:233], v[36:37]
	v_pk_add_f32 v[232:233], v[232:233], v[38:39]
	v_pk_add_f32 v[232:233], v[232:233], v[40:41]
	v_pk_add_f32 v[232:233], v[232:233], v[42:43]
	v_pk_add_f32 v[232:233], v[232:233], v[44:45]
	v_pk_add_f32 v[232:233], v[232:233], v[46:47]
	s_waitcnt lgkmcnt(12)
	v_mfma_f32_32x32x16_bf16 v[0:15], v[64:67], v[72:75], v[0:15]
	v_mfma_f32_32x32x16_bf16 v[16:31], v[64:67], v[76:79], v[16:31]
	v_mfma_f32_32x32x16_bf16 v[0:15], v[68:71], v[220:223], v[0:15]
	v_mfma_f32_32x32x16_bf16 v[16:31], v[68:71], v[224:227], v[16:31]
	global_load_dwordx4 v[116:119], v235, s[84:85]
	global_load_dwordx4 v[120:123], v236, s[84:85]
	global_load_dwordx4 v[124:127], v237, s[84:85]
	global_load_dwordx4 v[128:131], v238, s[84:85]
	global_load_dwordx4 v[132:135], v100, s[84:85] offset:768
	global_load_dwordx4 v[136:139], v149, s[84:85] offset:768
	global_load_dwordx4 v[140:143], v100, s[84:85] offset:832
	global_load_dwordx4 v[144:147], v149, s[84:85] offset:832
	s_add_u32 s84, s84, 0x30000
	s_addc_u32 s85, s85, 0
	ds_read2_b32 v[32:33], v115 offset0:68 offset1:69
	ds_read2_b32 v[34:35], v115 offset0:70 offset1:71
	ds_read2_b32 v[36:37], v115 offset0:76 offset1:77
	ds_read2_b32 v[38:39], v115 offset0:78 offset1:79
	ds_read2_b32 v[40:41], v115 offset0:85 offset1:86
	ds_read2_b32 v[42:43], v115 offset0:87 offset1:88
	ds_read2_b32 v[44:45], v115 offset0:93 offset1:94
	ds_read2_b32 v[46:47], v115 offset0:95 offset1:96
	s_waitcnt lgkmcnt(0)
	v_mfma_f32_32x32x16_bf16 v[32:47], v[156:159], v[48:51], v[32:47]
	ds_read_b64_tr_b16 v[72:73], v231
	ds_read_b64_tr_b16 v[74:75], v231 offset:512
	ds_read_b64_tr_b16 v[76:77], v231 offset:2048
	ds_read_b64_tr_b16 v[78:79], v231 offset:2560
	ds_read_b64_tr_b16 v[220:221], v231 offset:1024
	ds_read_b64_tr_b16 v[222:223], v231 offset:1536
	ds_read_b64_tr_b16 v[224:225], v231 offset:3072
	ds_read_b64_tr_b16 v[226:227], v231 offset:3584
	s_waitcnt vmcnt(8)
	ds_write_b128 v247, v[188:191]
	ds_write_b128 v247, v[192:195] offset:1024
	ds_write_b128 v247, v[196:199] offset:2048
	ds_write_b128 v247, v[200:203] offset:3072
	ds_read_b128 v[188:191], v248
	ds_read_b128 v[192:195], v249
	ds_read_b128 v[196:199], v250
	ds_read_b128 v[200:203], v251
	ds_write_b128 v112, v[204:207]
	ds_write_b128 v112, v[208:211] offset:1024
	ds_write_b128 v112, v[212:215] offset:2048
	ds_write_b128 v112, v[216:219] offset:3072
	v_mfma_f32_32x32x16_bf16 v[32:47], v[160:163], v[52:55], v[32:47]
	v_mfma_f32_32x32x16_bf16 v[32:47], v[164:167], v[56:59], v[32:47]
	v_mfma_f32_32x32x16_bf16 v[32:47], v[168:171], v[60:63], v[32:47]
	s_nop 11
	v_exp_f32_e32 v32, v32
	v_exp_f32_e32 v33, v33
	v_exp_f32_e32 v34, v34
	v_exp_f32_e32 v35, v35
	v_exp_f32_e32 v36, v36
	v_exp_f32_e32 v37, v37
	v_exp_f32_e32 v38, v38
	v_exp_f32_e32 v39, v39
	v_exp_f32_e32 v40, v40
	v_exp_f32_e32 v41, v41
	v_exp_f32_e32 v42, v42
	v_exp_f32_e32 v43, v43
	v_exp_f32_e32 v44, v44
	v_exp_f32_e32 v45, v45
	v_exp_f32_e32 v46, v46
	v_exp_f32_e32 v47, v47
	v_cvt_pk_bf16_f32 v64, v32, v33
	v_cvt_pk_bf16_f32 v65, v34, v35
	v_cvt_pk_bf16_f32 v66, v36, v37
	v_cvt_pk_bf16_f32 v67, v38, v39
	v_cvt_pk_bf16_f32 v68, v40, v41
	v_cvt_pk_bf16_f32 v69, v42, v43
	v_cvt_pk_bf16_f32 v70, v44, v45
	v_cvt_pk_bf16_f32 v71, v46, v47
	v_pk_add_f32 v[232:233], v[232:233], v[32:33]
	v_pk_add_f32 v[232:233], v[232:233], v[34:35]
	v_pk_add_f32 v[232:233], v[232:233], v[36:37]
	v_pk_add_f32 v[232:233], v[232:233], v[38:39]
	v_pk_add_f32 v[232:233], v[232:233], v[40:41]
	v_pk_add_f32 v[232:233], v[232:233], v[42:43]
	v_pk_add_f32 v[232:233], v[232:233], v[44:45]
	v_pk_add_f32 v[232:233], v[232:233], v[46:47]
	s_waitcnt lgkmcnt(12)
	v_mfma_f32_32x32x16_bf16 v[0:15], v[64:67], v[72:75], v[0:15]
	v_mfma_f32_32x32x16_bf16 v[16:31], v[64:67], v[76:79], v[16:31]
	v_mfma_f32_32x32x16_bf16 v[0:15], v[68:71], v[220:223], v[0:15]
	v_mfma_f32_32x32x16_bf16 v[16:31], v[68:71], v[224:227], v[16:31]
	global_load_dwordx4 v[156:159], v235, s[84:85]
	global_load_dwordx4 v[160:163], v236, s[84:85]
	global_load_dwordx4 v[164:167], v237, s[84:85]
	global_load_dwordx4 v[168:171], v238, s[84:85]
	global_load_dwordx4 v[172:175], v100, s[84:85] offset:768
	global_load_dwordx4 v[176:179], v149, s[84:85] offset:768
	global_load_dwordx4 v[180:183], v100, s[84:85] offset:832
	global_load_dwordx4 v[184:187], v149, s[84:85] offset:832
	ds_read2_b32 v[32:33], v115 offset0:102 offset1:103
	ds_read2_b32 v[34:35], v115 offset0:104 offset1:105
	ds_read2_b32 v[36:37], v115 offset0:110 offset1:111
	ds_read2_b32 v[38:39], v115 offset0:112 offset1:113
	ds_read2_b32 v[40:41], v115 offset0:119 offset1:120
	ds_read2_b32 v[42:43], v115 offset0:121 offset1:122
	ds_read2_b32 v[44:45], v115 offset0:127 offset1:128
	ds_read2_b32 v[46:47], v115 offset0:129 offset1:130
	s_waitcnt lgkmcnt(0)
	v_mfma_f32_32x32x16_bf16 v[32:47], v[188:191], v[48:51], v[32:47]
	ds_read_b64_tr_b16 v[72:73], v231
	ds_read_b64_tr_b16 v[74:75], v231 offset:512
	ds_read_b64_tr_b16 v[76:77], v231 offset:2048
	ds_read_b64_tr_b16 v[78:79], v231 offset:2560
	ds_read_b64_tr_b16 v[220:221], v231 offset:1024
	ds_read_b64_tr_b16 v[222:223], v231 offset:1536
	ds_read_b64_tr_b16 v[224:225], v231 offset:3072
	ds_read_b64_tr_b16 v[226:227], v231 offset:3584
	s_waitcnt vmcnt(8)
	ds_write_b128 v247, v[116:119]
	ds_write_b128 v247, v[120:123] offset:1024
	ds_write_b128 v247, v[124:127] offset:2048
	ds_write_b128 v247, v[128:131] offset:3072
	ds_read_b128 v[116:119], v248
	ds_read_b128 v[120:123], v249
	ds_read_b128 v[124:127], v250
	ds_read_b128 v[128:131], v251
	ds_write_b128 v112, v[132:135]
	ds_write_b128 v112, v[136:139] offset:1024
	ds_write_b128 v112, v[140:143] offset:2048
	ds_write_b128 v112, v[144:147] offset:3072
	v_mfma_f32_32x32x16_bf16 v[32:47], v[192:195], v[52:55], v[32:47]
	v_mfma_f32_32x32x16_bf16 v[32:47], v[196:199], v[56:59], v[32:47]
	v_mfma_f32_32x32x16_bf16 v[32:47], v[200:203], v[60:63], v[32:47]
	s_nop 11
	v_exp_f32_e32 v32, v32
	v_exp_f32_e32 v33, v33
	v_exp_f32_e32 v34, v34
	v_exp_f32_e32 v35, v35
	v_exp_f32_e32 v36, v36
	v_exp_f32_e32 v37, v37
	v_exp_f32_e32 v38, v38
	v_exp_f32_e32 v39, v39
	v_exp_f32_e32 v40, v40
	v_exp_f32_e32 v41, v41
	v_exp_f32_e32 v42, v42
	v_exp_f32_e32 v43, v43
	v_exp_f32_e32 v44, v44
	v_exp_f32_e32 v45, v45
	v_exp_f32_e32 v46, v46
	v_exp_f32_e32 v47, v47
	v_cvt_pk_bf16_f32 v64, v32, v33
	v_cvt_pk_bf16_f32 v65, v34, v35
	v_cvt_pk_bf16_f32 v66, v36, v37
	v_cvt_pk_bf16_f32 v67, v38, v39
	v_cvt_pk_bf16_f32 v68, v40, v41
	v_cvt_pk_bf16_f32 v69, v42, v43
	v_cvt_pk_bf16_f32 v70, v44, v45
	v_cvt_pk_bf16_f32 v71, v46, v47
	v_pk_add_f32 v[232:233], v[232:233], v[32:33]
	v_pk_add_f32 v[232:233], v[232:233], v[34:35]
	v_pk_add_f32 v[232:233], v[232:233], v[36:37]
	v_pk_add_f32 v[232:233], v[232:233], v[38:39]
	v_pk_add_f32 v[232:233], v[232:233], v[40:41]
	v_pk_add_f32 v[232:233], v[232:233], v[42:43]
	v_pk_add_f32 v[232:233], v[232:233], v[44:45]
	v_pk_add_f32 v[232:233], v[232:233], v[46:47]
	s_waitcnt lgkmcnt(12)
	v_mfma_f32_32x32x16_bf16 v[0:15], v[64:67], v[72:75], v[0:15]
	v_mfma_f32_32x32x16_bf16 v[16:31], v[64:67], v[76:79], v[16:31]
	v_mfma_f32_32x32x16_bf16 v[0:15], v[68:71], v[220:223], v[0:15]
	v_mfma_f32_32x32x16_bf16 v[16:31], v[68:71], v[224:227], v[16:31]
	global_load_dwordx4 v[188:191], v239, s[86:87]
	global_load_dwordx4 v[192:195], v240, s[86:87]
	global_load_dwordx4 v[196:199], v241, s[86:87]
	global_load_dwordx4 v[200:203], v242, s[86:87]
	global_load_dwordx4 v[204:207], v101, s[86:87] offset:768
	global_load_dwordx4 v[208:211], v150, s[86:87] offset:768
	global_load_dwordx4 v[212:215], v101, s[86:87] offset:832
	global_load_dwordx4 v[216:219], v150, s[86:87] offset:832
	s_add_u32 s86, s86, 0xc0000
	s_addc_u32 s87, s87, 0
	ds_read2_b32 v[32:33], v115 offset0:136 offset1:137
	ds_read2_b32 v[34:35], v115 offset0:138 offset1:139
	ds_read2_b32 v[36:37], v115 offset0:144 offset1:145
	ds_read2_b32 v[38:39], v115 offset0:146 offset1:147
	ds_read2_b32 v[40:41], v115 offset0:153 offset1:154
	ds_read2_b32 v[42:43], v115 offset0:155 offset1:156
	ds_read2_b32 v[44:45], v115 offset0:161 offset1:162
	ds_read2_b32 v[46:47], v115 offset0:163 offset1:164
	s_waitcnt lgkmcnt(0)
	v_mfma_f32_32x32x16_bf16 v[32:47], v[116:119], v[48:51], v[32:47]
	ds_read_b64_tr_b16 v[72:73], v231
	ds_read_b64_tr_b16 v[74:75], v231 offset:512
	ds_read_b64_tr_b16 v[76:77], v231 offset:2048
	ds_read_b64_tr_b16 v[78:79], v231 offset:2560
	ds_read_b64_tr_b16 v[220:221], v231 offset:1024
	ds_read_b64_tr_b16 v[222:223], v231 offset:1536
	ds_read_b64_tr_b16 v[224:225], v231 offset:3072
	ds_read_b64_tr_b16 v[226:227], v231 offset:3584
	s_waitcnt vmcnt(8)
	ds_write_b128 v247, v[156:159]
	ds_write_b128 v247, v[160:163] offset:1024
	ds_write_b128 v247, v[164:167] offset:2048
	ds_write_b128 v247, v[168:171] offset:3072
	ds_read_b128 v[156:159], v248
	ds_read_b128 v[160:163], v249
	ds_read_b128 v[164:167], v250
	ds_read_b128 v[168:171], v251
	ds_write_b128 v112, v[172:175]
	ds_write_b128 v112, v[176:179] offset:1024
	ds_write_b128 v112, v[180:183] offset:2048
	ds_write_b128 v112, v[184:187] offset:3072
	v_mfma_f32_32x32x16_bf16 v[32:47], v[120:123], v[52:55], v[32:47]
	v_mfma_f32_32x32x16_bf16 v[32:47], v[124:127], v[56:59], v[32:47]
	v_mfma_f32_32x32x16_bf16 v[32:47], v[128:131], v[60:63], v[32:47]
	s_nop 11
	v_exp_f32_e32 v32, v32
	v_exp_f32_e32 v33, v33
	v_exp_f32_e32 v34, v34
	v_exp_f32_e32 v35, v35
	v_exp_f32_e32 v36, v36
	v_exp_f32_e32 v37, v37
	v_exp_f32_e32 v38, v38
	v_exp_f32_e32 v39, v39
	v_exp_f32_e32 v40, v40
	v_exp_f32_e32 v41, v41
	v_exp_f32_e32 v42, v42
	v_exp_f32_e32 v43, v43
	v_exp_f32_e32 v44, v44
	v_exp_f32_e32 v45, v45
	v_exp_f32_e32 v46, v46
	v_exp_f32_e32 v47, v47
	v_cvt_pk_bf16_f32 v64, v32, v33
	v_cvt_pk_bf16_f32 v65, v34, v35
	v_cvt_pk_bf16_f32 v66, v36, v37
	v_cvt_pk_bf16_f32 v67, v38, v39
	v_cvt_pk_bf16_f32 v68, v40, v41
	v_cvt_pk_bf16_f32 v69, v42, v43
	v_cvt_pk_bf16_f32 v70, v44, v45
	v_cvt_pk_bf16_f32 v71, v46, v47
	v_pk_add_f32 v[232:233], v[232:233], v[32:33]
	v_pk_add_f32 v[232:233], v[232:233], v[34:35]
	v_pk_add_f32 v[232:233], v[232:233], v[36:37]
	v_pk_add_f32 v[232:233], v[232:233], v[38:39]
	v_pk_add_f32 v[232:233], v[232:233], v[40:41]
	v_pk_add_f32 v[232:233], v[232:233], v[42:43]
	v_pk_add_f32 v[232:233], v[232:233], v[44:45]
	v_pk_add_f32 v[232:233], v[232:233], v[46:47]
	s_waitcnt lgkmcnt(12)
	v_mfma_f32_32x32x16_bf16 v[0:15], v[64:67], v[72:75], v[0:15]
	v_mfma_f32_32x32x16_bf16 v[16:31], v[64:67], v[76:79], v[16:31]
	v_mfma_f32_32x32x16_bf16 v[0:15], v[68:71], v[220:223], v[0:15]
	v_mfma_f32_32x32x16_bf16 v[16:31], v[68:71], v[224:227], v[16:31]
	global_load_dwordx4 v[116:119], v239, s[86:87]
	global_load_dwordx4 v[120:123], v240, s[86:87]
	global_load_dwordx4 v[124:127], v241, s[86:87]
	global_load_dwordx4 v[128:131], v242, s[86:87]
	global_load_dwordx4 v[132:135], v101, s[86:87] offset:768
	global_load_dwordx4 v[136:139], v150, s[86:87] offset:768
	global_load_dwordx4 v[140:143], v101, s[86:87] offset:832
	global_load_dwordx4 v[144:147], v150, s[86:87] offset:832
	s_add_u32 s86, s86, 0xc0000
	s_addc_u32 s87, s87, 0
	ds_read2_b32 v[32:33], v115 offset0:170 offset1:171
	ds_read2_b32 v[34:35], v115 offset0:172 offset1:173
	ds_read2_b32 v[36:37], v115 offset0:178 offset1:179
	ds_read2_b32 v[38:39], v115 offset0:180 offset1:181
	ds_read2_b32 v[40:41], v115 offset0:187 offset1:188
	ds_read2_b32 v[42:43], v115 offset0:189 offset1:190
	ds_read2_b32 v[44:45], v115 offset0:195 offset1:196
	ds_read2_b32 v[46:47], v115 offset0:197 offset1:198
	s_waitcnt lgkmcnt(0)
	v_mfma_f32_32x32x16_bf16 v[32:47], v[156:159], v[48:51], v[32:47]
	ds_read_b64_tr_b16 v[72:73], v231
	ds_read_b64_tr_b16 v[74:75], v231 offset:512
	ds_read_b64_tr_b16 v[76:77], v231 offset:2048
	ds_read_b64_tr_b16 v[78:79], v231 offset:2560
	ds_read_b64_tr_b16 v[220:221], v231 offset:1024
	ds_read_b64_tr_b16 v[222:223], v231 offset:1536
	ds_read_b64_tr_b16 v[224:225], v231 offset:3072
	ds_read_b64_tr_b16 v[226:227], v231 offset:3584
	s_waitcnt vmcnt(8)
	ds_write_b128 v247, v[188:191]
	ds_write_b128 v247, v[192:195] offset:1024
	ds_write_b128 v247, v[196:199] offset:2048
	ds_write_b128 v247, v[200:203] offset:3072
	ds_read_b128 v[188:191], v248
	ds_read_b128 v[192:195], v249
	ds_read_b128 v[196:199], v250
	ds_read_b128 v[200:203], v251
	ds_write_b128 v112, v[204:207]
	ds_write_b128 v112, v[208:211] offset:1024
	ds_write_b128 v112, v[212:215] offset:2048
	ds_write_b128 v112, v[216:219] offset:3072
	v_mfma_f32_32x32x16_bf16 v[32:47], v[160:163], v[52:55], v[32:47]
	v_mfma_f32_32x32x16_bf16 v[32:47], v[164:167], v[56:59], v[32:47]
	v_mfma_f32_32x32x16_bf16 v[32:47], v[168:171], v[60:63], v[32:47]
	s_nop 11
	v_exp_f32_e32 v32, v32
	v_exp_f32_e32 v33, v33
	v_exp_f32_e32 v34, v34
	v_exp_f32_e32 v35, v35
	v_exp_f32_e32 v36, v36
	v_exp_f32_e32 v37, v37
	v_exp_f32_e32 v38, v38
	v_exp_f32_e32 v39, v39
	v_exp_f32_e32 v40, v40
	v_exp_f32_e32 v41, v41
	v_exp_f32_e32 v42, v42
	v_exp_f32_e32 v43, v43
	v_exp_f32_e32 v44, v44
	v_exp_f32_e32 v45, v45
	v_exp_f32_e32 v46, v46
	v_exp_f32_e32 v47, v47
	v_cvt_pk_bf16_f32 v64, v32, v33
	v_cvt_pk_bf16_f32 v65, v34, v35
	v_cvt_pk_bf16_f32 v66, v36, v37
	v_cvt_pk_bf16_f32 v67, v38, v39
	v_cvt_pk_bf16_f32 v68, v40, v41
	v_cvt_pk_bf16_f32 v69, v42, v43
	v_cvt_pk_bf16_f32 v70, v44, v45
	v_cvt_pk_bf16_f32 v71, v46, v47
	v_pk_add_f32 v[232:233], v[232:233], v[32:33]
	v_pk_add_f32 v[232:233], v[232:233], v[34:35]
	v_pk_add_f32 v[232:233], v[232:233], v[36:37]
	v_pk_add_f32 v[232:233], v[232:233], v[38:39]
	v_pk_add_f32 v[232:233], v[232:233], v[40:41]
	v_pk_add_f32 v[232:233], v[232:233], v[42:43]
	v_pk_add_f32 v[232:233], v[232:233], v[44:45]
	v_pk_add_f32 v[232:233], v[232:233], v[46:47]
	s_waitcnt lgkmcnt(12)
	v_mfma_f32_32x32x16_bf16 v[0:15], v[64:67], v[72:75], v[0:15]
	v_mfma_f32_32x32x16_bf16 v[16:31], v[64:67], v[76:79], v[16:31]
	v_mfma_f32_32x32x16_bf16 v[0:15], v[68:71], v[220:223], v[0:15]
	v_mfma_f32_32x32x16_bf16 v[16:31], v[68:71], v[224:227], v[16:31]
	global_load_dwordx4 v[156:159], v239, s[86:87]
	global_load_dwordx4 v[160:163], v240, s[86:87]
	global_load_dwordx4 v[164:167], v241, s[86:87]
	global_load_dwordx4 v[168:171], v242, s[86:87]
	global_load_dwordx4 v[172:175], v101, s[86:87] offset:768
	global_load_dwordx4 v[176:179], v150, s[86:87] offset:768
	global_load_dwordx4 v[180:183], v101, s[86:87] offset:832
	global_load_dwordx4 v[184:187], v150, s[86:87] offset:832
	s_add_u32 s86, s86, 0xc0000
	s_addc_u32 s87, s87, 0
	v_mov_b32_e32 v115, v229
	ds_read2_b32 v[32:33], v115 offset0:0 offset1:1
	ds_read2_b32 v[34:35], v115 offset0:2 offset1:3
	ds_read2_b32 v[36:37], v115 offset0:8 offset1:9
	ds_read2_b32 v[38:39], v115 offset0:10 offset1:11
	ds_read2_b32 v[40:41], v115 offset0:16 offset1:17
	ds_read2_b32 v[42:43], v115 offset0:18 offset1:19
	ds_read2_b32 v[44:45], v115 offset0:24 offset1:25
	ds_read2_b32 v[46:47], v115 offset0:26 offset1:27
	s_waitcnt lgkmcnt(0)
	v_mfma_f32_32x32x16_bf16 v[32:47], v[188:191], v[48:51], v[32:47]
	ds_read_b64_tr_b16 v[72:73], v231
	ds_read_b64_tr_b16 v[74:75], v231 offset:512
	ds_read_b64_tr_b16 v[76:77], v231 offset:2048
	ds_read_b64_tr_b16 v[78:79], v231 offset:2560
	ds_read_b64_tr_b16 v[220:221], v231 offset:1024
	ds_read_b64_tr_b16 v[222:223], v231 offset:1536
	ds_read_b64_tr_b16 v[224:225], v231 offset:3072
	ds_read_b64_tr_b16 v[226:227], v231 offset:3584
	s_waitcnt vmcnt(8)
	ds_write_b128 v247, v[116:119]
	ds_write_b128 v247, v[120:123] offset:1024
	ds_write_b128 v247, v[124:127] offset:2048
	ds_write_b128 v247, v[128:131] offset:3072
	ds_read_b128 v[116:119], v248
	ds_read_b128 v[120:123], v249
	ds_read_b128 v[124:127], v250
	ds_read_b128 v[128:131], v251
	ds_write_b128 v112, v[132:135]
	ds_write_b128 v112, v[136:139] offset:1024
	ds_write_b128 v112, v[140:143] offset:2048
	ds_write_b128 v112, v[144:147] offset:3072
	v_mfma_f32_32x32x16_bf16 v[32:47], v[192:195], v[52:55], v[32:47]
	v_mfma_f32_32x32x16_bf16 v[32:47], v[196:199], v[56:59], v[32:47]
	v_mfma_f32_32x32x16_bf16 v[32:47], v[200:203], v[60:63], v[32:47]
	s_nop 11
	v_exp_f32_e32 v32, v32
	v_exp_f32_e32 v33, v33
	v_exp_f32_e32 v34, v34
	v_exp_f32_e32 v35, v35
	v_exp_f32_e32 v36, v36
	v_exp_f32_e32 v37, v37
	v_exp_f32_e32 v38, v38
	v_exp_f32_e32 v39, v39
	v_exp_f32_e32 v40, v40
	v_exp_f32_e32 v41, v41
	v_exp_f32_e32 v42, v42
	v_exp_f32_e32 v43, v43
	v_exp_f32_e32 v44, v44
	v_exp_f32_e32 v45, v45
	v_exp_f32_e32 v46, v46
	v_exp_f32_e32 v47, v47
	v_cvt_pk_bf16_f32 v64, v32, v33
	v_cvt_pk_bf16_f32 v65, v34, v35
	v_cvt_pk_bf16_f32 v66, v36, v37
	v_cvt_pk_bf16_f32 v67, v38, v39
	v_cvt_pk_bf16_f32 v68, v40, v41
	v_cvt_pk_bf16_f32 v69, v42, v43
	v_cvt_pk_bf16_f32 v70, v44, v45
	v_cvt_pk_bf16_f32 v71, v46, v47
	v_pk_add_f32 v[232:233], v[232:233], v[32:33]
	v_pk_add_f32 v[232:233], v[232:233], v[34:35]
	v_pk_add_f32 v[232:233], v[232:233], v[36:37]
	v_pk_add_f32 v[232:233], v[232:233], v[38:39]
	v_pk_add_f32 v[232:233], v[232:233], v[40:41]
	v_pk_add_f32 v[232:233], v[232:233], v[42:43]
	v_pk_add_f32 v[232:233], v[232:233], v[44:45]
	v_pk_add_f32 v[232:233], v[232:233], v[46:47]
	s_waitcnt lgkmcnt(12)
	v_mfma_f32_32x32x16_bf16 v[0:15], v[64:67], v[72:75], v[0:15]
	v_mfma_f32_32x32x16_bf16 v[16:31], v[64:67], v[76:79], v[16:31]
	v_mfma_f32_32x32x16_bf16 v[0:15], v[68:71], v[220:223], v[0:15]
	v_mfma_f32_32x32x16_bf16 v[16:31], v[68:71], v[224:227], v[16:31]
	global_load_dwordx4 v[188:191], v239, s[86:87]
	global_load_dwordx4 v[192:195], v240, s[86:87]
	global_load_dwordx4 v[196:199], v241, s[86:87]
	global_load_dwordx4 v[200:203], v242, s[86:87]
	global_load_dwordx4 v[204:207], v101, s[86:87] offset:768
	global_load_dwordx4 v[208:211], v150, s[86:87] offset:768
	global_load_dwordx4 v[212:215], v101, s[86:87] offset:832
	global_load_dwordx4 v[216:219], v150, s[86:87] offset:832
	s_add_u32 s86, s86, 0xc0000
	s_addc_u32 s87, s87, 0
	ds_read2_b32 v[32:33], v115 offset0:32 offset1:33
	ds_read2_b32 v[34:35], v115 offset0:34 offset1:35
	ds_read2_b32 v[36:37], v115 offset0:40 offset1:41
	ds_read2_b32 v[38:39], v115 offset0:42 offset1:43
	ds_read2_b32 v[40:41], v115 offset0:48 offset1:49
	ds_read2_b32 v[42:43], v115 offset0:50 offset1:51
	ds_read2_b32 v[44:45], v115 offset0:56 offset1:57
	ds_read2_b32 v[46:47], v115 offset0:58 offset1:59
	s_waitcnt lgkmcnt(0)
	v_mfma_f32_32x32x16_bf16 v[32:47], v[116:119], v[48:51], v[32:47]
	ds_read_b64_tr_b16 v[72:73], v231
	ds_read_b64_tr_b16 v[74:75], v231 offset:512
	ds_read_b64_tr_b16 v[76:77], v231 offset:2048
	ds_read_b64_tr_b16 v[78:79], v231 offset:2560
	ds_read_b64_tr_b16 v[220:221], v231 offset:1024
	ds_read_b64_tr_b16 v[222:223], v231 offset:1536
	ds_read_b64_tr_b16 v[224:225], v231 offset:3072
	ds_read_b64_tr_b16 v[226:227], v231 offset:3584
	s_waitcnt vmcnt(8)
	ds_write_b128 v247, v[156:159]
	ds_write_b128 v247, v[160:163] offset:1024
	ds_write_b128 v247, v[164:167] offset:2048
	ds_write_b128 v247, v[168:171] offset:3072
	ds_read_b128 v[156:159], v248
	ds_read_b128 v[160:163], v249
	ds_read_b128 v[164:167], v250
	ds_read_b128 v[168:171], v251
	ds_write_b128 v112, v[172:175]
	ds_write_b128 v112, v[176:179] offset:1024
	ds_write_b128 v112, v[180:183] offset:2048
	ds_write_b128 v112, v[184:187] offset:3072
	v_mfma_f32_32x32x16_bf16 v[32:47], v[120:123], v[52:55], v[32:47]
	v_mfma_f32_32x32x16_bf16 v[32:47], v[124:127], v[56:59], v[32:47]
	v_mfma_f32_32x32x16_bf16 v[32:47], v[128:131], v[60:63], v[32:47]
	s_nop 11
	v_exp_f32_e32 v32, v32
	v_exp_f32_e32 v33, v33
	v_exp_f32_e32 v34, v34
	v_exp_f32_e32 v35, v35
	v_exp_f32_e32 v36, v36
	v_exp_f32_e32 v37, v37
	v_exp_f32_e32 v38, v38
	v_exp_f32_e32 v39, v39
	v_exp_f32_e32 v40, v40
	v_exp_f32_e32 v41, v41
	v_exp_f32_e32 v42, v42
	v_exp_f32_e32 v43, v43
	v_exp_f32_e32 v44, v44
	v_exp_f32_e32 v45, v45
	v_exp_f32_e32 v46, v46
	v_exp_f32_e32 v47, v47
	v_cvt_pk_bf16_f32 v64, v32, v33
	v_cvt_pk_bf16_f32 v65, v34, v35
	v_cvt_pk_bf16_f32 v66, v36, v37
	v_cvt_pk_bf16_f32 v67, v38, v39
	v_cvt_pk_bf16_f32 v68, v40, v41
	v_cvt_pk_bf16_f32 v69, v42, v43
	v_cvt_pk_bf16_f32 v70, v44, v45
	v_cvt_pk_bf16_f32 v71, v46, v47
	v_pk_add_f32 v[232:233], v[232:233], v[32:33]
	v_pk_add_f32 v[232:233], v[232:233], v[34:35]
	v_pk_add_f32 v[232:233], v[232:233], v[36:37]
	v_pk_add_f32 v[232:233], v[232:233], v[38:39]
	v_pk_add_f32 v[232:233], v[232:233], v[40:41]
	v_pk_add_f32 v[232:233], v[232:233], v[42:43]
	v_pk_add_f32 v[232:233], v[232:233], v[44:45]
	v_pk_add_f32 v[232:233], v[232:233], v[46:47]
	s_waitcnt lgkmcnt(12)
	v_mfma_f32_32x32x16_bf16 v[0:15], v[64:67], v[72:75], v[0:15]
	v_mfma_f32_32x32x16_bf16 v[16:31], v[64:67], v[76:79], v[16:31]
	v_mfma_f32_32x32x16_bf16 v[0:15], v[68:71], v[220:223], v[0:15]
	v_mfma_f32_32x32x16_bf16 v[16:31], v[68:71], v[224:227], v[16:31]
	global_load_dwordx4 v[116:119], v239, s[86:87]
	global_load_dwordx4 v[120:123], v240, s[86:87]
	global_load_dwordx4 v[124:127], v241, s[86:87]
	global_load_dwordx4 v[128:131], v242, s[86:87]
	global_load_dwordx4 v[132:135], v101, s[86:87] offset:768
	global_load_dwordx4 v[136:139], v150, s[86:87] offset:768
	global_load_dwordx4 v[140:143], v101, s[86:87] offset:832
	global_load_dwordx4 v[144:147], v150, s[86:87] offset:832
	s_add_u32 s86, s86, 0xc0000
	s_addc_u32 s87, s87, 0
	ds_read2_b32 v[32:33], v115 offset0:64 offset1:65
	ds_read2_b32 v[34:35], v115 offset0:66 offset1:67
	ds_read2_b32 v[36:37], v115 offset0:72 offset1:73
	ds_read2_b32 v[38:39], v115 offset0:74 offset1:75
	ds_read2_b32 v[40:41], v115 offset0:80 offset1:81
	ds_read2_b32 v[42:43], v115 offset0:82 offset1:83
	ds_read2_b32 v[44:45], v115 offset0:88 offset1:89
	ds_read2_b32 v[46:47], v115 offset0:90 offset1:91
	s_waitcnt lgkmcnt(0)
	v_mfma_f32_32x32x16_bf16 v[32:47], v[156:159], v[48:51], v[32:47]
	ds_read_b64_tr_b16 v[72:73], v231
	ds_read_b64_tr_b16 v[74:75], v231 offset:512
	ds_read_b64_tr_b16 v[76:77], v231 offset:2048
	ds_read_b64_tr_b16 v[78:79], v231 offset:2560
	ds_read_b64_tr_b16 v[220:221], v231 offset:1024
	ds_read_b64_tr_b16 v[222:223], v231 offset:1536
	ds_read_b64_tr_b16 v[224:225], v231 offset:3072
	ds_read_b64_tr_b16 v[226:227], v231 offset:3584
	s_waitcnt vmcnt(8)
	ds_write_b128 v247, v[188:191]
	ds_write_b128 v247, v[192:195] offset:1024
	ds_write_b128 v247, v[196:199] offset:2048
	ds_write_b128 v247, v[200:203] offset:3072
	ds_read_b128 v[188:191], v248
	ds_read_b128 v[192:195], v249
	ds_read_b128 v[196:199], v250
	ds_read_b128 v[200:203], v251
	ds_write_b128 v112, v[204:207]
	ds_write_b128 v112, v[208:211] offset:1024
	ds_write_b128 v112, v[212:215] offset:2048
	ds_write_b128 v112, v[216:219] offset:3072
	v_mfma_f32_32x32x16_bf16 v[32:47], v[160:163], v[52:55], v[32:47]
	v_mfma_f32_32x32x16_bf16 v[32:47], v[164:167], v[56:59], v[32:47]
	v_mfma_f32_32x32x16_bf16 v[32:47], v[168:171], v[60:63], v[32:47]
	s_nop 11
	v_exp_f32_e32 v32, v32
	v_exp_f32_e32 v33, v33
	v_exp_f32_e32 v34, v34
	v_exp_f32_e32 v35, v35
	v_exp_f32_e32 v36, v36
	v_exp_f32_e32 v37, v37
	v_exp_f32_e32 v38, v38
	v_exp_f32_e32 v39, v39
	v_exp_f32_e32 v40, v40
	v_exp_f32_e32 v41, v41
	v_exp_f32_e32 v42, v42
	v_exp_f32_e32 v43, v43
	v_exp_f32_e32 v44, v44
	v_exp_f32_e32 v45, v45
	v_exp_f32_e32 v46, v46
	v_exp_f32_e32 v47, v47
	v_cvt_pk_bf16_f32 v64, v32, v33
	v_cvt_pk_bf16_f32 v65, v34, v35
	v_cvt_pk_bf16_f32 v66, v36, v37
	v_cvt_pk_bf16_f32 v67, v38, v39
	v_cvt_pk_bf16_f32 v68, v40, v41
	v_cvt_pk_bf16_f32 v69, v42, v43
	v_cvt_pk_bf16_f32 v70, v44, v45
	v_cvt_pk_bf16_f32 v71, v46, v47
	v_pk_add_f32 v[232:233], v[232:233], v[32:33]
	v_pk_add_f32 v[232:233], v[232:233], v[34:35]
	v_pk_add_f32 v[232:233], v[232:233], v[36:37]
	v_pk_add_f32 v[232:233], v[232:233], v[38:39]
	v_pk_add_f32 v[232:233], v[232:233], v[40:41]
	v_pk_add_f32 v[232:233], v[232:233], v[42:43]
	v_pk_add_f32 v[232:233], v[232:233], v[44:45]
	v_pk_add_f32 v[232:233], v[232:233], v[46:47]
	s_waitcnt lgkmcnt(12)
	v_mfma_f32_32x32x16_bf16 v[0:15], v[64:67], v[72:75], v[0:15]
	v_mfma_f32_32x32x16_bf16 v[16:31], v[64:67], v[76:79], v[16:31]
	v_mfma_f32_32x32x16_bf16 v[0:15], v[68:71], v[220:223], v[0:15]
	v_mfma_f32_32x32x16_bf16 v[16:31], v[68:71], v[224:227], v[16:31]
	global_load_dwordx4 v[156:159], v239, s[86:87]
	global_load_dwordx4 v[160:163], v240, s[86:87]
	global_load_dwordx4 v[164:167], v241, s[86:87]
	global_load_dwordx4 v[168:171], v242, s[86:87]
	global_load_dwordx4 v[172:175], v101, s[86:87] offset:768
	global_load_dwordx4 v[176:179], v150, s[86:87] offset:768
	global_load_dwordx4 v[180:183], v101, s[86:87] offset:832
	global_load_dwordx4 v[184:187], v150, s[86:87] offset:832
	s_add_u32 s86, s86, 0xc0000
	s_addc_u32 s87, s87, 0
	ds_read2_b32 v[32:33], v115 offset0:96 offset1:97
	ds_read2_b32 v[34:35], v115 offset0:98 offset1:99
	ds_read2_b32 v[36:37], v115 offset0:104 offset1:105
	ds_read2_b32 v[38:39], v115 offset0:106 offset1:107
	ds_read2_b32 v[40:41], v115 offset0:112 offset1:113
	ds_read2_b32 v[42:43], v115 offset0:114 offset1:115
	ds_read2_b32 v[44:45], v115 offset0:120 offset1:121
	ds_read2_b32 v[46:47], v115 offset0:122 offset1:123
	s_waitcnt lgkmcnt(0)
	v_mfma_f32_32x32x16_bf16 v[32:47], v[188:191], v[48:51], v[32:47]
	ds_read_b64_tr_b16 v[72:73], v231
	ds_read_b64_tr_b16 v[74:75], v231 offset:512
	ds_read_b64_tr_b16 v[76:77], v231 offset:2048
	ds_read_b64_tr_b16 v[78:79], v231 offset:2560
	ds_read_b64_tr_b16 v[220:221], v231 offset:1024
	ds_read_b64_tr_b16 v[222:223], v231 offset:1536
	ds_read_b64_tr_b16 v[224:225], v231 offset:3072
	ds_read_b64_tr_b16 v[226:227], v231 offset:3584
	s_waitcnt vmcnt(8)
	ds_write_b128 v247, v[116:119]
	ds_write_b128 v247, v[120:123] offset:1024
	ds_write_b128 v247, v[124:127] offset:2048
	ds_write_b128 v247, v[128:131] offset:3072
	ds_read_b128 v[116:119], v248
	ds_read_b128 v[120:123], v249
	ds_read_b128 v[124:127], v250
	ds_read_b128 v[128:131], v251
	ds_write_b128 v112, v[132:135]
	ds_write_b128 v112, v[136:139] offset:1024
	ds_write_b128 v112, v[140:143] offset:2048
	ds_write_b128 v112, v[144:147] offset:3072
	v_mfma_f32_32x32x16_bf16 v[32:47], v[192:195], v[52:55], v[32:47]
	v_mfma_f32_32x32x16_bf16 v[32:47], v[196:199], v[56:59], v[32:47]
	v_mfma_f32_32x32x16_bf16 v[32:47], v[200:203], v[60:63], v[32:47]
	s_nop 11
	v_exp_f32_e32 v32, v32
	v_exp_f32_e32 v33, v33
	v_exp_f32_e32 v34, v34
	v_exp_f32_e32 v35, v35
	v_exp_f32_e32 v36, v36
	v_exp_f32_e32 v37, v37
	v_exp_f32_e32 v38, v38
	v_exp_f32_e32 v39, v39
	v_exp_f32_e32 v40, v40
	v_exp_f32_e32 v41, v41
	v_exp_f32_e32 v42, v42
	v_exp_f32_e32 v43, v43
	v_exp_f32_e32 v44, v44
	v_exp_f32_e32 v45, v45
	v_exp_f32_e32 v46, v46
	v_exp_f32_e32 v47, v47
	v_cvt_pk_bf16_f32 v64, v32, v33
	v_cvt_pk_bf16_f32 v65, v34, v35
	v_cvt_pk_bf16_f32 v66, v36, v37
	v_cvt_pk_bf16_f32 v67, v38, v39
	v_cvt_pk_bf16_f32 v68, v40, v41
	v_cvt_pk_bf16_f32 v69, v42, v43
	v_cvt_pk_bf16_f32 v70, v44, v45
	v_cvt_pk_bf16_f32 v71, v46, v47
	v_pk_add_f32 v[232:233], v[232:233], v[32:33]
	v_pk_add_f32 v[232:233], v[232:233], v[34:35]
	v_pk_add_f32 v[232:233], v[232:233], v[36:37]
	v_pk_add_f32 v[232:233], v[232:233], v[38:39]
	v_pk_add_f32 v[232:233], v[232:233], v[40:41]
	v_pk_add_f32 v[232:233], v[232:233], v[42:43]
	v_pk_add_f32 v[232:233], v[232:233], v[44:45]
	v_pk_add_f32 v[232:233], v[232:233], v[46:47]
	s_waitcnt lgkmcnt(12)
	v_mfma_f32_32x32x16_bf16 v[0:15], v[64:67], v[72:75], v[0:15]
	v_mfma_f32_32x32x16_bf16 v[16:31], v[64:67], v[76:79], v[16:31]
	v_mfma_f32_32x32x16_bf16 v[0:15], v[68:71], v[220:223], v[0:15]
	v_mfma_f32_32x32x16_bf16 v[16:31], v[68:71], v[224:227], v[16:31]
	global_load_dwordx4 v[188:191], v239, s[86:87]
	global_load_dwordx4 v[192:195], v240, s[86:87]
	global_load_dwordx4 v[196:199], v241, s[86:87]
	global_load_dwordx4 v[200:203], v242, s[86:87]
	global_load_dwordx4 v[204:207], v101, s[86:87] offset:768
	global_load_dwordx4 v[208:211], v150, s[86:87] offset:768
	global_load_dwordx4 v[212:215], v101, s[86:87] offset:832
	global_load_dwordx4 v[216:219], v150, s[86:87] offset:832
	s_add_u32 s86, s86, 0xc0000
	s_addc_u32 s87, s87, 0
	ds_read2_b32 v[32:33], v115 offset0:128 offset1:129
	ds_read2_b32 v[34:35], v115 offset0:130 offset1:131
	ds_read2_b32 v[36:37], v115 offset0:136 offset1:137
	ds_read2_b32 v[38:39], v115 offset0:138 offset1:139
	ds_read2_b32 v[40:41], v115 offset0:144 offset1:145
	ds_read2_b32 v[42:43], v115 offset0:146 offset1:147
	ds_read2_b32 v[44:45], v115 offset0:152 offset1:153
	ds_read2_b32 v[46:47], v115 offset0:154 offset1:155
	s_waitcnt lgkmcnt(0)
	v_mfma_f32_32x32x16_bf16 v[32:47], v[116:119], v[48:51], v[32:47]
	ds_read_b64_tr_b16 v[72:73], v231
	ds_read_b64_tr_b16 v[74:75], v231 offset:512
	ds_read_b64_tr_b16 v[76:77], v231 offset:2048
	ds_read_b64_tr_b16 v[78:79], v231 offset:2560
	ds_read_b64_tr_b16 v[220:221], v231 offset:1024
	ds_read_b64_tr_b16 v[222:223], v231 offset:1536
	ds_read_b64_tr_b16 v[224:225], v231 offset:3072
	ds_read_b64_tr_b16 v[226:227], v231 offset:3584
	s_waitcnt vmcnt(8)
	ds_write_b128 v247, v[156:159]
	ds_write_b128 v247, v[160:163] offset:1024
	ds_write_b128 v247, v[164:167] offset:2048
	ds_write_b128 v247, v[168:171] offset:3072
	ds_read_b128 v[156:159], v248
	ds_read_b128 v[160:163], v249
	ds_read_b128 v[164:167], v250
	ds_read_b128 v[168:171], v251
	ds_write_b128 v112, v[172:175]
	ds_write_b128 v112, v[176:179] offset:1024
	ds_write_b128 v112, v[180:183] offset:2048
	ds_write_b128 v112, v[184:187] offset:3072
	v_mfma_f32_32x32x16_bf16 v[32:47], v[120:123], v[52:55], v[32:47]
	v_mfma_f32_32x32x16_bf16 v[32:47], v[124:127], v[56:59], v[32:47]
	v_mfma_f32_32x32x16_bf16 v[32:47], v[128:131], v[60:63], v[32:47]
	s_nop 11
	v_exp_f32_e32 v32, v32
	v_exp_f32_e32 v33, v33
	v_exp_f32_e32 v34, v34
	v_exp_f32_e32 v35, v35
	v_exp_f32_e32 v36, v36
	v_exp_f32_e32 v37, v37
	v_exp_f32_e32 v38, v38
	v_exp_f32_e32 v39, v39
	v_exp_f32_e32 v40, v40
	v_exp_f32_e32 v41, v41
	v_exp_f32_e32 v42, v42
	v_exp_f32_e32 v43, v43
	v_exp_f32_e32 v44, v44
	v_exp_f32_e32 v45, v45
	v_exp_f32_e32 v46, v46
	v_exp_f32_e32 v47, v47
	v_cvt_pk_bf16_f32 v64, v32, v33
	v_cvt_pk_bf16_f32 v65, v34, v35
	v_cvt_pk_bf16_f32 v66, v36, v37
	v_cvt_pk_bf16_f32 v67, v38, v39
	v_cvt_pk_bf16_f32 v68, v40, v41
	v_cvt_pk_bf16_f32 v69, v42, v43
	v_cvt_pk_bf16_f32 v70, v44, v45
	v_cvt_pk_bf16_f32 v71, v46, v47
	v_pk_add_f32 v[232:233], v[232:233], v[32:33]
	v_pk_add_f32 v[232:233], v[232:233], v[34:35]
	v_pk_add_f32 v[232:233], v[232:233], v[36:37]
	v_pk_add_f32 v[232:233], v[232:233], v[38:39]
	v_pk_add_f32 v[232:233], v[232:233], v[40:41]
	v_pk_add_f32 v[232:233], v[232:233], v[42:43]
	v_pk_add_f32 v[232:233], v[232:233], v[44:45]
	v_pk_add_f32 v[232:233], v[232:233], v[46:47]
	s_waitcnt lgkmcnt(12)
	v_mfma_f32_32x32x16_bf16 v[0:15], v[64:67], v[72:75], v[0:15]
	v_mfma_f32_32x32x16_bf16 v[16:31], v[64:67], v[76:79], v[16:31]
	v_mfma_f32_32x32x16_bf16 v[0:15], v[68:71], v[220:223], v[0:15]
	v_mfma_f32_32x32x16_bf16 v[16:31], v[68:71], v[224:227], v[16:31]
	global_load_dwordx4 v[116:119], v239, s[86:87]
	global_load_dwordx4 v[120:123], v240, s[86:87]
	global_load_dwordx4 v[124:127], v241, s[86:87]
	global_load_dwordx4 v[128:131], v242, s[86:87]
	global_load_dwordx4 v[132:135], v101, s[86:87] offset:768
	global_load_dwordx4 v[136:139], v150, s[86:87] offset:768
	global_load_dwordx4 v[140:143], v101, s[86:87] offset:832
	global_load_dwordx4 v[144:147], v150, s[86:87] offset:832
	ds_read2_b32 v[32:33], v115 offset0:160 offset1:161
	ds_read2_b32 v[34:35], v115 offset0:162 offset1:163
	ds_read2_b32 v[36:37], v115 offset0:168 offset1:169
	ds_read2_b32 v[38:39], v115 offset0:170 offset1:171
	ds_read2_b32 v[40:41], v115 offset0:176 offset1:177
	ds_read2_b32 v[42:43], v115 offset0:178 offset1:179
	ds_read2_b32 v[44:45], v115 offset0:184 offset1:185
	ds_read2_b32 v[46:47], v115 offset0:186 offset1:187
	s_waitcnt lgkmcnt(0)
	v_mfma_f32_32x32x16_bf16 v[32:47], v[156:159], v[48:51], v[32:47]
	ds_read_b64_tr_b16 v[72:73], v231
	ds_read_b64_tr_b16 v[74:75], v231 offset:512
	ds_read_b64_tr_b16 v[76:77], v231 offset:2048
	ds_read_b64_tr_b16 v[78:79], v231 offset:2560
	ds_read_b64_tr_b16 v[220:221], v231 offset:1024
	ds_read_b64_tr_b16 v[222:223], v231 offset:1536
	ds_read_b64_tr_b16 v[224:225], v231 offset:3072
	ds_read_b64_tr_b16 v[226:227], v231 offset:3584
	s_waitcnt vmcnt(8)
	ds_write_b128 v247, v[188:191]
	ds_write_b128 v247, v[192:195] offset:1024
	ds_write_b128 v247, v[196:199] offset:2048
	ds_write_b128 v247, v[200:203] offset:3072
	ds_read_b128 v[188:191], v248
	ds_read_b128 v[192:195], v249
	ds_read_b128 v[196:199], v250
	ds_read_b128 v[200:203], v251
	ds_write_b128 v112, v[204:207]
	ds_write_b128 v112, v[208:211] offset:1024
	ds_write_b128 v112, v[212:215] offset:2048
	ds_write_b128 v112, v[216:219] offset:3072
	v_mfma_f32_32x32x16_bf16 v[32:47], v[160:163], v[52:55], v[32:47]
	v_mfma_f32_32x32x16_bf16 v[32:47], v[164:167], v[56:59], v[32:47]
	v_mfma_f32_32x32x16_bf16 v[32:47], v[168:171], v[60:63], v[32:47]
	s_nop 11
	v_exp_f32_e32 v32, v32
	v_exp_f32_e32 v33, v33
	v_exp_f32_e32 v34, v34
	v_exp_f32_e32 v35, v35
	v_exp_f32_e32 v36, v36
	v_exp_f32_e32 v37, v37
	v_exp_f32_e32 v38, v38
	v_exp_f32_e32 v39, v39
	v_exp_f32_e32 v40, v40
	v_exp_f32_e32 v41, v41
	v_exp_f32_e32 v42, v42
	v_exp_f32_e32 v43, v43
	v_exp_f32_e32 v44, v44
	v_exp_f32_e32 v45, v45
	v_exp_f32_e32 v46, v46
	v_exp_f32_e32 v47, v47
	v_cvt_pk_bf16_f32 v64, v32, v33
	v_cvt_pk_bf16_f32 v65, v34, v35
	v_cvt_pk_bf16_f32 v66, v36, v37
	v_cvt_pk_bf16_f32 v67, v38, v39
	v_cvt_pk_bf16_f32 v68, v40, v41
	v_cvt_pk_bf16_f32 v69, v42, v43
	v_cvt_pk_bf16_f32 v70, v44, v45
	v_cvt_pk_bf16_f32 v71, v46, v47
	v_pk_add_f32 v[232:233], v[232:233], v[32:33]
	v_pk_add_f32 v[232:233], v[232:233], v[34:35]
	v_pk_add_f32 v[232:233], v[232:233], v[36:37]
	v_pk_add_f32 v[232:233], v[232:233], v[38:39]
	v_pk_add_f32 v[232:233], v[232:233], v[40:41]
	v_pk_add_f32 v[232:233], v[232:233], v[42:43]
	v_pk_add_f32 v[232:233], v[232:233], v[44:45]
	v_pk_add_f32 v[232:233], v[232:233], v[46:47]
	s_waitcnt lgkmcnt(12)
	v_mfma_f32_32x32x16_bf16 v[0:15], v[64:67], v[72:75], v[0:15]
	v_mfma_f32_32x32x16_bf16 v[16:31], v[64:67], v[76:79], v[16:31]
	v_mfma_f32_32x32x16_bf16 v[0:15], v[68:71], v[220:223], v[0:15]
	v_mfma_f32_32x32x16_bf16 v[16:31], v[68:71], v[224:227], v[16:31]
	global_load_dwordx4 v[156:159], v243, s[88:89]
	global_load_dwordx4 v[160:163], v244, s[88:89]
	global_load_dwordx4 v[164:167], v245, s[88:89]
	global_load_dwordx4 v[168:171], v246, s[88:89]
	global_load_dwordx4 v[172:175], v148, s[88:89] offset:768
	global_load_dwordx4 v[176:179], v151, s[88:89] offset:768
	global_load_dwordx4 v[180:183], v148, s[88:89] offset:832
	global_load_dwordx4 v[184:187], v151, s[88:89] offset:832
	s_add_u32 s88, s88, 0x300000
	s_addc_u32 s89, s89, 0
	ds_read2_b32 v[32:33], v115 offset0:192 offset1:193
	ds_read2_b32 v[34:35], v115 offset0:194 offset1:195
	ds_read2_b32 v[36:37], v115 offset0:200 offset1:201
	ds_read2_b32 v[38:39], v115 offset0:202 offset1:203
	ds_read2_b32 v[40:41], v115 offset0:208 offset1:209
	ds_read2_b32 v[42:43], v115 offset0:210 offset1:211
	ds_read2_b32 v[44:45], v115 offset0:216 offset1:217
	ds_read2_b32 v[46:47], v115 offset0:218 offset1:219
	s_waitcnt lgkmcnt(0)
	v_mfma_f32_32x32x16_bf16 v[32:47], v[188:191], v[48:51], v[32:47]
	ds_read_b64_tr_b16 v[72:73], v231
	ds_read_b64_tr_b16 v[74:75], v231 offset:512
	ds_read_b64_tr_b16 v[76:77], v231 offset:2048
	ds_read_b64_tr_b16 v[78:79], v231 offset:2560
	ds_read_b64_tr_b16 v[220:221], v231 offset:1024
	ds_read_b64_tr_b16 v[222:223], v231 offset:1536
	ds_read_b64_tr_b16 v[224:225], v231 offset:3072
	ds_read_b64_tr_b16 v[226:227], v231 offset:3584
	s_waitcnt vmcnt(8)
	ds_write_b128 v247, v[116:119]
	ds_write_b128 v247, v[120:123] offset:1024
	ds_write_b128 v247, v[124:127] offset:2048
	ds_write_b128 v247, v[128:131] offset:3072
	ds_read_b128 v[116:119], v248
	ds_read_b128 v[120:123], v249
	ds_read_b128 v[124:127], v250
	ds_read_b128 v[128:131], v251
	ds_write_b128 v112, v[132:135]
	ds_write_b128 v112, v[136:139] offset:1024
	ds_write_b128 v112, v[140:143] offset:2048
	ds_write_b128 v112, v[144:147] offset:3072
	v_mfma_f32_32x32x16_bf16 v[32:47], v[192:195], v[52:55], v[32:47]
	v_mfma_f32_32x32x16_bf16 v[32:47], v[196:199], v[56:59], v[32:47]
	v_mfma_f32_32x32x16_bf16 v[32:47], v[200:203], v[60:63], v[32:47]
	s_nop 11
	v_exp_f32_e32 v32, v32
	v_exp_f32_e32 v33, v33
	v_exp_f32_e32 v34, v34
	v_exp_f32_e32 v35, v35
	v_exp_f32_e32 v36, v36
	v_exp_f32_e32 v37, v37
	v_exp_f32_e32 v38, v38
	v_exp_f32_e32 v39, v39
	v_exp_f32_e32 v40, v40
	v_exp_f32_e32 v41, v41
	v_exp_f32_e32 v42, v42
	v_exp_f32_e32 v43, v43
	v_exp_f32_e32 v44, v44
	v_exp_f32_e32 v45, v45
	v_exp_f32_e32 v46, v46
	v_exp_f32_e32 v47, v47
	v_cvt_pk_bf16_f32 v64, v32, v33
	v_cvt_pk_bf16_f32 v65, v34, v35
	v_cvt_pk_bf16_f32 v66, v36, v37
	v_cvt_pk_bf16_f32 v67, v38, v39
	v_cvt_pk_bf16_f32 v68, v40, v41
	v_cvt_pk_bf16_f32 v69, v42, v43
	v_cvt_pk_bf16_f32 v70, v44, v45
	v_cvt_pk_bf16_f32 v71, v46, v47
	v_pk_add_f32 v[232:233], v[232:233], v[32:33]
	v_pk_add_f32 v[232:233], v[232:233], v[34:35]
	v_pk_add_f32 v[232:233], v[232:233], v[36:37]
	v_pk_add_f32 v[232:233], v[232:233], v[38:39]
	v_pk_add_f32 v[232:233], v[232:233], v[40:41]
	v_pk_add_f32 v[232:233], v[232:233], v[42:43]
	v_pk_add_f32 v[232:233], v[232:233], v[44:45]
	v_pk_add_f32 v[232:233], v[232:233], v[46:47]
	s_waitcnt lgkmcnt(12)
	v_mfma_f32_32x32x16_bf16 v[0:15], v[64:67], v[72:75], v[0:15]
	v_mfma_f32_32x32x16_bf16 v[16:31], v[64:67], v[76:79], v[16:31]
	v_mfma_f32_32x32x16_bf16 v[0:15], v[68:71], v[220:223], v[0:15]
	v_mfma_f32_32x32x16_bf16 v[16:31], v[68:71], v[224:227], v[16:31]
	global_load_dwordx4 v[188:191], v243, s[88:89]
	global_load_dwordx4 v[192:195], v244, s[88:89]
	global_load_dwordx4 v[196:199], v245, s[88:89]
	global_load_dwordx4 v[200:203], v246, s[88:89]
	global_load_dwordx4 v[204:207], v148, s[88:89] offset:768
	global_load_dwordx4 v[208:211], v151, s[88:89] offset:768
	global_load_dwordx4 v[212:215], v148, s[88:89] offset:832
	global_load_dwordx4 v[216:219], v151, s[88:89] offset:832
	s_add_u32 s88, s88, 0x300000
	s_addc_u32 s89, s89, 0
	ds_read2_b32 v[32:33], v115 offset0:224 offset1:225
	ds_read2_b32 v[34:35], v115 offset0:226 offset1:227
	ds_read2_b32 v[36:37], v115 offset0:232 offset1:233
	ds_read2_b32 v[38:39], v115 offset0:234 offset1:235
	ds_read2_b32 v[40:41], v115 offset0:240 offset1:241
	ds_read2_b32 v[42:43], v115 offset0:242 offset1:243
	ds_read2_b32 v[44:45], v115 offset0:248 offset1:249
	ds_read2_b32 v[46:47], v115 offset0:250 offset1:251
	s_waitcnt lgkmcnt(0)
	v_mfma_f32_32x32x16_bf16 v[32:47], v[116:119], v[48:51], v[32:47]
	ds_read_b64_tr_b16 v[72:73], v231
	ds_read_b64_tr_b16 v[74:75], v231 offset:512
	ds_read_b64_tr_b16 v[76:77], v231 offset:2048
	ds_read_b64_tr_b16 v[78:79], v231 offset:2560
	ds_read_b64_tr_b16 v[220:221], v231 offset:1024
	ds_read_b64_tr_b16 v[222:223], v231 offset:1536
	ds_read_b64_tr_b16 v[224:225], v231 offset:3072
	ds_read_b64_tr_b16 v[226:227], v231 offset:3584
	s_waitcnt vmcnt(8)
	ds_write_b128 v247, v[156:159]
	ds_write_b128 v247, v[160:163] offset:1024
	ds_write_b128 v247, v[164:167] offset:2048
	ds_write_b128 v247, v[168:171] offset:3072
	ds_read_b128 v[156:159], v248
	ds_read_b128 v[160:163], v249
	ds_read_b128 v[164:167], v250
	ds_read_b128 v[168:171], v251
	ds_write_b128 v112, v[172:175]
	ds_write_b128 v112, v[176:179] offset:1024
	ds_write_b128 v112, v[180:183] offset:2048
	ds_write_b128 v112, v[184:187] offset:3072
	v_mfma_f32_32x32x16_bf16 v[32:47], v[120:123], v[52:55], v[32:47]
	v_mfma_f32_32x32x16_bf16 v[32:47], v[124:127], v[56:59], v[32:47]
	v_mfma_f32_32x32x16_bf16 v[32:47], v[128:131], v[60:63], v[32:47]
	s_nop 11
	v_exp_f32_e32 v32, v32
	v_exp_f32_e32 v33, v33
	v_exp_f32_e32 v34, v34
	v_exp_f32_e32 v35, v35
	v_exp_f32_e32 v36, v36
	v_exp_f32_e32 v37, v37
	v_exp_f32_e32 v38, v38
	v_exp_f32_e32 v39, v39
	v_exp_f32_e32 v40, v40
	v_exp_f32_e32 v41, v41
	v_exp_f32_e32 v42, v42
	v_exp_f32_e32 v43, v43
	v_exp_f32_e32 v44, v44
	v_exp_f32_e32 v45, v45
	v_exp_f32_e32 v46, v46
	v_exp_f32_e32 v47, v47
	v_cvt_pk_bf16_f32 v64, v32, v33
	v_cvt_pk_bf16_f32 v65, v34, v35
	v_cvt_pk_bf16_f32 v66, v36, v37
	v_cvt_pk_bf16_f32 v67, v38, v39
	v_cvt_pk_bf16_f32 v68, v40, v41
	v_cvt_pk_bf16_f32 v69, v42, v43
	v_cvt_pk_bf16_f32 v70, v44, v45
	v_cvt_pk_bf16_f32 v71, v46, v47
	v_pk_add_f32 v[232:233], v[232:233], v[32:33]
	v_pk_add_f32 v[232:233], v[232:233], v[34:35]
	v_pk_add_f32 v[232:233], v[232:233], v[36:37]
	v_pk_add_f32 v[232:233], v[232:233], v[38:39]
	v_pk_add_f32 v[232:233], v[232:233], v[40:41]
	v_pk_add_f32 v[232:233], v[232:233], v[42:43]
	v_pk_add_f32 v[232:233], v[232:233], v[44:45]
	v_pk_add_f32 v[232:233], v[232:233], v[46:47]
	s_waitcnt lgkmcnt(12)
	v_mfma_f32_32x32x16_bf16 v[0:15], v[64:67], v[72:75], v[0:15]
	v_mfma_f32_32x32x16_bf16 v[16:31], v[64:67], v[76:79], v[16:31]
	v_mfma_f32_32x32x16_bf16 v[0:15], v[68:71], v[220:223], v[0:15]
	v_mfma_f32_32x32x16_bf16 v[16:31], v[68:71], v[224:227], v[16:31]
	global_load_dwordx4 v[116:119], v243, s[88:89]
	global_load_dwordx4 v[120:123], v244, s[88:89]
	global_load_dwordx4 v[124:127], v245, s[88:89]
	global_load_dwordx4 v[128:131], v246, s[88:89]
	global_load_dwordx4 v[132:135], v148, s[88:89] offset:768
	global_load_dwordx4 v[136:139], v151, s[88:89] offset:768
	global_load_dwordx4 v[140:143], v148, s[88:89] offset:832
	global_load_dwordx4 v[144:147], v151, s[88:89] offset:832
	s_add_u32 s88, s88, 0x300000
	s_addc_u32 s89, s89, 0
	v_mov_b32_e32 v115, v230
	ds_read2_b32 v[32:33], v115 offset0:0 offset1:1
	ds_read2_b32 v[34:35], v115 offset0:2 offset1:3
	ds_read2_b32 v[36:37], v115 offset0:8 offset1:9
	ds_read2_b32 v[38:39], v115 offset0:10 offset1:11
	ds_read2_b32 v[40:41], v115 offset0:16 offset1:17
	ds_read2_b32 v[42:43], v115 offset0:18 offset1:19
	ds_read2_b32 v[44:45], v115 offset0:24 offset1:25
	ds_read2_b32 v[46:47], v115 offset0:26 offset1:27
	s_waitcnt lgkmcnt(0)
	v_mfma_f32_32x32x16_bf16 v[32:47], v[156:159], v[48:51], v[32:47]
	ds_read_b64_tr_b16 v[72:73], v231
	ds_read_b64_tr_b16 v[74:75], v231 offset:512
	ds_read_b64_tr_b16 v[76:77], v231 offset:2048
	ds_read_b64_tr_b16 v[78:79], v231 offset:2560
	ds_read_b64_tr_b16 v[220:221], v231 offset:1024
	ds_read_b64_tr_b16 v[222:223], v231 offset:1536
	ds_read_b64_tr_b16 v[224:225], v231 offset:3072
	ds_read_b64_tr_b16 v[226:227], v231 offset:3584
	s_waitcnt vmcnt(8)
	ds_write_b128 v247, v[188:191]
	ds_write_b128 v247, v[192:195] offset:1024
	ds_write_b128 v247, v[196:199] offset:2048
	ds_write_b128 v247, v[200:203] offset:3072
	ds_read_b128 v[188:191], v248
	ds_read_b128 v[192:195], v249
	ds_read_b128 v[196:199], v250
	ds_read_b128 v[200:203], v251
	ds_write_b128 v112, v[204:207]
	ds_write_b128 v112, v[208:211] offset:1024
	ds_write_b128 v112, v[212:215] offset:2048
	ds_write_b128 v112, v[216:219] offset:3072
	v_mfma_f32_32x32x16_bf16 v[32:47], v[160:163], v[52:55], v[32:47]
	v_mfma_f32_32x32x16_bf16 v[32:47], v[164:167], v[56:59], v[32:47]
	v_mfma_f32_32x32x16_bf16 v[32:47], v[168:171], v[60:63], v[32:47]
	s_nop 11
	v_exp_f32_e32 v32, v32
	v_exp_f32_e32 v33, v33
	v_exp_f32_e32 v34, v34
	v_exp_f32_e32 v35, v35
	v_exp_f32_e32 v36, v36
	v_exp_f32_e32 v37, v37
	v_exp_f32_e32 v38, v38
	v_exp_f32_e32 v39, v39
	v_exp_f32_e32 v40, v40
	v_exp_f32_e32 v41, v41
	v_exp_f32_e32 v42, v42
	v_exp_f32_e32 v43, v43
	v_exp_f32_e32 v44, v44
	v_exp_f32_e32 v45, v45
	v_exp_f32_e32 v46, v46
	v_exp_f32_e32 v47, v47
	v_cvt_pk_bf16_f32 v64, v32, v33
	v_cvt_pk_bf16_f32 v65, v34, v35
	v_cvt_pk_bf16_f32 v66, v36, v37
	v_cvt_pk_bf16_f32 v67, v38, v39
	v_cvt_pk_bf16_f32 v68, v40, v41
	v_cvt_pk_bf16_f32 v69, v42, v43
	v_cvt_pk_bf16_f32 v70, v44, v45
	v_cvt_pk_bf16_f32 v71, v46, v47
	v_pk_add_f32 v[232:233], v[232:233], v[32:33]
	v_pk_add_f32 v[232:233], v[232:233], v[34:35]
	v_pk_add_f32 v[232:233], v[232:233], v[36:37]
	v_pk_add_f32 v[232:233], v[232:233], v[38:39]
	v_pk_add_f32 v[232:233], v[232:233], v[40:41]
	v_pk_add_f32 v[232:233], v[232:233], v[42:43]
	v_pk_add_f32 v[232:233], v[232:233], v[44:45]
	v_pk_add_f32 v[232:233], v[232:233], v[46:47]
	s_waitcnt lgkmcnt(12)
	v_mfma_f32_32x32x16_bf16 v[0:15], v[64:67], v[72:75], v[0:15]
	v_mfma_f32_32x32x16_bf16 v[16:31], v[64:67], v[76:79], v[16:31]
	v_mfma_f32_32x32x16_bf16 v[0:15], v[68:71], v[220:223], v[0:15]
	v_mfma_f32_32x32x16_bf16 v[16:31], v[68:71], v[224:227], v[16:31]
	global_load_dwordx4 v[156:159], v243, s[88:89]
	global_load_dwordx4 v[160:163], v244, s[88:89]
	global_load_dwordx4 v[164:167], v245, s[88:89]
	global_load_dwordx4 v[168:171], v246, s[88:89]
	global_load_dwordx4 v[172:175], v148, s[88:89] offset:768
	global_load_dwordx4 v[176:179], v151, s[88:89] offset:768
	global_load_dwordx4 v[180:183], v148, s[88:89] offset:832
	global_load_dwordx4 v[184:187], v151, s[88:89] offset:832
	s_add_u32 s88, s88, 0x300000
	s_addc_u32 s89, s89, 0
	ds_read2_b32 v[32:33], v115 offset0:32 offset1:33
	ds_read2_b32 v[34:35], v115 offset0:34 offset1:35
	ds_read2_b32 v[36:37], v115 offset0:40 offset1:41
	ds_read2_b32 v[38:39], v115 offset0:42 offset1:43
	ds_read2_b32 v[40:41], v115 offset0:48 offset1:49
	ds_read2_b32 v[42:43], v115 offset0:50 offset1:51
	ds_read2_b32 v[44:45], v115 offset0:56 offset1:57
	ds_read2_b32 v[46:47], v115 offset0:58 offset1:59
	s_waitcnt lgkmcnt(0)
	v_mfma_f32_32x32x16_bf16 v[32:47], v[188:191], v[48:51], v[32:47]
	ds_read_b64_tr_b16 v[72:73], v231
	ds_read_b64_tr_b16 v[74:75], v231 offset:512
	ds_read_b64_tr_b16 v[76:77], v231 offset:2048
	ds_read_b64_tr_b16 v[78:79], v231 offset:2560
	ds_read_b64_tr_b16 v[220:221], v231 offset:1024
	ds_read_b64_tr_b16 v[222:223], v231 offset:1536
	ds_read_b64_tr_b16 v[224:225], v231 offset:3072
	ds_read_b64_tr_b16 v[226:227], v231 offset:3584
	s_waitcnt vmcnt(8)
	ds_write_b128 v247, v[116:119]
	ds_write_b128 v247, v[120:123] offset:1024
	ds_write_b128 v247, v[124:127] offset:2048
	ds_write_b128 v247, v[128:131] offset:3072
	ds_read_b128 v[116:119], v248
	ds_read_b128 v[120:123], v249
	ds_read_b128 v[124:127], v250
	ds_read_b128 v[128:131], v251
	ds_write_b128 v112, v[132:135]
	ds_write_b128 v112, v[136:139] offset:1024
	ds_write_b128 v112, v[140:143] offset:2048
	ds_write_b128 v112, v[144:147] offset:3072
	v_mfma_f32_32x32x16_bf16 v[32:47], v[192:195], v[52:55], v[32:47]
	v_mfma_f32_32x32x16_bf16 v[32:47], v[196:199], v[56:59], v[32:47]
	v_mfma_f32_32x32x16_bf16 v[32:47], v[200:203], v[60:63], v[32:47]
	s_nop 11
	v_exp_f32_e32 v32, v32
	v_exp_f32_e32 v33, v33
	v_exp_f32_e32 v34, v34
	v_exp_f32_e32 v35, v35
	v_exp_f32_e32 v36, v36
	v_exp_f32_e32 v37, v37
	v_exp_f32_e32 v38, v38
	v_exp_f32_e32 v39, v39
	v_exp_f32_e32 v40, v40
	v_exp_f32_e32 v41, v41
	v_exp_f32_e32 v42, v42
	v_exp_f32_e32 v43, v43
	v_exp_f32_e32 v44, v44
	v_exp_f32_e32 v45, v45
	v_exp_f32_e32 v46, v46
	v_exp_f32_e32 v47, v47
	v_cvt_pk_bf16_f32 v64, v32, v33
	v_cvt_pk_bf16_f32 v65, v34, v35
	v_cvt_pk_bf16_f32 v66, v36, v37
	v_cvt_pk_bf16_f32 v67, v38, v39
	v_cvt_pk_bf16_f32 v68, v40, v41
	v_cvt_pk_bf16_f32 v69, v42, v43
	v_cvt_pk_bf16_f32 v70, v44, v45
	v_cvt_pk_bf16_f32 v71, v46, v47
	v_pk_add_f32 v[232:233], v[232:233], v[32:33]
	v_pk_add_f32 v[232:233], v[232:233], v[34:35]
	v_pk_add_f32 v[232:233], v[232:233], v[36:37]
	v_pk_add_f32 v[232:233], v[232:233], v[38:39]
	v_pk_add_f32 v[232:233], v[232:233], v[40:41]
	v_pk_add_f32 v[232:233], v[232:233], v[42:43]
	v_pk_add_f32 v[232:233], v[232:233], v[44:45]
	v_pk_add_f32 v[232:233], v[232:233], v[46:47]
	s_waitcnt lgkmcnt(12)
	v_mfma_f32_32x32x16_bf16 v[0:15], v[64:67], v[72:75], v[0:15]
	v_mfma_f32_32x32x16_bf16 v[16:31], v[64:67], v[76:79], v[16:31]
	v_mfma_f32_32x32x16_bf16 v[0:15], v[68:71], v[220:223], v[0:15]
	v_mfma_f32_32x32x16_bf16 v[16:31], v[68:71], v[224:227], v[16:31]
	global_load_dwordx4 v[188:191], v243, s[88:89]
	global_load_dwordx4 v[192:195], v244, s[88:89]
	global_load_dwordx4 v[196:199], v245, s[88:89]
	global_load_dwordx4 v[200:203], v246, s[88:89]
	global_load_dwordx4 v[204:207], v148, s[88:89] offset:768
	global_load_dwordx4 v[208:211], v151, s[88:89] offset:768
	global_load_dwordx4 v[212:215], v148, s[88:89] offset:832
	global_load_dwordx4 v[216:219], v151, s[88:89] offset:832
	ds_read2_b32 v[32:33], v115 offset0:64 offset1:65
	ds_read2_b32 v[34:35], v115 offset0:66 offset1:67
	ds_read2_b32 v[36:37], v115 offset0:72 offset1:73
	ds_read2_b32 v[38:39], v115 offset0:74 offset1:75
	ds_read2_b32 v[40:41], v115 offset0:80 offset1:81
	ds_read2_b32 v[42:43], v115 offset0:82 offset1:83
	ds_read2_b32 v[44:45], v115 offset0:88 offset1:89
	ds_read2_b32 v[46:47], v115 offset0:90 offset1:91
	s_waitcnt lgkmcnt(0)
	v_mfma_f32_32x32x16_bf16 v[32:47], v[116:119], v[48:51], v[32:47]
	ds_read_b64_tr_b16 v[72:73], v231
	ds_read_b64_tr_b16 v[74:75], v231 offset:512
	ds_read_b64_tr_b16 v[76:77], v231 offset:2048
	ds_read_b64_tr_b16 v[78:79], v231 offset:2560
	ds_read_b64_tr_b16 v[220:221], v231 offset:1024
	ds_read_b64_tr_b16 v[222:223], v231 offset:1536
	ds_read_b64_tr_b16 v[224:225], v231 offset:3072
	ds_read_b64_tr_b16 v[226:227], v231 offset:3584
	s_waitcnt vmcnt(8)
	ds_write_b128 v247, v[156:159]
	ds_write_b128 v247, v[160:163] offset:1024
	ds_write_b128 v247, v[164:167] offset:2048
	ds_write_b128 v247, v[168:171] offset:3072
	ds_read_b128 v[156:159], v248
	ds_read_b128 v[160:163], v249
	ds_read_b128 v[164:167], v250
	ds_read_b128 v[168:171], v251
	ds_write_b128 v112, v[172:175]
	ds_write_b128 v112, v[176:179] offset:1024
	ds_write_b128 v112, v[180:183] offset:2048
	ds_write_b128 v112, v[184:187] offset:3072
	v_mfma_f32_32x32x16_bf16 v[32:47], v[120:123], v[52:55], v[32:47]
	v_mfma_f32_32x32x16_bf16 v[32:47], v[124:127], v[56:59], v[32:47]
	v_mfma_f32_32x32x16_bf16 v[32:47], v[128:131], v[60:63], v[32:47]
	s_nop 11
	v_exp_f32_e32 v32, v32
	v_exp_f32_e32 v33, v33
	v_exp_f32_e32 v34, v34
	v_exp_f32_e32 v35, v35
	v_exp_f32_e32 v36, v36
	v_exp_f32_e32 v37, v37
	v_exp_f32_e32 v38, v38
	v_exp_f32_e32 v39, v39
	v_exp_f32_e32 v40, v40
	v_exp_f32_e32 v41, v41
	v_exp_f32_e32 v42, v42
	v_exp_f32_e32 v43, v43
	v_exp_f32_e32 v44, v44
	v_exp_f32_e32 v45, v45
	v_exp_f32_e32 v46, v46
	v_exp_f32_e32 v47, v47
	v_cvt_pk_bf16_f32 v64, v32, v33
	v_cvt_pk_bf16_f32 v65, v34, v35
	v_cvt_pk_bf16_f32 v66, v36, v37
	v_cvt_pk_bf16_f32 v67, v38, v39
	v_cvt_pk_bf16_f32 v68, v40, v41
	v_cvt_pk_bf16_f32 v69, v42, v43
	v_cvt_pk_bf16_f32 v70, v44, v45
	v_cvt_pk_bf16_f32 v71, v46, v47
	v_pk_add_f32 v[232:233], v[232:233], v[32:33]
	v_pk_add_f32 v[232:233], v[232:233], v[34:35]
	v_pk_add_f32 v[232:233], v[232:233], v[36:37]
	v_pk_add_f32 v[232:233], v[232:233], v[38:39]
	v_pk_add_f32 v[232:233], v[232:233], v[40:41]
	v_pk_add_f32 v[232:233], v[232:233], v[42:43]
	v_pk_add_f32 v[232:233], v[232:233], v[44:45]
	v_pk_add_f32 v[232:233], v[232:233], v[46:47]
	s_waitcnt lgkmcnt(12)
	v_mfma_f32_32x32x16_bf16 v[0:15], v[64:67], v[72:75], v[0:15]
	v_mfma_f32_32x32x16_bf16 v[16:31], v[64:67], v[76:79], v[16:31]
	v_mfma_f32_32x32x16_bf16 v[0:15], v[68:71], v[220:223], v[0:15]
	v_mfma_f32_32x32x16_bf16 v[16:31], v[68:71], v[224:227], v[16:31]
	ds_read2_b32 v[32:33], v115 offset0:96 offset1:97
	ds_read2_b32 v[34:35], v115 offset0:98 offset1:99
	ds_read2_b32 v[36:37], v115 offset0:104 offset1:105
	ds_read2_b32 v[38:39], v115 offset0:106 offset1:107
	ds_read2_b32 v[40:41], v115 offset0:112 offset1:113
	ds_read2_b32 v[42:43], v115 offset0:114 offset1:115
	ds_read2_b32 v[44:45], v115 offset0:120 offset1:121
	ds_read2_b32 v[46:47], v115 offset0:122 offset1:123
	s_waitcnt lgkmcnt(0)
	v_mfma_f32_32x32x16_bf16 v[32:47], v[156:159], v[48:51], v[32:47]
	ds_read_b64_tr_b16 v[72:73], v231
	ds_read_b64_tr_b16 v[74:75], v231 offset:512
	ds_read_b64_tr_b16 v[76:77], v231 offset:2048
	ds_read_b64_tr_b16 v[78:79], v231 offset:2560
	ds_read_b64_tr_b16 v[220:221], v231 offset:1024
	ds_read_b64_tr_b16 v[222:223], v231 offset:1536
	ds_read_b64_tr_b16 v[224:225], v231 offset:3072
	ds_read_b64_tr_b16 v[226:227], v231 offset:3584
	s_waitcnt vmcnt(0)
	ds_write_b128 v247, v[188:191]
	ds_write_b128 v247, v[192:195] offset:1024
	ds_write_b128 v247, v[196:199] offset:2048
	ds_write_b128 v247, v[200:203] offset:3072
	ds_read_b128 v[188:191], v248
	ds_read_b128 v[192:195], v249
	ds_read_b128 v[196:199], v250
	ds_read_b128 v[200:203], v251
	ds_write_b128 v112, v[204:207]
	ds_write_b128 v112, v[208:211] offset:1024
	ds_write_b128 v112, v[212:215] offset:2048
	ds_write_b128 v112, v[216:219] offset:3072
	v_mfma_f32_32x32x16_bf16 v[32:47], v[160:163], v[52:55], v[32:47]
	v_mfma_f32_32x32x16_bf16 v[32:47], v[164:167], v[56:59], v[32:47]
	v_mfma_f32_32x32x16_bf16 v[32:47], v[168:171], v[60:63], v[32:47]
	s_nop 11
	v_exp_f32_e32 v32, v32
	v_exp_f32_e32 v33, v33
	v_exp_f32_e32 v34, v34
	v_exp_f32_e32 v35, v35
	v_exp_f32_e32 v36, v36
	v_exp_f32_e32 v37, v37
	v_exp_f32_e32 v38, v38
	v_exp_f32_e32 v39, v39
	v_exp_f32_e32 v40, v40
	v_exp_f32_e32 v41, v41
	v_exp_f32_e32 v42, v42
	v_exp_f32_e32 v43, v43
	v_exp_f32_e32 v44, v44
	v_exp_f32_e32 v45, v45
	v_exp_f32_e32 v46, v46
	v_exp_f32_e32 v47, v47
	v_cvt_pk_bf16_f32 v64, v32, v33
	v_cvt_pk_bf16_f32 v65, v34, v35
	v_cvt_pk_bf16_f32 v66, v36, v37
	v_cvt_pk_bf16_f32 v67, v38, v39
	v_cvt_pk_bf16_f32 v68, v40, v41
	v_cvt_pk_bf16_f32 v69, v42, v43
	v_cvt_pk_bf16_f32 v70, v44, v45
	v_cvt_pk_bf16_f32 v71, v46, v47
	v_pk_add_f32 v[232:233], v[232:233], v[32:33]
	v_pk_add_f32 v[232:233], v[232:233], v[34:35]
	v_pk_add_f32 v[232:233], v[232:233], v[36:37]
	v_pk_add_f32 v[232:233], v[232:233], v[38:39]
	v_pk_add_f32 v[232:233], v[232:233], v[40:41]
	v_pk_add_f32 v[232:233], v[232:233], v[42:43]
	v_pk_add_f32 v[232:233], v[232:233], v[44:45]
	v_pk_add_f32 v[232:233], v[232:233], v[46:47]
	s_waitcnt lgkmcnt(12)
	v_mfma_f32_32x32x16_bf16 v[0:15], v[64:67], v[72:75], v[0:15]
	v_mfma_f32_32x32x16_bf16 v[16:31], v[64:67], v[76:79], v[16:31]
	v_mfma_f32_32x32x16_bf16 v[0:15], v[68:71], v[220:223], v[0:15]
	v_mfma_f32_32x32x16_bf16 v[16:31], v[68:71], v[224:227], v[16:31]
	ds_read2_b32 v[32:33], v115 offset0:128 offset1:129
	ds_read2_b32 v[34:35], v115 offset0:130 offset1:131
	ds_read2_b32 v[36:37], v115 offset0:136 offset1:137
	ds_read2_b32 v[38:39], v115 offset0:138 offset1:139
	ds_read2_b32 v[40:41], v115 offset0:144 offset1:145
	ds_read2_b32 v[42:43], v115 offset0:146 offset1:147
	ds_read2_b32 v[44:45], v115 offset0:152 offset1:153
	ds_read2_b32 v[46:47], v115 offset0:154 offset1:155
	s_waitcnt lgkmcnt(0)
; #define LAS __attribute__((address_space(3)))
; __device__ __forceinline__ int crow(int r, int hi) { return (r & 3) + 8 * (r >> 2) + 4 * hi; }
; __device__ __forceinline__ void dil_unit(LAS unsigned char* lds, bf16_t* proj, int seq, int hd, int T0, int rho) {
;     ...
;     const bool bound = (T0 < 1024) || (T0 >= 15360);
;     ...
;     if (bound) DIL_LOOP(true); else DIL_LOOP(false);
;     ...
;     LAS bf16_t* stg = (LAS bf16_t*)wbuf;
;     l += __shfl_xor(l, 32);
; #pragma unroll
;     for (int rr = 0; rr < 16; ++rr) {
;         const int j = crow(rr, hi);
;         const float il = __builtin_amdgcn_rcpf(__shfl(l, j));
	v_mfma_f32_32x32x16_bf16 v[32:47], v[188:191], v[48:51], v[32:47]
	ds_read_b64_tr_b16 v[72:73], v231
	ds_read_b64_tr_b16 v[74:75], v231 offset:512
	ds_read_b64_tr_b16 v[76:77], v231 offset:2048
	ds_read_b64_tr_b16 v[78:79], v231 offset:2560
	ds_read_b64_tr_b16 v[220:221], v231 offset:1024
	ds_read_b64_tr_b16 v[222:223], v231 offset:1536
	ds_read_b64_tr_b16 v[224:225], v231 offset:3072
	ds_read_b64_tr_b16 v[226:227], v231 offset:3584
	v_mfma_f32_32x32x16_bf16 v[32:47], v[192:195], v[52:55], v[32:47]
	v_mfma_f32_32x32x16_bf16 v[32:47], v[196:199], v[56:59], v[32:47]
	v_mfma_f32_32x32x16_bf16 v[32:47], v[200:203], v[60:63], v[32:47]
	s_nop 11
	v_exp_f32_e32 v32, v32
	v_exp_f32_e32 v33, v33
	v_exp_f32_e32 v34, v34
	v_exp_f32_e32 v35, v35
	v_exp_f32_e32 v36, v36
	v_exp_f32_e32 v37, v37
	v_exp_f32_e32 v38, v38
	v_exp_f32_e32 v39, v39
	v_exp_f32_e32 v40, v40
	v_exp_f32_e32 v41, v41
	v_exp_f32_e32 v42, v42
	v_exp_f32_e32 v43, v43
	v_exp_f32_e32 v44, v44
	v_exp_f32_e32 v45, v45
	v_exp_f32_e32 v46, v46
	v_exp_f32_e32 v47, v47
	v_cvt_pk_bf16_f32 v64, v32, v33
	v_cvt_pk_bf16_f32 v65, v34, v35
	v_cvt_pk_bf16_f32 v66, v36, v37
	v_cvt_pk_bf16_f32 v67, v38, v39
	v_cvt_pk_bf16_f32 v68, v40, v41
	v_cvt_pk_bf16_f32 v69, v42, v43
	v_cvt_pk_bf16_f32 v70, v44, v45
	v_cvt_pk_bf16_f32 v71, v46, v47
	v_pk_add_f32 v[232:233], v[232:233], v[32:33]
	v_pk_add_f32 v[232:233], v[232:233], v[34:35]
	v_pk_add_f32 v[232:233], v[232:233], v[36:37]
	v_pk_add_f32 v[232:233], v[232:233], v[38:39]
	v_pk_add_f32 v[232:233], v[232:233], v[40:41]
	v_pk_add_f32 v[232:233], v[232:233], v[42:43]
	v_pk_add_f32 v[232:233], v[232:233], v[44:45]
	v_pk_add_f32 v[232:233], v[232:233], v[46:47]
	s_waitcnt lgkmcnt(0)
	v_mfma_f32_32x32x16_bf16 v[0:15], v[64:67], v[72:75], v[0:15]
	v_mfma_f32_32x32x16_bf16 v[16:31], v[64:67], v[76:79], v[16:31]
	v_mfma_f32_32x32x16_bf16 v[0:15], v[68:71], v[220:223], v[0:15]
	v_mfma_f32_32x32x16_bf16 v[16:31], v[68:71], v[224:227], v[16:31]
	v_add_f32_e32 v113, v232, v233
	v_or_b32_e32 v114, 1, v107
	v_or_b32_e32 v97, 2, v107
	v_or_b32_e32 v96, 3, v107
	v_or_b32_e32 v95, 8, v107
	v_or_b32_e32 v94, 9, v107
	v_or_b32_e32 v93, 10, v107
	v_or_b32_e32 v92, 11, v107
	v_or_b32_e32 v91, 16, v107
	v_or_b32_e32 v90, 17, v107
	v_or_b32_e32 v89, 18, v107
	v_or_b32_e32 v88, 19, v107
	v_or_b32_e32 v87, 24, v107
	v_or_b32_e32 v86, 25, v107
	v_or_b32_e32 v85, 26, v107
	v_or_b32_e32 v84, 27, v107
	s_nop 11
	s_branch .LBB0_553
.LBB0_558:
	s_movk_i32 s100, 0x1800
	s_add_i32 s101, s6, 0x15c00
	s_lshl_b32 s90, s58, 1
	s_add_u32 s82, s56, s90
	s_addc_u32 s83, s57, 0
	s_add_u32 s82, s82, 0x1200
	s_addc_u32 s83, s83, 0
	s_sub_i32 s90, s76, 64
	s_mul_i32 s90, s90, 0x1800
	s_add_u32 s84, s82, s90
	s_addc_u32 s85, s83, 0
	s_sub_i32 s90, s76, 256
	s_mul_i32 s90, s90, 0x1800
	s_add_u32 s86, s82, s90
	s_addc_u32 s87, s83, 0
	s_sub_i32 s90, s76, 1024
	s_mul_i32 s90, s90, 0x1800
	s_add_u32 s88, s82, s90
	s_addc_u32 s89, s83, 0
	v_lshlrev_b32_e32 v153, 1, v98
	v_mad_u32_u24 v80, v105, s100, v82
	v_mad_u32_u24 v100, v110, s100, v153
	v_add_u32_e32 v149, 0x18000, v100
	v_lshlrev_b32_e32 v83, 2, v105
	v_mad_u32_u24 v83, v83, s100, v82
	v_lshlrev_b32_e32 v101, 2, v110
	v_mad_u32_u24 v101, v101, s100, v153
	v_add_u32_e32 v150, 0x60000, v101
	v_lshlrev_b32_e32 v99, 4, v105
	v_mad_u32_u24 v99, v99, s100, v82
	v_lshlrev_b32_e32 v148, 4, v110
	v_mad_u32_u24 v148, v148, s100, v153
	v_add_u32_e32 v151, 0x180000, v148
	v_lshrrev_b32_e32 v249, 3, v103
	v_and_b32_e32 v250, 7, v103
	v_lshlrev_b32_e32 v250, 4, v250
	v_add_u32_e32 v235, 0, v249
	v_add_u32_e32 v236, 8, v249
	v_add_u32_e32 v237, 16, v249
	v_add_u32_e32 v238, 24, v249
	v_add_u32_e32 v239, 0, v249
	v_lshlrev_b32_e32 v239, 2, v239
	v_add_u32_e32 v240, 8, v249
	v_lshlrev_b32_e32 v240, 2, v240
	v_add_u32_e32 v241, 16, v249
	v_lshlrev_b32_e32 v241, 2, v241
	v_add_u32_e32 v242, 24, v249
	v_lshlrev_b32_e32 v242, 2, v242
	v_add_u32_e32 v243, 0, v249
	v_lshlrev_b32_e32 v243, 4, v243
	v_add_u32_e32 v244, 8, v249
	v_lshlrev_b32_e32 v244, 4, v244
	v_add_u32_e32 v245, 16, v249
	v_lshlrev_b32_e32 v245, 4, v245
	v_add_u32_e32 v246, 24, v249
	v_lshlrev_b32_e32 v246, 4, v246
	v_mov_b32_e32 v252, v250
	v_mov_b32_e32 v100, v110
	v_add_u32_e32 v149, 16, v100
	v_lshlrev_b32_e32 v101, 2, v110
	v_add_u32_e32 v150, 64, v101
	v_lshlrev_b32_e32 v148, 4, v110
	v_add_u32_e32 v151, 256, v148
	s_mov_b32 s98, 0x4000
	s_mov_b32 s99, 0x3fff
	v_and_b32_e32 v247, 7, v249
	v_lshlrev_b32_e32 v247, 4, v247
	v_xor_b32_e32 v247, v247, v112
	v_and_b32_e32 v153, 7, v105
	v_or_b32_e32 v248, 0, v106
	v_xor_b32_e32 v248, v248, v153
	v_lshlrev_b32_e32 v248, 4, v248
	v_lshl_add_u32 v248, v105, 7, v248
	v_add_u32_e32 v248, s77, v248
	v_or_b32_e32 v249, 2, v106
	v_xor_b32_e32 v249, v249, v153
	v_lshlrev_b32_e32 v249, 4, v249
	v_lshl_add_u32 v249, v105, 7, v249
	v_add_u32_e32 v249, s77, v249
	v_or_b32_e32 v250, 4, v106
	v_xor_b32_e32 v250, v250, v153
	v_lshlrev_b32_e32 v250, 4, v250
	v_lshl_add_u32 v250, v105, 7, v250
	v_add_u32_e32 v250, s77, v250
	v_or_b32_e32 v251, 6, v106
	v_xor_b32_e32 v251, v251, v153
	v_lshlrev_b32_e32 v251, 4, v251
	v_lshl_add_u32 v251, v105, 7, v251
	v_add_u32_e32 v251, s77, v251
	v_lshlrev_b32_e32 v153, 1, v98
	v_mul_u32_u24_e32 v228, 17, v105
	v_sub_u32_e32 v228, v107, v228
	s_mul_i32 s90, s58, 153
	s_lshr_b32 s90, s90, 1
	s_add_i32 s90, s90, 34876
	v_lshl_add_u32 v228, v228, 2, s90
	v_lshlrev_b32_e32 v229, 2, v105
	v_sub_u32_e32 v229, v107, v229
	s_add_i32 s90, s101, 5104
	v_lshl_add_u32 v229, v229, 2, s90
	v_sub_u32_e32 v230, v107, v105
	s_add_i32 s90, s101, 6364
	v_lshl_add_u32 v230, v230, 2, s90
	v_add_u32_e32 v231, v109, v108
	v_mov_b64_e32 v[232:233], 0
; __device__ __forceinline__ void dil_unit(LAS unsigned char* lds, bf16_t* proj, int seq, int hd, int T0, int rho) {
;     ...
;     f32x16 o0 = {}, o1 = {}; float l = 0.f;
;     const bool bound = (T0 < 1024) || (T0 >= 15360);
	v_mov_b64_e32 v[0:1], 0
	v_mov_b64_e32 v[2:3], 0
	v_mov_b64_e32 v[4:5], 0
	v_mov_b64_e32 v[6:7], 0
	v_mov_b64_e32 v[8:9], 0
	v_mov_b64_e32 v[10:11], 0
	v_mov_b64_e32 v[12:13], 0
	v_mov_b64_e32 v[14:15], 0
	v_mov_b64_e32 v[16:17], 0
	v_mov_b64_e32 v[18:19], 0
	v_mov_b64_e32 v[20:21], 0
	v_mov_b64_e32 v[22:23], 0
	v_mov_b64_e32 v[24:25], 0
	v_mov_b64_e32 v[26:27], 0
	v_mov_b64_e32 v[28:29], 0
	v_mov_b64_e32 v[30:31], 0
	s_add_i32 s90, s76, -64
	v_add_u32_e32 v80, s90, v235
	v_add_u32_e32 v83, s90, v236
	v_add_u32_e32 v99, s90, v237
	v_add_u32_e32 v253, s90, v238
	v_add_u32_e32 v254, s90, v100
	v_add_u32_e32 v255, s90, v149
	v_med3_i32 v80, v80, 0, s99
	v_med3_i32 v83, v83, 0, s99
	v_med3_i32 v99, v99, 0, s99
	v_med3_i32 v253, v253, 0, s99
	v_med3_i32 v254, v254, 0, s99
	v_med3_i32 v255, v255, 0, s99
	v_mad_u32_u24 v80, v80, s100, v252
	v_mad_u32_u24 v83, v83, s100, v252
	v_mad_u32_u24 v99, v99, s100, v252
	v_mad_u32_u24 v253, v253, s100, v252
	v_mad_u32_u24 v254, v254, s100, v153
	v_mad_u32_u24 v255, v255, s100, v153
	global_load_dwordx4 v[116:119], v80, s[82:83]
	global_load_dwordx4 v[120:123], v83, s[82:83]
	global_load_dwordx4 v[124:127], v99, s[82:83]
	global_load_dwordx4 v[128:131], v253, s[82:83]
	global_load_dwordx4 v[132:135], v254, s[82:83] offset:768
	global_load_dwordx4 v[136:139], v255, s[82:83] offset:768
	global_load_dwordx4 v[140:143], v254, s[82:83] offset:832
	global_load_dwordx4 v[144:147], v255, s[82:83] offset:832
	s_add_i32 s90, s76, -32
	v_add_u32_e32 v80, s90, v235
	v_add_u32_e32 v83, s90, v236
	v_add_u32_e32 v99, s90, v237
	v_add_u32_e32 v253, s90, v238
	v_add_u32_e32 v254, s90, v100
	v_add_u32_e32 v255, s90, v149
	v_med3_i32 v80, v80, 0, s99
	v_med3_i32 v83, v83, 0, s99
	v_med3_i32 v99, v99, 0, s99
	v_med3_i32 v253, v253, 0, s99
	v_med3_i32 v254, v254, 0, s99
	v_med3_i32 v255, v255, 0, s99
	v_mad_u32_u24 v80, v80, s100, v252
	v_mad_u32_u24 v83, v83, s100, v252
	v_mad_u32_u24 v99, v99, s100, v252
	v_mad_u32_u24 v253, v253, s100, v252
	v_mad_u32_u24 v254, v254, s100, v153
	v_mad_u32_u24 v255, v255, s100, v153
	global_load_dwordx4 v[156:159], v80, s[82:83]
	global_load_dwordx4 v[160:163], v83, s[82:83]
	global_load_dwordx4 v[164:167], v99, s[82:83]
	global_load_dwordx4 v[168:171], v253, s[82:83]
	global_load_dwordx4 v[172:175], v254, s[82:83] offset:768
	global_load_dwordx4 v[176:179], v255, s[82:83] offset:768
	global_load_dwordx4 v[180:183], v254, s[82:83] offset:832
	global_load_dwordx4 v[184:187], v255, s[82:83] offset:832
	s_add_i32 s90, s76, 0
	v_add_u32_e32 v80, s90, v235
	v_add_u32_e32 v83, s90, v236
	v_add_u32_e32 v99, s90, v237
	v_add_u32_e32 v253, s90, v238
	v_add_u32_e32 v254, s90, v100
	v_add_u32_e32 v255, s90, v149
	v_med3_i32 v80, v80, 0, s99
	v_med3_i32 v83, v83, 0, s99
	v_med3_i32 v99, v99, 0, s99
	v_med3_i32 v253, v253, 0, s99
	v_med3_i32 v254, v254, 0, s99
	v_med3_i32 v255, v255, 0, s99
	v_mad_u32_u24 v80, v80, s100, v252
	v_mad_u32_u24 v83, v83, s100, v252
	v_mad_u32_u24 v99, v99, s100, v252
	v_mad_u32_u24 v253, v253, s100, v252
	v_mad_u32_u24 v254, v254, s100, v153
	v_mad_u32_u24 v255, v255, s100, v153
	global_load_dwordx4 v[188:191], v80, s[82:83]
	global_load_dwordx4 v[192:195], v83, s[82:83]
	global_load_dwordx4 v[196:199], v99, s[82:83]
	global_load_dwordx4 v[200:203], v253, s[82:83]
	global_load_dwordx4 v[204:207], v254, s[82:83] offset:768
	global_load_dwordx4 v[208:211], v255, s[82:83] offset:768
	global_load_dwordx4 v[212:215], v254, s[82:83] offset:832
	global_load_dwordx4 v[216:219], v255, s[82:83] offset:832
	s_waitcnt vmcnt(16)
	ds_write_b128 v247, v[116:119]
	ds_write_b128 v247, v[120:123] offset:1024
	ds_write_b128 v247, v[124:127] offset:2048
	ds_write_b128 v247, v[128:131] offset:3072
	ds_read_b128 v[116:119], v248
	ds_read_b128 v[120:123], v249
	ds_read_b128 v[124:127], v250
	ds_read_b128 v[128:131], v251
	ds_write_b128 v112, v[132:135]
	ds_write_b128 v112, v[136:139] offset:1024
	ds_write_b128 v112, v[140:143] offset:2048
	ds_write_b128 v112, v[144:147] offset:3072
	v_mov_b32_e32 v115, v228
	ds_read2_b32 v[32:33], v115 offset0:0 offset1:1
	ds_read2_b32 v[34:35], v115 offset0:2 offset1:3
	ds_read2_b32 v[36:37], v115 offset0:8 offset1:9
	ds_read2_b32 v[38:39], v115 offset0:10 offset1:11
	ds_read2_b32 v[40:41], v115 offset0:17 offset1:18
	ds_read2_b32 v[42:43], v115 offset0:19 offset1:20
	ds_read2_b32 v[44:45], v115 offset0:25 offset1:26
	ds_read2_b32 v[46:47], v115 offset0:27 offset1:28
	s_waitcnt lgkmcnt(0)
	v_mfma_f32_32x32x16_bf16 v[32:47], v[116:119], v[48:51], v[32:47]
	ds_read_b64_tr_b16 v[72:73], v231
	ds_read_b64_tr_b16 v[74:75], v231 offset:512
	ds_read_b64_tr_b16 v[76:77], v231 offset:2048
	ds_read_b64_tr_b16 v[78:79], v231 offset:2560
	ds_read_b64_tr_b16 v[220:221], v231 offset:1024
	ds_read_b64_tr_b16 v[222:223], v231 offset:1536
	ds_read_b64_tr_b16 v[224:225], v231 offset:3072
	ds_read_b64_tr_b16 v[226:227], v231 offset:3584
	s_waitcnt vmcnt(8)
	ds_write_b128 v247, v[156:159]
	ds_write_b128 v247, v[160:163] offset:1024
	ds_write_b128 v247, v[164:167] offset:2048
	ds_write_b128 v247, v[168:171] offset:3072
	ds_read_b128 v[156:159], v248
	ds_read_b128 v[160:163], v249
	ds_read_b128 v[164:167], v250
	ds_read_b128 v[168:171], v251
	ds_write_b128 v112, v[172:175]
	ds_write_b128 v112, v[176:179] offset:1024
	ds_write_b128 v112, v[180:183] offset:2048
	ds_write_b128 v112, v[184:187] offset:3072
	v_mfma_f32_32x32x16_bf16 v[32:47], v[120:123], v[52:55], v[32:47]
	v_mfma_f32_32x32x16_bf16 v[32:47], v[124:127], v[56:59], v[32:47]
	v_mfma_f32_32x32x16_bf16 v[32:47], v[128:131], v[60:63], v[32:47]
	s_nop 11
	v_exp_f32_e32 v32, v32
	v_exp_f32_e32 v33, v33
	v_exp_f32_e32 v34, v34
	v_exp_f32_e32 v35, v35
	v_exp_f32_e32 v36, v36
	v_exp_f32_e32 v37, v37
	v_exp_f32_e32 v38, v38
	v_exp_f32_e32 v39, v39
	v_exp_f32_e32 v40, v40
	v_exp_f32_e32 v41, v41
	v_exp_f32_e32 v42, v42
	v_exp_f32_e32 v43, v43
	v_exp_f32_e32 v44, v44
	v_exp_f32_e32 v45, v45
	v_exp_f32_e32 v46, v46
	v_exp_f32_e32 v47, v47
	s_add_i32 s90, s76, -64
	v_add_u32_e32 v84, s90, v107
	v_add_u32_e32 v85, 0, v84
	v_add_u32_e32 v86, 1, v84
	v_add_u32_e32 v87, 2, v84
	v_add_u32_e32 v88, 3, v84
	v_cmp_gt_u32_e64 s[30:31], s98, v85
	v_cmp_gt_u32_e64 s[36:37], s98, v86
	v_cmp_gt_u32_e64 s[78:79], s98, v87
	v_cmp_gt_u32_e64 s[50:51], s98, v88
	v_cndmask_b32_e64 v32, 0, v32, s[30:31]
	v_add_u32_e32 v85, 8, v84
	v_cmp_gt_u32_e64 s[30:31], s98, v85
	v_cndmask_b32_e64 v33, 0, v33, s[36:37]
	v_add_u32_e32 v86, 9, v84
	v_cmp_gt_u32_e64 s[36:37], s98, v86
	v_cndmask_b32_e64 v34, 0, v34, s[78:79]
	v_add_u32_e32 v87, 10, v84
	v_cmp_gt_u32_e64 s[78:79], s98, v87
	v_cndmask_b32_e64 v35, 0, v35, s[50:51]
	v_add_u32_e32 v88, 11, v84
	v_cmp_gt_u32_e64 s[50:51], s98, v88
	v_cndmask_b32_e64 v36, 0, v36, s[30:31]
	v_add_u32_e32 v85, 16, v84
	v_cmp_gt_u32_e64 s[30:31], s98, v85
	v_cndmask_b32_e64 v37, 0, v37, s[36:37]
	v_add_u32_e32 v86, 17, v84
	v_cmp_gt_u32_e64 s[36:37], s98, v86
	v_cndmask_b32_e64 v38, 0, v38, s[78:79]
	v_add_u32_e32 v87, 18, v84
	v_cmp_gt_u32_e64 s[78:79], s98, v87
	v_cndmask_b32_e64 v39, 0, v39, s[50:51]
	v_add_u32_e32 v88, 19, v84
	v_cmp_gt_u32_e64 s[50:51], s98, v88
	v_cndmask_b32_e64 v40, 0, v40, s[30:31]
	v_add_u32_e32 v85, 24, v84
	v_cmp_gt_u32_e64 s[30:31], s98, v85
	v_cndmask_b32_e64 v41, 0, v41, s[36:37]
	v_add_u32_e32 v86, 25, v84
	v_cmp_gt_u32_e64 s[36:37], s98, v86
	v_cndmask_b32_e64 v42, 0, v42, s[78:79]
	v_add_u32_e32 v87, 26, v84
	v_cmp_gt_u32_e64 s[78:79], s98, v87
	v_cndmask_b32_e64 v43, 0, v43, s[50:51]
	v_add_u32_e32 v88, 27, v84
	v_cmp_gt_u32_e64 s[50:51], s98, v88
	v_nop
	v_cndmask_b32_e64 v44, 0, v44, s[30:31]
	v_cndmask_b32_e64 v45, 0, v45, s[36:37]
	v_cndmask_b32_e64 v46, 0, v46, s[78:79]
	v_cndmask_b32_e64 v47, 0, v47, s[50:51]
	v_cvt_pk_bf16_f32 v64, v32, v33
	v_cvt_pk_bf16_f32 v65, v34, v35
	v_cvt_pk_bf16_f32 v66, v36, v37
	v_cvt_pk_bf16_f32 v67, v38, v39
	v_cvt_pk_bf16_f32 v68, v40, v41
	v_cvt_pk_bf16_f32 v69, v42, v43
	v_cvt_pk_bf16_f32 v70, v44, v45
	v_cvt_pk_bf16_f32 v71, v46, v47
	v_pk_add_f32 v[232:233], v[232:233], v[32:33]
	v_pk_add_f32 v[232:233], v[232:233], v[34:35]
	v_pk_add_f32 v[232:233], v[232:233], v[36:37]
	v_pk_add_f32 v[232:233], v[232:233], v[38:39]
	v_pk_add_f32 v[232:233], v[232:233], v[40:41]
	v_pk_add_f32 v[232:233], v[232:233], v[42:43]
	v_pk_add_f32 v[232:233], v[232:233], v[44:45]
	v_pk_add_f32 v[232:233], v[232:233], v[46:47]
	s_waitcnt lgkmcnt(12)
	v_mfma_f32_32x32x16_bf16 v[0:15], v[64:67], v[72:75], v[0:15]
	v_mfma_f32_32x32x16_bf16 v[16:31], v[64:67], v[76:79], v[16:31]
	v_mfma_f32_32x32x16_bf16 v[0:15], v[68:71], v[220:223], v[0:15]
	v_mfma_f32_32x32x16_bf16 v[16:31], v[68:71], v[224:227], v[16:31]
	s_add_i32 s90, s76, 32
	v_add_u32_e32 v80, s90, v235
	v_add_u32_e32 v83, s90, v236
	v_add_u32_e32 v99, s90, v237
	v_add_u32_e32 v253, s90, v238
	v_add_u32_e32 v254, s90, v100
	v_add_u32_e32 v255, s90, v149
	v_med3_i32 v80, v80, 0, s99
	v_med3_i32 v83, v83, 0, s99
	v_med3_i32 v99, v99, 0, s99
	v_med3_i32 v253, v253, 0, s99
	v_med3_i32 v254, v254, 0, s99
	v_med3_i32 v255, v255, 0, s99
	v_mad_u32_u24 v80, v80, s100, v252
	v_mad_u32_u24 v83, v83, s100, v252
	v_mad_u32_u24 v99, v99, s100, v252
	v_mad_u32_u24 v253, v253, s100, v252
	v_mad_u32_u24 v254, v254, s100, v153
	v_mad_u32_u24 v255, v255, s100, v153
	global_load_dwordx4 v[116:119], v80, s[82:83]
	global_load_dwordx4 v[120:123], v83, s[82:83]
	global_load_dwordx4 v[124:127], v99, s[82:83]
	global_load_dwordx4 v[128:131], v253, s[82:83]
	global_load_dwordx4 v[132:135], v254, s[82:83] offset:768
	global_load_dwordx4 v[136:139], v255, s[82:83] offset:768
	global_load_dwordx4 v[140:143], v254, s[82:83] offset:832
	global_load_dwordx4 v[144:147], v255, s[82:83] offset:832
	ds_read2_b32 v[32:33], v115 offset0:34 offset1:35
	ds_read2_b32 v[34:35], v115 offset0:36 offset1:37
	ds_read2_b32 v[36:37], v115 offset0:42 offset1:43
	ds_read2_b32 v[38:39], v115 offset0:44 offset1:45
	ds_read2_b32 v[40:41], v115 offset0:51 offset1:52
	ds_read2_b32 v[42:43], v115 offset0:53 offset1:54
	ds_read2_b32 v[44:45], v115 offset0:59 offset1:60
	ds_read2_b32 v[46:47], v115 offset0:61 offset1:62
	s_waitcnt lgkmcnt(0)
	v_mfma_f32_32x32x16_bf16 v[32:47], v[156:159], v[48:51], v[32:47]
	ds_read_b64_tr_b16 v[72:73], v231
	ds_read_b64_tr_b16 v[74:75], v231 offset:512
	ds_read_b64_tr_b16 v[76:77], v231 offset:2048
	ds_read_b64_tr_b16 v[78:79], v231 offset:2560
	ds_read_b64_tr_b16 v[220:221], v231 offset:1024
	ds_read_b64_tr_b16 v[222:223], v231 offset:1536
	ds_read_b64_tr_b16 v[224:225], v231 offset:3072
	ds_read_b64_tr_b16 v[226:227], v231 offset:3584
	s_waitcnt vmcnt(8)
	ds_write_b128 v247, v[188:191]
	ds_write_b128 v247, v[192:195] offset:1024
	ds_write_b128 v247, v[196:199] offset:2048
	ds_write_b128 v247, v[200:203] offset:3072
	ds_read_b128 v[188:191], v248
	ds_read_b128 v[192:195], v249
	ds_read_b128 v[196:199], v250
	ds_read_b128 v[200:203], v251
	ds_write_b128 v112, v[204:207]
	ds_write_b128 v112, v[208:211] offset:1024
	ds_write_b128 v112, v[212:215] offset:2048
	ds_write_b128 v112, v[216:219] offset:3072
	v_mfma_f32_32x32x16_bf16 v[32:47], v[160:163], v[52:55], v[32:47]
	v_mfma_f32_32x32x16_bf16 v[32:47], v[164:167], v[56:59], v[32:47]
	v_mfma_f32_32x32x16_bf16 v[32:47], v[168:171], v[60:63], v[32:47]
	s_nop 11
	v_exp_f32_e32 v32, v32
	v_exp_f32_e32 v33, v33
	v_exp_f32_e32 v34, v34
	v_exp_f32_e32 v35, v35
	v_exp_f32_e32 v36, v36
	v_exp_f32_e32 v37, v37
	v_exp_f32_e32 v38, v38
	v_exp_f32_e32 v39, v39
	v_exp_f32_e32 v40, v40
	v_exp_f32_e32 v41, v41
	v_exp_f32_e32 v42, v42
	v_exp_f32_e32 v43, v43
	v_exp_f32_e32 v44, v44
	v_exp_f32_e32 v45, v45
	v_exp_f32_e32 v46, v46
	v_exp_f32_e32 v47, v47
	s_add_i32 s90, s76, -32
	v_add_u32_e32 v84, s90, v107
	v_add_u32_e32 v85, 0, v84
	v_add_u32_e32 v86, 1, v84
	v_add_u32_e32 v87, 2, v84
	v_add_u32_e32 v88, 3, v84
	v_cmp_gt_u32_e64 s[30:31], s98, v85
	v_cmp_gt_u32_e64 s[36:37], s98, v86
	v_cmp_gt_u32_e64 s[78:79], s98, v87
	v_cmp_gt_u32_e64 s[50:51], s98, v88
	v_cndmask_b32_e64 v32, 0, v32, s[30:31]
	v_add_u32_e32 v85, 8, v84
	v_cmp_gt_u32_e64 s[30:31], s98, v85
	v_cndmask_b32_e64 v33, 0, v33, s[36:37]
	v_add_u32_e32 v86, 9, v84
	v_cmp_gt_u32_e64 s[36:37], s98, v86
	v_cndmask_b32_e64 v34, 0, v34, s[78:79]
	v_add_u32_e32 v87, 10, v84
	v_cmp_gt_u32_e64 s[78:79], s98, v87
	v_cndmask_b32_e64 v35, 0, v35, s[50:51]
	v_add_u32_e32 v88, 11, v84
	v_cmp_gt_u32_e64 s[50:51], s98, v88
	v_cndmask_b32_e64 v36, 0, v36, s[30:31]
	v_add_u32_e32 v85, 16, v84
	v_cmp_gt_u32_e64 s[30:31], s98, v85
	v_cndmask_b32_e64 v37, 0, v37, s[36:37]
	v_add_u32_e32 v86, 17, v84
	v_cmp_gt_u32_e64 s[36:37], s98, v86
	v_cndmask_b32_e64 v38, 0, v38, s[78:79]
	v_add_u32_e32 v87, 18, v84
	v_cmp_gt_u32_e64 s[78:79], s98, v87
	v_cndmask_b32_e64 v39, 0, v39, s[50:51]
	v_add_u32_e32 v88, 19, v84
	v_cmp_gt_u32_e64 s[50:51], s98, v88
	v_cndmask_b32_e64 v40, 0, v40, s[30:31]
	v_add_u32_e32 v85, 24, v84
	v_cmp_gt_u32_e64 s[30:31], s98, v85
	v_cndmask_b32_e64 v41, 0, v41, s[36:37]
	v_add_u32_e32 v86, 25, v84
	v_cmp_gt_u32_e64 s[36:37], s98, v86
	v_cndmask_b32_e64 v42, 0, v42, s[78:79]
	v_add_u32_e32 v87, 26, v84
	v_cmp_gt_u32_e64 s[78:79], s98, v87
	v_cndmask_b32_e64 v43, 0, v43, s[50:51]
	v_add_u32_e32 v88, 27, v84
	v_cmp_gt_u32_e64 s[50:51], s98, v88
	v_nop
	v_cndmask_b32_e64 v44, 0, v44, s[30:31]
	v_cndmask_b32_e64 v45, 0, v45, s[36:37]
	v_cndmask_b32_e64 v46, 0, v46, s[78:79]
	v_cndmask_b32_e64 v47, 0, v47, s[50:51]
	v_cvt_pk_bf16_f32 v64, v32, v33
	v_cvt_pk_bf16_f32 v65, v34, v35
	v_cvt_pk_bf16_f32 v66, v36, v37
	v_cvt_pk_bf16_f32 v67, v38, v39
	v_cvt_pk_bf16_f32 v68, v40, v41
	v_cvt_pk_bf16_f32 v69, v42, v43
	v_cvt_pk_bf16_f32 v70, v44, v45
	v_cvt_pk_bf16_f32 v71, v46, v47
	v_pk_add_f32 v[232:233], v[232:233], v[32:33]
	v_pk_add_f32 v[232:233], v[232:233], v[34:35]
	v_pk_add_f32 v[232:233], v[232:233], v[36:37]
	v_pk_add_f32 v[232:233], v[232:233], v[38:39]
	v_pk_add_f32 v[232:233], v[232:233], v[40:41]
	v_pk_add_f32 v[232:233], v[232:233], v[42:43]
	v_pk_add_f32 v[232:233], v[232:233], v[44:45]
	v_pk_add_f32 v[232:233], v[232:233], v[46:47]
	s_waitcnt lgkmcnt(12)
	v_mfma_f32_32x32x16_bf16 v[0:15], v[64:67], v[72:75], v[0:15]
	v_mfma_f32_32x32x16_bf16 v[16:31], v[64:67], v[76:79], v[16:31]
	v_mfma_f32_32x32x16_bf16 v[0:15], v[68:71], v[220:223], v[0:15]
	v_mfma_f32_32x32x16_bf16 v[16:31], v[68:71], v[224:227], v[16:31]
	s_add_i32 s90, s76, 64
	v_add_u32_e32 v80, s90, v235
	v_add_u32_e32 v83, s90, v236
	v_add_u32_e32 v99, s90, v237
	v_add_u32_e32 v253, s90, v238
	v_add_u32_e32 v254, s90, v100
	v_add_u32_e32 v255, s90, v149
	v_med3_i32 v80, v80, 0, s99
	v_med3_i32 v83, v83, 0, s99
	v_med3_i32 v99, v99, 0, s99
	v_med3_i32 v253, v253, 0, s99
	v_med3_i32 v254, v254, 0, s99
	v_med3_i32 v255, v255, 0, s99
	v_mad_u32_u24 v80, v80, s100, v252
	v_mad_u32_u24 v83, v83, s100, v252
	v_mad_u32_u24 v99, v99, s100, v252
	v_mad_u32_u24 v253, v253, s100, v252
	v_mad_u32_u24 v254, v254, s100, v153
	v_mad_u32_u24 v255, v255, s100, v153
	global_load_dwordx4 v[156:159], v80, s[82:83]
	global_load_dwordx4 v[160:163], v83, s[82:83]
	global_load_dwordx4 v[164:167], v99, s[82:83]
	global_load_dwordx4 v[168:171], v253, s[82:83]
	global_load_dwordx4 v[172:175], v254, s[82:83] offset:768
	global_load_dwordx4 v[176:179], v255, s[82:83] offset:768
	global_load_dwordx4 v[180:183], v254, s[82:83] offset:832
	global_load_dwordx4 v[184:187], v255, s[82:83] offset:832
	ds_read2_b32 v[32:33], v115 offset0:68 offset1:69
	ds_read2_b32 v[34:35], v115 offset0:70 offset1:71
	ds_read2_b32 v[36:37], v115 offset0:76 offset1:77
	ds_read2_b32 v[38:39], v115 offset0:78 offset1:79
	ds_read2_b32 v[40:41], v115 offset0:85 offset1:86
	ds_read2_b32 v[42:43], v115 offset0:87 offset1:88
	ds_read2_b32 v[44:45], v115 offset0:93 offset1:94
	ds_read2_b32 v[46:47], v115 offset0:95 offset1:96
	s_waitcnt lgkmcnt(0)
	v_mfma_f32_32x32x16_bf16 v[32:47], v[188:191], v[48:51], v[32:47]
	ds_read_b64_tr_b16 v[72:73], v231
	ds_read_b64_tr_b16 v[74:75], v231 offset:512
	ds_read_b64_tr_b16 v[76:77], v231 offset:2048
	ds_read_b64_tr_b16 v[78:79], v231 offset:2560
	ds_read_b64_tr_b16 v[220:221], v231 offset:1024
	ds_read_b64_tr_b16 v[222:223], v231 offset:1536
	ds_read_b64_tr_b16 v[224:225], v231 offset:3072
	ds_read_b64_tr_b16 v[226:227], v231 offset:3584
	s_waitcnt vmcnt(8)
	ds_write_b128 v247, v[116:119]
	ds_write_b128 v247, v[120:123] offset:1024
	ds_write_b128 v247, v[124:127] offset:2048
	ds_write_b128 v247, v[128:131] offset:3072
	ds_read_b128 v[116:119], v248
	ds_read_b128 v[120:123], v249
	ds_read_b128 v[124:127], v250
	ds_read_b128 v[128:131], v251
	ds_write_b128 v112, v[132:135]
	ds_write_b128 v112, v[136:139] offset:1024
	ds_write_b128 v112, v[140:143] offset:2048
	ds_write_b128 v112, v[144:147] offset:3072
	v_mfma_f32_32x32x16_bf16 v[32:47], v[192:195], v[52:55], v[32:47]
	v_mfma_f32_32x32x16_bf16 v[32:47], v[196:199], v[56:59], v[32:47]
	v_mfma_f32_32x32x16_bf16 v[32:47], v[200:203], v[60:63], v[32:47]
	s_nop 11
	v_exp_f32_e32 v32, v32
	v_exp_f32_e32 v33, v33
	v_exp_f32_e32 v34, v34
	v_exp_f32_e32 v35, v35
	v_exp_f32_e32 v36, v36
	v_exp_f32_e32 v37, v37
	v_exp_f32_e32 v38, v38
	v_exp_f32_e32 v39, v39
	v_exp_f32_e32 v40, v40
	v_exp_f32_e32 v41, v41
	v_exp_f32_e32 v42, v42
	v_exp_f32_e32 v43, v43
	v_exp_f32_e32 v44, v44
	v_exp_f32_e32 v45, v45
	v_exp_f32_e32 v46, v46
	v_exp_f32_e32 v47, v47
	s_add_i32 s90, s76, 0
	v_add_u32_e32 v84, s90, v107
	v_add_u32_e32 v85, 0, v84
	v_add_u32_e32 v86, 1, v84
	v_add_u32_e32 v87, 2, v84
	v_add_u32_e32 v88, 3, v84
	v_cmp_gt_u32_e64 s[30:31], s98, v85
	v_cmp_gt_u32_e64 s[36:37], s98, v86
	v_cmp_gt_u32_e64 s[78:79], s98, v87
	v_cmp_gt_u32_e64 s[50:51], s98, v88
	v_cndmask_b32_e64 v32, 0, v32, s[30:31]
	v_add_u32_e32 v85, 8, v84
	v_cmp_gt_u32_e64 s[30:31], s98, v85
	v_cndmask_b32_e64 v33, 0, v33, s[36:37]
	v_add_u32_e32 v86, 9, v84
	v_cmp_gt_u32_e64 s[36:37], s98, v86
	v_cndmask_b32_e64 v34, 0, v34, s[78:79]
	v_add_u32_e32 v87, 10, v84
	v_cmp_gt_u32_e64 s[78:79], s98, v87
	v_cndmask_b32_e64 v35, 0, v35, s[50:51]
	v_add_u32_e32 v88, 11, v84
	v_cmp_gt_u32_e64 s[50:51], s98, v88
	v_cndmask_b32_e64 v36, 0, v36, s[30:31]
	v_add_u32_e32 v85, 16, v84
	v_cmp_gt_u32_e64 s[30:31], s98, v85
	v_cndmask_b32_e64 v37, 0, v37, s[36:37]
	v_add_u32_e32 v86, 17, v84
	v_cmp_gt_u32_e64 s[36:37], s98, v86
	v_cndmask_b32_e64 v38, 0, v38, s[78:79]
	v_add_u32_e32 v87, 18, v84
	v_cmp_gt_u32_e64 s[78:79], s98, v87
	v_cndmask_b32_e64 v39, 0, v39, s[50:51]
	v_add_u32_e32 v88, 19, v84
	v_cmp_gt_u32_e64 s[50:51], s98, v88
	v_cndmask_b32_e64 v40, 0, v40, s[30:31]
	v_add_u32_e32 v85, 24, v84
	v_cmp_gt_u32_e64 s[30:31], s98, v85
	v_cndmask_b32_e64 v41, 0, v41, s[36:37]
	v_add_u32_e32 v86, 25, v84
	v_cmp_gt_u32_e64 s[36:37], s98, v86
	v_cndmask_b32_e64 v42, 0, v42, s[78:79]
	v_add_u32_e32 v87, 26, v84
	v_cmp_gt_u32_e64 s[78:79], s98, v87
	v_cndmask_b32_e64 v43, 0, v43, s[50:51]
	v_add_u32_e32 v88, 27, v84
	v_cmp_gt_u32_e64 s[50:51], s98, v88
	v_nop
	v_cndmask_b32_e64 v44, 0, v44, s[30:31]
	v_cndmask_b32_e64 v45, 0, v45, s[36:37]
	v_cndmask_b32_e64 v46, 0, v46, s[78:79]
	v_cndmask_b32_e64 v47, 0, v47, s[50:51]
	v_cvt_pk_bf16_f32 v64, v32, v33
	v_cvt_pk_bf16_f32 v65, v34, v35
	v_cvt_pk_bf16_f32 v66, v36, v37
	v_cvt_pk_bf16_f32 v67, v38, v39
	v_cvt_pk_bf16_f32 v68, v40, v41
	v_cvt_pk_bf16_f32 v69, v42, v43
	v_cvt_pk_bf16_f32 v70, v44, v45
	v_cvt_pk_bf16_f32 v71, v46, v47
	v_pk_add_f32 v[232:233], v[232:233], v[32:33]
	v_pk_add_f32 v[232:233], v[232:233], v[34:35]
	v_pk_add_f32 v[232:233], v[232:233], v[36:37]
	v_pk_add_f32 v[232:233], v[232:233], v[38:39]
	v_pk_add_f32 v[232:233], v[232:233], v[40:41]
	v_pk_add_f32 v[232:233], v[232:233], v[42:43]
	v_pk_add_f32 v[232:233], v[232:233], v[44:45]
	v_pk_add_f32 v[232:233], v[232:233], v[46:47]
	s_waitcnt lgkmcnt(12)
	v_mfma_f32_32x32x16_bf16 v[0:15], v[64:67], v[72:75], v[0:15]
	v_mfma_f32_32x32x16_bf16 v[16:31], v[64:67], v[76:79], v[16:31]
	v_mfma_f32_32x32x16_bf16 v[0:15], v[68:71], v[220:223], v[0:15]
	v_mfma_f32_32x32x16_bf16 v[16:31], v[68:71], v[224:227], v[16:31]
	s_add_i32 s90, s76, 96
	v_add_u32_e32 v80, s90, v235
	v_add_u32_e32 v83, s90, v236
	v_add_u32_e32 v99, s90, v237
	v_add_u32_e32 v253, s90, v238
	v_add_u32_e32 v254, s90, v100
	v_add_u32_e32 v255, s90, v149
	v_med3_i32 v80, v80, 0, s99
	v_med3_i32 v83, v83, 0, s99
	v_med3_i32 v99, v99, 0, s99
	v_med3_i32 v253, v253, 0, s99
	v_med3_i32 v254, v254, 0, s99
	v_med3_i32 v255, v255, 0, s99
	v_mad_u32_u24 v80, v80, s100, v252
	v_mad_u32_u24 v83, v83, s100, v252
	v_mad_u32_u24 v99, v99, s100, v252
	v_mad_u32_u24 v253, v253, s100, v252
	v_mad_u32_u24 v254, v254, s100, v153
	v_mad_u32_u24 v255, v255, s100, v153
	global_load_dwordx4 v[188:191], v80, s[82:83]
	global_load_dwordx4 v[192:195], v83, s[82:83]
	global_load_dwordx4 v[196:199], v99, s[82:83]
	global_load_dwordx4 v[200:203], v253, s[82:83]
	global_load_dwordx4 v[204:207], v254, s[82:83] offset:768
	global_load_dwordx4 v[208:211], v255, s[82:83] offset:768
	global_load_dwordx4 v[212:215], v254, s[82:83] offset:832
	global_load_dwordx4 v[216:219], v255, s[82:83] offset:832
	ds_read2_b32 v[32:33], v115 offset0:102 offset1:103
	ds_read2_b32 v[34:35], v115 offset0:104 offset1:105
	ds_read2_b32 v[36:37], v115 offset0:110 offset1:111
	ds_read2_b32 v[38:39], v115 offset0:112 offset1:113
	ds_read2_b32 v[40:41], v115 offset0:119 offset1:120
	ds_read2_b32 v[42:43], v115 offset0:121 offset1:122
	ds_read2_b32 v[44:45], v115 offset0:127 offset1:128
	ds_read2_b32 v[46:47], v115 offset0:129 offset1:130
	s_waitcnt lgkmcnt(0)
	v_mfma_f32_32x32x16_bf16 v[32:47], v[116:119], v[48:51], v[32:47]
	ds_read_b64_tr_b16 v[72:73], v231
	ds_read_b64_tr_b16 v[74:75], v231 offset:512
	ds_read_b64_tr_b16 v[76:77], v231 offset:2048
	ds_read_b64_tr_b16 v[78:79], v231 offset:2560
	ds_read_b64_tr_b16 v[220:221], v231 offset:1024
	ds_read_b64_tr_b16 v[222:223], v231 offset:1536
	ds_read_b64_tr_b16 v[224:225], v231 offset:3072
	ds_read_b64_tr_b16 v[226:227], v231 offset:3584
	s_waitcnt vmcnt(8)
	ds_write_b128 v247, v[156:159]
	ds_write_b128 v247, v[160:163] offset:1024
	ds_write_b128 v247, v[164:167] offset:2048
	ds_write_b128 v247, v[168:171] offset:3072
	ds_read_b128 v[156:159], v248
	ds_read_b128 v[160:163], v249
	ds_read_b128 v[164:167], v250
	ds_read_b128 v[168:171], v251
	ds_write_b128 v112, v[172:175]
	ds_write_b128 v112, v[176:179] offset:1024
	ds_write_b128 v112, v[180:183] offset:2048
	ds_write_b128 v112, v[184:187] offset:3072
	v_mfma_f32_32x32x16_bf16 v[32:47], v[120:123], v[52:55], v[32:47]
	v_mfma_f32_32x32x16_bf16 v[32:47], v[124:127], v[56:59], v[32:47]
	v_mfma_f32_32x32x16_bf16 v[32:47], v[128:131], v[60:63], v[32:47]
	s_nop 11
	v_exp_f32_e32 v32, v32
	v_exp_f32_e32 v33, v33
	v_exp_f32_e32 v34, v34
	v_exp_f32_e32 v35, v35
	v_exp_f32_e32 v36, v36
	v_exp_f32_e32 v37, v37
	v_exp_f32_e32 v38, v38
	v_exp_f32_e32 v39, v39
	v_exp_f32_e32 v40, v40
	v_exp_f32_e32 v41, v41
	v_exp_f32_e32 v42, v42
	v_exp_f32_e32 v43, v43
	v_exp_f32_e32 v44, v44
	v_exp_f32_e32 v45, v45
	v_exp_f32_e32 v46, v46
	v_exp_f32_e32 v47, v47
	s_add_i32 s90, s76, 32
	v_add_u32_e32 v84, s90, v107
	v_add_u32_e32 v85, 0, v84
	v_add_u32_e32 v86, 1, v84
	v_add_u32_e32 v87, 2, v84
	v_add_u32_e32 v88, 3, v84
	v_cmp_gt_u32_e64 s[30:31], s98, v85
	v_cmp_gt_u32_e64 s[36:37], s98, v86
	v_cmp_gt_u32_e64 s[78:79], s98, v87
	v_cmp_gt_u32_e64 s[50:51], s98, v88
	v_cndmask_b32_e64 v32, 0, v32, s[30:31]
	v_add_u32_e32 v85, 8, v84
	v_cmp_gt_u32_e64 s[30:31], s98, v85
	v_cndmask_b32_e64 v33, 0, v33, s[36:37]
	v_add_u32_e32 v86, 9, v84
	v_cmp_gt_u32_e64 s[36:37], s98, v86
	v_cndmask_b32_e64 v34, 0, v34, s[78:79]
	v_add_u32_e32 v87, 10, v84
	v_cmp_gt_u32_e64 s[78:79], s98, v87
	v_cndmask_b32_e64 v35, 0, v35, s[50:51]
	v_add_u32_e32 v88, 11, v84
	v_cmp_gt_u32_e64 s[50:51], s98, v88
	v_cndmask_b32_e64 v36, 0, v36, s[30:31]
	v_add_u32_e32 v85, 16, v84
	v_cmp_gt_u32_e64 s[30:31], s98, v85
	v_cndmask_b32_e64 v37, 0, v37, s[36:37]
	v_add_u32_e32 v86, 17, v84
	v_cmp_gt_u32_e64 s[36:37], s98, v86
	v_cndmask_b32_e64 v38, 0, v38, s[78:79]
	v_add_u32_e32 v87, 18, v84
	v_cmp_gt_u32_e64 s[78:79], s98, v87
	v_cndmask_b32_e64 v39, 0, v39, s[50:51]
	v_add_u32_e32 v88, 19, v84
	v_cmp_gt_u32_e64 s[50:51], s98, v88
	v_cndmask_b32_e64 v40, 0, v40, s[30:31]
	v_add_u32_e32 v85, 24, v84
	v_cmp_gt_u32_e64 s[30:31], s98, v85
	v_cndmask_b32_e64 v41, 0, v41, s[36:37]
	v_add_u32_e32 v86, 25, v84
	v_cmp_gt_u32_e64 s[36:37], s98, v86
	v_cndmask_b32_e64 v42, 0, v42, s[78:79]
	v_add_u32_e32 v87, 26, v84
	v_cmp_gt_u32_e64 s[78:79], s98, v87
	v_cndmask_b32_e64 v43, 0, v43, s[50:51]
	v_add_u32_e32 v88, 27, v84
	v_cmp_gt_u32_e64 s[50:51], s98, v88
	v_nop
	v_cndmask_b32_e64 v44, 0, v44, s[30:31]
	v_cndmask_b32_e64 v45, 0, v45, s[36:37]
	v_cndmask_b32_e64 v46, 0, v46, s[78:79]
	v_cndmask_b32_e64 v47, 0, v47, s[50:51]
	v_cvt_pk_bf16_f32 v64, v32, v33
	v_cvt_pk_bf16_f32 v65, v34, v35
	v_cvt_pk_bf16_f32 v66, v36, v37
	v_cvt_pk_bf16_f32 v67, v38, v39
	v_cvt_pk_bf16_f32 v68, v40, v41
	v_cvt_pk_bf16_f32 v69, v42, v43
	v_cvt_pk_bf16_f32 v70, v44, v45
	v_cvt_pk_bf16_f32 v71, v46, v47
	v_pk_add_f32 v[232:233], v[232:233], v[32:33]
	v_pk_add_f32 v[232:233], v[232:233], v[34:35]
	v_pk_add_f32 v[232:233], v[232:233], v[36:37]
	v_pk_add_f32 v[232:233], v[232:233], v[38:39]
	v_pk_add_f32 v[232:233], v[232:233], v[40:41]
	v_pk_add_f32 v[232:233], v[232:233], v[42:43]
	v_pk_add_f32 v[232:233], v[232:233], v[44:45]
	v_pk_add_f32 v[232:233], v[232:233], v[46:47]
	s_waitcnt lgkmcnt(12)
	v_mfma_f32_32x32x16_bf16 v[0:15], v[64:67], v[72:75], v[0:15]
	v_mfma_f32_32x32x16_bf16 v[16:31], v[64:67], v[76:79], v[16:31]
	v_mfma_f32_32x32x16_bf16 v[0:15], v[68:71], v[220:223], v[0:15]
	v_mfma_f32_32x32x16_bf16 v[16:31], v[68:71], v[224:227], v[16:31]
	s_add_i32 s90, s76, 128
	v_add_u32_e32 v80, s90, v235
	v_add_u32_e32 v83, s90, v236
	v_add_u32_e32 v99, s90, v237
	v_add_u32_e32 v253, s90, v238
	v_add_u32_e32 v254, s90, v100
	v_add_u32_e32 v255, s90, v149
	v_med3_i32 v80, v80, 0, s99
	v_med3_i32 v83, v83, 0, s99
	v_med3_i32 v99, v99, 0, s99
	v_med3_i32 v253, v253, 0, s99
	v_med3_i32 v254, v254, 0, s99
	v_med3_i32 v255, v255, 0, s99
	v_mad_u32_u24 v80, v80, s100, v252
	v_mad_u32_u24 v83, v83, s100, v252
	v_mad_u32_u24 v99, v99, s100, v252
	v_mad_u32_u24 v253, v253, s100, v252
	v_mad_u32_u24 v254, v254, s100, v153
	v_mad_u32_u24 v255, v255, s100, v153
	global_load_dwordx4 v[116:119], v80, s[82:83]
	global_load_dwordx4 v[120:123], v83, s[82:83]
	global_load_dwordx4 v[124:127], v99, s[82:83]
	global_load_dwordx4 v[128:131], v253, s[82:83]
	global_load_dwordx4 v[132:135], v254, s[82:83] offset:768
	global_load_dwordx4 v[136:139], v255, s[82:83] offset:768
	global_load_dwordx4 v[140:143], v254, s[82:83] offset:832
	global_load_dwordx4 v[144:147], v255, s[82:83] offset:832
	ds_read2_b32 v[32:33], v115 offset0:136 offset1:137
	ds_read2_b32 v[34:35], v115 offset0:138 offset1:139
	ds_read2_b32 v[36:37], v115 offset0:144 offset1:145
	ds_read2_b32 v[38:39], v115 offset0:146 offset1:147
	ds_read2_b32 v[40:41], v115 offset0:153 offset1:154
	ds_read2_b32 v[42:43], v115 offset0:155 offset1:156
	ds_read2_b32 v[44:45], v115 offset0:161 offset1:162
	ds_read2_b32 v[46:47], v115 offset0:163 offset1:164
	s_waitcnt lgkmcnt(0)
	v_mfma_f32_32x32x16_bf16 v[32:47], v[156:159], v[48:51], v[32:47]
	ds_read_b64_tr_b16 v[72:73], v231
	ds_read_b64_tr_b16 v[74:75], v231 offset:512
	ds_read_b64_tr_b16 v[76:77], v231 offset:2048
	ds_read_b64_tr_b16 v[78:79], v231 offset:2560
	ds_read_b64_tr_b16 v[220:221], v231 offset:1024
	ds_read_b64_tr_b16 v[222:223], v231 offset:1536
	ds_read_b64_tr_b16 v[224:225], v231 offset:3072
	ds_read_b64_tr_b16 v[226:227], v231 offset:3584
	s_waitcnt vmcnt(8)
	ds_write_b128 v247, v[188:191]
	ds_write_b128 v247, v[192:195] offset:1024
	ds_write_b128 v247, v[196:199] offset:2048
	ds_write_b128 v247, v[200:203] offset:3072
	ds_read_b128 v[188:191], v248
	ds_read_b128 v[192:195], v249
	ds_read_b128 v[196:199], v250
	ds_read_b128 v[200:203], v251
	ds_write_b128 v112, v[204:207]
	ds_write_b128 v112, v[208:211] offset:1024
	ds_write_b128 v112, v[212:215] offset:2048
	ds_write_b128 v112, v[216:219] offset:3072
	v_mfma_f32_32x32x16_bf16 v[32:47], v[160:163], v[52:55], v[32:47]
	v_mfma_f32_32x32x16_bf16 v[32:47], v[164:167], v[56:59], v[32:47]
	v_mfma_f32_32x32x16_bf16 v[32:47], v[168:171], v[60:63], v[32:47]
	s_nop 11
	v_exp_f32_e32 v32, v32
	v_exp_f32_e32 v33, v33
	v_exp_f32_e32 v34, v34
	v_exp_f32_e32 v35, v35
	v_exp_f32_e32 v36, v36
	v_exp_f32_e32 v37, v37
	v_exp_f32_e32 v38, v38
	v_exp_f32_e32 v39, v39
	v_exp_f32_e32 v40, v40
	v_exp_f32_e32 v41, v41
	v_exp_f32_e32 v42, v42
	v_exp_f32_e32 v43, v43
	v_exp_f32_e32 v44, v44
	v_exp_f32_e32 v45, v45
	v_exp_f32_e32 v46, v46
	v_exp_f32_e32 v47, v47
	s_add_i32 s90, s76, 64
	v_add_u32_e32 v84, s90, v107
	v_add_u32_e32 v85, 0, v84
	v_add_u32_e32 v86, 1, v84
	v_add_u32_e32 v87, 2, v84
	v_add_u32_e32 v88, 3, v84
	v_cmp_gt_u32_e64 s[30:31], s98, v85
	v_cmp_gt_u32_e64 s[36:37], s98, v86
	v_cmp_gt_u32_e64 s[78:79], s98, v87
	v_cmp_gt_u32_e64 s[50:51], s98, v88
	v_cndmask_b32_e64 v32, 0, v32, s[30:31]
	v_add_u32_e32 v85, 8, v84
	v_cmp_gt_u32_e64 s[30:31], s98, v85
	v_cndmask_b32_e64 v33, 0, v33, s[36:37]
	v_add_u32_e32 v86, 9, v84
	v_cmp_gt_u32_e64 s[36:37], s98, v86
	v_cndmask_b32_e64 v34, 0, v34, s[78:79]
	v_add_u32_e32 v87, 10, v84
	v_cmp_gt_u32_e64 s[78:79], s98, v87
	v_cndmask_b32_e64 v35, 0, v35, s[50:51]
	v_add_u32_e32 v88, 11, v84
	v_cmp_gt_u32_e64 s[50:51], s98, v88
	v_cndmask_b32_e64 v36, 0, v36, s[30:31]
	v_add_u32_e32 v85, 16, v84
	v_cmp_gt_u32_e64 s[30:31], s98, v85
	v_cndmask_b32_e64 v37, 0, v37, s[36:37]
	v_add_u32_e32 v86, 17, v84
	v_cmp_gt_u32_e64 s[36:37], s98, v86
	v_cndmask_b32_e64 v38, 0, v38, s[78:79]
	v_add_u32_e32 v87, 18, v84
	v_cmp_gt_u32_e64 s[78:79], s98, v87
	v_cndmask_b32_e64 v39, 0, v39, s[50:51]
	v_add_u32_e32 v88, 19, v84
	v_cmp_gt_u32_e64 s[50:51], s98, v88
	v_cndmask_b32_e64 v40, 0, v40, s[30:31]
	v_add_u32_e32 v85, 24, v84
	v_cmp_gt_u32_e64 s[30:31], s98, v85
	v_cndmask_b32_e64 v41, 0, v41, s[36:37]
	v_add_u32_e32 v86, 25, v84
	v_cmp_gt_u32_e64 s[36:37], s98, v86
	v_cndmask_b32_e64 v42, 0, v42, s[78:79]
	v_add_u32_e32 v87, 26, v84
	v_cmp_gt_u32_e64 s[78:79], s98, v87
	v_cndmask_b32_e64 v43, 0, v43, s[50:51]
	v_add_u32_e32 v88, 27, v84
	v_cmp_gt_u32_e64 s[50:51], s98, v88
	v_nop
	v_cndmask_b32_e64 v44, 0, v44, s[30:31]
	v_cndmask_b32_e64 v45, 0, v45, s[36:37]
	v_cndmask_b32_e64 v46, 0, v46, s[78:79]
	v_cndmask_b32_e64 v47, 0, v47, s[50:51]
	v_cvt_pk_bf16_f32 v64, v32, v33
	v_cvt_pk_bf16_f32 v65, v34, v35
	v_cvt_pk_bf16_f32 v66, v36, v37
	v_cvt_pk_bf16_f32 v67, v38, v39
	v_cvt_pk_bf16_f32 v68, v40, v41
	v_cvt_pk_bf16_f32 v69, v42, v43
	v_cvt_pk_bf16_f32 v70, v44, v45
	v_cvt_pk_bf16_f32 v71, v46, v47
	v_pk_add_f32 v[232:233], v[232:233], v[32:33]
	v_pk_add_f32 v[232:233], v[232:233], v[34:35]
	v_pk_add_f32 v[232:233], v[232:233], v[36:37]
	v_pk_add_f32 v[232:233], v[232:233], v[38:39]
	v_pk_add_f32 v[232:233], v[232:233], v[40:41]
	v_pk_add_f32 v[232:233], v[232:233], v[42:43]
	v_pk_add_f32 v[232:233], v[232:233], v[44:45]
	v_pk_add_f32 v[232:233], v[232:233], v[46:47]
	s_waitcnt lgkmcnt(12)
	v_mfma_f32_32x32x16_bf16 v[0:15], v[64:67], v[72:75], v[0:15]
	v_mfma_f32_32x32x16_bf16 v[16:31], v[64:67], v[76:79], v[16:31]
	v_mfma_f32_32x32x16_bf16 v[0:15], v[68:71], v[220:223], v[0:15]
	v_mfma_f32_32x32x16_bf16 v[16:31], v[68:71], v[224:227], v[16:31]
	s_add_i32 s90, s76, 160
	v_add_u32_e32 v80, s90, v235
	v_add_u32_e32 v83, s90, v236
	v_add_u32_e32 v99, s90, v237
	v_add_u32_e32 v253, s90, v238
	v_add_u32_e32 v254, s90, v100
	v_add_u32_e32 v255, s90, v149
	v_med3_i32 v80, v80, 0, s99
	v_med3_i32 v83, v83, 0, s99
	v_med3_i32 v99, v99, 0, s99
	v_med3_i32 v253, v253, 0, s99
	v_med3_i32 v254, v254, 0, s99
	v_med3_i32 v255, v255, 0, s99
	v_mad_u32_u24 v80, v80, s100, v252
	v_mad_u32_u24 v83, v83, s100, v252
	v_mad_u32_u24 v99, v99, s100, v252
	v_mad_u32_u24 v253, v253, s100, v252
	v_mad_u32_u24 v254, v254, s100, v153
	v_mad_u32_u24 v255, v255, s100, v153
	global_load_dwordx4 v[156:159], v80, s[82:83]
	global_load_dwordx4 v[160:163], v83, s[82:83]
	global_load_dwordx4 v[164:167], v99, s[82:83]
	global_load_dwordx4 v[168:171], v253, s[82:83]
	global_load_dwordx4 v[172:175], v254, s[82:83] offset:768
	global_load_dwordx4 v[176:179], v255, s[82:83] offset:768
	global_load_dwordx4 v[180:183], v254, s[82:83] offset:832
	global_load_dwordx4 v[184:187], v255, s[82:83] offset:832
	ds_read2_b32 v[32:33], v115 offset0:170 offset1:171
	ds_read2_b32 v[34:35], v115 offset0:172 offset1:173
	ds_read2_b32 v[36:37], v115 offset0:178 offset1:179
	ds_read2_b32 v[38:39], v115 offset0:180 offset1:181
	ds_read2_b32 v[40:41], v115 offset0:187 offset1:188
	ds_read2_b32 v[42:43], v115 offset0:189 offset1:190
	ds_read2_b32 v[44:45], v115 offset0:195 offset1:196
	ds_read2_b32 v[46:47], v115 offset0:197 offset1:198
	s_waitcnt lgkmcnt(0)
	v_mfma_f32_32x32x16_bf16 v[32:47], v[188:191], v[48:51], v[32:47]
	ds_read_b64_tr_b16 v[72:73], v231
	ds_read_b64_tr_b16 v[74:75], v231 offset:512
	ds_read_b64_tr_b16 v[76:77], v231 offset:2048
	ds_read_b64_tr_b16 v[78:79], v231 offset:2560
	ds_read_b64_tr_b16 v[220:221], v231 offset:1024
	ds_read_b64_tr_b16 v[222:223], v231 offset:1536
	ds_read_b64_tr_b16 v[224:225], v231 offset:3072
	ds_read_b64_tr_b16 v[226:227], v231 offset:3584
	s_waitcnt vmcnt(8)
	ds_write_b128 v247, v[116:119]
	ds_write_b128 v247, v[120:123] offset:1024
	ds_write_b128 v247, v[124:127] offset:2048
	ds_write_b128 v247, v[128:131] offset:3072
	ds_read_b128 v[116:119], v248
	ds_read_b128 v[120:123], v249
	ds_read_b128 v[124:127], v250
	ds_read_b128 v[128:131], v251
	ds_write_b128 v112, v[132:135]
	ds_write_b128 v112, v[136:139] offset:1024
	ds_write_b128 v112, v[140:143] offset:2048
	ds_write_b128 v112, v[144:147] offset:3072
	v_mfma_f32_32x32x16_bf16 v[32:47], v[192:195], v[52:55], v[32:47]
	v_mfma_f32_32x32x16_bf16 v[32:47], v[196:199], v[56:59], v[32:47]
	v_mfma_f32_32x32x16_bf16 v[32:47], v[200:203], v[60:63], v[32:47]
	s_nop 11
	v_exp_f32_e32 v32, v32
	v_exp_f32_e32 v33, v33
	v_exp_f32_e32 v34, v34
	v_exp_f32_e32 v35, v35
	v_exp_f32_e32 v36, v36
	v_exp_f32_e32 v37, v37
	v_exp_f32_e32 v38, v38
	v_exp_f32_e32 v39, v39
	v_exp_f32_e32 v40, v40
	v_exp_f32_e32 v41, v41
	v_exp_f32_e32 v42, v42
	v_exp_f32_e32 v43, v43
	v_exp_f32_e32 v44, v44
	v_exp_f32_e32 v45, v45
	v_exp_f32_e32 v46, v46
	v_exp_f32_e32 v47, v47
	s_add_i32 s90, s76, 96
	v_add_u32_e32 v84, s90, v107
	v_add_u32_e32 v85, 0, v84
	v_add_u32_e32 v86, 1, v84
	v_add_u32_e32 v87, 2, v84
	v_add_u32_e32 v88, 3, v84
	v_cmp_gt_u32_e64 s[30:31], s98, v85
	v_cmp_gt_u32_e64 s[36:37], s98, v86
	v_cmp_gt_u32_e64 s[78:79], s98, v87
	v_cmp_gt_u32_e64 s[50:51], s98, v88
	v_cndmask_b32_e64 v32, 0, v32, s[30:31]
	v_add_u32_e32 v85, 8, v84
	v_cmp_gt_u32_e64 s[30:31], s98, v85
	v_cndmask_b32_e64 v33, 0, v33, s[36:37]
	v_add_u32_e32 v86, 9, v84
	v_cmp_gt_u32_e64 s[36:37], s98, v86
	v_cndmask_b32_e64 v34, 0, v34, s[78:79]
	v_add_u32_e32 v87, 10, v84
	v_cmp_gt_u32_e64 s[78:79], s98, v87
	v_cndmask_b32_e64 v35, 0, v35, s[50:51]
	v_add_u32_e32 v88, 11, v84
	v_cmp_gt_u32_e64 s[50:51], s98, v88
	v_cndmask_b32_e64 v36, 0, v36, s[30:31]
	v_add_u32_e32 v85, 16, v84
	v_cmp_gt_u32_e64 s[30:31], s98, v85
	v_cndmask_b32_e64 v37, 0, v37, s[36:37]
	v_add_u32_e32 v86, 17, v84
	v_cmp_gt_u32_e64 s[36:37], s98, v86
	v_cndmask_b32_e64 v38, 0, v38, s[78:79]
	v_add_u32_e32 v87, 18, v84
	v_cmp_gt_u32_e64 s[78:79], s98, v87
	v_cndmask_b32_e64 v39, 0, v39, s[50:51]
	v_add_u32_e32 v88, 19, v84
	v_cmp_gt_u32_e64 s[50:51], s98, v88
	v_cndmask_b32_e64 v40, 0, v40, s[30:31]
	v_add_u32_e32 v85, 24, v84
	v_cmp_gt_u32_e64 s[30:31], s98, v85
	v_cndmask_b32_e64 v41, 0, v41, s[36:37]
	v_add_u32_e32 v86, 25, v84
	v_cmp_gt_u32_e64 s[36:37], s98, v86
	v_cndmask_b32_e64 v42, 0, v42, s[78:79]
	v_add_u32_e32 v87, 26, v84
	v_cmp_gt_u32_e64 s[78:79], s98, v87
	v_cndmask_b32_e64 v43, 0, v43, s[50:51]
	v_add_u32_e32 v88, 27, v84
	v_cmp_gt_u32_e64 s[50:51], s98, v88
	v_nop
	v_cndmask_b32_e64 v44, 0, v44, s[30:31]
	v_cndmask_b32_e64 v45, 0, v45, s[36:37]
	v_cndmask_b32_e64 v46, 0, v46, s[78:79]
	v_cndmask_b32_e64 v47, 0, v47, s[50:51]
	v_cvt_pk_bf16_f32 v64, v32, v33
	v_cvt_pk_bf16_f32 v65, v34, v35
	v_cvt_pk_bf16_f32 v66, v36, v37
	v_cvt_pk_bf16_f32 v67, v38, v39
	v_cvt_pk_bf16_f32 v68, v40, v41
	v_cvt_pk_bf16_f32 v69, v42, v43
	v_cvt_pk_bf16_f32 v70, v44, v45
	v_cvt_pk_bf16_f32 v71, v46, v47
	v_pk_add_f32 v[232:233], v[232:233], v[32:33]
	v_pk_add_f32 v[232:233], v[232:233], v[34:35]
	v_pk_add_f32 v[232:233], v[232:233], v[36:37]
	v_pk_add_f32 v[232:233], v[232:233], v[38:39]
	v_pk_add_f32 v[232:233], v[232:233], v[40:41]
	v_pk_add_f32 v[232:233], v[232:233], v[42:43]
	v_pk_add_f32 v[232:233], v[232:233], v[44:45]
	v_pk_add_f32 v[232:233], v[232:233], v[46:47]
	s_waitcnt lgkmcnt(12)
	v_mfma_f32_32x32x16_bf16 v[0:15], v[64:67], v[72:75], v[0:15]
	v_mfma_f32_32x32x16_bf16 v[16:31], v[64:67], v[76:79], v[16:31]
	v_mfma_f32_32x32x16_bf16 v[0:15], v[68:71], v[220:223], v[0:15]
	v_mfma_f32_32x32x16_bf16 v[16:31], v[68:71], v[224:227], v[16:31]
	s_add_i32 s90, s76, 192
	v_add_u32_e32 v80, s90, v235
	v_add_u32_e32 v83, s90, v236
	v_add_u32_e32 v99, s90, v237
	v_add_u32_e32 v253, s90, v238
	v_add_u32_e32 v254, s90, v100
	v_add_u32_e32 v255, s90, v149
	v_med3_i32 v80, v80, 0, s99
	v_med3_i32 v83, v83, 0, s99
	v_med3_i32 v99, v99, 0, s99
	v_med3_i32 v253, v253, 0, s99
	v_med3_i32 v254, v254, 0, s99
	v_med3_i32 v255, v255, 0, s99
	v_mad_u32_u24 v80, v80, s100, v252
	v_mad_u32_u24 v83, v83, s100, v252
	v_mad_u32_u24 v99, v99, s100, v252
	v_mad_u32_u24 v253, v253, s100, v252
	v_mad_u32_u24 v254, v254, s100, v153
	v_mad_u32_u24 v255, v255, s100, v153
	global_load_dwordx4 v[188:191], v80, s[82:83]
	global_load_dwordx4 v[192:195], v83, s[82:83]
	global_load_dwordx4 v[196:199], v99, s[82:83]
	global_load_dwordx4 v[200:203], v253, s[82:83]
	global_load_dwordx4 v[204:207], v254, s[82:83] offset:768
	global_load_dwordx4 v[208:211], v255, s[82:83] offset:768
	global_load_dwordx4 v[212:215], v254, s[82:83] offset:832
	global_load_dwordx4 v[216:219], v255, s[82:83] offset:832
	ds_read2_b32 v[32:33], v115 offset0:204 offset1:205
	ds_read2_b32 v[34:35], v115 offset0:206 offset1:207
	ds_read2_b32 v[36:37], v115 offset0:212 offset1:213
	ds_read2_b32 v[38:39], v115 offset0:214 offset1:215
	ds_read2_b32 v[40:41], v115 offset0:221 offset1:222
	ds_read2_b32 v[42:43], v115 offset0:223 offset1:224
	ds_read2_b32 v[44:45], v115 offset0:229 offset1:230
	ds_read2_b32 v[46:47], v115 offset0:231 offset1:232
	s_waitcnt lgkmcnt(0)
	v_mfma_f32_32x32x16_bf16 v[32:47], v[116:119], v[48:51], v[32:47]
	ds_read_b64_tr_b16 v[72:73], v231
	ds_read_b64_tr_b16 v[74:75], v231 offset:512
	ds_read_b64_tr_b16 v[76:77], v231 offset:2048
	ds_read_b64_tr_b16 v[78:79], v231 offset:2560
	ds_read_b64_tr_b16 v[220:221], v231 offset:1024
	ds_read_b64_tr_b16 v[222:223], v231 offset:1536
	ds_read_b64_tr_b16 v[224:225], v231 offset:3072
	ds_read_b64_tr_b16 v[226:227], v231 offset:3584
	s_waitcnt vmcnt(8)
	ds_write_b128 v247, v[156:159]
	ds_write_b128 v247, v[160:163] offset:1024
	ds_write_b128 v247, v[164:167] offset:2048
	ds_write_b128 v247, v[168:171] offset:3072
	ds_read_b128 v[156:159], v248
	ds_read_b128 v[160:163], v249
	ds_read_b128 v[164:167], v250
	ds_read_b128 v[168:171], v251
	ds_write_b128 v112, v[172:175]
	ds_write_b128 v112, v[176:179] offset:1024
	ds_write_b128 v112, v[180:183] offset:2048
	ds_write_b128 v112, v[184:187] offset:3072
	v_mfma_f32_32x32x16_bf16 v[32:47], v[120:123], v[52:55], v[32:47]
	v_mfma_f32_32x32x16_bf16 v[32:47], v[124:127], v[56:59], v[32:47]
	v_mfma_f32_32x32x16_bf16 v[32:47], v[128:131], v[60:63], v[32:47]
	s_nop 11
	v_exp_f32_e32 v32, v32
	v_exp_f32_e32 v33, v33
	v_exp_f32_e32 v34, v34
	v_exp_f32_e32 v35, v35
	v_exp_f32_e32 v36, v36
	v_exp_f32_e32 v37, v37
	v_exp_f32_e32 v38, v38
	v_exp_f32_e32 v39, v39
	v_exp_f32_e32 v40, v40
	v_exp_f32_e32 v41, v41
	v_exp_f32_e32 v42, v42
	v_exp_f32_e32 v43, v43
	v_exp_f32_e32 v44, v44
	v_exp_f32_e32 v45, v45
	v_exp_f32_e32 v46, v46
	v_exp_f32_e32 v47, v47
	s_add_i32 s90, s76, 128
	v_add_u32_e32 v84, s90, v107
	v_add_u32_e32 v85, 0, v84
	v_add_u32_e32 v86, 1, v84
	v_add_u32_e32 v87, 2, v84
	v_add_u32_e32 v88, 3, v84
	v_cmp_gt_u32_e64 s[30:31], s98, v85
	v_cmp_gt_u32_e64 s[36:37], s98, v86
	v_cmp_gt_u32_e64 s[78:79], s98, v87
	v_cmp_gt_u32_e64 s[50:51], s98, v88
	v_cndmask_b32_e64 v32, 0, v32, s[30:31]
	v_add_u32_e32 v85, 8, v84
	v_cmp_gt_u32_e64 s[30:31], s98, v85
	v_cndmask_b32_e64 v33, 0, v33, s[36:37]
	v_add_u32_e32 v86, 9, v84
	v_cmp_gt_u32_e64 s[36:37], s98, v86
	v_cndmask_b32_e64 v34, 0, v34, s[78:79]
	v_add_u32_e32 v87, 10, v84
	v_cmp_gt_u32_e64 s[78:79], s98, v87
	v_cndmask_b32_e64 v35, 0, v35, s[50:51]
	v_add_u32_e32 v88, 11, v84
	v_cmp_gt_u32_e64 s[50:51], s98, v88
	v_cndmask_b32_e64 v36, 0, v36, s[30:31]
	v_add_u32_e32 v85, 16, v84
	v_cmp_gt_u32_e64 s[30:31], s98, v85
	v_cndmask_b32_e64 v37, 0, v37, s[36:37]
	v_add_u32_e32 v86, 17, v84
	v_cmp_gt_u32_e64 s[36:37], s98, v86
	v_cndmask_b32_e64 v38, 0, v38, s[78:79]
	v_add_u32_e32 v87, 18, v84
	v_cmp_gt_u32_e64 s[78:79], s98, v87
	v_cndmask_b32_e64 v39, 0, v39, s[50:51]
	v_add_u32_e32 v88, 19, v84
	v_cmp_gt_u32_e64 s[50:51], s98, v88
	v_cndmask_b32_e64 v40, 0, v40, s[30:31]
	v_add_u32_e32 v85, 24, v84
	v_cmp_gt_u32_e64 s[30:31], s98, v85
	v_cndmask_b32_e64 v41, 0, v41, s[36:37]
	v_add_u32_e32 v86, 25, v84
	v_cmp_gt_u32_e64 s[36:37], s98, v86
	v_cndmask_b32_e64 v42, 0, v42, s[78:79]
	v_add_u32_e32 v87, 26, v84
	v_cmp_gt_u32_e64 s[78:79], s98, v87
	v_cndmask_b32_e64 v43, 0, v43, s[50:51]
	v_add_u32_e32 v88, 27, v84
	v_cmp_gt_u32_e64 s[50:51], s98, v88
	v_nop
	v_cndmask_b32_e64 v44, 0, v44, s[30:31]
	v_cndmask_b32_e64 v45, 0, v45, s[36:37]
	v_cndmask_b32_e64 v46, 0, v46, s[78:79]
	v_cndmask_b32_e64 v47, 0, v47, s[50:51]
	v_cvt_pk_bf16_f32 v64, v32, v33
	v_cvt_pk_bf16_f32 v65, v34, v35
	v_cvt_pk_bf16_f32 v66, v36, v37
	v_cvt_pk_bf16_f32 v67, v38, v39
	v_cvt_pk_bf16_f32 v68, v40, v41
	v_cvt_pk_bf16_f32 v69, v42, v43
	v_cvt_pk_bf16_f32 v70, v44, v45
	v_cvt_pk_bf16_f32 v71, v46, v47
	v_pk_add_f32 v[232:233], v[232:233], v[32:33]
	v_pk_add_f32 v[232:233], v[232:233], v[34:35]
	v_pk_add_f32 v[232:233], v[232:233], v[36:37]
	v_pk_add_f32 v[232:233], v[232:233], v[38:39]
	v_pk_add_f32 v[232:233], v[232:233], v[40:41]
	v_pk_add_f32 v[232:233], v[232:233], v[42:43]
	v_pk_add_f32 v[232:233], v[232:233], v[44:45]
	v_pk_add_f32 v[232:233], v[232:233], v[46:47]
	s_waitcnt lgkmcnt(12)
	v_mfma_f32_32x32x16_bf16 v[0:15], v[64:67], v[72:75], v[0:15]
	v_mfma_f32_32x32x16_bf16 v[16:31], v[64:67], v[76:79], v[16:31]
	v_mfma_f32_32x32x16_bf16 v[0:15], v[68:71], v[220:223], v[0:15]
	v_mfma_f32_32x32x16_bf16 v[16:31], v[68:71], v[224:227], v[16:31]
	s_add_i32 s90, s76, 224
	v_add_u32_e32 v80, s90, v235
	v_add_u32_e32 v83, s90, v236
	v_add_u32_e32 v99, s90, v237
	v_add_u32_e32 v253, s90, v238
	v_add_u32_e32 v254, s90, v100
	v_add_u32_e32 v255, s90, v149
	v_med3_i32 v80, v80, 0, s99
	v_med3_i32 v83, v83, 0, s99
	v_med3_i32 v99, v99, 0, s99
	v_med3_i32 v253, v253, 0, s99
	v_med3_i32 v254, v254, 0, s99
	v_med3_i32 v255, v255, 0, s99
	v_mad_u32_u24 v80, v80, s100, v252
	v_mad_u32_u24 v83, v83, s100, v252
	v_mad_u32_u24 v99, v99, s100, v252
	v_mad_u32_u24 v253, v253, s100, v252
	v_mad_u32_u24 v254, v254, s100, v153
	v_mad_u32_u24 v255, v255, s100, v153
	global_load_dwordx4 v[116:119], v80, s[82:83]
	global_load_dwordx4 v[120:123], v83, s[82:83]
	global_load_dwordx4 v[124:127], v99, s[82:83]
	global_load_dwordx4 v[128:131], v253, s[82:83]
	global_load_dwordx4 v[132:135], v254, s[82:83] offset:768
	global_load_dwordx4 v[136:139], v255, s[82:83] offset:768
	global_load_dwordx4 v[140:143], v254, s[82:83] offset:832
	global_load_dwordx4 v[144:147], v255, s[82:83] offset:832
	v_add_u32_e32 v115, 952, v115
	ds_read2_b32 v[32:33], v115 offset0:0 offset1:1
	ds_read2_b32 v[34:35], v115 offset0:2 offset1:3
	ds_read2_b32 v[36:37], v115 offset0:8 offset1:9
	ds_read2_b32 v[38:39], v115 offset0:10 offset1:11
	ds_read2_b32 v[40:41], v115 offset0:17 offset1:18
	ds_read2_b32 v[42:43], v115 offset0:19 offset1:20
	ds_read2_b32 v[44:45], v115 offset0:25 offset1:26
	ds_read2_b32 v[46:47], v115 offset0:27 offset1:28
	s_waitcnt lgkmcnt(0)
	v_mfma_f32_32x32x16_bf16 v[32:47], v[156:159], v[48:51], v[32:47]
	ds_read_b64_tr_b16 v[72:73], v231
	ds_read_b64_tr_b16 v[74:75], v231 offset:512
	ds_read_b64_tr_b16 v[76:77], v231 offset:2048
	ds_read_b64_tr_b16 v[78:79], v231 offset:2560
	ds_read_b64_tr_b16 v[220:221], v231 offset:1024
	ds_read_b64_tr_b16 v[222:223], v231 offset:1536
	ds_read_b64_tr_b16 v[224:225], v231 offset:3072
	ds_read_b64_tr_b16 v[226:227], v231 offset:3584
	s_waitcnt vmcnt(8)
	ds_write_b128 v247, v[188:191]
	ds_write_b128 v247, v[192:195] offset:1024
	ds_write_b128 v247, v[196:199] offset:2048
	ds_write_b128 v247, v[200:203] offset:3072
	ds_read_b128 v[188:191], v248
	ds_read_b128 v[192:195], v249
	ds_read_b128 v[196:199], v250
	ds_read_b128 v[200:203], v251
	ds_write_b128 v112, v[204:207]
	ds_write_b128 v112, v[208:211] offset:1024
	ds_write_b128 v112, v[212:215] offset:2048
	ds_write_b128 v112, v[216:219] offset:3072
	v_mfma_f32_32x32x16_bf16 v[32:47], v[160:163], v[52:55], v[32:47]
	v_mfma_f32_32x32x16_bf16 v[32:47], v[164:167], v[56:59], v[32:47]
	v_mfma_f32_32x32x16_bf16 v[32:47], v[168:171], v[60:63], v[32:47]
	s_nop 11
	v_exp_f32_e32 v32, v32
	v_exp_f32_e32 v33, v33
	v_exp_f32_e32 v34, v34
	v_exp_f32_e32 v35, v35
	v_exp_f32_e32 v36, v36
	v_exp_f32_e32 v37, v37
	v_exp_f32_e32 v38, v38
	v_exp_f32_e32 v39, v39
	v_exp_f32_e32 v40, v40
	v_exp_f32_e32 v41, v41
	v_exp_f32_e32 v42, v42
	v_exp_f32_e32 v43, v43
	v_exp_f32_e32 v44, v44
	v_exp_f32_e32 v45, v45
	v_exp_f32_e32 v46, v46
	v_exp_f32_e32 v47, v47
	s_add_i32 s90, s76, 160
	v_add_u32_e32 v84, s90, v107
	v_add_u32_e32 v85, 0, v84
	v_add_u32_e32 v86, 1, v84
	v_add_u32_e32 v87, 2, v84
	v_add_u32_e32 v88, 3, v84
	v_cmp_gt_u32_e64 s[30:31], s98, v85
	v_cmp_gt_u32_e64 s[36:37], s98, v86
	v_cmp_gt_u32_e64 s[78:79], s98, v87
	v_cmp_gt_u32_e64 s[50:51], s98, v88
	v_cndmask_b32_e64 v32, 0, v32, s[30:31]
	v_add_u32_e32 v85, 8, v84
	v_cmp_gt_u32_e64 s[30:31], s98, v85
	v_cndmask_b32_e64 v33, 0, v33, s[36:37]
	v_add_u32_e32 v86, 9, v84
	v_cmp_gt_u32_e64 s[36:37], s98, v86
	v_cndmask_b32_e64 v34, 0, v34, s[78:79]
	v_add_u32_e32 v87, 10, v84
	v_cmp_gt_u32_e64 s[78:79], s98, v87
	v_cndmask_b32_e64 v35, 0, v35, s[50:51]
	v_add_u32_e32 v88, 11, v84
	v_cmp_gt_u32_e64 s[50:51], s98, v88
	v_cndmask_b32_e64 v36, 0, v36, s[30:31]
	v_add_u32_e32 v85, 16, v84
	v_cmp_gt_u32_e64 s[30:31], s98, v85
	v_cndmask_b32_e64 v37, 0, v37, s[36:37]
	v_add_u32_e32 v86, 17, v84
	v_cmp_gt_u32_e64 s[36:37], s98, v86
	v_cndmask_b32_e64 v38, 0, v38, s[78:79]
	v_add_u32_e32 v87, 18, v84
	v_cmp_gt_u32_e64 s[78:79], s98, v87
	v_cndmask_b32_e64 v39, 0, v39, s[50:51]
	v_add_u32_e32 v88, 19, v84
	v_cmp_gt_u32_e64 s[50:51], s98, v88
	v_cndmask_b32_e64 v40, 0, v40, s[30:31]
	v_add_u32_e32 v85, 24, v84
	v_cmp_gt_u32_e64 s[30:31], s98, v85
	v_cndmask_b32_e64 v41, 0, v41, s[36:37]
	v_add_u32_e32 v86, 25, v84
	v_cmp_gt_u32_e64 s[36:37], s98, v86
	v_cndmask_b32_e64 v42, 0, v42, s[78:79]
	v_add_u32_e32 v87, 26, v84
	v_cmp_gt_u32_e64 s[78:79], s98, v87
	v_cndmask_b32_e64 v43, 0, v43, s[50:51]
	v_add_u32_e32 v88, 27, v84
	v_cmp_gt_u32_e64 s[50:51], s98, v88
	v_nop
	v_cndmask_b32_e64 v44, 0, v44, s[30:31]
	v_cndmask_b32_e64 v45, 0, v45, s[36:37]
	v_cndmask_b32_e64 v46, 0, v46, s[78:79]
	v_cndmask_b32_e64 v47, 0, v47, s[50:51]
	v_cvt_pk_bf16_f32 v64, v32, v33
	v_cvt_pk_bf16_f32 v65, v34, v35
	v_cvt_pk_bf16_f32 v66, v36, v37
	v_cvt_pk_bf16_f32 v67, v38, v39
	v_cvt_pk_bf16_f32 v68, v40, v41
	v_cvt_pk_bf16_f32 v69, v42, v43
	v_cvt_pk_bf16_f32 v70, v44, v45
	v_cvt_pk_bf16_f32 v71, v46, v47
	v_pk_add_f32 v[232:233], v[232:233], v[32:33]
	v_pk_add_f32 v[232:233], v[232:233], v[34:35]
	v_pk_add_f32 v[232:233], v[232:233], v[36:37]
	v_pk_add_f32 v[232:233], v[232:233], v[38:39]
	v_pk_add_f32 v[232:233], v[232:233], v[40:41]
	v_pk_add_f32 v[232:233], v[232:233], v[42:43]
	v_pk_add_f32 v[232:233], v[232:233], v[44:45]
	v_pk_add_f32 v[232:233], v[232:233], v[46:47]
	s_waitcnt lgkmcnt(12)
	v_mfma_f32_32x32x16_bf16 v[0:15], v[64:67], v[72:75], v[0:15]
	v_mfma_f32_32x32x16_bf16 v[16:31], v[64:67], v[76:79], v[16:31]
	v_mfma_f32_32x32x16_bf16 v[0:15], v[68:71], v[220:223], v[0:15]
	v_mfma_f32_32x32x16_bf16 v[16:31], v[68:71], v[224:227], v[16:31]
	s_add_i32 s90, s76, 256
	v_add_u32_e32 v80, s90, v235
	v_add_u32_e32 v83, s90, v236
	v_add_u32_e32 v99, s90, v237
	v_add_u32_e32 v253, s90, v238
	v_add_u32_e32 v254, s90, v100
	v_add_u32_e32 v255, s90, v149
	v_med3_i32 v80, v80, 0, s99
	v_med3_i32 v83, v83, 0, s99
	v_med3_i32 v99, v99, 0, s99
	v_med3_i32 v253, v253, 0, s99
	v_med3_i32 v254, v254, 0, s99
	v_med3_i32 v255, v255, 0, s99
	v_mad_u32_u24 v80, v80, s100, v252
	v_mad_u32_u24 v83, v83, s100, v252
	v_mad_u32_u24 v99, v99, s100, v252
	v_mad_u32_u24 v253, v253, s100, v252
	v_mad_u32_u24 v254, v254, s100, v153
	v_mad_u32_u24 v255, v255, s100, v153
	global_load_dwordx4 v[156:159], v80, s[82:83]
	global_load_dwordx4 v[160:163], v83, s[82:83]
	global_load_dwordx4 v[164:167], v99, s[82:83]
	global_load_dwordx4 v[168:171], v253, s[82:83]
	global_load_dwordx4 v[172:175], v254, s[82:83] offset:768
	global_load_dwordx4 v[176:179], v255, s[82:83] offset:768
	global_load_dwordx4 v[180:183], v254, s[82:83] offset:832
	global_load_dwordx4 v[184:187], v255, s[82:83] offset:832
	ds_read2_b32 v[32:33], v115 offset0:34 offset1:35
	ds_read2_b32 v[34:35], v115 offset0:36 offset1:37
	ds_read2_b32 v[36:37], v115 offset0:42 offset1:43
	ds_read2_b32 v[38:39], v115 offset0:44 offset1:45
	ds_read2_b32 v[40:41], v115 offset0:51 offset1:52
	ds_read2_b32 v[42:43], v115 offset0:53 offset1:54
	ds_read2_b32 v[44:45], v115 offset0:59 offset1:60
	ds_read2_b32 v[46:47], v115 offset0:61 offset1:62
	s_waitcnt lgkmcnt(0)
	v_mfma_f32_32x32x16_bf16 v[32:47], v[188:191], v[48:51], v[32:47]
	ds_read_b64_tr_b16 v[72:73], v231
	ds_read_b64_tr_b16 v[74:75], v231 offset:512
	ds_read_b64_tr_b16 v[76:77], v231 offset:2048
	ds_read_b64_tr_b16 v[78:79], v231 offset:2560
	ds_read_b64_tr_b16 v[220:221], v231 offset:1024
	ds_read_b64_tr_b16 v[222:223], v231 offset:1536
	ds_read_b64_tr_b16 v[224:225], v231 offset:3072
	ds_read_b64_tr_b16 v[226:227], v231 offset:3584
	s_waitcnt vmcnt(8)
	ds_write_b128 v247, v[116:119]
	ds_write_b128 v247, v[120:123] offset:1024
	ds_write_b128 v247, v[124:127] offset:2048
	ds_write_b128 v247, v[128:131] offset:3072
	ds_read_b128 v[116:119], v248
	ds_read_b128 v[120:123], v249
	ds_read_b128 v[124:127], v250
	ds_read_b128 v[128:131], v251
	ds_write_b128 v112, v[132:135]
	ds_write_b128 v112, v[136:139] offset:1024
	ds_write_b128 v112, v[140:143] offset:2048
	ds_write_b128 v112, v[144:147] offset:3072
	v_mfma_f32_32x32x16_bf16 v[32:47], v[192:195], v[52:55], v[32:47]
	v_mfma_f32_32x32x16_bf16 v[32:47], v[196:199], v[56:59], v[32:47]
	v_mfma_f32_32x32x16_bf16 v[32:47], v[200:203], v[60:63], v[32:47]
	s_nop 11
	v_exp_f32_e32 v32, v32
	v_exp_f32_e32 v33, v33
	v_exp_f32_e32 v34, v34
	v_exp_f32_e32 v35, v35
	v_exp_f32_e32 v36, v36
	v_exp_f32_e32 v37, v37
	v_exp_f32_e32 v38, v38
	v_exp_f32_e32 v39, v39
	v_exp_f32_e32 v40, v40
	v_exp_f32_e32 v41, v41
	v_exp_f32_e32 v42, v42
	v_exp_f32_e32 v43, v43
	v_exp_f32_e32 v44, v44
	v_exp_f32_e32 v45, v45
	v_exp_f32_e32 v46, v46
	v_exp_f32_e32 v47, v47
	s_add_i32 s90, s76, 192
	v_add_u32_e32 v84, s90, v107
	v_add_u32_e32 v85, 0, v84
	v_add_u32_e32 v86, 1, v84
	v_add_u32_e32 v87, 2, v84
	v_add_u32_e32 v88, 3, v84
	v_cmp_gt_u32_e64 s[30:31], s98, v85
	v_cmp_gt_u32_e64 s[36:37], s98, v86
	v_cmp_gt_u32_e64 s[78:79], s98, v87
	v_cmp_gt_u32_e64 s[50:51], s98, v88
	v_cndmask_b32_e64 v32, 0, v32, s[30:31]
	v_add_u32_e32 v85, 8, v84
	v_cmp_gt_u32_e64 s[30:31], s98, v85
	v_cndmask_b32_e64 v33, 0, v33, s[36:37]
	v_add_u32_e32 v86, 9, v84
	v_cmp_gt_u32_e64 s[36:37], s98, v86
	v_cndmask_b32_e64 v34, 0, v34, s[78:79]
	v_add_u32_e32 v87, 10, v84
	v_cmp_gt_u32_e64 s[78:79], s98, v87
	v_cndmask_b32_e64 v35, 0, v35, s[50:51]
	v_add_u32_e32 v88, 11, v84
	v_cmp_gt_u32_e64 s[50:51], s98, v88
	v_cndmask_b32_e64 v36, 0, v36, s[30:31]
	v_add_u32_e32 v85, 16, v84
	v_cmp_gt_u32_e64 s[30:31], s98, v85
	v_cndmask_b32_e64 v37, 0, v37, s[36:37]
	v_add_u32_e32 v86, 17, v84
	v_cmp_gt_u32_e64 s[36:37], s98, v86
	v_cndmask_b32_e64 v38, 0, v38, s[78:79]
	v_add_u32_e32 v87, 18, v84
	v_cmp_gt_u32_e64 s[78:79], s98, v87
	v_cndmask_b32_e64 v39, 0, v39, s[50:51]
	v_add_u32_e32 v88, 19, v84
	v_cmp_gt_u32_e64 s[50:51], s98, v88
	v_cndmask_b32_e64 v40, 0, v40, s[30:31]
	v_add_u32_e32 v85, 24, v84
	v_cmp_gt_u32_e64 s[30:31], s98, v85
	v_cndmask_b32_e64 v41, 0, v41, s[36:37]
	v_add_u32_e32 v86, 25, v84
	v_cmp_gt_u32_e64 s[36:37], s98, v86
	v_cndmask_b32_e64 v42, 0, v42, s[78:79]
	v_add_u32_e32 v87, 26, v84
	v_cmp_gt_u32_e64 s[78:79], s98, v87
	v_cndmask_b32_e64 v43, 0, v43, s[50:51]
	v_add_u32_e32 v88, 27, v84
	v_cmp_gt_u32_e64 s[50:51], s98, v88
	v_nop
	v_cndmask_b32_e64 v44, 0, v44, s[30:31]
	v_cndmask_b32_e64 v45, 0, v45, s[36:37]
	v_cndmask_b32_e64 v46, 0, v46, s[78:79]
	v_cndmask_b32_e64 v47, 0, v47, s[50:51]
	v_cvt_pk_bf16_f32 v64, v32, v33
	v_cvt_pk_bf16_f32 v65, v34, v35
	v_cvt_pk_bf16_f32 v66, v36, v37
	v_cvt_pk_bf16_f32 v67, v38, v39
	v_cvt_pk_bf16_f32 v68, v40, v41
	v_cvt_pk_bf16_f32 v69, v42, v43
	v_cvt_pk_bf16_f32 v70, v44, v45
	v_cvt_pk_bf16_f32 v71, v46, v47
	v_pk_add_f32 v[232:233], v[232:233], v[32:33]
	v_pk_add_f32 v[232:233], v[232:233], v[34:35]
	v_pk_add_f32 v[232:233], v[232:233], v[36:37]
	v_pk_add_f32 v[232:233], v[232:233], v[38:39]
	v_pk_add_f32 v[232:233], v[232:233], v[40:41]
	v_pk_add_f32 v[232:233], v[232:233], v[42:43]
	v_pk_add_f32 v[232:233], v[232:233], v[44:45]
	v_pk_add_f32 v[232:233], v[232:233], v[46:47]
	s_waitcnt lgkmcnt(12)
	v_mfma_f32_32x32x16_bf16 v[0:15], v[64:67], v[72:75], v[0:15]
	v_mfma_f32_32x32x16_bf16 v[16:31], v[64:67], v[76:79], v[16:31]
	v_mfma_f32_32x32x16_bf16 v[0:15], v[68:71], v[220:223], v[0:15]
	v_mfma_f32_32x32x16_bf16 v[16:31], v[68:71], v[224:227], v[16:31]
	s_add_i32 s90, s76, 288
	v_add_u32_e32 v80, s90, v235
	v_add_u32_e32 v83, s90, v236
	v_add_u32_e32 v99, s90, v237
	v_add_u32_e32 v253, s90, v238
	v_add_u32_e32 v254, s90, v100
	v_add_u32_e32 v255, s90, v149
	v_med3_i32 v80, v80, 0, s99
	v_med3_i32 v83, v83, 0, s99
	v_med3_i32 v99, v99, 0, s99
	v_med3_i32 v253, v253, 0, s99
	v_med3_i32 v254, v254, 0, s99
	v_med3_i32 v255, v255, 0, s99
	v_mad_u32_u24 v80, v80, s100, v252
	v_mad_u32_u24 v83, v83, s100, v252
	v_mad_u32_u24 v99, v99, s100, v252
	v_mad_u32_u24 v253, v253, s100, v252
	v_mad_u32_u24 v254, v254, s100, v153
	v_mad_u32_u24 v255, v255, s100, v153
	global_load_dwordx4 v[188:191], v80, s[82:83]
	global_load_dwordx4 v[192:195], v83, s[82:83]
	global_load_dwordx4 v[196:199], v99, s[82:83]
	global_load_dwordx4 v[200:203], v253, s[82:83]
	global_load_dwordx4 v[204:207], v254, s[82:83] offset:768
	global_load_dwordx4 v[208:211], v255, s[82:83] offset:768
	global_load_dwordx4 v[212:215], v254, s[82:83] offset:832
	global_load_dwordx4 v[216:219], v255, s[82:83] offset:832
	ds_read2_b32 v[32:33], v115 offset0:68 offset1:69
	ds_read2_b32 v[34:35], v115 offset0:70 offset1:71
	ds_read2_b32 v[36:37], v115 offset0:76 offset1:77
	ds_read2_b32 v[38:39], v115 offset0:78 offset1:79
	ds_read2_b32 v[40:41], v115 offset0:85 offset1:86
	ds_read2_b32 v[42:43], v115 offset0:87 offset1:88
	ds_read2_b32 v[44:45], v115 offset0:93 offset1:94
	ds_read2_b32 v[46:47], v115 offset0:95 offset1:96
	s_waitcnt lgkmcnt(0)
	v_mfma_f32_32x32x16_bf16 v[32:47], v[116:119], v[48:51], v[32:47]
	ds_read_b64_tr_b16 v[72:73], v231
	ds_read_b64_tr_b16 v[74:75], v231 offset:512
	ds_read_b64_tr_b16 v[76:77], v231 offset:2048
	ds_read_b64_tr_b16 v[78:79], v231 offset:2560
	ds_read_b64_tr_b16 v[220:221], v231 offset:1024
	ds_read_b64_tr_b16 v[222:223], v231 offset:1536
	ds_read_b64_tr_b16 v[224:225], v231 offset:3072
	ds_read_b64_tr_b16 v[226:227], v231 offset:3584
	s_waitcnt vmcnt(8)
	ds_write_b128 v247, v[156:159]
	ds_write_b128 v247, v[160:163] offset:1024
	ds_write_b128 v247, v[164:167] offset:2048
	ds_write_b128 v247, v[168:171] offset:3072
	ds_read_b128 v[156:159], v248
	ds_read_b128 v[160:163], v249
	ds_read_b128 v[164:167], v250
	ds_read_b128 v[168:171], v251
	ds_write_b128 v112, v[172:175]
	ds_write_b128 v112, v[176:179] offset:1024
	ds_write_b128 v112, v[180:183] offset:2048
	ds_write_b128 v112, v[184:187] offset:3072
	v_mfma_f32_32x32x16_bf16 v[32:47], v[120:123], v[52:55], v[32:47]
	v_mfma_f32_32x32x16_bf16 v[32:47], v[124:127], v[56:59], v[32:47]
	v_mfma_f32_32x32x16_bf16 v[32:47], v[128:131], v[60:63], v[32:47]
	s_nop 11
	v_exp_f32_e32 v32, v32
	v_exp_f32_e32 v33, v33
	v_exp_f32_e32 v34, v34
	v_exp_f32_e32 v35, v35
	v_exp_f32_e32 v36, v36
	v_exp_f32_e32 v37, v37
	v_exp_f32_e32 v38, v38
	v_exp_f32_e32 v39, v39
	v_exp_f32_e32 v40, v40
	v_exp_f32_e32 v41, v41
	v_exp_f32_e32 v42, v42
	v_exp_f32_e32 v43, v43
	v_exp_f32_e32 v44, v44
	v_exp_f32_e32 v45, v45
	v_exp_f32_e32 v46, v46
	v_exp_f32_e32 v47, v47
	s_add_i32 s90, s76, 224
	v_add_u32_e32 v84, s90, v107
	v_add_u32_e32 v85, 0, v84
	v_add_u32_e32 v86, 1, v84
	v_add_u32_e32 v87, 2, v84
	v_add_u32_e32 v88, 3, v84
	v_cmp_gt_u32_e64 s[30:31], s98, v85
	v_cmp_gt_u32_e64 s[36:37], s98, v86
	v_cmp_gt_u32_e64 s[78:79], s98, v87
	v_cmp_gt_u32_e64 s[50:51], s98, v88
	v_cndmask_b32_e64 v32, 0, v32, s[30:31]
	v_add_u32_e32 v85, 8, v84
	v_cmp_gt_u32_e64 s[30:31], s98, v85
	v_cndmask_b32_e64 v33, 0, v33, s[36:37]
	v_add_u32_e32 v86, 9, v84
	v_cmp_gt_u32_e64 s[36:37], s98, v86
	v_cndmask_b32_e64 v34, 0, v34, s[78:79]
	v_add_u32_e32 v87, 10, v84
	v_cmp_gt_u32_e64 s[78:79], s98, v87
	v_cndmask_b32_e64 v35, 0, v35, s[50:51]
	v_add_u32_e32 v88, 11, v84
	v_cmp_gt_u32_e64 s[50:51], s98, v88
	v_cndmask_b32_e64 v36, 0, v36, s[30:31]
	v_add_u32_e32 v85, 16, v84
	v_cmp_gt_u32_e64 s[30:31], s98, v85
	v_cndmask_b32_e64 v37, 0, v37, s[36:37]
	v_add_u32_e32 v86, 17, v84
	v_cmp_gt_u32_e64 s[36:37], s98, v86
	v_cndmask_b32_e64 v38, 0, v38, s[78:79]
	v_add_u32_e32 v87, 18, v84
	v_cmp_gt_u32_e64 s[78:79], s98, v87
	v_cndmask_b32_e64 v39, 0, v39, s[50:51]
	v_add_u32_e32 v88, 19, v84
	v_cmp_gt_u32_e64 s[50:51], s98, v88
	v_cndmask_b32_e64 v40, 0, v40, s[30:31]
	v_add_u32_e32 v85, 24, v84
	v_cmp_gt_u32_e64 s[30:31], s98, v85
	v_cndmask_b32_e64 v41, 0, v41, s[36:37]
	v_add_u32_e32 v86, 25, v84
	v_cmp_gt_u32_e64 s[36:37], s98, v86
	v_cndmask_b32_e64 v42, 0, v42, s[78:79]
	v_add_u32_e32 v87, 26, v84
	v_cmp_gt_u32_e64 s[78:79], s98, v87
	v_cndmask_b32_e64 v43, 0, v43, s[50:51]
	v_add_u32_e32 v88, 27, v84
	v_cmp_gt_u32_e64 s[50:51], s98, v88
	v_nop
	v_cndmask_b32_e64 v44, 0, v44, s[30:31]
	v_cndmask_b32_e64 v45, 0, v45, s[36:37]
	v_cndmask_b32_e64 v46, 0, v46, s[78:79]
	v_cndmask_b32_e64 v47, 0, v47, s[50:51]
	v_cvt_pk_bf16_f32 v64, v32, v33
	v_cvt_pk_bf16_f32 v65, v34, v35
	v_cvt_pk_bf16_f32 v66, v36, v37
	v_cvt_pk_bf16_f32 v67, v38, v39
	v_cvt_pk_bf16_f32 v68, v40, v41
	v_cvt_pk_bf16_f32 v69, v42, v43
	v_cvt_pk_bf16_f32 v70, v44, v45
	v_cvt_pk_bf16_f32 v71, v46, v47
	v_pk_add_f32 v[232:233], v[232:233], v[32:33]
	v_pk_add_f32 v[232:233], v[232:233], v[34:35]
	v_pk_add_f32 v[232:233], v[232:233], v[36:37]
	v_pk_add_f32 v[232:233], v[232:233], v[38:39]
	v_pk_add_f32 v[232:233], v[232:233], v[40:41]
	v_pk_add_f32 v[232:233], v[232:233], v[42:43]
	v_pk_add_f32 v[232:233], v[232:233], v[44:45]
	v_pk_add_f32 v[232:233], v[232:233], v[46:47]
	s_waitcnt lgkmcnt(12)
	v_mfma_f32_32x32x16_bf16 v[0:15], v[64:67], v[72:75], v[0:15]
	v_mfma_f32_32x32x16_bf16 v[16:31], v[64:67], v[76:79], v[16:31]
	v_mfma_f32_32x32x16_bf16 v[0:15], v[68:71], v[220:223], v[0:15]
	v_mfma_f32_32x32x16_bf16 v[16:31], v[68:71], v[224:227], v[16:31]
	s_add_i32 s90, s76, 320
	v_add_u32_e32 v80, s90, v235
	v_add_u32_e32 v83, s90, v236
	v_add_u32_e32 v99, s90, v237
	v_add_u32_e32 v253, s90, v238
	v_add_u32_e32 v254, s90, v100
	v_add_u32_e32 v255, s90, v149
	v_med3_i32 v80, v80, 0, s99
	v_med3_i32 v83, v83, 0, s99
	v_med3_i32 v99, v99, 0, s99
	v_med3_i32 v253, v253, 0, s99
	v_med3_i32 v254, v254, 0, s99
	v_med3_i32 v255, v255, 0, s99
	v_mad_u32_u24 v80, v80, s100, v252
	v_mad_u32_u24 v83, v83, s100, v252
	v_mad_u32_u24 v99, v99, s100, v252
	v_mad_u32_u24 v253, v253, s100, v252
	v_mad_u32_u24 v254, v254, s100, v153
	v_mad_u32_u24 v255, v255, s100, v153
	global_load_dwordx4 v[116:119], v80, s[82:83]
	global_load_dwordx4 v[120:123], v83, s[82:83]
	global_load_dwordx4 v[124:127], v99, s[82:83]
	global_load_dwordx4 v[128:131], v253, s[82:83]
	global_load_dwordx4 v[132:135], v254, s[82:83] offset:768
	global_load_dwordx4 v[136:139], v255, s[82:83] offset:768
	global_load_dwordx4 v[140:143], v254, s[82:83] offset:832
	global_load_dwordx4 v[144:147], v255, s[82:83] offset:832
	ds_read2_b32 v[32:33], v115 offset0:102 offset1:103
	ds_read2_b32 v[34:35], v115 offset0:104 offset1:105
	ds_read2_b32 v[36:37], v115 offset0:110 offset1:111
	ds_read2_b32 v[38:39], v115 offset0:112 offset1:113
	ds_read2_b32 v[40:41], v115 offset0:119 offset1:120
	ds_read2_b32 v[42:43], v115 offset0:121 offset1:122
	ds_read2_b32 v[44:45], v115 offset0:127 offset1:128
	ds_read2_b32 v[46:47], v115 offset0:129 offset1:130
	s_waitcnt lgkmcnt(0)
	v_mfma_f32_32x32x16_bf16 v[32:47], v[156:159], v[48:51], v[32:47]
	ds_read_b64_tr_b16 v[72:73], v231
	ds_read_b64_tr_b16 v[74:75], v231 offset:512
	ds_read_b64_tr_b16 v[76:77], v231 offset:2048
	ds_read_b64_tr_b16 v[78:79], v231 offset:2560
	ds_read_b64_tr_b16 v[220:221], v231 offset:1024
	ds_read_b64_tr_b16 v[222:223], v231 offset:1536
	ds_read_b64_tr_b16 v[224:225], v231 offset:3072
	ds_read_b64_tr_b16 v[226:227], v231 offset:3584
	s_waitcnt vmcnt(8)
	ds_write_b128 v247, v[188:191]
	ds_write_b128 v247, v[192:195] offset:1024
	ds_write_b128 v247, v[196:199] offset:2048
	ds_write_b128 v247, v[200:203] offset:3072
	ds_read_b128 v[188:191], v248
	ds_read_b128 v[192:195], v249
	ds_read_b128 v[196:199], v250
	ds_read_b128 v[200:203], v251
	ds_write_b128 v112, v[204:207]
	ds_write_b128 v112, v[208:211] offset:1024
	ds_write_b128 v112, v[212:215] offset:2048
	ds_write_b128 v112, v[216:219] offset:3072
	v_mfma_f32_32x32x16_bf16 v[32:47], v[160:163], v[52:55], v[32:47]
	v_mfma_f32_32x32x16_bf16 v[32:47], v[164:167], v[56:59], v[32:47]
	v_mfma_f32_32x32x16_bf16 v[32:47], v[168:171], v[60:63], v[32:47]
	s_nop 11
	v_exp_f32_e32 v32, v32
	v_exp_f32_e32 v33, v33
	v_exp_f32_e32 v34, v34
	v_exp_f32_e32 v35, v35
	v_exp_f32_e32 v36, v36
	v_exp_f32_e32 v37, v37
	v_exp_f32_e32 v38, v38
	v_exp_f32_e32 v39, v39
	v_exp_f32_e32 v40, v40
	v_exp_f32_e32 v41, v41
	v_exp_f32_e32 v42, v42
	v_exp_f32_e32 v43, v43
	v_exp_f32_e32 v44, v44
	v_exp_f32_e32 v45, v45
	v_exp_f32_e32 v46, v46
	v_exp_f32_e32 v47, v47
	s_add_i32 s90, s76, 256
	v_add_u32_e32 v84, s90, v107
	v_add_u32_e32 v85, 0, v84
	v_add_u32_e32 v86, 1, v84
	v_add_u32_e32 v87, 2, v84
	v_add_u32_e32 v88, 3, v84
	v_cmp_gt_u32_e64 s[30:31], s98, v85
	v_cmp_gt_u32_e64 s[36:37], s98, v86
	v_cmp_gt_u32_e64 s[78:79], s98, v87
	v_cmp_gt_u32_e64 s[50:51], s98, v88
	v_cndmask_b32_e64 v32, 0, v32, s[30:31]
	v_add_u32_e32 v85, 8, v84
	v_cmp_gt_u32_e64 s[30:31], s98, v85
	v_cndmask_b32_e64 v33, 0, v33, s[36:37]
	v_add_u32_e32 v86, 9, v84
	v_cmp_gt_u32_e64 s[36:37], s98, v86
	v_cndmask_b32_e64 v34, 0, v34, s[78:79]
	v_add_u32_e32 v87, 10, v84
	v_cmp_gt_u32_e64 s[78:79], s98, v87
	v_cndmask_b32_e64 v35, 0, v35, s[50:51]
	v_add_u32_e32 v88, 11, v84
	v_cmp_gt_u32_e64 s[50:51], s98, v88
	v_cndmask_b32_e64 v36, 0, v36, s[30:31]
	v_add_u32_e32 v85, 16, v84
	v_cmp_gt_u32_e64 s[30:31], s98, v85
	v_cndmask_b32_e64 v37, 0, v37, s[36:37]
	v_add_u32_e32 v86, 17, v84
	v_cmp_gt_u32_e64 s[36:37], s98, v86
	v_cndmask_b32_e64 v38, 0, v38, s[78:79]
	v_add_u32_e32 v87, 18, v84
	v_cmp_gt_u32_e64 s[78:79], s98, v87
	v_cndmask_b32_e64 v39, 0, v39, s[50:51]
	v_add_u32_e32 v88, 19, v84
	v_cmp_gt_u32_e64 s[50:51], s98, v88
	v_cndmask_b32_e64 v40, 0, v40, s[30:31]
	v_add_u32_e32 v85, 24, v84
	v_cmp_gt_u32_e64 s[30:31], s98, v85
	v_cndmask_b32_e64 v41, 0, v41, s[36:37]
	v_add_u32_e32 v86, 25, v84
	v_cmp_gt_u32_e64 s[36:37], s98, v86
	v_cndmask_b32_e64 v42, 0, v42, s[78:79]
	v_add_u32_e32 v87, 26, v84
	v_cmp_gt_u32_e64 s[78:79], s98, v87
	v_cndmask_b32_e64 v43, 0, v43, s[50:51]
	v_add_u32_e32 v88, 27, v84
	v_cmp_gt_u32_e64 s[50:51], s98, v88
	v_nop
	v_cndmask_b32_e64 v44, 0, v44, s[30:31]
	v_cndmask_b32_e64 v45, 0, v45, s[36:37]
	v_cndmask_b32_e64 v46, 0, v46, s[78:79]
	v_cndmask_b32_e64 v47, 0, v47, s[50:51]
	v_cvt_pk_bf16_f32 v64, v32, v33
	v_cvt_pk_bf16_f32 v65, v34, v35
	v_cvt_pk_bf16_f32 v66, v36, v37
	v_cvt_pk_bf16_f32 v67, v38, v39
	v_cvt_pk_bf16_f32 v68, v40, v41
	v_cvt_pk_bf16_f32 v69, v42, v43
	v_cvt_pk_bf16_f32 v70, v44, v45
	v_cvt_pk_bf16_f32 v71, v46, v47
	v_pk_add_f32 v[232:233], v[232:233], v[32:33]
	v_pk_add_f32 v[232:233], v[232:233], v[34:35]
	v_pk_add_f32 v[232:233], v[232:233], v[36:37]
	v_pk_add_f32 v[232:233], v[232:233], v[38:39]
	v_pk_add_f32 v[232:233], v[232:233], v[40:41]
	v_pk_add_f32 v[232:233], v[232:233], v[42:43]
	v_pk_add_f32 v[232:233], v[232:233], v[44:45]
	v_pk_add_f32 v[232:233], v[232:233], v[46:47]
	s_waitcnt lgkmcnt(12)
	v_mfma_f32_32x32x16_bf16 v[0:15], v[64:67], v[72:75], v[0:15]
	v_mfma_f32_32x32x16_bf16 v[16:31], v[64:67], v[76:79], v[16:31]
	v_mfma_f32_32x32x16_bf16 v[0:15], v[68:71], v[220:223], v[0:15]
	v_mfma_f32_32x32x16_bf16 v[16:31], v[68:71], v[224:227], v[16:31]
	s_add_i32 s90, s76, 352
	v_add_u32_e32 v80, s90, v235
	v_add_u32_e32 v83, s90, v236
	v_add_u32_e32 v99, s90, v237
	v_add_u32_e32 v253, s90, v238
	v_add_u32_e32 v254, s90, v100
	v_add_u32_e32 v255, s90, v149
	v_med3_i32 v80, v80, 0, s99
	v_med3_i32 v83, v83, 0, s99
	v_med3_i32 v99, v99, 0, s99
	v_med3_i32 v253, v253, 0, s99
	v_med3_i32 v254, v254, 0, s99
	v_med3_i32 v255, v255, 0, s99
	v_mad_u32_u24 v80, v80, s100, v252
	v_mad_u32_u24 v83, v83, s100, v252
	v_mad_u32_u24 v99, v99, s100, v252
	v_mad_u32_u24 v253, v253, s100, v252
	v_mad_u32_u24 v254, v254, s100, v153
	v_mad_u32_u24 v255, v255, s100, v153
	global_load_dwordx4 v[156:159], v80, s[82:83]
	global_load_dwordx4 v[160:163], v83, s[82:83]
	global_load_dwordx4 v[164:167], v99, s[82:83]
	global_load_dwordx4 v[168:171], v253, s[82:83]
	global_load_dwordx4 v[172:175], v254, s[82:83] offset:768
	global_load_dwordx4 v[176:179], v255, s[82:83] offset:768
	global_load_dwordx4 v[180:183], v254, s[82:83] offset:832
	global_load_dwordx4 v[184:187], v255, s[82:83] offset:832
	ds_read2_b32 v[32:33], v115 offset0:136 offset1:137
	ds_read2_b32 v[34:35], v115 offset0:138 offset1:139
	ds_read2_b32 v[36:37], v115 offset0:144 offset1:145
	ds_read2_b32 v[38:39], v115 offset0:146 offset1:147
	ds_read2_b32 v[40:41], v115 offset0:153 offset1:154
	ds_read2_b32 v[42:43], v115 offset0:155 offset1:156
	ds_read2_b32 v[44:45], v115 offset0:161 offset1:162
	ds_read2_b32 v[46:47], v115 offset0:163 offset1:164
	s_waitcnt lgkmcnt(0)
	v_mfma_f32_32x32x16_bf16 v[32:47], v[188:191], v[48:51], v[32:47]
	ds_read_b64_tr_b16 v[72:73], v231
	ds_read_b64_tr_b16 v[74:75], v231 offset:512
	ds_read_b64_tr_b16 v[76:77], v231 offset:2048
	ds_read_b64_tr_b16 v[78:79], v231 offset:2560
	ds_read_b64_tr_b16 v[220:221], v231 offset:1024
	ds_read_b64_tr_b16 v[222:223], v231 offset:1536
	ds_read_b64_tr_b16 v[224:225], v231 offset:3072
	ds_read_b64_tr_b16 v[226:227], v231 offset:3584
	s_waitcnt vmcnt(8)
	ds_write_b128 v247, v[116:119]
	ds_write_b128 v247, v[120:123] offset:1024
	ds_write_b128 v247, v[124:127] offset:2048
	ds_write_b128 v247, v[128:131] offset:3072
	ds_read_b128 v[116:119], v248
	ds_read_b128 v[120:123], v249
	ds_read_b128 v[124:127], v250
	ds_read_b128 v[128:131], v251
	ds_write_b128 v112, v[132:135]
	ds_write_b128 v112, v[136:139] offset:1024
	ds_write_b128 v112, v[140:143] offset:2048
	ds_write_b128 v112, v[144:147] offset:3072
	v_mfma_f32_32x32x16_bf16 v[32:47], v[192:195], v[52:55], v[32:47]
	v_mfma_f32_32x32x16_bf16 v[32:47], v[196:199], v[56:59], v[32:47]
	v_mfma_f32_32x32x16_bf16 v[32:47], v[200:203], v[60:63], v[32:47]
	s_nop 11
	v_exp_f32_e32 v32, v32
	v_exp_f32_e32 v33, v33
	v_exp_f32_e32 v34, v34
	v_exp_f32_e32 v35, v35
	v_exp_f32_e32 v36, v36
	v_exp_f32_e32 v37, v37
	v_exp_f32_e32 v38, v38
	v_exp_f32_e32 v39, v39
	v_exp_f32_e32 v40, v40
	v_exp_f32_e32 v41, v41
	v_exp_f32_e32 v42, v42
	v_exp_f32_e32 v43, v43
	v_exp_f32_e32 v44, v44
	v_exp_f32_e32 v45, v45
	v_exp_f32_e32 v46, v46
	v_exp_f32_e32 v47, v47
	s_add_i32 s90, s76, 288
	v_add_u32_e32 v84, s90, v107
	v_add_u32_e32 v85, 0, v84
	v_add_u32_e32 v86, 1, v84
	v_add_u32_e32 v87, 2, v84
	v_add_u32_e32 v88, 3, v84
	v_cmp_gt_u32_e64 s[30:31], s98, v85
	v_cmp_gt_u32_e64 s[36:37], s98, v86
	v_cmp_gt_u32_e64 s[78:79], s98, v87
	v_cmp_gt_u32_e64 s[50:51], s98, v88
	v_cndmask_b32_e64 v32, 0, v32, s[30:31]
	v_add_u32_e32 v85, 8, v84
	v_cmp_gt_u32_e64 s[30:31], s98, v85
	v_cndmask_b32_e64 v33, 0, v33, s[36:37]
	v_add_u32_e32 v86, 9, v84
	v_cmp_gt_u32_e64 s[36:37], s98, v86
	v_cndmask_b32_e64 v34, 0, v34, s[78:79]
	v_add_u32_e32 v87, 10, v84
	v_cmp_gt_u32_e64 s[78:79], s98, v87
	v_cndmask_b32_e64 v35, 0, v35, s[50:51]
	v_add_u32_e32 v88, 11, v84
	v_cmp_gt_u32_e64 s[50:51], s98, v88
	v_cndmask_b32_e64 v36, 0, v36, s[30:31]
	v_add_u32_e32 v85, 16, v84
	v_cmp_gt_u32_e64 s[30:31], s98, v85
	v_cndmask_b32_e64 v37, 0, v37, s[36:37]
	v_add_u32_e32 v86, 17, v84
	v_cmp_gt_u32_e64 s[36:37], s98, v86
	v_cndmask_b32_e64 v38, 0, v38, s[78:79]
	v_add_u32_e32 v87, 18, v84
	v_cmp_gt_u32_e64 s[78:79], s98, v87
	v_cndmask_b32_e64 v39, 0, v39, s[50:51]
	v_add_u32_e32 v88, 19, v84
	v_cmp_gt_u32_e64 s[50:51], s98, v88
	v_cndmask_b32_e64 v40, 0, v40, s[30:31]
	v_add_u32_e32 v85, 24, v84
	v_cmp_gt_u32_e64 s[30:31], s98, v85
	v_cndmask_b32_e64 v41, 0, v41, s[36:37]
	v_add_u32_e32 v86, 25, v84
	v_cmp_gt_u32_e64 s[36:37], s98, v86
	v_cndmask_b32_e64 v42, 0, v42, s[78:79]
	v_add_u32_e32 v87, 26, v84
	v_cmp_gt_u32_e64 s[78:79], s98, v87
	v_cndmask_b32_e64 v43, 0, v43, s[50:51]
	v_add_u32_e32 v88, 27, v84
	v_cmp_gt_u32_e64 s[50:51], s98, v88
	v_nop
	v_cndmask_b32_e64 v44, 0, v44, s[30:31]
	v_cndmask_b32_e64 v45, 0, v45, s[36:37]
	v_cndmask_b32_e64 v46, 0, v46, s[78:79]
	v_cndmask_b32_e64 v47, 0, v47, s[50:51]
	v_cvt_pk_bf16_f32 v64, v32, v33
	v_cvt_pk_bf16_f32 v65, v34, v35
	v_cvt_pk_bf16_f32 v66, v36, v37
	v_cvt_pk_bf16_f32 v67, v38, v39
	v_cvt_pk_bf16_f32 v68, v40, v41
	v_cvt_pk_bf16_f32 v69, v42, v43
	v_cvt_pk_bf16_f32 v70, v44, v45
	v_cvt_pk_bf16_f32 v71, v46, v47
	v_pk_add_f32 v[232:233], v[232:233], v[32:33]
	v_pk_add_f32 v[232:233], v[232:233], v[34:35]
	v_pk_add_f32 v[232:233], v[232:233], v[36:37]
	v_pk_add_f32 v[232:233], v[232:233], v[38:39]
	v_pk_add_f32 v[232:233], v[232:233], v[40:41]
	v_pk_add_f32 v[232:233], v[232:233], v[42:43]
	v_pk_add_f32 v[232:233], v[232:233], v[44:45]
	v_pk_add_f32 v[232:233], v[232:233], v[46:47]
	s_waitcnt lgkmcnt(12)
	v_mfma_f32_32x32x16_bf16 v[0:15], v[64:67], v[72:75], v[0:15]
	v_mfma_f32_32x32x16_bf16 v[16:31], v[64:67], v[76:79], v[16:31]
	v_mfma_f32_32x32x16_bf16 v[0:15], v[68:71], v[220:223], v[0:15]
	v_mfma_f32_32x32x16_bf16 v[16:31], v[68:71], v[224:227], v[16:31]
	s_add_i32 s90, s76, 384
	v_add_u32_e32 v80, s90, v235
	v_add_u32_e32 v83, s90, v236
	v_add_u32_e32 v99, s90, v237
	v_add_u32_e32 v253, s90, v238
	v_add_u32_e32 v254, s90, v100
	v_add_u32_e32 v255, s90, v149
	v_med3_i32 v80, v80, 0, s99
	v_med3_i32 v83, v83, 0, s99
	v_med3_i32 v99, v99, 0, s99
	v_med3_i32 v253, v253, 0, s99
	v_med3_i32 v254, v254, 0, s99
	v_med3_i32 v255, v255, 0, s99
	v_mad_u32_u24 v80, v80, s100, v252
	v_mad_u32_u24 v83, v83, s100, v252
	v_mad_u32_u24 v99, v99, s100, v252
	v_mad_u32_u24 v253, v253, s100, v252
	v_mad_u32_u24 v254, v254, s100, v153
	v_mad_u32_u24 v255, v255, s100, v153
	global_load_dwordx4 v[188:191], v80, s[82:83]
	global_load_dwordx4 v[192:195], v83, s[82:83]
	global_load_dwordx4 v[196:199], v99, s[82:83]
	global_load_dwordx4 v[200:203], v253, s[82:83]
	global_load_dwordx4 v[204:207], v254, s[82:83] offset:768
	global_load_dwordx4 v[208:211], v255, s[82:83] offset:768
	global_load_dwordx4 v[212:215], v254, s[82:83] offset:832
	global_load_dwordx4 v[216:219], v255, s[82:83] offset:832
	ds_read2_b32 v[32:33], v115 offset0:170 offset1:171
	ds_read2_b32 v[34:35], v115 offset0:172 offset1:173
	ds_read2_b32 v[36:37], v115 offset0:178 offset1:179
	ds_read2_b32 v[38:39], v115 offset0:180 offset1:181
	ds_read2_b32 v[40:41], v115 offset0:187 offset1:188
	ds_read2_b32 v[42:43], v115 offset0:189 offset1:190
	ds_read2_b32 v[44:45], v115 offset0:195 offset1:196
	ds_read2_b32 v[46:47], v115 offset0:197 offset1:198
	s_waitcnt lgkmcnt(0)
	v_mfma_f32_32x32x16_bf16 v[32:47], v[116:119], v[48:51], v[32:47]
	ds_read_b64_tr_b16 v[72:73], v231
	ds_read_b64_tr_b16 v[74:75], v231 offset:512
	ds_read_b64_tr_b16 v[76:77], v231 offset:2048
	ds_read_b64_tr_b16 v[78:79], v231 offset:2560
	ds_read_b64_tr_b16 v[220:221], v231 offset:1024
	ds_read_b64_tr_b16 v[222:223], v231 offset:1536
	ds_read_b64_tr_b16 v[224:225], v231 offset:3072
	ds_read_b64_tr_b16 v[226:227], v231 offset:3584
	s_waitcnt vmcnt(8)
	ds_write_b128 v247, v[156:159]
	ds_write_b128 v247, v[160:163] offset:1024
	ds_write_b128 v247, v[164:167] offset:2048
	ds_write_b128 v247, v[168:171] offset:3072
	ds_read_b128 v[156:159], v248
	ds_read_b128 v[160:163], v249
	ds_read_b128 v[164:167], v250
	ds_read_b128 v[168:171], v251
	ds_write_b128 v112, v[172:175]
	ds_write_b128 v112, v[176:179] offset:1024
	ds_write_b128 v112, v[180:183] offset:2048
	ds_write_b128 v112, v[184:187] offset:3072
	v_mfma_f32_32x32x16_bf16 v[32:47], v[120:123], v[52:55], v[32:47]
	v_mfma_f32_32x32x16_bf16 v[32:47], v[124:127], v[56:59], v[32:47]
	v_mfma_f32_32x32x16_bf16 v[32:47], v[128:131], v[60:63], v[32:47]
	s_nop 11
	v_exp_f32_e32 v32, v32
	v_exp_f32_e32 v33, v33
	v_exp_f32_e32 v34, v34
	v_exp_f32_e32 v35, v35
	v_exp_f32_e32 v36, v36
	v_exp_f32_e32 v37, v37
	v_exp_f32_e32 v38, v38
	v_exp_f32_e32 v39, v39
	v_exp_f32_e32 v40, v40
	v_exp_f32_e32 v41, v41
	v_exp_f32_e32 v42, v42
	v_exp_f32_e32 v43, v43
	v_exp_f32_e32 v44, v44
	v_exp_f32_e32 v45, v45
	v_exp_f32_e32 v46, v46
	v_exp_f32_e32 v47, v47
	s_add_i32 s90, s76, 320
	v_add_u32_e32 v84, s90, v107
	v_add_u32_e32 v85, 0, v84
	v_add_u32_e32 v86, 1, v84
	v_add_u32_e32 v87, 2, v84
	v_add_u32_e32 v88, 3, v84
	v_cmp_gt_u32_e64 s[30:31], s98, v85
	v_cmp_gt_u32_e64 s[36:37], s98, v86
	v_cmp_gt_u32_e64 s[78:79], s98, v87
	v_cmp_gt_u32_e64 s[50:51], s98, v88
	v_cndmask_b32_e64 v32, 0, v32, s[30:31]
	v_add_u32_e32 v85, 8, v84
	v_cmp_gt_u32_e64 s[30:31], s98, v85
	v_cndmask_b32_e64 v33, 0, v33, s[36:37]
	v_add_u32_e32 v86, 9, v84
	v_cmp_gt_u32_e64 s[36:37], s98, v86
	v_cndmask_b32_e64 v34, 0, v34, s[78:79]
	v_add_u32_e32 v87, 10, v84
	v_cmp_gt_u32_e64 s[78:79], s98, v87
	v_cndmask_b32_e64 v35, 0, v35, s[50:51]
	v_add_u32_e32 v88, 11, v84
	v_cmp_gt_u32_e64 s[50:51], s98, v88
	v_cndmask_b32_e64 v36, 0, v36, s[30:31]
	v_add_u32_e32 v85, 16, v84
	v_cmp_gt_u32_e64 s[30:31], s98, v85
	v_cndmask_b32_e64 v37, 0, v37, s[36:37]
	v_add_u32_e32 v86, 17, v84
	v_cmp_gt_u32_e64 s[36:37], s98, v86
	v_cndmask_b32_e64 v38, 0, v38, s[78:79]
	v_add_u32_e32 v87, 18, v84
	v_cmp_gt_u32_e64 s[78:79], s98, v87
	v_cndmask_b32_e64 v39, 0, v39, s[50:51]
	v_add_u32_e32 v88, 19, v84
	v_cmp_gt_u32_e64 s[50:51], s98, v88
	v_cndmask_b32_e64 v40, 0, v40, s[30:31]
	v_add_u32_e32 v85, 24, v84
	v_cmp_gt_u32_e64 s[30:31], s98, v85
	v_cndmask_b32_e64 v41, 0, v41, s[36:37]
	v_add_u32_e32 v86, 25, v84
	v_cmp_gt_u32_e64 s[36:37], s98, v86
	v_cndmask_b32_e64 v42, 0, v42, s[78:79]
	v_add_u32_e32 v87, 26, v84
	v_cmp_gt_u32_e64 s[78:79], s98, v87
	v_cndmask_b32_e64 v43, 0, v43, s[50:51]
	v_add_u32_e32 v88, 27, v84
	v_cmp_gt_u32_e64 s[50:51], s98, v88
	v_nop
	v_cndmask_b32_e64 v44, 0, v44, s[30:31]
	v_cndmask_b32_e64 v45, 0, v45, s[36:37]
	v_cndmask_b32_e64 v46, 0, v46, s[78:79]
	v_cndmask_b32_e64 v47, 0, v47, s[50:51]
	v_cvt_pk_bf16_f32 v64, v32, v33
	v_cvt_pk_bf16_f32 v65, v34, v35
	v_cvt_pk_bf16_f32 v66, v36, v37
	v_cvt_pk_bf16_f32 v67, v38, v39
	v_cvt_pk_bf16_f32 v68, v40, v41
	v_cvt_pk_bf16_f32 v69, v42, v43
	v_cvt_pk_bf16_f32 v70, v44, v45
	v_cvt_pk_bf16_f32 v71, v46, v47
	v_pk_add_f32 v[232:233], v[232:233], v[32:33]
	v_pk_add_f32 v[232:233], v[232:233], v[34:35]
	v_pk_add_f32 v[232:233], v[232:233], v[36:37]
	v_pk_add_f32 v[232:233], v[232:233], v[38:39]
	v_pk_add_f32 v[232:233], v[232:233], v[40:41]
	v_pk_add_f32 v[232:233], v[232:233], v[42:43]
	v_pk_add_f32 v[232:233], v[232:233], v[44:45]
	v_pk_add_f32 v[232:233], v[232:233], v[46:47]
	s_waitcnt lgkmcnt(12)
	v_mfma_f32_32x32x16_bf16 v[0:15], v[64:67], v[72:75], v[0:15]
	v_mfma_f32_32x32x16_bf16 v[16:31], v[64:67], v[76:79], v[16:31]
	v_mfma_f32_32x32x16_bf16 v[0:15], v[68:71], v[220:223], v[0:15]
	v_mfma_f32_32x32x16_bf16 v[16:31], v[68:71], v[224:227], v[16:31]
	s_add_i32 s90, s76, 416
	v_add_u32_e32 v80, s90, v235
	v_add_u32_e32 v83, s90, v236
	v_add_u32_e32 v99, s90, v237
	v_add_u32_e32 v253, s90, v238
	v_add_u32_e32 v254, s90, v100
	v_add_u32_e32 v255, s90, v149
	v_med3_i32 v80, v80, 0, s99
	v_med3_i32 v83, v83, 0, s99
	v_med3_i32 v99, v99, 0, s99
	v_med3_i32 v253, v253, 0, s99
	v_med3_i32 v254, v254, 0, s99
	v_med3_i32 v255, v255, 0, s99
	v_mad_u32_u24 v80, v80, s100, v252
	v_mad_u32_u24 v83, v83, s100, v252
	v_mad_u32_u24 v99, v99, s100, v252
	v_mad_u32_u24 v253, v253, s100, v252
	v_mad_u32_u24 v254, v254, s100, v153
	v_mad_u32_u24 v255, v255, s100, v153
	global_load_dwordx4 v[116:119], v80, s[82:83]
	global_load_dwordx4 v[120:123], v83, s[82:83]
	global_load_dwordx4 v[124:127], v99, s[82:83]
	global_load_dwordx4 v[128:131], v253, s[82:83]
	global_load_dwordx4 v[132:135], v254, s[82:83] offset:768
	global_load_dwordx4 v[136:139], v255, s[82:83] offset:768
	global_load_dwordx4 v[140:143], v254, s[82:83] offset:832
	global_load_dwordx4 v[144:147], v255, s[82:83] offset:832
	ds_read2_b32 v[32:33], v115 offset0:204 offset1:205
	ds_read2_b32 v[34:35], v115 offset0:206 offset1:207
	ds_read2_b32 v[36:37], v115 offset0:212 offset1:213
	ds_read2_b32 v[38:39], v115 offset0:214 offset1:215
	ds_read2_b32 v[40:41], v115 offset0:221 offset1:222
	ds_read2_b32 v[42:43], v115 offset0:223 offset1:224
	ds_read2_b32 v[44:45], v115 offset0:229 offset1:230
	ds_read2_b32 v[46:47], v115 offset0:231 offset1:232
	s_waitcnt lgkmcnt(0)
	v_mfma_f32_32x32x16_bf16 v[32:47], v[156:159], v[48:51], v[32:47]
	ds_read_b64_tr_b16 v[72:73], v231
	ds_read_b64_tr_b16 v[74:75], v231 offset:512
	ds_read_b64_tr_b16 v[76:77], v231 offset:2048
	ds_read_b64_tr_b16 v[78:79], v231 offset:2560
	ds_read_b64_tr_b16 v[220:221], v231 offset:1024
	ds_read_b64_tr_b16 v[222:223], v231 offset:1536
	ds_read_b64_tr_b16 v[224:225], v231 offset:3072
	ds_read_b64_tr_b16 v[226:227], v231 offset:3584
	s_waitcnt vmcnt(8)
	ds_write_b128 v247, v[188:191]
	ds_write_b128 v247, v[192:195] offset:1024
	ds_write_b128 v247, v[196:199] offset:2048
	ds_write_b128 v247, v[200:203] offset:3072
	ds_read_b128 v[188:191], v248
	ds_read_b128 v[192:195], v249
	ds_read_b128 v[196:199], v250
	ds_read_b128 v[200:203], v251
	ds_write_b128 v112, v[204:207]
	ds_write_b128 v112, v[208:211] offset:1024
	ds_write_b128 v112, v[212:215] offset:2048
	ds_write_b128 v112, v[216:219] offset:3072
	v_mfma_f32_32x32x16_bf16 v[32:47], v[160:163], v[52:55], v[32:47]
	v_mfma_f32_32x32x16_bf16 v[32:47], v[164:167], v[56:59], v[32:47]
	v_mfma_f32_32x32x16_bf16 v[32:47], v[168:171], v[60:63], v[32:47]
	s_nop 11
	v_exp_f32_e32 v32, v32
	v_exp_f32_e32 v33, v33
	v_exp_f32_e32 v34, v34
	v_exp_f32_e32 v35, v35
	v_exp_f32_e32 v36, v36
	v_exp_f32_e32 v37, v37
	v_exp_f32_e32 v38, v38
	v_exp_f32_e32 v39, v39
	v_exp_f32_e32 v40, v40
	v_exp_f32_e32 v41, v41
	v_exp_f32_e32 v42, v42
	v_exp_f32_e32 v43, v43
	v_exp_f32_e32 v44, v44
	v_exp_f32_e32 v45, v45
	v_exp_f32_e32 v46, v46
	v_exp_f32_e32 v47, v47
	s_add_i32 s90, s76, 352
	v_add_u32_e32 v84, s90, v107
	v_add_u32_e32 v85, 0, v84
	v_add_u32_e32 v86, 1, v84
	v_add_u32_e32 v87, 2, v84
	v_add_u32_e32 v88, 3, v84
	v_cmp_gt_u32_e64 s[30:31], s98, v85
	v_cmp_gt_u32_e64 s[36:37], s98, v86
	v_cmp_gt_u32_e64 s[78:79], s98, v87
	v_cmp_gt_u32_e64 s[50:51], s98, v88
	v_cndmask_b32_e64 v32, 0, v32, s[30:31]
	v_add_u32_e32 v85, 8, v84
	v_cmp_gt_u32_e64 s[30:31], s98, v85
	v_cndmask_b32_e64 v33, 0, v33, s[36:37]
	v_add_u32_e32 v86, 9, v84
	v_cmp_gt_u32_e64 s[36:37], s98, v86
	v_cndmask_b32_e64 v34, 0, v34, s[78:79]
	v_add_u32_e32 v87, 10, v84
	v_cmp_gt_u32_e64 s[78:79], s98, v87
	v_cndmask_b32_e64 v35, 0, v35, s[50:51]
	v_add_u32_e32 v88, 11, v84
	v_cmp_gt_u32_e64 s[50:51], s98, v88
	v_cndmask_b32_e64 v36, 0, v36, s[30:31]
	v_add_u32_e32 v85, 16, v84
	v_cmp_gt_u32_e64 s[30:31], s98, v85
	v_cndmask_b32_e64 v37, 0, v37, s[36:37]
	v_add_u32_e32 v86, 17, v84
	v_cmp_gt_u32_e64 s[36:37], s98, v86
	v_cndmask_b32_e64 v38, 0, v38, s[78:79]
	v_add_u32_e32 v87, 18, v84
	v_cmp_gt_u32_e64 s[78:79], s98, v87
	v_cndmask_b32_e64 v39, 0, v39, s[50:51]
	v_add_u32_e32 v88, 19, v84
	v_cmp_gt_u32_e64 s[50:51], s98, v88
	v_cndmask_b32_e64 v40, 0, v40, s[30:31]
	v_add_u32_e32 v85, 24, v84
	v_cmp_gt_u32_e64 s[30:31], s98, v85
	v_cndmask_b32_e64 v41, 0, v41, s[36:37]
	v_add_u32_e32 v86, 25, v84
	v_cmp_gt_u32_e64 s[36:37], s98, v86
	v_cndmask_b32_e64 v42, 0, v42, s[78:79]
	v_add_u32_e32 v87, 26, v84
	v_cmp_gt_u32_e64 s[78:79], s98, v87
	v_cndmask_b32_e64 v43, 0, v43, s[50:51]
	v_add_u32_e32 v88, 27, v84
	v_cmp_gt_u32_e64 s[50:51], s98, v88
	v_nop
	v_cndmask_b32_e64 v44, 0, v44, s[30:31]
	v_cndmask_b32_e64 v45, 0, v45, s[36:37]
	v_cndmask_b32_e64 v46, 0, v46, s[78:79]
	v_cndmask_b32_e64 v47, 0, v47, s[50:51]
	v_cvt_pk_bf16_f32 v64, v32, v33
	v_cvt_pk_bf16_f32 v65, v34, v35
	v_cvt_pk_bf16_f32 v66, v36, v37
	v_cvt_pk_bf16_f32 v67, v38, v39
	v_cvt_pk_bf16_f32 v68, v40, v41
	v_cvt_pk_bf16_f32 v69, v42, v43
	v_cvt_pk_bf16_f32 v70, v44, v45
	v_cvt_pk_bf16_f32 v71, v46, v47
	v_pk_add_f32 v[232:233], v[232:233], v[32:33]
	v_pk_add_f32 v[232:233], v[232:233], v[34:35]
	v_pk_add_f32 v[232:233], v[232:233], v[36:37]
	v_pk_add_f32 v[232:233], v[232:233], v[38:39]
	v_pk_add_f32 v[232:233], v[232:233], v[40:41]
	v_pk_add_f32 v[232:233], v[232:233], v[42:43]
	v_pk_add_f32 v[232:233], v[232:233], v[44:45]
	v_pk_add_f32 v[232:233], v[232:233], v[46:47]
	s_waitcnt lgkmcnt(12)
	v_mfma_f32_32x32x16_bf16 v[0:15], v[64:67], v[72:75], v[0:15]
	v_mfma_f32_32x32x16_bf16 v[16:31], v[64:67], v[76:79], v[16:31]
	v_mfma_f32_32x32x16_bf16 v[0:15], v[68:71], v[220:223], v[0:15]
	v_mfma_f32_32x32x16_bf16 v[16:31], v[68:71], v[224:227], v[16:31]
	s_add_i32 s90, s76, 448
	v_add_u32_e32 v80, s90, v235
	v_add_u32_e32 v83, s90, v236
	v_add_u32_e32 v99, s90, v237
	v_add_u32_e32 v253, s90, v238
	v_add_u32_e32 v254, s90, v100
	v_add_u32_e32 v255, s90, v149
	v_med3_i32 v80, v80, 0, s99
	v_med3_i32 v83, v83, 0, s99
	v_med3_i32 v99, v99, 0, s99
	v_med3_i32 v253, v253, 0, s99
	v_med3_i32 v254, v254, 0, s99
	v_med3_i32 v255, v255, 0, s99
	v_mad_u32_u24 v80, v80, s100, v252
	v_mad_u32_u24 v83, v83, s100, v252
	v_mad_u32_u24 v99, v99, s100, v252
	v_mad_u32_u24 v253, v253, s100, v252
	v_mad_u32_u24 v254, v254, s100, v153
	v_mad_u32_u24 v255, v255, s100, v153
	global_load_dwordx4 v[156:159], v80, s[82:83]
	global_load_dwordx4 v[160:163], v83, s[82:83]
	global_load_dwordx4 v[164:167], v99, s[82:83]
	global_load_dwordx4 v[168:171], v253, s[82:83]
	global_load_dwordx4 v[172:175], v254, s[82:83] offset:768
	global_load_dwordx4 v[176:179], v255, s[82:83] offset:768
	global_load_dwordx4 v[180:183], v254, s[82:83] offset:832
	global_load_dwordx4 v[184:187], v255, s[82:83] offset:832
	v_add_u32_e32 v115, 952, v115
	ds_read2_b32 v[32:33], v115 offset0:0 offset1:1
	ds_read2_b32 v[34:35], v115 offset0:2 offset1:3
	ds_read2_b32 v[36:37], v115 offset0:8 offset1:9
	ds_read2_b32 v[38:39], v115 offset0:10 offset1:11
	ds_read2_b32 v[40:41], v115 offset0:17 offset1:18
	ds_read2_b32 v[42:43], v115 offset0:19 offset1:20
	ds_read2_b32 v[44:45], v115 offset0:25 offset1:26
	ds_read2_b32 v[46:47], v115 offset0:27 offset1:28
	s_waitcnt lgkmcnt(0)
	v_mfma_f32_32x32x16_bf16 v[32:47], v[188:191], v[48:51], v[32:47]
	ds_read_b64_tr_b16 v[72:73], v231
	ds_read_b64_tr_b16 v[74:75], v231 offset:512
	ds_read_b64_tr_b16 v[76:77], v231 offset:2048
	ds_read_b64_tr_b16 v[78:79], v231 offset:2560
	ds_read_b64_tr_b16 v[220:221], v231 offset:1024
	ds_read_b64_tr_b16 v[222:223], v231 offset:1536
	ds_read_b64_tr_b16 v[224:225], v231 offset:3072
	ds_read_b64_tr_b16 v[226:227], v231 offset:3584
	s_waitcnt vmcnt(8)
	ds_write_b128 v247, v[116:119]
	ds_write_b128 v247, v[120:123] offset:1024
	ds_write_b128 v247, v[124:127] offset:2048
	ds_write_b128 v247, v[128:131] offset:3072
	ds_read_b128 v[116:119], v248
	ds_read_b128 v[120:123], v249
	ds_read_b128 v[124:127], v250
	ds_read_b128 v[128:131], v251
	ds_write_b128 v112, v[132:135]
	ds_write_b128 v112, v[136:139] offset:1024
	ds_write_b128 v112, v[140:143] offset:2048
	ds_write_b128 v112, v[144:147] offset:3072
	v_mfma_f32_32x32x16_bf16 v[32:47], v[192:195], v[52:55], v[32:47]
	v_mfma_f32_32x32x16_bf16 v[32:47], v[196:199], v[56:59], v[32:47]
	v_mfma_f32_32x32x16_bf16 v[32:47], v[200:203], v[60:63], v[32:47]
	s_nop 11
	v_exp_f32_e32 v32, v32
	v_exp_f32_e32 v33, v33
	v_exp_f32_e32 v34, v34
	v_exp_f32_e32 v35, v35
	v_exp_f32_e32 v36, v36
	v_exp_f32_e32 v37, v37
	v_exp_f32_e32 v38, v38
	v_exp_f32_e32 v39, v39
	v_exp_f32_e32 v40, v40
	v_exp_f32_e32 v41, v41
	v_exp_f32_e32 v42, v42
	v_exp_f32_e32 v43, v43
	v_exp_f32_e32 v44, v44
	v_exp_f32_e32 v45, v45
	v_exp_f32_e32 v46, v46
	v_exp_f32_e32 v47, v47
	s_add_i32 s90, s76, 384
	v_add_u32_e32 v84, s90, v107
	v_add_u32_e32 v85, 0, v84
	v_add_u32_e32 v86, 1, v84
	v_add_u32_e32 v87, 2, v84
	v_add_u32_e32 v88, 3, v84
	v_cmp_gt_u32_e64 s[30:31], s98, v85
	v_cmp_gt_u32_e64 s[36:37], s98, v86
	v_cmp_gt_u32_e64 s[78:79], s98, v87
	v_cmp_gt_u32_e64 s[50:51], s98, v88
	v_cndmask_b32_e64 v32, 0, v32, s[30:31]
	v_add_u32_e32 v85, 8, v84
	v_cmp_gt_u32_e64 s[30:31], s98, v85
	v_cndmask_b32_e64 v33, 0, v33, s[36:37]
	v_add_u32_e32 v86, 9, v84
	v_cmp_gt_u32_e64 s[36:37], s98, v86
	v_cndmask_b32_e64 v34, 0, v34, s[78:79]
	v_add_u32_e32 v87, 10, v84
	v_cmp_gt_u32_e64 s[78:79], s98, v87
	v_cndmask_b32_e64 v35, 0, v35, s[50:51]
	v_add_u32_e32 v88, 11, v84
	v_cmp_gt_u32_e64 s[50:51], s98, v88
	v_cndmask_b32_e64 v36, 0, v36, s[30:31]
	v_add_u32_e32 v85, 16, v84
	v_cmp_gt_u32_e64 s[30:31], s98, v85
	v_cndmask_b32_e64 v37, 0, v37, s[36:37]
	v_add_u32_e32 v86, 17, v84
	v_cmp_gt_u32_e64 s[36:37], s98, v86
	v_cndmask_b32_e64 v38, 0, v38, s[78:79]
	v_add_u32_e32 v87, 18, v84
	v_cmp_gt_u32_e64 s[78:79], s98, v87
	v_cndmask_b32_e64 v39, 0, v39, s[50:51]
	v_add_u32_e32 v88, 19, v84
	v_cmp_gt_u32_e64 s[50:51], s98, v88
	v_cndmask_b32_e64 v40, 0, v40, s[30:31]
	v_add_u32_e32 v85, 24, v84
	v_cmp_gt_u32_e64 s[30:31], s98, v85
	v_cndmask_b32_e64 v41, 0, v41, s[36:37]
	v_add_u32_e32 v86, 25, v84
	v_cmp_gt_u32_e64 s[36:37], s98, v86
	v_cndmask_b32_e64 v42, 0, v42, s[78:79]
	v_add_u32_e32 v87, 26, v84
	v_cmp_gt_u32_e64 s[78:79], s98, v87
	v_cndmask_b32_e64 v43, 0, v43, s[50:51]
	v_add_u32_e32 v88, 27, v84
	v_cmp_gt_u32_e64 s[50:51], s98, v88
	v_nop
	v_cndmask_b32_e64 v44, 0, v44, s[30:31]
	v_cndmask_b32_e64 v45, 0, v45, s[36:37]
	v_cndmask_b32_e64 v46, 0, v46, s[78:79]
	v_cndmask_b32_e64 v47, 0, v47, s[50:51]
	v_cvt_pk_bf16_f32 v64, v32, v33
	v_cvt_pk_bf16_f32 v65, v34, v35
	v_cvt_pk_bf16_f32 v66, v36, v37
	v_cvt_pk_bf16_f32 v67, v38, v39
	v_cvt_pk_bf16_f32 v68, v40, v41
	v_cvt_pk_bf16_f32 v69, v42, v43
	v_cvt_pk_bf16_f32 v70, v44, v45
	v_cvt_pk_bf16_f32 v71, v46, v47
	v_pk_add_f32 v[232:233], v[232:233], v[32:33]
	v_pk_add_f32 v[232:233], v[232:233], v[34:35]
	v_pk_add_f32 v[232:233], v[232:233], v[36:37]
	v_pk_add_f32 v[232:233], v[232:233], v[38:39]
	v_pk_add_f32 v[232:233], v[232:233], v[40:41]
	v_pk_add_f32 v[232:233], v[232:233], v[42:43]
	v_pk_add_f32 v[232:233], v[232:233], v[44:45]
	v_pk_add_f32 v[232:233], v[232:233], v[46:47]
	s_waitcnt lgkmcnt(12)
	v_mfma_f32_32x32x16_bf16 v[0:15], v[64:67], v[72:75], v[0:15]
	v_mfma_f32_32x32x16_bf16 v[16:31], v[64:67], v[76:79], v[16:31]
	v_mfma_f32_32x32x16_bf16 v[0:15], v[68:71], v[220:223], v[0:15]
	v_mfma_f32_32x32x16_bf16 v[16:31], v[68:71], v[224:227], v[16:31]
	s_add_i32 s90, s76, 480
	v_add_u32_e32 v80, s90, v235
	v_add_u32_e32 v83, s90, v236
	v_add_u32_e32 v99, s90, v237
	v_add_u32_e32 v253, s90, v238
	v_add_u32_e32 v254, s90, v100
	v_add_u32_e32 v255, s90, v149
	v_med3_i32 v80, v80, 0, s99
	v_med3_i32 v83, v83, 0, s99
	v_med3_i32 v99, v99, 0, s99
	v_med3_i32 v253, v253, 0, s99
	v_med3_i32 v254, v254, 0, s99
	v_med3_i32 v255, v255, 0, s99
	v_mad_u32_u24 v80, v80, s100, v252
	v_mad_u32_u24 v83, v83, s100, v252
	v_mad_u32_u24 v99, v99, s100, v252
	v_mad_u32_u24 v253, v253, s100, v252
	v_mad_u32_u24 v254, v254, s100, v153
	v_mad_u32_u24 v255, v255, s100, v153
	global_load_dwordx4 v[188:191], v80, s[82:83]
	global_load_dwordx4 v[192:195], v83, s[82:83]
	global_load_dwordx4 v[196:199], v99, s[82:83]
	global_load_dwordx4 v[200:203], v253, s[82:83]
	global_load_dwordx4 v[204:207], v254, s[82:83] offset:768
	global_load_dwordx4 v[208:211], v255, s[82:83] offset:768
	global_load_dwordx4 v[212:215], v254, s[82:83] offset:832
	global_load_dwordx4 v[216:219], v255, s[82:83] offset:832
	ds_read2_b32 v[32:33], v115 offset0:34 offset1:35
	ds_read2_b32 v[34:35], v115 offset0:36 offset1:37
	ds_read2_b32 v[36:37], v115 offset0:42 offset1:43
	ds_read2_b32 v[38:39], v115 offset0:44 offset1:45
	ds_read2_b32 v[40:41], v115 offset0:51 offset1:52
	ds_read2_b32 v[42:43], v115 offset0:53 offset1:54
	ds_read2_b32 v[44:45], v115 offset0:59 offset1:60
	ds_read2_b32 v[46:47], v115 offset0:61 offset1:62
	s_waitcnt lgkmcnt(0)
	v_mfma_f32_32x32x16_bf16 v[32:47], v[116:119], v[48:51], v[32:47]
	ds_read_b64_tr_b16 v[72:73], v231
	ds_read_b64_tr_b16 v[74:75], v231 offset:512
	ds_read_b64_tr_b16 v[76:77], v231 offset:2048
	ds_read_b64_tr_b16 v[78:79], v231 offset:2560
	ds_read_b64_tr_b16 v[220:221], v231 offset:1024
	ds_read_b64_tr_b16 v[222:223], v231 offset:1536
	ds_read_b64_tr_b16 v[224:225], v231 offset:3072
	ds_read_b64_tr_b16 v[226:227], v231 offset:3584
	s_waitcnt vmcnt(8)
	ds_write_b128 v247, v[156:159]
	ds_write_b128 v247, v[160:163] offset:1024
	ds_write_b128 v247, v[164:167] offset:2048
	ds_write_b128 v247, v[168:171] offset:3072
	ds_read_b128 v[156:159], v248
	ds_read_b128 v[160:163], v249
	ds_read_b128 v[164:167], v250
	ds_read_b128 v[168:171], v251
	ds_write_b128 v112, v[172:175]
	ds_write_b128 v112, v[176:179] offset:1024
	ds_write_b128 v112, v[180:183] offset:2048
	ds_write_b128 v112, v[184:187] offset:3072
	v_mfma_f32_32x32x16_bf16 v[32:47], v[120:123], v[52:55], v[32:47]
	v_mfma_f32_32x32x16_bf16 v[32:47], v[124:127], v[56:59], v[32:47]
	v_mfma_f32_32x32x16_bf16 v[32:47], v[128:131], v[60:63], v[32:47]
	s_nop 11
	v_exp_f32_e32 v32, v32
	v_exp_f32_e32 v33, v33
	v_exp_f32_e32 v34, v34
	v_exp_f32_e32 v35, v35
	v_exp_f32_e32 v36, v36
	v_exp_f32_e32 v37, v37
	v_exp_f32_e32 v38, v38
	v_exp_f32_e32 v39, v39
	v_exp_f32_e32 v40, v40
	v_exp_f32_e32 v41, v41
	v_exp_f32_e32 v42, v42
	v_exp_f32_e32 v43, v43
	v_exp_f32_e32 v44, v44
	v_exp_f32_e32 v45, v45
	v_exp_f32_e32 v46, v46
	v_exp_f32_e32 v47, v47
	s_add_i32 s90, s76, 416
	v_add_u32_e32 v84, s90, v107
	v_add_u32_e32 v85, 0, v84
	v_add_u32_e32 v86, 1, v84
	v_add_u32_e32 v87, 2, v84
	v_add_u32_e32 v88, 3, v84
	v_cmp_gt_u32_e64 s[30:31], s98, v85
	v_cmp_gt_u32_e64 s[36:37], s98, v86
	v_cmp_gt_u32_e64 s[78:79], s98, v87
	v_cmp_gt_u32_e64 s[50:51], s98, v88
	v_cndmask_b32_e64 v32, 0, v32, s[30:31]
	v_add_u32_e32 v85, 8, v84
	v_cmp_gt_u32_e64 s[30:31], s98, v85
	v_cndmask_b32_e64 v33, 0, v33, s[36:37]
	v_add_u32_e32 v86, 9, v84
	v_cmp_gt_u32_e64 s[36:37], s98, v86
	v_cndmask_b32_e64 v34, 0, v34, s[78:79]
	v_add_u32_e32 v87, 10, v84
	v_cmp_gt_u32_e64 s[78:79], s98, v87
	v_cndmask_b32_e64 v35, 0, v35, s[50:51]
	v_add_u32_e32 v88, 11, v84
	v_cmp_gt_u32_e64 s[50:51], s98, v88
	v_cndmask_b32_e64 v36, 0, v36, s[30:31]
	v_add_u32_e32 v85, 16, v84
	v_cmp_gt_u32_e64 s[30:31], s98, v85
	v_cndmask_b32_e64 v37, 0, v37, s[36:37]
	v_add_u32_e32 v86, 17, v84
	v_cmp_gt_u32_e64 s[36:37], s98, v86
	v_cndmask_b32_e64 v38, 0, v38, s[78:79]
	v_add_u32_e32 v87, 18, v84
	v_cmp_gt_u32_e64 s[78:79], s98, v87
	v_cndmask_b32_e64 v39, 0, v39, s[50:51]
	v_add_u32_e32 v88, 19, v84
	v_cmp_gt_u32_e64 s[50:51], s98, v88
	v_cndmask_b32_e64 v40, 0, v40, s[30:31]
	v_add_u32_e32 v85, 24, v84
	v_cmp_gt_u32_e64 s[30:31], s98, v85
	v_cndmask_b32_e64 v41, 0, v41, s[36:37]
	v_add_u32_e32 v86, 25, v84
	v_cmp_gt_u32_e64 s[36:37], s98, v86
	v_cndmask_b32_e64 v42, 0, v42, s[78:79]
	v_add_u32_e32 v87, 26, v84
	v_cmp_gt_u32_e64 s[78:79], s98, v87
	v_cndmask_b32_e64 v43, 0, v43, s[50:51]
	v_add_u32_e32 v88, 27, v84
	v_cmp_gt_u32_e64 s[50:51], s98, v88
	v_nop
	v_cndmask_b32_e64 v44, 0, v44, s[30:31]
	v_cndmask_b32_e64 v45, 0, v45, s[36:37]
	v_cndmask_b32_e64 v46, 0, v46, s[78:79]
	v_cndmask_b32_e64 v47, 0, v47, s[50:51]
	v_cvt_pk_bf16_f32 v64, v32, v33
	v_cvt_pk_bf16_f32 v65, v34, v35
	v_cvt_pk_bf16_f32 v66, v36, v37
	v_cvt_pk_bf16_f32 v67, v38, v39
	v_cvt_pk_bf16_f32 v68, v40, v41
	v_cvt_pk_bf16_f32 v69, v42, v43
	v_cvt_pk_bf16_f32 v70, v44, v45
	v_cvt_pk_bf16_f32 v71, v46, v47
	v_pk_add_f32 v[232:233], v[232:233], v[32:33]
	v_pk_add_f32 v[232:233], v[232:233], v[34:35]
	v_pk_add_f32 v[232:233], v[232:233], v[36:37]
	v_pk_add_f32 v[232:233], v[232:233], v[38:39]
	v_pk_add_f32 v[232:233], v[232:233], v[40:41]
	v_pk_add_f32 v[232:233], v[232:233], v[42:43]
	v_pk_add_f32 v[232:233], v[232:233], v[44:45]
	v_pk_add_f32 v[232:233], v[232:233], v[46:47]
	s_waitcnt lgkmcnt(12)
	v_mfma_f32_32x32x16_bf16 v[0:15], v[64:67], v[72:75], v[0:15]
	v_mfma_f32_32x32x16_bf16 v[16:31], v[64:67], v[76:79], v[16:31]
	v_mfma_f32_32x32x16_bf16 v[0:15], v[68:71], v[220:223], v[0:15]
	v_mfma_f32_32x32x16_bf16 v[16:31], v[68:71], v[224:227], v[16:31]
	s_add_i32 s90, s76, 512
	v_add_u32_e32 v80, s90, v235
	v_add_u32_e32 v83, s90, v236
	v_add_u32_e32 v99, s90, v237
	v_add_u32_e32 v253, s90, v238
	v_add_u32_e32 v254, s90, v100
	v_add_u32_e32 v255, s90, v149
	v_med3_i32 v80, v80, 0, s99
	v_med3_i32 v83, v83, 0, s99
	v_med3_i32 v99, v99, 0, s99
	v_med3_i32 v253, v253, 0, s99
	v_med3_i32 v254, v254, 0, s99
	v_med3_i32 v255, v255, 0, s99
	v_mad_u32_u24 v80, v80, s100, v252
	v_mad_u32_u24 v83, v83, s100, v252
	v_mad_u32_u24 v99, v99, s100, v252
	v_mad_u32_u24 v253, v253, s100, v252
	v_mad_u32_u24 v254, v254, s100, v153
	v_mad_u32_u24 v255, v255, s100, v153
	global_load_dwordx4 v[116:119], v80, s[82:83]
	global_load_dwordx4 v[120:123], v83, s[82:83]
	global_load_dwordx4 v[124:127], v99, s[82:83]
	global_load_dwordx4 v[128:131], v253, s[82:83]
	global_load_dwordx4 v[132:135], v254, s[82:83] offset:768
	global_load_dwordx4 v[136:139], v255, s[82:83] offset:768
	global_load_dwordx4 v[140:143], v254, s[82:83] offset:832
	global_load_dwordx4 v[144:147], v255, s[82:83] offset:832
	ds_read2_b32 v[32:33], v115 offset0:68 offset1:69
	ds_read2_b32 v[34:35], v115 offset0:70 offset1:71
	ds_read2_b32 v[36:37], v115 offset0:76 offset1:77
	ds_read2_b32 v[38:39], v115 offset0:78 offset1:79
	ds_read2_b32 v[40:41], v115 offset0:85 offset1:86
	ds_read2_b32 v[42:43], v115 offset0:87 offset1:88
	ds_read2_b32 v[44:45], v115 offset0:93 offset1:94
	ds_read2_b32 v[46:47], v115 offset0:95 offset1:96
	s_waitcnt lgkmcnt(0)
	v_mfma_f32_32x32x16_bf16 v[32:47], v[156:159], v[48:51], v[32:47]
	ds_read_b64_tr_b16 v[72:73], v231
	ds_read_b64_tr_b16 v[74:75], v231 offset:512
	ds_read_b64_tr_b16 v[76:77], v231 offset:2048
	ds_read_b64_tr_b16 v[78:79], v231 offset:2560
	ds_read_b64_tr_b16 v[220:221], v231 offset:1024
	ds_read_b64_tr_b16 v[222:223], v231 offset:1536
	ds_read_b64_tr_b16 v[224:225], v231 offset:3072
	ds_read_b64_tr_b16 v[226:227], v231 offset:3584
	s_waitcnt vmcnt(8)
	ds_write_b128 v247, v[188:191]
	ds_write_b128 v247, v[192:195] offset:1024
	ds_write_b128 v247, v[196:199] offset:2048
	ds_write_b128 v247, v[200:203] offset:3072
	ds_read_b128 v[188:191], v248
	ds_read_b128 v[192:195], v249
	ds_read_b128 v[196:199], v250
	ds_read_b128 v[200:203], v251
	ds_write_b128 v112, v[204:207]
	ds_write_b128 v112, v[208:211] offset:1024
	ds_write_b128 v112, v[212:215] offset:2048
	ds_write_b128 v112, v[216:219] offset:3072
	v_mfma_f32_32x32x16_bf16 v[32:47], v[160:163], v[52:55], v[32:47]
	v_mfma_f32_32x32x16_bf16 v[32:47], v[164:167], v[56:59], v[32:47]
	v_mfma_f32_32x32x16_bf16 v[32:47], v[168:171], v[60:63], v[32:47]
	s_nop 11
	v_exp_f32_e32 v32, v32
	v_exp_f32_e32 v33, v33
	v_exp_f32_e32 v34, v34
	v_exp_f32_e32 v35, v35
	v_exp_f32_e32 v36, v36
	v_exp_f32_e32 v37, v37
	v_exp_f32_e32 v38, v38
	v_exp_f32_e32 v39, v39
	v_exp_f32_e32 v40, v40
	v_exp_f32_e32 v41, v41
	v_exp_f32_e32 v42, v42
	v_exp_f32_e32 v43, v43
	v_exp_f32_e32 v44, v44
	v_exp_f32_e32 v45, v45
	v_exp_f32_e32 v46, v46
	v_exp_f32_e32 v47, v47
	s_add_i32 s90, s76, 448
	v_add_u32_e32 v84, s90, v107
	v_add_u32_e32 v85, 0, v84
	v_add_u32_e32 v86, 1, v84
	v_add_u32_e32 v87, 2, v84
	v_add_u32_e32 v88, 3, v84
	v_cmp_gt_u32_e64 s[30:31], s98, v85
	v_cmp_gt_u32_e64 s[36:37], s98, v86
	v_cmp_gt_u32_e64 s[78:79], s98, v87
	v_cmp_gt_u32_e64 s[50:51], s98, v88
	v_cndmask_b32_e64 v32, 0, v32, s[30:31]
	v_add_u32_e32 v85, 8, v84
	v_cmp_gt_u32_e64 s[30:31], s98, v85
	v_cndmask_b32_e64 v33, 0, v33, s[36:37]
	v_add_u32_e32 v86, 9, v84
	v_cmp_gt_u32_e64 s[36:37], s98, v86
	v_cndmask_b32_e64 v34, 0, v34, s[78:79]
	v_add_u32_e32 v87, 10, v84
	v_cmp_gt_u32_e64 s[78:79], s98, v87
	v_cndmask_b32_e64 v35, 0, v35, s[50:51]
	v_add_u32_e32 v88, 11, v84
	v_cmp_gt_u32_e64 s[50:51], s98, v88
	v_cndmask_b32_e64 v36, 0, v36, s[30:31]
	v_add_u32_e32 v85, 16, v84
	v_cmp_gt_u32_e64 s[30:31], s98, v85
	v_cndmask_b32_e64 v37, 0, v37, s[36:37]
	v_add_u32_e32 v86, 17, v84
	v_cmp_gt_u32_e64 s[36:37], s98, v86
	v_cndmask_b32_e64 v38, 0, v38, s[78:79]
	v_add_u32_e32 v87, 18, v84
	v_cmp_gt_u32_e64 s[78:79], s98, v87
	v_cndmask_b32_e64 v39, 0, v39, s[50:51]
	v_add_u32_e32 v88, 19, v84
	v_cmp_gt_u32_e64 s[50:51], s98, v88
	v_cndmask_b32_e64 v40, 0, v40, s[30:31]
	v_add_u32_e32 v85, 24, v84
	v_cmp_gt_u32_e64 s[30:31], s98, v85
	v_cndmask_b32_e64 v41, 0, v41, s[36:37]
	v_add_u32_e32 v86, 25, v84
	v_cmp_gt_u32_e64 s[36:37], s98, v86
	v_cndmask_b32_e64 v42, 0, v42, s[78:79]
	v_add_u32_e32 v87, 26, v84
	v_cmp_gt_u32_e64 s[78:79], s98, v87
	v_cndmask_b32_e64 v43, 0, v43, s[50:51]
	v_add_u32_e32 v88, 27, v84
	v_cmp_gt_u32_e64 s[50:51], s98, v88
	v_nop
	v_cndmask_b32_e64 v44, 0, v44, s[30:31]
	v_cndmask_b32_e64 v45, 0, v45, s[36:37]
	v_cndmask_b32_e64 v46, 0, v46, s[78:79]
	v_cndmask_b32_e64 v47, 0, v47, s[50:51]
	v_cvt_pk_bf16_f32 v64, v32, v33
	v_cvt_pk_bf16_f32 v65, v34, v35
	v_cvt_pk_bf16_f32 v66, v36, v37
	v_cvt_pk_bf16_f32 v67, v38, v39
	v_cvt_pk_bf16_f32 v68, v40, v41
	v_cvt_pk_bf16_f32 v69, v42, v43
	v_cvt_pk_bf16_f32 v70, v44, v45
	v_cvt_pk_bf16_f32 v71, v46, v47
	v_pk_add_f32 v[232:233], v[232:233], v[32:33]
	v_pk_add_f32 v[232:233], v[232:233], v[34:35]
	v_pk_add_f32 v[232:233], v[232:233], v[36:37]
	v_pk_add_f32 v[232:233], v[232:233], v[38:39]
	v_pk_add_f32 v[232:233], v[232:233], v[40:41]
	v_pk_add_f32 v[232:233], v[232:233], v[42:43]
	v_pk_add_f32 v[232:233], v[232:233], v[44:45]
	v_pk_add_f32 v[232:233], v[232:233], v[46:47]
	s_waitcnt lgkmcnt(12)
	v_mfma_f32_32x32x16_bf16 v[0:15], v[64:67], v[72:75], v[0:15]
	v_mfma_f32_32x32x16_bf16 v[16:31], v[64:67], v[76:79], v[16:31]
	v_mfma_f32_32x32x16_bf16 v[0:15], v[68:71], v[220:223], v[0:15]
	v_mfma_f32_32x32x16_bf16 v[16:31], v[68:71], v[224:227], v[16:31]
	s_add_i32 s90, s76, 544
	v_add_u32_e32 v80, s90, v235
	v_add_u32_e32 v83, s90, v236
	v_add_u32_e32 v99, s90, v237
	v_add_u32_e32 v253, s90, v238
	v_add_u32_e32 v254, s90, v100
	v_add_u32_e32 v255, s90, v149
	v_med3_i32 v80, v80, 0, s99
	v_med3_i32 v83, v83, 0, s99
	v_med3_i32 v99, v99, 0, s99
	v_med3_i32 v253, v253, 0, s99
	v_med3_i32 v254, v254, 0, s99
	v_med3_i32 v255, v255, 0, s99
	v_mad_u32_u24 v80, v80, s100, v252
	v_mad_u32_u24 v83, v83, s100, v252
	v_mad_u32_u24 v99, v99, s100, v252
	v_mad_u32_u24 v253, v253, s100, v252
	v_mad_u32_u24 v254, v254, s100, v153
	v_mad_u32_u24 v255, v255, s100, v153
	global_load_dwordx4 v[156:159], v80, s[82:83]
	global_load_dwordx4 v[160:163], v83, s[82:83]
	global_load_dwordx4 v[164:167], v99, s[82:83]
	global_load_dwordx4 v[168:171], v253, s[82:83]
	global_load_dwordx4 v[172:175], v254, s[82:83] offset:768
	global_load_dwordx4 v[176:179], v255, s[82:83] offset:768
	global_load_dwordx4 v[180:183], v254, s[82:83] offset:832
	global_load_dwordx4 v[184:187], v255, s[82:83] offset:832
	ds_read2_b32 v[32:33], v115 offset0:102 offset1:103
	ds_read2_b32 v[34:35], v115 offset0:104 offset1:105
	ds_read2_b32 v[36:37], v115 offset0:110 offset1:111
	ds_read2_b32 v[38:39], v115 offset0:112 offset1:113
	ds_read2_b32 v[40:41], v115 offset0:119 offset1:120
	ds_read2_b32 v[42:43], v115 offset0:121 offset1:122
	ds_read2_b32 v[44:45], v115 offset0:127 offset1:128
	ds_read2_b32 v[46:47], v115 offset0:129 offset1:130
	s_waitcnt lgkmcnt(0)
	v_mfma_f32_32x32x16_bf16 v[32:47], v[188:191], v[48:51], v[32:47]
	ds_read_b64_tr_b16 v[72:73], v231
	ds_read_b64_tr_b16 v[74:75], v231 offset:512
	ds_read_b64_tr_b16 v[76:77], v231 offset:2048
	ds_read_b64_tr_b16 v[78:79], v231 offset:2560
	ds_read_b64_tr_b16 v[220:221], v231 offset:1024
	ds_read_b64_tr_b16 v[222:223], v231 offset:1536
	ds_read_b64_tr_b16 v[224:225], v231 offset:3072
	ds_read_b64_tr_b16 v[226:227], v231 offset:3584
	s_waitcnt vmcnt(8)
	ds_write_b128 v247, v[116:119]
	ds_write_b128 v247, v[120:123] offset:1024
	ds_write_b128 v247, v[124:127] offset:2048
	ds_write_b128 v247, v[128:131] offset:3072
	ds_read_b128 v[116:119], v248
	ds_read_b128 v[120:123], v249
	ds_read_b128 v[124:127], v250
	ds_read_b128 v[128:131], v251
	ds_write_b128 v112, v[132:135]
	ds_write_b128 v112, v[136:139] offset:1024
	ds_write_b128 v112, v[140:143] offset:2048
	ds_write_b128 v112, v[144:147] offset:3072
	v_mfma_f32_32x32x16_bf16 v[32:47], v[192:195], v[52:55], v[32:47]
	v_mfma_f32_32x32x16_bf16 v[32:47], v[196:199], v[56:59], v[32:47]
	v_mfma_f32_32x32x16_bf16 v[32:47], v[200:203], v[60:63], v[32:47]
	s_nop 11
	v_exp_f32_e32 v32, v32
	v_exp_f32_e32 v33, v33
	v_exp_f32_e32 v34, v34
	v_exp_f32_e32 v35, v35
	v_exp_f32_e32 v36, v36
	v_exp_f32_e32 v37, v37
	v_exp_f32_e32 v38, v38
	v_exp_f32_e32 v39, v39
	v_exp_f32_e32 v40, v40
	v_exp_f32_e32 v41, v41
	v_exp_f32_e32 v42, v42
	v_exp_f32_e32 v43, v43
	v_exp_f32_e32 v44, v44
	v_exp_f32_e32 v45, v45
	v_exp_f32_e32 v46, v46
	v_exp_f32_e32 v47, v47
	s_add_i32 s90, s76, 480
	v_add_u32_e32 v84, s90, v107
	v_add_u32_e32 v85, 0, v84
	v_add_u32_e32 v86, 1, v84
	v_add_u32_e32 v87, 2, v84
	v_add_u32_e32 v88, 3, v84
	v_cmp_gt_u32_e64 s[30:31], s98, v85
	v_cmp_gt_u32_e64 s[36:37], s98, v86
	v_cmp_gt_u32_e64 s[78:79], s98, v87
	v_cmp_gt_u32_e64 s[50:51], s98, v88
	v_cndmask_b32_e64 v32, 0, v32, s[30:31]
	v_add_u32_e32 v85, 8, v84
	v_cmp_gt_u32_e64 s[30:31], s98, v85
	v_cndmask_b32_e64 v33, 0, v33, s[36:37]
	v_add_u32_e32 v86, 9, v84
	v_cmp_gt_u32_e64 s[36:37], s98, v86
	v_cndmask_b32_e64 v34, 0, v34, s[78:79]
	v_add_u32_e32 v87, 10, v84
	v_cmp_gt_u32_e64 s[78:79], s98, v87
	v_cndmask_b32_e64 v35, 0, v35, s[50:51]
	v_add_u32_e32 v88, 11, v84
	v_cmp_gt_u32_e64 s[50:51], s98, v88
	v_cndmask_b32_e64 v36, 0, v36, s[30:31]
	v_add_u32_e32 v85, 16, v84
	v_cmp_gt_u32_e64 s[30:31], s98, v85
	v_cndmask_b32_e64 v37, 0, v37, s[36:37]
	v_add_u32_e32 v86, 17, v84
	v_cmp_gt_u32_e64 s[36:37], s98, v86
	v_cndmask_b32_e64 v38, 0, v38, s[78:79]
	v_add_u32_e32 v87, 18, v84
	v_cmp_gt_u32_e64 s[78:79], s98, v87
	v_cndmask_b32_e64 v39, 0, v39, s[50:51]
	v_add_u32_e32 v88, 19, v84
	v_cmp_gt_u32_e64 s[50:51], s98, v88
	v_cndmask_b32_e64 v40, 0, v40, s[30:31]
	v_add_u32_e32 v85, 24, v84
	v_cmp_gt_u32_e64 s[30:31], s98, v85
	v_cndmask_b32_e64 v41, 0, v41, s[36:37]
	v_add_u32_e32 v86, 25, v84
	v_cmp_gt_u32_e64 s[36:37], s98, v86
	v_cndmask_b32_e64 v42, 0, v42, s[78:79]
	v_add_u32_e32 v87, 26, v84
	v_cmp_gt_u32_e64 s[78:79], s98, v87
	v_cndmask_b32_e64 v43, 0, v43, s[50:51]
	v_add_u32_e32 v88, 27, v84
	v_cmp_gt_u32_e64 s[50:51], s98, v88
	v_nop
	v_cndmask_b32_e64 v44, 0, v44, s[30:31]
	v_cndmask_b32_e64 v45, 0, v45, s[36:37]
	v_cndmask_b32_e64 v46, 0, v46, s[78:79]
	v_cndmask_b32_e64 v47, 0, v47, s[50:51]
	v_cvt_pk_bf16_f32 v64, v32, v33
	v_cvt_pk_bf16_f32 v65, v34, v35
	v_cvt_pk_bf16_f32 v66, v36, v37
	v_cvt_pk_bf16_f32 v67, v38, v39
	v_cvt_pk_bf16_f32 v68, v40, v41
	v_cvt_pk_bf16_f32 v69, v42, v43
	v_cvt_pk_bf16_f32 v70, v44, v45
	v_cvt_pk_bf16_f32 v71, v46, v47
	v_pk_add_f32 v[232:233], v[232:233], v[32:33]
	v_pk_add_f32 v[232:233], v[232:233], v[34:35]
	v_pk_add_f32 v[232:233], v[232:233], v[36:37]
	v_pk_add_f32 v[232:233], v[232:233], v[38:39]
	v_pk_add_f32 v[232:233], v[232:233], v[40:41]
	v_pk_add_f32 v[232:233], v[232:233], v[42:43]
	v_pk_add_f32 v[232:233], v[232:233], v[44:45]
	v_pk_add_f32 v[232:233], v[232:233], v[46:47]
	s_waitcnt lgkmcnt(12)
	v_mfma_f32_32x32x16_bf16 v[0:15], v[64:67], v[72:75], v[0:15]
	v_mfma_f32_32x32x16_bf16 v[16:31], v[64:67], v[76:79], v[16:31]
	v_mfma_f32_32x32x16_bf16 v[0:15], v[68:71], v[220:223], v[0:15]
	v_mfma_f32_32x32x16_bf16 v[16:31], v[68:71], v[224:227], v[16:31]
	s_add_i32 s90, s76, -256
	v_add_u32_e32 v80, s90, v239
	v_add_u32_e32 v83, s90, v240
	v_add_u32_e32 v99, s90, v241
	v_add_u32_e32 v253, s90, v242
	v_add_u32_e32 v254, s90, v101
	v_add_u32_e32 v255, s90, v150
	v_med3_i32 v80, v80, 0, s99
	v_med3_i32 v83, v83, 0, s99
	v_med3_i32 v99, v99, 0, s99
	v_med3_i32 v253, v253, 0, s99
	v_med3_i32 v254, v254, 0, s99
	v_med3_i32 v255, v255, 0, s99
	v_mad_u32_u24 v80, v80, s100, v252
	v_mad_u32_u24 v83, v83, s100, v252
	v_mad_u32_u24 v99, v99, s100, v252
	v_mad_u32_u24 v253, v253, s100, v252
	v_mad_u32_u24 v254, v254, s100, v153
	v_mad_u32_u24 v255, v255, s100, v153
	global_load_dwordx4 v[188:191], v80, s[82:83]
	global_load_dwordx4 v[192:195], v83, s[82:83]
	global_load_dwordx4 v[196:199], v99, s[82:83]
	global_load_dwordx4 v[200:203], v253, s[82:83]
	global_load_dwordx4 v[204:207], v254, s[82:83] offset:768
	global_load_dwordx4 v[208:211], v255, s[82:83] offset:768
	global_load_dwordx4 v[212:215], v254, s[82:83] offset:832
	global_load_dwordx4 v[216:219], v255, s[82:83] offset:832
	ds_read2_b32 v[32:33], v115 offset0:136 offset1:137
	ds_read2_b32 v[34:35], v115 offset0:138 offset1:139
	ds_read2_b32 v[36:37], v115 offset0:144 offset1:145
	ds_read2_b32 v[38:39], v115 offset0:146 offset1:147
	ds_read2_b32 v[40:41], v115 offset0:153 offset1:154
	ds_read2_b32 v[42:43], v115 offset0:155 offset1:156
	ds_read2_b32 v[44:45], v115 offset0:161 offset1:162
	ds_read2_b32 v[46:47], v115 offset0:163 offset1:164
	s_waitcnt lgkmcnt(0)
	v_mfma_f32_32x32x16_bf16 v[32:47], v[116:119], v[48:51], v[32:47]
	ds_read_b64_tr_b16 v[72:73], v231
	ds_read_b64_tr_b16 v[74:75], v231 offset:512
	ds_read_b64_tr_b16 v[76:77], v231 offset:2048
	ds_read_b64_tr_b16 v[78:79], v231 offset:2560
	ds_read_b64_tr_b16 v[220:221], v231 offset:1024
	ds_read_b64_tr_b16 v[222:223], v231 offset:1536
	ds_read_b64_tr_b16 v[224:225], v231 offset:3072
	ds_read_b64_tr_b16 v[226:227], v231 offset:3584
	s_waitcnt vmcnt(8)
	ds_write_b128 v247, v[156:159]
	ds_write_b128 v247, v[160:163] offset:1024
	ds_write_b128 v247, v[164:167] offset:2048
	ds_write_b128 v247, v[168:171] offset:3072
	ds_read_b128 v[156:159], v248
	ds_read_b128 v[160:163], v249
	ds_read_b128 v[164:167], v250
	ds_read_b128 v[168:171], v251
	ds_write_b128 v112, v[172:175]
	ds_write_b128 v112, v[176:179] offset:1024
	ds_write_b128 v112, v[180:183] offset:2048
	ds_write_b128 v112, v[184:187] offset:3072
	v_mfma_f32_32x32x16_bf16 v[32:47], v[120:123], v[52:55], v[32:47]
	v_mfma_f32_32x32x16_bf16 v[32:47], v[124:127], v[56:59], v[32:47]
	v_mfma_f32_32x32x16_bf16 v[32:47], v[128:131], v[60:63], v[32:47]
	s_nop 11
	v_exp_f32_e32 v32, v32
	v_exp_f32_e32 v33, v33
	v_exp_f32_e32 v34, v34
	v_exp_f32_e32 v35, v35
	v_exp_f32_e32 v36, v36
	v_exp_f32_e32 v37, v37
	v_exp_f32_e32 v38, v38
	v_exp_f32_e32 v39, v39
	v_exp_f32_e32 v40, v40
	v_exp_f32_e32 v41, v41
	v_exp_f32_e32 v42, v42
	v_exp_f32_e32 v43, v43
	v_exp_f32_e32 v44, v44
	v_exp_f32_e32 v45, v45
	v_exp_f32_e32 v46, v46
	v_exp_f32_e32 v47, v47
	s_add_i32 s90, s76, 512
	v_add_u32_e32 v84, s90, v107
	v_add_u32_e32 v85, 0, v84
	v_add_u32_e32 v86, 1, v84
	v_add_u32_e32 v87, 2, v84
	v_add_u32_e32 v88, 3, v84
	v_cmp_gt_u32_e64 s[30:31], s98, v85
	v_cmp_gt_u32_e64 s[36:37], s98, v86
	v_cmp_gt_u32_e64 s[78:79], s98, v87
	v_cmp_gt_u32_e64 s[50:51], s98, v88
	v_cndmask_b32_e64 v32, 0, v32, s[30:31]
	v_add_u32_e32 v85, 8, v84
	v_cmp_gt_u32_e64 s[30:31], s98, v85
	v_cndmask_b32_e64 v33, 0, v33, s[36:37]
	v_add_u32_e32 v86, 9, v84
	v_cmp_gt_u32_e64 s[36:37], s98, v86
	v_cndmask_b32_e64 v34, 0, v34, s[78:79]
	v_add_u32_e32 v87, 10, v84
	v_cmp_gt_u32_e64 s[78:79], s98, v87
	v_cndmask_b32_e64 v35, 0, v35, s[50:51]
	v_add_u32_e32 v88, 11, v84
	v_cmp_gt_u32_e64 s[50:51], s98, v88
	v_cndmask_b32_e64 v36, 0, v36, s[30:31]
	v_add_u32_e32 v85, 16, v84
	v_cmp_gt_u32_e64 s[30:31], s98, v85
	v_cndmask_b32_e64 v37, 0, v37, s[36:37]
	v_add_u32_e32 v86, 17, v84
	v_cmp_gt_u32_e64 s[36:37], s98, v86
	v_cndmask_b32_e64 v38, 0, v38, s[78:79]
	v_add_u32_e32 v87, 18, v84
	v_cmp_gt_u32_e64 s[78:79], s98, v87
	v_cndmask_b32_e64 v39, 0, v39, s[50:51]
	v_add_u32_e32 v88, 19, v84
	v_cmp_gt_u32_e64 s[50:51], s98, v88
	v_cndmask_b32_e64 v40, 0, v40, s[30:31]
	v_add_u32_e32 v85, 24, v84
	v_cmp_gt_u32_e64 s[30:31], s98, v85
	v_cndmask_b32_e64 v41, 0, v41, s[36:37]
	v_add_u32_e32 v86, 25, v84
	v_cmp_gt_u32_e64 s[36:37], s98, v86
	v_cndmask_b32_e64 v42, 0, v42, s[78:79]
	v_add_u32_e32 v87, 26, v84
	v_cmp_gt_u32_e64 s[78:79], s98, v87
	v_cndmask_b32_e64 v43, 0, v43, s[50:51]
	v_add_u32_e32 v88, 27, v84
	v_cmp_gt_u32_e64 s[50:51], s98, v88
	v_nop
	v_cndmask_b32_e64 v44, 0, v44, s[30:31]
	v_cndmask_b32_e64 v45, 0, v45, s[36:37]
	v_cndmask_b32_e64 v46, 0, v46, s[78:79]
	v_cndmask_b32_e64 v47, 0, v47, s[50:51]
	v_cvt_pk_bf16_f32 v64, v32, v33
	v_cvt_pk_bf16_f32 v65, v34, v35
	v_cvt_pk_bf16_f32 v66, v36, v37
	v_cvt_pk_bf16_f32 v67, v38, v39
	v_cvt_pk_bf16_f32 v68, v40, v41
	v_cvt_pk_bf16_f32 v69, v42, v43
	v_cvt_pk_bf16_f32 v70, v44, v45
	v_cvt_pk_bf16_f32 v71, v46, v47
	v_pk_add_f32 v[232:233], v[232:233], v[32:33]
	v_pk_add_f32 v[232:233], v[232:233], v[34:35]
	v_pk_add_f32 v[232:233], v[232:233], v[36:37]
	v_pk_add_f32 v[232:233], v[232:233], v[38:39]
	v_pk_add_f32 v[232:233], v[232:233], v[40:41]
	v_pk_add_f32 v[232:233], v[232:233], v[42:43]
	v_pk_add_f32 v[232:233], v[232:233], v[44:45]
	v_pk_add_f32 v[232:233], v[232:233], v[46:47]
	s_waitcnt lgkmcnt(12)
	v_mfma_f32_32x32x16_bf16 v[0:15], v[64:67], v[72:75], v[0:15]
	v_mfma_f32_32x32x16_bf16 v[16:31], v[64:67], v[76:79], v[16:31]
	v_mfma_f32_32x32x16_bf16 v[0:15], v[68:71], v[220:223], v[0:15]
	v_mfma_f32_32x32x16_bf16 v[16:31], v[68:71], v[224:227], v[16:31]
	s_add_i32 s90, s76, -128
	v_add_u32_e32 v80, s90, v239
	v_add_u32_e32 v83, s90, v240
	v_add_u32_e32 v99, s90, v241
	v_add_u32_e32 v253, s90, v242
	v_add_u32_e32 v254, s90, v101
	v_add_u32_e32 v255, s90, v150
	v_med3_i32 v80, v80, 0, s99
	v_med3_i32 v83, v83, 0, s99
	v_med3_i32 v99, v99, 0, s99
	v_med3_i32 v253, v253, 0, s99
	v_med3_i32 v254, v254, 0, s99
	v_med3_i32 v255, v255, 0, s99
	v_mad_u32_u24 v80, v80, s100, v252
	v_mad_u32_u24 v83, v83, s100, v252
	v_mad_u32_u24 v99, v99, s100, v252
	v_mad_u32_u24 v253, v253, s100, v252
	v_mad_u32_u24 v254, v254, s100, v153
	v_mad_u32_u24 v255, v255, s100, v153
	global_load_dwordx4 v[116:119], v80, s[82:83]
	global_load_dwordx4 v[120:123], v83, s[82:83]
	global_load_dwordx4 v[124:127], v99, s[82:83]
	global_load_dwordx4 v[128:131], v253, s[82:83]
	global_load_dwordx4 v[132:135], v254, s[82:83] offset:768
	global_load_dwordx4 v[136:139], v255, s[82:83] offset:768
	global_load_dwordx4 v[140:143], v254, s[82:83] offset:832
	global_load_dwordx4 v[144:147], v255, s[82:83] offset:832
	ds_read2_b32 v[32:33], v115 offset0:170 offset1:171
	ds_read2_b32 v[34:35], v115 offset0:172 offset1:173
	ds_read2_b32 v[36:37], v115 offset0:178 offset1:179
	ds_read2_b32 v[38:39], v115 offset0:180 offset1:181
	ds_read2_b32 v[40:41], v115 offset0:187 offset1:188
	ds_read2_b32 v[42:43], v115 offset0:189 offset1:190
	ds_read2_b32 v[44:45], v115 offset0:195 offset1:196
	ds_read2_b32 v[46:47], v115 offset0:197 offset1:198
	s_waitcnt lgkmcnt(0)
	v_mfma_f32_32x32x16_bf16 v[32:47], v[156:159], v[48:51], v[32:47]
	ds_read_b64_tr_b16 v[72:73], v231
	ds_read_b64_tr_b16 v[74:75], v231 offset:512
	ds_read_b64_tr_b16 v[76:77], v231 offset:2048
	ds_read_b64_tr_b16 v[78:79], v231 offset:2560
	ds_read_b64_tr_b16 v[220:221], v231 offset:1024
	ds_read_b64_tr_b16 v[222:223], v231 offset:1536
	ds_read_b64_tr_b16 v[224:225], v231 offset:3072
	ds_read_b64_tr_b16 v[226:227], v231 offset:3584
	s_waitcnt vmcnt(8)
	ds_write_b128 v247, v[188:191]
	ds_write_b128 v247, v[192:195] offset:1024
	ds_write_b128 v247, v[196:199] offset:2048
	ds_write_b128 v247, v[200:203] offset:3072
	ds_read_b128 v[188:191], v248
	ds_read_b128 v[192:195], v249
	ds_read_b128 v[196:199], v250
	ds_read_b128 v[200:203], v251
	ds_write_b128 v112, v[204:207]
	ds_write_b128 v112, v[208:211] offset:1024
	ds_write_b128 v112, v[212:215] offset:2048
	ds_write_b128 v112, v[216:219] offset:3072
	v_mfma_f32_32x32x16_bf16 v[32:47], v[160:163], v[52:55], v[32:47]
	v_mfma_f32_32x32x16_bf16 v[32:47], v[164:167], v[56:59], v[32:47]
	v_mfma_f32_32x32x16_bf16 v[32:47], v[168:171], v[60:63], v[32:47]
	s_nop 11
	v_exp_f32_e32 v32, v32
	v_exp_f32_e32 v33, v33
	v_exp_f32_e32 v34, v34
	v_exp_f32_e32 v35, v35
	v_exp_f32_e32 v36, v36
	v_exp_f32_e32 v37, v37
	v_exp_f32_e32 v38, v38
	v_exp_f32_e32 v39, v39
	v_exp_f32_e32 v40, v40
	v_exp_f32_e32 v41, v41
	v_exp_f32_e32 v42, v42
	v_exp_f32_e32 v43, v43
	v_exp_f32_e32 v44, v44
	v_exp_f32_e32 v45, v45
	v_exp_f32_e32 v46, v46
	v_exp_f32_e32 v47, v47
	s_add_i32 s90, s76, 544
	v_add_u32_e32 v84, s90, v107
	v_add_u32_e32 v85, 0, v84
	v_add_u32_e32 v86, 1, v84
	v_add_u32_e32 v87, 2, v84
	v_add_u32_e32 v88, 3, v84
	v_cmp_gt_u32_e64 s[30:31], s98, v85
	v_cmp_gt_u32_e64 s[36:37], s98, v86
	v_cmp_gt_u32_e64 s[78:79], s98, v87
	v_cmp_gt_u32_e64 s[50:51], s98, v88
	v_cndmask_b32_e64 v32, 0, v32, s[30:31]
	v_add_u32_e32 v85, 8, v84
	v_cmp_gt_u32_e64 s[30:31], s98, v85
	v_cndmask_b32_e64 v33, 0, v33, s[36:37]
	v_add_u32_e32 v86, 9, v84
	v_cmp_gt_u32_e64 s[36:37], s98, v86
	v_cndmask_b32_e64 v34, 0, v34, s[78:79]
	v_add_u32_e32 v87, 10, v84
	v_cmp_gt_u32_e64 s[78:79], s98, v87
	v_cndmask_b32_e64 v35, 0, v35, s[50:51]
	v_add_u32_e32 v88, 11, v84
	v_cmp_gt_u32_e64 s[50:51], s98, v88
	v_cndmask_b32_e64 v36, 0, v36, s[30:31]
	v_add_u32_e32 v85, 16, v84
	v_cmp_gt_u32_e64 s[30:31], s98, v85
	v_cndmask_b32_e64 v37, 0, v37, s[36:37]
	v_add_u32_e32 v86, 17, v84
	v_cmp_gt_u32_e64 s[36:37], s98, v86
	v_cndmask_b32_e64 v38, 0, v38, s[78:79]
	v_add_u32_e32 v87, 18, v84
	v_cmp_gt_u32_e64 s[78:79], s98, v87
	v_cndmask_b32_e64 v39, 0, v39, s[50:51]
	v_add_u32_e32 v88, 19, v84
	v_cmp_gt_u32_e64 s[50:51], s98, v88
	v_cndmask_b32_e64 v40, 0, v40, s[30:31]
	v_add_u32_e32 v85, 24, v84
	v_cmp_gt_u32_e64 s[30:31], s98, v85
	v_cndmask_b32_e64 v41, 0, v41, s[36:37]
	v_add_u32_e32 v86, 25, v84
	v_cmp_gt_u32_e64 s[36:37], s98, v86
	v_cndmask_b32_e64 v42, 0, v42, s[78:79]
	v_add_u32_e32 v87, 26, v84
	v_cmp_gt_u32_e64 s[78:79], s98, v87
	v_cndmask_b32_e64 v43, 0, v43, s[50:51]
	v_add_u32_e32 v88, 27, v84
	v_cmp_gt_u32_e64 s[50:51], s98, v88
	v_nop
	v_cndmask_b32_e64 v44, 0, v44, s[30:31]
	v_cndmask_b32_e64 v45, 0, v45, s[36:37]
	v_cndmask_b32_e64 v46, 0, v46, s[78:79]
	v_cndmask_b32_e64 v47, 0, v47, s[50:51]
	v_cvt_pk_bf16_f32 v64, v32, v33
	v_cvt_pk_bf16_f32 v65, v34, v35
	v_cvt_pk_bf16_f32 v66, v36, v37
	v_cvt_pk_bf16_f32 v67, v38, v39
	v_cvt_pk_bf16_f32 v68, v40, v41
	v_cvt_pk_bf16_f32 v69, v42, v43
	v_cvt_pk_bf16_f32 v70, v44, v45
	v_cvt_pk_bf16_f32 v71, v46, v47
	v_pk_add_f32 v[232:233], v[232:233], v[32:33]
	v_pk_add_f32 v[232:233], v[232:233], v[34:35]
	v_pk_add_f32 v[232:233], v[232:233], v[36:37]
	v_pk_add_f32 v[232:233], v[232:233], v[38:39]
	v_pk_add_f32 v[232:233], v[232:233], v[40:41]
	v_pk_add_f32 v[232:233], v[232:233], v[42:43]
	v_pk_add_f32 v[232:233], v[232:233], v[44:45]
	v_pk_add_f32 v[232:233], v[232:233], v[46:47]
	s_waitcnt lgkmcnt(12)
	v_mfma_f32_32x32x16_bf16 v[0:15], v[64:67], v[72:75], v[0:15]
	v_mfma_f32_32x32x16_bf16 v[16:31], v[64:67], v[76:79], v[16:31]
	v_mfma_f32_32x32x16_bf16 v[0:15], v[68:71], v[220:223], v[0:15]
	v_mfma_f32_32x32x16_bf16 v[16:31], v[68:71], v[224:227], v[16:31]
	s_add_i32 s90, s76, 0
	v_add_u32_e32 v80, s90, v239
	v_add_u32_e32 v83, s90, v240
	v_add_u32_e32 v99, s90, v241
	v_add_u32_e32 v253, s90, v242
	v_add_u32_e32 v254, s90, v101
	v_add_u32_e32 v255, s90, v150
	v_med3_i32 v80, v80, 0, s99
	v_med3_i32 v83, v83, 0, s99
	v_med3_i32 v99, v99, 0, s99
	v_med3_i32 v253, v253, 0, s99
	v_med3_i32 v254, v254, 0, s99
	v_med3_i32 v255, v255, 0, s99
	v_mad_u32_u24 v80, v80, s100, v252
	v_mad_u32_u24 v83, v83, s100, v252
	v_mad_u32_u24 v99, v99, s100, v252
	v_mad_u32_u24 v253, v253, s100, v252
	v_mad_u32_u24 v254, v254, s100, v153
	v_mad_u32_u24 v255, v255, s100, v153
	global_load_dwordx4 v[156:159], v80, s[82:83]
	global_load_dwordx4 v[160:163], v83, s[82:83]
	global_load_dwordx4 v[164:167], v99, s[82:83]
	global_load_dwordx4 v[168:171], v253, s[82:83]
	global_load_dwordx4 v[172:175], v254, s[82:83] offset:768
	global_load_dwordx4 v[176:179], v255, s[82:83] offset:768
	global_load_dwordx4 v[180:183], v254, s[82:83] offset:832
	global_load_dwordx4 v[184:187], v255, s[82:83] offset:832
	v_mov_b32_e32 v115, v229
	ds_read2_b32 v[32:33], v115 offset0:0 offset1:1
	ds_read2_b32 v[34:35], v115 offset0:2 offset1:3
	ds_read2_b32 v[36:37], v115 offset0:8 offset1:9
	ds_read2_b32 v[38:39], v115 offset0:10 offset1:11
	ds_read2_b32 v[40:41], v115 offset0:16 offset1:17
	ds_read2_b32 v[42:43], v115 offset0:18 offset1:19
	ds_read2_b32 v[44:45], v115 offset0:24 offset1:25
	ds_read2_b32 v[46:47], v115 offset0:26 offset1:27
	s_waitcnt lgkmcnt(0)
	v_mfma_f32_32x32x16_bf16 v[32:47], v[188:191], v[48:51], v[32:47]
	ds_read_b64_tr_b16 v[72:73], v231
	ds_read_b64_tr_b16 v[74:75], v231 offset:512
	ds_read_b64_tr_b16 v[76:77], v231 offset:2048
	ds_read_b64_tr_b16 v[78:79], v231 offset:2560
	ds_read_b64_tr_b16 v[220:221], v231 offset:1024
	ds_read_b64_tr_b16 v[222:223], v231 offset:1536
	ds_read_b64_tr_b16 v[224:225], v231 offset:3072
	ds_read_b64_tr_b16 v[226:227], v231 offset:3584
	s_waitcnt vmcnt(8)
	ds_write_b128 v247, v[116:119]
	ds_write_b128 v247, v[120:123] offset:1024
	ds_write_b128 v247, v[124:127] offset:2048
	ds_write_b128 v247, v[128:131] offset:3072
	ds_read_b128 v[116:119], v248
	ds_read_b128 v[120:123], v249
	ds_read_b128 v[124:127], v250
	ds_read_b128 v[128:131], v251
	ds_write_b128 v112, v[132:135]
	ds_write_b128 v112, v[136:139] offset:1024
	ds_write_b128 v112, v[140:143] offset:2048
	ds_write_b128 v112, v[144:147] offset:3072
	v_mfma_f32_32x32x16_bf16 v[32:47], v[192:195], v[52:55], v[32:47]
	v_mfma_f32_32x32x16_bf16 v[32:47], v[196:199], v[56:59], v[32:47]
	v_mfma_f32_32x32x16_bf16 v[32:47], v[200:203], v[60:63], v[32:47]
	s_nop 11
	v_exp_f32_e32 v32, v32
	v_exp_f32_e32 v33, v33
	v_exp_f32_e32 v34, v34
	v_exp_f32_e32 v35, v35
	v_exp_f32_e32 v36, v36
	v_exp_f32_e32 v37, v37
	v_exp_f32_e32 v38, v38
	v_exp_f32_e32 v39, v39
	v_exp_f32_e32 v40, v40
	v_exp_f32_e32 v41, v41
	v_exp_f32_e32 v42, v42
	v_exp_f32_e32 v43, v43
	v_exp_f32_e32 v44, v44
	v_exp_f32_e32 v45, v45
	v_exp_f32_e32 v46, v46
	v_exp_f32_e32 v47, v47
	s_add_i32 s90, s76, -256
	v_lshlrev_b32_e32 v84, 2, v107
	v_add_u32_e32 v84, s90, v84
	v_add_u32_e32 v85, 0, v84
	v_add_u32_e32 v86, 4, v84
	v_add_u32_e32 v87, 8, v84
	v_add_u32_e32 v88, 12, v84
	v_cmp_gt_u32_e64 s[30:31], s98, v85
	v_cmp_gt_u32_e64 s[36:37], s98, v86
	v_cmp_gt_u32_e64 s[78:79], s98, v87
	v_cmp_gt_u32_e64 s[50:51], s98, v88
	v_cndmask_b32_e64 v32, 0, v32, s[30:31]
	v_add_u32_e32 v85, 32, v84
	v_cmp_gt_u32_e64 s[30:31], s98, v85
	v_cndmask_b32_e64 v33, 0, v33, s[36:37]
	v_add_u32_e32 v86, 36, v84
	v_cmp_gt_u32_e64 s[36:37], s98, v86
	v_cndmask_b32_e64 v34, 0, v34, s[78:79]
	v_add_u32_e32 v87, 40, v84
	v_cmp_gt_u32_e64 s[78:79], s98, v87
	v_cndmask_b32_e64 v35, 0, v35, s[50:51]
	v_add_u32_e32 v88, 44, v84
	v_cmp_gt_u32_e64 s[50:51], s98, v88
	v_cndmask_b32_e64 v36, 0, v36, s[30:31]
	v_add_u32_e32 v85, 64, v84
	v_cmp_gt_u32_e64 s[30:31], s98, v85
	v_cndmask_b32_e64 v37, 0, v37, s[36:37]
	v_add_u32_e32 v86, 68, v84
	v_cmp_gt_u32_e64 s[36:37], s98, v86
	v_cndmask_b32_e64 v38, 0, v38, s[78:79]
	v_add_u32_e32 v87, 72, v84
	v_cmp_gt_u32_e64 s[78:79], s98, v87
	v_cndmask_b32_e64 v39, 0, v39, s[50:51]
	v_add_u32_e32 v88, 76, v84
	v_cmp_gt_u32_e64 s[50:51], s98, v88
	v_cndmask_b32_e64 v40, 0, v40, s[30:31]
	v_add_u32_e32 v85, 96, v84
	v_cmp_gt_u32_e64 s[30:31], s98, v85
	v_cndmask_b32_e64 v41, 0, v41, s[36:37]
	v_add_u32_e32 v86, 100, v84
	v_cmp_gt_u32_e64 s[36:37], s98, v86
	v_cndmask_b32_e64 v42, 0, v42, s[78:79]
	v_add_u32_e32 v87, 104, v84
	v_cmp_gt_u32_e64 s[78:79], s98, v87
	v_cndmask_b32_e64 v43, 0, v43, s[50:51]
	v_add_u32_e32 v88, 108, v84
	v_cmp_gt_u32_e64 s[50:51], s98, v88
	v_nop
	v_cndmask_b32_e64 v44, 0, v44, s[30:31]
	v_cndmask_b32_e64 v45, 0, v45, s[36:37]
	v_cndmask_b32_e64 v46, 0, v46, s[78:79]
	v_cndmask_b32_e64 v47, 0, v47, s[50:51]
	v_cvt_pk_bf16_f32 v64, v32, v33
	v_cvt_pk_bf16_f32 v65, v34, v35
	v_cvt_pk_bf16_f32 v66, v36, v37
	v_cvt_pk_bf16_f32 v67, v38, v39
	v_cvt_pk_bf16_f32 v68, v40, v41
	v_cvt_pk_bf16_f32 v69, v42, v43
	v_cvt_pk_bf16_f32 v70, v44, v45
	v_cvt_pk_bf16_f32 v71, v46, v47
	v_pk_add_f32 v[232:233], v[232:233], v[32:33]
	v_pk_add_f32 v[232:233], v[232:233], v[34:35]
	v_pk_add_f32 v[232:233], v[232:233], v[36:37]
	v_pk_add_f32 v[232:233], v[232:233], v[38:39]
	v_pk_add_f32 v[232:233], v[232:233], v[40:41]
	v_pk_add_f32 v[232:233], v[232:233], v[42:43]
	v_pk_add_f32 v[232:233], v[232:233], v[44:45]
	v_pk_add_f32 v[232:233], v[232:233], v[46:47]
	s_waitcnt lgkmcnt(12)
	v_mfma_f32_32x32x16_bf16 v[0:15], v[64:67], v[72:75], v[0:15]
	v_mfma_f32_32x32x16_bf16 v[16:31], v[64:67], v[76:79], v[16:31]
	v_mfma_f32_32x32x16_bf16 v[0:15], v[68:71], v[220:223], v[0:15]
	v_mfma_f32_32x32x16_bf16 v[16:31], v[68:71], v[224:227], v[16:31]
	s_add_i32 s90, s76, 128
	v_add_u32_e32 v80, s90, v239
	v_add_u32_e32 v83, s90, v240
	v_add_u32_e32 v99, s90, v241
	v_add_u32_e32 v253, s90, v242
	v_add_u32_e32 v254, s90, v101
	v_add_u32_e32 v255, s90, v150
	v_med3_i32 v80, v80, 0, s99
	v_med3_i32 v83, v83, 0, s99
	v_med3_i32 v99, v99, 0, s99
	v_med3_i32 v253, v253, 0, s99
	v_med3_i32 v254, v254, 0, s99
	v_med3_i32 v255, v255, 0, s99
	v_mad_u32_u24 v80, v80, s100, v252
	v_mad_u32_u24 v83, v83, s100, v252
	v_mad_u32_u24 v99, v99, s100, v252
	v_mad_u32_u24 v253, v253, s100, v252
	v_mad_u32_u24 v254, v254, s100, v153
	v_mad_u32_u24 v255, v255, s100, v153
	global_load_dwordx4 v[188:191], v80, s[82:83]
	global_load_dwordx4 v[192:195], v83, s[82:83]
	global_load_dwordx4 v[196:199], v99, s[82:83]
	global_load_dwordx4 v[200:203], v253, s[82:83]
	global_load_dwordx4 v[204:207], v254, s[82:83] offset:768
	global_load_dwordx4 v[208:211], v255, s[82:83] offset:768
	global_load_dwordx4 v[212:215], v254, s[82:83] offset:832
	global_load_dwordx4 v[216:219], v255, s[82:83] offset:832
	ds_read2_b32 v[32:33], v115 offset0:32 offset1:33
	ds_read2_b32 v[34:35], v115 offset0:34 offset1:35
	ds_read2_b32 v[36:37], v115 offset0:40 offset1:41
	ds_read2_b32 v[38:39], v115 offset0:42 offset1:43
	ds_read2_b32 v[40:41], v115 offset0:48 offset1:49
	ds_read2_b32 v[42:43], v115 offset0:50 offset1:51
	ds_read2_b32 v[44:45], v115 offset0:56 offset1:57
	ds_read2_b32 v[46:47], v115 offset0:58 offset1:59
	s_waitcnt lgkmcnt(0)
	v_mfma_f32_32x32x16_bf16 v[32:47], v[116:119], v[48:51], v[32:47]
	ds_read_b64_tr_b16 v[72:73], v231
	ds_read_b64_tr_b16 v[74:75], v231 offset:512
	ds_read_b64_tr_b16 v[76:77], v231 offset:2048
	ds_read_b64_tr_b16 v[78:79], v231 offset:2560
	ds_read_b64_tr_b16 v[220:221], v231 offset:1024
	ds_read_b64_tr_b16 v[222:223], v231 offset:1536
	ds_read_b64_tr_b16 v[224:225], v231 offset:3072
	ds_read_b64_tr_b16 v[226:227], v231 offset:3584
	s_waitcnt vmcnt(8)
	ds_write_b128 v247, v[156:159]
	ds_write_b128 v247, v[160:163] offset:1024
	ds_write_b128 v247, v[164:167] offset:2048
	ds_write_b128 v247, v[168:171] offset:3072
	ds_read_b128 v[156:159], v248
	ds_read_b128 v[160:163], v249
	ds_read_b128 v[164:167], v250
	ds_read_b128 v[168:171], v251
	ds_write_b128 v112, v[172:175]
	ds_write_b128 v112, v[176:179] offset:1024
	ds_write_b128 v112, v[180:183] offset:2048
	ds_write_b128 v112, v[184:187] offset:3072
	v_mfma_f32_32x32x16_bf16 v[32:47], v[120:123], v[52:55], v[32:47]
	v_mfma_f32_32x32x16_bf16 v[32:47], v[124:127], v[56:59], v[32:47]
	v_mfma_f32_32x32x16_bf16 v[32:47], v[128:131], v[60:63], v[32:47]
	s_nop 11
	v_exp_f32_e32 v32, v32
	v_exp_f32_e32 v33, v33
	v_exp_f32_e32 v34, v34
	v_exp_f32_e32 v35, v35
	v_exp_f32_e32 v36, v36
	v_exp_f32_e32 v37, v37
	v_exp_f32_e32 v38, v38
	v_exp_f32_e32 v39, v39
	v_exp_f32_e32 v40, v40
	v_exp_f32_e32 v41, v41
	v_exp_f32_e32 v42, v42
	v_exp_f32_e32 v43, v43
	v_exp_f32_e32 v44, v44
	v_exp_f32_e32 v45, v45
	v_exp_f32_e32 v46, v46
	v_exp_f32_e32 v47, v47
	s_add_i32 s90, s76, -128
	v_lshlrev_b32_e32 v84, 2, v107
	v_add_u32_e32 v84, s90, v84
	v_add_u32_e32 v85, 0, v84
	v_add_u32_e32 v86, 4, v84
	v_add_u32_e32 v87, 8, v84
	v_add_u32_e32 v88, 12, v84
	v_cmp_gt_u32_e64 s[30:31], s98, v85
	v_cmp_gt_u32_e64 s[36:37], s98, v86
	v_cmp_gt_u32_e64 s[78:79], s98, v87
	v_cmp_gt_u32_e64 s[50:51], s98, v88
	v_cndmask_b32_e64 v32, 0, v32, s[30:31]
	v_add_u32_e32 v85, 32, v84
	v_cmp_gt_u32_e64 s[30:31], s98, v85
	v_cndmask_b32_e64 v33, 0, v33, s[36:37]
	v_add_u32_e32 v86, 36, v84
	v_cmp_gt_u32_e64 s[36:37], s98, v86
	v_cndmask_b32_e64 v34, 0, v34, s[78:79]
	v_add_u32_e32 v87, 40, v84
	v_cmp_gt_u32_e64 s[78:79], s98, v87
	v_cndmask_b32_e64 v35, 0, v35, s[50:51]
	v_add_u32_e32 v88, 44, v84
	v_cmp_gt_u32_e64 s[50:51], s98, v88
	v_cndmask_b32_e64 v36, 0, v36, s[30:31]
	v_add_u32_e32 v85, 64, v84
	v_cmp_gt_u32_e64 s[30:31], s98, v85
	v_cndmask_b32_e64 v37, 0, v37, s[36:37]
	v_add_u32_e32 v86, 68, v84
	v_cmp_gt_u32_e64 s[36:37], s98, v86
	v_cndmask_b32_e64 v38, 0, v38, s[78:79]
	v_add_u32_e32 v87, 72, v84
	v_cmp_gt_u32_e64 s[78:79], s98, v87
	v_cndmask_b32_e64 v39, 0, v39, s[50:51]
	v_add_u32_e32 v88, 76, v84
	v_cmp_gt_u32_e64 s[50:51], s98, v88
	v_cndmask_b32_e64 v40, 0, v40, s[30:31]
	v_add_u32_e32 v85, 96, v84
	v_cmp_gt_u32_e64 s[30:31], s98, v85
	v_cndmask_b32_e64 v41, 0, v41, s[36:37]
	v_add_u32_e32 v86, 100, v84
	v_cmp_gt_u32_e64 s[36:37], s98, v86
	v_cndmask_b32_e64 v42, 0, v42, s[78:79]
	v_add_u32_e32 v87, 104, v84
	v_cmp_gt_u32_e64 s[78:79], s98, v87
	v_cndmask_b32_e64 v43, 0, v43, s[50:51]
	v_add_u32_e32 v88, 108, v84
	v_cmp_gt_u32_e64 s[50:51], s98, v88
	v_nop
	v_cndmask_b32_e64 v44, 0, v44, s[30:31]
	v_cndmask_b32_e64 v45, 0, v45, s[36:37]
	v_cndmask_b32_e64 v46, 0, v46, s[78:79]
	v_cndmask_b32_e64 v47, 0, v47, s[50:51]
	v_cvt_pk_bf16_f32 v64, v32, v33
	v_cvt_pk_bf16_f32 v65, v34, v35
	v_cvt_pk_bf16_f32 v66, v36, v37
	v_cvt_pk_bf16_f32 v67, v38, v39
	v_cvt_pk_bf16_f32 v68, v40, v41
	v_cvt_pk_bf16_f32 v69, v42, v43
	v_cvt_pk_bf16_f32 v70, v44, v45
	v_cvt_pk_bf16_f32 v71, v46, v47
	v_pk_add_f32 v[232:233], v[232:233], v[32:33]
	v_pk_add_f32 v[232:233], v[232:233], v[34:35]
	v_pk_add_f32 v[232:233], v[232:233], v[36:37]
	v_pk_add_f32 v[232:233], v[232:233], v[38:39]
	v_pk_add_f32 v[232:233], v[232:233], v[40:41]
	v_pk_add_f32 v[232:233], v[232:233], v[42:43]
	v_pk_add_f32 v[232:233], v[232:233], v[44:45]
	v_pk_add_f32 v[232:233], v[232:233], v[46:47]
	s_waitcnt lgkmcnt(12)
	v_mfma_f32_32x32x16_bf16 v[0:15], v[64:67], v[72:75], v[0:15]
	v_mfma_f32_32x32x16_bf16 v[16:31], v[64:67], v[76:79], v[16:31]
	v_mfma_f32_32x32x16_bf16 v[0:15], v[68:71], v[220:223], v[0:15]
	v_mfma_f32_32x32x16_bf16 v[16:31], v[68:71], v[224:227], v[16:31]
	s_add_i32 s90, s76, 256
	v_add_u32_e32 v80, s90, v239
	v_add_u32_e32 v83, s90, v240
	v_add_u32_e32 v99, s90, v241
	v_add_u32_e32 v253, s90, v242
	v_add_u32_e32 v254, s90, v101
	v_add_u32_e32 v255, s90, v150
	v_med3_i32 v80, v80, 0, s99
	v_med3_i32 v83, v83, 0, s99
	v_med3_i32 v99, v99, 0, s99
	v_med3_i32 v253, v253, 0, s99
	v_med3_i32 v254, v254, 0, s99
	v_med3_i32 v255, v255, 0, s99
	v_mad_u32_u24 v80, v80, s100, v252
	v_mad_u32_u24 v83, v83, s100, v252
	v_mad_u32_u24 v99, v99, s100, v252
	v_mad_u32_u24 v253, v253, s100, v252
	v_mad_u32_u24 v254, v254, s100, v153
	v_mad_u32_u24 v255, v255, s100, v153
	global_load_dwordx4 v[116:119], v80, s[82:83]
	global_load_dwordx4 v[120:123], v83, s[82:83]
	global_load_dwordx4 v[124:127], v99, s[82:83]
	global_load_dwordx4 v[128:131], v253, s[82:83]
	global_load_dwordx4 v[132:135], v254, s[82:83] offset:768
	global_load_dwordx4 v[136:139], v255, s[82:83] offset:768
	global_load_dwordx4 v[140:143], v254, s[82:83] offset:832
	global_load_dwordx4 v[144:147], v255, s[82:83] offset:832
	ds_read2_b32 v[32:33], v115 offset0:64 offset1:65
	ds_read2_b32 v[34:35], v115 offset0:66 offset1:67
	ds_read2_b32 v[36:37], v115 offset0:72 offset1:73
	ds_read2_b32 v[38:39], v115 offset0:74 offset1:75
	ds_read2_b32 v[40:41], v115 offset0:80 offset1:81
	ds_read2_b32 v[42:43], v115 offset0:82 offset1:83
	ds_read2_b32 v[44:45], v115 offset0:88 offset1:89
	ds_read2_b32 v[46:47], v115 offset0:90 offset1:91
	s_waitcnt lgkmcnt(0)
	v_mfma_f32_32x32x16_bf16 v[32:47], v[156:159], v[48:51], v[32:47]
	ds_read_b64_tr_b16 v[72:73], v231
	ds_read_b64_tr_b16 v[74:75], v231 offset:512
	ds_read_b64_tr_b16 v[76:77], v231 offset:2048
	ds_read_b64_tr_b16 v[78:79], v231 offset:2560
	ds_read_b64_tr_b16 v[220:221], v231 offset:1024
	ds_read_b64_tr_b16 v[222:223], v231 offset:1536
	ds_read_b64_tr_b16 v[224:225], v231 offset:3072
	ds_read_b64_tr_b16 v[226:227], v231 offset:3584
	s_waitcnt vmcnt(8)
	ds_write_b128 v247, v[188:191]
	ds_write_b128 v247, v[192:195] offset:1024
	ds_write_b128 v247, v[196:199] offset:2048
	ds_write_b128 v247, v[200:203] offset:3072
	ds_read_b128 v[188:191], v248
	ds_read_b128 v[192:195], v249
	ds_read_b128 v[196:199], v250
	ds_read_b128 v[200:203], v251
	ds_write_b128 v112, v[204:207]
	ds_write_b128 v112, v[208:211] offset:1024
	ds_write_b128 v112, v[212:215] offset:2048
	ds_write_b128 v112, v[216:219] offset:3072
	v_mfma_f32_32x32x16_bf16 v[32:47], v[160:163], v[52:55], v[32:47]
	v_mfma_f32_32x32x16_bf16 v[32:47], v[164:167], v[56:59], v[32:47]
	v_mfma_f32_32x32x16_bf16 v[32:47], v[168:171], v[60:63], v[32:47]
	s_nop 11
	v_exp_f32_e32 v32, v32
	v_exp_f32_e32 v33, v33
	v_exp_f32_e32 v34, v34
	v_exp_f32_e32 v35, v35
	v_exp_f32_e32 v36, v36
	v_exp_f32_e32 v37, v37
	v_exp_f32_e32 v38, v38
	v_exp_f32_e32 v39, v39
	v_exp_f32_e32 v40, v40
	v_exp_f32_e32 v41, v41
	v_exp_f32_e32 v42, v42
	v_exp_f32_e32 v43, v43
	v_exp_f32_e32 v44, v44
	v_exp_f32_e32 v45, v45
	v_exp_f32_e32 v46, v46
	v_exp_f32_e32 v47, v47
	s_add_i32 s90, s76, 0
	v_lshlrev_b32_e32 v84, 2, v107
	v_add_u32_e32 v84, s90, v84
	v_add_u32_e32 v85, 0, v84
	v_add_u32_e32 v86, 4, v84
	v_add_u32_e32 v87, 8, v84
	v_add_u32_e32 v88, 12, v84
	v_cmp_gt_u32_e64 s[30:31], s98, v85
	v_cmp_gt_u32_e64 s[36:37], s98, v86
	v_cmp_gt_u32_e64 s[78:79], s98, v87
	v_cmp_gt_u32_e64 s[50:51], s98, v88
	v_cndmask_b32_e64 v32, 0, v32, s[30:31]
	v_add_u32_e32 v85, 32, v84
	v_cmp_gt_u32_e64 s[30:31], s98, v85
	v_cndmask_b32_e64 v33, 0, v33, s[36:37]
	v_add_u32_e32 v86, 36, v84
	v_cmp_gt_u32_e64 s[36:37], s98, v86
	v_cndmask_b32_e64 v34, 0, v34, s[78:79]
	v_add_u32_e32 v87, 40, v84
	v_cmp_gt_u32_e64 s[78:79], s98, v87
	v_cndmask_b32_e64 v35, 0, v35, s[50:51]
	v_add_u32_e32 v88, 44, v84
	v_cmp_gt_u32_e64 s[50:51], s98, v88
	v_cndmask_b32_e64 v36, 0, v36, s[30:31]
	v_add_u32_e32 v85, 64, v84
	v_cmp_gt_u32_e64 s[30:31], s98, v85
	v_cndmask_b32_e64 v37, 0, v37, s[36:37]
	v_add_u32_e32 v86, 68, v84
	v_cmp_gt_u32_e64 s[36:37], s98, v86
	v_cndmask_b32_e64 v38, 0, v38, s[78:79]
	v_add_u32_e32 v87, 72, v84
	v_cmp_gt_u32_e64 s[78:79], s98, v87
	v_cndmask_b32_e64 v39, 0, v39, s[50:51]
	v_add_u32_e32 v88, 76, v84
	v_cmp_gt_u32_e64 s[50:51], s98, v88
	v_cndmask_b32_e64 v40, 0, v40, s[30:31]
	v_add_u32_e32 v85, 96, v84
	v_cmp_gt_u32_e64 s[30:31], s98, v85
	v_cndmask_b32_e64 v41, 0, v41, s[36:37]
	v_add_u32_e32 v86, 100, v84
	v_cmp_gt_u32_e64 s[36:37], s98, v86
	v_cndmask_b32_e64 v42, 0, v42, s[78:79]
	v_add_u32_e32 v87, 104, v84
	v_cmp_gt_u32_e64 s[78:79], s98, v87
	v_cndmask_b32_e64 v43, 0, v43, s[50:51]
	v_add_u32_e32 v88, 108, v84
	v_cmp_gt_u32_e64 s[50:51], s98, v88
	v_nop
	v_cndmask_b32_e64 v44, 0, v44, s[30:31]
	v_cndmask_b32_e64 v45, 0, v45, s[36:37]
	v_cndmask_b32_e64 v46, 0, v46, s[78:79]
	v_cndmask_b32_e64 v47, 0, v47, s[50:51]
	v_cvt_pk_bf16_f32 v64, v32, v33
	v_cvt_pk_bf16_f32 v65, v34, v35
	v_cvt_pk_bf16_f32 v66, v36, v37
	v_cvt_pk_bf16_f32 v67, v38, v39
	v_cvt_pk_bf16_f32 v68, v40, v41
	v_cvt_pk_bf16_f32 v69, v42, v43
	v_cvt_pk_bf16_f32 v70, v44, v45
	v_cvt_pk_bf16_f32 v71, v46, v47
	v_pk_add_f32 v[232:233], v[232:233], v[32:33]
	v_pk_add_f32 v[232:233], v[232:233], v[34:35]
	v_pk_add_f32 v[232:233], v[232:233], v[36:37]
	v_pk_add_f32 v[232:233], v[232:233], v[38:39]
	v_pk_add_f32 v[232:233], v[232:233], v[40:41]
	v_pk_add_f32 v[232:233], v[232:233], v[42:43]
	v_pk_add_f32 v[232:233], v[232:233], v[44:45]
	v_pk_add_f32 v[232:233], v[232:233], v[46:47]
	s_waitcnt lgkmcnt(12)
	v_mfma_f32_32x32x16_bf16 v[0:15], v[64:67], v[72:75], v[0:15]
	v_mfma_f32_32x32x16_bf16 v[16:31], v[64:67], v[76:79], v[16:31]
	v_mfma_f32_32x32x16_bf16 v[0:15], v[68:71], v[220:223], v[0:15]
	v_mfma_f32_32x32x16_bf16 v[16:31], v[68:71], v[224:227], v[16:31]
	s_add_i32 s90, s76, 384
	v_add_u32_e32 v80, s90, v239
	v_add_u32_e32 v83, s90, v240
	v_add_u32_e32 v99, s90, v241
	v_add_u32_e32 v253, s90, v242
	v_add_u32_e32 v254, s90, v101
	v_add_u32_e32 v255, s90, v150
	v_med3_i32 v80, v80, 0, s99
	v_med3_i32 v83, v83, 0, s99
	v_med3_i32 v99, v99, 0, s99
	v_med3_i32 v253, v253, 0, s99
	v_med3_i32 v254, v254, 0, s99
	v_med3_i32 v255, v255, 0, s99
	v_mad_u32_u24 v80, v80, s100, v252
	v_mad_u32_u24 v83, v83, s100, v252
	v_mad_u32_u24 v99, v99, s100, v252
	v_mad_u32_u24 v253, v253, s100, v252
	v_mad_u32_u24 v254, v254, s100, v153
	v_mad_u32_u24 v255, v255, s100, v153
	global_load_dwordx4 v[156:159], v80, s[82:83]
	global_load_dwordx4 v[160:163], v83, s[82:83]
	global_load_dwordx4 v[164:167], v99, s[82:83]
	global_load_dwordx4 v[168:171], v253, s[82:83]
	global_load_dwordx4 v[172:175], v254, s[82:83] offset:768
	global_load_dwordx4 v[176:179], v255, s[82:83] offset:768
	global_load_dwordx4 v[180:183], v254, s[82:83] offset:832
	global_load_dwordx4 v[184:187], v255, s[82:83] offset:832
	ds_read2_b32 v[32:33], v115 offset0:96 offset1:97
	ds_read2_b32 v[34:35], v115 offset0:98 offset1:99
	ds_read2_b32 v[36:37], v115 offset0:104 offset1:105
	ds_read2_b32 v[38:39], v115 offset0:106 offset1:107
	ds_read2_b32 v[40:41], v115 offset0:112 offset1:113
	ds_read2_b32 v[42:43], v115 offset0:114 offset1:115
	ds_read2_b32 v[44:45], v115 offset0:120 offset1:121
	ds_read2_b32 v[46:47], v115 offset0:122 offset1:123
	s_waitcnt lgkmcnt(0)
	v_mfma_f32_32x32x16_bf16 v[32:47], v[188:191], v[48:51], v[32:47]
	ds_read_b64_tr_b16 v[72:73], v231
	ds_read_b64_tr_b16 v[74:75], v231 offset:512
	ds_read_b64_tr_b16 v[76:77], v231 offset:2048
	ds_read_b64_tr_b16 v[78:79], v231 offset:2560
	ds_read_b64_tr_b16 v[220:221], v231 offset:1024
	ds_read_b64_tr_b16 v[222:223], v231 offset:1536
	ds_read_b64_tr_b16 v[224:225], v231 offset:3072
	ds_read_b64_tr_b16 v[226:227], v231 offset:3584
	s_waitcnt vmcnt(8)
	ds_write_b128 v247, v[116:119]
	ds_write_b128 v247, v[120:123] offset:1024
	ds_write_b128 v247, v[124:127] offset:2048
	ds_write_b128 v247, v[128:131] offset:3072
	ds_read_b128 v[116:119], v248
	ds_read_b128 v[120:123], v249
	ds_read_b128 v[124:127], v250
	ds_read_b128 v[128:131], v251
	ds_write_b128 v112, v[132:135]
	ds_write_b128 v112, v[136:139] offset:1024
	ds_write_b128 v112, v[140:143] offset:2048
	ds_write_b128 v112, v[144:147] offset:3072
	v_mfma_f32_32x32x16_bf16 v[32:47], v[192:195], v[52:55], v[32:47]
	v_mfma_f32_32x32x16_bf16 v[32:47], v[196:199], v[56:59], v[32:47]
	v_mfma_f32_32x32x16_bf16 v[32:47], v[200:203], v[60:63], v[32:47]
	s_nop 11
	v_exp_f32_e32 v32, v32
	v_exp_f32_e32 v33, v33
	v_exp_f32_e32 v34, v34
	v_exp_f32_e32 v35, v35
	v_exp_f32_e32 v36, v36
	v_exp_f32_e32 v37, v37
	v_exp_f32_e32 v38, v38
	v_exp_f32_e32 v39, v39
	v_exp_f32_e32 v40, v40
	v_exp_f32_e32 v41, v41
	v_exp_f32_e32 v42, v42
	v_exp_f32_e32 v43, v43
	v_exp_f32_e32 v44, v44
	v_exp_f32_e32 v45, v45
	v_exp_f32_e32 v46, v46
	v_exp_f32_e32 v47, v47
	s_add_i32 s90, s76, 128
	v_lshlrev_b32_e32 v84, 2, v107
	v_add_u32_e32 v84, s90, v84
	v_add_u32_e32 v85, 0, v84
	v_add_u32_e32 v86, 4, v84
	v_add_u32_e32 v87, 8, v84
	v_add_u32_e32 v88, 12, v84
	v_cmp_gt_u32_e64 s[30:31], s98, v85
	v_cmp_gt_u32_e64 s[36:37], s98, v86
	v_cmp_gt_u32_e64 s[78:79], s98, v87
	v_cmp_gt_u32_e64 s[50:51], s98, v88
	v_cndmask_b32_e64 v32, 0, v32, s[30:31]
	v_add_u32_e32 v85, 32, v84
	v_cmp_gt_u32_e64 s[30:31], s98, v85
	v_cndmask_b32_e64 v33, 0, v33, s[36:37]
	v_add_u32_e32 v86, 36, v84
	v_cmp_gt_u32_e64 s[36:37], s98, v86
	v_cndmask_b32_e64 v34, 0, v34, s[78:79]
	v_add_u32_e32 v87, 40, v84
	v_cmp_gt_u32_e64 s[78:79], s98, v87
	v_cndmask_b32_e64 v35, 0, v35, s[50:51]
	v_add_u32_e32 v88, 44, v84
	v_cmp_gt_u32_e64 s[50:51], s98, v88
	v_cndmask_b32_e64 v36, 0, v36, s[30:31]
	v_add_u32_e32 v85, 64, v84
	v_cmp_gt_u32_e64 s[30:31], s98, v85
	v_cndmask_b32_e64 v37, 0, v37, s[36:37]
	v_add_u32_e32 v86, 68, v84
	v_cmp_gt_u32_e64 s[36:37], s98, v86
	v_cndmask_b32_e64 v38, 0, v38, s[78:79]
	v_add_u32_e32 v87, 72, v84
	v_cmp_gt_u32_e64 s[78:79], s98, v87
	v_cndmask_b32_e64 v39, 0, v39, s[50:51]
	v_add_u32_e32 v88, 76, v84
	v_cmp_gt_u32_e64 s[50:51], s98, v88
	v_cndmask_b32_e64 v40, 0, v40, s[30:31]
	v_add_u32_e32 v85, 96, v84
	v_cmp_gt_u32_e64 s[30:31], s98, v85
	v_cndmask_b32_e64 v41, 0, v41, s[36:37]
	v_add_u32_e32 v86, 100, v84
	v_cmp_gt_u32_e64 s[36:37], s98, v86
	v_cndmask_b32_e64 v42, 0, v42, s[78:79]
	v_add_u32_e32 v87, 104, v84
	v_cmp_gt_u32_e64 s[78:79], s98, v87
	v_cndmask_b32_e64 v43, 0, v43, s[50:51]
	v_add_u32_e32 v88, 108, v84
	v_cmp_gt_u32_e64 s[50:51], s98, v88
	v_nop
	v_cndmask_b32_e64 v44, 0, v44, s[30:31]
	v_cndmask_b32_e64 v45, 0, v45, s[36:37]
	v_cndmask_b32_e64 v46, 0, v46, s[78:79]
	v_cndmask_b32_e64 v47, 0, v47, s[50:51]
	v_cvt_pk_bf16_f32 v64, v32, v33
	v_cvt_pk_bf16_f32 v65, v34, v35
	v_cvt_pk_bf16_f32 v66, v36, v37
	v_cvt_pk_bf16_f32 v67, v38, v39
	v_cvt_pk_bf16_f32 v68, v40, v41
	v_cvt_pk_bf16_f32 v69, v42, v43
	v_cvt_pk_bf16_f32 v70, v44, v45
	v_cvt_pk_bf16_f32 v71, v46, v47
	v_pk_add_f32 v[232:233], v[232:233], v[32:33]
	v_pk_add_f32 v[232:233], v[232:233], v[34:35]
	v_pk_add_f32 v[232:233], v[232:233], v[36:37]
	v_pk_add_f32 v[232:233], v[232:233], v[38:39]
	v_pk_add_f32 v[232:233], v[232:233], v[40:41]
	v_pk_add_f32 v[232:233], v[232:233], v[42:43]
	v_pk_add_f32 v[232:233], v[232:233], v[44:45]
	v_pk_add_f32 v[232:233], v[232:233], v[46:47]
	s_waitcnt lgkmcnt(12)
	v_mfma_f32_32x32x16_bf16 v[0:15], v[64:67], v[72:75], v[0:15]
	v_mfma_f32_32x32x16_bf16 v[16:31], v[64:67], v[76:79], v[16:31]
	v_mfma_f32_32x32x16_bf16 v[0:15], v[68:71], v[220:223], v[0:15]
	v_mfma_f32_32x32x16_bf16 v[16:31], v[68:71], v[224:227], v[16:31]
	s_add_i32 s90, s76, 512
	v_add_u32_e32 v80, s90, v239
	v_add_u32_e32 v83, s90, v240
	v_add_u32_e32 v99, s90, v241
	v_add_u32_e32 v253, s90, v242
	v_add_u32_e32 v254, s90, v101
	v_add_u32_e32 v255, s90, v150
	v_med3_i32 v80, v80, 0, s99
	v_med3_i32 v83, v83, 0, s99
	v_med3_i32 v99, v99, 0, s99
	v_med3_i32 v253, v253, 0, s99
	v_med3_i32 v254, v254, 0, s99
	v_med3_i32 v255, v255, 0, s99
	v_mad_u32_u24 v80, v80, s100, v252
	v_mad_u32_u24 v83, v83, s100, v252
	v_mad_u32_u24 v99, v99, s100, v252
	v_mad_u32_u24 v253, v253, s100, v252
	v_mad_u32_u24 v254, v254, s100, v153
	v_mad_u32_u24 v255, v255, s100, v153
	global_load_dwordx4 v[188:191], v80, s[82:83]
	global_load_dwordx4 v[192:195], v83, s[82:83]
	global_load_dwordx4 v[196:199], v99, s[82:83]
	global_load_dwordx4 v[200:203], v253, s[82:83]
	global_load_dwordx4 v[204:207], v254, s[82:83] offset:768
	global_load_dwordx4 v[208:211], v255, s[82:83] offset:768
	global_load_dwordx4 v[212:215], v254, s[82:83] offset:832
	global_load_dwordx4 v[216:219], v255, s[82:83] offset:832
	ds_read2_b32 v[32:33], v115 offset0:128 offset1:129
	ds_read2_b32 v[34:35], v115 offset0:130 offset1:131
	ds_read2_b32 v[36:37], v115 offset0:136 offset1:137
	ds_read2_b32 v[38:39], v115 offset0:138 offset1:139
	ds_read2_b32 v[40:41], v115 offset0:144 offset1:145
	ds_read2_b32 v[42:43], v115 offset0:146 offset1:147
	ds_read2_b32 v[44:45], v115 offset0:152 offset1:153
	ds_read2_b32 v[46:47], v115 offset0:154 offset1:155
	s_waitcnt lgkmcnt(0)
	v_mfma_f32_32x32x16_bf16 v[32:47], v[116:119], v[48:51], v[32:47]
	ds_read_b64_tr_b16 v[72:73], v231
	ds_read_b64_tr_b16 v[74:75], v231 offset:512
	ds_read_b64_tr_b16 v[76:77], v231 offset:2048
	ds_read_b64_tr_b16 v[78:79], v231 offset:2560
	ds_read_b64_tr_b16 v[220:221], v231 offset:1024
	ds_read_b64_tr_b16 v[222:223], v231 offset:1536
	ds_read_b64_tr_b16 v[224:225], v231 offset:3072
	ds_read_b64_tr_b16 v[226:227], v231 offset:3584
	s_waitcnt vmcnt(8)
	ds_write_b128 v247, v[156:159]
	ds_write_b128 v247, v[160:163] offset:1024
	ds_write_b128 v247, v[164:167] offset:2048
	ds_write_b128 v247, v[168:171] offset:3072
	ds_read_b128 v[156:159], v248
	ds_read_b128 v[160:163], v249
	ds_read_b128 v[164:167], v250
	ds_read_b128 v[168:171], v251
	ds_write_b128 v112, v[172:175]
	ds_write_b128 v112, v[176:179] offset:1024
	ds_write_b128 v112, v[180:183] offset:2048
	ds_write_b128 v112, v[184:187] offset:3072
	v_mfma_f32_32x32x16_bf16 v[32:47], v[120:123], v[52:55], v[32:47]
	v_mfma_f32_32x32x16_bf16 v[32:47], v[124:127], v[56:59], v[32:47]
	v_mfma_f32_32x32x16_bf16 v[32:47], v[128:131], v[60:63], v[32:47]
	s_nop 11
	v_exp_f32_e32 v32, v32
	v_exp_f32_e32 v33, v33
	v_exp_f32_e32 v34, v34
	v_exp_f32_e32 v35, v35
	v_exp_f32_e32 v36, v36
	v_exp_f32_e32 v37, v37
	v_exp_f32_e32 v38, v38
	v_exp_f32_e32 v39, v39
	v_exp_f32_e32 v40, v40
	v_exp_f32_e32 v41, v41
	v_exp_f32_e32 v42, v42
	v_exp_f32_e32 v43, v43
	v_exp_f32_e32 v44, v44
	v_exp_f32_e32 v45, v45
	v_exp_f32_e32 v46, v46
	v_exp_f32_e32 v47, v47
	s_add_i32 s90, s76, 256
	v_lshlrev_b32_e32 v84, 2, v107
	v_add_u32_e32 v84, s90, v84
	v_add_u32_e32 v85, 0, v84
	v_add_u32_e32 v86, 4, v84
	v_add_u32_e32 v87, 8, v84
	v_add_u32_e32 v88, 12, v84
	v_cmp_gt_u32_e64 s[30:31], s98, v85
	v_cmp_gt_u32_e64 s[36:37], s98, v86
	v_cmp_gt_u32_e64 s[78:79], s98, v87
	v_cmp_gt_u32_e64 s[50:51], s98, v88
	v_cndmask_b32_e64 v32, 0, v32, s[30:31]
	v_add_u32_e32 v85, 32, v84
	v_cmp_gt_u32_e64 s[30:31], s98, v85
	v_cndmask_b32_e64 v33, 0, v33, s[36:37]
	v_add_u32_e32 v86, 36, v84
	v_cmp_gt_u32_e64 s[36:37], s98, v86
	v_cndmask_b32_e64 v34, 0, v34, s[78:79]
	v_add_u32_e32 v87, 40, v84
	v_cmp_gt_u32_e64 s[78:79], s98, v87
	v_cndmask_b32_e64 v35, 0, v35, s[50:51]
	v_add_u32_e32 v88, 44, v84
	v_cmp_gt_u32_e64 s[50:51], s98, v88
	v_cndmask_b32_e64 v36, 0, v36, s[30:31]
	v_add_u32_e32 v85, 64, v84
	v_cmp_gt_u32_e64 s[30:31], s98, v85
	v_cndmask_b32_e64 v37, 0, v37, s[36:37]
	v_add_u32_e32 v86, 68, v84
	v_cmp_gt_u32_e64 s[36:37], s98, v86
	v_cndmask_b32_e64 v38, 0, v38, s[78:79]
	v_add_u32_e32 v87, 72, v84
	v_cmp_gt_u32_e64 s[78:79], s98, v87
	v_cndmask_b32_e64 v39, 0, v39, s[50:51]
	v_add_u32_e32 v88, 76, v84
	v_cmp_gt_u32_e64 s[50:51], s98, v88
	v_cndmask_b32_e64 v40, 0, v40, s[30:31]
	v_add_u32_e32 v85, 96, v84
	v_cmp_gt_u32_e64 s[30:31], s98, v85
	v_cndmask_b32_e64 v41, 0, v41, s[36:37]
	v_add_u32_e32 v86, 100, v84
	v_cmp_gt_u32_e64 s[36:37], s98, v86
	v_cndmask_b32_e64 v42, 0, v42, s[78:79]
	v_add_u32_e32 v87, 104, v84
	v_cmp_gt_u32_e64 s[78:79], s98, v87
	v_cndmask_b32_e64 v43, 0, v43, s[50:51]
	v_add_u32_e32 v88, 108, v84
	v_cmp_gt_u32_e64 s[50:51], s98, v88
	v_nop
	v_cndmask_b32_e64 v44, 0, v44, s[30:31]
	v_cndmask_b32_e64 v45, 0, v45, s[36:37]
	v_cndmask_b32_e64 v46, 0, v46, s[78:79]
	v_cndmask_b32_e64 v47, 0, v47, s[50:51]
	v_cvt_pk_bf16_f32 v64, v32, v33
	v_cvt_pk_bf16_f32 v65, v34, v35
	v_cvt_pk_bf16_f32 v66, v36, v37
	v_cvt_pk_bf16_f32 v67, v38, v39
	v_cvt_pk_bf16_f32 v68, v40, v41
	v_cvt_pk_bf16_f32 v69, v42, v43
	v_cvt_pk_bf16_f32 v70, v44, v45
	v_cvt_pk_bf16_f32 v71, v46, v47
	v_pk_add_f32 v[232:233], v[232:233], v[32:33]
	v_pk_add_f32 v[232:233], v[232:233], v[34:35]
	v_pk_add_f32 v[232:233], v[232:233], v[36:37]
	v_pk_add_f32 v[232:233], v[232:233], v[38:39]
	v_pk_add_f32 v[232:233], v[232:233], v[40:41]
	v_pk_add_f32 v[232:233], v[232:233], v[42:43]
	v_pk_add_f32 v[232:233], v[232:233], v[44:45]
	v_pk_add_f32 v[232:233], v[232:233], v[46:47]
	s_waitcnt lgkmcnt(12)
	v_mfma_f32_32x32x16_bf16 v[0:15], v[64:67], v[72:75], v[0:15]
	v_mfma_f32_32x32x16_bf16 v[16:31], v[64:67], v[76:79], v[16:31]
	v_mfma_f32_32x32x16_bf16 v[0:15], v[68:71], v[220:223], v[0:15]
	v_mfma_f32_32x32x16_bf16 v[16:31], v[68:71], v[224:227], v[16:31]
	s_add_i32 s90, s76, 640
	v_add_u32_e32 v80, s90, v239
	v_add_u32_e32 v83, s90, v240
	v_add_u32_e32 v99, s90, v241
	v_add_u32_e32 v253, s90, v242
	v_add_u32_e32 v254, s90, v101
	v_add_u32_e32 v255, s90, v150
	v_med3_i32 v80, v80, 0, s99
	v_med3_i32 v83, v83, 0, s99
	v_med3_i32 v99, v99, 0, s99
	v_med3_i32 v253, v253, 0, s99
	v_med3_i32 v254, v254, 0, s99
	v_med3_i32 v255, v255, 0, s99
	v_mad_u32_u24 v80, v80, s100, v252
	v_mad_u32_u24 v83, v83, s100, v252
	v_mad_u32_u24 v99, v99, s100, v252
	v_mad_u32_u24 v253, v253, s100, v252
	v_mad_u32_u24 v254, v254, s100, v153
	v_mad_u32_u24 v255, v255, s100, v153
	global_load_dwordx4 v[116:119], v80, s[82:83]
	global_load_dwordx4 v[120:123], v83, s[82:83]
	global_load_dwordx4 v[124:127], v99, s[82:83]
	global_load_dwordx4 v[128:131], v253, s[82:83]
	global_load_dwordx4 v[132:135], v254, s[82:83] offset:768
	global_load_dwordx4 v[136:139], v255, s[82:83] offset:768
	global_load_dwordx4 v[140:143], v254, s[82:83] offset:832
	global_load_dwordx4 v[144:147], v255, s[82:83] offset:832
	ds_read2_b32 v[32:33], v115 offset0:160 offset1:161
	ds_read2_b32 v[34:35], v115 offset0:162 offset1:163
	ds_read2_b32 v[36:37], v115 offset0:168 offset1:169
	ds_read2_b32 v[38:39], v115 offset0:170 offset1:171
	ds_read2_b32 v[40:41], v115 offset0:176 offset1:177
	ds_read2_b32 v[42:43], v115 offset0:178 offset1:179
	ds_read2_b32 v[44:45], v115 offset0:184 offset1:185
	ds_read2_b32 v[46:47], v115 offset0:186 offset1:187
	s_waitcnt lgkmcnt(0)
	v_mfma_f32_32x32x16_bf16 v[32:47], v[156:159], v[48:51], v[32:47]
	ds_read_b64_tr_b16 v[72:73], v231
	ds_read_b64_tr_b16 v[74:75], v231 offset:512
	ds_read_b64_tr_b16 v[76:77], v231 offset:2048
	ds_read_b64_tr_b16 v[78:79], v231 offset:2560
	ds_read_b64_tr_b16 v[220:221], v231 offset:1024
	ds_read_b64_tr_b16 v[222:223], v231 offset:1536
	ds_read_b64_tr_b16 v[224:225], v231 offset:3072
	ds_read_b64_tr_b16 v[226:227], v231 offset:3584
	s_waitcnt vmcnt(8)
	ds_write_b128 v247, v[188:191]
	ds_write_b128 v247, v[192:195] offset:1024
	ds_write_b128 v247, v[196:199] offset:2048
	ds_write_b128 v247, v[200:203] offset:3072
	ds_read_b128 v[188:191], v248
	ds_read_b128 v[192:195], v249
	ds_read_b128 v[196:199], v250
	ds_read_b128 v[200:203], v251
	ds_write_b128 v112, v[204:207]
	ds_write_b128 v112, v[208:211] offset:1024
	ds_write_b128 v112, v[212:215] offset:2048
	ds_write_b128 v112, v[216:219] offset:3072
	v_mfma_f32_32x32x16_bf16 v[32:47], v[160:163], v[52:55], v[32:47]
	v_mfma_f32_32x32x16_bf16 v[32:47], v[164:167], v[56:59], v[32:47]
	v_mfma_f32_32x32x16_bf16 v[32:47], v[168:171], v[60:63], v[32:47]
	s_nop 11
	v_exp_f32_e32 v32, v32
	v_exp_f32_e32 v33, v33
	v_exp_f32_e32 v34, v34
	v_exp_f32_e32 v35, v35
	v_exp_f32_e32 v36, v36
	v_exp_f32_e32 v37, v37
	v_exp_f32_e32 v38, v38
	v_exp_f32_e32 v39, v39
	v_exp_f32_e32 v40, v40
	v_exp_f32_e32 v41, v41
	v_exp_f32_e32 v42, v42
	v_exp_f32_e32 v43, v43
	v_exp_f32_e32 v44, v44
	v_exp_f32_e32 v45, v45
	v_exp_f32_e32 v46, v46
	v_exp_f32_e32 v47, v47
	s_add_i32 s90, s76, 384
	v_lshlrev_b32_e32 v84, 2, v107
	v_add_u32_e32 v84, s90, v84
	v_add_u32_e32 v85, 0, v84
	v_add_u32_e32 v86, 4, v84
	v_add_u32_e32 v87, 8, v84
	v_add_u32_e32 v88, 12, v84
	v_cmp_gt_u32_e64 s[30:31], s98, v85
	v_cmp_gt_u32_e64 s[36:37], s98, v86
	v_cmp_gt_u32_e64 s[78:79], s98, v87
	v_cmp_gt_u32_e64 s[50:51], s98, v88
	v_cndmask_b32_e64 v32, 0, v32, s[30:31]
	v_add_u32_e32 v85, 32, v84
	v_cmp_gt_u32_e64 s[30:31], s98, v85
	v_cndmask_b32_e64 v33, 0, v33, s[36:37]
	v_add_u32_e32 v86, 36, v84
	v_cmp_gt_u32_e64 s[36:37], s98, v86
	v_cndmask_b32_e64 v34, 0, v34, s[78:79]
	v_add_u32_e32 v87, 40, v84
	v_cmp_gt_u32_e64 s[78:79], s98, v87
	v_cndmask_b32_e64 v35, 0, v35, s[50:51]
	v_add_u32_e32 v88, 44, v84
	v_cmp_gt_u32_e64 s[50:51], s98, v88
	v_cndmask_b32_e64 v36, 0, v36, s[30:31]
	v_add_u32_e32 v85, 64, v84
	v_cmp_gt_u32_e64 s[30:31], s98, v85
	v_cndmask_b32_e64 v37, 0, v37, s[36:37]
	v_add_u32_e32 v86, 68, v84
	v_cmp_gt_u32_e64 s[36:37], s98, v86
	v_cndmask_b32_e64 v38, 0, v38, s[78:79]
	v_add_u32_e32 v87, 72, v84
	v_cmp_gt_u32_e64 s[78:79], s98, v87
	v_cndmask_b32_e64 v39, 0, v39, s[50:51]
	v_add_u32_e32 v88, 76, v84
	v_cmp_gt_u32_e64 s[50:51], s98, v88
	v_cndmask_b32_e64 v40, 0, v40, s[30:31]
	v_add_u32_e32 v85, 96, v84
	v_cmp_gt_u32_e64 s[30:31], s98, v85
	v_cndmask_b32_e64 v41, 0, v41, s[36:37]
	v_add_u32_e32 v86, 100, v84
	v_cmp_gt_u32_e64 s[36:37], s98, v86
	v_cndmask_b32_e64 v42, 0, v42, s[78:79]
	v_add_u32_e32 v87, 104, v84
	v_cmp_gt_u32_e64 s[78:79], s98, v87
	v_cndmask_b32_e64 v43, 0, v43, s[50:51]
	v_add_u32_e32 v88, 108, v84
	v_cmp_gt_u32_e64 s[50:51], s98, v88
	v_nop
	v_cndmask_b32_e64 v44, 0, v44, s[30:31]
	v_cndmask_b32_e64 v45, 0, v45, s[36:37]
	v_cndmask_b32_e64 v46, 0, v46, s[78:79]
	v_cndmask_b32_e64 v47, 0, v47, s[50:51]
	v_cvt_pk_bf16_f32 v64, v32, v33
	v_cvt_pk_bf16_f32 v65, v34, v35
	v_cvt_pk_bf16_f32 v66, v36, v37
	v_cvt_pk_bf16_f32 v67, v38, v39
	v_cvt_pk_bf16_f32 v68, v40, v41
	v_cvt_pk_bf16_f32 v69, v42, v43
	v_cvt_pk_bf16_f32 v70, v44, v45
	v_cvt_pk_bf16_f32 v71, v46, v47
	v_pk_add_f32 v[232:233], v[232:233], v[32:33]
	v_pk_add_f32 v[232:233], v[232:233], v[34:35]
	v_pk_add_f32 v[232:233], v[232:233], v[36:37]
	v_pk_add_f32 v[232:233], v[232:233], v[38:39]
	v_pk_add_f32 v[232:233], v[232:233], v[40:41]
	v_pk_add_f32 v[232:233], v[232:233], v[42:43]
	v_pk_add_f32 v[232:233], v[232:233], v[44:45]
	v_pk_add_f32 v[232:233], v[232:233], v[46:47]
	s_waitcnt lgkmcnt(12)
	v_mfma_f32_32x32x16_bf16 v[0:15], v[64:67], v[72:75], v[0:15]
	v_mfma_f32_32x32x16_bf16 v[16:31], v[64:67], v[76:79], v[16:31]
	v_mfma_f32_32x32x16_bf16 v[0:15], v[68:71], v[220:223], v[0:15]
	v_mfma_f32_32x32x16_bf16 v[16:31], v[68:71], v[224:227], v[16:31]
	s_add_i32 s90, s76, -1024
	v_add_u32_e32 v80, s90, v243
	v_add_u32_e32 v83, s90, v244
	v_add_u32_e32 v99, s90, v245
	v_add_u32_e32 v253, s90, v246
	v_add_u32_e32 v254, s90, v148
	v_add_u32_e32 v255, s90, v151
	v_med3_i32 v80, v80, 0, s99
	v_med3_i32 v83, v83, 0, s99
	v_med3_i32 v99, v99, 0, s99
	v_med3_i32 v253, v253, 0, s99
	v_med3_i32 v254, v254, 0, s99
	v_med3_i32 v255, v255, 0, s99
	v_mad_u32_u24 v80, v80, s100, v252
	v_mad_u32_u24 v83, v83, s100, v252
	v_mad_u32_u24 v99, v99, s100, v252
	v_mad_u32_u24 v253, v253, s100, v252
	v_mad_u32_u24 v254, v254, s100, v153
	v_mad_u32_u24 v255, v255, s100, v153
	global_load_dwordx4 v[156:159], v80, s[82:83]
	global_load_dwordx4 v[160:163], v83, s[82:83]
	global_load_dwordx4 v[164:167], v99, s[82:83]
	global_load_dwordx4 v[168:171], v253, s[82:83]
	global_load_dwordx4 v[172:175], v254, s[82:83] offset:768
	global_load_dwordx4 v[176:179], v255, s[82:83] offset:768
	global_load_dwordx4 v[180:183], v254, s[82:83] offset:832
	global_load_dwordx4 v[184:187], v255, s[82:83] offset:832
	ds_read2_b32 v[32:33], v115 offset0:192 offset1:193
	ds_read2_b32 v[34:35], v115 offset0:194 offset1:195
	ds_read2_b32 v[36:37], v115 offset0:200 offset1:201
	ds_read2_b32 v[38:39], v115 offset0:202 offset1:203
	ds_read2_b32 v[40:41], v115 offset0:208 offset1:209
	ds_read2_b32 v[42:43], v115 offset0:210 offset1:211
	ds_read2_b32 v[44:45], v115 offset0:216 offset1:217
	ds_read2_b32 v[46:47], v115 offset0:218 offset1:219
	s_waitcnt lgkmcnt(0)
	v_mfma_f32_32x32x16_bf16 v[32:47], v[188:191], v[48:51], v[32:47]
	ds_read_b64_tr_b16 v[72:73], v231
	ds_read_b64_tr_b16 v[74:75], v231 offset:512
	ds_read_b64_tr_b16 v[76:77], v231 offset:2048
	ds_read_b64_tr_b16 v[78:79], v231 offset:2560
	ds_read_b64_tr_b16 v[220:221], v231 offset:1024
	ds_read_b64_tr_b16 v[222:223], v231 offset:1536
	ds_read_b64_tr_b16 v[224:225], v231 offset:3072
	ds_read_b64_tr_b16 v[226:227], v231 offset:3584
	s_waitcnt vmcnt(8)
	ds_write_b128 v247, v[116:119]
	ds_write_b128 v247, v[120:123] offset:1024
	ds_write_b128 v247, v[124:127] offset:2048
	ds_write_b128 v247, v[128:131] offset:3072
	ds_read_b128 v[116:119], v248
	ds_read_b128 v[120:123], v249
	ds_read_b128 v[124:127], v250
	ds_read_b128 v[128:131], v251
	ds_write_b128 v112, v[132:135]
	ds_write_b128 v112, v[136:139] offset:1024
	ds_write_b128 v112, v[140:143] offset:2048
	ds_write_b128 v112, v[144:147] offset:3072
	v_mfma_f32_32x32x16_bf16 v[32:47], v[192:195], v[52:55], v[32:47]
	v_mfma_f32_32x32x16_bf16 v[32:47], v[196:199], v[56:59], v[32:47]
	v_mfma_f32_32x32x16_bf16 v[32:47], v[200:203], v[60:63], v[32:47]
	s_nop 11
	v_exp_f32_e32 v32, v32
	v_exp_f32_e32 v33, v33
	v_exp_f32_e32 v34, v34
	v_exp_f32_e32 v35, v35
	v_exp_f32_e32 v36, v36
	v_exp_f32_e32 v37, v37
	v_exp_f32_e32 v38, v38
	v_exp_f32_e32 v39, v39
	v_exp_f32_e32 v40, v40
	v_exp_f32_e32 v41, v41
	v_exp_f32_e32 v42, v42
	v_exp_f32_e32 v43, v43
	v_exp_f32_e32 v44, v44
	v_exp_f32_e32 v45, v45
	v_exp_f32_e32 v46, v46
	v_exp_f32_e32 v47, v47
	s_add_i32 s90, s76, 512
	v_lshlrev_b32_e32 v84, 2, v107
	v_add_u32_e32 v84, s90, v84
	v_add_u32_e32 v85, 0, v84
	v_add_u32_e32 v86, 4, v84
	v_add_u32_e32 v87, 8, v84
	v_add_u32_e32 v88, 12, v84
	v_cmp_gt_u32_e64 s[30:31], s98, v85
	v_cmp_gt_u32_e64 s[36:37], s98, v86
	v_cmp_gt_u32_e64 s[78:79], s98, v87
	v_cmp_gt_u32_e64 s[50:51], s98, v88
	v_cndmask_b32_e64 v32, 0, v32, s[30:31]
	v_add_u32_e32 v85, 32, v84
	v_cmp_gt_u32_e64 s[30:31], s98, v85
	v_cndmask_b32_e64 v33, 0, v33, s[36:37]
	v_add_u32_e32 v86, 36, v84
	v_cmp_gt_u32_e64 s[36:37], s98, v86
	v_cndmask_b32_e64 v34, 0, v34, s[78:79]
	v_add_u32_e32 v87, 40, v84
	v_cmp_gt_u32_e64 s[78:79], s98, v87
	v_cndmask_b32_e64 v35, 0, v35, s[50:51]
	v_add_u32_e32 v88, 44, v84
	v_cmp_gt_u32_e64 s[50:51], s98, v88
	v_cndmask_b32_e64 v36, 0, v36, s[30:31]
	v_add_u32_e32 v85, 64, v84
	v_cmp_gt_u32_e64 s[30:31], s98, v85
	v_cndmask_b32_e64 v37, 0, v37, s[36:37]
	v_add_u32_e32 v86, 68, v84
	v_cmp_gt_u32_e64 s[36:37], s98, v86
	v_cndmask_b32_e64 v38, 0, v38, s[78:79]
	v_add_u32_e32 v87, 72, v84
	v_cmp_gt_u32_e64 s[78:79], s98, v87
	v_cndmask_b32_e64 v39, 0, v39, s[50:51]
	v_add_u32_e32 v88, 76, v84
	v_cmp_gt_u32_e64 s[50:51], s98, v88
	v_cndmask_b32_e64 v40, 0, v40, s[30:31]
	v_add_u32_e32 v85, 96, v84
	v_cmp_gt_u32_e64 s[30:31], s98, v85
	v_cndmask_b32_e64 v41, 0, v41, s[36:37]
	v_add_u32_e32 v86, 100, v84
	v_cmp_gt_u32_e64 s[36:37], s98, v86
	v_cndmask_b32_e64 v42, 0, v42, s[78:79]
	v_add_u32_e32 v87, 104, v84
	v_cmp_gt_u32_e64 s[78:79], s98, v87
	v_cndmask_b32_e64 v43, 0, v43, s[50:51]
	v_add_u32_e32 v88, 108, v84
	v_cmp_gt_u32_e64 s[50:51], s98, v88
	v_nop
	v_cndmask_b32_e64 v44, 0, v44, s[30:31]
	v_cndmask_b32_e64 v45, 0, v45, s[36:37]
	v_cndmask_b32_e64 v46, 0, v46, s[78:79]
	v_cndmask_b32_e64 v47, 0, v47, s[50:51]
	v_cvt_pk_bf16_f32 v64, v32, v33
	v_cvt_pk_bf16_f32 v65, v34, v35
	v_cvt_pk_bf16_f32 v66, v36, v37
	v_cvt_pk_bf16_f32 v67, v38, v39
	v_cvt_pk_bf16_f32 v68, v40, v41
	v_cvt_pk_bf16_f32 v69, v42, v43
	v_cvt_pk_bf16_f32 v70, v44, v45
	v_cvt_pk_bf16_f32 v71, v46, v47
	v_pk_add_f32 v[232:233], v[232:233], v[32:33]
	v_pk_add_f32 v[232:233], v[232:233], v[34:35]
	v_pk_add_f32 v[232:233], v[232:233], v[36:37]
	v_pk_add_f32 v[232:233], v[232:233], v[38:39]
	v_pk_add_f32 v[232:233], v[232:233], v[40:41]
	v_pk_add_f32 v[232:233], v[232:233], v[42:43]
	v_pk_add_f32 v[232:233], v[232:233], v[44:45]
	v_pk_add_f32 v[232:233], v[232:233], v[46:47]
	s_waitcnt lgkmcnt(12)
	v_mfma_f32_32x32x16_bf16 v[0:15], v[64:67], v[72:75], v[0:15]
	v_mfma_f32_32x32x16_bf16 v[16:31], v[64:67], v[76:79], v[16:31]
	v_mfma_f32_32x32x16_bf16 v[0:15], v[68:71], v[220:223], v[0:15]
	v_mfma_f32_32x32x16_bf16 v[16:31], v[68:71], v[224:227], v[16:31]
	s_add_i32 s90, s76, -512
	v_add_u32_e32 v80, s90, v243
	v_add_u32_e32 v83, s90, v244
	v_add_u32_e32 v99, s90, v245
	v_add_u32_e32 v253, s90, v246
	v_add_u32_e32 v254, s90, v148
	v_add_u32_e32 v255, s90, v151
	v_med3_i32 v80, v80, 0, s99
	v_med3_i32 v83, v83, 0, s99
	v_med3_i32 v99, v99, 0, s99
	v_med3_i32 v253, v253, 0, s99
	v_med3_i32 v254, v254, 0, s99
	v_med3_i32 v255, v255, 0, s99
	v_mad_u32_u24 v80, v80, s100, v252
	v_mad_u32_u24 v83, v83, s100, v252
	v_mad_u32_u24 v99, v99, s100, v252
	v_mad_u32_u24 v253, v253, s100, v252
	v_mad_u32_u24 v254, v254, s100, v153
	v_mad_u32_u24 v255, v255, s100, v153
	global_load_dwordx4 v[188:191], v80, s[82:83]
	global_load_dwordx4 v[192:195], v83, s[82:83]
	global_load_dwordx4 v[196:199], v99, s[82:83]
	global_load_dwordx4 v[200:203], v253, s[82:83]
	global_load_dwordx4 v[204:207], v254, s[82:83] offset:768
	global_load_dwordx4 v[208:211], v255, s[82:83] offset:768
	global_load_dwordx4 v[212:215], v254, s[82:83] offset:832
	global_load_dwordx4 v[216:219], v255, s[82:83] offset:832
	ds_read2_b32 v[32:33], v115 offset0:224 offset1:225
	ds_read2_b32 v[34:35], v115 offset0:226 offset1:227
	ds_read2_b32 v[36:37], v115 offset0:232 offset1:233
	ds_read2_b32 v[38:39], v115 offset0:234 offset1:235
	ds_read2_b32 v[40:41], v115 offset0:240 offset1:241
	ds_read2_b32 v[42:43], v115 offset0:242 offset1:243
	ds_read2_b32 v[44:45], v115 offset0:248 offset1:249
	ds_read2_b32 v[46:47], v115 offset0:250 offset1:251
	s_waitcnt lgkmcnt(0)
	v_mfma_f32_32x32x16_bf16 v[32:47], v[116:119], v[48:51], v[32:47]
	ds_read_b64_tr_b16 v[72:73], v231
	ds_read_b64_tr_b16 v[74:75], v231 offset:512
	ds_read_b64_tr_b16 v[76:77], v231 offset:2048
	ds_read_b64_tr_b16 v[78:79], v231 offset:2560
	ds_read_b64_tr_b16 v[220:221], v231 offset:1024
	ds_read_b64_tr_b16 v[222:223], v231 offset:1536
	ds_read_b64_tr_b16 v[224:225], v231 offset:3072
	ds_read_b64_tr_b16 v[226:227], v231 offset:3584
	s_waitcnt vmcnt(8)
	ds_write_b128 v247, v[156:159]
	ds_write_b128 v247, v[160:163] offset:1024
	ds_write_b128 v247, v[164:167] offset:2048
	ds_write_b128 v247, v[168:171] offset:3072
	ds_read_b128 v[156:159], v248
	ds_read_b128 v[160:163], v249
	ds_read_b128 v[164:167], v250
	ds_read_b128 v[168:171], v251
	ds_write_b128 v112, v[172:175]
	ds_write_b128 v112, v[176:179] offset:1024
	ds_write_b128 v112, v[180:183] offset:2048
	ds_write_b128 v112, v[184:187] offset:3072
	v_mfma_f32_32x32x16_bf16 v[32:47], v[120:123], v[52:55], v[32:47]
	v_mfma_f32_32x32x16_bf16 v[32:47], v[124:127], v[56:59], v[32:47]
	v_mfma_f32_32x32x16_bf16 v[32:47], v[128:131], v[60:63], v[32:47]
	s_nop 11
	v_exp_f32_e32 v32, v32
	v_exp_f32_e32 v33, v33
	v_exp_f32_e32 v34, v34
	v_exp_f32_e32 v35, v35
	v_exp_f32_e32 v36, v36
	v_exp_f32_e32 v37, v37
	v_exp_f32_e32 v38, v38
	v_exp_f32_e32 v39, v39
	v_exp_f32_e32 v40, v40
	v_exp_f32_e32 v41, v41
	v_exp_f32_e32 v42, v42
	v_exp_f32_e32 v43, v43
	v_exp_f32_e32 v44, v44
	v_exp_f32_e32 v45, v45
	v_exp_f32_e32 v46, v46
	v_exp_f32_e32 v47, v47
	s_add_i32 s90, s76, 640
	v_lshlrev_b32_e32 v84, 2, v107
	v_add_u32_e32 v84, s90, v84
	v_add_u32_e32 v85, 0, v84
	v_add_u32_e32 v86, 4, v84
	v_add_u32_e32 v87, 8, v84
	v_add_u32_e32 v88, 12, v84
	v_cmp_gt_u32_e64 s[30:31], s98, v85
	v_cmp_gt_u32_e64 s[36:37], s98, v86
	v_cmp_gt_u32_e64 s[78:79], s98, v87
	v_cmp_gt_u32_e64 s[50:51], s98, v88
	v_cndmask_b32_e64 v32, 0, v32, s[30:31]
	v_add_u32_e32 v85, 32, v84
	v_cmp_gt_u32_e64 s[30:31], s98, v85
	v_cndmask_b32_e64 v33, 0, v33, s[36:37]
	v_add_u32_e32 v86, 36, v84
	v_cmp_gt_u32_e64 s[36:37], s98, v86
	v_cndmask_b32_e64 v34, 0, v34, s[78:79]
	v_add_u32_e32 v87, 40, v84
	v_cmp_gt_u32_e64 s[78:79], s98, v87
	v_cndmask_b32_e64 v35, 0, v35, s[50:51]
	v_add_u32_e32 v88, 44, v84
	v_cmp_gt_u32_e64 s[50:51], s98, v88
	v_cndmask_b32_e64 v36, 0, v36, s[30:31]
	v_add_u32_e32 v85, 64, v84
	v_cmp_gt_u32_e64 s[30:31], s98, v85
	v_cndmask_b32_e64 v37, 0, v37, s[36:37]
	v_add_u32_e32 v86, 68, v84
	v_cmp_gt_u32_e64 s[36:37], s98, v86
	v_cndmask_b32_e64 v38, 0, v38, s[78:79]
	v_add_u32_e32 v87, 72, v84
	v_cmp_gt_u32_e64 s[78:79], s98, v87
	v_cndmask_b32_e64 v39, 0, v39, s[50:51]
	v_add_u32_e32 v88, 76, v84
	v_cmp_gt_u32_e64 s[50:51], s98, v88
	v_cndmask_b32_e64 v40, 0, v40, s[30:31]
	v_add_u32_e32 v85, 96, v84
	v_cmp_gt_u32_e64 s[30:31], s98, v85
	v_cndmask_b32_e64 v41, 0, v41, s[36:37]
	v_add_u32_e32 v86, 100, v84
	v_cmp_gt_u32_e64 s[36:37], s98, v86
	v_cndmask_b32_e64 v42, 0, v42, s[78:79]
	v_add_u32_e32 v87, 104, v84
	v_cmp_gt_u32_e64 s[78:79], s98, v87
	v_cndmask_b32_e64 v43, 0, v43, s[50:51]
	v_add_u32_e32 v88, 108, v84
	v_cmp_gt_u32_e64 s[50:51], s98, v88
	v_nop
	v_cndmask_b32_e64 v44, 0, v44, s[30:31]
	v_cndmask_b32_e64 v45, 0, v45, s[36:37]
	v_cndmask_b32_e64 v46, 0, v46, s[78:79]
	v_cndmask_b32_e64 v47, 0, v47, s[50:51]
	v_cvt_pk_bf16_f32 v64, v32, v33
	v_cvt_pk_bf16_f32 v65, v34, v35
	v_cvt_pk_bf16_f32 v66, v36, v37
	v_cvt_pk_bf16_f32 v67, v38, v39
	v_cvt_pk_bf16_f32 v68, v40, v41
	v_cvt_pk_bf16_f32 v69, v42, v43
	v_cvt_pk_bf16_f32 v70, v44, v45
	v_cvt_pk_bf16_f32 v71, v46, v47
	v_pk_add_f32 v[232:233], v[232:233], v[32:33]
	v_pk_add_f32 v[232:233], v[232:233], v[34:35]
	v_pk_add_f32 v[232:233], v[232:233], v[36:37]
	v_pk_add_f32 v[232:233], v[232:233], v[38:39]
	v_pk_add_f32 v[232:233], v[232:233], v[40:41]
	v_pk_add_f32 v[232:233], v[232:233], v[42:43]
	v_pk_add_f32 v[232:233], v[232:233], v[44:45]
	v_pk_add_f32 v[232:233], v[232:233], v[46:47]
	s_waitcnt lgkmcnt(12)
	v_mfma_f32_32x32x16_bf16 v[0:15], v[64:67], v[72:75], v[0:15]
	v_mfma_f32_32x32x16_bf16 v[16:31], v[64:67], v[76:79], v[16:31]
	v_mfma_f32_32x32x16_bf16 v[0:15], v[68:71], v[220:223], v[0:15]
	v_mfma_f32_32x32x16_bf16 v[16:31], v[68:71], v[224:227], v[16:31]
	s_add_i32 s90, s76, 0
	v_add_u32_e32 v80, s90, v243
	v_add_u32_e32 v83, s90, v244
	v_add_u32_e32 v99, s90, v245
	v_add_u32_e32 v253, s90, v246
	v_add_u32_e32 v254, s90, v148
	v_add_u32_e32 v255, s90, v151
	v_med3_i32 v80, v80, 0, s99
	v_med3_i32 v83, v83, 0, s99
	v_med3_i32 v99, v99, 0, s99
	v_med3_i32 v253, v253, 0, s99
	v_med3_i32 v254, v254, 0, s99
	v_med3_i32 v255, v255, 0, s99
	v_mad_u32_u24 v80, v80, s100, v252
	v_mad_u32_u24 v83, v83, s100, v252
	v_mad_u32_u24 v99, v99, s100, v252
	v_mad_u32_u24 v253, v253, s100, v252
	v_mad_u32_u24 v254, v254, s100, v153
	v_mad_u32_u24 v255, v255, s100, v153
	global_load_dwordx4 v[116:119], v80, s[82:83]
	global_load_dwordx4 v[120:123], v83, s[82:83]
	global_load_dwordx4 v[124:127], v99, s[82:83]
	global_load_dwordx4 v[128:131], v253, s[82:83]
	global_load_dwordx4 v[132:135], v254, s[82:83] offset:768
	global_load_dwordx4 v[136:139], v255, s[82:83] offset:768
	global_load_dwordx4 v[140:143], v254, s[82:83] offset:832
	global_load_dwordx4 v[144:147], v255, s[82:83] offset:832
	v_mov_b32_e32 v115, v230
	ds_read2_b32 v[32:33], v115 offset0:0 offset1:1
	ds_read2_b32 v[34:35], v115 offset0:2 offset1:3
	ds_read2_b32 v[36:37], v115 offset0:8 offset1:9
	ds_read2_b32 v[38:39], v115 offset0:10 offset1:11
	ds_read2_b32 v[40:41], v115 offset0:16 offset1:17
	ds_read2_b32 v[42:43], v115 offset0:18 offset1:19
	ds_read2_b32 v[44:45], v115 offset0:24 offset1:25
	ds_read2_b32 v[46:47], v115 offset0:26 offset1:27
	s_waitcnt lgkmcnt(0)
	v_mfma_f32_32x32x16_bf16 v[32:47], v[156:159], v[48:51], v[32:47]
	ds_read_b64_tr_b16 v[72:73], v231
	ds_read_b64_tr_b16 v[74:75], v231 offset:512
	ds_read_b64_tr_b16 v[76:77], v231 offset:2048
	ds_read_b64_tr_b16 v[78:79], v231 offset:2560
	ds_read_b64_tr_b16 v[220:221], v231 offset:1024
	ds_read_b64_tr_b16 v[222:223], v231 offset:1536
	ds_read_b64_tr_b16 v[224:225], v231 offset:3072
	ds_read_b64_tr_b16 v[226:227], v231 offset:3584
	s_waitcnt vmcnt(8)
	ds_write_b128 v247, v[188:191]
	ds_write_b128 v247, v[192:195] offset:1024
	ds_write_b128 v247, v[196:199] offset:2048
	ds_write_b128 v247, v[200:203] offset:3072
	ds_read_b128 v[188:191], v248
	ds_read_b128 v[192:195], v249
	ds_read_b128 v[196:199], v250
	ds_read_b128 v[200:203], v251
	ds_write_b128 v112, v[204:207]
	ds_write_b128 v112, v[208:211] offset:1024
	ds_write_b128 v112, v[212:215] offset:2048
	ds_write_b128 v112, v[216:219] offset:3072
	v_mfma_f32_32x32x16_bf16 v[32:47], v[160:163], v[52:55], v[32:47]
	v_mfma_f32_32x32x16_bf16 v[32:47], v[164:167], v[56:59], v[32:47]
	v_mfma_f32_32x32x16_bf16 v[32:47], v[168:171], v[60:63], v[32:47]
	s_nop 11
	v_exp_f32_e32 v32, v32
	v_exp_f32_e32 v33, v33
	v_exp_f32_e32 v34, v34
	v_exp_f32_e32 v35, v35
	v_exp_f32_e32 v36, v36
	v_exp_f32_e32 v37, v37
	v_exp_f32_e32 v38, v38
	v_exp_f32_e32 v39, v39
	v_exp_f32_e32 v40, v40
	v_exp_f32_e32 v41, v41
	v_exp_f32_e32 v42, v42
	v_exp_f32_e32 v43, v43
	v_exp_f32_e32 v44, v44
	v_exp_f32_e32 v45, v45
	v_exp_f32_e32 v46, v46
	v_exp_f32_e32 v47, v47
	s_add_i32 s90, s76, -1024
	v_lshlrev_b32_e32 v84, 4, v107
	v_add_u32_e32 v84, s90, v84
	v_add_u32_e32 v85, 0, v84
	v_add_u32_e32 v86, 16, v84
	v_add_u32_e32 v87, 32, v84
	v_add_u32_e32 v88, 48, v84
	v_cmp_gt_u32_e64 s[30:31], s98, v85
	v_cmp_gt_u32_e64 s[36:37], s98, v86
	v_cmp_gt_u32_e64 s[78:79], s98, v87
	v_cmp_gt_u32_e64 s[50:51], s98, v88
	v_cndmask_b32_e64 v32, 0, v32, s[30:31]
	v_add_u32_e32 v85, 128, v84
	v_cmp_gt_u32_e64 s[30:31], s98, v85
	v_cndmask_b32_e64 v33, 0, v33, s[36:37]
	v_add_u32_e32 v86, 144, v84
	v_cmp_gt_u32_e64 s[36:37], s98, v86
	v_cndmask_b32_e64 v34, 0, v34, s[78:79]
	v_add_u32_e32 v87, 160, v84
	v_cmp_gt_u32_e64 s[78:79], s98, v87
	v_cndmask_b32_e64 v35, 0, v35, s[50:51]
	v_add_u32_e32 v88, 176, v84
	v_cmp_gt_u32_e64 s[50:51], s98, v88
	v_cndmask_b32_e64 v36, 0, v36, s[30:31]
	v_add_u32_e32 v85, 256, v84
	v_cmp_gt_u32_e64 s[30:31], s98, v85
	v_cndmask_b32_e64 v37, 0, v37, s[36:37]
	v_add_u32_e32 v86, 272, v84
	v_cmp_gt_u32_e64 s[36:37], s98, v86
	v_cndmask_b32_e64 v38, 0, v38, s[78:79]
	v_add_u32_e32 v87, 288, v84
	v_cmp_gt_u32_e64 s[78:79], s98, v87
	v_cndmask_b32_e64 v39, 0, v39, s[50:51]
	v_add_u32_e32 v88, 304, v84
	v_cmp_gt_u32_e64 s[50:51], s98, v88
	v_cndmask_b32_e64 v40, 0, v40, s[30:31]
	v_add_u32_e32 v85, 384, v84
	v_cmp_gt_u32_e64 s[30:31], s98, v85
	v_cndmask_b32_e64 v41, 0, v41, s[36:37]
	v_add_u32_e32 v86, 400, v84
	v_cmp_gt_u32_e64 s[36:37], s98, v86
	v_cndmask_b32_e64 v42, 0, v42, s[78:79]
	v_add_u32_e32 v87, 416, v84
	v_cmp_gt_u32_e64 s[78:79], s98, v87
	v_cndmask_b32_e64 v43, 0, v43, s[50:51]
	v_add_u32_e32 v88, 432, v84
	v_cmp_gt_u32_e64 s[50:51], s98, v88
	v_nop
	v_cndmask_b32_e64 v44, 0, v44, s[30:31]
	v_cndmask_b32_e64 v45, 0, v45, s[36:37]
	v_cndmask_b32_e64 v46, 0, v46, s[78:79]
	v_cndmask_b32_e64 v47, 0, v47, s[50:51]
	v_cvt_pk_bf16_f32 v64, v32, v33
	v_cvt_pk_bf16_f32 v65, v34, v35
	v_cvt_pk_bf16_f32 v66, v36, v37
	v_cvt_pk_bf16_f32 v67, v38, v39
	v_cvt_pk_bf16_f32 v68, v40, v41
	v_cvt_pk_bf16_f32 v69, v42, v43
	v_cvt_pk_bf16_f32 v70, v44, v45
	v_cvt_pk_bf16_f32 v71, v46, v47
	v_pk_add_f32 v[232:233], v[232:233], v[32:33]
	v_pk_add_f32 v[232:233], v[232:233], v[34:35]
	v_pk_add_f32 v[232:233], v[232:233], v[36:37]
	v_pk_add_f32 v[232:233], v[232:233], v[38:39]
	v_pk_add_f32 v[232:233], v[232:233], v[40:41]
	v_pk_add_f32 v[232:233], v[232:233], v[42:43]
	v_pk_add_f32 v[232:233], v[232:233], v[44:45]
	v_pk_add_f32 v[232:233], v[232:233], v[46:47]
	s_waitcnt lgkmcnt(12)
	v_mfma_f32_32x32x16_bf16 v[0:15], v[64:67], v[72:75], v[0:15]
	v_mfma_f32_32x32x16_bf16 v[16:31], v[64:67], v[76:79], v[16:31]
	v_mfma_f32_32x32x16_bf16 v[0:15], v[68:71], v[220:223], v[0:15]
	v_mfma_f32_32x32x16_bf16 v[16:31], v[68:71], v[224:227], v[16:31]
	s_add_i32 s90, s76, 512
	v_add_u32_e32 v80, s90, v243
	v_add_u32_e32 v83, s90, v244
	v_add_u32_e32 v99, s90, v245
	v_add_u32_e32 v253, s90, v246
	v_add_u32_e32 v254, s90, v148
	v_add_u32_e32 v255, s90, v151
	v_med3_i32 v80, v80, 0, s99
	v_med3_i32 v83, v83, 0, s99
	v_med3_i32 v99, v99, 0, s99
	v_med3_i32 v253, v253, 0, s99
	v_med3_i32 v254, v254, 0, s99
	v_med3_i32 v255, v255, 0, s99
	v_mad_u32_u24 v80, v80, s100, v252
	v_mad_u32_u24 v83, v83, s100, v252
	v_mad_u32_u24 v99, v99, s100, v252
	v_mad_u32_u24 v253, v253, s100, v252
	v_mad_u32_u24 v254, v254, s100, v153
	v_mad_u32_u24 v255, v255, s100, v153
	global_load_dwordx4 v[156:159], v80, s[82:83]
	global_load_dwordx4 v[160:163], v83, s[82:83]
	global_load_dwordx4 v[164:167], v99, s[82:83]
	global_load_dwordx4 v[168:171], v253, s[82:83]
	global_load_dwordx4 v[172:175], v254, s[82:83] offset:768
	global_load_dwordx4 v[176:179], v255, s[82:83] offset:768
	global_load_dwordx4 v[180:183], v254, s[82:83] offset:832
	global_load_dwordx4 v[184:187], v255, s[82:83] offset:832
	ds_read2_b32 v[32:33], v115 offset0:32 offset1:33
	ds_read2_b32 v[34:35], v115 offset0:34 offset1:35
	ds_read2_b32 v[36:37], v115 offset0:40 offset1:41
	ds_read2_b32 v[38:39], v115 offset0:42 offset1:43
	ds_read2_b32 v[40:41], v115 offset0:48 offset1:49
	ds_read2_b32 v[42:43], v115 offset0:50 offset1:51
	ds_read2_b32 v[44:45], v115 offset0:56 offset1:57
	ds_read2_b32 v[46:47], v115 offset0:58 offset1:59
	s_waitcnt lgkmcnt(0)
	v_mfma_f32_32x32x16_bf16 v[32:47], v[188:191], v[48:51], v[32:47]
	ds_read_b64_tr_b16 v[72:73], v231
	ds_read_b64_tr_b16 v[74:75], v231 offset:512
	ds_read_b64_tr_b16 v[76:77], v231 offset:2048
	ds_read_b64_tr_b16 v[78:79], v231 offset:2560
	ds_read_b64_tr_b16 v[220:221], v231 offset:1024
	ds_read_b64_tr_b16 v[222:223], v231 offset:1536
	ds_read_b64_tr_b16 v[224:225], v231 offset:3072
	ds_read_b64_tr_b16 v[226:227], v231 offset:3584
	s_waitcnt vmcnt(8)
	ds_write_b128 v247, v[116:119]
	ds_write_b128 v247, v[120:123] offset:1024
	ds_write_b128 v247, v[124:127] offset:2048
	ds_write_b128 v247, v[128:131] offset:3072
	ds_read_b128 v[116:119], v248
	ds_read_b128 v[120:123], v249
	ds_read_b128 v[124:127], v250
	ds_read_b128 v[128:131], v251
	ds_write_b128 v112, v[132:135]
	ds_write_b128 v112, v[136:139] offset:1024
	ds_write_b128 v112, v[140:143] offset:2048
	ds_write_b128 v112, v[144:147] offset:3072
	v_mfma_f32_32x32x16_bf16 v[32:47], v[192:195], v[52:55], v[32:47]
	v_mfma_f32_32x32x16_bf16 v[32:47], v[196:199], v[56:59], v[32:47]
	v_mfma_f32_32x32x16_bf16 v[32:47], v[200:203], v[60:63], v[32:47]
	s_nop 11
	v_exp_f32_e32 v32, v32
	v_exp_f32_e32 v33, v33
	v_exp_f32_e32 v34, v34
	v_exp_f32_e32 v35, v35
	v_exp_f32_e32 v36, v36
	v_exp_f32_e32 v37, v37
	v_exp_f32_e32 v38, v38
	v_exp_f32_e32 v39, v39
	v_exp_f32_e32 v40, v40
	v_exp_f32_e32 v41, v41
	v_exp_f32_e32 v42, v42
	v_exp_f32_e32 v43, v43
	v_exp_f32_e32 v44, v44
	v_exp_f32_e32 v45, v45
	v_exp_f32_e32 v46, v46
	v_exp_f32_e32 v47, v47
	s_add_i32 s90, s76, -512
	v_lshlrev_b32_e32 v84, 4, v107
	v_add_u32_e32 v84, s90, v84
	v_add_u32_e32 v85, 0, v84
	v_add_u32_e32 v86, 16, v84
	v_add_u32_e32 v87, 32, v84
	v_add_u32_e32 v88, 48, v84
	v_cmp_gt_u32_e64 s[30:31], s98, v85
	v_cmp_gt_u32_e64 s[36:37], s98, v86
	v_cmp_gt_u32_e64 s[78:79], s98, v87
	v_cmp_gt_u32_e64 s[50:51], s98, v88
	v_cndmask_b32_e64 v32, 0, v32, s[30:31]
	v_add_u32_e32 v85, 128, v84
	v_cmp_gt_u32_e64 s[30:31], s98, v85
	v_cndmask_b32_e64 v33, 0, v33, s[36:37]
	v_add_u32_e32 v86, 144, v84
	v_cmp_gt_u32_e64 s[36:37], s98, v86
	v_cndmask_b32_e64 v34, 0, v34, s[78:79]
	v_add_u32_e32 v87, 160, v84
	v_cmp_gt_u32_e64 s[78:79], s98, v87
	v_cndmask_b32_e64 v35, 0, v35, s[50:51]
	v_add_u32_e32 v88, 176, v84
	v_cmp_gt_u32_e64 s[50:51], s98, v88
	v_cndmask_b32_e64 v36, 0, v36, s[30:31]
	v_add_u32_e32 v85, 256, v84
	v_cmp_gt_u32_e64 s[30:31], s98, v85
	v_cndmask_b32_e64 v37, 0, v37, s[36:37]
	v_add_u32_e32 v86, 272, v84
	v_cmp_gt_u32_e64 s[36:37], s98, v86
	v_cndmask_b32_e64 v38, 0, v38, s[78:79]
	v_add_u32_e32 v87, 288, v84
	v_cmp_gt_u32_e64 s[78:79], s98, v87
	v_cndmask_b32_e64 v39, 0, v39, s[50:51]
	v_add_u32_e32 v88, 304, v84
	v_cmp_gt_u32_e64 s[50:51], s98, v88
	v_cndmask_b32_e64 v40, 0, v40, s[30:31]
	v_add_u32_e32 v85, 384, v84
	v_cmp_gt_u32_e64 s[30:31], s98, v85
	v_cndmask_b32_e64 v41, 0, v41, s[36:37]
	v_add_u32_e32 v86, 400, v84
	v_cmp_gt_u32_e64 s[36:37], s98, v86
	v_cndmask_b32_e64 v42, 0, v42, s[78:79]
	v_add_u32_e32 v87, 416, v84
	v_cmp_gt_u32_e64 s[78:79], s98, v87
	v_cndmask_b32_e64 v43, 0, v43, s[50:51]
	v_add_u32_e32 v88, 432, v84
	v_cmp_gt_u32_e64 s[50:51], s98, v88
	v_nop
	v_cndmask_b32_e64 v44, 0, v44, s[30:31]
	v_cndmask_b32_e64 v45, 0, v45, s[36:37]
	v_cndmask_b32_e64 v46, 0, v46, s[78:79]
	v_cndmask_b32_e64 v47, 0, v47, s[50:51]
	v_cvt_pk_bf16_f32 v64, v32, v33
	v_cvt_pk_bf16_f32 v65, v34, v35
	v_cvt_pk_bf16_f32 v66, v36, v37
	v_cvt_pk_bf16_f32 v67, v38, v39
	v_cvt_pk_bf16_f32 v68, v40, v41
	v_cvt_pk_bf16_f32 v69, v42, v43
	v_cvt_pk_bf16_f32 v70, v44, v45
	v_cvt_pk_bf16_f32 v71, v46, v47
	v_pk_add_f32 v[232:233], v[232:233], v[32:33]
	v_pk_add_f32 v[232:233], v[232:233], v[34:35]
	v_pk_add_f32 v[232:233], v[232:233], v[36:37]
	v_pk_add_f32 v[232:233], v[232:233], v[38:39]
	v_pk_add_f32 v[232:233], v[232:233], v[40:41]
	v_pk_add_f32 v[232:233], v[232:233], v[42:43]
	v_pk_add_f32 v[232:233], v[232:233], v[44:45]
	v_pk_add_f32 v[232:233], v[232:233], v[46:47]
	s_waitcnt lgkmcnt(12)
	v_mfma_f32_32x32x16_bf16 v[0:15], v[64:67], v[72:75], v[0:15]
	v_mfma_f32_32x32x16_bf16 v[16:31], v[64:67], v[76:79], v[16:31]
	v_mfma_f32_32x32x16_bf16 v[0:15], v[68:71], v[220:223], v[0:15]
	v_mfma_f32_32x32x16_bf16 v[16:31], v[68:71], v[224:227], v[16:31]
	s_add_i32 s90, s76, 1024
	v_add_u32_e32 v80, s90, v243
	v_add_u32_e32 v83, s90, v244
	v_add_u32_e32 v99, s90, v245
	v_add_u32_e32 v253, s90, v246
	v_add_u32_e32 v254, s90, v148
	v_add_u32_e32 v255, s90, v151
	v_med3_i32 v80, v80, 0, s99
	v_med3_i32 v83, v83, 0, s99
	v_med3_i32 v99, v99, 0, s99
	v_med3_i32 v253, v253, 0, s99
	v_med3_i32 v254, v254, 0, s99
	v_med3_i32 v255, v255, 0, s99
	v_mad_u32_u24 v80, v80, s100, v252
	v_mad_u32_u24 v83, v83, s100, v252
	v_mad_u32_u24 v99, v99, s100, v252
	v_mad_u32_u24 v253, v253, s100, v252
	v_mad_u32_u24 v254, v254, s100, v153
	v_mad_u32_u24 v255, v255, s100, v153
	global_load_dwordx4 v[188:191], v80, s[82:83]
	global_load_dwordx4 v[192:195], v83, s[82:83]
	global_load_dwordx4 v[196:199], v99, s[82:83]
	global_load_dwordx4 v[200:203], v253, s[82:83]
	global_load_dwordx4 v[204:207], v254, s[82:83] offset:768
	global_load_dwordx4 v[208:211], v255, s[82:83] offset:768
	global_load_dwordx4 v[212:215], v254, s[82:83] offset:832
	global_load_dwordx4 v[216:219], v255, s[82:83] offset:832
	ds_read2_b32 v[32:33], v115 offset0:64 offset1:65
	ds_read2_b32 v[34:35], v115 offset0:66 offset1:67
	ds_read2_b32 v[36:37], v115 offset0:72 offset1:73
	ds_read2_b32 v[38:39], v115 offset0:74 offset1:75
	ds_read2_b32 v[40:41], v115 offset0:80 offset1:81
	ds_read2_b32 v[42:43], v115 offset0:82 offset1:83
	ds_read2_b32 v[44:45], v115 offset0:88 offset1:89
	ds_read2_b32 v[46:47], v115 offset0:90 offset1:91
	s_waitcnt lgkmcnt(0)
	v_mfma_f32_32x32x16_bf16 v[32:47], v[116:119], v[48:51], v[32:47]
	ds_read_b64_tr_b16 v[72:73], v231
	ds_read_b64_tr_b16 v[74:75], v231 offset:512
	ds_read_b64_tr_b16 v[76:77], v231 offset:2048
	ds_read_b64_tr_b16 v[78:79], v231 offset:2560
	ds_read_b64_tr_b16 v[220:221], v231 offset:1024
	ds_read_b64_tr_b16 v[222:223], v231 offset:1536
	ds_read_b64_tr_b16 v[224:225], v231 offset:3072
	ds_read_b64_tr_b16 v[226:227], v231 offset:3584
	s_waitcnt vmcnt(8)
	ds_write_b128 v247, v[156:159]
	ds_write_b128 v247, v[160:163] offset:1024
	ds_write_b128 v247, v[164:167] offset:2048
	ds_write_b128 v247, v[168:171] offset:3072
	ds_read_b128 v[156:159], v248
	ds_read_b128 v[160:163], v249
	ds_read_b128 v[164:167], v250
	ds_read_b128 v[168:171], v251
	ds_write_b128 v112, v[172:175]
	ds_write_b128 v112, v[176:179] offset:1024
	ds_write_b128 v112, v[180:183] offset:2048
	ds_write_b128 v112, v[184:187] offset:3072
	v_mfma_f32_32x32x16_bf16 v[32:47], v[120:123], v[52:55], v[32:47]
	v_mfma_f32_32x32x16_bf16 v[32:47], v[124:127], v[56:59], v[32:47]
	v_mfma_f32_32x32x16_bf16 v[32:47], v[128:131], v[60:63], v[32:47]
	s_nop 11
	v_exp_f32_e32 v32, v32
	v_exp_f32_e32 v33, v33
	v_exp_f32_e32 v34, v34
	v_exp_f32_e32 v35, v35
	v_exp_f32_e32 v36, v36
	v_exp_f32_e32 v37, v37
	v_exp_f32_e32 v38, v38
	v_exp_f32_e32 v39, v39
	v_exp_f32_e32 v40, v40
	v_exp_f32_e32 v41, v41
	v_exp_f32_e32 v42, v42
	v_exp_f32_e32 v43, v43
	v_exp_f32_e32 v44, v44
	v_exp_f32_e32 v45, v45
	v_exp_f32_e32 v46, v46
	v_exp_f32_e32 v47, v47
	s_add_i32 s90, s76, 0
	v_lshlrev_b32_e32 v84, 4, v107
	v_add_u32_e32 v84, s90, v84
	v_add_u32_e32 v85, 0, v84
	v_add_u32_e32 v86, 16, v84
	v_add_u32_e32 v87, 32, v84
	v_add_u32_e32 v88, 48, v84
	v_cmp_gt_u32_e64 s[30:31], s98, v85
	v_cmp_gt_u32_e64 s[36:37], s98, v86
	v_cmp_gt_u32_e64 s[78:79], s98, v87
	v_cmp_gt_u32_e64 s[50:51], s98, v88
	v_cndmask_b32_e64 v32, 0, v32, s[30:31]
	v_add_u32_e32 v85, 128, v84
	v_cmp_gt_u32_e64 s[30:31], s98, v85
	v_cndmask_b32_e64 v33, 0, v33, s[36:37]
	v_add_u32_e32 v86, 144, v84
	v_cmp_gt_u32_e64 s[36:37], s98, v86
	v_cndmask_b32_e64 v34, 0, v34, s[78:79]
	v_add_u32_e32 v87, 160, v84
	v_cmp_gt_u32_e64 s[78:79], s98, v87
	v_cndmask_b32_e64 v35, 0, v35, s[50:51]
	v_add_u32_e32 v88, 176, v84
	v_cmp_gt_u32_e64 s[50:51], s98, v88
	v_cndmask_b32_e64 v36, 0, v36, s[30:31]
	v_add_u32_e32 v85, 256, v84
	v_cmp_gt_u32_e64 s[30:31], s98, v85
	v_cndmask_b32_e64 v37, 0, v37, s[36:37]
	v_add_u32_e32 v86, 272, v84
	v_cmp_gt_u32_e64 s[36:37], s98, v86
	v_cndmask_b32_e64 v38, 0, v38, s[78:79]
	v_add_u32_e32 v87, 288, v84
	v_cmp_gt_u32_e64 s[78:79], s98, v87
	v_cndmask_b32_e64 v39, 0, v39, s[50:51]
	v_add_u32_e32 v88, 304, v84
	v_cmp_gt_u32_e64 s[50:51], s98, v88
	v_cndmask_b32_e64 v40, 0, v40, s[30:31]
	v_add_u32_e32 v85, 384, v84
	v_cmp_gt_u32_e64 s[30:31], s98, v85
	v_cndmask_b32_e64 v41, 0, v41, s[36:37]
	v_add_u32_e32 v86, 400, v84
	v_cmp_gt_u32_e64 s[36:37], s98, v86
	v_cndmask_b32_e64 v42, 0, v42, s[78:79]
	v_add_u32_e32 v87, 416, v84
	v_cmp_gt_u32_e64 s[78:79], s98, v87
	v_cndmask_b32_e64 v43, 0, v43, s[50:51]
	v_add_u32_e32 v88, 432, v84
	v_cmp_gt_u32_e64 s[50:51], s98, v88
	v_nop
	v_cndmask_b32_e64 v44, 0, v44, s[30:31]
	v_cndmask_b32_e64 v45, 0, v45, s[36:37]
	v_cndmask_b32_e64 v46, 0, v46, s[78:79]
	v_cndmask_b32_e64 v47, 0, v47, s[50:51]
	v_cvt_pk_bf16_f32 v64, v32, v33
	v_cvt_pk_bf16_f32 v65, v34, v35
	v_cvt_pk_bf16_f32 v66, v36, v37
	v_cvt_pk_bf16_f32 v67, v38, v39
	v_cvt_pk_bf16_f32 v68, v40, v41
	v_cvt_pk_bf16_f32 v69, v42, v43
	v_cvt_pk_bf16_f32 v70, v44, v45
	v_cvt_pk_bf16_f32 v71, v46, v47
	v_pk_add_f32 v[232:233], v[232:233], v[32:33]
	v_pk_add_f32 v[232:233], v[232:233], v[34:35]
	v_pk_add_f32 v[232:233], v[232:233], v[36:37]
	v_pk_add_f32 v[232:233], v[232:233], v[38:39]
	v_pk_add_f32 v[232:233], v[232:233], v[40:41]
	v_pk_add_f32 v[232:233], v[232:233], v[42:43]
	v_pk_add_f32 v[232:233], v[232:233], v[44:45]
	v_pk_add_f32 v[232:233], v[232:233], v[46:47]
	s_waitcnt lgkmcnt(12)
	v_mfma_f32_32x32x16_bf16 v[0:15], v[64:67], v[72:75], v[0:15]
	v_mfma_f32_32x32x16_bf16 v[16:31], v[64:67], v[76:79], v[16:31]
	v_mfma_f32_32x32x16_bf16 v[0:15], v[68:71], v[220:223], v[0:15]
	v_mfma_f32_32x32x16_bf16 v[16:31], v[68:71], v[224:227], v[16:31]
	ds_read2_b32 v[32:33], v115 offset0:96 offset1:97
	ds_read2_b32 v[34:35], v115 offset0:98 offset1:99
	ds_read2_b32 v[36:37], v115 offset0:104 offset1:105
	ds_read2_b32 v[38:39], v115 offset0:106 offset1:107
	ds_read2_b32 v[40:41], v115 offset0:112 offset1:113
	ds_read2_b32 v[42:43], v115 offset0:114 offset1:115
	ds_read2_b32 v[44:45], v115 offset0:120 offset1:121
	ds_read2_b32 v[46:47], v115 offset0:122 offset1:123
	s_waitcnt lgkmcnt(0)
	v_mfma_f32_32x32x16_bf16 v[32:47], v[156:159], v[48:51], v[32:47]
	ds_read_b64_tr_b16 v[72:73], v231
	ds_read_b64_tr_b16 v[74:75], v231 offset:512
	ds_read_b64_tr_b16 v[76:77], v231 offset:2048
	ds_read_b64_tr_b16 v[78:79], v231 offset:2560
	ds_read_b64_tr_b16 v[220:221], v231 offset:1024
	ds_read_b64_tr_b16 v[222:223], v231 offset:1536
	ds_read_b64_tr_b16 v[224:225], v231 offset:3072
	ds_read_b64_tr_b16 v[226:227], v231 offset:3584
	s_waitcnt vmcnt(0)
	ds_write_b128 v247, v[188:191]
	ds_write_b128 v247, v[192:195] offset:1024
	ds_write_b128 v247, v[196:199] offset:2048
	ds_write_b128 v247, v[200:203] offset:3072
	ds_read_b128 v[188:191], v248
	ds_read_b128 v[192:195], v249
	ds_read_b128 v[196:199], v250
	ds_read_b128 v[200:203], v251
	ds_write_b128 v112, v[204:207]
	ds_write_b128 v112, v[208:211] offset:1024
	ds_write_b128 v112, v[212:215] offset:2048
	ds_write_b128 v112, v[216:219] offset:3072
	v_mfma_f32_32x32x16_bf16 v[32:47], v[160:163], v[52:55], v[32:47]
	v_mfma_f32_32x32x16_bf16 v[32:47], v[164:167], v[56:59], v[32:47]
	v_mfma_f32_32x32x16_bf16 v[32:47], v[168:171], v[60:63], v[32:47]
	s_nop 11
	v_exp_f32_e32 v32, v32
	v_exp_f32_e32 v33, v33
	v_exp_f32_e32 v34, v34
	v_exp_f32_e32 v35, v35
	v_exp_f32_e32 v36, v36
	v_exp_f32_e32 v37, v37
	v_exp_f32_e32 v38, v38
	v_exp_f32_e32 v39, v39
	v_exp_f32_e32 v40, v40
	v_exp_f32_e32 v41, v41
	v_exp_f32_e32 v42, v42
	v_exp_f32_e32 v43, v43
	v_exp_f32_e32 v44, v44
	v_exp_f32_e32 v45, v45
	v_exp_f32_e32 v46, v46
	v_exp_f32_e32 v47, v47
	s_add_i32 s90, s76, 512
	v_lshlrev_b32_e32 v84, 4, v107
	v_add_u32_e32 v84, s90, v84
	v_add_u32_e32 v85, 0, v84
	v_add_u32_e32 v86, 16, v84
	v_add_u32_e32 v87, 32, v84
	v_add_u32_e32 v88, 48, v84
	v_cmp_gt_u32_e64 s[30:31], s98, v85
	v_cmp_gt_u32_e64 s[36:37], s98, v86
	v_cmp_gt_u32_e64 s[78:79], s98, v87
	v_cmp_gt_u32_e64 s[50:51], s98, v88
	v_cndmask_b32_e64 v32, 0, v32, s[30:31]
	v_add_u32_e32 v85, 128, v84
	v_cmp_gt_u32_e64 s[30:31], s98, v85
	v_cndmask_b32_e64 v33, 0, v33, s[36:37]
	v_add_u32_e32 v86, 144, v84
	v_cmp_gt_u32_e64 s[36:37], s98, v86
	v_cndmask_b32_e64 v34, 0, v34, s[78:79]
	v_add_u32_e32 v87, 160, v84
	v_cmp_gt_u32_e64 s[78:79], s98, v87
	v_cndmask_b32_e64 v35, 0, v35, s[50:51]
	v_add_u32_e32 v88, 176, v84
	v_cmp_gt_u32_e64 s[50:51], s98, v88
	v_cndmask_b32_e64 v36, 0, v36, s[30:31]
	v_add_u32_e32 v85, 256, v84
	v_cmp_gt_u32_e64 s[30:31], s98, v85
	v_cndmask_b32_e64 v37, 0, v37, s[36:37]
	v_add_u32_e32 v86, 272, v84
	v_cmp_gt_u32_e64 s[36:37], s98, v86
	v_cndmask_b32_e64 v38, 0, v38, s[78:79]
	v_add_u32_e32 v87, 288, v84
	v_cmp_gt_u32_e64 s[78:79], s98, v87
	v_cndmask_b32_e64 v39, 0, v39, s[50:51]
	v_add_u32_e32 v88, 304, v84
	v_cmp_gt_u32_e64 s[50:51], s98, v88
	v_cndmask_b32_e64 v40, 0, v40, s[30:31]
	v_add_u32_e32 v85, 384, v84
	v_cmp_gt_u32_e64 s[30:31], s98, v85
	v_cndmask_b32_e64 v41, 0, v41, s[36:37]
	v_add_u32_e32 v86, 400, v84
	v_cmp_gt_u32_e64 s[36:37], s98, v86
	v_cndmask_b32_e64 v42, 0, v42, s[78:79]
	v_add_u32_e32 v87, 416, v84
	v_cmp_gt_u32_e64 s[78:79], s98, v87
	v_cndmask_b32_e64 v43, 0, v43, s[50:51]
	v_add_u32_e32 v88, 432, v84
	v_cmp_gt_u32_e64 s[50:51], s98, v88
	v_nop
	v_cndmask_b32_e64 v44, 0, v44, s[30:31]
	v_cndmask_b32_e64 v45, 0, v45, s[36:37]
	v_cndmask_b32_e64 v46, 0, v46, s[78:79]
	v_cndmask_b32_e64 v47, 0, v47, s[50:51]
	v_cvt_pk_bf16_f32 v64, v32, v33
	v_cvt_pk_bf16_f32 v65, v34, v35
	v_cvt_pk_bf16_f32 v66, v36, v37
	v_cvt_pk_bf16_f32 v67, v38, v39
	v_cvt_pk_bf16_f32 v68, v40, v41
	v_cvt_pk_bf16_f32 v69, v42, v43
	v_cvt_pk_bf16_f32 v70, v44, v45
	v_cvt_pk_bf16_f32 v71, v46, v47
	v_pk_add_f32 v[232:233], v[232:233], v[32:33]
	v_pk_add_f32 v[232:233], v[232:233], v[34:35]
	v_pk_add_f32 v[232:233], v[232:233], v[36:37]
	v_pk_add_f32 v[232:233], v[232:233], v[38:39]
	v_pk_add_f32 v[232:233], v[232:233], v[40:41]
	v_pk_add_f32 v[232:233], v[232:233], v[42:43]
	v_pk_add_f32 v[232:233], v[232:233], v[44:45]
	v_pk_add_f32 v[232:233], v[232:233], v[46:47]
	s_waitcnt lgkmcnt(12)
	v_mfma_f32_32x32x16_bf16 v[0:15], v[64:67], v[72:75], v[0:15]
	v_mfma_f32_32x32x16_bf16 v[16:31], v[64:67], v[76:79], v[16:31]
	v_mfma_f32_32x32x16_bf16 v[0:15], v[68:71], v[220:223], v[0:15]
	v_mfma_f32_32x32x16_bf16 v[16:31], v[68:71], v[224:227], v[16:31]
	ds_read2_b32 v[32:33], v115 offset0:128 offset1:129
	ds_read2_b32 v[34:35], v115 offset0:130 offset1:131
	ds_read2_b32 v[36:37], v115 offset0:136 offset1:137
	ds_read2_b32 v[38:39], v115 offset0:138 offset1:139
	ds_read2_b32 v[40:41], v115 offset0:144 offset1:145
	ds_read2_b32 v[42:43], v115 offset0:146 offset1:147
	ds_read2_b32 v[44:45], v115 offset0:152 offset1:153
	ds_read2_b32 v[46:47], v115 offset0:154 offset1:155
	s_waitcnt lgkmcnt(0)
; __device__ __forceinline__ int crow(int r, int hi) { return (r & 3) + 8 * (r >> 2) + 4 * hi; }
; __device__ __forceinline__ void dil_unit(LAS unsigned char* lds, bf16_t* proj, int seq, int hd, int T0, int rho) {
;     ...
;     l += __shfl_xor(l, 32);
; #pragma unroll
;     for (int rr = 0; rr < 16; ++rr) {
;         const int j = crow(rr, hi);
;         const float il = __builtin_amdgcn_rcpf(__shfl(l, j));
	v_mfma_f32_32x32x16_bf16 v[32:47], v[188:191], v[48:51], v[32:47]
	ds_read_b64_tr_b16 v[72:73], v231
	ds_read_b64_tr_b16 v[74:75], v231 offset:512
	ds_read_b64_tr_b16 v[76:77], v231 offset:2048
	ds_read_b64_tr_b16 v[78:79], v231 offset:2560
	ds_read_b64_tr_b16 v[220:221], v231 offset:1024
	ds_read_b64_tr_b16 v[222:223], v231 offset:1536
	ds_read_b64_tr_b16 v[224:225], v231 offset:3072
	ds_read_b64_tr_b16 v[226:227], v231 offset:3584
	v_mfma_f32_32x32x16_bf16 v[32:47], v[192:195], v[52:55], v[32:47]
	v_mfma_f32_32x32x16_bf16 v[32:47], v[196:199], v[56:59], v[32:47]
	v_mfma_f32_32x32x16_bf16 v[32:47], v[200:203], v[60:63], v[32:47]
	s_nop 11
	v_exp_f32_e32 v32, v32
	v_exp_f32_e32 v33, v33
	v_exp_f32_e32 v34, v34
	v_exp_f32_e32 v35, v35
	v_exp_f32_e32 v36, v36
	v_exp_f32_e32 v37, v37
	v_exp_f32_e32 v38, v38
	v_exp_f32_e32 v39, v39
	v_exp_f32_e32 v40, v40
	v_exp_f32_e32 v41, v41
	v_exp_f32_e32 v42, v42
	v_exp_f32_e32 v43, v43
	v_exp_f32_e32 v44, v44
	v_exp_f32_e32 v45, v45
	v_exp_f32_e32 v46, v46
	v_exp_f32_e32 v47, v47
	s_add_i32 s90, s76, 1024
	v_lshlrev_b32_e32 v84, 4, v107
	v_add_u32_e32 v84, s90, v84
	v_add_u32_e32 v85, 0, v84
	v_add_u32_e32 v86, 16, v84
	v_add_u32_e32 v87, 32, v84
	v_add_u32_e32 v88, 48, v84
	v_cmp_gt_u32_e64 s[30:31], s98, v85
	v_cmp_gt_u32_e64 s[36:37], s98, v86
	v_cmp_gt_u32_e64 s[78:79], s98, v87
	v_cmp_gt_u32_e64 s[50:51], s98, v88
	v_cndmask_b32_e64 v32, 0, v32, s[30:31]
	v_add_u32_e32 v85, 128, v84
	v_cmp_gt_u32_e64 s[30:31], s98, v85
	v_cndmask_b32_e64 v33, 0, v33, s[36:37]
	v_add_u32_e32 v86, 144, v84
	v_cmp_gt_u32_e64 s[36:37], s98, v86
	v_cndmask_b32_e64 v34, 0, v34, s[78:79]
	v_add_u32_e32 v87, 160, v84
	v_cmp_gt_u32_e64 s[78:79], s98, v87
	v_cndmask_b32_e64 v35, 0, v35, s[50:51]
	v_add_u32_e32 v88, 176, v84
	v_cmp_gt_u32_e64 s[50:51], s98, v88
	v_cndmask_b32_e64 v36, 0, v36, s[30:31]
	v_add_u32_e32 v85, 256, v84
	v_cmp_gt_u32_e64 s[30:31], s98, v85
	v_cndmask_b32_e64 v37, 0, v37, s[36:37]
	v_add_u32_e32 v86, 272, v84
	v_cmp_gt_u32_e64 s[36:37], s98, v86
	v_cndmask_b32_e64 v38, 0, v38, s[78:79]
	v_add_u32_e32 v87, 288, v84
	v_cmp_gt_u32_e64 s[78:79], s98, v87
	v_cndmask_b32_e64 v39, 0, v39, s[50:51]
	v_add_u32_e32 v88, 304, v84
	v_cmp_gt_u32_e64 s[50:51], s98, v88
	v_cndmask_b32_e64 v40, 0, v40, s[30:31]
	v_add_u32_e32 v85, 384, v84
	v_cmp_gt_u32_e64 s[30:31], s98, v85
	v_cndmask_b32_e64 v41, 0, v41, s[36:37]
	v_add_u32_e32 v86, 400, v84
	v_cmp_gt_u32_e64 s[36:37], s98, v86
	v_cndmask_b32_e64 v42, 0, v42, s[78:79]
	v_add_u32_e32 v87, 416, v84
	v_cmp_gt_u32_e64 s[78:79], s98, v87
	v_cndmask_b32_e64 v43, 0, v43, s[50:51]
	v_add_u32_e32 v88, 432, v84
	v_cmp_gt_u32_e64 s[50:51], s98, v88
	v_nop
	v_cndmask_b32_e64 v44, 0, v44, s[30:31]
	v_cndmask_b32_e64 v45, 0, v45, s[36:37]
	v_cndmask_b32_e64 v46, 0, v46, s[78:79]
	v_cndmask_b32_e64 v47, 0, v47, s[50:51]
	v_cvt_pk_bf16_f32 v64, v32, v33
	v_cvt_pk_bf16_f32 v65, v34, v35
	v_cvt_pk_bf16_f32 v66, v36, v37
	v_cvt_pk_bf16_f32 v67, v38, v39
	v_cvt_pk_bf16_f32 v68, v40, v41
	v_cvt_pk_bf16_f32 v69, v42, v43
	v_cvt_pk_bf16_f32 v70, v44, v45
	v_cvt_pk_bf16_f32 v71, v46, v47
	v_pk_add_f32 v[232:233], v[232:233], v[32:33]
	v_pk_add_f32 v[232:233], v[232:233], v[34:35]
	v_pk_add_f32 v[232:233], v[232:233], v[36:37]
	v_pk_add_f32 v[232:233], v[232:233], v[38:39]
	v_pk_add_f32 v[232:233], v[232:233], v[40:41]
	v_pk_add_f32 v[232:233], v[232:233], v[42:43]
	v_pk_add_f32 v[232:233], v[232:233], v[44:45]
	v_pk_add_f32 v[232:233], v[232:233], v[46:47]
	s_waitcnt lgkmcnt(0)
	v_mfma_f32_32x32x16_bf16 v[0:15], v[64:67], v[72:75], v[0:15]
	v_mfma_f32_32x32x16_bf16 v[16:31], v[64:67], v[76:79], v[16:31]
	v_mfma_f32_32x32x16_bf16 v[0:15], v[68:71], v[220:223], v[0:15]
	v_mfma_f32_32x32x16_bf16 v[16:31], v[68:71], v[224:227], v[16:31]
	v_add_f32_e32 v113, v232, v233
	v_or_b32_e32 v114, 1, v107
	v_or_b32_e32 v97, 2, v107
	v_or_b32_e32 v96, 3, v107
	v_or_b32_e32 v95, 8, v107
	v_or_b32_e32 v94, 9, v107
	v_or_b32_e32 v93, 10, v107
	v_or_b32_e32 v92, 11, v107
	v_or_b32_e32 v91, 16, v107
	v_or_b32_e32 v90, 17, v107
	v_or_b32_e32 v89, 18, v107
	v_or_b32_e32 v88, 19, v107
	v_or_b32_e32 v87, 24, v107
	v_or_b32_e32 v86, 25, v107
	v_or_b32_e32 v85, 26, v107
	v_or_b32_e32 v84, 27, v107
	s_nop 11
	s_branch .LBB0_553

; #define LAS __attribute__((address_space(3)))
; #define GAS __attribute__((address_space(1)))
; __device__ __forceinline__ void dil_unit(LAS unsigned char* lds, bf16_t* proj, int seq, int hd, int T0, int rho) {
;     int tid_ = threadIdx.x; asm volatile("" : "+v"(tid_));
;     const int tid = tid_, lane = tid & 63, r32 = lane & 31, hi = lane >> 5, wid = __builtin_amdgcn_readfirstlane(tid >> 6);
;     bf16_t* base = proj + (size_t)seq * SEQ * NIN;
;     LAS unsigned char* wbuf = lds + wid * 4096;
;     const LAS unsigned char* vp = wbuf + ((lane >> 4) & 1) * 32 + (lane & 3) * 8 + (4 * hi + ((lane & 15) >> 2)) * 64;
;     const int P0 = T0 + rho;
;     bf16x8 qr[4];
; #pragma unroll
;     for (int ks = 0; ks < 4; ++ks) qr[ks] = *(const GAS bf16x8*)(base + (size_t)(P0 + 16 * r32) * NIN + PC_LQ + hd * 64 + 16 * ks + 8 * hi);
;     f32x16 o0 = {}, o1 = {}; float l = 0.f;
;     const bool bound = (T0 < 1024) || (T0 >= 15360);
; __device__ __forceinline__ void attn_phase(unsigned char* ws, int l, LAS unsigned char* lds, int G) {
;     ...
;     for (int bu = vb; bu < 1152; bu += G) {
;         const int sh = bu >> 6, rem = bu & 63, T0 = (rem >> 1) * 512, rho = (rem & 1) * 8 + wid;
;         dil_unit(lds, proj, sh / 6, sh % 6, T0, rho);
.LBB0_1266:
	s_lshr_b32 s82, s60, 8
	s_mul_i32 s82, s82, 13
	s_add_i32 s82, s82, s60
	s_ashr_i32 s4, s60, 6
	s_mul_hi_i32 s9, s4, 0x2aaaaaab
	s_lshl_b32 s5, s82, 8
	s_lshr_b32 s10, s9, 31
	s_and_b32 s8, s5, 0x3e00
	s_lshl_b32 s5, s82, 3
	s_add_i32 s9, s9, s10
	s_and_b32 s5, s5, 8
	s_mul_i32 s10, s9, 6
	s_add_i32 s5, s5, s61
	s_sub_i32 s10, s4, s10
	s_mul_hi_i32 s4, s9, 0x6000000
	s_mul_i32 s9, s9, 0x6000000
	v_mov_b32_e32 v2, v154
	s_add_u32 s52, s44, s9
	s_addc_u32 s53, s45, s4
	v_and_b32_e32 v105, 31, v2
	s_add_i32 s67, s5, s8
	v_lshl_add_u32 v3, v105, 4, s67
	v_mov_b64_e32 v[0:1], s[52:53]
	s_lshl_b32 s54, s10, 6
	v_bfe_u32 v106, v2, 5, 1
	v_mad_u64_u32 v[0:1], s[4:5], v3, s62, v[0:1]
	s_ashr_i32 s55, s54, 31
	v_lshl_add_u64 v[0:1], s[54:55], 1, v[0:1]
	v_lshlrev_b32_e32 v80, 4, v106
	v_lshl_add_u64 v[0:1], v[0:1], 0, v[80:81]
	global_load_dwordx4 v[48:51], v[0:1], off offset:1280
	global_load_dwordx4 v[52:55], v[0:1], off offset:1312
	global_load_dwordx4 v[56:59], v[0:1], off offset:1344
	global_load_dwordx4 v[60:63], v[0:1], off offset:1376
	v_readfirstlane_b32 s4, v2
	s_lshl_b32 s4, s4, 6
	s_and_b32 s4, s4, 0xfffff000
	v_lshlrev_b32_e32 v0, 1, v2
	v_lshlrev_b32_e32 v104, 3, v2
	v_lshlrev_b32_e32 v107, 2, v106
	v_lshrrev_b32_e32 v1, 2, v2
	v_and_b32_e32 v103, 63, v2
	v_and_b32_e32 v0, 32, v0
	v_and_b32_e32 v98, 24, v104
	v_and_or_b32 v1, v1, 3, v107
	s_add_i32 s69, s4, 0
	v_lshlrev_b32_e32 v108, 6, v1
	v_lshlrev_b32_e32 v1, 3, v106
	v_add3_u32 v109, s69, v0, v98
	s_addk_i32 s8, 0xc400
	v_lshrrev_b32_e32 v110, 2, v103
	v_lshlrev_b32_e32 v0, 4, v103
	s_mov_b64 s[4:5], -1
	s_cmp_gt_u32 s8, 0xffffc7ff
	v_lshlrev_b32_e32 v100, 1, v98
	s_mul_i32 s8, s10, 0x1c00
	v_lshlrev_b32_e32 v82, 1, v1
	v_or_b32_e32 v111, 16, v110
	v_add_u32_e32 v112, s69, v0
	s_cbranch_scc0 .LBB0_1270
	s_movk_i32 s100, 0x1800
	s_add_i32 s101, s8, 0x15c00
	s_lshl_b32 s90, s54, 1
	s_add_u32 s82, s52, s90
	s_addc_u32 s83, s53, 0
	s_add_u32 s82, s82, 0x1200
	s_addc_u32 s83, s83, 0
	s_sub_i32 s90, s67, 64
	s_mul_i32 s90, s90, 0x1800
	s_add_u32 s84, s82, s90
	s_addc_u32 s85, s83, 0
	s_sub_i32 s90, s67, 256
	s_mul_i32 s90, s90, 0x1800
	s_add_u32 s86, s82, s90
	s_addc_u32 s87, s83, 0
	s_sub_i32 s90, s67, 1024
	s_mul_i32 s90, s90, 0x1800
	s_add_u32 s88, s82, s90
	s_addc_u32 s89, s83, 0
	v_lshlrev_b32_e32 v153, 1, v98
	v_mad_u32_u24 v80, v105, s100, v82
	v_mad_u32_u24 v100, v110, s100, v153
	v_add_u32_e32 v149, 0x18000, v100
	v_lshlrev_b32_e32 v83, 2, v105
	v_mad_u32_u24 v83, v83, s100, v82
	v_lshlrev_b32_e32 v101, 2, v110
	v_mad_u32_u24 v101, v101, s100, v153
	v_add_u32_e32 v150, 0x60000, v101
	v_lshlrev_b32_e32 v99, 4, v105
	v_mad_u32_u24 v99, v99, s100, v82
	v_lshlrev_b32_e32 v148, 4, v110
	v_mad_u32_u24 v148, v148, s100, v153
	v_add_u32_e32 v151, 0x180000, v148
	v_lshrrev_b32_e32 v249, 3, v103
	v_and_b32_e32 v250, 7, v103
	v_lshlrev_b32_e32 v250, 4, v250
	v_add_u32_e32 v235, 0, v249
	v_mad_u32_u24 v235, v235, s100, v250
	v_add_u32_e32 v236, 8, v249
	v_mad_u32_u24 v236, v236, s100, v250
	v_add_u32_e32 v237, 16, v249
	v_mad_u32_u24 v237, v237, s100, v250
	v_add_u32_e32 v238, 24, v249
	v_mad_u32_u24 v238, v238, s100, v250
	v_add_u32_e32 v239, 0, v249
	v_lshlrev_b32_e32 v239, 2, v239
	v_mad_u32_u24 v239, v239, s100, v250
	v_add_u32_e32 v240, 8, v249
	v_lshlrev_b32_e32 v240, 2, v240
	v_mad_u32_u24 v240, v240, s100, v250
	v_add_u32_e32 v241, 16, v249
	v_lshlrev_b32_e32 v241, 2, v241
	v_mad_u32_u24 v241, v241, s100, v250
	v_add_u32_e32 v242, 24, v249
	v_lshlrev_b32_e32 v242, 2, v242
	v_mad_u32_u24 v242, v242, s100, v250
	v_add_u32_e32 v243, 0, v249
	v_lshlrev_b32_e32 v243, 4, v243
	v_mad_u32_u24 v243, v243, s100, v250
	v_add_u32_e32 v244, 8, v249
	v_lshlrev_b32_e32 v244, 4, v244
	v_mad_u32_u24 v244, v244, s100, v250
	v_add_u32_e32 v245, 16, v249
	v_lshlrev_b32_e32 v245, 4, v245
	v_mad_u32_u24 v245, v245, s100, v250
	v_add_u32_e32 v246, 24, v249
	v_lshlrev_b32_e32 v246, 4, v246
	v_mad_u32_u24 v246, v246, s100, v250
	v_and_b32_e32 v247, 7, v249
	v_lshlrev_b32_e32 v247, 4, v247
	v_xor_b32_e32 v247, v247, v112
	v_and_b32_e32 v153, 7, v105
	v_or_b32_e32 v248, 0, v106
	v_xor_b32_e32 v248, v248, v153
	v_lshlrev_b32_e32 v248, 4, v248
	v_lshl_add_u32 v248, v105, 7, v248
	v_add_u32_e32 v248, s69, v248
	v_or_b32_e32 v249, 2, v106
	v_xor_b32_e32 v249, v249, v153
	v_lshlrev_b32_e32 v249, 4, v249
	v_lshl_add_u32 v249, v105, 7, v249
	v_add_u32_e32 v249, s69, v249
	v_or_b32_e32 v250, 4, v106
	v_xor_b32_e32 v250, v250, v153
	v_lshlrev_b32_e32 v250, 4, v250
	v_lshl_add_u32 v250, v105, 7, v250
	v_add_u32_e32 v250, s69, v250
	v_or_b32_e32 v251, 6, v106
	v_xor_b32_e32 v251, v251, v153
	v_lshlrev_b32_e32 v251, 4, v251
	v_lshl_add_u32 v251, v105, 7, v251
	v_add_u32_e32 v251, s69, v251
	v_lshlrev_b32_e32 v153, 1, v98
	v_mul_u32_u24_e32 v228, 17, v105
	v_sub_u32_e32 v228, v107, v228
	s_mul_i32 s90, s54, 153
	s_lshr_b32 s90, s90, 1
	s_add_i32 s90, s90, 34876
	v_lshl_add_u32 v228, v228, 2, s90
	v_lshlrev_b32_e32 v229, 2, v105
	v_sub_u32_e32 v229, v107, v229
	s_add_i32 s90, s101, 5104
	v_lshl_add_u32 v229, v229, 2, s90
	v_sub_u32_e32 v230, v107, v105
	s_add_i32 s90, s101, 6364
	v_lshl_add_u32 v230, v230, 2, s90
	v_add_u32_e32 v231, v109, v108
	v_mov_b64_e32 v[232:233], 0
	v_mov_b64_e32 v[0:1], 0
	v_mov_b64_e32 v[2:3], 0
	v_mov_b64_e32 v[4:5], 0
	v_mov_b64_e32 v[6:7], 0
	v_mov_b64_e32 v[8:9], 0
	v_mov_b64_e32 v[10:11], 0
	v_mov_b64_e32 v[12:13], 0
	v_mov_b64_e32 v[14:15], 0
	v_mov_b64_e32 v[16:17], 0
	v_mov_b64_e32 v[18:19], 0
	v_mov_b64_e32 v[20:21], 0
	v_mov_b64_e32 v[22:23], 0
	v_mov_b64_e32 v[24:25], 0
	v_mov_b64_e32 v[26:27], 0
	v_mov_b64_e32 v[28:29], 0
	v_mov_b64_e32 v[30:31], 0
	global_load_dwordx4 v[116:119], v235, s[84:85]
	global_load_dwordx4 v[120:123], v236, s[84:85]
	global_load_dwordx4 v[124:127], v237, s[84:85]
	global_load_dwordx4 v[128:131], v238, s[84:85]
	global_load_dwordx4 v[132:135], v100, s[84:85] offset:768
	global_load_dwordx4 v[136:139], v149, s[84:85] offset:768
	global_load_dwordx4 v[140:143], v100, s[84:85] offset:832
	global_load_dwordx4 v[144:147], v149, s[84:85] offset:832
	s_add_u32 s84, s84, 0x30000
	s_addc_u32 s85, s85, 0
	global_load_dwordx4 v[156:159], v235, s[84:85]
	global_load_dwordx4 v[160:163], v236, s[84:85]
	global_load_dwordx4 v[164:167], v237, s[84:85]
	global_load_dwordx4 v[168:171], v238, s[84:85]
	global_load_dwordx4 v[172:175], v100, s[84:85] offset:768
	global_load_dwordx4 v[176:179], v149, s[84:85] offset:768
	global_load_dwordx4 v[180:183], v100, s[84:85] offset:832
	global_load_dwordx4 v[184:187], v149, s[84:85] offset:832
	s_add_u32 s84, s84, 0x30000
	s_addc_u32 s85, s85, 0
	global_load_dwordx4 v[188:191], v235, s[84:85]
	global_load_dwordx4 v[192:195], v236, s[84:85]
	global_load_dwordx4 v[196:199], v237, s[84:85]
	global_load_dwordx4 v[200:203], v238, s[84:85]
	global_load_dwordx4 v[204:207], v100, s[84:85] offset:768
	global_load_dwordx4 v[208:211], v149, s[84:85] offset:768
	global_load_dwordx4 v[212:215], v100, s[84:85] offset:832
	global_load_dwordx4 v[216:219], v149, s[84:85] offset:832
	s_add_u32 s84, s84, 0x30000
	s_addc_u32 s85, s85, 0
	s_waitcnt vmcnt(16)
	ds_write_b128 v247, v[116:119]
	ds_write_b128 v247, v[120:123] offset:1024
	ds_write_b128 v247, v[124:127] offset:2048
	ds_write_b128 v247, v[128:131] offset:3072
	ds_read_b128 v[116:119], v248
	ds_read_b128 v[120:123], v249
	ds_read_b128 v[124:127], v250
	ds_read_b128 v[128:131], v251
	ds_write_b128 v112, v[132:135]
	ds_write_b128 v112, v[136:139] offset:1024
	ds_write_b128 v112, v[140:143] offset:2048
	ds_write_b128 v112, v[144:147] offset:3072
	v_mov_b32_e32 v115, v228
	ds_read2_b32 v[32:33], v115 offset0:0 offset1:1
	ds_read2_b32 v[34:35], v115 offset0:2 offset1:3
	ds_read2_b32 v[36:37], v115 offset0:8 offset1:9
	ds_read2_b32 v[38:39], v115 offset0:10 offset1:11
	ds_read2_b32 v[40:41], v115 offset0:17 offset1:18
	ds_read2_b32 v[42:43], v115 offset0:19 offset1:20
	ds_read2_b32 v[44:45], v115 offset0:25 offset1:26
	ds_read2_b32 v[46:47], v115 offset0:27 offset1:28
	s_waitcnt lgkmcnt(0)
	v_mfma_f32_32x32x16_bf16 v[32:47], v[116:119], v[48:51], v[32:47]
	ds_read_b64_tr_b16 v[72:73], v231
	ds_read_b64_tr_b16 v[74:75], v231 offset:512
	ds_read_b64_tr_b16 v[76:77], v231 offset:2048
	ds_read_b64_tr_b16 v[78:79], v231 offset:2560
	ds_read_b64_tr_b16 v[220:221], v231 offset:1024
	ds_read_b64_tr_b16 v[222:223], v231 offset:1536
	ds_read_b64_tr_b16 v[224:225], v231 offset:3072
	ds_read_b64_tr_b16 v[226:227], v231 offset:3584
	s_waitcnt vmcnt(8)
	ds_write_b128 v247, v[156:159]
	ds_write_b128 v247, v[160:163] offset:1024
	ds_write_b128 v247, v[164:167] offset:2048
	ds_write_b128 v247, v[168:171] offset:3072
	ds_read_b128 v[156:159], v248
	ds_read_b128 v[160:163], v249
	ds_read_b128 v[164:167], v250
	ds_read_b128 v[168:171], v251
	ds_write_b128 v112, v[172:175]
	ds_write_b128 v112, v[176:179] offset:1024
	ds_write_b128 v112, v[180:183] offset:2048
	ds_write_b128 v112, v[184:187] offset:3072
	v_mfma_f32_32x32x16_bf16 v[32:47], v[120:123], v[52:55], v[32:47]
	v_mfma_f32_32x32x16_bf16 v[32:47], v[124:127], v[56:59], v[32:47]
	v_mfma_f32_32x32x16_bf16 v[32:47], v[128:131], v[60:63], v[32:47]
	s_nop 11
	v_exp_f32_e32 v32, v32
	v_exp_f32_e32 v33, v33
	v_exp_f32_e32 v34, v34
	v_exp_f32_e32 v35, v35
	v_exp_f32_e32 v36, v36
	v_exp_f32_e32 v37, v37
	v_exp_f32_e32 v38, v38
	v_exp_f32_e32 v39, v39
	v_exp_f32_e32 v40, v40
	v_exp_f32_e32 v41, v41
	v_exp_f32_e32 v42, v42
	v_exp_f32_e32 v43, v43
	v_exp_f32_e32 v44, v44
	v_exp_f32_e32 v45, v45
	v_exp_f32_e32 v46, v46
	v_exp_f32_e32 v47, v47
	v_cvt_pk_bf16_f32 v64, v32, v33
	v_cvt_pk_bf16_f32 v65, v34, v35
	v_cvt_pk_bf16_f32 v66, v36, v37
	v_cvt_pk_bf16_f32 v67, v38, v39
	v_cvt_pk_bf16_f32 v68, v40, v41
	v_cvt_pk_bf16_f32 v69, v42, v43
	v_cvt_pk_bf16_f32 v70, v44, v45
	v_cvt_pk_bf16_f32 v71, v46, v47
	v_pk_add_f32 v[232:233], v[232:233], v[32:33]
	v_pk_add_f32 v[232:233], v[232:233], v[34:35]
	v_pk_add_f32 v[232:233], v[232:233], v[36:37]
	v_pk_add_f32 v[232:233], v[232:233], v[38:39]
	v_pk_add_f32 v[232:233], v[232:233], v[40:41]
	v_pk_add_f32 v[232:233], v[232:233], v[42:43]
	v_pk_add_f32 v[232:233], v[232:233], v[44:45]
	v_pk_add_f32 v[232:233], v[232:233], v[46:47]
	s_waitcnt lgkmcnt(12)
	v_mfma_f32_32x32x16_bf16 v[0:15], v[64:67], v[72:75], v[0:15]
	v_mfma_f32_32x32x16_bf16 v[16:31], v[64:67], v[76:79], v[16:31]
	v_mfma_f32_32x32x16_bf16 v[0:15], v[68:71], v[220:223], v[0:15]
	v_mfma_f32_32x32x16_bf16 v[16:31], v[68:71], v[224:227], v[16:31]
	global_load_dwordx4 v[116:119], v235, s[84:85]
	global_load_dwordx4 v[120:123], v236, s[84:85]
	global_load_dwordx4 v[124:127], v237, s[84:85]
	global_load_dwordx4 v[128:131], v238, s[84:85]
	global_load_dwordx4 v[132:135], v100, s[84:85] offset:768
	global_load_dwordx4 v[136:139], v149, s[84:85] offset:768
	global_load_dwordx4 v[140:143], v100, s[84:85] offset:832
	global_load_dwordx4 v[144:147], v149, s[84:85] offset:832
	s_add_u32 s84, s84, 0x30000
	s_addc_u32 s85, s85, 0
	ds_read2_b32 v[32:33], v115 offset0:34 offset1:35
	ds_read2_b32 v[34:35], v115 offset0:36 offset1:37
	ds_read2_b32 v[36:37], v115 offset0:42 offset1:43
	ds_read2_b32 v[38:39], v115 offset0:44 offset1:45
	ds_read2_b32 v[40:41], v115 offset0:51 offset1:52
	ds_read2_b32 v[42:43], v115 offset0:53 offset1:54
	ds_read2_b32 v[44:45], v115 offset0:59 offset1:60
	ds_read2_b32 v[46:47], v115 offset0:61 offset1:62
	s_waitcnt lgkmcnt(0)
	v_mfma_f32_32x32x16_bf16 v[32:47], v[156:159], v[48:51], v[32:47]
	ds_read_b64_tr_b16 v[72:73], v231
	ds_read_b64_tr_b16 v[74:75], v231 offset:512
	ds_read_b64_tr_b16 v[76:77], v231 offset:2048
	ds_read_b64_tr_b16 v[78:79], v231 offset:2560
	ds_read_b64_tr_b16 v[220:221], v231 offset:1024
	ds_read_b64_tr_b16 v[222:223], v231 offset:1536
	ds_read_b64_tr_b16 v[224:225], v231 offset:3072
	ds_read_b64_tr_b16 v[226:227], v231 offset:3584
	s_waitcnt vmcnt(8)
	ds_write_b128 v247, v[188:191]
	ds_write_b128 v247, v[192:195] offset:1024
	ds_write_b128 v247, v[196:199] offset:2048
	ds_write_b128 v247, v[200:203] offset:3072
	ds_read_b128 v[188:191], v248
	ds_read_b128 v[192:195], v249
	ds_read_b128 v[196:199], v250
	ds_read_b128 v[200:203], v251
	ds_write_b128 v112, v[204:207]
	ds_write_b128 v112, v[208:211] offset:1024
	ds_write_b128 v112, v[212:215] offset:2048
	ds_write_b128 v112, v[216:219] offset:3072
	v_mfma_f32_32x32x16_bf16 v[32:47], v[160:163], v[52:55], v[32:47]
	v_mfma_f32_32x32x16_bf16 v[32:47], v[164:167], v[56:59], v[32:47]
	v_mfma_f32_32x32x16_bf16 v[32:47], v[168:171], v[60:63], v[32:47]
	s_nop 11
	v_exp_f32_e32 v32, v32
	v_exp_f32_e32 v33, v33
	v_exp_f32_e32 v34, v34
	v_exp_f32_e32 v35, v35
	v_exp_f32_e32 v36, v36
	v_exp_f32_e32 v37, v37
	v_exp_f32_e32 v38, v38
	v_exp_f32_e32 v39, v39
	v_exp_f32_e32 v40, v40
	v_exp_f32_e32 v41, v41
	v_exp_f32_e32 v42, v42
	v_exp_f32_e32 v43, v43
	v_exp_f32_e32 v44, v44
	v_exp_f32_e32 v45, v45
	v_exp_f32_e32 v46, v46
	v_exp_f32_e32 v47, v47
	v_cvt_pk_bf16_f32 v64, v32, v33
	v_cvt_pk_bf16_f32 v65, v34, v35
	v_cvt_pk_bf16_f32 v66, v36, v37
	v_cvt_pk_bf16_f32 v67, v38, v39
	v_cvt_pk_bf16_f32 v68, v40, v41
	v_cvt_pk_bf16_f32 v69, v42, v43
	v_cvt_pk_bf16_f32 v70, v44, v45
	v_cvt_pk_bf16_f32 v71, v46, v47
	v_pk_add_f32 v[232:233], v[232:233], v[32:33]
	v_pk_add_f32 v[232:233], v[232:233], v[34:35]
	v_pk_add_f32 v[232:233], v[232:233], v[36:37]
	v_pk_add_f32 v[232:233], v[232:233], v[38:39]
	v_pk_add_f32 v[232:233], v[232:233], v[40:41]
	v_pk_add_f32 v[232:233], v[232:233], v[42:43]
	v_pk_add_f32 v[232:233], v[232:233], v[44:45]
	v_pk_add_f32 v[232:233], v[232:233], v[46:47]
	s_waitcnt lgkmcnt(12)
	v_mfma_f32_32x32x16_bf16 v[0:15], v[64:67], v[72:75], v[0:15]
	v_mfma_f32_32x32x16_bf16 v[16:31], v[64:67], v[76:79], v[16:31]
	v_mfma_f32_32x32x16_bf16 v[0:15], v[68:71], v[220:223], v[0:15]
	v_mfma_f32_32x32x16_bf16 v[16:31], v[68:71], v[224:227], v[16:31]
	global_load_dwordx4 v[156:159], v235, s[84:85]
	global_load_dwordx4 v[160:163], v236, s[84:85]
	global_load_dwordx4 v[164:167], v237, s[84:85]
	global_load_dwordx4 v[168:171], v238, s[84:85]
	global_load_dwordx4 v[172:175], v100, s[84:85] offset:768
	global_load_dwordx4 v[176:179], v149, s[84:85] offset:768
	global_load_dwordx4 v[180:183], v100, s[84:85] offset:832
	global_load_dwordx4 v[184:187], v149, s[84:85] offset:832
	s_add_u32 s84, s84, 0x30000
	s_addc_u32 s85, s85, 0
	ds_read2_b32 v[32:33], v115 offset0:68 offset1:69
	ds_read2_b32 v[34:35], v115 offset0:70 offset1:71
	ds_read2_b32 v[36:37], v115 offset0:76 offset1:77
	ds_read2_b32 v[38:39], v115 offset0:78 offset1:79
	ds_read2_b32 v[40:41], v115 offset0:85 offset1:86
	ds_read2_b32 v[42:43], v115 offset0:87 offset1:88
	ds_read2_b32 v[44:45], v115 offset0:93 offset1:94
	ds_read2_b32 v[46:47], v115 offset0:95 offset1:96
	s_waitcnt lgkmcnt(0)
	v_mfma_f32_32x32x16_bf16 v[32:47], v[188:191], v[48:51], v[32:47]
	ds_read_b64_tr_b16 v[72:73], v231
	ds_read_b64_tr_b16 v[74:75], v231 offset:512
	ds_read_b64_tr_b16 v[76:77], v231 offset:2048
	ds_read_b64_tr_b16 v[78:79], v231 offset:2560
	ds_read_b64_tr_b16 v[220:221], v231 offset:1024
	ds_read_b64_tr_b16 v[222:223], v231 offset:1536
	ds_read_b64_tr_b16 v[224:225], v231 offset:3072
	ds_read_b64_tr_b16 v[226:227], v231 offset:3584
	s_waitcnt vmcnt(8)
	ds_write_b128 v247, v[116:119]
	ds_write_b128 v247, v[120:123] offset:1024
	ds_write_b128 v247, v[124:127] offset:2048
	ds_write_b128 v247, v[128:131] offset:3072
	ds_read_b128 v[116:119], v248
	ds_read_b128 v[120:123], v249
	ds_read_b128 v[124:127], v250
	ds_read_b128 v[128:131], v251
	ds_write_b128 v112, v[132:135]
	ds_write_b128 v112, v[136:139] offset:1024
	ds_write_b128 v112, v[140:143] offset:2048
	ds_write_b128 v112, v[144:147] offset:3072
	v_mfma_f32_32x32x16_bf16 v[32:47], v[192:195], v[52:55], v[32:47]
	v_mfma_f32_32x32x16_bf16 v[32:47], v[196:199], v[56:59], v[32:47]
	v_mfma_f32_32x32x16_bf16 v[32:47], v[200:203], v[60:63], v[32:47]
	s_nop 11
	v_exp_f32_e32 v32, v32
	v_exp_f32_e32 v33, v33
	v_exp_f32_e32 v34, v34
	v_exp_f32_e32 v35, v35
	v_exp_f32_e32 v36, v36
	v_exp_f32_e32 v37, v37
	v_exp_f32_e32 v38, v38
	v_exp_f32_e32 v39, v39
	v_exp_f32_e32 v40, v40
	v_exp_f32_e32 v41, v41
	v_exp_f32_e32 v42, v42
	v_exp_f32_e32 v43, v43
	v_exp_f32_e32 v44, v44
	v_exp_f32_e32 v45, v45
	v_exp_f32_e32 v46, v46
	v_exp_f32_e32 v47, v47
	v_cvt_pk_bf16_f32 v64, v32, v33
	v_cvt_pk_bf16_f32 v65, v34, v35
	v_cvt_pk_bf16_f32 v66, v36, v37
	v_cvt_pk_bf16_f32 v67, v38, v39
	v_cvt_pk_bf16_f32 v68, v40, v41
	v_cvt_pk_bf16_f32 v69, v42, v43
	v_cvt_pk_bf16_f32 v70, v44, v45
	v_cvt_pk_bf16_f32 v71, v46, v47
	v_pk_add_f32 v[232:233], v[232:233], v[32:33]
	v_pk_add_f32 v[232:233], v[232:233], v[34:35]
	v_pk_add_f32 v[232:233], v[232:233], v[36:37]
	v_pk_add_f32 v[232:233], v[232:233], v[38:39]
	v_pk_add_f32 v[232:233], v[232:233], v[40:41]
	v_pk_add_f32 v[232:233], v[232:233], v[42:43]
	v_pk_add_f32 v[232:233], v[232:233], v[44:45]
	v_pk_add_f32 v[232:233], v[232:233], v[46:47]
	s_waitcnt lgkmcnt(12)
	v_mfma_f32_32x32x16_bf16 v[0:15], v[64:67], v[72:75], v[0:15]
	v_mfma_f32_32x32x16_bf16 v[16:31], v[64:67], v[76:79], v[16:31]
	v_mfma_f32_32x32x16_bf16 v[0:15], v[68:71], v[220:223], v[0:15]
	v_mfma_f32_32x32x16_bf16 v[16:31], v[68:71], v[224:227], v[16:31]
	global_load_dwordx4 v[188:191], v235, s[84:85]
	global_load_dwordx4 v[192:195], v236, s[84:85]
	global_load_dwordx4 v[196:199], v237, s[84:85]
	global_load_dwordx4 v[200:203], v238, s[84:85]
	global_load_dwordx4 v[204:207], v100, s[84:85] offset:768
	global_load_dwordx4 v[208:211], v149, s[84:85] offset:768
	global_load_dwordx4 v[212:215], v100, s[84:85] offset:832
	global_load_dwordx4 v[216:219], v149, s[84:85] offset:832
	s_add_u32 s84, s84, 0x30000
	s_addc_u32 s85, s85, 0
	ds_read2_b32 v[32:33], v115 offset0:102 offset1:103
	ds_read2_b32 v[34:35], v115 offset0:104 offset1:105
	ds_read2_b32 v[36:37], v115 offset0:110 offset1:111
	ds_read2_b32 v[38:39], v115 offset0:112 offset1:113
	ds_read2_b32 v[40:41], v115 offset0:119 offset1:120
	ds_read2_b32 v[42:43], v115 offset0:121 offset1:122
	ds_read2_b32 v[44:45], v115 offset0:127 offset1:128
	ds_read2_b32 v[46:47], v115 offset0:129 offset1:130
	s_waitcnt lgkmcnt(0)
	v_mfma_f32_32x32x16_bf16 v[32:47], v[116:119], v[48:51], v[32:47]
	ds_read_b64_tr_b16 v[72:73], v231
	ds_read_b64_tr_b16 v[74:75], v231 offset:512
	ds_read_b64_tr_b16 v[76:77], v231 offset:2048
	ds_read_b64_tr_b16 v[78:79], v231 offset:2560
	ds_read_b64_tr_b16 v[220:221], v231 offset:1024
	ds_read_b64_tr_b16 v[222:223], v231 offset:1536
	ds_read_b64_tr_b16 v[224:225], v231 offset:3072
	ds_read_b64_tr_b16 v[226:227], v231 offset:3584
	s_waitcnt vmcnt(8)
	ds_write_b128 v247, v[156:159]
	ds_write_b128 v247, v[160:163] offset:1024
	ds_write_b128 v247, v[164:167] offset:2048
	ds_write_b128 v247, v[168:171] offset:3072
	ds_read_b128 v[156:159], v248
	ds_read_b128 v[160:163], v249
	ds_read_b128 v[164:167], v250
	ds_read_b128 v[168:171], v251
	ds_write_b128 v112, v[172:175]
	ds_write_b128 v112, v[176:179] offset:1024
	ds_write_b128 v112, v[180:183] offset:2048
	ds_write_b128 v112, v[184:187] offset:3072
	v_mfma_f32_32x32x16_bf16 v[32:47], v[120:123], v[52:55], v[32:47]
	v_mfma_f32_32x32x16_bf16 v[32:47], v[124:127], v[56:59], v[32:47]
	v_mfma_f32_32x32x16_bf16 v[32:47], v[128:131], v[60:63], v[32:47]
	s_nop 11
	v_exp_f32_e32 v32, v32
	v_exp_f32_e32 v33, v33
	v_exp_f32_e32 v34, v34
	v_exp_f32_e32 v35, v35
	v_exp_f32_e32 v36, v36
	v_exp_f32_e32 v37, v37
	v_exp_f32_e32 v38, v38
	v_exp_f32_e32 v39, v39
	v_exp_f32_e32 v40, v40
	v_exp_f32_e32 v41, v41
	v_exp_f32_e32 v42, v42
	v_exp_f32_e32 v43, v43
	v_exp_f32_e32 v44, v44
	v_exp_f32_e32 v45, v45
	v_exp_f32_e32 v46, v46
	v_exp_f32_e32 v47, v47
	v_cvt_pk_bf16_f32 v64, v32, v33
	v_cvt_pk_bf16_f32 v65, v34, v35
	v_cvt_pk_bf16_f32 v66, v36, v37
	v_cvt_pk_bf16_f32 v67, v38, v39
	v_cvt_pk_bf16_f32 v68, v40, v41
	v_cvt_pk_bf16_f32 v69, v42, v43
	v_cvt_pk_bf16_f32 v70, v44, v45
	v_cvt_pk_bf16_f32 v71, v46, v47
	v_pk_add_f32 v[232:233], v[232:233], v[32:33]
	v_pk_add_f32 v[232:233], v[232:233], v[34:35]
	v_pk_add_f32 v[232:233], v[232:233], v[36:37]
	v_pk_add_f32 v[232:233], v[232:233], v[38:39]
	v_pk_add_f32 v[232:233], v[232:233], v[40:41]
	v_pk_add_f32 v[232:233], v[232:233], v[42:43]
	v_pk_add_f32 v[232:233], v[232:233], v[44:45]
	v_pk_add_f32 v[232:233], v[232:233], v[46:47]
	s_waitcnt lgkmcnt(12)
	v_mfma_f32_32x32x16_bf16 v[0:15], v[64:67], v[72:75], v[0:15]
	v_mfma_f32_32x32x16_bf16 v[16:31], v[64:67], v[76:79], v[16:31]
	v_mfma_f32_32x32x16_bf16 v[0:15], v[68:71], v[220:223], v[0:15]
	v_mfma_f32_32x32x16_bf16 v[16:31], v[68:71], v[224:227], v[16:31]
	global_load_dwordx4 v[116:119], v235, s[84:85]
	global_load_dwordx4 v[120:123], v236, s[84:85]
	global_load_dwordx4 v[124:127], v237, s[84:85]
	global_load_dwordx4 v[128:131], v238, s[84:85]
	global_load_dwordx4 v[132:135], v100, s[84:85] offset:768
	global_load_dwordx4 v[136:139], v149, s[84:85] offset:768
	global_load_dwordx4 v[140:143], v100, s[84:85] offset:832
	global_load_dwordx4 v[144:147], v149, s[84:85] offset:832
	s_add_u32 s84, s84, 0x30000
	s_addc_u32 s85, s85, 0
	ds_read2_b32 v[32:33], v115 offset0:136 offset1:137
	ds_read2_b32 v[34:35], v115 offset0:138 offset1:139
	ds_read2_b32 v[36:37], v115 offset0:144 offset1:145
	ds_read2_b32 v[38:39], v115 offset0:146 offset1:147
	ds_read2_b32 v[40:41], v115 offset0:153 offset1:154
	ds_read2_b32 v[42:43], v115 offset0:155 offset1:156
	ds_read2_b32 v[44:45], v115 offset0:161 offset1:162
	ds_read2_b32 v[46:47], v115 offset0:163 offset1:164
	s_waitcnt lgkmcnt(0)
	v_mfma_f32_32x32x16_bf16 v[32:47], v[156:159], v[48:51], v[32:47]
	ds_read_b64_tr_b16 v[72:73], v231
	ds_read_b64_tr_b16 v[74:75], v231 offset:512
	ds_read_b64_tr_b16 v[76:77], v231 offset:2048
	ds_read_b64_tr_b16 v[78:79], v231 offset:2560
	ds_read_b64_tr_b16 v[220:221], v231 offset:1024
	ds_read_b64_tr_b16 v[222:223], v231 offset:1536
	ds_read_b64_tr_b16 v[224:225], v231 offset:3072
	ds_read_b64_tr_b16 v[226:227], v231 offset:3584
	s_waitcnt vmcnt(8)
	ds_write_b128 v247, v[188:191]
	ds_write_b128 v247, v[192:195] offset:1024
	ds_write_b128 v247, v[196:199] offset:2048
	ds_write_b128 v247, v[200:203] offset:3072
	ds_read_b128 v[188:191], v248
	ds_read_b128 v[192:195], v249
	ds_read_b128 v[196:199], v250
	ds_read_b128 v[200:203], v251
	ds_write_b128 v112, v[204:207]
	ds_write_b128 v112, v[208:211] offset:1024
	ds_write_b128 v112, v[212:215] offset:2048
	ds_write_b128 v112, v[216:219] offset:3072
	v_mfma_f32_32x32x16_bf16 v[32:47], v[160:163], v[52:55], v[32:47]
	v_mfma_f32_32x32x16_bf16 v[32:47], v[164:167], v[56:59], v[32:47]
	v_mfma_f32_32x32x16_bf16 v[32:47], v[168:171], v[60:63], v[32:47]
	s_nop 11
	v_exp_f32_e32 v32, v32
	v_exp_f32_e32 v33, v33
	v_exp_f32_e32 v34, v34
	v_exp_f32_e32 v35, v35
	v_exp_f32_e32 v36, v36
	v_exp_f32_e32 v37, v37
	v_exp_f32_e32 v38, v38
	v_exp_f32_e32 v39, v39
	v_exp_f32_e32 v40, v40
	v_exp_f32_e32 v41, v41
	v_exp_f32_e32 v42, v42
	v_exp_f32_e32 v43, v43
	v_exp_f32_e32 v44, v44
	v_exp_f32_e32 v45, v45
	v_exp_f32_e32 v46, v46
	v_exp_f32_e32 v47, v47
	v_cvt_pk_bf16_f32 v64, v32, v33
	v_cvt_pk_bf16_f32 v65, v34, v35
	v_cvt_pk_bf16_f32 v66, v36, v37
	v_cvt_pk_bf16_f32 v67, v38, v39
	v_cvt_pk_bf16_f32 v68, v40, v41
	v_cvt_pk_bf16_f32 v69, v42, v43
	v_cvt_pk_bf16_f32 v70, v44, v45
	v_cvt_pk_bf16_f32 v71, v46, v47
	v_pk_add_f32 v[232:233], v[232:233], v[32:33]
	v_pk_add_f32 v[232:233], v[232:233], v[34:35]
	v_pk_add_f32 v[232:233], v[232:233], v[36:37]
	v_pk_add_f32 v[232:233], v[232:233], v[38:39]
	v_pk_add_f32 v[232:233], v[232:233], v[40:41]
	v_pk_add_f32 v[232:233], v[232:233], v[42:43]
	v_pk_add_f32 v[232:233], v[232:233], v[44:45]
	v_pk_add_f32 v[232:233], v[232:233], v[46:47]
	s_waitcnt lgkmcnt(12)
	v_mfma_f32_32x32x16_bf16 v[0:15], v[64:67], v[72:75], v[0:15]
	v_mfma_f32_32x32x16_bf16 v[16:31], v[64:67], v[76:79], v[16:31]
	v_mfma_f32_32x32x16_bf16 v[0:15], v[68:71], v[220:223], v[0:15]
	v_mfma_f32_32x32x16_bf16 v[16:31], v[68:71], v[224:227], v[16:31]
	global_load_dwordx4 v[156:159], v235, s[84:85]
	global_load_dwordx4 v[160:163], v236, s[84:85]
	global_load_dwordx4 v[164:167], v237, s[84:85]
	global_load_dwordx4 v[168:171], v238, s[84:85]
	global_load_dwordx4 v[172:175], v100, s[84:85] offset:768
	global_load_dwordx4 v[176:179], v149, s[84:85] offset:768
	global_load_dwordx4 v[180:183], v100, s[84:85] offset:832
	global_load_dwordx4 v[184:187], v149, s[84:85] offset:832
	s_add_u32 s84, s84, 0x30000
	s_addc_u32 s85, s85, 0
	ds_read2_b32 v[32:33], v115 offset0:170 offset1:171
	ds_read2_b32 v[34:35], v115 offset0:172 offset1:173
	ds_read2_b32 v[36:37], v115 offset0:178 offset1:179
	ds_read2_b32 v[38:39], v115 offset0:180 offset1:181
	ds_read2_b32 v[40:41], v115 offset0:187 offset1:188
	ds_read2_b32 v[42:43], v115 offset0:189 offset1:190
	ds_read2_b32 v[44:45], v115 offset0:195 offset1:196
	ds_read2_b32 v[46:47], v115 offset0:197 offset1:198
	s_waitcnt lgkmcnt(0)
	v_mfma_f32_32x32x16_bf16 v[32:47], v[188:191], v[48:51], v[32:47]
	ds_read_b64_tr_b16 v[72:73], v231
	ds_read_b64_tr_b16 v[74:75], v231 offset:512
	ds_read_b64_tr_b16 v[76:77], v231 offset:2048
	ds_read_b64_tr_b16 v[78:79], v231 offset:2560
	ds_read_b64_tr_b16 v[220:221], v231 offset:1024
	ds_read_b64_tr_b16 v[222:223], v231 offset:1536
	ds_read_b64_tr_b16 v[224:225], v231 offset:3072
	ds_read_b64_tr_b16 v[226:227], v231 offset:3584
	s_waitcnt vmcnt(8)
	ds_write_b128 v247, v[116:119]
	ds_write_b128 v247, v[120:123] offset:1024
	ds_write_b128 v247, v[124:127] offset:2048
	ds_write_b128 v247, v[128:131] offset:3072
	ds_read_b128 v[116:119], v248
	ds_read_b128 v[120:123], v249
	ds_read_b128 v[124:127], v250
	ds_read_b128 v[128:131], v251
	ds_write_b128 v112, v[132:135]
	ds_write_b128 v112, v[136:139] offset:1024
	ds_write_b128 v112, v[140:143] offset:2048
	ds_write_b128 v112, v[144:147] offset:3072
	v_mfma_f32_32x32x16_bf16 v[32:47], v[192:195], v[52:55], v[32:47]
	v_mfma_f32_32x32x16_bf16 v[32:47], v[196:199], v[56:59], v[32:47]
	v_mfma_f32_32x32x16_bf16 v[32:47], v[200:203], v[60:63], v[32:47]
	s_nop 11
	v_exp_f32_e32 v32, v32
	v_exp_f32_e32 v33, v33
	v_exp_f32_e32 v34, v34
	v_exp_f32_e32 v35, v35
	v_exp_f32_e32 v36, v36
	v_exp_f32_e32 v37, v37
	v_exp_f32_e32 v38, v38
	v_exp_f32_e32 v39, v39
	v_exp_f32_e32 v40, v40
	v_exp_f32_e32 v41, v41
	v_exp_f32_e32 v42, v42
	v_exp_f32_e32 v43, v43
	v_exp_f32_e32 v44, v44
	v_exp_f32_e32 v45, v45
	v_exp_f32_e32 v46, v46
	v_exp_f32_e32 v47, v47
	v_cvt_pk_bf16_f32 v64, v32, v33
	v_cvt_pk_bf16_f32 v65, v34, v35
	v_cvt_pk_bf16_f32 v66, v36, v37
	v_cvt_pk_bf16_f32 v67, v38, v39
	v_cvt_pk_bf16_f32 v68, v40, v41
	v_cvt_pk_bf16_f32 v69, v42, v43
	v_cvt_pk_bf16_f32 v70, v44, v45
	v_cvt_pk_bf16_f32 v71, v46, v47
	v_pk_add_f32 v[232:233], v[232:233], v[32:33]
	v_pk_add_f32 v[232:233], v[232:233], v[34:35]
	v_pk_add_f32 v[232:233], v[232:233], v[36:37]
	v_pk_add_f32 v[232:233], v[232:233], v[38:39]
	v_pk_add_f32 v[232:233], v[232:233], v[40:41]
	v_pk_add_f32 v[232:233], v[232:233], v[42:43]
	v_pk_add_f32 v[232:233], v[232:233], v[44:45]
	v_pk_add_f32 v[232:233], v[232:233], v[46:47]
	s_waitcnt lgkmcnt(12)
	v_mfma_f32_32x32x16_bf16 v[0:15], v[64:67], v[72:75], v[0:15]
	v_mfma_f32_32x32x16_bf16 v[16:31], v[64:67], v[76:79], v[16:31]
	v_mfma_f32_32x32x16_bf16 v[0:15], v[68:71], v[220:223], v[0:15]
	v_mfma_f32_32x32x16_bf16 v[16:31], v[68:71], v[224:227], v[16:31]
	global_load_dwordx4 v[188:191], v235, s[84:85]
	global_load_dwordx4 v[192:195], v236, s[84:85]
	global_load_dwordx4 v[196:199], v237, s[84:85]
	global_load_dwordx4 v[200:203], v238, s[84:85]
	global_load_dwordx4 v[204:207], v100, s[84:85] offset:768
	global_load_dwordx4 v[208:211], v149, s[84:85] offset:768
	global_load_dwordx4 v[212:215], v100, s[84:85] offset:832
	global_load_dwordx4 v[216:219], v149, s[84:85] offset:832
	s_add_u32 s84, s84, 0x30000
	s_addc_u32 s85, s85, 0
	ds_read2_b32 v[32:33], v115 offset0:204 offset1:205
	ds_read2_b32 v[34:35], v115 offset0:206 offset1:207
	ds_read2_b32 v[36:37], v115 offset0:212 offset1:213
	ds_read2_b32 v[38:39], v115 offset0:214 offset1:215
	ds_read2_b32 v[40:41], v115 offset0:221 offset1:222
	ds_read2_b32 v[42:43], v115 offset0:223 offset1:224
	ds_read2_b32 v[44:45], v115 offset0:229 offset1:230
	ds_read2_b32 v[46:47], v115 offset0:231 offset1:232
	s_waitcnt lgkmcnt(0)
	v_mfma_f32_32x32x16_bf16 v[32:47], v[116:119], v[48:51], v[32:47]
	ds_read_b64_tr_b16 v[72:73], v231
	ds_read_b64_tr_b16 v[74:75], v231 offset:512
	ds_read_b64_tr_b16 v[76:77], v231 offset:2048
	ds_read_b64_tr_b16 v[78:79], v231 offset:2560
	ds_read_b64_tr_b16 v[220:221], v231 offset:1024
	ds_read_b64_tr_b16 v[222:223], v231 offset:1536
	ds_read_b64_tr_b16 v[224:225], v231 offset:3072
	ds_read_b64_tr_b16 v[226:227], v231 offset:3584
	s_waitcnt vmcnt(8)
	ds_write_b128 v247, v[156:159]
	ds_write_b128 v247, v[160:163] offset:1024
	ds_write_b128 v247, v[164:167] offset:2048
	ds_write_b128 v247, v[168:171] offset:3072
	ds_read_b128 v[156:159], v248
	ds_read_b128 v[160:163], v249
	ds_read_b128 v[164:167], v250
	ds_read_b128 v[168:171], v251
	ds_write_b128 v112, v[172:175]
	ds_write_b128 v112, v[176:179] offset:1024
	ds_write_b128 v112, v[180:183] offset:2048
	ds_write_b128 v112, v[184:187] offset:3072
	v_mfma_f32_32x32x16_bf16 v[32:47], v[120:123], v[52:55], v[32:47]
	v_mfma_f32_32x32x16_bf16 v[32:47], v[124:127], v[56:59], v[32:47]
	v_mfma_f32_32x32x16_bf16 v[32:47], v[128:131], v[60:63], v[32:47]
	s_nop 11
	v_exp_f32_e32 v32, v32
	v_exp_f32_e32 v33, v33
	v_exp_f32_e32 v34, v34
	v_exp_f32_e32 v35, v35
	v_exp_f32_e32 v36, v36
	v_exp_f32_e32 v37, v37
	v_exp_f32_e32 v38, v38
	v_exp_f32_e32 v39, v39
	v_exp_f32_e32 v40, v40
	v_exp_f32_e32 v41, v41
	v_exp_f32_e32 v42, v42
	v_exp_f32_e32 v43, v43
	v_exp_f32_e32 v44, v44
	v_exp_f32_e32 v45, v45
	v_exp_f32_e32 v46, v46
	v_exp_f32_e32 v47, v47
	v_cvt_pk_bf16_f32 v64, v32, v33
	v_cvt_pk_bf16_f32 v65, v34, v35
	v_cvt_pk_bf16_f32 v66, v36, v37
	v_cvt_pk_bf16_f32 v67, v38, v39
	v_cvt_pk_bf16_f32 v68, v40, v41
	v_cvt_pk_bf16_f32 v69, v42, v43
	v_cvt_pk_bf16_f32 v70, v44, v45
	v_cvt_pk_bf16_f32 v71, v46, v47
	v_pk_add_f32 v[232:233], v[232:233], v[32:33]
	v_pk_add_f32 v[232:233], v[232:233], v[34:35]
	v_pk_add_f32 v[232:233], v[232:233], v[36:37]
	v_pk_add_f32 v[232:233], v[232:233], v[38:39]
	v_pk_add_f32 v[232:233], v[232:233], v[40:41]
	v_pk_add_f32 v[232:233], v[232:233], v[42:43]
	v_pk_add_f32 v[232:233], v[232:233], v[44:45]
	v_pk_add_f32 v[232:233], v[232:233], v[46:47]
	s_waitcnt lgkmcnt(12)
	v_mfma_f32_32x32x16_bf16 v[0:15], v[64:67], v[72:75], v[0:15]
	v_mfma_f32_32x32x16_bf16 v[16:31], v[64:67], v[76:79], v[16:31]
	v_mfma_f32_32x32x16_bf16 v[0:15], v[68:71], v[220:223], v[0:15]
	v_mfma_f32_32x32x16_bf16 v[16:31], v[68:71], v[224:227], v[16:31]
	global_load_dwordx4 v[116:119], v235, s[84:85]
	global_load_dwordx4 v[120:123], v236, s[84:85]
	global_load_dwordx4 v[124:127], v237, s[84:85]
	global_load_dwordx4 v[128:131], v238, s[84:85]
	global_load_dwordx4 v[132:135], v100, s[84:85] offset:768
	global_load_dwordx4 v[136:139], v149, s[84:85] offset:768
	global_load_dwordx4 v[140:143], v100, s[84:85] offset:832
	global_load_dwordx4 v[144:147], v149, s[84:85] offset:832
	s_add_u32 s84, s84, 0x30000
	s_addc_u32 s85, s85, 0
	v_add_u32_e32 v115, 952, v115
	ds_read2_b32 v[32:33], v115 offset0:0 offset1:1
	ds_read2_b32 v[34:35], v115 offset0:2 offset1:3
	ds_read2_b32 v[36:37], v115 offset0:8 offset1:9
	ds_read2_b32 v[38:39], v115 offset0:10 offset1:11
	ds_read2_b32 v[40:41], v115 offset0:17 offset1:18
	ds_read2_b32 v[42:43], v115 offset0:19 offset1:20
	ds_read2_b32 v[44:45], v115 offset0:25 offset1:26
	ds_read2_b32 v[46:47], v115 offset0:27 offset1:28
	s_waitcnt lgkmcnt(0)
	v_mfma_f32_32x32x16_bf16 v[32:47], v[156:159], v[48:51], v[32:47]
	ds_read_b64_tr_b16 v[72:73], v231
	ds_read_b64_tr_b16 v[74:75], v231 offset:512
	ds_read_b64_tr_b16 v[76:77], v231 offset:2048
	ds_read_b64_tr_b16 v[78:79], v231 offset:2560
	ds_read_b64_tr_b16 v[220:221], v231 offset:1024
	ds_read_b64_tr_b16 v[222:223], v231 offset:1536
	ds_read_b64_tr_b16 v[224:225], v231 offset:3072
	ds_read_b64_tr_b16 v[226:227], v231 offset:3584
	s_waitcnt vmcnt(8)
	ds_write_b128 v247, v[188:191]
	ds_write_b128 v247, v[192:195] offset:1024
	ds_write_b128 v247, v[196:199] offset:2048
	ds_write_b128 v247, v[200:203] offset:3072
	ds_read_b128 v[188:191], v248
	ds_read_b128 v[192:195], v249
	ds_read_b128 v[196:199], v250
	ds_read_b128 v[200:203], v251
	ds_write_b128 v112, v[204:207]
	ds_write_b128 v112, v[208:211] offset:1024
	ds_write_b128 v112, v[212:215] offset:2048
	ds_write_b128 v112, v[216:219] offset:3072
	v_mfma_f32_32x32x16_bf16 v[32:47], v[160:163], v[52:55], v[32:47]
	v_mfma_f32_32x32x16_bf16 v[32:47], v[164:167], v[56:59], v[32:47]
	v_mfma_f32_32x32x16_bf16 v[32:47], v[168:171], v[60:63], v[32:47]
	s_nop 11
	v_exp_f32_e32 v32, v32
	v_exp_f32_e32 v33, v33
	v_exp_f32_e32 v34, v34
	v_exp_f32_e32 v35, v35
	v_exp_f32_e32 v36, v36
	v_exp_f32_e32 v37, v37
	v_exp_f32_e32 v38, v38
	v_exp_f32_e32 v39, v39
	v_exp_f32_e32 v40, v40
	v_exp_f32_e32 v41, v41
	v_exp_f32_e32 v42, v42
	v_exp_f32_e32 v43, v43
	v_exp_f32_e32 v44, v44
	v_exp_f32_e32 v45, v45
	v_exp_f32_e32 v46, v46
	v_exp_f32_e32 v47, v47
	v_cvt_pk_bf16_f32 v64, v32, v33
	v_cvt_pk_bf16_f32 v65, v34, v35
	v_cvt_pk_bf16_f32 v66, v36, v37
	v_cvt_pk_bf16_f32 v67, v38, v39
	v_cvt_pk_bf16_f32 v68, v40, v41
	v_cvt_pk_bf16_f32 v69, v42, v43
	v_cvt_pk_bf16_f32 v70, v44, v45
	v_cvt_pk_bf16_f32 v71, v46, v47
	v_pk_add_f32 v[232:233], v[232:233], v[32:33]
	v_pk_add_f32 v[232:233], v[232:233], v[34:35]
	v_pk_add_f32 v[232:233], v[232:233], v[36:37]
	v_pk_add_f32 v[232:233], v[232:233], v[38:39]
	v_pk_add_f32 v[232:233], v[232:233], v[40:41]
	v_pk_add_f32 v[232:233], v[232:233], v[42:43]
	v_pk_add_f32 v[232:233], v[232:233], v[44:45]
	v_pk_add_f32 v[232:233], v[232:233], v[46:47]
	s_waitcnt lgkmcnt(12)
	v_mfma_f32_32x32x16_bf16 v[0:15], v[64:67], v[72:75], v[0:15]
	v_mfma_f32_32x32x16_bf16 v[16:31], v[64:67], v[76:79], v[16:31]
	v_mfma_f32_32x32x16_bf16 v[0:15], v[68:71], v[220:223], v[0:15]
	v_mfma_f32_32x32x16_bf16 v[16:31], v[68:71], v[224:227], v[16:31]
	global_load_dwordx4 v[156:159], v235, s[84:85]
	global_load_dwordx4 v[160:163], v236, s[84:85]
	global_load_dwordx4 v[164:167], v237, s[84:85]
	global_load_dwordx4 v[168:171], v238, s[84:85]
	global_load_dwordx4 v[172:175], v100, s[84:85] offset:768
	global_load_dwordx4 v[176:179], v149, s[84:85] offset:768
	global_load_dwordx4 v[180:183], v100, s[84:85] offset:832
	global_load_dwordx4 v[184:187], v149, s[84:85] offset:832
	s_add_u32 s84, s84, 0x30000
	s_addc_u32 s85, s85, 0
	ds_read2_b32 v[32:33], v115 offset0:34 offset1:35
	ds_read2_b32 v[34:35], v115 offset0:36 offset1:37
	ds_read2_b32 v[36:37], v115 offset0:42 offset1:43
	ds_read2_b32 v[38:39], v115 offset0:44 offset1:45
	ds_read2_b32 v[40:41], v115 offset0:51 offset1:52
	ds_read2_b32 v[42:43], v115 offset0:53 offset1:54
	ds_read2_b32 v[44:45], v115 offset0:59 offset1:60
	ds_read2_b32 v[46:47], v115 offset0:61 offset1:62
	s_waitcnt lgkmcnt(0)
	v_mfma_f32_32x32x16_bf16 v[32:47], v[188:191], v[48:51], v[32:47]
	ds_read_b64_tr_b16 v[72:73], v231
	ds_read_b64_tr_b16 v[74:75], v231 offset:512
	ds_read_b64_tr_b16 v[76:77], v231 offset:2048
	ds_read_b64_tr_b16 v[78:79], v231 offset:2560
	ds_read_b64_tr_b16 v[220:221], v231 offset:1024
	ds_read_b64_tr_b16 v[222:223], v231 offset:1536
	ds_read_b64_tr_b16 v[224:225], v231 offset:3072
	ds_read_b64_tr_b16 v[226:227], v231 offset:3584
	s_waitcnt vmcnt(8)
	ds_write_b128 v247, v[116:119]
	ds_write_b128 v247, v[120:123] offset:1024
	ds_write_b128 v247, v[124:127] offset:2048
	ds_write_b128 v247, v[128:131] offset:3072
	ds_read_b128 v[116:119], v248
	ds_read_b128 v[120:123], v249
	ds_read_b128 v[124:127], v250
	ds_read_b128 v[128:131], v251
	ds_write_b128 v112, v[132:135]
	ds_write_b128 v112, v[136:139] offset:1024
	ds_write_b128 v112, v[140:143] offset:2048
	ds_write_b128 v112, v[144:147] offset:3072
	v_mfma_f32_32x32x16_bf16 v[32:47], v[192:195], v[52:55], v[32:47]
	v_mfma_f32_32x32x16_bf16 v[32:47], v[196:199], v[56:59], v[32:47]
	v_mfma_f32_32x32x16_bf16 v[32:47], v[200:203], v[60:63], v[32:47]
	s_nop 11
	v_exp_f32_e32 v32, v32
	v_exp_f32_e32 v33, v33
	v_exp_f32_e32 v34, v34
	v_exp_f32_e32 v35, v35
	v_exp_f32_e32 v36, v36
	v_exp_f32_e32 v37, v37
	v_exp_f32_e32 v38, v38
	v_exp_f32_e32 v39, v39
	v_exp_f32_e32 v40, v40
	v_exp_f32_e32 v41, v41
	v_exp_f32_e32 v42, v42
	v_exp_f32_e32 v43, v43
	v_exp_f32_e32 v44, v44
	v_exp_f32_e32 v45, v45
	v_exp_f32_e32 v46, v46
	v_exp_f32_e32 v47, v47
	v_cvt_pk_bf16_f32 v64, v32, v33
	v_cvt_pk_bf16_f32 v65, v34, v35
	v_cvt_pk_bf16_f32 v66, v36, v37
	v_cvt_pk_bf16_f32 v67, v38, v39
	v_cvt_pk_bf16_f32 v68, v40, v41
	v_cvt_pk_bf16_f32 v69, v42, v43
	v_cvt_pk_bf16_f32 v70, v44, v45
	v_cvt_pk_bf16_f32 v71, v46, v47
	v_pk_add_f32 v[232:233], v[232:233], v[32:33]
	v_pk_add_f32 v[232:233], v[232:233], v[34:35]
	v_pk_add_f32 v[232:233], v[232:233], v[36:37]
	v_pk_add_f32 v[232:233], v[232:233], v[38:39]
	v_pk_add_f32 v[232:233], v[232:233], v[40:41]
	v_pk_add_f32 v[232:233], v[232:233], v[42:43]
	v_pk_add_f32 v[232:233], v[232:233], v[44:45]
	v_pk_add_f32 v[232:233], v[232:233], v[46:47]
	s_waitcnt lgkmcnt(12)
	v_mfma_f32_32x32x16_bf16 v[0:15], v[64:67], v[72:75], v[0:15]
	v_mfma_f32_32x32x16_bf16 v[16:31], v[64:67], v[76:79], v[16:31]
	v_mfma_f32_32x32x16_bf16 v[0:15], v[68:71], v[220:223], v[0:15]
	v_mfma_f32_32x32x16_bf16 v[16:31], v[68:71], v[224:227], v[16:31]
	global_load_dwordx4 v[188:191], v235, s[84:85]
	global_load_dwordx4 v[192:195], v236, s[84:85]
	global_load_dwordx4 v[196:199], v237, s[84:85]
	global_load_dwordx4 v[200:203], v238, s[84:85]
	global_load_dwordx4 v[204:207], v100, s[84:85] offset:768
	global_load_dwordx4 v[208:211], v149, s[84:85] offset:768
	global_load_dwordx4 v[212:215], v100, s[84:85] offset:832
	global_load_dwordx4 v[216:219], v149, s[84:85] offset:832
	s_add_u32 s84, s84, 0x30000
	s_addc_u32 s85, s85, 0
	ds_read2_b32 v[32:33], v115 offset0:68 offset1:69
	ds_read2_b32 v[34:35], v115 offset0:70 offset1:71
	ds_read2_b32 v[36:37], v115 offset0:76 offset1:77
	ds_read2_b32 v[38:39], v115 offset0:78 offset1:79
	ds_read2_b32 v[40:41], v115 offset0:85 offset1:86
	ds_read2_b32 v[42:43], v115 offset0:87 offset1:88
	ds_read2_b32 v[44:45], v115 offset0:93 offset1:94
	ds_read2_b32 v[46:47], v115 offset0:95 offset1:96
	s_waitcnt lgkmcnt(0)
	v_mfma_f32_32x32x16_bf16 v[32:47], v[116:119], v[48:51], v[32:47]
	ds_read_b64_tr_b16 v[72:73], v231
	ds_read_b64_tr_b16 v[74:75], v231 offset:512
	ds_read_b64_tr_b16 v[76:77], v231 offset:2048
	ds_read_b64_tr_b16 v[78:79], v231 offset:2560
	ds_read_b64_tr_b16 v[220:221], v231 offset:1024
	ds_read_b64_tr_b16 v[222:223], v231 offset:1536
	ds_read_b64_tr_b16 v[224:225], v231 offset:3072
	ds_read_b64_tr_b16 v[226:227], v231 offset:3584
	s_waitcnt vmcnt(8)
	ds_write_b128 v247, v[156:159]
	ds_write_b128 v247, v[160:163] offset:1024
	ds_write_b128 v247, v[164:167] offset:2048
	ds_write_b128 v247, v[168:171] offset:3072
	ds_read_b128 v[156:159], v248
	ds_read_b128 v[160:163], v249
	ds_read_b128 v[164:167], v250
	ds_read_b128 v[168:171], v251
	ds_write_b128 v112, v[172:175]
	ds_write_b128 v112, v[176:179] offset:1024
	ds_write_b128 v112, v[180:183] offset:2048
	ds_write_b128 v112, v[184:187] offset:3072
	v_mfma_f32_32x32x16_bf16 v[32:47], v[120:123], v[52:55], v[32:47]
	v_mfma_f32_32x32x16_bf16 v[32:47], v[124:127], v[56:59], v[32:47]
	v_mfma_f32_32x32x16_bf16 v[32:47], v[128:131], v[60:63], v[32:47]
	s_nop 11
	v_exp_f32_e32 v32, v32
	v_exp_f32_e32 v33, v33
	v_exp_f32_e32 v34, v34
	v_exp_f32_e32 v35, v35
	v_exp_f32_e32 v36, v36
	v_exp_f32_e32 v37, v37
	v_exp_f32_e32 v38, v38
	v_exp_f32_e32 v39, v39
	v_exp_f32_e32 v40, v40
	v_exp_f32_e32 v41, v41
	v_exp_f32_e32 v42, v42
	v_exp_f32_e32 v43, v43
	v_exp_f32_e32 v44, v44
	v_exp_f32_e32 v45, v45
	v_exp_f32_e32 v46, v46
	v_exp_f32_e32 v47, v47
	v_cvt_pk_bf16_f32 v64, v32, v33
	v_cvt_pk_bf16_f32 v65, v34, v35
	v_cvt_pk_bf16_f32 v66, v36, v37
	v_cvt_pk_bf16_f32 v67, v38, v39
	v_cvt_pk_bf16_f32 v68, v40, v41
	v_cvt_pk_bf16_f32 v69, v42, v43
	v_cvt_pk_bf16_f32 v70, v44, v45
	v_cvt_pk_bf16_f32 v71, v46, v47
	v_pk_add_f32 v[232:233], v[232:233], v[32:33]
	v_pk_add_f32 v[232:233], v[232:233], v[34:35]
	v_pk_add_f32 v[232:233], v[232:233], v[36:37]
	v_pk_add_f32 v[232:233], v[232:233], v[38:39]
	v_pk_add_f32 v[232:233], v[232:233], v[40:41]
	v_pk_add_f32 v[232:233], v[232:233], v[42:43]
	v_pk_add_f32 v[232:233], v[232:233], v[44:45]
	v_pk_add_f32 v[232:233], v[232:233], v[46:47]
	s_waitcnt lgkmcnt(12)
	v_mfma_f32_32x32x16_bf16 v[0:15], v[64:67], v[72:75], v[0:15]
	v_mfma_f32_32x32x16_bf16 v[16:31], v[64:67], v[76:79], v[16:31]
	v_mfma_f32_32x32x16_bf16 v[0:15], v[68:71], v[220:223], v[0:15]
	v_mfma_f32_32x32x16_bf16 v[16:31], v[68:71], v[224:227], v[16:31]
	global_load_dwordx4 v[116:119], v235, s[84:85]
	global_load_dwordx4 v[120:123], v236, s[84:85]
	global_load_dwordx4 v[124:127], v237, s[84:85]
	global_load_dwordx4 v[128:131], v238, s[84:85]
	global_load_dwordx4 v[132:135], v100, s[84:85] offset:768
	global_load_dwordx4 v[136:139], v149, s[84:85] offset:768
	global_load_dwordx4 v[140:143], v100, s[84:85] offset:832
	global_load_dwordx4 v[144:147], v149, s[84:85] offset:832
	s_add_u32 s84, s84, 0x30000
	s_addc_u32 s85, s85, 0
	ds_read2_b32 v[32:33], v115 offset0:102 offset1:103
	ds_read2_b32 v[34:35], v115 offset0:104 offset1:105
	ds_read2_b32 v[36:37], v115 offset0:110 offset1:111
	ds_read2_b32 v[38:39], v115 offset0:112 offset1:113
	ds_read2_b32 v[40:41], v115 offset0:119 offset1:120
	ds_read2_b32 v[42:43], v115 offset0:121 offset1:122
	ds_read2_b32 v[44:45], v115 offset0:127 offset1:128
	ds_read2_b32 v[46:47], v115 offset0:129 offset1:130
	s_waitcnt lgkmcnt(0)
	v_mfma_f32_32x32x16_bf16 v[32:47], v[156:159], v[48:51], v[32:47]
	ds_read_b64_tr_b16 v[72:73], v231
	ds_read_b64_tr_b16 v[74:75], v231 offset:512
	ds_read_b64_tr_b16 v[76:77], v231 offset:2048
	ds_read_b64_tr_b16 v[78:79], v231 offset:2560
	ds_read_b64_tr_b16 v[220:221], v231 offset:1024
	ds_read_b64_tr_b16 v[222:223], v231 offset:1536
	ds_read_b64_tr_b16 v[224:225], v231 offset:3072
	ds_read_b64_tr_b16 v[226:227], v231 offset:3584
	s_waitcnt vmcnt(8)
	ds_write_b128 v247, v[188:191]
	ds_write_b128 v247, v[192:195] offset:1024
	ds_write_b128 v247, v[196:199] offset:2048
	ds_write_b128 v247, v[200:203] offset:3072
	ds_read_b128 v[188:191], v248
	ds_read_b128 v[192:195], v249
	ds_read_b128 v[196:199], v250
	ds_read_b128 v[200:203], v251
	ds_write_b128 v112, v[204:207]
	ds_write_b128 v112, v[208:211] offset:1024
	ds_write_b128 v112, v[212:215] offset:2048
	ds_write_b128 v112, v[216:219] offset:3072
	v_mfma_f32_32x32x16_bf16 v[32:47], v[160:163], v[52:55], v[32:47]
	v_mfma_f32_32x32x16_bf16 v[32:47], v[164:167], v[56:59], v[32:47]
	v_mfma_f32_32x32x16_bf16 v[32:47], v[168:171], v[60:63], v[32:47]
	s_nop 11
	v_exp_f32_e32 v32, v32
	v_exp_f32_e32 v33, v33
	v_exp_f32_e32 v34, v34
	v_exp_f32_e32 v35, v35
	v_exp_f32_e32 v36, v36
	v_exp_f32_e32 v37, v37
	v_exp_f32_e32 v38, v38
	v_exp_f32_e32 v39, v39
	v_exp_f32_e32 v40, v40
	v_exp_f32_e32 v41, v41
	v_exp_f32_e32 v42, v42
	v_exp_f32_e32 v43, v43
	v_exp_f32_e32 v44, v44
	v_exp_f32_e32 v45, v45
	v_exp_f32_e32 v46, v46
	v_exp_f32_e32 v47, v47
	v_cvt_pk_bf16_f32 v64, v32, v33
	v_cvt_pk_bf16_f32 v65, v34, v35
	v_cvt_pk_bf16_f32 v66, v36, v37
	v_cvt_pk_bf16_f32 v67, v38, v39
	v_cvt_pk_bf16_f32 v68, v40, v41
	v_cvt_pk_bf16_f32 v69, v42, v43
	v_cvt_pk_bf16_f32 v70, v44, v45
	v_cvt_pk_bf16_f32 v71, v46, v47
	v_pk_add_f32 v[232:233], v[232:233], v[32:33]
	v_pk_add_f32 v[232:233], v[232:233], v[34:35]
	v_pk_add_f32 v[232:233], v[232:233], v[36:37]
	v_pk_add_f32 v[232:233], v[232:233], v[38:39]
	v_pk_add_f32 v[232:233], v[232:233], v[40:41]
	v_pk_add_f32 v[232:233], v[232:233], v[42:43]
	v_pk_add_f32 v[232:233], v[232:233], v[44:45]
	v_pk_add_f32 v[232:233], v[232:233], v[46:47]
	s_waitcnt lgkmcnt(12)
	v_mfma_f32_32x32x16_bf16 v[0:15], v[64:67], v[72:75], v[0:15]
	v_mfma_f32_32x32x16_bf16 v[16:31], v[64:67], v[76:79], v[16:31]
	v_mfma_f32_32x32x16_bf16 v[0:15], v[68:71], v[220:223], v[0:15]
	v_mfma_f32_32x32x16_bf16 v[16:31], v[68:71], v[224:227], v[16:31]
	global_load_dwordx4 v[156:159], v235, s[84:85]
	global_load_dwordx4 v[160:163], v236, s[84:85]
	global_load_dwordx4 v[164:167], v237, s[84:85]
	global_load_dwordx4 v[168:171], v238, s[84:85]
	global_load_dwordx4 v[172:175], v100, s[84:85] offset:768
	global_load_dwordx4 v[176:179], v149, s[84:85] offset:768
	global_load_dwordx4 v[180:183], v100, s[84:85] offset:832
	global_load_dwordx4 v[184:187], v149, s[84:85] offset:832
	s_add_u32 s84, s84, 0x30000
	s_addc_u32 s85, s85, 0
	ds_read2_b32 v[32:33], v115 offset0:136 offset1:137
	ds_read2_b32 v[34:35], v115 offset0:138 offset1:139
	ds_read2_b32 v[36:37], v115 offset0:144 offset1:145
	ds_read2_b32 v[38:39], v115 offset0:146 offset1:147
	ds_read2_b32 v[40:41], v115 offset0:153 offset1:154
	ds_read2_b32 v[42:43], v115 offset0:155 offset1:156
	ds_read2_b32 v[44:45], v115 offset0:161 offset1:162
	ds_read2_b32 v[46:47], v115 offset0:163 offset1:164
	s_waitcnt lgkmcnt(0)
	v_mfma_f32_32x32x16_bf16 v[32:47], v[188:191], v[48:51], v[32:47]
	ds_read_b64_tr_b16 v[72:73], v231
	ds_read_b64_tr_b16 v[74:75], v231 offset:512
	ds_read_b64_tr_b16 v[76:77], v231 offset:2048
	ds_read_b64_tr_b16 v[78:79], v231 offset:2560
	ds_read_b64_tr_b16 v[220:221], v231 offset:1024
	ds_read_b64_tr_b16 v[222:223], v231 offset:1536
	ds_read_b64_tr_b16 v[224:225], v231 offset:3072
	ds_read_b64_tr_b16 v[226:227], v231 offset:3584
	s_waitcnt vmcnt(8)
	ds_write_b128 v247, v[116:119]
	ds_write_b128 v247, v[120:123] offset:1024
	ds_write_b128 v247, v[124:127] offset:2048
	ds_write_b128 v247, v[128:131] offset:3072
	ds_read_b128 v[116:119], v248
	ds_read_b128 v[120:123], v249
	ds_read_b128 v[124:127], v250
	ds_read_b128 v[128:131], v251
	ds_write_b128 v112, v[132:135]
	ds_write_b128 v112, v[136:139] offset:1024
	ds_write_b128 v112, v[140:143] offset:2048
	ds_write_b128 v112, v[144:147] offset:3072
	v_mfma_f32_32x32x16_bf16 v[32:47], v[192:195], v[52:55], v[32:47]
	v_mfma_f32_32x32x16_bf16 v[32:47], v[196:199], v[56:59], v[32:47]
	v_mfma_f32_32x32x16_bf16 v[32:47], v[200:203], v[60:63], v[32:47]
	s_nop 11
	v_exp_f32_e32 v32, v32
	v_exp_f32_e32 v33, v33
	v_exp_f32_e32 v34, v34
	v_exp_f32_e32 v35, v35
	v_exp_f32_e32 v36, v36
	v_exp_f32_e32 v37, v37
	v_exp_f32_e32 v38, v38
	v_exp_f32_e32 v39, v39
	v_exp_f32_e32 v40, v40
	v_exp_f32_e32 v41, v41
	v_exp_f32_e32 v42, v42
	v_exp_f32_e32 v43, v43
	v_exp_f32_e32 v44, v44
	v_exp_f32_e32 v45, v45
	v_exp_f32_e32 v46, v46
	v_exp_f32_e32 v47, v47
	v_cvt_pk_bf16_f32 v64, v32, v33
	v_cvt_pk_bf16_f32 v65, v34, v35
	v_cvt_pk_bf16_f32 v66, v36, v37
	v_cvt_pk_bf16_f32 v67, v38, v39
	v_cvt_pk_bf16_f32 v68, v40, v41
	v_cvt_pk_bf16_f32 v69, v42, v43
	v_cvt_pk_bf16_f32 v70, v44, v45
	v_cvt_pk_bf16_f32 v71, v46, v47
	v_pk_add_f32 v[232:233], v[232:233], v[32:33]
	v_pk_add_f32 v[232:233], v[232:233], v[34:35]
	v_pk_add_f32 v[232:233], v[232:233], v[36:37]
	v_pk_add_f32 v[232:233], v[232:233], v[38:39]
	v_pk_add_f32 v[232:233], v[232:233], v[40:41]
	v_pk_add_f32 v[232:233], v[232:233], v[42:43]
	v_pk_add_f32 v[232:233], v[232:233], v[44:45]
	v_pk_add_f32 v[232:233], v[232:233], v[46:47]
	s_waitcnt lgkmcnt(12)
	v_mfma_f32_32x32x16_bf16 v[0:15], v[64:67], v[72:75], v[0:15]
	v_mfma_f32_32x32x16_bf16 v[16:31], v[64:67], v[76:79], v[16:31]
	v_mfma_f32_32x32x16_bf16 v[0:15], v[68:71], v[220:223], v[0:15]
	v_mfma_f32_32x32x16_bf16 v[16:31], v[68:71], v[224:227], v[16:31]
	global_load_dwordx4 v[188:191], v235, s[84:85]
	global_load_dwordx4 v[192:195], v236, s[84:85]
	global_load_dwordx4 v[196:199], v237, s[84:85]
	global_load_dwordx4 v[200:203], v238, s[84:85]
	global_load_dwordx4 v[204:207], v100, s[84:85] offset:768
	global_load_dwordx4 v[208:211], v149, s[84:85] offset:768
	global_load_dwordx4 v[212:215], v100, s[84:85] offset:832
	global_load_dwordx4 v[216:219], v149, s[84:85] offset:832
	s_add_u32 s84, s84, 0x30000
	s_addc_u32 s85, s85, 0
	ds_read2_b32 v[32:33], v115 offset0:170 offset1:171
	ds_read2_b32 v[34:35], v115 offset0:172 offset1:173
	ds_read2_b32 v[36:37], v115 offset0:178 offset1:179
	ds_read2_b32 v[38:39], v115 offset0:180 offset1:181
	ds_read2_b32 v[40:41], v115 offset0:187 offset1:188
	ds_read2_b32 v[42:43], v115 offset0:189 offset1:190
	ds_read2_b32 v[44:45], v115 offset0:195 offset1:196
	ds_read2_b32 v[46:47], v115 offset0:197 offset1:198
	s_waitcnt lgkmcnt(0)
	v_mfma_f32_32x32x16_bf16 v[32:47], v[116:119], v[48:51], v[32:47]
	ds_read_b64_tr_b16 v[72:73], v231
	ds_read_b64_tr_b16 v[74:75], v231 offset:512
	ds_read_b64_tr_b16 v[76:77], v231 offset:2048
	ds_read_b64_tr_b16 v[78:79], v231 offset:2560
	ds_read_b64_tr_b16 v[220:221], v231 offset:1024
	ds_read_b64_tr_b16 v[222:223], v231 offset:1536
	ds_read_b64_tr_b16 v[224:225], v231 offset:3072
	ds_read_b64_tr_b16 v[226:227], v231 offset:3584
	s_waitcnt vmcnt(8)
	ds_write_b128 v247, v[156:159]
	ds_write_b128 v247, v[160:163] offset:1024
	ds_write_b128 v247, v[164:167] offset:2048
	ds_write_b128 v247, v[168:171] offset:3072
	ds_read_b128 v[156:159], v248
	ds_read_b128 v[160:163], v249
	ds_read_b128 v[164:167], v250
	ds_read_b128 v[168:171], v251
	ds_write_b128 v112, v[172:175]
	ds_write_b128 v112, v[176:179] offset:1024
	ds_write_b128 v112, v[180:183] offset:2048
	ds_write_b128 v112, v[184:187] offset:3072
	v_mfma_f32_32x32x16_bf16 v[32:47], v[120:123], v[52:55], v[32:47]
	v_mfma_f32_32x32x16_bf16 v[32:47], v[124:127], v[56:59], v[32:47]
	v_mfma_f32_32x32x16_bf16 v[32:47], v[128:131], v[60:63], v[32:47]
	s_nop 11
	v_exp_f32_e32 v32, v32
	v_exp_f32_e32 v33, v33
	v_exp_f32_e32 v34, v34
	v_exp_f32_e32 v35, v35
	v_exp_f32_e32 v36, v36
	v_exp_f32_e32 v37, v37
	v_exp_f32_e32 v38, v38
	v_exp_f32_e32 v39, v39
	v_exp_f32_e32 v40, v40
	v_exp_f32_e32 v41, v41
	v_exp_f32_e32 v42, v42
	v_exp_f32_e32 v43, v43
	v_exp_f32_e32 v44, v44
	v_exp_f32_e32 v45, v45
	v_exp_f32_e32 v46, v46
	v_exp_f32_e32 v47, v47
	v_cvt_pk_bf16_f32 v64, v32, v33
	v_cvt_pk_bf16_f32 v65, v34, v35
	v_cvt_pk_bf16_f32 v66, v36, v37
	v_cvt_pk_bf16_f32 v67, v38, v39
	v_cvt_pk_bf16_f32 v68, v40, v41
	v_cvt_pk_bf16_f32 v69, v42, v43
	v_cvt_pk_bf16_f32 v70, v44, v45
	v_cvt_pk_bf16_f32 v71, v46, v47
	v_pk_add_f32 v[232:233], v[232:233], v[32:33]
	v_pk_add_f32 v[232:233], v[232:233], v[34:35]
	v_pk_add_f32 v[232:233], v[232:233], v[36:37]
	v_pk_add_f32 v[232:233], v[232:233], v[38:39]
	v_pk_add_f32 v[232:233], v[232:233], v[40:41]
	v_pk_add_f32 v[232:233], v[232:233], v[42:43]
	v_pk_add_f32 v[232:233], v[232:233], v[44:45]
	v_pk_add_f32 v[232:233], v[232:233], v[46:47]
	s_waitcnt lgkmcnt(12)
	v_mfma_f32_32x32x16_bf16 v[0:15], v[64:67], v[72:75], v[0:15]
	v_mfma_f32_32x32x16_bf16 v[16:31], v[64:67], v[76:79], v[16:31]
	v_mfma_f32_32x32x16_bf16 v[0:15], v[68:71], v[220:223], v[0:15]
	v_mfma_f32_32x32x16_bf16 v[16:31], v[68:71], v[224:227], v[16:31]
	global_load_dwordx4 v[116:119], v235, s[84:85]
	global_load_dwordx4 v[120:123], v236, s[84:85]
	global_load_dwordx4 v[124:127], v237, s[84:85]
	global_load_dwordx4 v[128:131], v238, s[84:85]
	global_load_dwordx4 v[132:135], v100, s[84:85] offset:768
	global_load_dwordx4 v[136:139], v149, s[84:85] offset:768
	global_load_dwordx4 v[140:143], v100, s[84:85] offset:832
	global_load_dwordx4 v[144:147], v149, s[84:85] offset:832
	s_add_u32 s84, s84, 0x30000
	s_addc_u32 s85, s85, 0
	ds_read2_b32 v[32:33], v115 offset0:204 offset1:205
	ds_read2_b32 v[34:35], v115 offset0:206 offset1:207
	ds_read2_b32 v[36:37], v115 offset0:212 offset1:213
	ds_read2_b32 v[38:39], v115 offset0:214 offset1:215
	ds_read2_b32 v[40:41], v115 offset0:221 offset1:222
	ds_read2_b32 v[42:43], v115 offset0:223 offset1:224
	ds_read2_b32 v[44:45], v115 offset0:229 offset1:230
	ds_read2_b32 v[46:47], v115 offset0:231 offset1:232
	s_waitcnt lgkmcnt(0)
	v_mfma_f32_32x32x16_bf16 v[32:47], v[156:159], v[48:51], v[32:47]
	ds_read_b64_tr_b16 v[72:73], v231
	ds_read_b64_tr_b16 v[74:75], v231 offset:512
	ds_read_b64_tr_b16 v[76:77], v231 offset:2048
	ds_read_b64_tr_b16 v[78:79], v231 offset:2560
	ds_read_b64_tr_b16 v[220:221], v231 offset:1024
	ds_read_b64_tr_b16 v[222:223], v231 offset:1536
	ds_read_b64_tr_b16 v[224:225], v231 offset:3072
	ds_read_b64_tr_b16 v[226:227], v231 offset:3584
	s_waitcnt vmcnt(8)
	ds_write_b128 v247, v[188:191]
	ds_write_b128 v247, v[192:195] offset:1024
	ds_write_b128 v247, v[196:199] offset:2048
	ds_write_b128 v247, v[200:203] offset:3072
	ds_read_b128 v[188:191], v248
	ds_read_b128 v[192:195], v249
	ds_read_b128 v[196:199], v250
	ds_read_b128 v[200:203], v251
	ds_write_b128 v112, v[204:207]
	ds_write_b128 v112, v[208:211] offset:1024
	ds_write_b128 v112, v[212:215] offset:2048
	ds_write_b128 v112, v[216:219] offset:3072
	v_mfma_f32_32x32x16_bf16 v[32:47], v[160:163], v[52:55], v[32:47]
	v_mfma_f32_32x32x16_bf16 v[32:47], v[164:167], v[56:59], v[32:47]
	v_mfma_f32_32x32x16_bf16 v[32:47], v[168:171], v[60:63], v[32:47]
	s_nop 11
	v_exp_f32_e32 v32, v32
	v_exp_f32_e32 v33, v33
	v_exp_f32_e32 v34, v34
	v_exp_f32_e32 v35, v35
	v_exp_f32_e32 v36, v36
	v_exp_f32_e32 v37, v37
	v_exp_f32_e32 v38, v38
	v_exp_f32_e32 v39, v39
	v_exp_f32_e32 v40, v40
	v_exp_f32_e32 v41, v41
	v_exp_f32_e32 v42, v42
	v_exp_f32_e32 v43, v43
	v_exp_f32_e32 v44, v44
	v_exp_f32_e32 v45, v45
	v_exp_f32_e32 v46, v46
	v_exp_f32_e32 v47, v47
	v_cvt_pk_bf16_f32 v64, v32, v33
	v_cvt_pk_bf16_f32 v65, v34, v35
	v_cvt_pk_bf16_f32 v66, v36, v37
	v_cvt_pk_bf16_f32 v67, v38, v39
	v_cvt_pk_bf16_f32 v68, v40, v41
	v_cvt_pk_bf16_f32 v69, v42, v43
	v_cvt_pk_bf16_f32 v70, v44, v45
	v_cvt_pk_bf16_f32 v71, v46, v47
	v_pk_add_f32 v[232:233], v[232:233], v[32:33]
	v_pk_add_f32 v[232:233], v[232:233], v[34:35]
	v_pk_add_f32 v[232:233], v[232:233], v[36:37]
	v_pk_add_f32 v[232:233], v[232:233], v[38:39]
	v_pk_add_f32 v[232:233], v[232:233], v[40:41]
	v_pk_add_f32 v[232:233], v[232:233], v[42:43]
	v_pk_add_f32 v[232:233], v[232:233], v[44:45]
	v_pk_add_f32 v[232:233], v[232:233], v[46:47]
	s_waitcnt lgkmcnt(12)
	v_mfma_f32_32x32x16_bf16 v[0:15], v[64:67], v[72:75], v[0:15]
	v_mfma_f32_32x32x16_bf16 v[16:31], v[64:67], v[76:79], v[16:31]
	v_mfma_f32_32x32x16_bf16 v[0:15], v[68:71], v[220:223], v[0:15]
	v_mfma_f32_32x32x16_bf16 v[16:31], v[68:71], v[224:227], v[16:31]
	global_load_dwordx4 v[156:159], v235, s[84:85]
	global_load_dwordx4 v[160:163], v236, s[84:85]
	global_load_dwordx4 v[164:167], v237, s[84:85]
	global_load_dwordx4 v[168:171], v238, s[84:85]
	global_load_dwordx4 v[172:175], v100, s[84:85] offset:768
	global_load_dwordx4 v[176:179], v149, s[84:85] offset:768
	global_load_dwordx4 v[180:183], v100, s[84:85] offset:832
	global_load_dwordx4 v[184:187], v149, s[84:85] offset:832
	s_add_u32 s84, s84, 0x30000
	s_addc_u32 s85, s85, 0
	v_add_u32_e32 v115, 952, v115
	ds_read2_b32 v[32:33], v115 offset0:0 offset1:1
	ds_read2_b32 v[34:35], v115 offset0:2 offset1:3
	ds_read2_b32 v[36:37], v115 offset0:8 offset1:9
	ds_read2_b32 v[38:39], v115 offset0:10 offset1:11
	ds_read2_b32 v[40:41], v115 offset0:17 offset1:18
	ds_read2_b32 v[42:43], v115 offset0:19 offset1:20
	ds_read2_b32 v[44:45], v115 offset0:25 offset1:26
	ds_read2_b32 v[46:47], v115 offset0:27 offset1:28
	s_waitcnt lgkmcnt(0)
	v_mfma_f32_32x32x16_bf16 v[32:47], v[188:191], v[48:51], v[32:47]
	ds_read_b64_tr_b16 v[72:73], v231
	ds_read_b64_tr_b16 v[74:75], v231 offset:512
	ds_read_b64_tr_b16 v[76:77], v231 offset:2048
	ds_read_b64_tr_b16 v[78:79], v231 offset:2560
	ds_read_b64_tr_b16 v[220:221], v231 offset:1024
	ds_read_b64_tr_b16 v[222:223], v231 offset:1536
	ds_read_b64_tr_b16 v[224:225], v231 offset:3072
	ds_read_b64_tr_b16 v[226:227], v231 offset:3584
	s_waitcnt vmcnt(8)
	ds_write_b128 v247, v[116:119]
	ds_write_b128 v247, v[120:123] offset:1024
	ds_write_b128 v247, v[124:127] offset:2048
	ds_write_b128 v247, v[128:131] offset:3072
	ds_read_b128 v[116:119], v248
	ds_read_b128 v[120:123], v249
	ds_read_b128 v[124:127], v250
	ds_read_b128 v[128:131], v251
	ds_write_b128 v112, v[132:135]
	ds_write_b128 v112, v[136:139] offset:1024
	ds_write_b128 v112, v[140:143] offset:2048
	ds_write_b128 v112, v[144:147] offset:3072
	v_mfma_f32_32x32x16_bf16 v[32:47], v[192:195], v[52:55], v[32:47]
	v_mfma_f32_32x32x16_bf16 v[32:47], v[196:199], v[56:59], v[32:47]
	v_mfma_f32_32x32x16_bf16 v[32:47], v[200:203], v[60:63], v[32:47]
	s_nop 11
	v_exp_f32_e32 v32, v32
	v_exp_f32_e32 v33, v33
	v_exp_f32_e32 v34, v34
	v_exp_f32_e32 v35, v35
	v_exp_f32_e32 v36, v36
	v_exp_f32_e32 v37, v37
	v_exp_f32_e32 v38, v38
	v_exp_f32_e32 v39, v39
	v_exp_f32_e32 v40, v40
	v_exp_f32_e32 v41, v41
	v_exp_f32_e32 v42, v42
	v_exp_f32_e32 v43, v43
	v_exp_f32_e32 v44, v44
	v_exp_f32_e32 v45, v45
	v_exp_f32_e32 v46, v46
	v_exp_f32_e32 v47, v47
	v_cvt_pk_bf16_f32 v64, v32, v33
	v_cvt_pk_bf16_f32 v65, v34, v35
	v_cvt_pk_bf16_f32 v66, v36, v37
	v_cvt_pk_bf16_f32 v67, v38, v39
	v_cvt_pk_bf16_f32 v68, v40, v41
	v_cvt_pk_bf16_f32 v69, v42, v43
	v_cvt_pk_bf16_f32 v70, v44, v45
	v_cvt_pk_bf16_f32 v71, v46, v47
	v_pk_add_f32 v[232:233], v[232:233], v[32:33]
	v_pk_add_f32 v[232:233], v[232:233], v[34:35]
	v_pk_add_f32 v[232:233], v[232:233], v[36:37]
	v_pk_add_f32 v[232:233], v[232:233], v[38:39]
	v_pk_add_f32 v[232:233], v[232:233], v[40:41]
	v_pk_add_f32 v[232:233], v[232:233], v[42:43]
	v_pk_add_f32 v[232:233], v[232:233], v[44:45]
	v_pk_add_f32 v[232:233], v[232:233], v[46:47]
	s_waitcnt lgkmcnt(12)
	v_mfma_f32_32x32x16_bf16 v[0:15], v[64:67], v[72:75], v[0:15]
	v_mfma_f32_32x32x16_bf16 v[16:31], v[64:67], v[76:79], v[16:31]
	v_mfma_f32_32x32x16_bf16 v[0:15], v[68:71], v[220:223], v[0:15]
	v_mfma_f32_32x32x16_bf16 v[16:31], v[68:71], v[224:227], v[16:31]
	global_load_dwordx4 v[188:191], v235, s[84:85]
	global_load_dwordx4 v[192:195], v236, s[84:85]
	global_load_dwordx4 v[196:199], v237, s[84:85]
	global_load_dwordx4 v[200:203], v238, s[84:85]
	global_load_dwordx4 v[204:207], v100, s[84:85] offset:768
	global_load_dwordx4 v[208:211], v149, s[84:85] offset:768
	global_load_dwordx4 v[212:215], v100, s[84:85] offset:832
	global_load_dwordx4 v[216:219], v149, s[84:85] offset:832
	s_add_u32 s84, s84, 0x30000
	s_addc_u32 s85, s85, 0
	ds_read2_b32 v[32:33], v115 offset0:34 offset1:35
	ds_read2_b32 v[34:35], v115 offset0:36 offset1:37
	ds_read2_b32 v[36:37], v115 offset0:42 offset1:43
	ds_read2_b32 v[38:39], v115 offset0:44 offset1:45
	ds_read2_b32 v[40:41], v115 offset0:51 offset1:52
	ds_read2_b32 v[42:43], v115 offset0:53 offset1:54
	ds_read2_b32 v[44:45], v115 offset0:59 offset1:60
	ds_read2_b32 v[46:47], v115 offset0:61 offset1:62
	s_waitcnt lgkmcnt(0)
	v_mfma_f32_32x32x16_bf16 v[32:47], v[116:119], v[48:51], v[32:47]
	ds_read_b64_tr_b16 v[72:73], v231
	ds_read_b64_tr_b16 v[74:75], v231 offset:512
	ds_read_b64_tr_b16 v[76:77], v231 offset:2048
	ds_read_b64_tr_b16 v[78:79], v231 offset:2560
	ds_read_b64_tr_b16 v[220:221], v231 offset:1024
	ds_read_b64_tr_b16 v[222:223], v231 offset:1536
	ds_read_b64_tr_b16 v[224:225], v231 offset:3072
	ds_read_b64_tr_b16 v[226:227], v231 offset:3584
	s_waitcnt vmcnt(8)
	ds_write_b128 v247, v[156:159]
	ds_write_b128 v247, v[160:163] offset:1024
	ds_write_b128 v247, v[164:167] offset:2048
	ds_write_b128 v247, v[168:171] offset:3072
	ds_read_b128 v[156:159], v248
	ds_read_b128 v[160:163], v249
	ds_read_b128 v[164:167], v250
	ds_read_b128 v[168:171], v251
	ds_write_b128 v112, v[172:175]
	ds_write_b128 v112, v[176:179] offset:1024
	ds_write_b128 v112, v[180:183] offset:2048
	ds_write_b128 v112, v[184:187] offset:3072
	v_mfma_f32_32x32x16_bf16 v[32:47], v[120:123], v[52:55], v[32:47]
	v_mfma_f32_32x32x16_bf16 v[32:47], v[124:127], v[56:59], v[32:47]
	v_mfma_f32_32x32x16_bf16 v[32:47], v[128:131], v[60:63], v[32:47]
	s_nop 11
	v_exp_f32_e32 v32, v32
	v_exp_f32_e32 v33, v33
	v_exp_f32_e32 v34, v34
	v_exp_f32_e32 v35, v35
	v_exp_f32_e32 v36, v36
	v_exp_f32_e32 v37, v37
	v_exp_f32_e32 v38, v38
	v_exp_f32_e32 v39, v39
	v_exp_f32_e32 v40, v40
	v_exp_f32_e32 v41, v41
	v_exp_f32_e32 v42, v42
	v_exp_f32_e32 v43, v43
	v_exp_f32_e32 v44, v44
	v_exp_f32_e32 v45, v45
	v_exp_f32_e32 v46, v46
	v_exp_f32_e32 v47, v47
	v_cvt_pk_bf16_f32 v64, v32, v33
	v_cvt_pk_bf16_f32 v65, v34, v35
	v_cvt_pk_bf16_f32 v66, v36, v37
	v_cvt_pk_bf16_f32 v67, v38, v39
	v_cvt_pk_bf16_f32 v68, v40, v41
	v_cvt_pk_bf16_f32 v69, v42, v43
	v_cvt_pk_bf16_f32 v70, v44, v45
	v_cvt_pk_bf16_f32 v71, v46, v47
	v_pk_add_f32 v[232:233], v[232:233], v[32:33]
	v_pk_add_f32 v[232:233], v[232:233], v[34:35]
	v_pk_add_f32 v[232:233], v[232:233], v[36:37]
	v_pk_add_f32 v[232:233], v[232:233], v[38:39]
	v_pk_add_f32 v[232:233], v[232:233], v[40:41]
	v_pk_add_f32 v[232:233], v[232:233], v[42:43]
	v_pk_add_f32 v[232:233], v[232:233], v[44:45]
	v_pk_add_f32 v[232:233], v[232:233], v[46:47]
	s_waitcnt lgkmcnt(12)
	v_mfma_f32_32x32x16_bf16 v[0:15], v[64:67], v[72:75], v[0:15]
	v_mfma_f32_32x32x16_bf16 v[16:31], v[64:67], v[76:79], v[16:31]
	v_mfma_f32_32x32x16_bf16 v[0:15], v[68:71], v[220:223], v[0:15]
	v_mfma_f32_32x32x16_bf16 v[16:31], v[68:71], v[224:227], v[16:31]
	global_load_dwordx4 v[116:119], v235, s[84:85]
	global_load_dwordx4 v[120:123], v236, s[84:85]
	global_load_dwordx4 v[124:127], v237, s[84:85]
	global_load_dwordx4 v[128:131], v238, s[84:85]
	global_load_dwordx4 v[132:135], v100, s[84:85] offset:768
	global_load_dwordx4 v[136:139], v149, s[84:85] offset:768
	global_load_dwordx4 v[140:143], v100, s[84:85] offset:832
	global_load_dwordx4 v[144:147], v149, s[84:85] offset:832
	s_add_u32 s84, s84, 0x30000
	s_addc_u32 s85, s85, 0
	ds_read2_b32 v[32:33], v115 offset0:68 offset1:69
	ds_read2_b32 v[34:35], v115 offset0:70 offset1:71
	ds_read2_b32 v[36:37], v115 offset0:76 offset1:77
	ds_read2_b32 v[38:39], v115 offset0:78 offset1:79
	ds_read2_b32 v[40:41], v115 offset0:85 offset1:86
	ds_read2_b32 v[42:43], v115 offset0:87 offset1:88
	ds_read2_b32 v[44:45], v115 offset0:93 offset1:94
	ds_read2_b32 v[46:47], v115 offset0:95 offset1:96
	s_waitcnt lgkmcnt(0)
	v_mfma_f32_32x32x16_bf16 v[32:47], v[156:159], v[48:51], v[32:47]
	ds_read_b64_tr_b16 v[72:73], v231
	ds_read_b64_tr_b16 v[74:75], v231 offset:512
	ds_read_b64_tr_b16 v[76:77], v231 offset:2048
	ds_read_b64_tr_b16 v[78:79], v231 offset:2560
	ds_read_b64_tr_b16 v[220:221], v231 offset:1024
	ds_read_b64_tr_b16 v[222:223], v231 offset:1536
	ds_read_b64_tr_b16 v[224:225], v231 offset:3072
	ds_read_b64_tr_b16 v[226:227], v231 offset:3584
	s_waitcnt vmcnt(8)
	ds_write_b128 v247, v[188:191]
	ds_write_b128 v247, v[192:195] offset:1024
	ds_write_b128 v247, v[196:199] offset:2048
	ds_write_b128 v247, v[200:203] offset:3072
	ds_read_b128 v[188:191], v248
	ds_read_b128 v[192:195], v249
	ds_read_b128 v[196:199], v250
	ds_read_b128 v[200:203], v251
	ds_write_b128 v112, v[204:207]
	ds_write_b128 v112, v[208:211] offset:1024
	ds_write_b128 v112, v[212:215] offset:2048
	ds_write_b128 v112, v[216:219] offset:3072
	v_mfma_f32_32x32x16_bf16 v[32:47], v[160:163], v[52:55], v[32:47]
	v_mfma_f32_32x32x16_bf16 v[32:47], v[164:167], v[56:59], v[32:47]
	v_mfma_f32_32x32x16_bf16 v[32:47], v[168:171], v[60:63], v[32:47]
	s_nop 11
	v_exp_f32_e32 v32, v32
	v_exp_f32_e32 v33, v33
	v_exp_f32_e32 v34, v34
	v_exp_f32_e32 v35, v35
	v_exp_f32_e32 v36, v36
	v_exp_f32_e32 v37, v37
	v_exp_f32_e32 v38, v38
	v_exp_f32_e32 v39, v39
	v_exp_f32_e32 v40, v40
	v_exp_f32_e32 v41, v41
	v_exp_f32_e32 v42, v42
	v_exp_f32_e32 v43, v43
	v_exp_f32_e32 v44, v44
	v_exp_f32_e32 v45, v45
	v_exp_f32_e32 v46, v46
	v_exp_f32_e32 v47, v47
	v_cvt_pk_bf16_f32 v64, v32, v33
	v_cvt_pk_bf16_f32 v65, v34, v35
	v_cvt_pk_bf16_f32 v66, v36, v37
	v_cvt_pk_bf16_f32 v67, v38, v39
	v_cvt_pk_bf16_f32 v68, v40, v41
	v_cvt_pk_bf16_f32 v69, v42, v43
	v_cvt_pk_bf16_f32 v70, v44, v45
	v_cvt_pk_bf16_f32 v71, v46, v47
	v_pk_add_f32 v[232:233], v[232:233], v[32:33]
	v_pk_add_f32 v[232:233], v[232:233], v[34:35]
	v_pk_add_f32 v[232:233], v[232:233], v[36:37]
	v_pk_add_f32 v[232:233], v[232:233], v[38:39]
	v_pk_add_f32 v[232:233], v[232:233], v[40:41]
	v_pk_add_f32 v[232:233], v[232:233], v[42:43]
	v_pk_add_f32 v[232:233], v[232:233], v[44:45]
	v_pk_add_f32 v[232:233], v[232:233], v[46:47]
	s_waitcnt lgkmcnt(12)
	v_mfma_f32_32x32x16_bf16 v[0:15], v[64:67], v[72:75], v[0:15]
	v_mfma_f32_32x32x16_bf16 v[16:31], v[64:67], v[76:79], v[16:31]
	v_mfma_f32_32x32x16_bf16 v[0:15], v[68:71], v[220:223], v[0:15]
	v_mfma_f32_32x32x16_bf16 v[16:31], v[68:71], v[224:227], v[16:31]
	global_load_dwordx4 v[156:159], v235, s[84:85]
	global_load_dwordx4 v[160:163], v236, s[84:85]
	global_load_dwordx4 v[164:167], v237, s[84:85]
	global_load_dwordx4 v[168:171], v238, s[84:85]
	global_load_dwordx4 v[172:175], v100, s[84:85] offset:768
	global_load_dwordx4 v[176:179], v149, s[84:85] offset:768
	global_load_dwordx4 v[180:183], v100, s[84:85] offset:832
	global_load_dwordx4 v[184:187], v149, s[84:85] offset:832
	ds_read2_b32 v[32:33], v115 offset0:102 offset1:103
	ds_read2_b32 v[34:35], v115 offset0:104 offset1:105
	ds_read2_b32 v[36:37], v115 offset0:110 offset1:111
	ds_read2_b32 v[38:39], v115 offset0:112 offset1:113
	ds_read2_b32 v[40:41], v115 offset0:119 offset1:120
	ds_read2_b32 v[42:43], v115 offset0:121 offset1:122
	ds_read2_b32 v[44:45], v115 offset0:127 offset1:128
	ds_read2_b32 v[46:47], v115 offset0:129 offset1:130
	s_waitcnt lgkmcnt(0)
	v_mfma_f32_32x32x16_bf16 v[32:47], v[188:191], v[48:51], v[32:47]
	ds_read_b64_tr_b16 v[72:73], v231
	ds_read_b64_tr_b16 v[74:75], v231 offset:512
	ds_read_b64_tr_b16 v[76:77], v231 offset:2048
	ds_read_b64_tr_b16 v[78:79], v231 offset:2560
	ds_read_b64_tr_b16 v[220:221], v231 offset:1024
	ds_read_b64_tr_b16 v[222:223], v231 offset:1536
	ds_read_b64_tr_b16 v[224:225], v231 offset:3072
	ds_read_b64_tr_b16 v[226:227], v231 offset:3584
	s_waitcnt vmcnt(8)
	ds_write_b128 v247, v[116:119]
	ds_write_b128 v247, v[120:123] offset:1024
	ds_write_b128 v247, v[124:127] offset:2048
	ds_write_b128 v247, v[128:131] offset:3072
	ds_read_b128 v[116:119], v248
	ds_read_b128 v[120:123], v249
	ds_read_b128 v[124:127], v250
	ds_read_b128 v[128:131], v251
	ds_write_b128 v112, v[132:135]
	ds_write_b128 v112, v[136:139] offset:1024
	ds_write_b128 v112, v[140:143] offset:2048
	ds_write_b128 v112, v[144:147] offset:3072
	v_mfma_f32_32x32x16_bf16 v[32:47], v[192:195], v[52:55], v[32:47]
	v_mfma_f32_32x32x16_bf16 v[32:47], v[196:199], v[56:59], v[32:47]
	v_mfma_f32_32x32x16_bf16 v[32:47], v[200:203], v[60:63], v[32:47]
	s_nop 11
	v_exp_f32_e32 v32, v32
	v_exp_f32_e32 v33, v33
	v_exp_f32_e32 v34, v34
	v_exp_f32_e32 v35, v35
	v_exp_f32_e32 v36, v36
	v_exp_f32_e32 v37, v37
	v_exp_f32_e32 v38, v38
	v_exp_f32_e32 v39, v39
	v_exp_f32_e32 v40, v40
	v_exp_f32_e32 v41, v41
	v_exp_f32_e32 v42, v42
	v_exp_f32_e32 v43, v43
	v_exp_f32_e32 v44, v44
	v_exp_f32_e32 v45, v45
	v_exp_f32_e32 v46, v46
	v_exp_f32_e32 v47, v47
	v_cvt_pk_bf16_f32 v64, v32, v33
	v_cvt_pk_bf16_f32 v65, v34, v35
	v_cvt_pk_bf16_f32 v66, v36, v37
	v_cvt_pk_bf16_f32 v67, v38, v39
	v_cvt_pk_bf16_f32 v68, v40, v41
	v_cvt_pk_bf16_f32 v69, v42, v43
	v_cvt_pk_bf16_f32 v70, v44, v45
	v_cvt_pk_bf16_f32 v71, v46, v47
	v_pk_add_f32 v[232:233], v[232:233], v[32:33]
	v_pk_add_f32 v[232:233], v[232:233], v[34:35]
	v_pk_add_f32 v[232:233], v[232:233], v[36:37]
	v_pk_add_f32 v[232:233], v[232:233], v[38:39]
	v_pk_add_f32 v[232:233], v[232:233], v[40:41]
	v_pk_add_f32 v[232:233], v[232:233], v[42:43]
	v_pk_add_f32 v[232:233], v[232:233], v[44:45]
	v_pk_add_f32 v[232:233], v[232:233], v[46:47]
	s_waitcnt lgkmcnt(12)
	v_mfma_f32_32x32x16_bf16 v[0:15], v[64:67], v[72:75], v[0:15]
	v_mfma_f32_32x32x16_bf16 v[16:31], v[64:67], v[76:79], v[16:31]
	v_mfma_f32_32x32x16_bf16 v[0:15], v[68:71], v[220:223], v[0:15]
	v_mfma_f32_32x32x16_bf16 v[16:31], v[68:71], v[224:227], v[16:31]
	global_load_dwordx4 v[188:191], v239, s[86:87]
	global_load_dwordx4 v[192:195], v240, s[86:87]
	global_load_dwordx4 v[196:199], v241, s[86:87]
	global_load_dwordx4 v[200:203], v242, s[86:87]
	global_load_dwordx4 v[204:207], v101, s[86:87] offset:768
	global_load_dwordx4 v[208:211], v150, s[86:87] offset:768
	global_load_dwordx4 v[212:215], v101, s[86:87] offset:832
	global_load_dwordx4 v[216:219], v150, s[86:87] offset:832
	s_add_u32 s86, s86, 0xc0000
	s_addc_u32 s87, s87, 0
	ds_read2_b32 v[32:33], v115 offset0:136 offset1:137
	ds_read2_b32 v[34:35], v115 offset0:138 offset1:139
	ds_read2_b32 v[36:37], v115 offset0:144 offset1:145
	ds_read2_b32 v[38:39], v115 offset0:146 offset1:147
	ds_read2_b32 v[40:41], v115 offset0:153 offset1:154
	ds_read2_b32 v[42:43], v115 offset0:155 offset1:156
	ds_read2_b32 v[44:45], v115 offset0:161 offset1:162
	ds_read2_b32 v[46:47], v115 offset0:163 offset1:164
	s_waitcnt lgkmcnt(0)
	v_mfma_f32_32x32x16_bf16 v[32:47], v[116:119], v[48:51], v[32:47]
	ds_read_b64_tr_b16 v[72:73], v231
	ds_read_b64_tr_b16 v[74:75], v231 offset:512
	ds_read_b64_tr_b16 v[76:77], v231 offset:2048
	ds_read_b64_tr_b16 v[78:79], v231 offset:2560
	ds_read_b64_tr_b16 v[220:221], v231 offset:1024
	ds_read_b64_tr_b16 v[222:223], v231 offset:1536
	ds_read_b64_tr_b16 v[224:225], v231 offset:3072
	ds_read_b64_tr_b16 v[226:227], v231 offset:3584
	s_waitcnt vmcnt(8)
	ds_write_b128 v247, v[156:159]
	ds_write_b128 v247, v[160:163] offset:1024
	ds_write_b128 v247, v[164:167] offset:2048
	ds_write_b128 v247, v[168:171] offset:3072
	ds_read_b128 v[156:159], v248
	ds_read_b128 v[160:163], v249
	ds_read_b128 v[164:167], v250
	ds_read_b128 v[168:171], v251
	ds_write_b128 v112, v[172:175]
	ds_write_b128 v112, v[176:179] offset:1024
	ds_write_b128 v112, v[180:183] offset:2048
	ds_write_b128 v112, v[184:187] offset:3072
	v_mfma_f32_32x32x16_bf16 v[32:47], v[120:123], v[52:55], v[32:47]
	v_mfma_f32_32x32x16_bf16 v[32:47], v[124:127], v[56:59], v[32:47]
	v_mfma_f32_32x32x16_bf16 v[32:47], v[128:131], v[60:63], v[32:47]
	s_nop 11
	v_exp_f32_e32 v32, v32
	v_exp_f32_e32 v33, v33
	v_exp_f32_e32 v34, v34
	v_exp_f32_e32 v35, v35
	v_exp_f32_e32 v36, v36
	v_exp_f32_e32 v37, v37
	v_exp_f32_e32 v38, v38
	v_exp_f32_e32 v39, v39
	v_exp_f32_e32 v40, v40
	v_exp_f32_e32 v41, v41
	v_exp_f32_e32 v42, v42
	v_exp_f32_e32 v43, v43
	v_exp_f32_e32 v44, v44
	v_exp_f32_e32 v45, v45
	v_exp_f32_e32 v46, v46
	v_exp_f32_e32 v47, v47
	v_cvt_pk_bf16_f32 v64, v32, v33
	v_cvt_pk_bf16_f32 v65, v34, v35
	v_cvt_pk_bf16_f32 v66, v36, v37
	v_cvt_pk_bf16_f32 v67, v38, v39
	v_cvt_pk_bf16_f32 v68, v40, v41
	v_cvt_pk_bf16_f32 v69, v42, v43
	v_cvt_pk_bf16_f32 v70, v44, v45
	v_cvt_pk_bf16_f32 v71, v46, v47
	v_pk_add_f32 v[232:233], v[232:233], v[32:33]
	v_pk_add_f32 v[232:233], v[232:233], v[34:35]
	v_pk_add_f32 v[232:233], v[232:233], v[36:37]
	v_pk_add_f32 v[232:233], v[232:233], v[38:39]
	v_pk_add_f32 v[232:233], v[232:233], v[40:41]
	v_pk_add_f32 v[232:233], v[232:233], v[42:43]
	v_pk_add_f32 v[232:233], v[232:233], v[44:45]
	v_pk_add_f32 v[232:233], v[232:233], v[46:47]
	s_waitcnt lgkmcnt(12)
	v_mfma_f32_32x32x16_bf16 v[0:15], v[64:67], v[72:75], v[0:15]
	v_mfma_f32_32x32x16_bf16 v[16:31], v[64:67], v[76:79], v[16:31]
	v_mfma_f32_32x32x16_bf16 v[0:15], v[68:71], v[220:223], v[0:15]
	v_mfma_f32_32x32x16_bf16 v[16:31], v[68:71], v[224:227], v[16:31]
	global_load_dwordx4 v[116:119], v239, s[86:87]
	global_load_dwordx4 v[120:123], v240, s[86:87]
	global_load_dwordx4 v[124:127], v241, s[86:87]
	global_load_dwordx4 v[128:131], v242, s[86:87]
	global_load_dwordx4 v[132:135], v101, s[86:87] offset:768
	global_load_dwordx4 v[136:139], v150, s[86:87] offset:768
	global_load_dwordx4 v[140:143], v101, s[86:87] offset:832
	global_load_dwordx4 v[144:147], v150, s[86:87] offset:832
	s_add_u32 s86, s86, 0xc0000
	s_addc_u32 s87, s87, 0
	ds_read2_b32 v[32:33], v115 offset0:170 offset1:171
	ds_read2_b32 v[34:35], v115 offset0:172 offset1:173
	ds_read2_b32 v[36:37], v115 offset0:178 offset1:179
	ds_read2_b32 v[38:39], v115 offset0:180 offset1:181
	ds_read2_b32 v[40:41], v115 offset0:187 offset1:188
	ds_read2_b32 v[42:43], v115 offset0:189 offset1:190
	ds_read2_b32 v[44:45], v115 offset0:195 offset1:196
	ds_read2_b32 v[46:47], v115 offset0:197 offset1:198
	s_waitcnt lgkmcnt(0)
	v_mfma_f32_32x32x16_bf16 v[32:47], v[156:159], v[48:51], v[32:47]
	ds_read_b64_tr_b16 v[72:73], v231
	ds_read_b64_tr_b16 v[74:75], v231 offset:512
	ds_read_b64_tr_b16 v[76:77], v231 offset:2048
	ds_read_b64_tr_b16 v[78:79], v231 offset:2560
	ds_read_b64_tr_b16 v[220:221], v231 offset:1024
	ds_read_b64_tr_b16 v[222:223], v231 offset:1536
	ds_read_b64_tr_b16 v[224:225], v231 offset:3072
	ds_read_b64_tr_b16 v[226:227], v231 offset:3584
	s_waitcnt vmcnt(8)
	ds_write_b128 v247, v[188:191]
	ds_write_b128 v247, v[192:195] offset:1024
	ds_write_b128 v247, v[196:199] offset:2048
	ds_write_b128 v247, v[200:203] offset:3072
	ds_read_b128 v[188:191], v248
	ds_read_b128 v[192:195], v249
	ds_read_b128 v[196:199], v250
	ds_read_b128 v[200:203], v251
	ds_write_b128 v112, v[204:207]
	ds_write_b128 v112, v[208:211] offset:1024
	ds_write_b128 v112, v[212:215] offset:2048
	ds_write_b128 v112, v[216:219] offset:3072
	v_mfma_f32_32x32x16_bf16 v[32:47], v[160:163], v[52:55], v[32:47]
	v_mfma_f32_32x32x16_bf16 v[32:47], v[164:167], v[56:59], v[32:47]
	v_mfma_f32_32x32x16_bf16 v[32:47], v[168:171], v[60:63], v[32:47]
	s_nop 11
	v_exp_f32_e32 v32, v32
	v_exp_f32_e32 v33, v33
	v_exp_f32_e32 v34, v34
	v_exp_f32_e32 v35, v35
	v_exp_f32_e32 v36, v36
	v_exp_f32_e32 v37, v37
	v_exp_f32_e32 v38, v38
	v_exp_f32_e32 v39, v39
	v_exp_f32_e32 v40, v40
	v_exp_f32_e32 v41, v41
	v_exp_f32_e32 v42, v42
	v_exp_f32_e32 v43, v43
	v_exp_f32_e32 v44, v44
	v_exp_f32_e32 v45, v45
	v_exp_f32_e32 v46, v46
	v_exp_f32_e32 v47, v47
	v_cvt_pk_bf16_f32 v64, v32, v33
	v_cvt_pk_bf16_f32 v65, v34, v35
	v_cvt_pk_bf16_f32 v66, v36, v37
	v_cvt_pk_bf16_f32 v67, v38, v39
	v_cvt_pk_bf16_f32 v68, v40, v41
	v_cvt_pk_bf16_f32 v69, v42, v43
	v_cvt_pk_bf16_f32 v70, v44, v45
	v_cvt_pk_bf16_f32 v71, v46, v47
	v_pk_add_f32 v[232:233], v[232:233], v[32:33]
	v_pk_add_f32 v[232:233], v[232:233], v[34:35]
	v_pk_add_f32 v[232:233], v[232:233], v[36:37]
	v_pk_add_f32 v[232:233], v[232:233], v[38:39]
	v_pk_add_f32 v[232:233], v[232:233], v[40:41]
	v_pk_add_f32 v[232:233], v[232:233], v[42:43]
	v_pk_add_f32 v[232:233], v[232:233], v[44:45]
	v_pk_add_f32 v[232:233], v[232:233], v[46:47]
	s_waitcnt lgkmcnt(12)
	v_mfma_f32_32x32x16_bf16 v[0:15], v[64:67], v[72:75], v[0:15]
	v_mfma_f32_32x32x16_bf16 v[16:31], v[64:67], v[76:79], v[16:31]
	v_mfma_f32_32x32x16_bf16 v[0:15], v[68:71], v[220:223], v[0:15]
	v_mfma_f32_32x32x16_bf16 v[16:31], v[68:71], v[224:227], v[16:31]
	global_load_dwordx4 v[156:159], v239, s[86:87]
	global_load_dwordx4 v[160:163], v240, s[86:87]
	global_load_dwordx4 v[164:167], v241, s[86:87]
	global_load_dwordx4 v[168:171], v242, s[86:87]
	global_load_dwordx4 v[172:175], v101, s[86:87] offset:768
	global_load_dwordx4 v[176:179], v150, s[86:87] offset:768
	global_load_dwordx4 v[180:183], v101, s[86:87] offset:832
	global_load_dwordx4 v[184:187], v150, s[86:87] offset:832
	s_add_u32 s86, s86, 0xc0000
	s_addc_u32 s87, s87, 0
	v_mov_b32_e32 v115, v229
	ds_read2_b32 v[32:33], v115 offset0:0 offset1:1
	ds_read2_b32 v[34:35], v115 offset0:2 offset1:3
	ds_read2_b32 v[36:37], v115 offset0:8 offset1:9
	ds_read2_b32 v[38:39], v115 offset0:10 offset1:11
	ds_read2_b32 v[40:41], v115 offset0:16 offset1:17
	ds_read2_b32 v[42:43], v115 offset0:18 offset1:19
	ds_read2_b32 v[44:45], v115 offset0:24 offset1:25
	ds_read2_b32 v[46:47], v115 offset0:26 offset1:27
	s_waitcnt lgkmcnt(0)
	v_mfma_f32_32x32x16_bf16 v[32:47], v[188:191], v[48:51], v[32:47]
	ds_read_b64_tr_b16 v[72:73], v231
	ds_read_b64_tr_b16 v[74:75], v231 offset:512
	ds_read_b64_tr_b16 v[76:77], v231 offset:2048
	ds_read_b64_tr_b16 v[78:79], v231 offset:2560
	ds_read_b64_tr_b16 v[220:221], v231 offset:1024
	ds_read_b64_tr_b16 v[222:223], v231 offset:1536
	ds_read_b64_tr_b16 v[224:225], v231 offset:3072
	ds_read_b64_tr_b16 v[226:227], v231 offset:3584
	s_waitcnt vmcnt(8)
	ds_write_b128 v247, v[116:119]
	ds_write_b128 v247, v[120:123] offset:1024
	ds_write_b128 v247, v[124:127] offset:2048
	ds_write_b128 v247, v[128:131] offset:3072
	ds_read_b128 v[116:119], v248
	ds_read_b128 v[120:123], v249
	ds_read_b128 v[124:127], v250
	ds_read_b128 v[128:131], v251
	ds_write_b128 v112, v[132:135]
	ds_write_b128 v112, v[136:139] offset:1024
	ds_write_b128 v112, v[140:143] offset:2048
	ds_write_b128 v112, v[144:147] offset:3072
	v_mfma_f32_32x32x16_bf16 v[32:47], v[192:195], v[52:55], v[32:47]
	v_mfma_f32_32x32x16_bf16 v[32:47], v[196:199], v[56:59], v[32:47]
	v_mfma_f32_32x32x16_bf16 v[32:47], v[200:203], v[60:63], v[32:47]
	s_nop 11
	v_exp_f32_e32 v32, v32
	v_exp_f32_e32 v33, v33
	v_exp_f32_e32 v34, v34
	v_exp_f32_e32 v35, v35
	v_exp_f32_e32 v36, v36
	v_exp_f32_e32 v37, v37
	v_exp_f32_e32 v38, v38
	v_exp_f32_e32 v39, v39
	v_exp_f32_e32 v40, v40
	v_exp_f32_e32 v41, v41
	v_exp_f32_e32 v42, v42
	v_exp_f32_e32 v43, v43
	v_exp_f32_e32 v44, v44
	v_exp_f32_e32 v45, v45
	v_exp_f32_e32 v46, v46
	v_exp_f32_e32 v47, v47
	v_cvt_pk_bf16_f32 v64, v32, v33
	v_cvt_pk_bf16_f32 v65, v34, v35
	v_cvt_pk_bf16_f32 v66, v36, v37
	v_cvt_pk_bf16_f32 v67, v38, v39
	v_cvt_pk_bf16_f32 v68, v40, v41
	v_cvt_pk_bf16_f32 v69, v42, v43
	v_cvt_pk_bf16_f32 v70, v44, v45
	v_cvt_pk_bf16_f32 v71, v46, v47
	v_pk_add_f32 v[232:233], v[232:233], v[32:33]
	v_pk_add_f32 v[232:233], v[232:233], v[34:35]
	v_pk_add_f32 v[232:233], v[232:233], v[36:37]
	v_pk_add_f32 v[232:233], v[232:233], v[38:39]
	v_pk_add_f32 v[232:233], v[232:233], v[40:41]
	v_pk_add_f32 v[232:233], v[232:233], v[42:43]
	v_pk_add_f32 v[232:233], v[232:233], v[44:45]
	v_pk_add_f32 v[232:233], v[232:233], v[46:47]
	s_waitcnt lgkmcnt(12)
	v_mfma_f32_32x32x16_bf16 v[0:15], v[64:67], v[72:75], v[0:15]
	v_mfma_f32_32x32x16_bf16 v[16:31], v[64:67], v[76:79], v[16:31]
	v_mfma_f32_32x32x16_bf16 v[0:15], v[68:71], v[220:223], v[0:15]
	v_mfma_f32_32x32x16_bf16 v[16:31], v[68:71], v[224:227], v[16:31]
	global_load_dwordx4 v[188:191], v239, s[86:87]
	global_load_dwordx4 v[192:195], v240, s[86:87]
	global_load_dwordx4 v[196:199], v241, s[86:87]
	global_load_dwordx4 v[200:203], v242, s[86:87]
	global_load_dwordx4 v[204:207], v101, s[86:87] offset:768
	global_load_dwordx4 v[208:211], v150, s[86:87] offset:768
	global_load_dwordx4 v[212:215], v101, s[86:87] offset:832
	global_load_dwordx4 v[216:219], v150, s[86:87] offset:832
	s_add_u32 s86, s86, 0xc0000
	s_addc_u32 s87, s87, 0
	ds_read2_b32 v[32:33], v115 offset0:32 offset1:33
	ds_read2_b32 v[34:35], v115 offset0:34 offset1:35
	ds_read2_b32 v[36:37], v115 offset0:40 offset1:41
	ds_read2_b32 v[38:39], v115 offset0:42 offset1:43
	ds_read2_b32 v[40:41], v115 offset0:48 offset1:49
	ds_read2_b32 v[42:43], v115 offset0:50 offset1:51
	ds_read2_b32 v[44:45], v115 offset0:56 offset1:57
	ds_read2_b32 v[46:47], v115 offset0:58 offset1:59
	s_waitcnt lgkmcnt(0)
	v_mfma_f32_32x32x16_bf16 v[32:47], v[116:119], v[48:51], v[32:47]
	ds_read_b64_tr_b16 v[72:73], v231
	ds_read_b64_tr_b16 v[74:75], v231 offset:512
	ds_read_b64_tr_b16 v[76:77], v231 offset:2048
	ds_read_b64_tr_b16 v[78:79], v231 offset:2560
	ds_read_b64_tr_b16 v[220:221], v231 offset:1024
	ds_read_b64_tr_b16 v[222:223], v231 offset:1536
	ds_read_b64_tr_b16 v[224:225], v231 offset:3072
	ds_read_b64_tr_b16 v[226:227], v231 offset:3584
	s_waitcnt vmcnt(8)
	ds_write_b128 v247, v[156:159]
	ds_write_b128 v247, v[160:163] offset:1024
	ds_write_b128 v247, v[164:167] offset:2048
	ds_write_b128 v247, v[168:171] offset:3072
	ds_read_b128 v[156:159], v248
	ds_read_b128 v[160:163], v249
	ds_read_b128 v[164:167], v250
	ds_read_b128 v[168:171], v251
	ds_write_b128 v112, v[172:175]
	ds_write_b128 v112, v[176:179] offset:1024
	ds_write_b128 v112, v[180:183] offset:2048
	ds_write_b128 v112, v[184:187] offset:3072
	v_mfma_f32_32x32x16_bf16 v[32:47], v[120:123], v[52:55], v[32:47]
	v_mfma_f32_32x32x16_bf16 v[32:47], v[124:127], v[56:59], v[32:47]
	v_mfma_f32_32x32x16_bf16 v[32:47], v[128:131], v[60:63], v[32:47]
	s_nop 11
	v_exp_f32_e32 v32, v32
	v_exp_f32_e32 v33, v33
	v_exp_f32_e32 v34, v34
	v_exp_f32_e32 v35, v35
	v_exp_f32_e32 v36, v36
	v_exp_f32_e32 v37, v37
	v_exp_f32_e32 v38, v38
	v_exp_f32_e32 v39, v39
	v_exp_f32_e32 v40, v40
	v_exp_f32_e32 v41, v41
	v_exp_f32_e32 v42, v42
	v_exp_f32_e32 v43, v43
	v_exp_f32_e32 v44, v44
	v_exp_f32_e32 v45, v45
	v_exp_f32_e32 v46, v46
	v_exp_f32_e32 v47, v47
	v_cvt_pk_bf16_f32 v64, v32, v33
	v_cvt_pk_bf16_f32 v65, v34, v35
	v_cvt_pk_bf16_f32 v66, v36, v37
	v_cvt_pk_bf16_f32 v67, v38, v39
	v_cvt_pk_bf16_f32 v68, v40, v41
	v_cvt_pk_bf16_f32 v69, v42, v43
	v_cvt_pk_bf16_f32 v70, v44, v45
	v_cvt_pk_bf16_f32 v71, v46, v47
	v_pk_add_f32 v[232:233], v[232:233], v[32:33]
	v_pk_add_f32 v[232:233], v[232:233], v[34:35]
	v_pk_add_f32 v[232:233], v[232:233], v[36:37]
	v_pk_add_f32 v[232:233], v[232:233], v[38:39]
	v_pk_add_f32 v[232:233], v[232:233], v[40:41]
	v_pk_add_f32 v[232:233], v[232:233], v[42:43]
	v_pk_add_f32 v[232:233], v[232:233], v[44:45]
	v_pk_add_f32 v[232:233], v[232:233], v[46:47]
	s_waitcnt lgkmcnt(12)
	v_mfma_f32_32x32x16_bf16 v[0:15], v[64:67], v[72:75], v[0:15]
	v_mfma_f32_32x32x16_bf16 v[16:31], v[64:67], v[76:79], v[16:31]
	v_mfma_f32_32x32x16_bf16 v[0:15], v[68:71], v[220:223], v[0:15]
	v_mfma_f32_32x32x16_bf16 v[16:31], v[68:71], v[224:227], v[16:31]
	global_load_dwordx4 v[116:119], v239, s[86:87]
	global_load_dwordx4 v[120:123], v240, s[86:87]
	global_load_dwordx4 v[124:127], v241, s[86:87]
	global_load_dwordx4 v[128:131], v242, s[86:87]
	global_load_dwordx4 v[132:135], v101, s[86:87] offset:768
	global_load_dwordx4 v[136:139], v150, s[86:87] offset:768
	global_load_dwordx4 v[140:143], v101, s[86:87] offset:832
	global_load_dwordx4 v[144:147], v150, s[86:87] offset:832
	s_add_u32 s86, s86, 0xc0000
	s_addc_u32 s87, s87, 0
	ds_read2_b32 v[32:33], v115 offset0:64 offset1:65
	ds_read2_b32 v[34:35], v115 offset0:66 offset1:67
	ds_read2_b32 v[36:37], v115 offset0:72 offset1:73
	ds_read2_b32 v[38:39], v115 offset0:74 offset1:75
	ds_read2_b32 v[40:41], v115 offset0:80 offset1:81
	ds_read2_b32 v[42:43], v115 offset0:82 offset1:83
	ds_read2_b32 v[44:45], v115 offset0:88 offset1:89
	ds_read2_b32 v[46:47], v115 offset0:90 offset1:91
	s_waitcnt lgkmcnt(0)
	v_mfma_f32_32x32x16_bf16 v[32:47], v[156:159], v[48:51], v[32:47]
	ds_read_b64_tr_b16 v[72:73], v231
	ds_read_b64_tr_b16 v[74:75], v231 offset:512
	ds_read_b64_tr_b16 v[76:77], v231 offset:2048
	ds_read_b64_tr_b16 v[78:79], v231 offset:2560
	ds_read_b64_tr_b16 v[220:221], v231 offset:1024
	ds_read_b64_tr_b16 v[222:223], v231 offset:1536
	ds_read_b64_tr_b16 v[224:225], v231 offset:3072
	ds_read_b64_tr_b16 v[226:227], v231 offset:3584
	s_waitcnt vmcnt(8)
	ds_write_b128 v247, v[188:191]
	ds_write_b128 v247, v[192:195] offset:1024
	ds_write_b128 v247, v[196:199] offset:2048
	ds_write_b128 v247, v[200:203] offset:3072
	ds_read_b128 v[188:191], v248
	ds_read_b128 v[192:195], v249
	ds_read_b128 v[196:199], v250
	ds_read_b128 v[200:203], v251
	ds_write_b128 v112, v[204:207]
	ds_write_b128 v112, v[208:211] offset:1024
	ds_write_b128 v112, v[212:215] offset:2048
	ds_write_b128 v112, v[216:219] offset:3072
	v_mfma_f32_32x32x16_bf16 v[32:47], v[160:163], v[52:55], v[32:47]
	v_mfma_f32_32x32x16_bf16 v[32:47], v[164:167], v[56:59], v[32:47]
	v_mfma_f32_32x32x16_bf16 v[32:47], v[168:171], v[60:63], v[32:47]
	s_nop 11
	v_exp_f32_e32 v32, v32
	v_exp_f32_e32 v33, v33
	v_exp_f32_e32 v34, v34
	v_exp_f32_e32 v35, v35
	v_exp_f32_e32 v36, v36
	v_exp_f32_e32 v37, v37
	v_exp_f32_e32 v38, v38
	v_exp_f32_e32 v39, v39
	v_exp_f32_e32 v40, v40
	v_exp_f32_e32 v41, v41
	v_exp_f32_e32 v42, v42
	v_exp_f32_e32 v43, v43
	v_exp_f32_e32 v44, v44
	v_exp_f32_e32 v45, v45
	v_exp_f32_e32 v46, v46
	v_exp_f32_e32 v47, v47
	v_cvt_pk_bf16_f32 v64, v32, v33
	v_cvt_pk_bf16_f32 v65, v34, v35
	v_cvt_pk_bf16_f32 v66, v36, v37
	v_cvt_pk_bf16_f32 v67, v38, v39
	v_cvt_pk_bf16_f32 v68, v40, v41
	v_cvt_pk_bf16_f32 v69, v42, v43
	v_cvt_pk_bf16_f32 v70, v44, v45
	v_cvt_pk_bf16_f32 v71, v46, v47
	v_pk_add_f32 v[232:233], v[232:233], v[32:33]
	v_pk_add_f32 v[232:233], v[232:233], v[34:35]
	v_pk_add_f32 v[232:233], v[232:233], v[36:37]
	v_pk_add_f32 v[232:233], v[232:233], v[38:39]
	v_pk_add_f32 v[232:233], v[232:233], v[40:41]
	v_pk_add_f32 v[232:233], v[232:233], v[42:43]
	v_pk_add_f32 v[232:233], v[232:233], v[44:45]
	v_pk_add_f32 v[232:233], v[232:233], v[46:47]
	s_waitcnt lgkmcnt(12)
	v_mfma_f32_32x32x16_bf16 v[0:15], v[64:67], v[72:75], v[0:15]
	v_mfma_f32_32x32x16_bf16 v[16:31], v[64:67], v[76:79], v[16:31]
	v_mfma_f32_32x32x16_bf16 v[0:15], v[68:71], v[220:223], v[0:15]
	v_mfma_f32_32x32x16_bf16 v[16:31], v[68:71], v[224:227], v[16:31]
	global_load_dwordx4 v[156:159], v239, s[86:87]
	global_load_dwordx4 v[160:163], v240, s[86:87]
	global_load_dwordx4 v[164:167], v241, s[86:87]
	global_load_dwordx4 v[168:171], v242, s[86:87]
	global_load_dwordx4 v[172:175], v101, s[86:87] offset:768
	global_load_dwordx4 v[176:179], v150, s[86:87] offset:768
	global_load_dwordx4 v[180:183], v101, s[86:87] offset:832
	global_load_dwordx4 v[184:187], v150, s[86:87] offset:832
	s_add_u32 s86, s86, 0xc0000
	s_addc_u32 s87, s87, 0
	ds_read2_b32 v[32:33], v115 offset0:96 offset1:97
	ds_read2_b32 v[34:35], v115 offset0:98 offset1:99
	ds_read2_b32 v[36:37], v115 offset0:104 offset1:105
	ds_read2_b32 v[38:39], v115 offset0:106 offset1:107
	ds_read2_b32 v[40:41], v115 offset0:112 offset1:113
	ds_read2_b32 v[42:43], v115 offset0:114 offset1:115
	ds_read2_b32 v[44:45], v115 offset0:120 offset1:121
	ds_read2_b32 v[46:47], v115 offset0:122 offset1:123
	s_waitcnt lgkmcnt(0)
	v_mfma_f32_32x32x16_bf16 v[32:47], v[188:191], v[48:51], v[32:47]
	ds_read_b64_tr_b16 v[72:73], v231
	ds_read_b64_tr_b16 v[74:75], v231 offset:512
	ds_read_b64_tr_b16 v[76:77], v231 offset:2048
	ds_read_b64_tr_b16 v[78:79], v231 offset:2560
	ds_read_b64_tr_b16 v[220:221], v231 offset:1024
	ds_read_b64_tr_b16 v[222:223], v231 offset:1536
	ds_read_b64_tr_b16 v[224:225], v231 offset:3072
	ds_read_b64_tr_b16 v[226:227], v231 offset:3584
	s_waitcnt vmcnt(8)
	ds_write_b128 v247, v[116:119]
	ds_write_b128 v247, v[120:123] offset:1024
	ds_write_b128 v247, v[124:127] offset:2048
	ds_write_b128 v247, v[128:131] offset:3072
	ds_read_b128 v[116:119], v248
	ds_read_b128 v[120:123], v249
	ds_read_b128 v[124:127], v250
	ds_read_b128 v[128:131], v251
	ds_write_b128 v112, v[132:135]
	ds_write_b128 v112, v[136:139] offset:1024
	ds_write_b128 v112, v[140:143] offset:2048
	ds_write_b128 v112, v[144:147] offset:3072
	v_mfma_f32_32x32x16_bf16 v[32:47], v[192:195], v[52:55], v[32:47]
	v_mfma_f32_32x32x16_bf16 v[32:47], v[196:199], v[56:59], v[32:47]
	v_mfma_f32_32x32x16_bf16 v[32:47], v[200:203], v[60:63], v[32:47]
	s_nop 11
	v_exp_f32_e32 v32, v32
	v_exp_f32_e32 v33, v33
	v_exp_f32_e32 v34, v34
	v_exp_f32_e32 v35, v35
	v_exp_f32_e32 v36, v36
	v_exp_f32_e32 v37, v37
	v_exp_f32_e32 v38, v38
	v_exp_f32_e32 v39, v39
	v_exp_f32_e32 v40, v40
	v_exp_f32_e32 v41, v41
	v_exp_f32_e32 v42, v42
	v_exp_f32_e32 v43, v43
	v_exp_f32_e32 v44, v44
	v_exp_f32_e32 v45, v45
	v_exp_f32_e32 v46, v46
	v_exp_f32_e32 v47, v47
	v_cvt_pk_bf16_f32 v64, v32, v33
	v_cvt_pk_bf16_f32 v65, v34, v35
	v_cvt_pk_bf16_f32 v66, v36, v37
	v_cvt_pk_bf16_f32 v67, v38, v39
	v_cvt_pk_bf16_f32 v68, v40, v41
	v_cvt_pk_bf16_f32 v69, v42, v43
	v_cvt_pk_bf16_f32 v70, v44, v45
	v_cvt_pk_bf16_f32 v71, v46, v47
	v_pk_add_f32 v[232:233], v[232:233], v[32:33]
	v_pk_add_f32 v[232:233], v[232:233], v[34:35]
	v_pk_add_f32 v[232:233], v[232:233], v[36:37]
	v_pk_add_f32 v[232:233], v[232:233], v[38:39]
	v_pk_add_f32 v[232:233], v[232:233], v[40:41]
	v_pk_add_f32 v[232:233], v[232:233], v[42:43]
	v_pk_add_f32 v[232:233], v[232:233], v[44:45]
	v_pk_add_f32 v[232:233], v[232:233], v[46:47]
	s_waitcnt lgkmcnt(12)
	v_mfma_f32_32x32x16_bf16 v[0:15], v[64:67], v[72:75], v[0:15]
	v_mfma_f32_32x32x16_bf16 v[16:31], v[64:67], v[76:79], v[16:31]
	v_mfma_f32_32x32x16_bf16 v[0:15], v[68:71], v[220:223], v[0:15]
	v_mfma_f32_32x32x16_bf16 v[16:31], v[68:71], v[224:227], v[16:31]
	global_load_dwordx4 v[188:191], v239, s[86:87]
	global_load_dwordx4 v[192:195], v240, s[86:87]
	global_load_dwordx4 v[196:199], v241, s[86:87]
	global_load_dwordx4 v[200:203], v242, s[86:87]
	global_load_dwordx4 v[204:207], v101, s[86:87] offset:768
	global_load_dwordx4 v[208:211], v150, s[86:87] offset:768
	global_load_dwordx4 v[212:215], v101, s[86:87] offset:832
	global_load_dwordx4 v[216:219], v150, s[86:87] offset:832
	s_add_u32 s86, s86, 0xc0000
	s_addc_u32 s87, s87, 0
	ds_read2_b32 v[32:33], v115 offset0:128 offset1:129
	ds_read2_b32 v[34:35], v115 offset0:130 offset1:131
	ds_read2_b32 v[36:37], v115 offset0:136 offset1:137
	ds_read2_b32 v[38:39], v115 offset0:138 offset1:139
	ds_read2_b32 v[40:41], v115 offset0:144 offset1:145
	ds_read2_b32 v[42:43], v115 offset0:146 offset1:147
	ds_read2_b32 v[44:45], v115 offset0:152 offset1:153
	ds_read2_b32 v[46:47], v115 offset0:154 offset1:155
	s_waitcnt lgkmcnt(0)
	v_mfma_f32_32x32x16_bf16 v[32:47], v[116:119], v[48:51], v[32:47]
	ds_read_b64_tr_b16 v[72:73], v231
	ds_read_b64_tr_b16 v[74:75], v231 offset:512
	ds_read_b64_tr_b16 v[76:77], v231 offset:2048
	ds_read_b64_tr_b16 v[78:79], v231 offset:2560
	ds_read_b64_tr_b16 v[220:221], v231 offset:1024
	ds_read_b64_tr_b16 v[222:223], v231 offset:1536
	ds_read_b64_tr_b16 v[224:225], v231 offset:3072
	ds_read_b64_tr_b16 v[226:227], v231 offset:3584
	s_waitcnt vmcnt(8)
	ds_write_b128 v247, v[156:159]
	ds_write_b128 v247, v[160:163] offset:1024
	ds_write_b128 v247, v[164:167] offset:2048
	ds_write_b128 v247, v[168:171] offset:3072
	ds_read_b128 v[156:159], v248
	ds_read_b128 v[160:163], v249
	ds_read_b128 v[164:167], v250
	ds_read_b128 v[168:171], v251
	ds_write_b128 v112, v[172:175]
	ds_write_b128 v112, v[176:179] offset:1024
	ds_write_b128 v112, v[180:183] offset:2048
	ds_write_b128 v112, v[184:187] offset:3072
	v_mfma_f32_32x32x16_bf16 v[32:47], v[120:123], v[52:55], v[32:47]
	v_mfma_f32_32x32x16_bf16 v[32:47], v[124:127], v[56:59], v[32:47]
	v_mfma_f32_32x32x16_bf16 v[32:47], v[128:131], v[60:63], v[32:47]
	s_nop 11
	v_exp_f32_e32 v32, v32
	v_exp_f32_e32 v33, v33
	v_exp_f32_e32 v34, v34
	v_exp_f32_e32 v35, v35
	v_exp_f32_e32 v36, v36
	v_exp_f32_e32 v37, v37
	v_exp_f32_e32 v38, v38
	v_exp_f32_e32 v39, v39
	v_exp_f32_e32 v40, v40
	v_exp_f32_e32 v41, v41
	v_exp_f32_e32 v42, v42
	v_exp_f32_e32 v43, v43
	v_exp_f32_e32 v44, v44
	v_exp_f32_e32 v45, v45
	v_exp_f32_e32 v46, v46
	v_exp_f32_e32 v47, v47
	v_cvt_pk_bf16_f32 v64, v32, v33
	v_cvt_pk_bf16_f32 v65, v34, v35
	v_cvt_pk_bf16_f32 v66, v36, v37
	v_cvt_pk_bf16_f32 v67, v38, v39
	v_cvt_pk_bf16_f32 v68, v40, v41
	v_cvt_pk_bf16_f32 v69, v42, v43
	v_cvt_pk_bf16_f32 v70, v44, v45
	v_cvt_pk_bf16_f32 v71, v46, v47
	v_pk_add_f32 v[232:233], v[232:233], v[32:33]
	v_pk_add_f32 v[232:233], v[232:233], v[34:35]
	v_pk_add_f32 v[232:233], v[232:233], v[36:37]
	v_pk_add_f32 v[232:233], v[232:233], v[38:39]
	v_pk_add_f32 v[232:233], v[232:233], v[40:41]
	v_pk_add_f32 v[232:233], v[232:233], v[42:43]
	v_pk_add_f32 v[232:233], v[232:233], v[44:45]
	v_pk_add_f32 v[232:233], v[232:233], v[46:47]
	s_waitcnt lgkmcnt(12)
	v_mfma_f32_32x32x16_bf16 v[0:15], v[64:67], v[72:75], v[0:15]
	v_mfma_f32_32x32x16_bf16 v[16:31], v[64:67], v[76:79], v[16:31]
	v_mfma_f32_32x32x16_bf16 v[0:15], v[68:71], v[220:223], v[0:15]
	v_mfma_f32_32x32x16_bf16 v[16:31], v[68:71], v[224:227], v[16:31]
	global_load_dwordx4 v[116:119], v239, s[86:87]
	global_load_dwordx4 v[120:123], v240, s[86:87]
	global_load_dwordx4 v[124:127], v241, s[86:87]
	global_load_dwordx4 v[128:131], v242, s[86:87]
	global_load_dwordx4 v[132:135], v101, s[86:87] offset:768
	global_load_dwordx4 v[136:139], v150, s[86:87] offset:768
	global_load_dwordx4 v[140:143], v101, s[86:87] offset:832
	global_load_dwordx4 v[144:147], v150, s[86:87] offset:832
	ds_read2_b32 v[32:33], v115 offset0:160 offset1:161
	ds_read2_b32 v[34:35], v115 offset0:162 offset1:163
	ds_read2_b32 v[36:37], v115 offset0:168 offset1:169
	ds_read2_b32 v[38:39], v115 offset0:170 offset1:171
	ds_read2_b32 v[40:41], v115 offset0:176 offset1:177
	ds_read2_b32 v[42:43], v115 offset0:178 offset1:179
	ds_read2_b32 v[44:45], v115 offset0:184 offset1:185
	ds_read2_b32 v[46:47], v115 offset0:186 offset1:187
	s_waitcnt lgkmcnt(0)
	v_mfma_f32_32x32x16_bf16 v[32:47], v[156:159], v[48:51], v[32:47]
	ds_read_b64_tr_b16 v[72:73], v231
	ds_read_b64_tr_b16 v[74:75], v231 offset:512
	ds_read_b64_tr_b16 v[76:77], v231 offset:2048
	ds_read_b64_tr_b16 v[78:79], v231 offset:2560
	ds_read_b64_tr_b16 v[220:221], v231 offset:1024
	ds_read_b64_tr_b16 v[222:223], v231 offset:1536
	ds_read_b64_tr_b16 v[224:225], v231 offset:3072
	ds_read_b64_tr_b16 v[226:227], v231 offset:3584
	s_waitcnt vmcnt(8)
	ds_write_b128 v247, v[188:191]
	ds_write_b128 v247, v[192:195] offset:1024
	ds_write_b128 v247, v[196:199] offset:2048
	ds_write_b128 v247, v[200:203] offset:3072
	ds_read_b128 v[188:191], v248
	ds_read_b128 v[192:195], v249
	ds_read_b128 v[196:199], v250
	ds_read_b128 v[200:203], v251
	ds_write_b128 v112, v[204:207]
	ds_write_b128 v112, v[208:211] offset:1024
	ds_write_b128 v112, v[212:215] offset:2048
	ds_write_b128 v112, v[216:219] offset:3072
	v_mfma_f32_32x32x16_bf16 v[32:47], v[160:163], v[52:55], v[32:47]
	v_mfma_f32_32x32x16_bf16 v[32:47], v[164:167], v[56:59], v[32:47]
	v_mfma_f32_32x32x16_bf16 v[32:47], v[168:171], v[60:63], v[32:47]
	s_nop 11
	v_exp_f32_e32 v32, v32
	v_exp_f32_e32 v33, v33
	v_exp_f32_e32 v34, v34
	v_exp_f32_e32 v35, v35
	v_exp_f32_e32 v36, v36
	v_exp_f32_e32 v37, v37
	v_exp_f32_e32 v38, v38
	v_exp_f32_e32 v39, v39
	v_exp_f32_e32 v40, v40
	v_exp_f32_e32 v41, v41
	v_exp_f32_e32 v42, v42
	v_exp_f32_e32 v43, v43
	v_exp_f32_e32 v44, v44
	v_exp_f32_e32 v45, v45
	v_exp_f32_e32 v46, v46
	v_exp_f32_e32 v47, v47
	v_cvt_pk_bf16_f32 v64, v32, v33
	v_cvt_pk_bf16_f32 v65, v34, v35
	v_cvt_pk_bf16_f32 v66, v36, v37
	v_cvt_pk_bf16_f32 v67, v38, v39
	v_cvt_pk_bf16_f32 v68, v40, v41
	v_cvt_pk_bf16_f32 v69, v42, v43
	v_cvt_pk_bf16_f32 v70, v44, v45
	v_cvt_pk_bf16_f32 v71, v46, v47
	v_pk_add_f32 v[232:233], v[232:233], v[32:33]
	v_pk_add_f32 v[232:233], v[232:233], v[34:35]
	v_pk_add_f32 v[232:233], v[232:233], v[36:37]
	v_pk_add_f32 v[232:233], v[232:233], v[38:39]
	v_pk_add_f32 v[232:233], v[232:233], v[40:41]
	v_pk_add_f32 v[232:233], v[232:233], v[42:43]
	v_pk_add_f32 v[232:233], v[232:233], v[44:45]
	v_pk_add_f32 v[232:233], v[232:233], v[46:47]
	s_waitcnt lgkmcnt(12)
	v_mfma_f32_32x32x16_bf16 v[0:15], v[64:67], v[72:75], v[0:15]
	v_mfma_f32_32x32x16_bf16 v[16:31], v[64:67], v[76:79], v[16:31]
	v_mfma_f32_32x32x16_bf16 v[0:15], v[68:71], v[220:223], v[0:15]
	v_mfma_f32_32x32x16_bf16 v[16:31], v[68:71], v[224:227], v[16:31]
	global_load_dwordx4 v[156:159], v243, s[88:89]
	global_load_dwordx4 v[160:163], v244, s[88:89]
	global_load_dwordx4 v[164:167], v245, s[88:89]
	global_load_dwordx4 v[168:171], v246, s[88:89]
	global_load_dwordx4 v[172:175], v148, s[88:89] offset:768
	global_load_dwordx4 v[176:179], v151, s[88:89] offset:768
	global_load_dwordx4 v[180:183], v148, s[88:89] offset:832
	global_load_dwordx4 v[184:187], v151, s[88:89] offset:832
	s_add_u32 s88, s88, 0x300000
	s_addc_u32 s89, s89, 0
	ds_read2_b32 v[32:33], v115 offset0:192 offset1:193
	ds_read2_b32 v[34:35], v115 offset0:194 offset1:195
	ds_read2_b32 v[36:37], v115 offset0:200 offset1:201
	ds_read2_b32 v[38:39], v115 offset0:202 offset1:203
	ds_read2_b32 v[40:41], v115 offset0:208 offset1:209
	ds_read2_b32 v[42:43], v115 offset0:210 offset1:211
	ds_read2_b32 v[44:45], v115 offset0:216 offset1:217
	ds_read2_b32 v[46:47], v115 offset0:218 offset1:219
	s_waitcnt lgkmcnt(0)
	v_mfma_f32_32x32x16_bf16 v[32:47], v[188:191], v[48:51], v[32:47]
	ds_read_b64_tr_b16 v[72:73], v231
	ds_read_b64_tr_b16 v[74:75], v231 offset:512
	ds_read_b64_tr_b16 v[76:77], v231 offset:2048
	ds_read_b64_tr_b16 v[78:79], v231 offset:2560
	ds_read_b64_tr_b16 v[220:221], v231 offset:1024
	ds_read_b64_tr_b16 v[222:223], v231 offset:1536
	ds_read_b64_tr_b16 v[224:225], v231 offset:3072
	ds_read_b64_tr_b16 v[226:227], v231 offset:3584
	s_waitcnt vmcnt(8)
	ds_write_b128 v247, v[116:119]
	ds_write_b128 v247, v[120:123] offset:1024
	ds_write_b128 v247, v[124:127] offset:2048
	ds_write_b128 v247, v[128:131] offset:3072
	ds_read_b128 v[116:119], v248
	ds_read_b128 v[120:123], v249
	ds_read_b128 v[124:127], v250
	ds_read_b128 v[128:131], v251
	ds_write_b128 v112, v[132:135]
	ds_write_b128 v112, v[136:139] offset:1024
	ds_write_b128 v112, v[140:143] offset:2048
	ds_write_b128 v112, v[144:147] offset:3072
	v_mfma_f32_32x32x16_bf16 v[32:47], v[192:195], v[52:55], v[32:47]
	v_mfma_f32_32x32x16_bf16 v[32:47], v[196:199], v[56:59], v[32:47]
	v_mfma_f32_32x32x16_bf16 v[32:47], v[200:203], v[60:63], v[32:47]
	s_nop 11
	v_exp_f32_e32 v32, v32
	v_exp_f32_e32 v33, v33
	v_exp_f32_e32 v34, v34
	v_exp_f32_e32 v35, v35
	v_exp_f32_e32 v36, v36
	v_exp_f32_e32 v37, v37
	v_exp_f32_e32 v38, v38
	v_exp_f32_e32 v39, v39
	v_exp_f32_e32 v40, v40
	v_exp_f32_e32 v41, v41
	v_exp_f32_e32 v42, v42
	v_exp_f32_e32 v43, v43
	v_exp_f32_e32 v44, v44
	v_exp_f32_e32 v45, v45
	v_exp_f32_e32 v46, v46
	v_exp_f32_e32 v47, v47
	v_cvt_pk_bf16_f32 v64, v32, v33
	v_cvt_pk_bf16_f32 v65, v34, v35
	v_cvt_pk_bf16_f32 v66, v36, v37
	v_cvt_pk_bf16_f32 v67, v38, v39
	v_cvt_pk_bf16_f32 v68, v40, v41
	v_cvt_pk_bf16_f32 v69, v42, v43
	v_cvt_pk_bf16_f32 v70, v44, v45
	v_cvt_pk_bf16_f32 v71, v46, v47
	v_pk_add_f32 v[232:233], v[232:233], v[32:33]
	v_pk_add_f32 v[232:233], v[232:233], v[34:35]
	v_pk_add_f32 v[232:233], v[232:233], v[36:37]
	v_pk_add_f32 v[232:233], v[232:233], v[38:39]
	v_pk_add_f32 v[232:233], v[232:233], v[40:41]
	v_pk_add_f32 v[232:233], v[232:233], v[42:43]
	v_pk_add_f32 v[232:233], v[232:233], v[44:45]
	v_pk_add_f32 v[232:233], v[232:233], v[46:47]
	s_waitcnt lgkmcnt(12)
	v_mfma_f32_32x32x16_bf16 v[0:15], v[64:67], v[72:75], v[0:15]
	v_mfma_f32_32x32x16_bf16 v[16:31], v[64:67], v[76:79], v[16:31]
	v_mfma_f32_32x32x16_bf16 v[0:15], v[68:71], v[220:223], v[0:15]
	v_mfma_f32_32x32x16_bf16 v[16:31], v[68:71], v[224:227], v[16:31]
	global_load_dwordx4 v[188:191], v243, s[88:89]
	global_load_dwordx4 v[192:195], v244, s[88:89]
	global_load_dwordx4 v[196:199], v245, s[88:89]
	global_load_dwordx4 v[200:203], v246, s[88:89]
	global_load_dwordx4 v[204:207], v148, s[88:89] offset:768
	global_load_dwordx4 v[208:211], v151, s[88:89] offset:768
	global_load_dwordx4 v[212:215], v148, s[88:89] offset:832
	global_load_dwordx4 v[216:219], v151, s[88:89] offset:832
	s_add_u32 s88, s88, 0x300000
	s_addc_u32 s89, s89, 0
	ds_read2_b32 v[32:33], v115 offset0:224 offset1:225
	ds_read2_b32 v[34:35], v115 offset0:226 offset1:227
	ds_read2_b32 v[36:37], v115 offset0:232 offset1:233
	ds_read2_b32 v[38:39], v115 offset0:234 offset1:235
	ds_read2_b32 v[40:41], v115 offset0:240 offset1:241
	ds_read2_b32 v[42:43], v115 offset0:242 offset1:243
	ds_read2_b32 v[44:45], v115 offset0:248 offset1:249
	ds_read2_b32 v[46:47], v115 offset0:250 offset1:251
	s_waitcnt lgkmcnt(0)
	v_mfma_f32_32x32x16_bf16 v[32:47], v[116:119], v[48:51], v[32:47]
	ds_read_b64_tr_b16 v[72:73], v231
	ds_read_b64_tr_b16 v[74:75], v231 offset:512
	ds_read_b64_tr_b16 v[76:77], v231 offset:2048
	ds_read_b64_tr_b16 v[78:79], v231 offset:2560
	ds_read_b64_tr_b16 v[220:221], v231 offset:1024
	ds_read_b64_tr_b16 v[222:223], v231 offset:1536
	ds_read_b64_tr_b16 v[224:225], v231 offset:3072
	ds_read_b64_tr_b16 v[226:227], v231 offset:3584
	s_waitcnt vmcnt(8)
	ds_write_b128 v247, v[156:159]
	ds_write_b128 v247, v[160:163] offset:1024
	ds_write_b128 v247, v[164:167] offset:2048
	ds_write_b128 v247, v[168:171] offset:3072
	ds_read_b128 v[156:159], v248
	ds_read_b128 v[160:163], v249
	ds_read_b128 v[164:167], v250
	ds_read_b128 v[168:171], v251
	ds_write_b128 v112, v[172:175]
	ds_write_b128 v112, v[176:179] offset:1024
	ds_write_b128 v112, v[180:183] offset:2048
	ds_write_b128 v112, v[184:187] offset:3072
	v_mfma_f32_32x32x16_bf16 v[32:47], v[120:123], v[52:55], v[32:47]
	v_mfma_f32_32x32x16_bf16 v[32:47], v[124:127], v[56:59], v[32:47]
	v_mfma_f32_32x32x16_bf16 v[32:47], v[128:131], v[60:63], v[32:47]
	s_nop 11
	v_exp_f32_e32 v32, v32
	v_exp_f32_e32 v33, v33
	v_exp_f32_e32 v34, v34
	v_exp_f32_e32 v35, v35
	v_exp_f32_e32 v36, v36
	v_exp_f32_e32 v37, v37
	v_exp_f32_e32 v38, v38
	v_exp_f32_e32 v39, v39
	v_exp_f32_e32 v40, v40
	v_exp_f32_e32 v41, v41
	v_exp_f32_e32 v42, v42
	v_exp_f32_e32 v43, v43
	v_exp_f32_e32 v44, v44
	v_exp_f32_e32 v45, v45
	v_exp_f32_e32 v46, v46
	v_exp_f32_e32 v47, v47
	v_cvt_pk_bf16_f32 v64, v32, v33
	v_cvt_pk_bf16_f32 v65, v34, v35
	v_cvt_pk_bf16_f32 v66, v36, v37
	v_cvt_pk_bf16_f32 v67, v38, v39
	v_cvt_pk_bf16_f32 v68, v40, v41
	v_cvt_pk_bf16_f32 v69, v42, v43
	v_cvt_pk_bf16_f32 v70, v44, v45
	v_cvt_pk_bf16_f32 v71, v46, v47
	v_pk_add_f32 v[232:233], v[232:233], v[32:33]
	v_pk_add_f32 v[232:233], v[232:233], v[34:35]
	v_pk_add_f32 v[232:233], v[232:233], v[36:37]
	v_pk_add_f32 v[232:233], v[232:233], v[38:39]
	v_pk_add_f32 v[232:233], v[232:233], v[40:41]
	v_pk_add_f32 v[232:233], v[232:233], v[42:43]
	v_pk_add_f32 v[232:233], v[232:233], v[44:45]
	v_pk_add_f32 v[232:233], v[232:233], v[46:47]
	s_waitcnt lgkmcnt(12)
	v_mfma_f32_32x32x16_bf16 v[0:15], v[64:67], v[72:75], v[0:15]
	v_mfma_f32_32x32x16_bf16 v[16:31], v[64:67], v[76:79], v[16:31]
	v_mfma_f32_32x32x16_bf16 v[0:15], v[68:71], v[220:223], v[0:15]
	v_mfma_f32_32x32x16_bf16 v[16:31], v[68:71], v[224:227], v[16:31]
	global_load_dwordx4 v[116:119], v243, s[88:89]
	global_load_dwordx4 v[120:123], v244, s[88:89]
	global_load_dwordx4 v[124:127], v245, s[88:89]
	global_load_dwordx4 v[128:131], v246, s[88:89]
	global_load_dwordx4 v[132:135], v148, s[88:89] offset:768
	global_load_dwordx4 v[136:139], v151, s[88:89] offset:768
	global_load_dwordx4 v[140:143], v148, s[88:89] offset:832
	global_load_dwordx4 v[144:147], v151, s[88:89] offset:832
	s_add_u32 s88, s88, 0x300000
	s_addc_u32 s89, s89, 0
	v_mov_b32_e32 v115, v230
	ds_read2_b32 v[32:33], v115 offset0:0 offset1:1
	ds_read2_b32 v[34:35], v115 offset0:2 offset1:3
	ds_read2_b32 v[36:37], v115 offset0:8 offset1:9
	ds_read2_b32 v[38:39], v115 offset0:10 offset1:11
	ds_read2_b32 v[40:41], v115 offset0:16 offset1:17
	ds_read2_b32 v[42:43], v115 offset0:18 offset1:19
	ds_read2_b32 v[44:45], v115 offset0:24 offset1:25
	ds_read2_b32 v[46:47], v115 offset0:26 offset1:27
	s_waitcnt lgkmcnt(0)
	v_mfma_f32_32x32x16_bf16 v[32:47], v[156:159], v[48:51], v[32:47]
	ds_read_b64_tr_b16 v[72:73], v231
	ds_read_b64_tr_b16 v[74:75], v231 offset:512
	ds_read_b64_tr_b16 v[76:77], v231 offset:2048
	ds_read_b64_tr_b16 v[78:79], v231 offset:2560
	ds_read_b64_tr_b16 v[220:221], v231 offset:1024
	ds_read_b64_tr_b16 v[222:223], v231 offset:1536
	ds_read_b64_tr_b16 v[224:225], v231 offset:3072
	ds_read_b64_tr_b16 v[226:227], v231 offset:3584
	s_waitcnt vmcnt(8)
	ds_write_b128 v247, v[188:191]
	ds_write_b128 v247, v[192:195] offset:1024
	ds_write_b128 v247, v[196:199] offset:2048
	ds_write_b128 v247, v[200:203] offset:3072
	ds_read_b128 v[188:191], v248
	ds_read_b128 v[192:195], v249
	ds_read_b128 v[196:199], v250
	ds_read_b128 v[200:203], v251
	ds_write_b128 v112, v[204:207]
	ds_write_b128 v112, v[208:211] offset:1024
	ds_write_b128 v112, v[212:215] offset:2048
	ds_write_b128 v112, v[216:219] offset:3072
	v_mfma_f32_32x32x16_bf16 v[32:47], v[160:163], v[52:55], v[32:47]
	v_mfma_f32_32x32x16_bf16 v[32:47], v[164:167], v[56:59], v[32:47]
	v_mfma_f32_32x32x16_bf16 v[32:47], v[168:171], v[60:63], v[32:47]
	s_nop 11
	v_exp_f32_e32 v32, v32
	v_exp_f32_e32 v33, v33
	v_exp_f32_e32 v34, v34
	v_exp_f32_e32 v35, v35
	v_exp_f32_e32 v36, v36
	v_exp_f32_e32 v37, v37
	v_exp_f32_e32 v38, v38
	v_exp_f32_e32 v39, v39
	v_exp_f32_e32 v40, v40
	v_exp_f32_e32 v41, v41
	v_exp_f32_e32 v42, v42
	v_exp_f32_e32 v43, v43
	v_exp_f32_e32 v44, v44
	v_exp_f32_e32 v45, v45
	v_exp_f32_e32 v46, v46
	v_exp_f32_e32 v47, v47
	v_cvt_pk_bf16_f32 v64, v32, v33
	v_cvt_pk_bf16_f32 v65, v34, v35
	v_cvt_pk_bf16_f32 v66, v36, v37
	v_cvt_pk_bf16_f32 v67, v38, v39
	v_cvt_pk_bf16_f32 v68, v40, v41
	v_cvt_pk_bf16_f32 v69, v42, v43
	v_cvt_pk_bf16_f32 v70, v44, v45
	v_cvt_pk_bf16_f32 v71, v46, v47
	v_pk_add_f32 v[232:233], v[232:233], v[32:33]
	v_pk_add_f32 v[232:233], v[232:233], v[34:35]
	v_pk_add_f32 v[232:233], v[232:233], v[36:37]
	v_pk_add_f32 v[232:233], v[232:233], v[38:39]
	v_pk_add_f32 v[232:233], v[232:233], v[40:41]
	v_pk_add_f32 v[232:233], v[232:233], v[42:43]
	v_pk_add_f32 v[232:233], v[232:233], v[44:45]
	v_pk_add_f32 v[232:233], v[232:233], v[46:47]
	s_waitcnt lgkmcnt(12)
	v_mfma_f32_32x32x16_bf16 v[0:15], v[64:67], v[72:75], v[0:15]
	v_mfma_f32_32x32x16_bf16 v[16:31], v[64:67], v[76:79], v[16:31]
	v_mfma_f32_32x32x16_bf16 v[0:15], v[68:71], v[220:223], v[0:15]
	v_mfma_f32_32x32x16_bf16 v[16:31], v[68:71], v[224:227], v[16:31]
	global_load_dwordx4 v[156:159], v243, s[88:89]
	global_load_dwordx4 v[160:163], v244, s[88:89]
	global_load_dwordx4 v[164:167], v245, s[88:89]
	global_load_dwordx4 v[168:171], v246, s[88:89]
	global_load_dwordx4 v[172:175], v148, s[88:89] offset:768
	global_load_dwordx4 v[176:179], v151, s[88:89] offset:768
	global_load_dwordx4 v[180:183], v148, s[88:89] offset:832
	global_load_dwordx4 v[184:187], v151, s[88:89] offset:832
	s_add_u32 s88, s88, 0x300000
	s_addc_u32 s89, s89, 0
	ds_read2_b32 v[32:33], v115 offset0:32 offset1:33
	ds_read2_b32 v[34:35], v115 offset0:34 offset1:35
	ds_read2_b32 v[36:37], v115 offset0:40 offset1:41
	ds_read2_b32 v[38:39], v115 offset0:42 offset1:43
	ds_read2_b32 v[40:41], v115 offset0:48 offset1:49
	ds_read2_b32 v[42:43], v115 offset0:50 offset1:51
	ds_read2_b32 v[44:45], v115 offset0:56 offset1:57
	ds_read2_b32 v[46:47], v115 offset0:58 offset1:59
	s_waitcnt lgkmcnt(0)
	v_mfma_f32_32x32x16_bf16 v[32:47], v[188:191], v[48:51], v[32:47]
	ds_read_b64_tr_b16 v[72:73], v231
	ds_read_b64_tr_b16 v[74:75], v231 offset:512
	ds_read_b64_tr_b16 v[76:77], v231 offset:2048
	ds_read_b64_tr_b16 v[78:79], v231 offset:2560
	ds_read_b64_tr_b16 v[220:221], v231 offset:1024
	ds_read_b64_tr_b16 v[222:223], v231 offset:1536
	ds_read_b64_tr_b16 v[224:225], v231 offset:3072
	ds_read_b64_tr_b16 v[226:227], v231 offset:3584
	s_waitcnt vmcnt(8)
	ds_write_b128 v247, v[116:119]
	ds_write_b128 v247, v[120:123] offset:1024
	ds_write_b128 v247, v[124:127] offset:2048
	ds_write_b128 v247, v[128:131] offset:3072
	ds_read_b128 v[116:119], v248
	ds_read_b128 v[120:123], v249
	ds_read_b128 v[124:127], v250
	ds_read_b128 v[128:131], v251
	ds_write_b128 v112, v[132:135]
	ds_write_b128 v112, v[136:139] offset:1024
	ds_write_b128 v112, v[140:143] offset:2048
	ds_write_b128 v112, v[144:147] offset:3072
	v_mfma_f32_32x32x16_bf16 v[32:47], v[192:195], v[52:55], v[32:47]
	v_mfma_f32_32x32x16_bf16 v[32:47], v[196:199], v[56:59], v[32:47]
	v_mfma_f32_32x32x16_bf16 v[32:47], v[200:203], v[60:63], v[32:47]
	s_nop 11
	v_exp_f32_e32 v32, v32
	v_exp_f32_e32 v33, v33
	v_exp_f32_e32 v34, v34
	v_exp_f32_e32 v35, v35
	v_exp_f32_e32 v36, v36
	v_exp_f32_e32 v37, v37
	v_exp_f32_e32 v38, v38
	v_exp_f32_e32 v39, v39
	v_exp_f32_e32 v40, v40
	v_exp_f32_e32 v41, v41
	v_exp_f32_e32 v42, v42
	v_exp_f32_e32 v43, v43
	v_exp_f32_e32 v44, v44
	v_exp_f32_e32 v45, v45
	v_exp_f32_e32 v46, v46
	v_exp_f32_e32 v47, v47
	v_cvt_pk_bf16_f32 v64, v32, v33
	v_cvt_pk_bf16_f32 v65, v34, v35
	v_cvt_pk_bf16_f32 v66, v36, v37
	v_cvt_pk_bf16_f32 v67, v38, v39
	v_cvt_pk_bf16_f32 v68, v40, v41
	v_cvt_pk_bf16_f32 v69, v42, v43
	v_cvt_pk_bf16_f32 v70, v44, v45
	v_cvt_pk_bf16_f32 v71, v46, v47
	v_pk_add_f32 v[232:233], v[232:233], v[32:33]
	v_pk_add_f32 v[232:233], v[232:233], v[34:35]
	v_pk_add_f32 v[232:233], v[232:233], v[36:37]
	v_pk_add_f32 v[232:233], v[232:233], v[38:39]
	v_pk_add_f32 v[232:233], v[232:233], v[40:41]
	v_pk_add_f32 v[232:233], v[232:233], v[42:43]
	v_pk_add_f32 v[232:233], v[232:233], v[44:45]
	v_pk_add_f32 v[232:233], v[232:233], v[46:47]
	s_waitcnt lgkmcnt(12)
	v_mfma_f32_32x32x16_bf16 v[0:15], v[64:67], v[72:75], v[0:15]
	v_mfma_f32_32x32x16_bf16 v[16:31], v[64:67], v[76:79], v[16:31]
	v_mfma_f32_32x32x16_bf16 v[0:15], v[68:71], v[220:223], v[0:15]
	v_mfma_f32_32x32x16_bf16 v[16:31], v[68:71], v[224:227], v[16:31]
	global_load_dwordx4 v[188:191], v243, s[88:89]
	global_load_dwordx4 v[192:195], v244, s[88:89]
	global_load_dwordx4 v[196:199], v245, s[88:89]
	global_load_dwordx4 v[200:203], v246, s[88:89]
	global_load_dwordx4 v[204:207], v148, s[88:89] offset:768
	global_load_dwordx4 v[208:211], v151, s[88:89] offset:768
	global_load_dwordx4 v[212:215], v148, s[88:89] offset:832
	global_load_dwordx4 v[216:219], v151, s[88:89] offset:832
	ds_read2_b32 v[32:33], v115 offset0:64 offset1:65
	ds_read2_b32 v[34:35], v115 offset0:66 offset1:67
	ds_read2_b32 v[36:37], v115 offset0:72 offset1:73
	ds_read2_b32 v[38:39], v115 offset0:74 offset1:75
	ds_read2_b32 v[40:41], v115 offset0:80 offset1:81
	ds_read2_b32 v[42:43], v115 offset0:82 offset1:83
	ds_read2_b32 v[44:45], v115 offset0:88 offset1:89
	ds_read2_b32 v[46:47], v115 offset0:90 offset1:91
	s_waitcnt lgkmcnt(0)
	v_mfma_f32_32x32x16_bf16 v[32:47], v[116:119], v[48:51], v[32:47]
	ds_read_b64_tr_b16 v[72:73], v231
	ds_read_b64_tr_b16 v[74:75], v231 offset:512
	ds_read_b64_tr_b16 v[76:77], v231 offset:2048
	ds_read_b64_tr_b16 v[78:79], v231 offset:2560
	ds_read_b64_tr_b16 v[220:221], v231 offset:1024
	ds_read_b64_tr_b16 v[222:223], v231 offset:1536
	ds_read_b64_tr_b16 v[224:225], v231 offset:3072
	ds_read_b64_tr_b16 v[226:227], v231 offset:3584
	s_waitcnt vmcnt(8)
	ds_write_b128 v247, v[156:159]
	ds_write_b128 v247, v[160:163] offset:1024
	ds_write_b128 v247, v[164:167] offset:2048
	ds_write_b128 v247, v[168:171] offset:3072
	ds_read_b128 v[156:159], v248
	ds_read_b128 v[160:163], v249
	ds_read_b128 v[164:167], v250
	ds_read_b128 v[168:171], v251
	ds_write_b128 v112, v[172:175]
	ds_write_b128 v112, v[176:179] offset:1024
	ds_write_b128 v112, v[180:183] offset:2048
	ds_write_b128 v112, v[184:187] offset:3072
	v_mfma_f32_32x32x16_bf16 v[32:47], v[120:123], v[52:55], v[32:47]
	v_mfma_f32_32x32x16_bf16 v[32:47], v[124:127], v[56:59], v[32:47]
	v_mfma_f32_32x32x16_bf16 v[32:47], v[128:131], v[60:63], v[32:47]
	s_nop 11
	v_exp_f32_e32 v32, v32
	v_exp_f32_e32 v33, v33
	v_exp_f32_e32 v34, v34
	v_exp_f32_e32 v35, v35
	v_exp_f32_e32 v36, v36
	v_exp_f32_e32 v37, v37
	v_exp_f32_e32 v38, v38
	v_exp_f32_e32 v39, v39
	v_exp_f32_e32 v40, v40
	v_exp_f32_e32 v41, v41
	v_exp_f32_e32 v42, v42
	v_exp_f32_e32 v43, v43
	v_exp_f32_e32 v44, v44
	v_exp_f32_e32 v45, v45
	v_exp_f32_e32 v46, v46
	v_exp_f32_e32 v47, v47
	v_cvt_pk_bf16_f32 v64, v32, v33
	v_cvt_pk_bf16_f32 v65, v34, v35
	v_cvt_pk_bf16_f32 v66, v36, v37
	v_cvt_pk_bf16_f32 v67, v38, v39
	v_cvt_pk_bf16_f32 v68, v40, v41
	v_cvt_pk_bf16_f32 v69, v42, v43
	v_cvt_pk_bf16_f32 v70, v44, v45
	v_cvt_pk_bf16_f32 v71, v46, v47
	v_pk_add_f32 v[232:233], v[232:233], v[32:33]
	v_pk_add_f32 v[232:233], v[232:233], v[34:35]
	v_pk_add_f32 v[232:233], v[232:233], v[36:37]
	v_pk_add_f32 v[232:233], v[232:233], v[38:39]
	v_pk_add_f32 v[232:233], v[232:233], v[40:41]
	v_pk_add_f32 v[232:233], v[232:233], v[42:43]
	v_pk_add_f32 v[232:233], v[232:233], v[44:45]
	v_pk_add_f32 v[232:233], v[232:233], v[46:47]
	s_waitcnt lgkmcnt(12)
	v_mfma_f32_32x32x16_bf16 v[0:15], v[64:67], v[72:75], v[0:15]
	v_mfma_f32_32x32x16_bf16 v[16:31], v[64:67], v[76:79], v[16:31]
	v_mfma_f32_32x32x16_bf16 v[0:15], v[68:71], v[220:223], v[0:15]
	v_mfma_f32_32x32x16_bf16 v[16:31], v[68:71], v[224:227], v[16:31]
	ds_read2_b32 v[32:33], v115 offset0:96 offset1:97
	ds_read2_b32 v[34:35], v115 offset0:98 offset1:99
	ds_read2_b32 v[36:37], v115 offset0:104 offset1:105
	ds_read2_b32 v[38:39], v115 offset0:106 offset1:107
	ds_read2_b32 v[40:41], v115 offset0:112 offset1:113
	ds_read2_b32 v[42:43], v115 offset0:114 offset1:115
	ds_read2_b32 v[44:45], v115 offset0:120 offset1:121
	ds_read2_b32 v[46:47], v115 offset0:122 offset1:123
	s_waitcnt lgkmcnt(0)
	v_mfma_f32_32x32x16_bf16 v[32:47], v[156:159], v[48:51], v[32:47]
	ds_read_b64_tr_b16 v[72:73], v231
	ds_read_b64_tr_b16 v[74:75], v231 offset:512
	ds_read_b64_tr_b16 v[76:77], v231 offset:2048
	ds_read_b64_tr_b16 v[78:79], v231 offset:2560
	ds_read_b64_tr_b16 v[220:221], v231 offset:1024
	ds_read_b64_tr_b16 v[222:223], v231 offset:1536
	ds_read_b64_tr_b16 v[224:225], v231 offset:3072
	ds_read_b64_tr_b16 v[226:227], v231 offset:3584
	s_waitcnt vmcnt(0)
	ds_write_b128 v247, v[188:191]
	ds_write_b128 v247, v[192:195] offset:1024
	ds_write_b128 v247, v[196:199] offset:2048
	ds_write_b128 v247, v[200:203] offset:3072
	ds_read_b128 v[188:191], v248
	ds_read_b128 v[192:195], v249
	ds_read_b128 v[196:199], v250
	ds_read_b128 v[200:203], v251
	ds_write_b128 v112, v[204:207]
	ds_write_b128 v112, v[208:211] offset:1024
	ds_write_b128 v112, v[212:215] offset:2048
	ds_write_b128 v112, v[216:219] offset:3072
	v_mfma_f32_32x32x16_bf16 v[32:47], v[160:163], v[52:55], v[32:47]
	v_mfma_f32_32x32x16_bf16 v[32:47], v[164:167], v[56:59], v[32:47]
	v_mfma_f32_32x32x16_bf16 v[32:47], v[168:171], v[60:63], v[32:47]
	s_nop 11
	v_exp_f32_e32 v32, v32
	v_exp_f32_e32 v33, v33
	v_exp_f32_e32 v34, v34
	v_exp_f32_e32 v35, v35
	v_exp_f32_e32 v36, v36
	v_exp_f32_e32 v37, v37
	v_exp_f32_e32 v38, v38
	v_exp_f32_e32 v39, v39
	v_exp_f32_e32 v40, v40
	v_exp_f32_e32 v41, v41
	v_exp_f32_e32 v42, v42
	v_exp_f32_e32 v43, v43
	v_exp_f32_e32 v44, v44
	v_exp_f32_e32 v45, v45
	v_exp_f32_e32 v46, v46
	v_exp_f32_e32 v47, v47
	v_cvt_pk_bf16_f32 v64, v32, v33
	v_cvt_pk_bf16_f32 v65, v34, v35
	v_cvt_pk_bf16_f32 v66, v36, v37
	v_cvt_pk_bf16_f32 v67, v38, v39
	v_cvt_pk_bf16_f32 v68, v40, v41
	v_cvt_pk_bf16_f32 v69, v42, v43
	v_cvt_pk_bf16_f32 v70, v44, v45
	v_cvt_pk_bf16_f32 v71, v46, v47
	v_pk_add_f32 v[232:233], v[232:233], v[32:33]
	v_pk_add_f32 v[232:233], v[232:233], v[34:35]
	v_pk_add_f32 v[232:233], v[232:233], v[36:37]
	v_pk_add_f32 v[232:233], v[232:233], v[38:39]
	v_pk_add_f32 v[232:233], v[232:233], v[40:41]
	v_pk_add_f32 v[232:233], v[232:233], v[42:43]
	v_pk_add_f32 v[232:233], v[232:233], v[44:45]
	v_pk_add_f32 v[232:233], v[232:233], v[46:47]
	s_waitcnt lgkmcnt(12)
	v_mfma_f32_32x32x16_bf16 v[0:15], v[64:67], v[72:75], v[0:15]
	v_mfma_f32_32x32x16_bf16 v[16:31], v[64:67], v[76:79], v[16:31]
	v_mfma_f32_32x32x16_bf16 v[0:15], v[68:71], v[220:223], v[0:15]
	v_mfma_f32_32x32x16_bf16 v[16:31], v[68:71], v[224:227], v[16:31]
	ds_read2_b32 v[32:33], v115 offset0:128 offset1:129
	ds_read2_b32 v[34:35], v115 offset0:130 offset1:131
	ds_read2_b32 v[36:37], v115 offset0:136 offset1:137
	ds_read2_b32 v[38:39], v115 offset0:138 offset1:139
	ds_read2_b32 v[40:41], v115 offset0:144 offset1:145
	ds_read2_b32 v[42:43], v115 offset0:146 offset1:147
	ds_read2_b32 v[44:45], v115 offset0:152 offset1:153
	ds_read2_b32 v[46:47], v115 offset0:154 offset1:155
	s_waitcnt lgkmcnt(0)
; #define LAS __attribute__((address_space(3)))
; #define GAS __attribute__((address_space(1)))
; __device__ __forceinline__ void dil_unit(LAS unsigned char* lds, bf16_t* proj, int seq, int hd, int T0, int rho) {
;     ...
;     const int tid = tid_, lane = tid & 63, r32 = lane & 31, hi = lane >> 5, wid = __builtin_amdgcn_readfirstlane(tid >> 6);
;     bf16_t* base = proj + (size_t)seq * SEQ * NIN;
;     LAS unsigned char* wbuf = lds + wid * 4096;
;     const LAS unsigned char* vp = wbuf + ((lane >> 4) & 1) * 32 + (lane & 3) * 8 + (4 * hi + ((lane & 15) >> 2)) * 64;
;     const int P0 = T0 + rho;
;     bf16x8 qr[4];
; #pragma unroll
;     for (int ks = 0; ks < 4; ++ks) qr[ks] = *(const GAS bf16x8*)(base + (size_t)(P0 + 16 * r32) * NIN + PC_LQ + hd * 64 + 16 * ks + 8 * hi);
;     f32x16 o0 = {}, o1 = {}; float l = 0.f;
;     const bool bound = (T0 < 1024) || (T0 >= 15360);
	v_mfma_f32_32x32x16_bf16 v[32:47], v[188:191], v[48:51], v[32:47]
	ds_read_b64_tr_b16 v[72:73], v231
	ds_read_b64_tr_b16 v[74:75], v231 offset:512
	ds_read_b64_tr_b16 v[76:77], v231 offset:2048
	ds_read_b64_tr_b16 v[78:79], v231 offset:2560
	ds_read_b64_tr_b16 v[220:221], v231 offset:1024
	ds_read_b64_tr_b16 v[222:223], v231 offset:1536
	ds_read_b64_tr_b16 v[224:225], v231 offset:3072
	ds_read_b64_tr_b16 v[226:227], v231 offset:3584
	v_mfma_f32_32x32x16_bf16 v[32:47], v[192:195], v[52:55], v[32:47]
	v_mfma_f32_32x32x16_bf16 v[32:47], v[196:199], v[56:59], v[32:47]
	v_mfma_f32_32x32x16_bf16 v[32:47], v[200:203], v[60:63], v[32:47]
	s_nop 11
	v_exp_f32_e32 v32, v32
	v_exp_f32_e32 v33, v33
	v_exp_f32_e32 v34, v34
	v_exp_f32_e32 v35, v35
	v_exp_f32_e32 v36, v36
	v_exp_f32_e32 v37, v37
	v_exp_f32_e32 v38, v38
	v_exp_f32_e32 v39, v39
	v_exp_f32_e32 v40, v40
	v_exp_f32_e32 v41, v41
	v_exp_f32_e32 v42, v42
	v_exp_f32_e32 v43, v43
	v_exp_f32_e32 v44, v44
	v_exp_f32_e32 v45, v45
	v_exp_f32_e32 v46, v46
	v_exp_f32_e32 v47, v47
	v_cvt_pk_bf16_f32 v64, v32, v33
	v_cvt_pk_bf16_f32 v65, v34, v35
	v_cvt_pk_bf16_f32 v66, v36, v37
	v_cvt_pk_bf16_f32 v67, v38, v39
	v_cvt_pk_bf16_f32 v68, v40, v41
	v_cvt_pk_bf16_f32 v69, v42, v43
	v_cvt_pk_bf16_f32 v70, v44, v45
	v_cvt_pk_bf16_f32 v71, v46, v47
	v_pk_add_f32 v[232:233], v[232:233], v[32:33]
	v_pk_add_f32 v[232:233], v[232:233], v[34:35]
	v_pk_add_f32 v[232:233], v[232:233], v[36:37]
	v_pk_add_f32 v[232:233], v[232:233], v[38:39]
	v_pk_add_f32 v[232:233], v[232:233], v[40:41]
	v_pk_add_f32 v[232:233], v[232:233], v[42:43]
	v_pk_add_f32 v[232:233], v[232:233], v[44:45]
	v_pk_add_f32 v[232:233], v[232:233], v[46:47]
	s_waitcnt lgkmcnt(0)
	v_mfma_f32_32x32x16_bf16 v[0:15], v[64:67], v[72:75], v[0:15]
	v_mfma_f32_32x32x16_bf16 v[16:31], v[64:67], v[76:79], v[16:31]
	v_mfma_f32_32x32x16_bf16 v[0:15], v[68:71], v[220:223], v[0:15]
	v_mfma_f32_32x32x16_bf16 v[16:31], v[68:71], v[224:227], v[16:31]
	v_add_f32_e32 v113, v232, v233
	v_or_b32_e32 v114, 1, v107
	v_or_b32_e32 v97, 2, v107
	v_or_b32_e32 v96, 3, v107
	v_or_b32_e32 v95, 8, v107
	v_or_b32_e32 v94, 9, v107
	v_or_b32_e32 v93, 10, v107
	v_or_b32_e32 v92, 11, v107
	v_or_b32_e32 v91, 16, v107
	v_or_b32_e32 v90, 17, v107
	v_or_b32_e32 v89, 18, v107
	v_or_b32_e32 v88, 19, v107
	v_or_b32_e32 v87, 24, v107
	v_or_b32_e32 v86, 25, v107
	v_or_b32_e32 v85, 26, v107
	v_or_b32_e32 v84, 27, v107
	s_nop 11
	s_branch .LBB0_1265
.LBB0_1270:
	s_movk_i32 s100, 0x1800
	s_add_i32 s101, s8, 0x15c00
	s_lshl_b32 s90, s54, 1
	s_add_u32 s82, s52, s90
	s_addc_u32 s83, s53, 0
	s_add_u32 s82, s82, 0x1200
	s_addc_u32 s83, s83, 0
	s_sub_i32 s90, s67, 64
	s_mul_i32 s90, s90, 0x1800
	s_add_u32 s84, s82, s90
	s_addc_u32 s85, s83, 0
	s_sub_i32 s90, s67, 256
	s_mul_i32 s90, s90, 0x1800
	s_add_u32 s86, s82, s90
	s_addc_u32 s87, s83, 0
	s_sub_i32 s90, s67, 1024
	s_mul_i32 s90, s90, 0x1800
	s_add_u32 s88, s82, s90
	s_addc_u32 s89, s83, 0
	v_lshlrev_b32_e32 v153, 1, v98
	v_mad_u32_u24 v80, v105, s100, v82
	v_mad_u32_u24 v100, v110, s100, v153
	v_add_u32_e32 v149, 0x18000, v100
	v_lshlrev_b32_e32 v83, 2, v105
	v_mad_u32_u24 v83, v83, s100, v82
	v_lshlrev_b32_e32 v101, 2, v110
	v_mad_u32_u24 v101, v101, s100, v153
	v_add_u32_e32 v150, 0x60000, v101
	v_lshlrev_b32_e32 v99, 4, v105
	v_mad_u32_u24 v99, v99, s100, v82
	v_lshlrev_b32_e32 v148, 4, v110
	v_mad_u32_u24 v148, v148, s100, v153
	v_add_u32_e32 v151, 0x180000, v148
	v_lshrrev_b32_e32 v249, 3, v103
	v_and_b32_e32 v250, 7, v103
	v_lshlrev_b32_e32 v250, 4, v250
	v_add_u32_e32 v235, 0, v249
	v_add_u32_e32 v236, 8, v249
	v_add_u32_e32 v237, 16, v249
	v_add_u32_e32 v238, 24, v249
	v_add_u32_e32 v239, 0, v249
	v_lshlrev_b32_e32 v239, 2, v239
	v_add_u32_e32 v240, 8, v249
	v_lshlrev_b32_e32 v240, 2, v240
	v_add_u32_e32 v241, 16, v249
	v_lshlrev_b32_e32 v241, 2, v241
	v_add_u32_e32 v242, 24, v249
	v_lshlrev_b32_e32 v242, 2, v242
	v_add_u32_e32 v243, 0, v249
	v_lshlrev_b32_e32 v243, 4, v243
	v_add_u32_e32 v244, 8, v249
	v_lshlrev_b32_e32 v244, 4, v244
	v_add_u32_e32 v245, 16, v249
	v_lshlrev_b32_e32 v245, 4, v245
	v_add_u32_e32 v246, 24, v249
	v_lshlrev_b32_e32 v246, 4, v246
	v_mov_b32_e32 v252, v250
	v_mov_b32_e32 v100, v110
	v_add_u32_e32 v149, 16, v100
	v_lshlrev_b32_e32 v101, 2, v110
	v_add_u32_e32 v150, 64, v101
	v_lshlrev_b32_e32 v148, 4, v110
	v_add_u32_e32 v151, 256, v148
	s_mov_b32 s98, 0x4000
	s_mov_b32 s99, 0x3fff
	v_and_b32_e32 v247, 7, v249
	v_lshlrev_b32_e32 v247, 4, v247
	v_xor_b32_e32 v247, v247, v112
	v_and_b32_e32 v153, 7, v105
	v_or_b32_e32 v248, 0, v106
	v_xor_b32_e32 v248, v248, v153
	v_lshlrev_b32_e32 v248, 4, v248
	v_lshl_add_u32 v248, v105, 7, v248
	v_add_u32_e32 v248, s69, v248
	v_or_b32_e32 v249, 2, v106
	v_xor_b32_e32 v249, v249, v153
	v_lshlrev_b32_e32 v249, 4, v249
	v_lshl_add_u32 v249, v105, 7, v249
	v_add_u32_e32 v249, s69, v249
	v_or_b32_e32 v250, 4, v106
	v_xor_b32_e32 v250, v250, v153
	v_lshlrev_b32_e32 v250, 4, v250
	v_lshl_add_u32 v250, v105, 7, v250
	v_add_u32_e32 v250, s69, v250
	v_or_b32_e32 v251, 6, v106
	v_xor_b32_e32 v251, v251, v153
	v_lshlrev_b32_e32 v251, 4, v251
	v_lshl_add_u32 v251, v105, 7, v251
	v_add_u32_e32 v251, s69, v251
	v_lshlrev_b32_e32 v153, 1, v98
	v_mul_u32_u24_e32 v228, 17, v105
	v_sub_u32_e32 v228, v107, v228
	s_mul_i32 s90, s54, 153
	s_lshr_b32 s90, s90, 1
	s_add_i32 s90, s90, 34876
	v_lshl_add_u32 v228, v228, 2, s90
	v_lshlrev_b32_e32 v229, 2, v105
	v_sub_u32_e32 v229, v107, v229
	s_add_i32 s90, s101, 5104
	v_lshl_add_u32 v229, v229, 2, s90
	v_sub_u32_e32 v230, v107, v105
	s_add_i32 s90, s101, 6364
	v_lshl_add_u32 v230, v230, 2, s90
	v_add_u32_e32 v231, v109, v108
	v_mov_b64_e32 v[232:233], 0
; __device__ __forceinline__ void dil_unit(LAS unsigned char* lds, bf16_t* proj, int seq, int hd, int T0, int rho) {
;     ...
;     f32x16 o0 = {}, o1 = {}; float l = 0.f;
;     const bool bound = (T0 < 1024) || (T0 >= 15360);
	v_mov_b64_e32 v[0:1], 0
	v_mov_b64_e32 v[2:3], 0
	v_mov_b64_e32 v[4:5], 0
	v_mov_b64_e32 v[6:7], 0
	v_mov_b64_e32 v[8:9], 0
	v_mov_b64_e32 v[10:11], 0
	v_mov_b64_e32 v[12:13], 0
	v_mov_b64_e32 v[14:15], 0
	v_mov_b64_e32 v[16:17], 0
	v_mov_b64_e32 v[18:19], 0
	v_mov_b64_e32 v[20:21], 0
	v_mov_b64_e32 v[22:23], 0
	v_mov_b64_e32 v[24:25], 0
	v_mov_b64_e32 v[26:27], 0
	v_mov_b64_e32 v[28:29], 0
	v_mov_b64_e32 v[30:31], 0
	s_add_i32 s90, s67, -64
	v_add_u32_e32 v80, s90, v235
	v_add_u32_e32 v83, s90, v236
	v_add_u32_e32 v99, s90, v237
	v_add_u32_e32 v253, s90, v238
	v_add_u32_e32 v254, s90, v100
	v_add_u32_e32 v255, s90, v149
	v_med3_i32 v80, v80, 0, s99
	v_med3_i32 v83, v83, 0, s99
	v_med3_i32 v99, v99, 0, s99
	v_med3_i32 v253, v253, 0, s99
	v_med3_i32 v254, v254, 0, s99
	v_med3_i32 v255, v255, 0, s99
	v_mad_u32_u24 v80, v80, s100, v252
	v_mad_u32_u24 v83, v83, s100, v252
	v_mad_u32_u24 v99, v99, s100, v252
	v_mad_u32_u24 v253, v253, s100, v252
	v_mad_u32_u24 v254, v254, s100, v153
	v_mad_u32_u24 v255, v255, s100, v153
	global_load_dwordx4 v[116:119], v80, s[82:83]
	global_load_dwordx4 v[120:123], v83, s[82:83]
	global_load_dwordx4 v[124:127], v99, s[82:83]
	global_load_dwordx4 v[128:131], v253, s[82:83]
	global_load_dwordx4 v[132:135], v254, s[82:83] offset:768
	global_load_dwordx4 v[136:139], v255, s[82:83] offset:768
	global_load_dwordx4 v[140:143], v254, s[82:83] offset:832
	global_load_dwordx4 v[144:147], v255, s[82:83] offset:832
	s_add_i32 s90, s67, -32
	v_add_u32_e32 v80, s90, v235
	v_add_u32_e32 v83, s90, v236
	v_add_u32_e32 v99, s90, v237
	v_add_u32_e32 v253, s90, v238
	v_add_u32_e32 v254, s90, v100
	v_add_u32_e32 v255, s90, v149
	v_med3_i32 v80, v80, 0, s99
	v_med3_i32 v83, v83, 0, s99
	v_med3_i32 v99, v99, 0, s99
	v_med3_i32 v253, v253, 0, s99
	v_med3_i32 v254, v254, 0, s99
	v_med3_i32 v255, v255, 0, s99
	v_mad_u32_u24 v80, v80, s100, v252
	v_mad_u32_u24 v83, v83, s100, v252
	v_mad_u32_u24 v99, v99, s100, v252
	v_mad_u32_u24 v253, v253, s100, v252
	v_mad_u32_u24 v254, v254, s100, v153
	v_mad_u32_u24 v255, v255, s100, v153
	global_load_dwordx4 v[156:159], v80, s[82:83]
	global_load_dwordx4 v[160:163], v83, s[82:83]
	global_load_dwordx4 v[164:167], v99, s[82:83]
	global_load_dwordx4 v[168:171], v253, s[82:83]
	global_load_dwordx4 v[172:175], v254, s[82:83] offset:768
	global_load_dwordx4 v[176:179], v255, s[82:83] offset:768
	global_load_dwordx4 v[180:183], v254, s[82:83] offset:832
	global_load_dwordx4 v[184:187], v255, s[82:83] offset:832
	s_add_i32 s90, s67, 0
	v_add_u32_e32 v80, s90, v235
	v_add_u32_e32 v83, s90, v236
	v_add_u32_e32 v99, s90, v237
	v_add_u32_e32 v253, s90, v238
	v_add_u32_e32 v254, s90, v100
	v_add_u32_e32 v255, s90, v149
	v_med3_i32 v80, v80, 0, s99
	v_med3_i32 v83, v83, 0, s99
	v_med3_i32 v99, v99, 0, s99
	v_med3_i32 v253, v253, 0, s99
	v_med3_i32 v254, v254, 0, s99
	v_med3_i32 v255, v255, 0, s99
	v_mad_u32_u24 v80, v80, s100, v252
	v_mad_u32_u24 v83, v83, s100, v252
	v_mad_u32_u24 v99, v99, s100, v252
	v_mad_u32_u24 v253, v253, s100, v252
	v_mad_u32_u24 v254, v254, s100, v153
	v_mad_u32_u24 v255, v255, s100, v153
	global_load_dwordx4 v[188:191], v80, s[82:83]
	global_load_dwordx4 v[192:195], v83, s[82:83]
	global_load_dwordx4 v[196:199], v99, s[82:83]
	global_load_dwordx4 v[200:203], v253, s[82:83]
	global_load_dwordx4 v[204:207], v254, s[82:83] offset:768
	global_load_dwordx4 v[208:211], v255, s[82:83] offset:768
	global_load_dwordx4 v[212:215], v254, s[82:83] offset:832
	global_load_dwordx4 v[216:219], v255, s[82:83] offset:832
	s_waitcnt vmcnt(16)
	ds_write_b128 v247, v[116:119]
	ds_write_b128 v247, v[120:123] offset:1024
	ds_write_b128 v247, v[124:127] offset:2048
	ds_write_b128 v247, v[128:131] offset:3072
	ds_read_b128 v[116:119], v248
	ds_read_b128 v[120:123], v249
	ds_read_b128 v[124:127], v250
	ds_read_b128 v[128:131], v251
	ds_write_b128 v112, v[132:135]
	ds_write_b128 v112, v[136:139] offset:1024
	ds_write_b128 v112, v[140:143] offset:2048
	ds_write_b128 v112, v[144:147] offset:3072
	v_mov_b32_e32 v115, v228
	ds_read2_b32 v[32:33], v115 offset0:0 offset1:1
	ds_read2_b32 v[34:35], v115 offset0:2 offset1:3
	ds_read2_b32 v[36:37], v115 offset0:8 offset1:9
	ds_read2_b32 v[38:39], v115 offset0:10 offset1:11
	ds_read2_b32 v[40:41], v115 offset0:17 offset1:18
	ds_read2_b32 v[42:43], v115 offset0:19 offset1:20
	ds_read2_b32 v[44:45], v115 offset0:25 offset1:26
	ds_read2_b32 v[46:47], v115 offset0:27 offset1:28
	s_waitcnt lgkmcnt(0)
	v_mfma_f32_32x32x16_bf16 v[32:47], v[116:119], v[48:51], v[32:47]
	ds_read_b64_tr_b16 v[72:73], v231
	ds_read_b64_tr_b16 v[74:75], v231 offset:512
	ds_read_b64_tr_b16 v[76:77], v231 offset:2048
	ds_read_b64_tr_b16 v[78:79], v231 offset:2560
	ds_read_b64_tr_b16 v[220:221], v231 offset:1024
	ds_read_b64_tr_b16 v[222:223], v231 offset:1536
	ds_read_b64_tr_b16 v[224:225], v231 offset:3072
	ds_read_b64_tr_b16 v[226:227], v231 offset:3584
	s_waitcnt vmcnt(8)
	ds_write_b128 v247, v[156:159]
	ds_write_b128 v247, v[160:163] offset:1024
	ds_write_b128 v247, v[164:167] offset:2048
	ds_write_b128 v247, v[168:171] offset:3072
	ds_read_b128 v[156:159], v248
	ds_read_b128 v[160:163], v249
	ds_read_b128 v[164:167], v250
	ds_read_b128 v[168:171], v251
	ds_write_b128 v112, v[172:175]
	ds_write_b128 v112, v[176:179] offset:1024
	ds_write_b128 v112, v[180:183] offset:2048
	ds_write_b128 v112, v[184:187] offset:3072
	v_mfma_f32_32x32x16_bf16 v[32:47], v[120:123], v[52:55], v[32:47]
	v_mfma_f32_32x32x16_bf16 v[32:47], v[124:127], v[56:59], v[32:47]
	v_mfma_f32_32x32x16_bf16 v[32:47], v[128:131], v[60:63], v[32:47]
	s_nop 11
	v_exp_f32_e32 v32, v32
	v_exp_f32_e32 v33, v33
	v_exp_f32_e32 v34, v34
	v_exp_f32_e32 v35, v35
	v_exp_f32_e32 v36, v36
	v_exp_f32_e32 v37, v37
	v_exp_f32_e32 v38, v38
	v_exp_f32_e32 v39, v39
	v_exp_f32_e32 v40, v40
	v_exp_f32_e32 v41, v41
	v_exp_f32_e32 v42, v42
	v_exp_f32_e32 v43, v43
	v_exp_f32_e32 v44, v44
	v_exp_f32_e32 v45, v45
	v_exp_f32_e32 v46, v46
	v_exp_f32_e32 v47, v47
	s_add_i32 s90, s67, -64
	v_add_u32_e32 v84, s90, v107
	v_add_u32_e32 v85, 0, v84
	v_add_u32_e32 v86, 1, v84
	v_add_u32_e32 v87, 2, v84
	v_add_u32_e32 v88, 3, v84
	v_cmp_gt_u32_e64 s[30:31], s98, v85
	v_cmp_gt_u32_e64 s[36:37], s98, v86
	v_cmp_gt_u32_e64 s[78:79], s98, v87
	v_cmp_gt_u32_e64 s[50:51], s98, v88
	v_cndmask_b32_e64 v32, 0, v32, s[30:31]
	v_add_u32_e32 v85, 8, v84
	v_cmp_gt_u32_e64 s[30:31], s98, v85
	v_cndmask_b32_e64 v33, 0, v33, s[36:37]
	v_add_u32_e32 v86, 9, v84
	v_cmp_gt_u32_e64 s[36:37], s98, v86
	v_cndmask_b32_e64 v34, 0, v34, s[78:79]
	v_add_u32_e32 v87, 10, v84
	v_cmp_gt_u32_e64 s[78:79], s98, v87
	v_cndmask_b32_e64 v35, 0, v35, s[50:51]
	v_add_u32_e32 v88, 11, v84
	v_cmp_gt_u32_e64 s[50:51], s98, v88
	v_cndmask_b32_e64 v36, 0, v36, s[30:31]
	v_add_u32_e32 v85, 16, v84
	v_cmp_gt_u32_e64 s[30:31], s98, v85
	v_cndmask_b32_e64 v37, 0, v37, s[36:37]
	v_add_u32_e32 v86, 17, v84
	v_cmp_gt_u32_e64 s[36:37], s98, v86
	v_cndmask_b32_e64 v38, 0, v38, s[78:79]
	v_add_u32_e32 v87, 18, v84
	v_cmp_gt_u32_e64 s[78:79], s98, v87
	v_cndmask_b32_e64 v39, 0, v39, s[50:51]
	v_add_u32_e32 v88, 19, v84
	v_cmp_gt_u32_e64 s[50:51], s98, v88
	v_cndmask_b32_e64 v40, 0, v40, s[30:31]
	v_add_u32_e32 v85, 24, v84
	v_cmp_gt_u32_e64 s[30:31], s98, v85
	v_cndmask_b32_e64 v41, 0, v41, s[36:37]
	v_add_u32_e32 v86, 25, v84
	v_cmp_gt_u32_e64 s[36:37], s98, v86
	v_cndmask_b32_e64 v42, 0, v42, s[78:79]
	v_add_u32_e32 v87, 26, v84
	v_cmp_gt_u32_e64 s[78:79], s98, v87
	v_cndmask_b32_e64 v43, 0, v43, s[50:51]
	v_add_u32_e32 v88, 27, v84
	v_cmp_gt_u32_e64 s[50:51], s98, v88
	v_nop
	v_cndmask_b32_e64 v44, 0, v44, s[30:31]
	v_cndmask_b32_e64 v45, 0, v45, s[36:37]
	v_cndmask_b32_e64 v46, 0, v46, s[78:79]
	v_cndmask_b32_e64 v47, 0, v47, s[50:51]
	v_cvt_pk_bf16_f32 v64, v32, v33
	v_cvt_pk_bf16_f32 v65, v34, v35
	v_cvt_pk_bf16_f32 v66, v36, v37
	v_cvt_pk_bf16_f32 v67, v38, v39
	v_cvt_pk_bf16_f32 v68, v40, v41
	v_cvt_pk_bf16_f32 v69, v42, v43
	v_cvt_pk_bf16_f32 v70, v44, v45
	v_cvt_pk_bf16_f32 v71, v46, v47
	v_pk_add_f32 v[232:233], v[232:233], v[32:33]
	v_pk_add_f32 v[232:233], v[232:233], v[34:35]
	v_pk_add_f32 v[232:233], v[232:233], v[36:37]
	v_pk_add_f32 v[232:233], v[232:233], v[38:39]
	v_pk_add_f32 v[232:233], v[232:233], v[40:41]
	v_pk_add_f32 v[232:233], v[232:233], v[42:43]
	v_pk_add_f32 v[232:233], v[232:233], v[44:45]
	v_pk_add_f32 v[232:233], v[232:233], v[46:47]
	s_waitcnt lgkmcnt(12)
	v_mfma_f32_32x32x16_bf16 v[0:15], v[64:67], v[72:75], v[0:15]
	v_mfma_f32_32x32x16_bf16 v[16:31], v[64:67], v[76:79], v[16:31]
	v_mfma_f32_32x32x16_bf16 v[0:15], v[68:71], v[220:223], v[0:15]
	v_mfma_f32_32x32x16_bf16 v[16:31], v[68:71], v[224:227], v[16:31]
	s_add_i32 s90, s67, 32
	v_add_u32_e32 v80, s90, v235
	v_add_u32_e32 v83, s90, v236
	v_add_u32_e32 v99, s90, v237
	v_add_u32_e32 v253, s90, v238
	v_add_u32_e32 v254, s90, v100
	v_add_u32_e32 v255, s90, v149
	v_med3_i32 v80, v80, 0, s99
	v_med3_i32 v83, v83, 0, s99
	v_med3_i32 v99, v99, 0, s99
	v_med3_i32 v253, v253, 0, s99
	v_med3_i32 v254, v254, 0, s99
	v_med3_i32 v255, v255, 0, s99
	v_mad_u32_u24 v80, v80, s100, v252
	v_mad_u32_u24 v83, v83, s100, v252
	v_mad_u32_u24 v99, v99, s100, v252
	v_mad_u32_u24 v253, v253, s100, v252
	v_mad_u32_u24 v254, v254, s100, v153
	v_mad_u32_u24 v255, v255, s100, v153
	global_load_dwordx4 v[116:119], v80, s[82:83]
	global_load_dwordx4 v[120:123], v83, s[82:83]
	global_load_dwordx4 v[124:127], v99, s[82:83]
	global_load_dwordx4 v[128:131], v253, s[82:83]
	global_load_dwordx4 v[132:135], v254, s[82:83] offset:768
	global_load_dwordx4 v[136:139], v255, s[82:83] offset:768
	global_load_dwordx4 v[140:143], v254, s[82:83] offset:832
	global_load_dwordx4 v[144:147], v255, s[82:83] offset:832
	ds_read2_b32 v[32:33], v115 offset0:34 offset1:35
	ds_read2_b32 v[34:35], v115 offset0:36 offset1:37
	ds_read2_b32 v[36:37], v115 offset0:42 offset1:43
	ds_read2_b32 v[38:39], v115 offset0:44 offset1:45
	ds_read2_b32 v[40:41], v115 offset0:51 offset1:52
	ds_read2_b32 v[42:43], v115 offset0:53 offset1:54
	ds_read2_b32 v[44:45], v115 offset0:59 offset1:60
	ds_read2_b32 v[46:47], v115 offset0:61 offset1:62
	s_waitcnt lgkmcnt(0)
	v_mfma_f32_32x32x16_bf16 v[32:47], v[156:159], v[48:51], v[32:47]
	ds_read_b64_tr_b16 v[72:73], v231
	ds_read_b64_tr_b16 v[74:75], v231 offset:512
	ds_read_b64_tr_b16 v[76:77], v231 offset:2048
	ds_read_b64_tr_b16 v[78:79], v231 offset:2560
	ds_read_b64_tr_b16 v[220:221], v231 offset:1024
	ds_read_b64_tr_b16 v[222:223], v231 offset:1536
	ds_read_b64_tr_b16 v[224:225], v231 offset:3072
	ds_read_b64_tr_b16 v[226:227], v231 offset:3584
	s_waitcnt vmcnt(8)
	ds_write_b128 v247, v[188:191]
	ds_write_b128 v247, v[192:195] offset:1024
	ds_write_b128 v247, v[196:199] offset:2048
	ds_write_b128 v247, v[200:203] offset:3072
	ds_read_b128 v[188:191], v248
	ds_read_b128 v[192:195], v249
	ds_read_b128 v[196:199], v250
	ds_read_b128 v[200:203], v251
	ds_write_b128 v112, v[204:207]
	ds_write_b128 v112, v[208:211] offset:1024
	ds_write_b128 v112, v[212:215] offset:2048
	ds_write_b128 v112, v[216:219] offset:3072
	v_mfma_f32_32x32x16_bf16 v[32:47], v[160:163], v[52:55], v[32:47]
	v_mfma_f32_32x32x16_bf16 v[32:47], v[164:167], v[56:59], v[32:47]
	v_mfma_f32_32x32x16_bf16 v[32:47], v[168:171], v[60:63], v[32:47]
	s_nop 11
	v_exp_f32_e32 v32, v32
	v_exp_f32_e32 v33, v33
	v_exp_f32_e32 v34, v34
	v_exp_f32_e32 v35, v35
	v_exp_f32_e32 v36, v36
	v_exp_f32_e32 v37, v37
	v_exp_f32_e32 v38, v38
	v_exp_f32_e32 v39, v39
	v_exp_f32_e32 v40, v40
	v_exp_f32_e32 v41, v41
	v_exp_f32_e32 v42, v42
	v_exp_f32_e32 v43, v43
	v_exp_f32_e32 v44, v44
	v_exp_f32_e32 v45, v45
	v_exp_f32_e32 v46, v46
	v_exp_f32_e32 v47, v47
	s_add_i32 s90, s67, -32
	v_add_u32_e32 v84, s90, v107
	v_add_u32_e32 v85, 0, v84
	v_add_u32_e32 v86, 1, v84
	v_add_u32_e32 v87, 2, v84
	v_add_u32_e32 v88, 3, v84
	v_cmp_gt_u32_e64 s[30:31], s98, v85
	v_cmp_gt_u32_e64 s[36:37], s98, v86
	v_cmp_gt_u32_e64 s[78:79], s98, v87
	v_cmp_gt_u32_e64 s[50:51], s98, v88
	v_cndmask_b32_e64 v32, 0, v32, s[30:31]
	v_add_u32_e32 v85, 8, v84
	v_cmp_gt_u32_e64 s[30:31], s98, v85
	v_cndmask_b32_e64 v33, 0, v33, s[36:37]
	v_add_u32_e32 v86, 9, v84
	v_cmp_gt_u32_e64 s[36:37], s98, v86
	v_cndmask_b32_e64 v34, 0, v34, s[78:79]
	v_add_u32_e32 v87, 10, v84
	v_cmp_gt_u32_e64 s[78:79], s98, v87
	v_cndmask_b32_e64 v35, 0, v35, s[50:51]
	v_add_u32_e32 v88, 11, v84
	v_cmp_gt_u32_e64 s[50:51], s98, v88
	v_cndmask_b32_e64 v36, 0, v36, s[30:31]
	v_add_u32_e32 v85, 16, v84
	v_cmp_gt_u32_e64 s[30:31], s98, v85
	v_cndmask_b32_e64 v37, 0, v37, s[36:37]
	v_add_u32_e32 v86, 17, v84
	v_cmp_gt_u32_e64 s[36:37], s98, v86
	v_cndmask_b32_e64 v38, 0, v38, s[78:79]
	v_add_u32_e32 v87, 18, v84
	v_cmp_gt_u32_e64 s[78:79], s98, v87
	v_cndmask_b32_e64 v39, 0, v39, s[50:51]
	v_add_u32_e32 v88, 19, v84
	v_cmp_gt_u32_e64 s[50:51], s98, v88
	v_cndmask_b32_e64 v40, 0, v40, s[30:31]
	v_add_u32_e32 v85, 24, v84
	v_cmp_gt_u32_e64 s[30:31], s98, v85
	v_cndmask_b32_e64 v41, 0, v41, s[36:37]
	v_add_u32_e32 v86, 25, v84
	v_cmp_gt_u32_e64 s[36:37], s98, v86
	v_cndmask_b32_e64 v42, 0, v42, s[78:79]
	v_add_u32_e32 v87, 26, v84
	v_cmp_gt_u32_e64 s[78:79], s98, v87
	v_cndmask_b32_e64 v43, 0, v43, s[50:51]
	v_add_u32_e32 v88, 27, v84
	v_cmp_gt_u32_e64 s[50:51], s98, v88
	v_nop
	v_cndmask_b32_e64 v44, 0, v44, s[30:31]
	v_cndmask_b32_e64 v45, 0, v45, s[36:37]
	v_cndmask_b32_e64 v46, 0, v46, s[78:79]
	v_cndmask_b32_e64 v47, 0, v47, s[50:51]
	v_cvt_pk_bf16_f32 v64, v32, v33
	v_cvt_pk_bf16_f32 v65, v34, v35
	v_cvt_pk_bf16_f32 v66, v36, v37
	v_cvt_pk_bf16_f32 v67, v38, v39
	v_cvt_pk_bf16_f32 v68, v40, v41
	v_cvt_pk_bf16_f32 v69, v42, v43
	v_cvt_pk_bf16_f32 v70, v44, v45
	v_cvt_pk_bf16_f32 v71, v46, v47
	v_pk_add_f32 v[232:233], v[232:233], v[32:33]
	v_pk_add_f32 v[232:233], v[232:233], v[34:35]
	v_pk_add_f32 v[232:233], v[232:233], v[36:37]
	v_pk_add_f32 v[232:233], v[232:233], v[38:39]
	v_pk_add_f32 v[232:233], v[232:233], v[40:41]
	v_pk_add_f32 v[232:233], v[232:233], v[42:43]
	v_pk_add_f32 v[232:233], v[232:233], v[44:45]
	v_pk_add_f32 v[232:233], v[232:233], v[46:47]
	s_waitcnt lgkmcnt(12)
	v_mfma_f32_32x32x16_bf16 v[0:15], v[64:67], v[72:75], v[0:15]
	v_mfma_f32_32x32x16_bf16 v[16:31], v[64:67], v[76:79], v[16:31]
	v_mfma_f32_32x32x16_bf16 v[0:15], v[68:71], v[220:223], v[0:15]
	v_mfma_f32_32x32x16_bf16 v[16:31], v[68:71], v[224:227], v[16:31]
	s_add_i32 s90, s67, 64
	v_add_u32_e32 v80, s90, v235
	v_add_u32_e32 v83, s90, v236
	v_add_u32_e32 v99, s90, v237
	v_add_u32_e32 v253, s90, v238
	v_add_u32_e32 v254, s90, v100
	v_add_u32_e32 v255, s90, v149
	v_med3_i32 v80, v80, 0, s99
	v_med3_i32 v83, v83, 0, s99
	v_med3_i32 v99, v99, 0, s99
	v_med3_i32 v253, v253, 0, s99
	v_med3_i32 v254, v254, 0, s99
	v_med3_i32 v255, v255, 0, s99
	v_mad_u32_u24 v80, v80, s100, v252
	v_mad_u32_u24 v83, v83, s100, v252
	v_mad_u32_u24 v99, v99, s100, v252
	v_mad_u32_u24 v253, v253, s100, v252
	v_mad_u32_u24 v254, v254, s100, v153
	v_mad_u32_u24 v255, v255, s100, v153
	global_load_dwordx4 v[156:159], v80, s[82:83]
	global_load_dwordx4 v[160:163], v83, s[82:83]
	global_load_dwordx4 v[164:167], v99, s[82:83]
	global_load_dwordx4 v[168:171], v253, s[82:83]
	global_load_dwordx4 v[172:175], v254, s[82:83] offset:768
	global_load_dwordx4 v[176:179], v255, s[82:83] offset:768
	global_load_dwordx4 v[180:183], v254, s[82:83] offset:832
	global_load_dwordx4 v[184:187], v255, s[82:83] offset:832
	ds_read2_b32 v[32:33], v115 offset0:68 offset1:69
	ds_read2_b32 v[34:35], v115 offset0:70 offset1:71
	ds_read2_b32 v[36:37], v115 offset0:76 offset1:77
	ds_read2_b32 v[38:39], v115 offset0:78 offset1:79
	ds_read2_b32 v[40:41], v115 offset0:85 offset1:86
	ds_read2_b32 v[42:43], v115 offset0:87 offset1:88
	ds_read2_b32 v[44:45], v115 offset0:93 offset1:94
	ds_read2_b32 v[46:47], v115 offset0:95 offset1:96
	s_waitcnt lgkmcnt(0)
	v_mfma_f32_32x32x16_bf16 v[32:47], v[188:191], v[48:51], v[32:47]
	ds_read_b64_tr_b16 v[72:73], v231
	ds_read_b64_tr_b16 v[74:75], v231 offset:512
	ds_read_b64_tr_b16 v[76:77], v231 offset:2048
	ds_read_b64_tr_b16 v[78:79], v231 offset:2560
	ds_read_b64_tr_b16 v[220:221], v231 offset:1024
	ds_read_b64_tr_b16 v[222:223], v231 offset:1536
	ds_read_b64_tr_b16 v[224:225], v231 offset:3072
	ds_read_b64_tr_b16 v[226:227], v231 offset:3584
	s_waitcnt vmcnt(8)
	ds_write_b128 v247, v[116:119]
	ds_write_b128 v247, v[120:123] offset:1024
	ds_write_b128 v247, v[124:127] offset:2048
	ds_write_b128 v247, v[128:131] offset:3072
	ds_read_b128 v[116:119], v248
	ds_read_b128 v[120:123], v249
	ds_read_b128 v[124:127], v250
	ds_read_b128 v[128:131], v251
	ds_write_b128 v112, v[132:135]
	ds_write_b128 v112, v[136:139] offset:1024
	ds_write_b128 v112, v[140:143] offset:2048
	ds_write_b128 v112, v[144:147] offset:3072
	v_mfma_f32_32x32x16_bf16 v[32:47], v[192:195], v[52:55], v[32:47]
	v_mfma_f32_32x32x16_bf16 v[32:47], v[196:199], v[56:59], v[32:47]
	v_mfma_f32_32x32x16_bf16 v[32:47], v[200:203], v[60:63], v[32:47]
	s_nop 11
	v_exp_f32_e32 v32, v32
	v_exp_f32_e32 v33, v33
	v_exp_f32_e32 v34, v34
	v_exp_f32_e32 v35, v35
	v_exp_f32_e32 v36, v36
	v_exp_f32_e32 v37, v37
	v_exp_f32_e32 v38, v38
	v_exp_f32_e32 v39, v39
	v_exp_f32_e32 v40, v40
	v_exp_f32_e32 v41, v41
	v_exp_f32_e32 v42, v42
	v_exp_f32_e32 v43, v43
	v_exp_f32_e32 v44, v44
	v_exp_f32_e32 v45, v45
	v_exp_f32_e32 v46, v46
	v_exp_f32_e32 v47, v47
	s_add_i32 s90, s67, 0
	v_add_u32_e32 v84, s90, v107
	v_add_u32_e32 v85, 0, v84
	v_add_u32_e32 v86, 1, v84
	v_add_u32_e32 v87, 2, v84
	v_add_u32_e32 v88, 3, v84
	v_cmp_gt_u32_e64 s[30:31], s98, v85
	v_cmp_gt_u32_e64 s[36:37], s98, v86
	v_cmp_gt_u32_e64 s[78:79], s98, v87
	v_cmp_gt_u32_e64 s[50:51], s98, v88
	v_cndmask_b32_e64 v32, 0, v32, s[30:31]
	v_add_u32_e32 v85, 8, v84
	v_cmp_gt_u32_e64 s[30:31], s98, v85
	v_cndmask_b32_e64 v33, 0, v33, s[36:37]
	v_add_u32_e32 v86, 9, v84
	v_cmp_gt_u32_e64 s[36:37], s98, v86
	v_cndmask_b32_e64 v34, 0, v34, s[78:79]
	v_add_u32_e32 v87, 10, v84
	v_cmp_gt_u32_e64 s[78:79], s98, v87
	v_cndmask_b32_e64 v35, 0, v35, s[50:51]
	v_add_u32_e32 v88, 11, v84
	v_cmp_gt_u32_e64 s[50:51], s98, v88
	v_cndmask_b32_e64 v36, 0, v36, s[30:31]
	v_add_u32_e32 v85, 16, v84
	v_cmp_gt_u32_e64 s[30:31], s98, v85
	v_cndmask_b32_e64 v37, 0, v37, s[36:37]
	v_add_u32_e32 v86, 17, v84
	v_cmp_gt_u32_e64 s[36:37], s98, v86
	v_cndmask_b32_e64 v38, 0, v38, s[78:79]
	v_add_u32_e32 v87, 18, v84
	v_cmp_gt_u32_e64 s[78:79], s98, v87
	v_cndmask_b32_e64 v39, 0, v39, s[50:51]
	v_add_u32_e32 v88, 19, v84
	v_cmp_gt_u32_e64 s[50:51], s98, v88
	v_cndmask_b32_e64 v40, 0, v40, s[30:31]
	v_add_u32_e32 v85, 24, v84
	v_cmp_gt_u32_e64 s[30:31], s98, v85
	v_cndmask_b32_e64 v41, 0, v41, s[36:37]
	v_add_u32_e32 v86, 25, v84
	v_cmp_gt_u32_e64 s[36:37], s98, v86
	v_cndmask_b32_e64 v42, 0, v42, s[78:79]
	v_add_u32_e32 v87, 26, v84
	v_cmp_gt_u32_e64 s[78:79], s98, v87
	v_cndmask_b32_e64 v43, 0, v43, s[50:51]
	v_add_u32_e32 v88, 27, v84
	v_cmp_gt_u32_e64 s[50:51], s98, v88
	v_nop
	v_cndmask_b32_e64 v44, 0, v44, s[30:31]
	v_cndmask_b32_e64 v45, 0, v45, s[36:37]
	v_cndmask_b32_e64 v46, 0, v46, s[78:79]
	v_cndmask_b32_e64 v47, 0, v47, s[50:51]
	v_cvt_pk_bf16_f32 v64, v32, v33
	v_cvt_pk_bf16_f32 v65, v34, v35
	v_cvt_pk_bf16_f32 v66, v36, v37
	v_cvt_pk_bf16_f32 v67, v38, v39
	v_cvt_pk_bf16_f32 v68, v40, v41
	v_cvt_pk_bf16_f32 v69, v42, v43
	v_cvt_pk_bf16_f32 v70, v44, v45
	v_cvt_pk_bf16_f32 v71, v46, v47
	v_pk_add_f32 v[232:233], v[232:233], v[32:33]
	v_pk_add_f32 v[232:233], v[232:233], v[34:35]
	v_pk_add_f32 v[232:233], v[232:233], v[36:37]
	v_pk_add_f32 v[232:233], v[232:233], v[38:39]
	v_pk_add_f32 v[232:233], v[232:233], v[40:41]
	v_pk_add_f32 v[232:233], v[232:233], v[42:43]
	v_pk_add_f32 v[232:233], v[232:233], v[44:45]
	v_pk_add_f32 v[232:233], v[232:233], v[46:47]
	s_waitcnt lgkmcnt(12)
	v_mfma_f32_32x32x16_bf16 v[0:15], v[64:67], v[72:75], v[0:15]
	v_mfma_f32_32x32x16_bf16 v[16:31], v[64:67], v[76:79], v[16:31]
	v_mfma_f32_32x32x16_bf16 v[0:15], v[68:71], v[220:223], v[0:15]
	v_mfma_f32_32x32x16_bf16 v[16:31], v[68:71], v[224:227], v[16:31]
	s_add_i32 s90, s67, 96
	v_add_u32_e32 v80, s90, v235
	v_add_u32_e32 v83, s90, v236
	v_add_u32_e32 v99, s90, v237
	v_add_u32_e32 v253, s90, v238
	v_add_u32_e32 v254, s90, v100
	v_add_u32_e32 v255, s90, v149
	v_med3_i32 v80, v80, 0, s99
	v_med3_i32 v83, v83, 0, s99
	v_med3_i32 v99, v99, 0, s99
	v_med3_i32 v253, v253, 0, s99
	v_med3_i32 v254, v254, 0, s99
	v_med3_i32 v255, v255, 0, s99
	v_mad_u32_u24 v80, v80, s100, v252
	v_mad_u32_u24 v83, v83, s100, v252
	v_mad_u32_u24 v99, v99, s100, v252
	v_mad_u32_u24 v253, v253, s100, v252
	v_mad_u32_u24 v254, v254, s100, v153
	v_mad_u32_u24 v255, v255, s100, v153
	global_load_dwordx4 v[188:191], v80, s[82:83]
	global_load_dwordx4 v[192:195], v83, s[82:83]
	global_load_dwordx4 v[196:199], v99, s[82:83]
	global_load_dwordx4 v[200:203], v253, s[82:83]
	global_load_dwordx4 v[204:207], v254, s[82:83] offset:768
	global_load_dwordx4 v[208:211], v255, s[82:83] offset:768
	global_load_dwordx4 v[212:215], v254, s[82:83] offset:832
	global_load_dwordx4 v[216:219], v255, s[82:83] offset:832
	ds_read2_b32 v[32:33], v115 offset0:102 offset1:103
	ds_read2_b32 v[34:35], v115 offset0:104 offset1:105
	ds_read2_b32 v[36:37], v115 offset0:110 offset1:111
	ds_read2_b32 v[38:39], v115 offset0:112 offset1:113
	ds_read2_b32 v[40:41], v115 offset0:119 offset1:120
	ds_read2_b32 v[42:43], v115 offset0:121 offset1:122
	ds_read2_b32 v[44:45], v115 offset0:127 offset1:128
	ds_read2_b32 v[46:47], v115 offset0:129 offset1:130
	s_waitcnt lgkmcnt(0)
	v_mfma_f32_32x32x16_bf16 v[32:47], v[116:119], v[48:51], v[32:47]
	ds_read_b64_tr_b16 v[72:73], v231
	ds_read_b64_tr_b16 v[74:75], v231 offset:512
	ds_read_b64_tr_b16 v[76:77], v231 offset:2048
	ds_read_b64_tr_b16 v[78:79], v231 offset:2560
	ds_read_b64_tr_b16 v[220:221], v231 offset:1024
	ds_read_b64_tr_b16 v[222:223], v231 offset:1536
	ds_read_b64_tr_b16 v[224:225], v231 offset:3072
	ds_read_b64_tr_b16 v[226:227], v231 offset:3584
	s_waitcnt vmcnt(8)
	ds_write_b128 v247, v[156:159]
	ds_write_b128 v247, v[160:163] offset:1024
	ds_write_b128 v247, v[164:167] offset:2048
	ds_write_b128 v247, v[168:171] offset:3072
	ds_read_b128 v[156:159], v248
	ds_read_b128 v[160:163], v249
	ds_read_b128 v[164:167], v250
	ds_read_b128 v[168:171], v251
	ds_write_b128 v112, v[172:175]
	ds_write_b128 v112, v[176:179] offset:1024
	ds_write_b128 v112, v[180:183] offset:2048
	ds_write_b128 v112, v[184:187] offset:3072
	v_mfma_f32_32x32x16_bf16 v[32:47], v[120:123], v[52:55], v[32:47]
	v_mfma_f32_32x32x16_bf16 v[32:47], v[124:127], v[56:59], v[32:47]
	v_mfma_f32_32x32x16_bf16 v[32:47], v[128:131], v[60:63], v[32:47]
	s_nop 11
	v_exp_f32_e32 v32, v32
	v_exp_f32_e32 v33, v33
	v_exp_f32_e32 v34, v34
	v_exp_f32_e32 v35, v35
	v_exp_f32_e32 v36, v36
	v_exp_f32_e32 v37, v37
	v_exp_f32_e32 v38, v38
	v_exp_f32_e32 v39, v39
	v_exp_f32_e32 v40, v40
	v_exp_f32_e32 v41, v41
	v_exp_f32_e32 v42, v42
	v_exp_f32_e32 v43, v43
	v_exp_f32_e32 v44, v44
	v_exp_f32_e32 v45, v45
	v_exp_f32_e32 v46, v46
	v_exp_f32_e32 v47, v47
	s_add_i32 s90, s67, 32
	v_add_u32_e32 v84, s90, v107
	v_add_u32_e32 v85, 0, v84
	v_add_u32_e32 v86, 1, v84
	v_add_u32_e32 v87, 2, v84
	v_add_u32_e32 v88, 3, v84
	v_cmp_gt_u32_e64 s[30:31], s98, v85
	v_cmp_gt_u32_e64 s[36:37], s98, v86
	v_cmp_gt_u32_e64 s[78:79], s98, v87
	v_cmp_gt_u32_e64 s[50:51], s98, v88
	v_cndmask_b32_e64 v32, 0, v32, s[30:31]
	v_add_u32_e32 v85, 8, v84
	v_cmp_gt_u32_e64 s[30:31], s98, v85
	v_cndmask_b32_e64 v33, 0, v33, s[36:37]
	v_add_u32_e32 v86, 9, v84
	v_cmp_gt_u32_e64 s[36:37], s98, v86
	v_cndmask_b32_e64 v34, 0, v34, s[78:79]
	v_add_u32_e32 v87, 10, v84
	v_cmp_gt_u32_e64 s[78:79], s98, v87
	v_cndmask_b32_e64 v35, 0, v35, s[50:51]
	v_add_u32_e32 v88, 11, v84
	v_cmp_gt_u32_e64 s[50:51], s98, v88
	v_cndmask_b32_e64 v36, 0, v36, s[30:31]
	v_add_u32_e32 v85, 16, v84
	v_cmp_gt_u32_e64 s[30:31], s98, v85
	v_cndmask_b32_e64 v37, 0, v37, s[36:37]
	v_add_u32_e32 v86, 17, v84
	v_cmp_gt_u32_e64 s[36:37], s98, v86
	v_cndmask_b32_e64 v38, 0, v38, s[78:79]
	v_add_u32_e32 v87, 18, v84
	v_cmp_gt_u32_e64 s[78:79], s98, v87
	v_cndmask_b32_e64 v39, 0, v39, s[50:51]
	v_add_u32_e32 v88, 19, v84
	v_cmp_gt_u32_e64 s[50:51], s98, v88
	v_cndmask_b32_e64 v40, 0, v40, s[30:31]
	v_add_u32_e32 v85, 24, v84
	v_cmp_gt_u32_e64 s[30:31], s98, v85
	v_cndmask_b32_e64 v41, 0, v41, s[36:37]
	v_add_u32_e32 v86, 25, v84
	v_cmp_gt_u32_e64 s[36:37], s98, v86
	v_cndmask_b32_e64 v42, 0, v42, s[78:79]
	v_add_u32_e32 v87, 26, v84
	v_cmp_gt_u32_e64 s[78:79], s98, v87
	v_cndmask_b32_e64 v43, 0, v43, s[50:51]
	v_add_u32_e32 v88, 27, v84
	v_cmp_gt_u32_e64 s[50:51], s98, v88
	v_nop
	v_cndmask_b32_e64 v44, 0, v44, s[30:31]
	v_cndmask_b32_e64 v45, 0, v45, s[36:37]
	v_cndmask_b32_e64 v46, 0, v46, s[78:79]
	v_cndmask_b32_e64 v47, 0, v47, s[50:51]
	v_cvt_pk_bf16_f32 v64, v32, v33
	v_cvt_pk_bf16_f32 v65, v34, v35
	v_cvt_pk_bf16_f32 v66, v36, v37
	v_cvt_pk_bf16_f32 v67, v38, v39
	v_cvt_pk_bf16_f32 v68, v40, v41
	v_cvt_pk_bf16_f32 v69, v42, v43
	v_cvt_pk_bf16_f32 v70, v44, v45
	v_cvt_pk_bf16_f32 v71, v46, v47
	v_pk_add_f32 v[232:233], v[232:233], v[32:33]
	v_pk_add_f32 v[232:233], v[232:233], v[34:35]
	v_pk_add_f32 v[232:233], v[232:233], v[36:37]
	v_pk_add_f32 v[232:233], v[232:233], v[38:39]
	v_pk_add_f32 v[232:233], v[232:233], v[40:41]
	v_pk_add_f32 v[232:233], v[232:233], v[42:43]
	v_pk_add_f32 v[232:233], v[232:233], v[44:45]
	v_pk_add_f32 v[232:233], v[232:233], v[46:47]
	s_waitcnt lgkmcnt(12)
	v_mfma_f32_32x32x16_bf16 v[0:15], v[64:67], v[72:75], v[0:15]
	v_mfma_f32_32x32x16_bf16 v[16:31], v[64:67], v[76:79], v[16:31]
	v_mfma_f32_32x32x16_bf16 v[0:15], v[68:71], v[220:223], v[0:15]
	v_mfma_f32_32x32x16_bf16 v[16:31], v[68:71], v[224:227], v[16:31]
	s_add_i32 s90, s67, 128
	v_add_u32_e32 v80, s90, v235
	v_add_u32_e32 v83, s90, v236
	v_add_u32_e32 v99, s90, v237
	v_add_u32_e32 v253, s90, v238
	v_add_u32_e32 v254, s90, v100
	v_add_u32_e32 v255, s90, v149
	v_med3_i32 v80, v80, 0, s99
	v_med3_i32 v83, v83, 0, s99
	v_med3_i32 v99, v99, 0, s99
	v_med3_i32 v253, v253, 0, s99
	v_med3_i32 v254, v254, 0, s99
	v_med3_i32 v255, v255, 0, s99
	v_mad_u32_u24 v80, v80, s100, v252
	v_mad_u32_u24 v83, v83, s100, v252
	v_mad_u32_u24 v99, v99, s100, v252
	v_mad_u32_u24 v253, v253, s100, v252
	v_mad_u32_u24 v254, v254, s100, v153
	v_mad_u32_u24 v255, v255, s100, v153
	global_load_dwordx4 v[116:119], v80, s[82:83]
	global_load_dwordx4 v[120:123], v83, s[82:83]
	global_load_dwordx4 v[124:127], v99, s[82:83]
	global_load_dwordx4 v[128:131], v253, s[82:83]
	global_load_dwordx4 v[132:135], v254, s[82:83] offset:768
	global_load_dwordx4 v[136:139], v255, s[82:83] offset:768
	global_load_dwordx4 v[140:143], v254, s[82:83] offset:832
	global_load_dwordx4 v[144:147], v255, s[82:83] offset:832
	ds_read2_b32 v[32:33], v115 offset0:136 offset1:137
	ds_read2_b32 v[34:35], v115 offset0:138 offset1:139
	ds_read2_b32 v[36:37], v115 offset0:144 offset1:145
	ds_read2_b32 v[38:39], v115 offset0:146 offset1:147
	ds_read2_b32 v[40:41], v115 offset0:153 offset1:154
	ds_read2_b32 v[42:43], v115 offset0:155 offset1:156
	ds_read2_b32 v[44:45], v115 offset0:161 offset1:162
	ds_read2_b32 v[46:47], v115 offset0:163 offset1:164
	s_waitcnt lgkmcnt(0)
	v_mfma_f32_32x32x16_bf16 v[32:47], v[156:159], v[48:51], v[32:47]
	ds_read_b64_tr_b16 v[72:73], v231
	ds_read_b64_tr_b16 v[74:75], v231 offset:512
	ds_read_b64_tr_b16 v[76:77], v231 offset:2048
	ds_read_b64_tr_b16 v[78:79], v231 offset:2560
	ds_read_b64_tr_b16 v[220:221], v231 offset:1024
	ds_read_b64_tr_b16 v[222:223], v231 offset:1536
	ds_read_b64_tr_b16 v[224:225], v231 offset:3072
	ds_read_b64_tr_b16 v[226:227], v231 offset:3584
	s_waitcnt vmcnt(8)
	ds_write_b128 v247, v[188:191]
	ds_write_b128 v247, v[192:195] offset:1024
	ds_write_b128 v247, v[196:199] offset:2048
	ds_write_b128 v247, v[200:203] offset:3072
	ds_read_b128 v[188:191], v248
	ds_read_b128 v[192:195], v249
	ds_read_b128 v[196:199], v250
	ds_read_b128 v[200:203], v251
	ds_write_b128 v112, v[204:207]
	ds_write_b128 v112, v[208:211] offset:1024
	ds_write_b128 v112, v[212:215] offset:2048
	ds_write_b128 v112, v[216:219] offset:3072
	v_mfma_f32_32x32x16_bf16 v[32:47], v[160:163], v[52:55], v[32:47]
	v_mfma_f32_32x32x16_bf16 v[32:47], v[164:167], v[56:59], v[32:47]
	v_mfma_f32_32x32x16_bf16 v[32:47], v[168:171], v[60:63], v[32:47]
	s_nop 11
	v_exp_f32_e32 v32, v32
	v_exp_f32_e32 v33, v33
	v_exp_f32_e32 v34, v34
	v_exp_f32_e32 v35, v35
	v_exp_f32_e32 v36, v36
	v_exp_f32_e32 v37, v37
	v_exp_f32_e32 v38, v38
	v_exp_f32_e32 v39, v39
	v_exp_f32_e32 v40, v40
	v_exp_f32_e32 v41, v41
	v_exp_f32_e32 v42, v42
	v_exp_f32_e32 v43, v43
	v_exp_f32_e32 v44, v44
	v_exp_f32_e32 v45, v45
	v_exp_f32_e32 v46, v46
	v_exp_f32_e32 v47, v47
	s_add_i32 s90, s67, 64
	v_add_u32_e32 v84, s90, v107
	v_add_u32_e32 v85, 0, v84
	v_add_u32_e32 v86, 1, v84
	v_add_u32_e32 v87, 2, v84
	v_add_u32_e32 v88, 3, v84
	v_cmp_gt_u32_e64 s[30:31], s98, v85
	v_cmp_gt_u32_e64 s[36:37], s98, v86
	v_cmp_gt_u32_e64 s[78:79], s98, v87
	v_cmp_gt_u32_e64 s[50:51], s98, v88
	v_cndmask_b32_e64 v32, 0, v32, s[30:31]
	v_add_u32_e32 v85, 8, v84
	v_cmp_gt_u32_e64 s[30:31], s98, v85
	v_cndmask_b32_e64 v33, 0, v33, s[36:37]
	v_add_u32_e32 v86, 9, v84
	v_cmp_gt_u32_e64 s[36:37], s98, v86
	v_cndmask_b32_e64 v34, 0, v34, s[78:79]
	v_add_u32_e32 v87, 10, v84
	v_cmp_gt_u32_e64 s[78:79], s98, v87
	v_cndmask_b32_e64 v35, 0, v35, s[50:51]
	v_add_u32_e32 v88, 11, v84
	v_cmp_gt_u32_e64 s[50:51], s98, v88
	v_cndmask_b32_e64 v36, 0, v36, s[30:31]
	v_add_u32_e32 v85, 16, v84
	v_cmp_gt_u32_e64 s[30:31], s98, v85
	v_cndmask_b32_e64 v37, 0, v37, s[36:37]
	v_add_u32_e32 v86, 17, v84
	v_cmp_gt_u32_e64 s[36:37], s98, v86
	v_cndmask_b32_e64 v38, 0, v38, s[78:79]
	v_add_u32_e32 v87, 18, v84
	v_cmp_gt_u32_e64 s[78:79], s98, v87
	v_cndmask_b32_e64 v39, 0, v39, s[50:51]
	v_add_u32_e32 v88, 19, v84
	v_cmp_gt_u32_e64 s[50:51], s98, v88
	v_cndmask_b32_e64 v40, 0, v40, s[30:31]
	v_add_u32_e32 v85, 24, v84
	v_cmp_gt_u32_e64 s[30:31], s98, v85
	v_cndmask_b32_e64 v41, 0, v41, s[36:37]
	v_add_u32_e32 v86, 25, v84
	v_cmp_gt_u32_e64 s[36:37], s98, v86
	v_cndmask_b32_e64 v42, 0, v42, s[78:79]
	v_add_u32_e32 v87, 26, v84
	v_cmp_gt_u32_e64 s[78:79], s98, v87
	v_cndmask_b32_e64 v43, 0, v43, s[50:51]
	v_add_u32_e32 v88, 27, v84
	v_cmp_gt_u32_e64 s[50:51], s98, v88
	v_nop
	v_cndmask_b32_e64 v44, 0, v44, s[30:31]
	v_cndmask_b32_e64 v45, 0, v45, s[36:37]
	v_cndmask_b32_e64 v46, 0, v46, s[78:79]
	v_cndmask_b32_e64 v47, 0, v47, s[50:51]
	v_cvt_pk_bf16_f32 v64, v32, v33
	v_cvt_pk_bf16_f32 v65, v34, v35
	v_cvt_pk_bf16_f32 v66, v36, v37
	v_cvt_pk_bf16_f32 v67, v38, v39
	v_cvt_pk_bf16_f32 v68, v40, v41
	v_cvt_pk_bf16_f32 v69, v42, v43
	v_cvt_pk_bf16_f32 v70, v44, v45
	v_cvt_pk_bf16_f32 v71, v46, v47
	v_pk_add_f32 v[232:233], v[232:233], v[32:33]
	v_pk_add_f32 v[232:233], v[232:233], v[34:35]
	v_pk_add_f32 v[232:233], v[232:233], v[36:37]
	v_pk_add_f32 v[232:233], v[232:233], v[38:39]
	v_pk_add_f32 v[232:233], v[232:233], v[40:41]
	v_pk_add_f32 v[232:233], v[232:233], v[42:43]
	v_pk_add_f32 v[232:233], v[232:233], v[44:45]
	v_pk_add_f32 v[232:233], v[232:233], v[46:47]
	s_waitcnt lgkmcnt(12)
	v_mfma_f32_32x32x16_bf16 v[0:15], v[64:67], v[72:75], v[0:15]
	v_mfma_f32_32x32x16_bf16 v[16:31], v[64:67], v[76:79], v[16:31]
	v_mfma_f32_32x32x16_bf16 v[0:15], v[68:71], v[220:223], v[0:15]
	v_mfma_f32_32x32x16_bf16 v[16:31], v[68:71], v[224:227], v[16:31]
	s_add_i32 s90, s67, 160
	v_add_u32_e32 v80, s90, v235
	v_add_u32_e32 v83, s90, v236
	v_add_u32_e32 v99, s90, v237
	v_add_u32_e32 v253, s90, v238
	v_add_u32_e32 v254, s90, v100
	v_add_u32_e32 v255, s90, v149
	v_med3_i32 v80, v80, 0, s99
	v_med3_i32 v83, v83, 0, s99
	v_med3_i32 v99, v99, 0, s99
	v_med3_i32 v253, v253, 0, s99
	v_med3_i32 v254, v254, 0, s99
	v_med3_i32 v255, v255, 0, s99
	v_mad_u32_u24 v80, v80, s100, v252
	v_mad_u32_u24 v83, v83, s100, v252
	v_mad_u32_u24 v99, v99, s100, v252
	v_mad_u32_u24 v253, v253, s100, v252
	v_mad_u32_u24 v254, v254, s100, v153
	v_mad_u32_u24 v255, v255, s100, v153
	global_load_dwordx4 v[156:159], v80, s[82:83]
	global_load_dwordx4 v[160:163], v83, s[82:83]
	global_load_dwordx4 v[164:167], v99, s[82:83]
	global_load_dwordx4 v[168:171], v253, s[82:83]
	global_load_dwordx4 v[172:175], v254, s[82:83] offset:768
	global_load_dwordx4 v[176:179], v255, s[82:83] offset:768
	global_load_dwordx4 v[180:183], v254, s[82:83] offset:832
	global_load_dwordx4 v[184:187], v255, s[82:83] offset:832
	ds_read2_b32 v[32:33], v115 offset0:170 offset1:171
	ds_read2_b32 v[34:35], v115 offset0:172 offset1:173
	ds_read2_b32 v[36:37], v115 offset0:178 offset1:179
	ds_read2_b32 v[38:39], v115 offset0:180 offset1:181
	ds_read2_b32 v[40:41], v115 offset0:187 offset1:188
	ds_read2_b32 v[42:43], v115 offset0:189 offset1:190
	ds_read2_b32 v[44:45], v115 offset0:195 offset1:196
	ds_read2_b32 v[46:47], v115 offset0:197 offset1:198
	s_waitcnt lgkmcnt(0)
	v_mfma_f32_32x32x16_bf16 v[32:47], v[188:191], v[48:51], v[32:47]
	ds_read_b64_tr_b16 v[72:73], v231
	ds_read_b64_tr_b16 v[74:75], v231 offset:512
	ds_read_b64_tr_b16 v[76:77], v231 offset:2048
	ds_read_b64_tr_b16 v[78:79], v231 offset:2560
	ds_read_b64_tr_b16 v[220:221], v231 offset:1024
	ds_read_b64_tr_b16 v[222:223], v231 offset:1536
	ds_read_b64_tr_b16 v[224:225], v231 offset:3072
	ds_read_b64_tr_b16 v[226:227], v231 offset:3584
	s_waitcnt vmcnt(8)
	ds_write_b128 v247, v[116:119]
	ds_write_b128 v247, v[120:123] offset:1024
	ds_write_b128 v247, v[124:127] offset:2048
	ds_write_b128 v247, v[128:131] offset:3072
	ds_read_b128 v[116:119], v248
	ds_read_b128 v[120:123], v249
	ds_read_b128 v[124:127], v250
	ds_read_b128 v[128:131], v251
	ds_write_b128 v112, v[132:135]
	ds_write_b128 v112, v[136:139] offset:1024
	ds_write_b128 v112, v[140:143] offset:2048
	ds_write_b128 v112, v[144:147] offset:3072
	v_mfma_f32_32x32x16_bf16 v[32:47], v[192:195], v[52:55], v[32:47]
	v_mfma_f32_32x32x16_bf16 v[32:47], v[196:199], v[56:59], v[32:47]
	v_mfma_f32_32x32x16_bf16 v[32:47], v[200:203], v[60:63], v[32:47]
	s_nop 11
	v_exp_f32_e32 v32, v32
	v_exp_f32_e32 v33, v33
	v_exp_f32_e32 v34, v34
	v_exp_f32_e32 v35, v35
	v_exp_f32_e32 v36, v36
	v_exp_f32_e32 v37, v37
	v_exp_f32_e32 v38, v38
	v_exp_f32_e32 v39, v39
	v_exp_f32_e32 v40, v40
	v_exp_f32_e32 v41, v41
	v_exp_f32_e32 v42, v42
	v_exp_f32_e32 v43, v43
	v_exp_f32_e32 v44, v44
	v_exp_f32_e32 v45, v45
	v_exp_f32_e32 v46, v46
	v_exp_f32_e32 v47, v47
	s_add_i32 s90, s67, 96
	v_add_u32_e32 v84, s90, v107
	v_add_u32_e32 v85, 0, v84
	v_add_u32_e32 v86, 1, v84
	v_add_u32_e32 v87, 2, v84
	v_add_u32_e32 v88, 3, v84
	v_cmp_gt_u32_e64 s[30:31], s98, v85
	v_cmp_gt_u32_e64 s[36:37], s98, v86
	v_cmp_gt_u32_e64 s[78:79], s98, v87
	v_cmp_gt_u32_e64 s[50:51], s98, v88
	v_cndmask_b32_e64 v32, 0, v32, s[30:31]
	v_add_u32_e32 v85, 8, v84
	v_cmp_gt_u32_e64 s[30:31], s98, v85
	v_cndmask_b32_e64 v33, 0, v33, s[36:37]
	v_add_u32_e32 v86, 9, v84
	v_cmp_gt_u32_e64 s[36:37], s98, v86
	v_cndmask_b32_e64 v34, 0, v34, s[78:79]
	v_add_u32_e32 v87, 10, v84
	v_cmp_gt_u32_e64 s[78:79], s98, v87
	v_cndmask_b32_e64 v35, 0, v35, s[50:51]
	v_add_u32_e32 v88, 11, v84
	v_cmp_gt_u32_e64 s[50:51], s98, v88
	v_cndmask_b32_e64 v36, 0, v36, s[30:31]
	v_add_u32_e32 v85, 16, v84
	v_cmp_gt_u32_e64 s[30:31], s98, v85
	v_cndmask_b32_e64 v37, 0, v37, s[36:37]
	v_add_u32_e32 v86, 17, v84
	v_cmp_gt_u32_e64 s[36:37], s98, v86
	v_cndmask_b32_e64 v38, 0, v38, s[78:79]
	v_add_u32_e32 v87, 18, v84
	v_cmp_gt_u32_e64 s[78:79], s98, v87
	v_cndmask_b32_e64 v39, 0, v39, s[50:51]
	v_add_u32_e32 v88, 19, v84
	v_cmp_gt_u32_e64 s[50:51], s98, v88
	v_cndmask_b32_e64 v40, 0, v40, s[30:31]
	v_add_u32_e32 v85, 24, v84
	v_cmp_gt_u32_e64 s[30:31], s98, v85
	v_cndmask_b32_e64 v41, 0, v41, s[36:37]
	v_add_u32_e32 v86, 25, v84
	v_cmp_gt_u32_e64 s[36:37], s98, v86
	v_cndmask_b32_e64 v42, 0, v42, s[78:79]
	v_add_u32_e32 v87, 26, v84
	v_cmp_gt_u32_e64 s[78:79], s98, v87
	v_cndmask_b32_e64 v43, 0, v43, s[50:51]
	v_add_u32_e32 v88, 27, v84
	v_cmp_gt_u32_e64 s[50:51], s98, v88
	v_nop
	v_cndmask_b32_e64 v44, 0, v44, s[30:31]
	v_cndmask_b32_e64 v45, 0, v45, s[36:37]
	v_cndmask_b32_e64 v46, 0, v46, s[78:79]
	v_cndmask_b32_e64 v47, 0, v47, s[50:51]
	v_cvt_pk_bf16_f32 v64, v32, v33
	v_cvt_pk_bf16_f32 v65, v34, v35
	v_cvt_pk_bf16_f32 v66, v36, v37
	v_cvt_pk_bf16_f32 v67, v38, v39
	v_cvt_pk_bf16_f32 v68, v40, v41
	v_cvt_pk_bf16_f32 v69, v42, v43
	v_cvt_pk_bf16_f32 v70, v44, v45
	v_cvt_pk_bf16_f32 v71, v46, v47
	v_pk_add_f32 v[232:233], v[232:233], v[32:33]
	v_pk_add_f32 v[232:233], v[232:233], v[34:35]
	v_pk_add_f32 v[232:233], v[232:233], v[36:37]
	v_pk_add_f32 v[232:233], v[232:233], v[38:39]
	v_pk_add_f32 v[232:233], v[232:233], v[40:41]
	v_pk_add_f32 v[232:233], v[232:233], v[42:43]
	v_pk_add_f32 v[232:233], v[232:233], v[44:45]
	v_pk_add_f32 v[232:233], v[232:233], v[46:47]
	s_waitcnt lgkmcnt(12)
	v_mfma_f32_32x32x16_bf16 v[0:15], v[64:67], v[72:75], v[0:15]
	v_mfma_f32_32x32x16_bf16 v[16:31], v[64:67], v[76:79], v[16:31]
	v_mfma_f32_32x32x16_bf16 v[0:15], v[68:71], v[220:223], v[0:15]
	v_mfma_f32_32x32x16_bf16 v[16:31], v[68:71], v[224:227], v[16:31]
	s_add_i32 s90, s67, 192
	v_add_u32_e32 v80, s90, v235
	v_add_u32_e32 v83, s90, v236
	v_add_u32_e32 v99, s90, v237
	v_add_u32_e32 v253, s90, v238
	v_add_u32_e32 v254, s90, v100
	v_add_u32_e32 v255, s90, v149
	v_med3_i32 v80, v80, 0, s99
	v_med3_i32 v83, v83, 0, s99
	v_med3_i32 v99, v99, 0, s99
	v_med3_i32 v253, v253, 0, s99
	v_med3_i32 v254, v254, 0, s99
	v_med3_i32 v255, v255, 0, s99
	v_mad_u32_u24 v80, v80, s100, v252
	v_mad_u32_u24 v83, v83, s100, v252
	v_mad_u32_u24 v99, v99, s100, v252
	v_mad_u32_u24 v253, v253, s100, v252
	v_mad_u32_u24 v254, v254, s100, v153
	v_mad_u32_u24 v255, v255, s100, v153
	global_load_dwordx4 v[188:191], v80, s[82:83]
	global_load_dwordx4 v[192:195], v83, s[82:83]
	global_load_dwordx4 v[196:199], v99, s[82:83]
	global_load_dwordx4 v[200:203], v253, s[82:83]
	global_load_dwordx4 v[204:207], v254, s[82:83] offset:768
	global_load_dwordx4 v[208:211], v255, s[82:83] offset:768
	global_load_dwordx4 v[212:215], v254, s[82:83] offset:832
	global_load_dwordx4 v[216:219], v255, s[82:83] offset:832
	ds_read2_b32 v[32:33], v115 offset0:204 offset1:205
	ds_read2_b32 v[34:35], v115 offset0:206 offset1:207
	ds_read2_b32 v[36:37], v115 offset0:212 offset1:213
	ds_read2_b32 v[38:39], v115 offset0:214 offset1:215
	ds_read2_b32 v[40:41], v115 offset0:221 offset1:222
	ds_read2_b32 v[42:43], v115 offset0:223 offset1:224
	ds_read2_b32 v[44:45], v115 offset0:229 offset1:230
	ds_read2_b32 v[46:47], v115 offset0:231 offset1:232
	s_waitcnt lgkmcnt(0)
	v_mfma_f32_32x32x16_bf16 v[32:47], v[116:119], v[48:51], v[32:47]
	ds_read_b64_tr_b16 v[72:73], v231
	ds_read_b64_tr_b16 v[74:75], v231 offset:512
	ds_read_b64_tr_b16 v[76:77], v231 offset:2048
	ds_read_b64_tr_b16 v[78:79], v231 offset:2560
	ds_read_b64_tr_b16 v[220:221], v231 offset:1024
	ds_read_b64_tr_b16 v[222:223], v231 offset:1536
	ds_read_b64_tr_b16 v[224:225], v231 offset:3072
	ds_read_b64_tr_b16 v[226:227], v231 offset:3584
	s_waitcnt vmcnt(8)
	ds_write_b128 v247, v[156:159]
	ds_write_b128 v247, v[160:163] offset:1024
	ds_write_b128 v247, v[164:167] offset:2048
	ds_write_b128 v247, v[168:171] offset:3072
	ds_read_b128 v[156:159], v248
	ds_read_b128 v[160:163], v249
	ds_read_b128 v[164:167], v250
	ds_read_b128 v[168:171], v251
	ds_write_b128 v112, v[172:175]
	ds_write_b128 v112, v[176:179] offset:1024
	ds_write_b128 v112, v[180:183] offset:2048
	ds_write_b128 v112, v[184:187] offset:3072
	v_mfma_f32_32x32x16_bf16 v[32:47], v[120:123], v[52:55], v[32:47]
	v_mfma_f32_32x32x16_bf16 v[32:47], v[124:127], v[56:59], v[32:47]
	v_mfma_f32_32x32x16_bf16 v[32:47], v[128:131], v[60:63], v[32:47]
	s_nop 11
	v_exp_f32_e32 v32, v32
	v_exp_f32_e32 v33, v33
	v_exp_f32_e32 v34, v34
	v_exp_f32_e32 v35, v35
	v_exp_f32_e32 v36, v36
	v_exp_f32_e32 v37, v37
	v_exp_f32_e32 v38, v38
	v_exp_f32_e32 v39, v39
	v_exp_f32_e32 v40, v40
	v_exp_f32_e32 v41, v41
	v_exp_f32_e32 v42, v42
	v_exp_f32_e32 v43, v43
	v_exp_f32_e32 v44, v44
	v_exp_f32_e32 v45, v45
	v_exp_f32_e32 v46, v46
	v_exp_f32_e32 v47, v47
	s_add_i32 s90, s67, 128
	v_add_u32_e32 v84, s90, v107
	v_add_u32_e32 v85, 0, v84
	v_add_u32_e32 v86, 1, v84
	v_add_u32_e32 v87, 2, v84
	v_add_u32_e32 v88, 3, v84
	v_cmp_gt_u32_e64 s[30:31], s98, v85
	v_cmp_gt_u32_e64 s[36:37], s98, v86
	v_cmp_gt_u32_e64 s[78:79], s98, v87
	v_cmp_gt_u32_e64 s[50:51], s98, v88
	v_cndmask_b32_e64 v32, 0, v32, s[30:31]
	v_add_u32_e32 v85, 8, v84
	v_cmp_gt_u32_e64 s[30:31], s98, v85
	v_cndmask_b32_e64 v33, 0, v33, s[36:37]
	v_add_u32_e32 v86, 9, v84
	v_cmp_gt_u32_e64 s[36:37], s98, v86
	v_cndmask_b32_e64 v34, 0, v34, s[78:79]
	v_add_u32_e32 v87, 10, v84
	v_cmp_gt_u32_e64 s[78:79], s98, v87
	v_cndmask_b32_e64 v35, 0, v35, s[50:51]
	v_add_u32_e32 v88, 11, v84
	v_cmp_gt_u32_e64 s[50:51], s98, v88
	v_cndmask_b32_e64 v36, 0, v36, s[30:31]
	v_add_u32_e32 v85, 16, v84
	v_cmp_gt_u32_e64 s[30:31], s98, v85
	v_cndmask_b32_e64 v37, 0, v37, s[36:37]
	v_add_u32_e32 v86, 17, v84
	v_cmp_gt_u32_e64 s[36:37], s98, v86
	v_cndmask_b32_e64 v38, 0, v38, s[78:79]
	v_add_u32_e32 v87, 18, v84
	v_cmp_gt_u32_e64 s[78:79], s98, v87
	v_cndmask_b32_e64 v39, 0, v39, s[50:51]
	v_add_u32_e32 v88, 19, v84
	v_cmp_gt_u32_e64 s[50:51], s98, v88
	v_cndmask_b32_e64 v40, 0, v40, s[30:31]
	v_add_u32_e32 v85, 24, v84
	v_cmp_gt_u32_e64 s[30:31], s98, v85
	v_cndmask_b32_e64 v41, 0, v41, s[36:37]
	v_add_u32_e32 v86, 25, v84
	v_cmp_gt_u32_e64 s[36:37], s98, v86
	v_cndmask_b32_e64 v42, 0, v42, s[78:79]
	v_add_u32_e32 v87, 26, v84
	v_cmp_gt_u32_e64 s[78:79], s98, v87
	v_cndmask_b32_e64 v43, 0, v43, s[50:51]
	v_add_u32_e32 v88, 27, v84
	v_cmp_gt_u32_e64 s[50:51], s98, v88
	v_nop
	v_cndmask_b32_e64 v44, 0, v44, s[30:31]
	v_cndmask_b32_e64 v45, 0, v45, s[36:37]
	v_cndmask_b32_e64 v46, 0, v46, s[78:79]
	v_cndmask_b32_e64 v47, 0, v47, s[50:51]
	v_cvt_pk_bf16_f32 v64, v32, v33
	v_cvt_pk_bf16_f32 v65, v34, v35
	v_cvt_pk_bf16_f32 v66, v36, v37
	v_cvt_pk_bf16_f32 v67, v38, v39
	v_cvt_pk_bf16_f32 v68, v40, v41
	v_cvt_pk_bf16_f32 v69, v42, v43
	v_cvt_pk_bf16_f32 v70, v44, v45
	v_cvt_pk_bf16_f32 v71, v46, v47
	v_pk_add_f32 v[232:233], v[232:233], v[32:33]
	v_pk_add_f32 v[232:233], v[232:233], v[34:35]
	v_pk_add_f32 v[232:233], v[232:233], v[36:37]
	v_pk_add_f32 v[232:233], v[232:233], v[38:39]
	v_pk_add_f32 v[232:233], v[232:233], v[40:41]
	v_pk_add_f32 v[232:233], v[232:233], v[42:43]
	v_pk_add_f32 v[232:233], v[232:233], v[44:45]
	v_pk_add_f32 v[232:233], v[232:233], v[46:47]
	s_waitcnt lgkmcnt(12)
	v_mfma_f32_32x32x16_bf16 v[0:15], v[64:67], v[72:75], v[0:15]
	v_mfma_f32_32x32x16_bf16 v[16:31], v[64:67], v[76:79], v[16:31]
	v_mfma_f32_32x32x16_bf16 v[0:15], v[68:71], v[220:223], v[0:15]
	v_mfma_f32_32x32x16_bf16 v[16:31], v[68:71], v[224:227], v[16:31]
	s_add_i32 s90, s67, 224
	v_add_u32_e32 v80, s90, v235
	v_add_u32_e32 v83, s90, v236
	v_add_u32_e32 v99, s90, v237
	v_add_u32_e32 v253, s90, v238
	v_add_u32_e32 v254, s90, v100
	v_add_u32_e32 v255, s90, v149
	v_med3_i32 v80, v80, 0, s99
	v_med3_i32 v83, v83, 0, s99
	v_med3_i32 v99, v99, 0, s99
	v_med3_i32 v253, v253, 0, s99
	v_med3_i32 v254, v254, 0, s99
	v_med3_i32 v255, v255, 0, s99
	v_mad_u32_u24 v80, v80, s100, v252
	v_mad_u32_u24 v83, v83, s100, v252
	v_mad_u32_u24 v99, v99, s100, v252
	v_mad_u32_u24 v253, v253, s100, v252
	v_mad_u32_u24 v254, v254, s100, v153
	v_mad_u32_u24 v255, v255, s100, v153
	global_load_dwordx4 v[116:119], v80, s[82:83]
	global_load_dwordx4 v[120:123], v83, s[82:83]
	global_load_dwordx4 v[124:127], v99, s[82:83]
	global_load_dwordx4 v[128:131], v253, s[82:83]
	global_load_dwordx4 v[132:135], v254, s[82:83] offset:768
	global_load_dwordx4 v[136:139], v255, s[82:83] offset:768
	global_load_dwordx4 v[140:143], v254, s[82:83] offset:832
	global_load_dwordx4 v[144:147], v255, s[82:83] offset:832
	v_add_u32_e32 v115, 952, v115
	ds_read2_b32 v[32:33], v115 offset0:0 offset1:1
	ds_read2_b32 v[34:35], v115 offset0:2 offset1:3
	ds_read2_b32 v[36:37], v115 offset0:8 offset1:9
	ds_read2_b32 v[38:39], v115 offset0:10 offset1:11
	ds_read2_b32 v[40:41], v115 offset0:17 offset1:18
	ds_read2_b32 v[42:43], v115 offset0:19 offset1:20
	ds_read2_b32 v[44:45], v115 offset0:25 offset1:26
	ds_read2_b32 v[46:47], v115 offset0:27 offset1:28
	s_waitcnt lgkmcnt(0)
	v_mfma_f32_32x32x16_bf16 v[32:47], v[156:159], v[48:51], v[32:47]
	ds_read_b64_tr_b16 v[72:73], v231
	ds_read_b64_tr_b16 v[74:75], v231 offset:512
	ds_read_b64_tr_b16 v[76:77], v231 offset:2048
	ds_read_b64_tr_b16 v[78:79], v231 offset:2560
	ds_read_b64_tr_b16 v[220:221], v231 offset:1024
	ds_read_b64_tr_b16 v[222:223], v231 offset:1536
	ds_read_b64_tr_b16 v[224:225], v231 offset:3072
	ds_read_b64_tr_b16 v[226:227], v231 offset:3584
	s_waitcnt vmcnt(8)
	ds_write_b128 v247, v[188:191]
	ds_write_b128 v247, v[192:195] offset:1024
	ds_write_b128 v247, v[196:199] offset:2048
	ds_write_b128 v247, v[200:203] offset:3072
	ds_read_b128 v[188:191], v248
	ds_read_b128 v[192:195], v249
	ds_read_b128 v[196:199], v250
	ds_read_b128 v[200:203], v251
	ds_write_b128 v112, v[204:207]
	ds_write_b128 v112, v[208:211] offset:1024
	ds_write_b128 v112, v[212:215] offset:2048
	ds_write_b128 v112, v[216:219] offset:3072
	v_mfma_f32_32x32x16_bf16 v[32:47], v[160:163], v[52:55], v[32:47]
	v_mfma_f32_32x32x16_bf16 v[32:47], v[164:167], v[56:59], v[32:47]
	v_mfma_f32_32x32x16_bf16 v[32:47], v[168:171], v[60:63], v[32:47]
	s_nop 11
	v_exp_f32_e32 v32, v32
	v_exp_f32_e32 v33, v33
	v_exp_f32_e32 v34, v34
	v_exp_f32_e32 v35, v35
	v_exp_f32_e32 v36, v36
	v_exp_f32_e32 v37, v37
	v_exp_f32_e32 v38, v38
	v_exp_f32_e32 v39, v39
	v_exp_f32_e32 v40, v40
	v_exp_f32_e32 v41, v41
	v_exp_f32_e32 v42, v42
	v_exp_f32_e32 v43, v43
	v_exp_f32_e32 v44, v44
	v_exp_f32_e32 v45, v45
	v_exp_f32_e32 v46, v46
	v_exp_f32_e32 v47, v47
	s_add_i32 s90, s67, 160
	v_add_u32_e32 v84, s90, v107
	v_add_u32_e32 v85, 0, v84
	v_add_u32_e32 v86, 1, v84
	v_add_u32_e32 v87, 2, v84
	v_add_u32_e32 v88, 3, v84
	v_cmp_gt_u32_e64 s[30:31], s98, v85
	v_cmp_gt_u32_e64 s[36:37], s98, v86
	v_cmp_gt_u32_e64 s[78:79], s98, v87
	v_cmp_gt_u32_e64 s[50:51], s98, v88
	v_cndmask_b32_e64 v32, 0, v32, s[30:31]
	v_add_u32_e32 v85, 8, v84
	v_cmp_gt_u32_e64 s[30:31], s98, v85
	v_cndmask_b32_e64 v33, 0, v33, s[36:37]
	v_add_u32_e32 v86, 9, v84
	v_cmp_gt_u32_e64 s[36:37], s98, v86
	v_cndmask_b32_e64 v34, 0, v34, s[78:79]
	v_add_u32_e32 v87, 10, v84
	v_cmp_gt_u32_e64 s[78:79], s98, v87
	v_cndmask_b32_e64 v35, 0, v35, s[50:51]
	v_add_u32_e32 v88, 11, v84
	v_cmp_gt_u32_e64 s[50:51], s98, v88
	v_cndmask_b32_e64 v36, 0, v36, s[30:31]
	v_add_u32_e32 v85, 16, v84
	v_cmp_gt_u32_e64 s[30:31], s98, v85
	v_cndmask_b32_e64 v37, 0, v37, s[36:37]
	v_add_u32_e32 v86, 17, v84
	v_cmp_gt_u32_e64 s[36:37], s98, v86
	v_cndmask_b32_e64 v38, 0, v38, s[78:79]
	v_add_u32_e32 v87, 18, v84
	v_cmp_gt_u32_e64 s[78:79], s98, v87
	v_cndmask_b32_e64 v39, 0, v39, s[50:51]
	v_add_u32_e32 v88, 19, v84
	v_cmp_gt_u32_e64 s[50:51], s98, v88
	v_cndmask_b32_e64 v40, 0, v40, s[30:31]
	v_add_u32_e32 v85, 24, v84
	v_cmp_gt_u32_e64 s[30:31], s98, v85
	v_cndmask_b32_e64 v41, 0, v41, s[36:37]
	v_add_u32_e32 v86, 25, v84
	v_cmp_gt_u32_e64 s[36:37], s98, v86
	v_cndmask_b32_e64 v42, 0, v42, s[78:79]
	v_add_u32_e32 v87, 26, v84
	v_cmp_gt_u32_e64 s[78:79], s98, v87
	v_cndmask_b32_e64 v43, 0, v43, s[50:51]
	v_add_u32_e32 v88, 27, v84
	v_cmp_gt_u32_e64 s[50:51], s98, v88
	v_nop
	v_cndmask_b32_e64 v44, 0, v44, s[30:31]
	v_cndmask_b32_e64 v45, 0, v45, s[36:37]
	v_cndmask_b32_e64 v46, 0, v46, s[78:79]
	v_cndmask_b32_e64 v47, 0, v47, s[50:51]
	v_cvt_pk_bf16_f32 v64, v32, v33
	v_cvt_pk_bf16_f32 v65, v34, v35
	v_cvt_pk_bf16_f32 v66, v36, v37
	v_cvt_pk_bf16_f32 v67, v38, v39
	v_cvt_pk_bf16_f32 v68, v40, v41
	v_cvt_pk_bf16_f32 v69, v42, v43
	v_cvt_pk_bf16_f32 v70, v44, v45
	v_cvt_pk_bf16_f32 v71, v46, v47
	v_pk_add_f32 v[232:233], v[232:233], v[32:33]
	v_pk_add_f32 v[232:233], v[232:233], v[34:35]
	v_pk_add_f32 v[232:233], v[232:233], v[36:37]
	v_pk_add_f32 v[232:233], v[232:233], v[38:39]
	v_pk_add_f32 v[232:233], v[232:233], v[40:41]
	v_pk_add_f32 v[232:233], v[232:233], v[42:43]
	v_pk_add_f32 v[232:233], v[232:233], v[44:45]
	v_pk_add_f32 v[232:233], v[232:233], v[46:47]
	s_waitcnt lgkmcnt(12)
	v_mfma_f32_32x32x16_bf16 v[0:15], v[64:67], v[72:75], v[0:15]
	v_mfma_f32_32x32x16_bf16 v[16:31], v[64:67], v[76:79], v[16:31]
	v_mfma_f32_32x32x16_bf16 v[0:15], v[68:71], v[220:223], v[0:15]
	v_mfma_f32_32x32x16_bf16 v[16:31], v[68:71], v[224:227], v[16:31]
	s_add_i32 s90, s67, 256
	v_add_u32_e32 v80, s90, v235
	v_add_u32_e32 v83, s90, v236
	v_add_u32_e32 v99, s90, v237
	v_add_u32_e32 v253, s90, v238
	v_add_u32_e32 v254, s90, v100
	v_add_u32_e32 v255, s90, v149
	v_med3_i32 v80, v80, 0, s99
	v_med3_i32 v83, v83, 0, s99
	v_med3_i32 v99, v99, 0, s99
	v_med3_i32 v253, v253, 0, s99
	v_med3_i32 v254, v254, 0, s99
	v_med3_i32 v255, v255, 0, s99
	v_mad_u32_u24 v80, v80, s100, v252
	v_mad_u32_u24 v83, v83, s100, v252
	v_mad_u32_u24 v99, v99, s100, v252
	v_mad_u32_u24 v253, v253, s100, v252
	v_mad_u32_u24 v254, v254, s100, v153
	v_mad_u32_u24 v255, v255, s100, v153
	global_load_dwordx4 v[156:159], v80, s[82:83]
	global_load_dwordx4 v[160:163], v83, s[82:83]
	global_load_dwordx4 v[164:167], v99, s[82:83]
	global_load_dwordx4 v[168:171], v253, s[82:83]
	global_load_dwordx4 v[172:175], v254, s[82:83] offset:768
	global_load_dwordx4 v[176:179], v255, s[82:83] offset:768
	global_load_dwordx4 v[180:183], v254, s[82:83] offset:832
	global_load_dwordx4 v[184:187], v255, s[82:83] offset:832
	ds_read2_b32 v[32:33], v115 offset0:34 offset1:35
	ds_read2_b32 v[34:35], v115 offset0:36 offset1:37
	ds_read2_b32 v[36:37], v115 offset0:42 offset1:43
	ds_read2_b32 v[38:39], v115 offset0:44 offset1:45
	ds_read2_b32 v[40:41], v115 offset0:51 offset1:52
	ds_read2_b32 v[42:43], v115 offset0:53 offset1:54
	ds_read2_b32 v[44:45], v115 offset0:59 offset1:60
	ds_read2_b32 v[46:47], v115 offset0:61 offset1:62
	s_waitcnt lgkmcnt(0)
	v_mfma_f32_32x32x16_bf16 v[32:47], v[188:191], v[48:51], v[32:47]
	ds_read_b64_tr_b16 v[72:73], v231
	ds_read_b64_tr_b16 v[74:75], v231 offset:512
	ds_read_b64_tr_b16 v[76:77], v231 offset:2048
	ds_read_b64_tr_b16 v[78:79], v231 offset:2560
	ds_read_b64_tr_b16 v[220:221], v231 offset:1024
	ds_read_b64_tr_b16 v[222:223], v231 offset:1536
	ds_read_b64_tr_b16 v[224:225], v231 offset:3072
	ds_read_b64_tr_b16 v[226:227], v231 offset:3584
	s_waitcnt vmcnt(8)
	ds_write_b128 v247, v[116:119]
	ds_write_b128 v247, v[120:123] offset:1024
	ds_write_b128 v247, v[124:127] offset:2048
	ds_write_b128 v247, v[128:131] offset:3072
	ds_read_b128 v[116:119], v248
	ds_read_b128 v[120:123], v249
	ds_read_b128 v[124:127], v250
	ds_read_b128 v[128:131], v251
	ds_write_b128 v112, v[132:135]
	ds_write_b128 v112, v[136:139] offset:1024
	ds_write_b128 v112, v[140:143] offset:2048
	ds_write_b128 v112, v[144:147] offset:3072
	v_mfma_f32_32x32x16_bf16 v[32:47], v[192:195], v[52:55], v[32:47]
	v_mfma_f32_32x32x16_bf16 v[32:47], v[196:199], v[56:59], v[32:47]
	v_mfma_f32_32x32x16_bf16 v[32:47], v[200:203], v[60:63], v[32:47]
	s_nop 11
	v_exp_f32_e32 v32, v32
	v_exp_f32_e32 v33, v33
	v_exp_f32_e32 v34, v34
	v_exp_f32_e32 v35, v35
	v_exp_f32_e32 v36, v36
	v_exp_f32_e32 v37, v37
	v_exp_f32_e32 v38, v38
	v_exp_f32_e32 v39, v39
	v_exp_f32_e32 v40, v40
	v_exp_f32_e32 v41, v41
	v_exp_f32_e32 v42, v42
	v_exp_f32_e32 v43, v43
	v_exp_f32_e32 v44, v44
	v_exp_f32_e32 v45, v45
	v_exp_f32_e32 v46, v46
	v_exp_f32_e32 v47, v47
	s_add_i32 s90, s67, 192
	v_add_u32_e32 v84, s90, v107
	v_add_u32_e32 v85, 0, v84
	v_add_u32_e32 v86, 1, v84
	v_add_u32_e32 v87, 2, v84
	v_add_u32_e32 v88, 3, v84
	v_cmp_gt_u32_e64 s[30:31], s98, v85
	v_cmp_gt_u32_e64 s[36:37], s98, v86
	v_cmp_gt_u32_e64 s[78:79], s98, v87
	v_cmp_gt_u32_e64 s[50:51], s98, v88
	v_cndmask_b32_e64 v32, 0, v32, s[30:31]
	v_add_u32_e32 v85, 8, v84
	v_cmp_gt_u32_e64 s[30:31], s98, v85
	v_cndmask_b32_e64 v33, 0, v33, s[36:37]
	v_add_u32_e32 v86, 9, v84
	v_cmp_gt_u32_e64 s[36:37], s98, v86
	v_cndmask_b32_e64 v34, 0, v34, s[78:79]
	v_add_u32_e32 v87, 10, v84
	v_cmp_gt_u32_e64 s[78:79], s98, v87
	v_cndmask_b32_e64 v35, 0, v35, s[50:51]
	v_add_u32_e32 v88, 11, v84
	v_cmp_gt_u32_e64 s[50:51], s98, v88
	v_cndmask_b32_e64 v36, 0, v36, s[30:31]
	v_add_u32_e32 v85, 16, v84
	v_cmp_gt_u32_e64 s[30:31], s98, v85
	v_cndmask_b32_e64 v37, 0, v37, s[36:37]
	v_add_u32_e32 v86, 17, v84
	v_cmp_gt_u32_e64 s[36:37], s98, v86
	v_cndmask_b32_e64 v38, 0, v38, s[78:79]
	v_add_u32_e32 v87, 18, v84
	v_cmp_gt_u32_e64 s[78:79], s98, v87
	v_cndmask_b32_e64 v39, 0, v39, s[50:51]
	v_add_u32_e32 v88, 19, v84
	v_cmp_gt_u32_e64 s[50:51], s98, v88
	v_cndmask_b32_e64 v40, 0, v40, s[30:31]
	v_add_u32_e32 v85, 24, v84
	v_cmp_gt_u32_e64 s[30:31], s98, v85
	v_cndmask_b32_e64 v41, 0, v41, s[36:37]
	v_add_u32_e32 v86, 25, v84
	v_cmp_gt_u32_e64 s[36:37], s98, v86
	v_cndmask_b32_e64 v42, 0, v42, s[78:79]
	v_add_u32_e32 v87, 26, v84
	v_cmp_gt_u32_e64 s[78:79], s98, v87
	v_cndmask_b32_e64 v43, 0, v43, s[50:51]
	v_add_u32_e32 v88, 27, v84
	v_cmp_gt_u32_e64 s[50:51], s98, v88
	v_nop
	v_cndmask_b32_e64 v44, 0, v44, s[30:31]
	v_cndmask_b32_e64 v45, 0, v45, s[36:37]
	v_cndmask_b32_e64 v46, 0, v46, s[78:79]
	v_cndmask_b32_e64 v47, 0, v47, s[50:51]
	v_cvt_pk_bf16_f32 v64, v32, v33
	v_cvt_pk_bf16_f32 v65, v34, v35
	v_cvt_pk_bf16_f32 v66, v36, v37
	v_cvt_pk_bf16_f32 v67, v38, v39
	v_cvt_pk_bf16_f32 v68, v40, v41
	v_cvt_pk_bf16_f32 v69, v42, v43
	v_cvt_pk_bf16_f32 v70, v44, v45
	v_cvt_pk_bf16_f32 v71, v46, v47
	v_pk_add_f32 v[232:233], v[232:233], v[32:33]
	v_pk_add_f32 v[232:233], v[232:233], v[34:35]
	v_pk_add_f32 v[232:233], v[232:233], v[36:37]
	v_pk_add_f32 v[232:233], v[232:233], v[38:39]
	v_pk_add_f32 v[232:233], v[232:233], v[40:41]
	v_pk_add_f32 v[232:233], v[232:233], v[42:43]
	v_pk_add_f32 v[232:233], v[232:233], v[44:45]
	v_pk_add_f32 v[232:233], v[232:233], v[46:47]
	s_waitcnt lgkmcnt(12)
	v_mfma_f32_32x32x16_bf16 v[0:15], v[64:67], v[72:75], v[0:15]
	v_mfma_f32_32x32x16_bf16 v[16:31], v[64:67], v[76:79], v[16:31]
	v_mfma_f32_32x32x16_bf16 v[0:15], v[68:71], v[220:223], v[0:15]
	v_mfma_f32_32x32x16_bf16 v[16:31], v[68:71], v[224:227], v[16:31]
	s_add_i32 s90, s67, 288
	v_add_u32_e32 v80, s90, v235
	v_add_u32_e32 v83, s90, v236
	v_add_u32_e32 v99, s90, v237
	v_add_u32_e32 v253, s90, v238
	v_add_u32_e32 v254, s90, v100
	v_add_u32_e32 v255, s90, v149
	v_med3_i32 v80, v80, 0, s99
	v_med3_i32 v83, v83, 0, s99
	v_med3_i32 v99, v99, 0, s99
	v_med3_i32 v253, v253, 0, s99
	v_med3_i32 v254, v254, 0, s99
	v_med3_i32 v255, v255, 0, s99
	v_mad_u32_u24 v80, v80, s100, v252
	v_mad_u32_u24 v83, v83, s100, v252
	v_mad_u32_u24 v99, v99, s100, v252
	v_mad_u32_u24 v253, v253, s100, v252
	v_mad_u32_u24 v254, v254, s100, v153
	v_mad_u32_u24 v255, v255, s100, v153
	global_load_dwordx4 v[188:191], v80, s[82:83]
	global_load_dwordx4 v[192:195], v83, s[82:83]
	global_load_dwordx4 v[196:199], v99, s[82:83]
	global_load_dwordx4 v[200:203], v253, s[82:83]
	global_load_dwordx4 v[204:207], v254, s[82:83] offset:768
	global_load_dwordx4 v[208:211], v255, s[82:83] offset:768
	global_load_dwordx4 v[212:215], v254, s[82:83] offset:832
	global_load_dwordx4 v[216:219], v255, s[82:83] offset:832
	ds_read2_b32 v[32:33], v115 offset0:68 offset1:69
	ds_read2_b32 v[34:35], v115 offset0:70 offset1:71
	ds_read2_b32 v[36:37], v115 offset0:76 offset1:77
	ds_read2_b32 v[38:39], v115 offset0:78 offset1:79
	ds_read2_b32 v[40:41], v115 offset0:85 offset1:86
	ds_read2_b32 v[42:43], v115 offset0:87 offset1:88
	ds_read2_b32 v[44:45], v115 offset0:93 offset1:94
	ds_read2_b32 v[46:47], v115 offset0:95 offset1:96
	s_waitcnt lgkmcnt(0)
	v_mfma_f32_32x32x16_bf16 v[32:47], v[116:119], v[48:51], v[32:47]
	ds_read_b64_tr_b16 v[72:73], v231
	ds_read_b64_tr_b16 v[74:75], v231 offset:512
	ds_read_b64_tr_b16 v[76:77], v231 offset:2048
	ds_read_b64_tr_b16 v[78:79], v231 offset:2560
	ds_read_b64_tr_b16 v[220:221], v231 offset:1024
	ds_read_b64_tr_b16 v[222:223], v231 offset:1536
	ds_read_b64_tr_b16 v[224:225], v231 offset:3072
	ds_read_b64_tr_b16 v[226:227], v231 offset:3584
	s_waitcnt vmcnt(8)
	ds_write_b128 v247, v[156:159]
	ds_write_b128 v247, v[160:163] offset:1024
	ds_write_b128 v247, v[164:167] offset:2048
	ds_write_b128 v247, v[168:171] offset:3072
	ds_read_b128 v[156:159], v248
	ds_read_b128 v[160:163], v249
	ds_read_b128 v[164:167], v250
	ds_read_b128 v[168:171], v251
	ds_write_b128 v112, v[172:175]
	ds_write_b128 v112, v[176:179] offset:1024
	ds_write_b128 v112, v[180:183] offset:2048
	ds_write_b128 v112, v[184:187] offset:3072
	v_mfma_f32_32x32x16_bf16 v[32:47], v[120:123], v[52:55], v[32:47]
	v_mfma_f32_32x32x16_bf16 v[32:47], v[124:127], v[56:59], v[32:47]
	v_mfma_f32_32x32x16_bf16 v[32:47], v[128:131], v[60:63], v[32:47]
	s_nop 11
	v_exp_f32_e32 v32, v32
	v_exp_f32_e32 v33, v33
	v_exp_f32_e32 v34, v34
	v_exp_f32_e32 v35, v35
	v_exp_f32_e32 v36, v36
	v_exp_f32_e32 v37, v37
	v_exp_f32_e32 v38, v38
	v_exp_f32_e32 v39, v39
	v_exp_f32_e32 v40, v40
	v_exp_f32_e32 v41, v41
	v_exp_f32_e32 v42, v42
	v_exp_f32_e32 v43, v43
	v_exp_f32_e32 v44, v44
	v_exp_f32_e32 v45, v45
	v_exp_f32_e32 v46, v46
	v_exp_f32_e32 v47, v47
	s_add_i32 s90, s67, 224
	v_add_u32_e32 v84, s90, v107
	v_add_u32_e32 v85, 0, v84
	v_add_u32_e32 v86, 1, v84
	v_add_u32_e32 v87, 2, v84
	v_add_u32_e32 v88, 3, v84
	v_cmp_gt_u32_e64 s[30:31], s98, v85
	v_cmp_gt_u32_e64 s[36:37], s98, v86
	v_cmp_gt_u32_e64 s[78:79], s98, v87
	v_cmp_gt_u32_e64 s[50:51], s98, v88
	v_cndmask_b32_e64 v32, 0, v32, s[30:31]
	v_add_u32_e32 v85, 8, v84
	v_cmp_gt_u32_e64 s[30:31], s98, v85
	v_cndmask_b32_e64 v33, 0, v33, s[36:37]
	v_add_u32_e32 v86, 9, v84
	v_cmp_gt_u32_e64 s[36:37], s98, v86
	v_cndmask_b32_e64 v34, 0, v34, s[78:79]
	v_add_u32_e32 v87, 10, v84
	v_cmp_gt_u32_e64 s[78:79], s98, v87
	v_cndmask_b32_e64 v35, 0, v35, s[50:51]
	v_add_u32_e32 v88, 11, v84
	v_cmp_gt_u32_e64 s[50:51], s98, v88
	v_cndmask_b32_e64 v36, 0, v36, s[30:31]
	v_add_u32_e32 v85, 16, v84
	v_cmp_gt_u32_e64 s[30:31], s98, v85
	v_cndmask_b32_e64 v37, 0, v37, s[36:37]
	v_add_u32_e32 v86, 17, v84
	v_cmp_gt_u32_e64 s[36:37], s98, v86
	v_cndmask_b32_e64 v38, 0, v38, s[78:79]
	v_add_u32_e32 v87, 18, v84
	v_cmp_gt_u32_e64 s[78:79], s98, v87
	v_cndmask_b32_e64 v39, 0, v39, s[50:51]
	v_add_u32_e32 v88, 19, v84
	v_cmp_gt_u32_e64 s[50:51], s98, v88
	v_cndmask_b32_e64 v40, 0, v40, s[30:31]
	v_add_u32_e32 v85, 24, v84
	v_cmp_gt_u32_e64 s[30:31], s98, v85
	v_cndmask_b32_e64 v41, 0, v41, s[36:37]
	v_add_u32_e32 v86, 25, v84
	v_cmp_gt_u32_e64 s[36:37], s98, v86
	v_cndmask_b32_e64 v42, 0, v42, s[78:79]
	v_add_u32_e32 v87, 26, v84
	v_cmp_gt_u32_e64 s[78:79], s98, v87
	v_cndmask_b32_e64 v43, 0, v43, s[50:51]
	v_add_u32_e32 v88, 27, v84
	v_cmp_gt_u32_e64 s[50:51], s98, v88
	v_nop
	v_cndmask_b32_e64 v44, 0, v44, s[30:31]
	v_cndmask_b32_e64 v45, 0, v45, s[36:37]
	v_cndmask_b32_e64 v46, 0, v46, s[78:79]
	v_cndmask_b32_e64 v47, 0, v47, s[50:51]
	v_cvt_pk_bf16_f32 v64, v32, v33
	v_cvt_pk_bf16_f32 v65, v34, v35
	v_cvt_pk_bf16_f32 v66, v36, v37
	v_cvt_pk_bf16_f32 v67, v38, v39
	v_cvt_pk_bf16_f32 v68, v40, v41
	v_cvt_pk_bf16_f32 v69, v42, v43
	v_cvt_pk_bf16_f32 v70, v44, v45
	v_cvt_pk_bf16_f32 v71, v46, v47
	v_pk_add_f32 v[232:233], v[232:233], v[32:33]
	v_pk_add_f32 v[232:233], v[232:233], v[34:35]
	v_pk_add_f32 v[232:233], v[232:233], v[36:37]
	v_pk_add_f32 v[232:233], v[232:233], v[38:39]
	v_pk_add_f32 v[232:233], v[232:233], v[40:41]
	v_pk_add_f32 v[232:233], v[232:233], v[42:43]
	v_pk_add_f32 v[232:233], v[232:233], v[44:45]
	v_pk_add_f32 v[232:233], v[232:233], v[46:47]
	s_waitcnt lgkmcnt(12)
	v_mfma_f32_32x32x16_bf16 v[0:15], v[64:67], v[72:75], v[0:15]
	v_mfma_f32_32x32x16_bf16 v[16:31], v[64:67], v[76:79], v[16:31]
	v_mfma_f32_32x32x16_bf16 v[0:15], v[68:71], v[220:223], v[0:15]
	v_mfma_f32_32x32x16_bf16 v[16:31], v[68:71], v[224:227], v[16:31]
	s_add_i32 s90, s67, 320
	v_add_u32_e32 v80, s90, v235
	v_add_u32_e32 v83, s90, v236
	v_add_u32_e32 v99, s90, v237
	v_add_u32_e32 v253, s90, v238
	v_add_u32_e32 v254, s90, v100
	v_add_u32_e32 v255, s90, v149
	v_med3_i32 v80, v80, 0, s99
	v_med3_i32 v83, v83, 0, s99
	v_med3_i32 v99, v99, 0, s99
	v_med3_i32 v253, v253, 0, s99
	v_med3_i32 v254, v254, 0, s99
	v_med3_i32 v255, v255, 0, s99
	v_mad_u32_u24 v80, v80, s100, v252
	v_mad_u32_u24 v83, v83, s100, v252
	v_mad_u32_u24 v99, v99, s100, v252
	v_mad_u32_u24 v253, v253, s100, v252
	v_mad_u32_u24 v254, v254, s100, v153
	v_mad_u32_u24 v255, v255, s100, v153
	global_load_dwordx4 v[116:119], v80, s[82:83]
	global_load_dwordx4 v[120:123], v83, s[82:83]
	global_load_dwordx4 v[124:127], v99, s[82:83]
	global_load_dwordx4 v[128:131], v253, s[82:83]
	global_load_dwordx4 v[132:135], v254, s[82:83] offset:768
	global_load_dwordx4 v[136:139], v255, s[82:83] offset:768
	global_load_dwordx4 v[140:143], v254, s[82:83] offset:832
	global_load_dwordx4 v[144:147], v255, s[82:83] offset:832
	ds_read2_b32 v[32:33], v115 offset0:102 offset1:103
	ds_read2_b32 v[34:35], v115 offset0:104 offset1:105
	ds_read2_b32 v[36:37], v115 offset0:110 offset1:111
	ds_read2_b32 v[38:39], v115 offset0:112 offset1:113
	ds_read2_b32 v[40:41], v115 offset0:119 offset1:120
	ds_read2_b32 v[42:43], v115 offset0:121 offset1:122
	ds_read2_b32 v[44:45], v115 offset0:127 offset1:128
	ds_read2_b32 v[46:47], v115 offset0:129 offset1:130
	s_waitcnt lgkmcnt(0)
	v_mfma_f32_32x32x16_bf16 v[32:47], v[156:159], v[48:51], v[32:47]
	ds_read_b64_tr_b16 v[72:73], v231
	ds_read_b64_tr_b16 v[74:75], v231 offset:512
	ds_read_b64_tr_b16 v[76:77], v231 offset:2048
	ds_read_b64_tr_b16 v[78:79], v231 offset:2560
	ds_read_b64_tr_b16 v[220:221], v231 offset:1024
	ds_read_b64_tr_b16 v[222:223], v231 offset:1536
	ds_read_b64_tr_b16 v[224:225], v231 offset:3072
	ds_read_b64_tr_b16 v[226:227], v231 offset:3584
	s_waitcnt vmcnt(8)
	ds_write_b128 v247, v[188:191]
	ds_write_b128 v247, v[192:195] offset:1024
	ds_write_b128 v247, v[196:199] offset:2048
	ds_write_b128 v247, v[200:203] offset:3072
	ds_read_b128 v[188:191], v248
	ds_read_b128 v[192:195], v249
	ds_read_b128 v[196:199], v250
	ds_read_b128 v[200:203], v251
	ds_write_b128 v112, v[204:207]
	ds_write_b128 v112, v[208:211] offset:1024
	ds_write_b128 v112, v[212:215] offset:2048
	ds_write_b128 v112, v[216:219] offset:3072
	v_mfma_f32_32x32x16_bf16 v[32:47], v[160:163], v[52:55], v[32:47]
	v_mfma_f32_32x32x16_bf16 v[32:47], v[164:167], v[56:59], v[32:47]
	v_mfma_f32_32x32x16_bf16 v[32:47], v[168:171], v[60:63], v[32:47]
	s_nop 11
	v_exp_f32_e32 v32, v32
	v_exp_f32_e32 v33, v33
	v_exp_f32_e32 v34, v34
	v_exp_f32_e32 v35, v35
	v_exp_f32_e32 v36, v36
	v_exp_f32_e32 v37, v37
	v_exp_f32_e32 v38, v38
	v_exp_f32_e32 v39, v39
	v_exp_f32_e32 v40, v40
	v_exp_f32_e32 v41, v41
	v_exp_f32_e32 v42, v42
	v_exp_f32_e32 v43, v43
	v_exp_f32_e32 v44, v44
	v_exp_f32_e32 v45, v45
	v_exp_f32_e32 v46, v46
	v_exp_f32_e32 v47, v47
	s_add_i32 s90, s67, 256
	v_add_u32_e32 v84, s90, v107
	v_add_u32_e32 v85, 0, v84
	v_add_u32_e32 v86, 1, v84
	v_add_u32_e32 v87, 2, v84
	v_add_u32_e32 v88, 3, v84
	v_cmp_gt_u32_e64 s[30:31], s98, v85
	v_cmp_gt_u32_e64 s[36:37], s98, v86
	v_cmp_gt_u32_e64 s[78:79], s98, v87
	v_cmp_gt_u32_e64 s[50:51], s98, v88
	v_cndmask_b32_e64 v32, 0, v32, s[30:31]
	v_add_u32_e32 v85, 8, v84
	v_cmp_gt_u32_e64 s[30:31], s98, v85
	v_cndmask_b32_e64 v33, 0, v33, s[36:37]
	v_add_u32_e32 v86, 9, v84
	v_cmp_gt_u32_e64 s[36:37], s98, v86
	v_cndmask_b32_e64 v34, 0, v34, s[78:79]
	v_add_u32_e32 v87, 10, v84
	v_cmp_gt_u32_e64 s[78:79], s98, v87
	v_cndmask_b32_e64 v35, 0, v35, s[50:51]
	v_add_u32_e32 v88, 11, v84
	v_cmp_gt_u32_e64 s[50:51], s98, v88
	v_cndmask_b32_e64 v36, 0, v36, s[30:31]
	v_add_u32_e32 v85, 16, v84
	v_cmp_gt_u32_e64 s[30:31], s98, v85
	v_cndmask_b32_e64 v37, 0, v37, s[36:37]
	v_add_u32_e32 v86, 17, v84
	v_cmp_gt_u32_e64 s[36:37], s98, v86
	v_cndmask_b32_e64 v38, 0, v38, s[78:79]
	v_add_u32_e32 v87, 18, v84
	v_cmp_gt_u32_e64 s[78:79], s98, v87
	v_cndmask_b32_e64 v39, 0, v39, s[50:51]
	v_add_u32_e32 v88, 19, v84
	v_cmp_gt_u32_e64 s[50:51], s98, v88
	v_cndmask_b32_e64 v40, 0, v40, s[30:31]
	v_add_u32_e32 v85, 24, v84
	v_cmp_gt_u32_e64 s[30:31], s98, v85
	v_cndmask_b32_e64 v41, 0, v41, s[36:37]
	v_add_u32_e32 v86, 25, v84
	v_cmp_gt_u32_e64 s[36:37], s98, v86
	v_cndmask_b32_e64 v42, 0, v42, s[78:79]
	v_add_u32_e32 v87, 26, v84
	v_cmp_gt_u32_e64 s[78:79], s98, v87
	v_cndmask_b32_e64 v43, 0, v43, s[50:51]
	v_add_u32_e32 v88, 27, v84
	v_cmp_gt_u32_e64 s[50:51], s98, v88
	v_nop
	v_cndmask_b32_e64 v44, 0, v44, s[30:31]
	v_cndmask_b32_e64 v45, 0, v45, s[36:37]
	v_cndmask_b32_e64 v46, 0, v46, s[78:79]
	v_cndmask_b32_e64 v47, 0, v47, s[50:51]
	v_cvt_pk_bf16_f32 v64, v32, v33
	v_cvt_pk_bf16_f32 v65, v34, v35
	v_cvt_pk_bf16_f32 v66, v36, v37
	v_cvt_pk_bf16_f32 v67, v38, v39
	v_cvt_pk_bf16_f32 v68, v40, v41
	v_cvt_pk_bf16_f32 v69, v42, v43
	v_cvt_pk_bf16_f32 v70, v44, v45
	v_cvt_pk_bf16_f32 v71, v46, v47
	v_pk_add_f32 v[232:233], v[232:233], v[32:33]
	v_pk_add_f32 v[232:233], v[232:233], v[34:35]
	v_pk_add_f32 v[232:233], v[232:233], v[36:37]
	v_pk_add_f32 v[232:233], v[232:233], v[38:39]
	v_pk_add_f32 v[232:233], v[232:233], v[40:41]
	v_pk_add_f32 v[232:233], v[232:233], v[42:43]
	v_pk_add_f32 v[232:233], v[232:233], v[44:45]
	v_pk_add_f32 v[232:233], v[232:233], v[46:47]
	s_waitcnt lgkmcnt(12)
	v_mfma_f32_32x32x16_bf16 v[0:15], v[64:67], v[72:75], v[0:15]
	v_mfma_f32_32x32x16_bf16 v[16:31], v[64:67], v[76:79], v[16:31]
	v_mfma_f32_32x32x16_bf16 v[0:15], v[68:71], v[220:223], v[0:15]
	v_mfma_f32_32x32x16_bf16 v[16:31], v[68:71], v[224:227], v[16:31]
	s_add_i32 s90, s67, 352
	v_add_u32_e32 v80, s90, v235
	v_add_u32_e32 v83, s90, v236
	v_add_u32_e32 v99, s90, v237
	v_add_u32_e32 v253, s90, v238
	v_add_u32_e32 v254, s90, v100
	v_add_u32_e32 v255, s90, v149
	v_med3_i32 v80, v80, 0, s99
	v_med3_i32 v83, v83, 0, s99
	v_med3_i32 v99, v99, 0, s99
	v_med3_i32 v253, v253, 0, s99
	v_med3_i32 v254, v254, 0, s99
	v_med3_i32 v255, v255, 0, s99
	v_mad_u32_u24 v80, v80, s100, v252
	v_mad_u32_u24 v83, v83, s100, v252
	v_mad_u32_u24 v99, v99, s100, v252
	v_mad_u32_u24 v253, v253, s100, v252
	v_mad_u32_u24 v254, v254, s100, v153
	v_mad_u32_u24 v255, v255, s100, v153
	global_load_dwordx4 v[156:159], v80, s[82:83]
	global_load_dwordx4 v[160:163], v83, s[82:83]
	global_load_dwordx4 v[164:167], v99, s[82:83]
	global_load_dwordx4 v[168:171], v253, s[82:83]
	global_load_dwordx4 v[172:175], v254, s[82:83] offset:768
	global_load_dwordx4 v[176:179], v255, s[82:83] offset:768
	global_load_dwordx4 v[180:183], v254, s[82:83] offset:832
	global_load_dwordx4 v[184:187], v255, s[82:83] offset:832
	ds_read2_b32 v[32:33], v115 offset0:136 offset1:137
	ds_read2_b32 v[34:35], v115 offset0:138 offset1:139
	ds_read2_b32 v[36:37], v115 offset0:144 offset1:145
	ds_read2_b32 v[38:39], v115 offset0:146 offset1:147
	ds_read2_b32 v[40:41], v115 offset0:153 offset1:154
	ds_read2_b32 v[42:43], v115 offset0:155 offset1:156
	ds_read2_b32 v[44:45], v115 offset0:161 offset1:162
	ds_read2_b32 v[46:47], v115 offset0:163 offset1:164
	s_waitcnt lgkmcnt(0)
	v_mfma_f32_32x32x16_bf16 v[32:47], v[188:191], v[48:51], v[32:47]
	ds_read_b64_tr_b16 v[72:73], v231
	ds_read_b64_tr_b16 v[74:75], v231 offset:512
	ds_read_b64_tr_b16 v[76:77], v231 offset:2048
	ds_read_b64_tr_b16 v[78:79], v231 offset:2560
	ds_read_b64_tr_b16 v[220:221], v231 offset:1024
	ds_read_b64_tr_b16 v[222:223], v231 offset:1536
	ds_read_b64_tr_b16 v[224:225], v231 offset:3072
	ds_read_b64_tr_b16 v[226:227], v231 offset:3584
	s_waitcnt vmcnt(8)
	ds_write_b128 v247, v[116:119]
	ds_write_b128 v247, v[120:123] offset:1024
	ds_write_b128 v247, v[124:127] offset:2048
	ds_write_b128 v247, v[128:131] offset:3072
	ds_read_b128 v[116:119], v248
	ds_read_b128 v[120:123], v249
	ds_read_b128 v[124:127], v250
	ds_read_b128 v[128:131], v251
	ds_write_b128 v112, v[132:135]
	ds_write_b128 v112, v[136:139] offset:1024
	ds_write_b128 v112, v[140:143] offset:2048
	ds_write_b128 v112, v[144:147] offset:3072
	v_mfma_f32_32x32x16_bf16 v[32:47], v[192:195], v[52:55], v[32:47]
	v_mfma_f32_32x32x16_bf16 v[32:47], v[196:199], v[56:59], v[32:47]
	v_mfma_f32_32x32x16_bf16 v[32:47], v[200:203], v[60:63], v[32:47]
	s_nop 11
	v_exp_f32_e32 v32, v32
	v_exp_f32_e32 v33, v33
	v_exp_f32_e32 v34, v34
	v_exp_f32_e32 v35, v35
	v_exp_f32_e32 v36, v36
	v_exp_f32_e32 v37, v37
	v_exp_f32_e32 v38, v38
	v_exp_f32_e32 v39, v39
	v_exp_f32_e32 v40, v40
	v_exp_f32_e32 v41, v41
	v_exp_f32_e32 v42, v42
	v_exp_f32_e32 v43, v43
	v_exp_f32_e32 v44, v44
	v_exp_f32_e32 v45, v45
	v_exp_f32_e32 v46, v46
	v_exp_f32_e32 v47, v47
	s_add_i32 s90, s67, 288
	v_add_u32_e32 v84, s90, v107
	v_add_u32_e32 v85, 0, v84
	v_add_u32_e32 v86, 1, v84
	v_add_u32_e32 v87, 2, v84
	v_add_u32_e32 v88, 3, v84
	v_cmp_gt_u32_e64 s[30:31], s98, v85
	v_cmp_gt_u32_e64 s[36:37], s98, v86
	v_cmp_gt_u32_e64 s[78:79], s98, v87
	v_cmp_gt_u32_e64 s[50:51], s98, v88
	v_cndmask_b32_e64 v32, 0, v32, s[30:31]
	v_add_u32_e32 v85, 8, v84
	v_cmp_gt_u32_e64 s[30:31], s98, v85
	v_cndmask_b32_e64 v33, 0, v33, s[36:37]
	v_add_u32_e32 v86, 9, v84
	v_cmp_gt_u32_e64 s[36:37], s98, v86
	v_cndmask_b32_e64 v34, 0, v34, s[78:79]
	v_add_u32_e32 v87, 10, v84
	v_cmp_gt_u32_e64 s[78:79], s98, v87
	v_cndmask_b32_e64 v35, 0, v35, s[50:51]
	v_add_u32_e32 v88, 11, v84
	v_cmp_gt_u32_e64 s[50:51], s98, v88
	v_cndmask_b32_e64 v36, 0, v36, s[30:31]
	v_add_u32_e32 v85, 16, v84
	v_cmp_gt_u32_e64 s[30:31], s98, v85
	v_cndmask_b32_e64 v37, 0, v37, s[36:37]
	v_add_u32_e32 v86, 17, v84
	v_cmp_gt_u32_e64 s[36:37], s98, v86
	v_cndmask_b32_e64 v38, 0, v38, s[78:79]
	v_add_u32_e32 v87, 18, v84
	v_cmp_gt_u32_e64 s[78:79], s98, v87
	v_cndmask_b32_e64 v39, 0, v39, s[50:51]
	v_add_u32_e32 v88, 19, v84
	v_cmp_gt_u32_e64 s[50:51], s98, v88
	v_cndmask_b32_e64 v40, 0, v40, s[30:31]
	v_add_u32_e32 v85, 24, v84
	v_cmp_gt_u32_e64 s[30:31], s98, v85
	v_cndmask_b32_e64 v41, 0, v41, s[36:37]
	v_add_u32_e32 v86, 25, v84
	v_cmp_gt_u32_e64 s[36:37], s98, v86
	v_cndmask_b32_e64 v42, 0, v42, s[78:79]
	v_add_u32_e32 v87, 26, v84
	v_cmp_gt_u32_e64 s[78:79], s98, v87
	v_cndmask_b32_e64 v43, 0, v43, s[50:51]
	v_add_u32_e32 v88, 27, v84
	v_cmp_gt_u32_e64 s[50:51], s98, v88
	v_nop
	v_cndmask_b32_e64 v44, 0, v44, s[30:31]
	v_cndmask_b32_e64 v45, 0, v45, s[36:37]
	v_cndmask_b32_e64 v46, 0, v46, s[78:79]
	v_cndmask_b32_e64 v47, 0, v47, s[50:51]
	v_cvt_pk_bf16_f32 v64, v32, v33
	v_cvt_pk_bf16_f32 v65, v34, v35
	v_cvt_pk_bf16_f32 v66, v36, v37
	v_cvt_pk_bf16_f32 v67, v38, v39
	v_cvt_pk_bf16_f32 v68, v40, v41
	v_cvt_pk_bf16_f32 v69, v42, v43
	v_cvt_pk_bf16_f32 v70, v44, v45
	v_cvt_pk_bf16_f32 v71, v46, v47
	v_pk_add_f32 v[232:233], v[232:233], v[32:33]
	v_pk_add_f32 v[232:233], v[232:233], v[34:35]
	v_pk_add_f32 v[232:233], v[232:233], v[36:37]
	v_pk_add_f32 v[232:233], v[232:233], v[38:39]
	v_pk_add_f32 v[232:233], v[232:233], v[40:41]
	v_pk_add_f32 v[232:233], v[232:233], v[42:43]
	v_pk_add_f32 v[232:233], v[232:233], v[44:45]
	v_pk_add_f32 v[232:233], v[232:233], v[46:47]
	s_waitcnt lgkmcnt(12)
	v_mfma_f32_32x32x16_bf16 v[0:15], v[64:67], v[72:75], v[0:15]
	v_mfma_f32_32x32x16_bf16 v[16:31], v[64:67], v[76:79], v[16:31]
	v_mfma_f32_32x32x16_bf16 v[0:15], v[68:71], v[220:223], v[0:15]
	v_mfma_f32_32x32x16_bf16 v[16:31], v[68:71], v[224:227], v[16:31]
	s_add_i32 s90, s67, 384
	v_add_u32_e32 v80, s90, v235
	v_add_u32_e32 v83, s90, v236
	v_add_u32_e32 v99, s90, v237
	v_add_u32_e32 v253, s90, v238
	v_add_u32_e32 v254, s90, v100
	v_add_u32_e32 v255, s90, v149
	v_med3_i32 v80, v80, 0, s99
	v_med3_i32 v83, v83, 0, s99
	v_med3_i32 v99, v99, 0, s99
	v_med3_i32 v253, v253, 0, s99
	v_med3_i32 v254, v254, 0, s99
	v_med3_i32 v255, v255, 0, s99
	v_mad_u32_u24 v80, v80, s100, v252
	v_mad_u32_u24 v83, v83, s100, v252
	v_mad_u32_u24 v99, v99, s100, v252
	v_mad_u32_u24 v253, v253, s100, v252
	v_mad_u32_u24 v254, v254, s100, v153
	v_mad_u32_u24 v255, v255, s100, v153
	global_load_dwordx4 v[188:191], v80, s[82:83]
	global_load_dwordx4 v[192:195], v83, s[82:83]
	global_load_dwordx4 v[196:199], v99, s[82:83]
	global_load_dwordx4 v[200:203], v253, s[82:83]
	global_load_dwordx4 v[204:207], v254, s[82:83] offset:768
	global_load_dwordx4 v[208:211], v255, s[82:83] offset:768
	global_load_dwordx4 v[212:215], v254, s[82:83] offset:832
	global_load_dwordx4 v[216:219], v255, s[82:83] offset:832
	ds_read2_b32 v[32:33], v115 offset0:170 offset1:171
	ds_read2_b32 v[34:35], v115 offset0:172 offset1:173
	ds_read2_b32 v[36:37], v115 offset0:178 offset1:179
	ds_read2_b32 v[38:39], v115 offset0:180 offset1:181
	ds_read2_b32 v[40:41], v115 offset0:187 offset1:188
	ds_read2_b32 v[42:43], v115 offset0:189 offset1:190
	ds_read2_b32 v[44:45], v115 offset0:195 offset1:196
	ds_read2_b32 v[46:47], v115 offset0:197 offset1:198
	s_waitcnt lgkmcnt(0)
	v_mfma_f32_32x32x16_bf16 v[32:47], v[116:119], v[48:51], v[32:47]
	ds_read_b64_tr_b16 v[72:73], v231
	ds_read_b64_tr_b16 v[74:75], v231 offset:512
	ds_read_b64_tr_b16 v[76:77], v231 offset:2048
	ds_read_b64_tr_b16 v[78:79], v231 offset:2560
	ds_read_b64_tr_b16 v[220:221], v231 offset:1024
	ds_read_b64_tr_b16 v[222:223], v231 offset:1536
	ds_read_b64_tr_b16 v[224:225], v231 offset:3072
	ds_read_b64_tr_b16 v[226:227], v231 offset:3584
	s_waitcnt vmcnt(8)
	ds_write_b128 v247, v[156:159]
	ds_write_b128 v247, v[160:163] offset:1024
	ds_write_b128 v247, v[164:167] offset:2048
	ds_write_b128 v247, v[168:171] offset:3072
	ds_read_b128 v[156:159], v248
	ds_read_b128 v[160:163], v249
	ds_read_b128 v[164:167], v250
	ds_read_b128 v[168:171], v251
	ds_write_b128 v112, v[172:175]
	ds_write_b128 v112, v[176:179] offset:1024
	ds_write_b128 v112, v[180:183] offset:2048
	ds_write_b128 v112, v[184:187] offset:3072
	v_mfma_f32_32x32x16_bf16 v[32:47], v[120:123], v[52:55], v[32:47]
	v_mfma_f32_32x32x16_bf16 v[32:47], v[124:127], v[56:59], v[32:47]
	v_mfma_f32_32x32x16_bf16 v[32:47], v[128:131], v[60:63], v[32:47]
	s_nop 11
	v_exp_f32_e32 v32, v32
	v_exp_f32_e32 v33, v33
	v_exp_f32_e32 v34, v34
	v_exp_f32_e32 v35, v35
	v_exp_f32_e32 v36, v36
	v_exp_f32_e32 v37, v37
	v_exp_f32_e32 v38, v38
	v_exp_f32_e32 v39, v39
	v_exp_f32_e32 v40, v40
	v_exp_f32_e32 v41, v41
	v_exp_f32_e32 v42, v42
	v_exp_f32_e32 v43, v43
	v_exp_f32_e32 v44, v44
	v_exp_f32_e32 v45, v45
	v_exp_f32_e32 v46, v46
	v_exp_f32_e32 v47, v47
	s_add_i32 s90, s67, 320
	v_add_u32_e32 v84, s90, v107
	v_add_u32_e32 v85, 0, v84
	v_add_u32_e32 v86, 1, v84
	v_add_u32_e32 v87, 2, v84
	v_add_u32_e32 v88, 3, v84
	v_cmp_gt_u32_e64 s[30:31], s98, v85
	v_cmp_gt_u32_e64 s[36:37], s98, v86
	v_cmp_gt_u32_e64 s[78:79], s98, v87
	v_cmp_gt_u32_e64 s[50:51], s98, v88
	v_cndmask_b32_e64 v32, 0, v32, s[30:31]
	v_add_u32_e32 v85, 8, v84
	v_cmp_gt_u32_e64 s[30:31], s98, v85
	v_cndmask_b32_e64 v33, 0, v33, s[36:37]
	v_add_u32_e32 v86, 9, v84
	v_cmp_gt_u32_e64 s[36:37], s98, v86
	v_cndmask_b32_e64 v34, 0, v34, s[78:79]
	v_add_u32_e32 v87, 10, v84
	v_cmp_gt_u32_e64 s[78:79], s98, v87
	v_cndmask_b32_e64 v35, 0, v35, s[50:51]
	v_add_u32_e32 v88, 11, v84
	v_cmp_gt_u32_e64 s[50:51], s98, v88
	v_cndmask_b32_e64 v36, 0, v36, s[30:31]
	v_add_u32_e32 v85, 16, v84
	v_cmp_gt_u32_e64 s[30:31], s98, v85
	v_cndmask_b32_e64 v37, 0, v37, s[36:37]
	v_add_u32_e32 v86, 17, v84
	v_cmp_gt_u32_e64 s[36:37], s98, v86
	v_cndmask_b32_e64 v38, 0, v38, s[78:79]
	v_add_u32_e32 v87, 18, v84
	v_cmp_gt_u32_e64 s[78:79], s98, v87
	v_cndmask_b32_e64 v39, 0, v39, s[50:51]
	v_add_u32_e32 v88, 19, v84
	v_cmp_gt_u32_e64 s[50:51], s98, v88
	v_cndmask_b32_e64 v40, 0, v40, s[30:31]
	v_add_u32_e32 v85, 24, v84
	v_cmp_gt_u32_e64 s[30:31], s98, v85
	v_cndmask_b32_e64 v41, 0, v41, s[36:37]
	v_add_u32_e32 v86, 25, v84
	v_cmp_gt_u32_e64 s[36:37], s98, v86
	v_cndmask_b32_e64 v42, 0, v42, s[78:79]
	v_add_u32_e32 v87, 26, v84
	v_cmp_gt_u32_e64 s[78:79], s98, v87
	v_cndmask_b32_e64 v43, 0, v43, s[50:51]
	v_add_u32_e32 v88, 27, v84
	v_cmp_gt_u32_e64 s[50:51], s98, v88
	v_nop
	v_cndmask_b32_e64 v44, 0, v44, s[30:31]
	v_cndmask_b32_e64 v45, 0, v45, s[36:37]
	v_cndmask_b32_e64 v46, 0, v46, s[78:79]
	v_cndmask_b32_e64 v47, 0, v47, s[50:51]
	v_cvt_pk_bf16_f32 v64, v32, v33
	v_cvt_pk_bf16_f32 v65, v34, v35
	v_cvt_pk_bf16_f32 v66, v36, v37
	v_cvt_pk_bf16_f32 v67, v38, v39
	v_cvt_pk_bf16_f32 v68, v40, v41
	v_cvt_pk_bf16_f32 v69, v42, v43
	v_cvt_pk_bf16_f32 v70, v44, v45
	v_cvt_pk_bf16_f32 v71, v46, v47
	v_pk_add_f32 v[232:233], v[232:233], v[32:33]
	v_pk_add_f32 v[232:233], v[232:233], v[34:35]
	v_pk_add_f32 v[232:233], v[232:233], v[36:37]
	v_pk_add_f32 v[232:233], v[232:233], v[38:39]
	v_pk_add_f32 v[232:233], v[232:233], v[40:41]
	v_pk_add_f32 v[232:233], v[232:233], v[42:43]
	v_pk_add_f32 v[232:233], v[232:233], v[44:45]
	v_pk_add_f32 v[232:233], v[232:233], v[46:47]
	s_waitcnt lgkmcnt(12)
	v_mfma_f32_32x32x16_bf16 v[0:15], v[64:67], v[72:75], v[0:15]
	v_mfma_f32_32x32x16_bf16 v[16:31], v[64:67], v[76:79], v[16:31]
	v_mfma_f32_32x32x16_bf16 v[0:15], v[68:71], v[220:223], v[0:15]
	v_mfma_f32_32x32x16_bf16 v[16:31], v[68:71], v[224:227], v[16:31]
	s_add_i32 s90, s67, 416
	v_add_u32_e32 v80, s90, v235
	v_add_u32_e32 v83, s90, v236
	v_add_u32_e32 v99, s90, v237
	v_add_u32_e32 v253, s90, v238
	v_add_u32_e32 v254, s90, v100
	v_add_u32_e32 v255, s90, v149
	v_med3_i32 v80, v80, 0, s99
	v_med3_i32 v83, v83, 0, s99
	v_med3_i32 v99, v99, 0, s99
	v_med3_i32 v253, v253, 0, s99
	v_med3_i32 v254, v254, 0, s99
	v_med3_i32 v255, v255, 0, s99
	v_mad_u32_u24 v80, v80, s100, v252
	v_mad_u32_u24 v83, v83, s100, v252
	v_mad_u32_u24 v99, v99, s100, v252
	v_mad_u32_u24 v253, v253, s100, v252
	v_mad_u32_u24 v254, v254, s100, v153
	v_mad_u32_u24 v255, v255, s100, v153
	global_load_dwordx4 v[116:119], v80, s[82:83]
	global_load_dwordx4 v[120:123], v83, s[82:83]
	global_load_dwordx4 v[124:127], v99, s[82:83]
	global_load_dwordx4 v[128:131], v253, s[82:83]
	global_load_dwordx4 v[132:135], v254, s[82:83] offset:768
	global_load_dwordx4 v[136:139], v255, s[82:83] offset:768
	global_load_dwordx4 v[140:143], v254, s[82:83] offset:832
	global_load_dwordx4 v[144:147], v255, s[82:83] offset:832
	ds_read2_b32 v[32:33], v115 offset0:204 offset1:205
	ds_read2_b32 v[34:35], v115 offset0:206 offset1:207
	ds_read2_b32 v[36:37], v115 offset0:212 offset1:213
	ds_read2_b32 v[38:39], v115 offset0:214 offset1:215
	ds_read2_b32 v[40:41], v115 offset0:221 offset1:222
	ds_read2_b32 v[42:43], v115 offset0:223 offset1:224
	ds_read2_b32 v[44:45], v115 offset0:229 offset1:230
	ds_read2_b32 v[46:47], v115 offset0:231 offset1:232
	s_waitcnt lgkmcnt(0)
	v_mfma_f32_32x32x16_bf16 v[32:47], v[156:159], v[48:51], v[32:47]
	ds_read_b64_tr_b16 v[72:73], v231
	ds_read_b64_tr_b16 v[74:75], v231 offset:512
	ds_read_b64_tr_b16 v[76:77], v231 offset:2048
	ds_read_b64_tr_b16 v[78:79], v231 offset:2560
	ds_read_b64_tr_b16 v[220:221], v231 offset:1024
	ds_read_b64_tr_b16 v[222:223], v231 offset:1536
	ds_read_b64_tr_b16 v[224:225], v231 offset:3072
	ds_read_b64_tr_b16 v[226:227], v231 offset:3584
	s_waitcnt vmcnt(8)
	ds_write_b128 v247, v[188:191]
	ds_write_b128 v247, v[192:195] offset:1024
	ds_write_b128 v247, v[196:199] offset:2048
	ds_write_b128 v247, v[200:203] offset:3072
	ds_read_b128 v[188:191], v248
	ds_read_b128 v[192:195], v249
	ds_read_b128 v[196:199], v250
	ds_read_b128 v[200:203], v251
	ds_write_b128 v112, v[204:207]
	ds_write_b128 v112, v[208:211] offset:1024
	ds_write_b128 v112, v[212:215] offset:2048
	ds_write_b128 v112, v[216:219] offset:3072
	v_mfma_f32_32x32x16_bf16 v[32:47], v[160:163], v[52:55], v[32:47]
	v_mfma_f32_32x32x16_bf16 v[32:47], v[164:167], v[56:59], v[32:47]
	v_mfma_f32_32x32x16_bf16 v[32:47], v[168:171], v[60:63], v[32:47]
	s_nop 11
	v_exp_f32_e32 v32, v32
	v_exp_f32_e32 v33, v33
	v_exp_f32_e32 v34, v34
	v_exp_f32_e32 v35, v35
	v_exp_f32_e32 v36, v36
	v_exp_f32_e32 v37, v37
	v_exp_f32_e32 v38, v38
	v_exp_f32_e32 v39, v39
	v_exp_f32_e32 v40, v40
	v_exp_f32_e32 v41, v41
	v_exp_f32_e32 v42, v42
	v_exp_f32_e32 v43, v43
	v_exp_f32_e32 v44, v44
	v_exp_f32_e32 v45, v45
	v_exp_f32_e32 v46, v46
	v_exp_f32_e32 v47, v47
	s_add_i32 s90, s67, 352
	v_add_u32_e32 v84, s90, v107
	v_add_u32_e32 v85, 0, v84
	v_add_u32_e32 v86, 1, v84
	v_add_u32_e32 v87, 2, v84
	v_add_u32_e32 v88, 3, v84
	v_cmp_gt_u32_e64 s[30:31], s98, v85
	v_cmp_gt_u32_e64 s[36:37], s98, v86
	v_cmp_gt_u32_e64 s[78:79], s98, v87
	v_cmp_gt_u32_e64 s[50:51], s98, v88
	v_cndmask_b32_e64 v32, 0, v32, s[30:31]
	v_add_u32_e32 v85, 8, v84
	v_cmp_gt_u32_e64 s[30:31], s98, v85
	v_cndmask_b32_e64 v33, 0, v33, s[36:37]
	v_add_u32_e32 v86, 9, v84
	v_cmp_gt_u32_e64 s[36:37], s98, v86
	v_cndmask_b32_e64 v34, 0, v34, s[78:79]
	v_add_u32_e32 v87, 10, v84
	v_cmp_gt_u32_e64 s[78:79], s98, v87
	v_cndmask_b32_e64 v35, 0, v35, s[50:51]
	v_add_u32_e32 v88, 11, v84
	v_cmp_gt_u32_e64 s[50:51], s98, v88
	v_cndmask_b32_e64 v36, 0, v36, s[30:31]
	v_add_u32_e32 v85, 16, v84
	v_cmp_gt_u32_e64 s[30:31], s98, v85
	v_cndmask_b32_e64 v37, 0, v37, s[36:37]
	v_add_u32_e32 v86, 17, v84
	v_cmp_gt_u32_e64 s[36:37], s98, v86
	v_cndmask_b32_e64 v38, 0, v38, s[78:79]
	v_add_u32_e32 v87, 18, v84
	v_cmp_gt_u32_e64 s[78:79], s98, v87
	v_cndmask_b32_e64 v39, 0, v39, s[50:51]
	v_add_u32_e32 v88, 19, v84
	v_cmp_gt_u32_e64 s[50:51], s98, v88
	v_cndmask_b32_e64 v40, 0, v40, s[30:31]
	v_add_u32_e32 v85, 24, v84
	v_cmp_gt_u32_e64 s[30:31], s98, v85
	v_cndmask_b32_e64 v41, 0, v41, s[36:37]
	v_add_u32_e32 v86, 25, v84
	v_cmp_gt_u32_e64 s[36:37], s98, v86
	v_cndmask_b32_e64 v42, 0, v42, s[78:79]
	v_add_u32_e32 v87, 26, v84
	v_cmp_gt_u32_e64 s[78:79], s98, v87
	v_cndmask_b32_e64 v43, 0, v43, s[50:51]
	v_add_u32_e32 v88, 27, v84
	v_cmp_gt_u32_e64 s[50:51], s98, v88
	v_nop
	v_cndmask_b32_e64 v44, 0, v44, s[30:31]
	v_cndmask_b32_e64 v45, 0, v45, s[36:37]
	v_cndmask_b32_e64 v46, 0, v46, s[78:79]
	v_cndmask_b32_e64 v47, 0, v47, s[50:51]
	v_cvt_pk_bf16_f32 v64, v32, v33
	v_cvt_pk_bf16_f32 v65, v34, v35
	v_cvt_pk_bf16_f32 v66, v36, v37
	v_cvt_pk_bf16_f32 v67, v38, v39
	v_cvt_pk_bf16_f32 v68, v40, v41
	v_cvt_pk_bf16_f32 v69, v42, v43
	v_cvt_pk_bf16_f32 v70, v44, v45
	v_cvt_pk_bf16_f32 v71, v46, v47
	v_pk_add_f32 v[232:233], v[232:233], v[32:33]
	v_pk_add_f32 v[232:233], v[232:233], v[34:35]
	v_pk_add_f32 v[232:233], v[232:233], v[36:37]
	v_pk_add_f32 v[232:233], v[232:233], v[38:39]
	v_pk_add_f32 v[232:233], v[232:233], v[40:41]
	v_pk_add_f32 v[232:233], v[232:233], v[42:43]
	v_pk_add_f32 v[232:233], v[232:233], v[44:45]
	v_pk_add_f32 v[232:233], v[232:233], v[46:47]
	s_waitcnt lgkmcnt(12)
	v_mfma_f32_32x32x16_bf16 v[0:15], v[64:67], v[72:75], v[0:15]
	v_mfma_f32_32x32x16_bf16 v[16:31], v[64:67], v[76:79], v[16:31]
	v_mfma_f32_32x32x16_bf16 v[0:15], v[68:71], v[220:223], v[0:15]
	v_mfma_f32_32x32x16_bf16 v[16:31], v[68:71], v[224:227], v[16:31]
	s_add_i32 s90, s67, 448
	v_add_u32_e32 v80, s90, v235
	v_add_u32_e32 v83, s90, v236
	v_add_u32_e32 v99, s90, v237
	v_add_u32_e32 v253, s90, v238
	v_add_u32_e32 v254, s90, v100
	v_add_u32_e32 v255, s90, v149
	v_med3_i32 v80, v80, 0, s99
	v_med3_i32 v83, v83, 0, s99
	v_med3_i32 v99, v99, 0, s99
	v_med3_i32 v253, v253, 0, s99
	v_med3_i32 v254, v254, 0, s99
	v_med3_i32 v255, v255, 0, s99
	v_mad_u32_u24 v80, v80, s100, v252
	v_mad_u32_u24 v83, v83, s100, v252
	v_mad_u32_u24 v99, v99, s100, v252
	v_mad_u32_u24 v253, v253, s100, v252
	v_mad_u32_u24 v254, v254, s100, v153
	v_mad_u32_u24 v255, v255, s100, v153
	global_load_dwordx4 v[156:159], v80, s[82:83]
	global_load_dwordx4 v[160:163], v83, s[82:83]
	global_load_dwordx4 v[164:167], v99, s[82:83]
	global_load_dwordx4 v[168:171], v253, s[82:83]
	global_load_dwordx4 v[172:175], v254, s[82:83] offset:768
	global_load_dwordx4 v[176:179], v255, s[82:83] offset:768
	global_load_dwordx4 v[180:183], v254, s[82:83] offset:832
	global_load_dwordx4 v[184:187], v255, s[82:83] offset:832
	v_add_u32_e32 v115, 952, v115
	ds_read2_b32 v[32:33], v115 offset0:0 offset1:1
	ds_read2_b32 v[34:35], v115 offset0:2 offset1:3
	ds_read2_b32 v[36:37], v115 offset0:8 offset1:9
	ds_read2_b32 v[38:39], v115 offset0:10 offset1:11
	ds_read2_b32 v[40:41], v115 offset0:17 offset1:18
	ds_read2_b32 v[42:43], v115 offset0:19 offset1:20
	ds_read2_b32 v[44:45], v115 offset0:25 offset1:26
	ds_read2_b32 v[46:47], v115 offset0:27 offset1:28
	s_waitcnt lgkmcnt(0)
	v_mfma_f32_32x32x16_bf16 v[32:47], v[188:191], v[48:51], v[32:47]
	ds_read_b64_tr_b16 v[72:73], v231
	ds_read_b64_tr_b16 v[74:75], v231 offset:512
	ds_read_b64_tr_b16 v[76:77], v231 offset:2048
	ds_read_b64_tr_b16 v[78:79], v231 offset:2560
	ds_read_b64_tr_b16 v[220:221], v231 offset:1024
	ds_read_b64_tr_b16 v[222:223], v231 offset:1536
	ds_read_b64_tr_b16 v[224:225], v231 offset:3072
	ds_read_b64_tr_b16 v[226:227], v231 offset:3584
	s_waitcnt vmcnt(8)
	ds_write_b128 v247, v[116:119]
	ds_write_b128 v247, v[120:123] offset:1024
	ds_write_b128 v247, v[124:127] offset:2048
	ds_write_b128 v247, v[128:131] offset:3072
	ds_read_b128 v[116:119], v248
	ds_read_b128 v[120:123], v249
	ds_read_b128 v[124:127], v250
	ds_read_b128 v[128:131], v251
	ds_write_b128 v112, v[132:135]
	ds_write_b128 v112, v[136:139] offset:1024
	ds_write_b128 v112, v[140:143] offset:2048
	ds_write_b128 v112, v[144:147] offset:3072
	v_mfma_f32_32x32x16_bf16 v[32:47], v[192:195], v[52:55], v[32:47]
	v_mfma_f32_32x32x16_bf16 v[32:47], v[196:199], v[56:59], v[32:47]
	v_mfma_f32_32x32x16_bf16 v[32:47], v[200:203], v[60:63], v[32:47]
	s_nop 11
	v_exp_f32_e32 v32, v32
	v_exp_f32_e32 v33, v33
	v_exp_f32_e32 v34, v34
	v_exp_f32_e32 v35, v35
	v_exp_f32_e32 v36, v36
	v_exp_f32_e32 v37, v37
	v_exp_f32_e32 v38, v38
	v_exp_f32_e32 v39, v39
	v_exp_f32_e32 v40, v40
	v_exp_f32_e32 v41, v41
	v_exp_f32_e32 v42, v42
	v_exp_f32_e32 v43, v43
	v_exp_f32_e32 v44, v44
	v_exp_f32_e32 v45, v45
	v_exp_f32_e32 v46, v46
	v_exp_f32_e32 v47, v47
	s_add_i32 s90, s67, 384
	v_add_u32_e32 v84, s90, v107
	v_add_u32_e32 v85, 0, v84
	v_add_u32_e32 v86, 1, v84
	v_add_u32_e32 v87, 2, v84
	v_add_u32_e32 v88, 3, v84
	v_cmp_gt_u32_e64 s[30:31], s98, v85
	v_cmp_gt_u32_e64 s[36:37], s98, v86
	v_cmp_gt_u32_e64 s[78:79], s98, v87
	v_cmp_gt_u32_e64 s[50:51], s98, v88
	v_cndmask_b32_e64 v32, 0, v32, s[30:31]
	v_add_u32_e32 v85, 8, v84
	v_cmp_gt_u32_e64 s[30:31], s98, v85
	v_cndmask_b32_e64 v33, 0, v33, s[36:37]
	v_add_u32_e32 v86, 9, v84
	v_cmp_gt_u32_e64 s[36:37], s98, v86
	v_cndmask_b32_e64 v34, 0, v34, s[78:79]
	v_add_u32_e32 v87, 10, v84
	v_cmp_gt_u32_e64 s[78:79], s98, v87
	v_cndmask_b32_e64 v35, 0, v35, s[50:51]
	v_add_u32_e32 v88, 11, v84
	v_cmp_gt_u32_e64 s[50:51], s98, v88
	v_cndmask_b32_e64 v36, 0, v36, s[30:31]
	v_add_u32_e32 v85, 16, v84
	v_cmp_gt_u32_e64 s[30:31], s98, v85
	v_cndmask_b32_e64 v37, 0, v37, s[36:37]
	v_add_u32_e32 v86, 17, v84
	v_cmp_gt_u32_e64 s[36:37], s98, v86
	v_cndmask_b32_e64 v38, 0, v38, s[78:79]
	v_add_u32_e32 v87, 18, v84
	v_cmp_gt_u32_e64 s[78:79], s98, v87
	v_cndmask_b32_e64 v39, 0, v39, s[50:51]
	v_add_u32_e32 v88, 19, v84
	v_cmp_gt_u32_e64 s[50:51], s98, v88
	v_cndmask_b32_e64 v40, 0, v40, s[30:31]
	v_add_u32_e32 v85, 24, v84
	v_cmp_gt_u32_e64 s[30:31], s98, v85
	v_cndmask_b32_e64 v41, 0, v41, s[36:37]
	v_add_u32_e32 v86, 25, v84
	v_cmp_gt_u32_e64 s[36:37], s98, v86
	v_cndmask_b32_e64 v42, 0, v42, s[78:79]
	v_add_u32_e32 v87, 26, v84
	v_cmp_gt_u32_e64 s[78:79], s98, v87
	v_cndmask_b32_e64 v43, 0, v43, s[50:51]
	v_add_u32_e32 v88, 27, v84
	v_cmp_gt_u32_e64 s[50:51], s98, v88
	v_nop
	v_cndmask_b32_e64 v44, 0, v44, s[30:31]
	v_cndmask_b32_e64 v45, 0, v45, s[36:37]
	v_cndmask_b32_e64 v46, 0, v46, s[78:79]
	v_cndmask_b32_e64 v47, 0, v47, s[50:51]
	v_cvt_pk_bf16_f32 v64, v32, v33
	v_cvt_pk_bf16_f32 v65, v34, v35
	v_cvt_pk_bf16_f32 v66, v36, v37
	v_cvt_pk_bf16_f32 v67, v38, v39
	v_cvt_pk_bf16_f32 v68, v40, v41
	v_cvt_pk_bf16_f32 v69, v42, v43
	v_cvt_pk_bf16_f32 v70, v44, v45
	v_cvt_pk_bf16_f32 v71, v46, v47
	v_pk_add_f32 v[232:233], v[232:233], v[32:33]
	v_pk_add_f32 v[232:233], v[232:233], v[34:35]
	v_pk_add_f32 v[232:233], v[232:233], v[36:37]
	v_pk_add_f32 v[232:233], v[232:233], v[38:39]
	v_pk_add_f32 v[232:233], v[232:233], v[40:41]
	v_pk_add_f32 v[232:233], v[232:233], v[42:43]
	v_pk_add_f32 v[232:233], v[232:233], v[44:45]
	v_pk_add_f32 v[232:233], v[232:233], v[46:47]
	s_waitcnt lgkmcnt(12)
	v_mfma_f32_32x32x16_bf16 v[0:15], v[64:67], v[72:75], v[0:15]
	v_mfma_f32_32x32x16_bf16 v[16:31], v[64:67], v[76:79], v[16:31]
	v_mfma_f32_32x32x16_bf16 v[0:15], v[68:71], v[220:223], v[0:15]
	v_mfma_f32_32x32x16_bf16 v[16:31], v[68:71], v[224:227], v[16:31]
	s_add_i32 s90, s67, 480
	v_add_u32_e32 v80, s90, v235
	v_add_u32_e32 v83, s90, v236
	v_add_u32_e32 v99, s90, v237
	v_add_u32_e32 v253, s90, v238
	v_add_u32_e32 v254, s90, v100
	v_add_u32_e32 v255, s90, v149
	v_med3_i32 v80, v80, 0, s99
	v_med3_i32 v83, v83, 0, s99
	v_med3_i32 v99, v99, 0, s99
	v_med3_i32 v253, v253, 0, s99
	v_med3_i32 v254, v254, 0, s99
	v_med3_i32 v255, v255, 0, s99
	v_mad_u32_u24 v80, v80, s100, v252
	v_mad_u32_u24 v83, v83, s100, v252
	v_mad_u32_u24 v99, v99, s100, v252
	v_mad_u32_u24 v253, v253, s100, v252
	v_mad_u32_u24 v254, v254, s100, v153
	v_mad_u32_u24 v255, v255, s100, v153
	global_load_dwordx4 v[188:191], v80, s[82:83]
	global_load_dwordx4 v[192:195], v83, s[82:83]
	global_load_dwordx4 v[196:199], v99, s[82:83]
	global_load_dwordx4 v[200:203], v253, s[82:83]
	global_load_dwordx4 v[204:207], v254, s[82:83] offset:768
	global_load_dwordx4 v[208:211], v255, s[82:83] offset:768
	global_load_dwordx4 v[212:215], v254, s[82:83] offset:832
	global_load_dwordx4 v[216:219], v255, s[82:83] offset:832
	ds_read2_b32 v[32:33], v115 offset0:34 offset1:35
	ds_read2_b32 v[34:35], v115 offset0:36 offset1:37
	ds_read2_b32 v[36:37], v115 offset0:42 offset1:43
	ds_read2_b32 v[38:39], v115 offset0:44 offset1:45
	ds_read2_b32 v[40:41], v115 offset0:51 offset1:52
	ds_read2_b32 v[42:43], v115 offset0:53 offset1:54
	ds_read2_b32 v[44:45], v115 offset0:59 offset1:60
	ds_read2_b32 v[46:47], v115 offset0:61 offset1:62
	s_waitcnt lgkmcnt(0)
	v_mfma_f32_32x32x16_bf16 v[32:47], v[116:119], v[48:51], v[32:47]
	ds_read_b64_tr_b16 v[72:73], v231
	ds_read_b64_tr_b16 v[74:75], v231 offset:512
	ds_read_b64_tr_b16 v[76:77], v231 offset:2048
	ds_read_b64_tr_b16 v[78:79], v231 offset:2560
	ds_read_b64_tr_b16 v[220:221], v231 offset:1024
	ds_read_b64_tr_b16 v[222:223], v231 offset:1536
	ds_read_b64_tr_b16 v[224:225], v231 offset:3072
	ds_read_b64_tr_b16 v[226:227], v231 offset:3584
	s_waitcnt vmcnt(8)
	ds_write_b128 v247, v[156:159]
	ds_write_b128 v247, v[160:163] offset:1024
	ds_write_b128 v247, v[164:167] offset:2048
	ds_write_b128 v247, v[168:171] offset:3072
	ds_read_b128 v[156:159], v248
	ds_read_b128 v[160:163], v249
	ds_read_b128 v[164:167], v250
	ds_read_b128 v[168:171], v251
	ds_write_b128 v112, v[172:175]
	ds_write_b128 v112, v[176:179] offset:1024
	ds_write_b128 v112, v[180:183] offset:2048
	ds_write_b128 v112, v[184:187] offset:3072
	v_mfma_f32_32x32x16_bf16 v[32:47], v[120:123], v[52:55], v[32:47]
	v_mfma_f32_32x32x16_bf16 v[32:47], v[124:127], v[56:59], v[32:47]
	v_mfma_f32_32x32x16_bf16 v[32:47], v[128:131], v[60:63], v[32:47]
	s_nop 11
	v_exp_f32_e32 v32, v32
	v_exp_f32_e32 v33, v33
	v_exp_f32_e32 v34, v34
	v_exp_f32_e32 v35, v35
	v_exp_f32_e32 v36, v36
	v_exp_f32_e32 v37, v37
	v_exp_f32_e32 v38, v38
	v_exp_f32_e32 v39, v39
	v_exp_f32_e32 v40, v40
	v_exp_f32_e32 v41, v41
	v_exp_f32_e32 v42, v42
	v_exp_f32_e32 v43, v43
	v_exp_f32_e32 v44, v44
	v_exp_f32_e32 v45, v45
	v_exp_f32_e32 v46, v46
	v_exp_f32_e32 v47, v47
	s_add_i32 s90, s67, 416
	v_add_u32_e32 v84, s90, v107
	v_add_u32_e32 v85, 0, v84
	v_add_u32_e32 v86, 1, v84
	v_add_u32_e32 v87, 2, v84
	v_add_u32_e32 v88, 3, v84
	v_cmp_gt_u32_e64 s[30:31], s98, v85
	v_cmp_gt_u32_e64 s[36:37], s98, v86
	v_cmp_gt_u32_e64 s[78:79], s98, v87
	v_cmp_gt_u32_e64 s[50:51], s98, v88
	v_cndmask_b32_e64 v32, 0, v32, s[30:31]
	v_add_u32_e32 v85, 8, v84
	v_cmp_gt_u32_e64 s[30:31], s98, v85
	v_cndmask_b32_e64 v33, 0, v33, s[36:37]
	v_add_u32_e32 v86, 9, v84
	v_cmp_gt_u32_e64 s[36:37], s98, v86
	v_cndmask_b32_e64 v34, 0, v34, s[78:79]
	v_add_u32_e32 v87, 10, v84
	v_cmp_gt_u32_e64 s[78:79], s98, v87
	v_cndmask_b32_e64 v35, 0, v35, s[50:51]
	v_add_u32_e32 v88, 11, v84
	v_cmp_gt_u32_e64 s[50:51], s98, v88
	v_cndmask_b32_e64 v36, 0, v36, s[30:31]
	v_add_u32_e32 v85, 16, v84
	v_cmp_gt_u32_e64 s[30:31], s98, v85
	v_cndmask_b32_e64 v37, 0, v37, s[36:37]
	v_add_u32_e32 v86, 17, v84
	v_cmp_gt_u32_e64 s[36:37], s98, v86
	v_cndmask_b32_e64 v38, 0, v38, s[78:79]
	v_add_u32_e32 v87, 18, v84
	v_cmp_gt_u32_e64 s[78:79], s98, v87
	v_cndmask_b32_e64 v39, 0, v39, s[50:51]
	v_add_u32_e32 v88, 19, v84
	v_cmp_gt_u32_e64 s[50:51], s98, v88
	v_cndmask_b32_e64 v40, 0, v40, s[30:31]
	v_add_u32_e32 v85, 24, v84
	v_cmp_gt_u32_e64 s[30:31], s98, v85
	v_cndmask_b32_e64 v41, 0, v41, s[36:37]
	v_add_u32_e32 v86, 25, v84
	v_cmp_gt_u32_e64 s[36:37], s98, v86
	v_cndmask_b32_e64 v42, 0, v42, s[78:79]
	v_add_u32_e32 v87, 26, v84
	v_cmp_gt_u32_e64 s[78:79], s98, v87
	v_cndmask_b32_e64 v43, 0, v43, s[50:51]
	v_add_u32_e32 v88, 27, v84
	v_cmp_gt_u32_e64 s[50:51], s98, v88
	v_nop
	v_cndmask_b32_e64 v44, 0, v44, s[30:31]
	v_cndmask_b32_e64 v45, 0, v45, s[36:37]
	v_cndmask_b32_e64 v46, 0, v46, s[78:79]
	v_cndmask_b32_e64 v47, 0, v47, s[50:51]
	v_cvt_pk_bf16_f32 v64, v32, v33
	v_cvt_pk_bf16_f32 v65, v34, v35
	v_cvt_pk_bf16_f32 v66, v36, v37
	v_cvt_pk_bf16_f32 v67, v38, v39
	v_cvt_pk_bf16_f32 v68, v40, v41
	v_cvt_pk_bf16_f32 v69, v42, v43
	v_cvt_pk_bf16_f32 v70, v44, v45
	v_cvt_pk_bf16_f32 v71, v46, v47
	v_pk_add_f32 v[232:233], v[232:233], v[32:33]
	v_pk_add_f32 v[232:233], v[232:233], v[34:35]
	v_pk_add_f32 v[232:233], v[232:233], v[36:37]
	v_pk_add_f32 v[232:233], v[232:233], v[38:39]
	v_pk_add_f32 v[232:233], v[232:233], v[40:41]
	v_pk_add_f32 v[232:233], v[232:233], v[42:43]
	v_pk_add_f32 v[232:233], v[232:233], v[44:45]
	v_pk_add_f32 v[232:233], v[232:233], v[46:47]
	s_waitcnt lgkmcnt(12)
	v_mfma_f32_32x32x16_bf16 v[0:15], v[64:67], v[72:75], v[0:15]
	v_mfma_f32_32x32x16_bf16 v[16:31], v[64:67], v[76:79], v[16:31]
	v_mfma_f32_32x32x16_bf16 v[0:15], v[68:71], v[220:223], v[0:15]
	v_mfma_f32_32x32x16_bf16 v[16:31], v[68:71], v[224:227], v[16:31]
	s_add_i32 s90, s67, 512
	v_add_u32_e32 v80, s90, v235
	v_add_u32_e32 v83, s90, v236
	v_add_u32_e32 v99, s90, v237
	v_add_u32_e32 v253, s90, v238
	v_add_u32_e32 v254, s90, v100
	v_add_u32_e32 v255, s90, v149
	v_med3_i32 v80, v80, 0, s99
	v_med3_i32 v83, v83, 0, s99
	v_med3_i32 v99, v99, 0, s99
	v_med3_i32 v253, v253, 0, s99
	v_med3_i32 v254, v254, 0, s99
	v_med3_i32 v255, v255, 0, s99
	v_mad_u32_u24 v80, v80, s100, v252
	v_mad_u32_u24 v83, v83, s100, v252
	v_mad_u32_u24 v99, v99, s100, v252
	v_mad_u32_u24 v253, v253, s100, v252
	v_mad_u32_u24 v254, v254, s100, v153
	v_mad_u32_u24 v255, v255, s100, v153
	global_load_dwordx4 v[116:119], v80, s[82:83]
	global_load_dwordx4 v[120:123], v83, s[82:83]
	global_load_dwordx4 v[124:127], v99, s[82:83]
	global_load_dwordx4 v[128:131], v253, s[82:83]
	global_load_dwordx4 v[132:135], v254, s[82:83] offset:768
	global_load_dwordx4 v[136:139], v255, s[82:83] offset:768
	global_load_dwordx4 v[140:143], v254, s[82:83] offset:832
	global_load_dwordx4 v[144:147], v255, s[82:83] offset:832
	ds_read2_b32 v[32:33], v115 offset0:68 offset1:69
	ds_read2_b32 v[34:35], v115 offset0:70 offset1:71
	ds_read2_b32 v[36:37], v115 offset0:76 offset1:77
	ds_read2_b32 v[38:39], v115 offset0:78 offset1:79
	ds_read2_b32 v[40:41], v115 offset0:85 offset1:86
	ds_read2_b32 v[42:43], v115 offset0:87 offset1:88
	ds_read2_b32 v[44:45], v115 offset0:93 offset1:94
	ds_read2_b32 v[46:47], v115 offset0:95 offset1:96
	s_waitcnt lgkmcnt(0)
	v_mfma_f32_32x32x16_bf16 v[32:47], v[156:159], v[48:51], v[32:47]
	ds_read_b64_tr_b16 v[72:73], v231
	ds_read_b64_tr_b16 v[74:75], v231 offset:512
	ds_read_b64_tr_b16 v[76:77], v231 offset:2048
	ds_read_b64_tr_b16 v[78:79], v231 offset:2560
	ds_read_b64_tr_b16 v[220:221], v231 offset:1024
	ds_read_b64_tr_b16 v[222:223], v231 offset:1536
	ds_read_b64_tr_b16 v[224:225], v231 offset:3072
	ds_read_b64_tr_b16 v[226:227], v231 offset:3584
	s_waitcnt vmcnt(8)
	ds_write_b128 v247, v[188:191]
	ds_write_b128 v247, v[192:195] offset:1024
	ds_write_b128 v247, v[196:199] offset:2048
	ds_write_b128 v247, v[200:203] offset:3072
	ds_read_b128 v[188:191], v248
	ds_read_b128 v[192:195], v249
	ds_read_b128 v[196:199], v250
	ds_read_b128 v[200:203], v251
	ds_write_b128 v112, v[204:207]
	ds_write_b128 v112, v[208:211] offset:1024
	ds_write_b128 v112, v[212:215] offset:2048
	ds_write_b128 v112, v[216:219] offset:3072
	v_mfma_f32_32x32x16_bf16 v[32:47], v[160:163], v[52:55], v[32:47]
	v_mfma_f32_32x32x16_bf16 v[32:47], v[164:167], v[56:59], v[32:47]
	v_mfma_f32_32x32x16_bf16 v[32:47], v[168:171], v[60:63], v[32:47]
	s_nop 11
	v_exp_f32_e32 v32, v32
	v_exp_f32_e32 v33, v33
	v_exp_f32_e32 v34, v34
	v_exp_f32_e32 v35, v35
	v_exp_f32_e32 v36, v36
	v_exp_f32_e32 v37, v37
	v_exp_f32_e32 v38, v38
	v_exp_f32_e32 v39, v39
	v_exp_f32_e32 v40, v40
	v_exp_f32_e32 v41, v41
	v_exp_f32_e32 v42, v42
	v_exp_f32_e32 v43, v43
	v_exp_f32_e32 v44, v44
	v_exp_f32_e32 v45, v45
	v_exp_f32_e32 v46, v46
	v_exp_f32_e32 v47, v47
	s_add_i32 s90, s67, 448
	v_add_u32_e32 v84, s90, v107
	v_add_u32_e32 v85, 0, v84
	v_add_u32_e32 v86, 1, v84
	v_add_u32_e32 v87, 2, v84
	v_add_u32_e32 v88, 3, v84
	v_cmp_gt_u32_e64 s[30:31], s98, v85
	v_cmp_gt_u32_e64 s[36:37], s98, v86
	v_cmp_gt_u32_e64 s[78:79], s98, v87
	v_cmp_gt_u32_e64 s[50:51], s98, v88
	v_cndmask_b32_e64 v32, 0, v32, s[30:31]
	v_add_u32_e32 v85, 8, v84
	v_cmp_gt_u32_e64 s[30:31], s98, v85
	v_cndmask_b32_e64 v33, 0, v33, s[36:37]
	v_add_u32_e32 v86, 9, v84
	v_cmp_gt_u32_e64 s[36:37], s98, v86
	v_cndmask_b32_e64 v34, 0, v34, s[78:79]
	v_add_u32_e32 v87, 10, v84
	v_cmp_gt_u32_e64 s[78:79], s98, v87
	v_cndmask_b32_e64 v35, 0, v35, s[50:51]
	v_add_u32_e32 v88, 11, v84
	v_cmp_gt_u32_e64 s[50:51], s98, v88
	v_cndmask_b32_e64 v36, 0, v36, s[30:31]
	v_add_u32_e32 v85, 16, v84
	v_cmp_gt_u32_e64 s[30:31], s98, v85
	v_cndmask_b32_e64 v37, 0, v37, s[36:37]
	v_add_u32_e32 v86, 17, v84
	v_cmp_gt_u32_e64 s[36:37], s98, v86
	v_cndmask_b32_e64 v38, 0, v38, s[78:79]
	v_add_u32_e32 v87, 18, v84
	v_cmp_gt_u32_e64 s[78:79], s98, v87
	v_cndmask_b32_e64 v39, 0, v39, s[50:51]
	v_add_u32_e32 v88, 19, v84
	v_cmp_gt_u32_e64 s[50:51], s98, v88
	v_cndmask_b32_e64 v40, 0, v40, s[30:31]
	v_add_u32_e32 v85, 24, v84
	v_cmp_gt_u32_e64 s[30:31], s98, v85
	v_cndmask_b32_e64 v41, 0, v41, s[36:37]
	v_add_u32_e32 v86, 25, v84
	v_cmp_gt_u32_e64 s[36:37], s98, v86
	v_cndmask_b32_e64 v42, 0, v42, s[78:79]
	v_add_u32_e32 v87, 26, v84
	v_cmp_gt_u32_e64 s[78:79], s98, v87
	v_cndmask_b32_e64 v43, 0, v43, s[50:51]
	v_add_u32_e32 v88, 27, v84
	v_cmp_gt_u32_e64 s[50:51], s98, v88
	v_nop
	v_cndmask_b32_e64 v44, 0, v44, s[30:31]
	v_cndmask_b32_e64 v45, 0, v45, s[36:37]
	v_cndmask_b32_e64 v46, 0, v46, s[78:79]
	v_cndmask_b32_e64 v47, 0, v47, s[50:51]
	v_cvt_pk_bf16_f32 v64, v32, v33
	v_cvt_pk_bf16_f32 v65, v34, v35
	v_cvt_pk_bf16_f32 v66, v36, v37
	v_cvt_pk_bf16_f32 v67, v38, v39
	v_cvt_pk_bf16_f32 v68, v40, v41
	v_cvt_pk_bf16_f32 v69, v42, v43
	v_cvt_pk_bf16_f32 v70, v44, v45
	v_cvt_pk_bf16_f32 v71, v46, v47
	v_pk_add_f32 v[232:233], v[232:233], v[32:33]
	v_pk_add_f32 v[232:233], v[232:233], v[34:35]
	v_pk_add_f32 v[232:233], v[232:233], v[36:37]
	v_pk_add_f32 v[232:233], v[232:233], v[38:39]
	v_pk_add_f32 v[232:233], v[232:233], v[40:41]
	v_pk_add_f32 v[232:233], v[232:233], v[42:43]
	v_pk_add_f32 v[232:233], v[232:233], v[44:45]
	v_pk_add_f32 v[232:233], v[232:233], v[46:47]
	s_waitcnt lgkmcnt(12)
	v_mfma_f32_32x32x16_bf16 v[0:15], v[64:67], v[72:75], v[0:15]
	v_mfma_f32_32x32x16_bf16 v[16:31], v[64:67], v[76:79], v[16:31]
	v_mfma_f32_32x32x16_bf16 v[0:15], v[68:71], v[220:223], v[0:15]
	v_mfma_f32_32x32x16_bf16 v[16:31], v[68:71], v[224:227], v[16:31]
	s_add_i32 s90, s67, 544
	v_add_u32_e32 v80, s90, v235
	v_add_u32_e32 v83, s90, v236
	v_add_u32_e32 v99, s90, v237
	v_add_u32_e32 v253, s90, v238
	v_add_u32_e32 v254, s90, v100
	v_add_u32_e32 v255, s90, v149
	v_med3_i32 v80, v80, 0, s99
	v_med3_i32 v83, v83, 0, s99
	v_med3_i32 v99, v99, 0, s99
	v_med3_i32 v253, v253, 0, s99
	v_med3_i32 v254, v254, 0, s99
	v_med3_i32 v255, v255, 0, s99
	v_mad_u32_u24 v80, v80, s100, v252
	v_mad_u32_u24 v83, v83, s100, v252
	v_mad_u32_u24 v99, v99, s100, v252
	v_mad_u32_u24 v253, v253, s100, v252
	v_mad_u32_u24 v254, v254, s100, v153
	v_mad_u32_u24 v255, v255, s100, v153
	global_load_dwordx4 v[156:159], v80, s[82:83]
	global_load_dwordx4 v[160:163], v83, s[82:83]
	global_load_dwordx4 v[164:167], v99, s[82:83]
	global_load_dwordx4 v[168:171], v253, s[82:83]
	global_load_dwordx4 v[172:175], v254, s[82:83] offset:768
	global_load_dwordx4 v[176:179], v255, s[82:83] offset:768
	global_load_dwordx4 v[180:183], v254, s[82:83] offset:832
	global_load_dwordx4 v[184:187], v255, s[82:83] offset:832
	ds_read2_b32 v[32:33], v115 offset0:102 offset1:103
	ds_read2_b32 v[34:35], v115 offset0:104 offset1:105
	ds_read2_b32 v[36:37], v115 offset0:110 offset1:111
	ds_read2_b32 v[38:39], v115 offset0:112 offset1:113
	ds_read2_b32 v[40:41], v115 offset0:119 offset1:120
	ds_read2_b32 v[42:43], v115 offset0:121 offset1:122
	ds_read2_b32 v[44:45], v115 offset0:127 offset1:128
	ds_read2_b32 v[46:47], v115 offset0:129 offset1:130
	s_waitcnt lgkmcnt(0)
	v_mfma_f32_32x32x16_bf16 v[32:47], v[188:191], v[48:51], v[32:47]
	ds_read_b64_tr_b16 v[72:73], v231
	ds_read_b64_tr_b16 v[74:75], v231 offset:512
	ds_read_b64_tr_b16 v[76:77], v231 offset:2048
	ds_read_b64_tr_b16 v[78:79], v231 offset:2560
	ds_read_b64_tr_b16 v[220:221], v231 offset:1024
	ds_read_b64_tr_b16 v[222:223], v231 offset:1536
	ds_read_b64_tr_b16 v[224:225], v231 offset:3072
	ds_read_b64_tr_b16 v[226:227], v231 offset:3584
	s_waitcnt vmcnt(8)
	ds_write_b128 v247, v[116:119]
	ds_write_b128 v247, v[120:123] offset:1024
	ds_write_b128 v247, v[124:127] offset:2048
	ds_write_b128 v247, v[128:131] offset:3072
	ds_read_b128 v[116:119], v248
	ds_read_b128 v[120:123], v249
	ds_read_b128 v[124:127], v250
	ds_read_b128 v[128:131], v251
	ds_write_b128 v112, v[132:135]
	ds_write_b128 v112, v[136:139] offset:1024
	ds_write_b128 v112, v[140:143] offset:2048
	ds_write_b128 v112, v[144:147] offset:3072
	v_mfma_f32_32x32x16_bf16 v[32:47], v[192:195], v[52:55], v[32:47]
	v_mfma_f32_32x32x16_bf16 v[32:47], v[196:199], v[56:59], v[32:47]
	v_mfma_f32_32x32x16_bf16 v[32:47], v[200:203], v[60:63], v[32:47]
	s_nop 11
	v_exp_f32_e32 v32, v32
	v_exp_f32_e32 v33, v33
	v_exp_f32_e32 v34, v34
	v_exp_f32_e32 v35, v35
	v_exp_f32_e32 v36, v36
	v_exp_f32_e32 v37, v37
	v_exp_f32_e32 v38, v38
	v_exp_f32_e32 v39, v39
	v_exp_f32_e32 v40, v40
	v_exp_f32_e32 v41, v41
	v_exp_f32_e32 v42, v42
	v_exp_f32_e32 v43, v43
	v_exp_f32_e32 v44, v44
	v_exp_f32_e32 v45, v45
	v_exp_f32_e32 v46, v46
	v_exp_f32_e32 v47, v47
	s_add_i32 s90, s67, 480
	v_add_u32_e32 v84, s90, v107
	v_add_u32_e32 v85, 0, v84
	v_add_u32_e32 v86, 1, v84
	v_add_u32_e32 v87, 2, v84
	v_add_u32_e32 v88, 3, v84
	v_cmp_gt_u32_e64 s[30:31], s98, v85
	v_cmp_gt_u32_e64 s[36:37], s98, v86
	v_cmp_gt_u32_e64 s[78:79], s98, v87
	v_cmp_gt_u32_e64 s[50:51], s98, v88
	v_cndmask_b32_e64 v32, 0, v32, s[30:31]
	v_add_u32_e32 v85, 8, v84
	v_cmp_gt_u32_e64 s[30:31], s98, v85
	v_cndmask_b32_e64 v33, 0, v33, s[36:37]
	v_add_u32_e32 v86, 9, v84
	v_cmp_gt_u32_e64 s[36:37], s98, v86
	v_cndmask_b32_e64 v34, 0, v34, s[78:79]
	v_add_u32_e32 v87, 10, v84
	v_cmp_gt_u32_e64 s[78:79], s98, v87
	v_cndmask_b32_e64 v35, 0, v35, s[50:51]
	v_add_u32_e32 v88, 11, v84
	v_cmp_gt_u32_e64 s[50:51], s98, v88
	v_cndmask_b32_e64 v36, 0, v36, s[30:31]
	v_add_u32_e32 v85, 16, v84
	v_cmp_gt_u32_e64 s[30:31], s98, v85
	v_cndmask_b32_e64 v37, 0, v37, s[36:37]
	v_add_u32_e32 v86, 17, v84
	v_cmp_gt_u32_e64 s[36:37], s98, v86
	v_cndmask_b32_e64 v38, 0, v38, s[78:79]
	v_add_u32_e32 v87, 18, v84
	v_cmp_gt_u32_e64 s[78:79], s98, v87
	v_cndmask_b32_e64 v39, 0, v39, s[50:51]
	v_add_u32_e32 v88, 19, v84
	v_cmp_gt_u32_e64 s[50:51], s98, v88
	v_cndmask_b32_e64 v40, 0, v40, s[30:31]
	v_add_u32_e32 v85, 24, v84
	v_cmp_gt_u32_e64 s[30:31], s98, v85
	v_cndmask_b32_e64 v41, 0, v41, s[36:37]
	v_add_u32_e32 v86, 25, v84
	v_cmp_gt_u32_e64 s[36:37], s98, v86
	v_cndmask_b32_e64 v42, 0, v42, s[78:79]
	v_add_u32_e32 v87, 26, v84
	v_cmp_gt_u32_e64 s[78:79], s98, v87
	v_cndmask_b32_e64 v43, 0, v43, s[50:51]
	v_add_u32_e32 v88, 27, v84
	v_cmp_gt_u32_e64 s[50:51], s98, v88
	v_nop
	v_cndmask_b32_e64 v44, 0, v44, s[30:31]
	v_cndmask_b32_e64 v45, 0, v45, s[36:37]
	v_cndmask_b32_e64 v46, 0, v46, s[78:79]
	v_cndmask_b32_e64 v47, 0, v47, s[50:51]
	v_cvt_pk_bf16_f32 v64, v32, v33
	v_cvt_pk_bf16_f32 v65, v34, v35
	v_cvt_pk_bf16_f32 v66, v36, v37
	v_cvt_pk_bf16_f32 v67, v38, v39
	v_cvt_pk_bf16_f32 v68, v40, v41
	v_cvt_pk_bf16_f32 v69, v42, v43
	v_cvt_pk_bf16_f32 v70, v44, v45
	v_cvt_pk_bf16_f32 v71, v46, v47
	v_pk_add_f32 v[232:233], v[232:233], v[32:33]
	v_pk_add_f32 v[232:233], v[232:233], v[34:35]
	v_pk_add_f32 v[232:233], v[232:233], v[36:37]
	v_pk_add_f32 v[232:233], v[232:233], v[38:39]
	v_pk_add_f32 v[232:233], v[232:233], v[40:41]
	v_pk_add_f32 v[232:233], v[232:233], v[42:43]
	v_pk_add_f32 v[232:233], v[232:233], v[44:45]
	v_pk_add_f32 v[232:233], v[232:233], v[46:47]
	s_waitcnt lgkmcnt(12)
	v_mfma_f32_32x32x16_bf16 v[0:15], v[64:67], v[72:75], v[0:15]
	v_mfma_f32_32x32x16_bf16 v[16:31], v[64:67], v[76:79], v[16:31]
	v_mfma_f32_32x32x16_bf16 v[0:15], v[68:71], v[220:223], v[0:15]
	v_mfma_f32_32x32x16_bf16 v[16:31], v[68:71], v[224:227], v[16:31]
	s_add_i32 s90, s67, -256
	v_add_u32_e32 v80, s90, v239
	v_add_u32_e32 v83, s90, v240
	v_add_u32_e32 v99, s90, v241
	v_add_u32_e32 v253, s90, v242
	v_add_u32_e32 v254, s90, v101
	v_add_u32_e32 v255, s90, v150
	v_med3_i32 v80, v80, 0, s99
	v_med3_i32 v83, v83, 0, s99
	v_med3_i32 v99, v99, 0, s99
	v_med3_i32 v253, v253, 0, s99
	v_med3_i32 v254, v254, 0, s99
	v_med3_i32 v255, v255, 0, s99
	v_mad_u32_u24 v80, v80, s100, v252
	v_mad_u32_u24 v83, v83, s100, v252
	v_mad_u32_u24 v99, v99, s100, v252
	v_mad_u32_u24 v253, v253, s100, v252
	v_mad_u32_u24 v254, v254, s100, v153
	v_mad_u32_u24 v255, v255, s100, v153
	global_load_dwordx4 v[188:191], v80, s[82:83]
	global_load_dwordx4 v[192:195], v83, s[82:83]
	global_load_dwordx4 v[196:199], v99, s[82:83]
	global_load_dwordx4 v[200:203], v253, s[82:83]
	global_load_dwordx4 v[204:207], v254, s[82:83] offset:768
	global_load_dwordx4 v[208:211], v255, s[82:83] offset:768
	global_load_dwordx4 v[212:215], v254, s[82:83] offset:832
	global_load_dwordx4 v[216:219], v255, s[82:83] offset:832
	ds_read2_b32 v[32:33], v115 offset0:136 offset1:137
	ds_read2_b32 v[34:35], v115 offset0:138 offset1:139
	ds_read2_b32 v[36:37], v115 offset0:144 offset1:145
	ds_read2_b32 v[38:39], v115 offset0:146 offset1:147
	ds_read2_b32 v[40:41], v115 offset0:153 offset1:154
	ds_read2_b32 v[42:43], v115 offset0:155 offset1:156
	ds_read2_b32 v[44:45], v115 offset0:161 offset1:162
	ds_read2_b32 v[46:47], v115 offset0:163 offset1:164
	s_waitcnt lgkmcnt(0)
	v_mfma_f32_32x32x16_bf16 v[32:47], v[116:119], v[48:51], v[32:47]
	ds_read_b64_tr_b16 v[72:73], v231
	ds_read_b64_tr_b16 v[74:75], v231 offset:512
	ds_read_b64_tr_b16 v[76:77], v231 offset:2048
	ds_read_b64_tr_b16 v[78:79], v231 offset:2560
	ds_read_b64_tr_b16 v[220:221], v231 offset:1024
	ds_read_b64_tr_b16 v[222:223], v231 offset:1536
	ds_read_b64_tr_b16 v[224:225], v231 offset:3072
	ds_read_b64_tr_b16 v[226:227], v231 offset:3584
	s_waitcnt vmcnt(8)
	ds_write_b128 v247, v[156:159]
	ds_write_b128 v247, v[160:163] offset:1024
	ds_write_b128 v247, v[164:167] offset:2048
	ds_write_b128 v247, v[168:171] offset:3072
	ds_read_b128 v[156:159], v248
	ds_read_b128 v[160:163], v249
	ds_read_b128 v[164:167], v250
	ds_read_b128 v[168:171], v251
	ds_write_b128 v112, v[172:175]
	ds_write_b128 v112, v[176:179] offset:1024
	ds_write_b128 v112, v[180:183] offset:2048
	ds_write_b128 v112, v[184:187] offset:3072
	v_mfma_f32_32x32x16_bf16 v[32:47], v[120:123], v[52:55], v[32:47]
	v_mfma_f32_32x32x16_bf16 v[32:47], v[124:127], v[56:59], v[32:47]
	v_mfma_f32_32x32x16_bf16 v[32:47], v[128:131], v[60:63], v[32:47]
	s_nop 11
	v_exp_f32_e32 v32, v32
	v_exp_f32_e32 v33, v33
	v_exp_f32_e32 v34, v34
	v_exp_f32_e32 v35, v35
	v_exp_f32_e32 v36, v36
	v_exp_f32_e32 v37, v37
	v_exp_f32_e32 v38, v38
	v_exp_f32_e32 v39, v39
	v_exp_f32_e32 v40, v40
	v_exp_f32_e32 v41, v41
	v_exp_f32_e32 v42, v42
	v_exp_f32_e32 v43, v43
	v_exp_f32_e32 v44, v44
	v_exp_f32_e32 v45, v45
	v_exp_f32_e32 v46, v46
	v_exp_f32_e32 v47, v47
	s_add_i32 s90, s67, 512
	v_add_u32_e32 v84, s90, v107
	v_add_u32_e32 v85, 0, v84
	v_add_u32_e32 v86, 1, v84
	v_add_u32_e32 v87, 2, v84
	v_add_u32_e32 v88, 3, v84
	v_cmp_gt_u32_e64 s[30:31], s98, v85
	v_cmp_gt_u32_e64 s[36:37], s98, v86
	v_cmp_gt_u32_e64 s[78:79], s98, v87
	v_cmp_gt_u32_e64 s[50:51], s98, v88
	v_cndmask_b32_e64 v32, 0, v32, s[30:31]
	v_add_u32_e32 v85, 8, v84
	v_cmp_gt_u32_e64 s[30:31], s98, v85
	v_cndmask_b32_e64 v33, 0, v33, s[36:37]
	v_add_u32_e32 v86, 9, v84
	v_cmp_gt_u32_e64 s[36:37], s98, v86
	v_cndmask_b32_e64 v34, 0, v34, s[78:79]
	v_add_u32_e32 v87, 10, v84
	v_cmp_gt_u32_e64 s[78:79], s98, v87
	v_cndmask_b32_e64 v35, 0, v35, s[50:51]
	v_add_u32_e32 v88, 11, v84
	v_cmp_gt_u32_e64 s[50:51], s98, v88
	v_cndmask_b32_e64 v36, 0, v36, s[30:31]
	v_add_u32_e32 v85, 16, v84
	v_cmp_gt_u32_e64 s[30:31], s98, v85
	v_cndmask_b32_e64 v37, 0, v37, s[36:37]
	v_add_u32_e32 v86, 17, v84
	v_cmp_gt_u32_e64 s[36:37], s98, v86
	v_cndmask_b32_e64 v38, 0, v38, s[78:79]
	v_add_u32_e32 v87, 18, v84
	v_cmp_gt_u32_e64 s[78:79], s98, v87
	v_cndmask_b32_e64 v39, 0, v39, s[50:51]
	v_add_u32_e32 v88, 19, v84
	v_cmp_gt_u32_e64 s[50:51], s98, v88
	v_cndmask_b32_e64 v40, 0, v40, s[30:31]
	v_add_u32_e32 v85, 24, v84
	v_cmp_gt_u32_e64 s[30:31], s98, v85
	v_cndmask_b32_e64 v41, 0, v41, s[36:37]
	v_add_u32_e32 v86, 25, v84
	v_cmp_gt_u32_e64 s[36:37], s98, v86
	v_cndmask_b32_e64 v42, 0, v42, s[78:79]
	v_add_u32_e32 v87, 26, v84
	v_cmp_gt_u32_e64 s[78:79], s98, v87
	v_cndmask_b32_e64 v43, 0, v43, s[50:51]
	v_add_u32_e32 v88, 27, v84
	v_cmp_gt_u32_e64 s[50:51], s98, v88
	v_nop
	v_cndmask_b32_e64 v44, 0, v44, s[30:31]
	v_cndmask_b32_e64 v45, 0, v45, s[36:37]
	v_cndmask_b32_e64 v46, 0, v46, s[78:79]
	v_cndmask_b32_e64 v47, 0, v47, s[50:51]
	v_cvt_pk_bf16_f32 v64, v32, v33
	v_cvt_pk_bf16_f32 v65, v34, v35
	v_cvt_pk_bf16_f32 v66, v36, v37
	v_cvt_pk_bf16_f32 v67, v38, v39
	v_cvt_pk_bf16_f32 v68, v40, v41
	v_cvt_pk_bf16_f32 v69, v42, v43
	v_cvt_pk_bf16_f32 v70, v44, v45
	v_cvt_pk_bf16_f32 v71, v46, v47
	v_pk_add_f32 v[232:233], v[232:233], v[32:33]
	v_pk_add_f32 v[232:233], v[232:233], v[34:35]
	v_pk_add_f32 v[232:233], v[232:233], v[36:37]
	v_pk_add_f32 v[232:233], v[232:233], v[38:39]
	v_pk_add_f32 v[232:233], v[232:233], v[40:41]
	v_pk_add_f32 v[232:233], v[232:233], v[42:43]
	v_pk_add_f32 v[232:233], v[232:233], v[44:45]
	v_pk_add_f32 v[232:233], v[232:233], v[46:47]
	s_waitcnt lgkmcnt(12)
	v_mfma_f32_32x32x16_bf16 v[0:15], v[64:67], v[72:75], v[0:15]
	v_mfma_f32_32x32x16_bf16 v[16:31], v[64:67], v[76:79], v[16:31]
	v_mfma_f32_32x32x16_bf16 v[0:15], v[68:71], v[220:223], v[0:15]
	v_mfma_f32_32x32x16_bf16 v[16:31], v[68:71], v[224:227], v[16:31]
	s_add_i32 s90, s67, -128
	v_add_u32_e32 v80, s90, v239
	v_add_u32_e32 v83, s90, v240
	v_add_u32_e32 v99, s90, v241
	v_add_u32_e32 v253, s90, v242
	v_add_u32_e32 v254, s90, v101
	v_add_u32_e32 v255, s90, v150
	v_med3_i32 v80, v80, 0, s99
	v_med3_i32 v83, v83, 0, s99
	v_med3_i32 v99, v99, 0, s99
	v_med3_i32 v253, v253, 0, s99
	v_med3_i32 v254, v254, 0, s99
	v_med3_i32 v255, v255, 0, s99
	v_mad_u32_u24 v80, v80, s100, v252
	v_mad_u32_u24 v83, v83, s100, v252
	v_mad_u32_u24 v99, v99, s100, v252
	v_mad_u32_u24 v253, v253, s100, v252
	v_mad_u32_u24 v254, v254, s100, v153
	v_mad_u32_u24 v255, v255, s100, v153
	global_load_dwordx4 v[116:119], v80, s[82:83]
	global_load_dwordx4 v[120:123], v83, s[82:83]
	global_load_dwordx4 v[124:127], v99, s[82:83]
	global_load_dwordx4 v[128:131], v253, s[82:83]
	global_load_dwordx4 v[132:135], v254, s[82:83] offset:768
	global_load_dwordx4 v[136:139], v255, s[82:83] offset:768
	global_load_dwordx4 v[140:143], v254, s[82:83] offset:832
	global_load_dwordx4 v[144:147], v255, s[82:83] offset:832
	ds_read2_b32 v[32:33], v115 offset0:170 offset1:171
	ds_read2_b32 v[34:35], v115 offset0:172 offset1:173
	ds_read2_b32 v[36:37], v115 offset0:178 offset1:179
	ds_read2_b32 v[38:39], v115 offset0:180 offset1:181
	ds_read2_b32 v[40:41], v115 offset0:187 offset1:188
	ds_read2_b32 v[42:43], v115 offset0:189 offset1:190
	ds_read2_b32 v[44:45], v115 offset0:195 offset1:196
	ds_read2_b32 v[46:47], v115 offset0:197 offset1:198
	s_waitcnt lgkmcnt(0)
	v_mfma_f32_32x32x16_bf16 v[32:47], v[156:159], v[48:51], v[32:47]
	ds_read_b64_tr_b16 v[72:73], v231
	ds_read_b64_tr_b16 v[74:75], v231 offset:512
	ds_read_b64_tr_b16 v[76:77], v231 offset:2048
	ds_read_b64_tr_b16 v[78:79], v231 offset:2560
	ds_read_b64_tr_b16 v[220:221], v231 offset:1024
	ds_read_b64_tr_b16 v[222:223], v231 offset:1536
	ds_read_b64_tr_b16 v[224:225], v231 offset:3072
	ds_read_b64_tr_b16 v[226:227], v231 offset:3584
	s_waitcnt vmcnt(8)
	ds_write_b128 v247, v[188:191]
	ds_write_b128 v247, v[192:195] offset:1024
	ds_write_b128 v247, v[196:199] offset:2048
	ds_write_b128 v247, v[200:203] offset:3072
	ds_read_b128 v[188:191], v248
	ds_read_b128 v[192:195], v249
	ds_read_b128 v[196:199], v250
	ds_read_b128 v[200:203], v251
	ds_write_b128 v112, v[204:207]
	ds_write_b128 v112, v[208:211] offset:1024
	ds_write_b128 v112, v[212:215] offset:2048
	ds_write_b128 v112, v[216:219] offset:3072
	v_mfma_f32_32x32x16_bf16 v[32:47], v[160:163], v[52:55], v[32:47]
	v_mfma_f32_32x32x16_bf16 v[32:47], v[164:167], v[56:59], v[32:47]
	v_mfma_f32_32x32x16_bf16 v[32:47], v[168:171], v[60:63], v[32:47]
	s_nop 11
	v_exp_f32_e32 v32, v32
	v_exp_f32_e32 v33, v33
	v_exp_f32_e32 v34, v34
	v_exp_f32_e32 v35, v35
	v_exp_f32_e32 v36, v36
	v_exp_f32_e32 v37, v37
	v_exp_f32_e32 v38, v38
	v_exp_f32_e32 v39, v39
	v_exp_f32_e32 v40, v40
	v_exp_f32_e32 v41, v41
	v_exp_f32_e32 v42, v42
	v_exp_f32_e32 v43, v43
	v_exp_f32_e32 v44, v44
	v_exp_f32_e32 v45, v45
	v_exp_f32_e32 v46, v46
	v_exp_f32_e32 v47, v47
	s_add_i32 s90, s67, 544
	v_add_u32_e32 v84, s90, v107
	v_add_u32_e32 v85, 0, v84
	v_add_u32_e32 v86, 1, v84
	v_add_u32_e32 v87, 2, v84
	v_add_u32_e32 v88, 3, v84
	v_cmp_gt_u32_e64 s[30:31], s98, v85
	v_cmp_gt_u32_e64 s[36:37], s98, v86
	v_cmp_gt_u32_e64 s[78:79], s98, v87
	v_cmp_gt_u32_e64 s[50:51], s98, v88
	v_cndmask_b32_e64 v32, 0, v32, s[30:31]
	v_add_u32_e32 v85, 8, v84
	v_cmp_gt_u32_e64 s[30:31], s98, v85
	v_cndmask_b32_e64 v33, 0, v33, s[36:37]
	v_add_u32_e32 v86, 9, v84
	v_cmp_gt_u32_e64 s[36:37], s98, v86
	v_cndmask_b32_e64 v34, 0, v34, s[78:79]
	v_add_u32_e32 v87, 10, v84
	v_cmp_gt_u32_e64 s[78:79], s98, v87
	v_cndmask_b32_e64 v35, 0, v35, s[50:51]
	v_add_u32_e32 v88, 11, v84
	v_cmp_gt_u32_e64 s[50:51], s98, v88
	v_cndmask_b32_e64 v36, 0, v36, s[30:31]
	v_add_u32_e32 v85, 16, v84
	v_cmp_gt_u32_e64 s[30:31], s98, v85
	v_cndmask_b32_e64 v37, 0, v37, s[36:37]
	v_add_u32_e32 v86, 17, v84
	v_cmp_gt_u32_e64 s[36:37], s98, v86
	v_cndmask_b32_e64 v38, 0, v38, s[78:79]
	v_add_u32_e32 v87, 18, v84
	v_cmp_gt_u32_e64 s[78:79], s98, v87
	v_cndmask_b32_e64 v39, 0, v39, s[50:51]
	v_add_u32_e32 v88, 19, v84
	v_cmp_gt_u32_e64 s[50:51], s98, v88
	v_cndmask_b32_e64 v40, 0, v40, s[30:31]
	v_add_u32_e32 v85, 24, v84
	v_cmp_gt_u32_e64 s[30:31], s98, v85
	v_cndmask_b32_e64 v41, 0, v41, s[36:37]
	v_add_u32_e32 v86, 25, v84
	v_cmp_gt_u32_e64 s[36:37], s98, v86
	v_cndmask_b32_e64 v42, 0, v42, s[78:79]
	v_add_u32_e32 v87, 26, v84
	v_cmp_gt_u32_e64 s[78:79], s98, v87
	v_cndmask_b32_e64 v43, 0, v43, s[50:51]
	v_add_u32_e32 v88, 27, v84
	v_cmp_gt_u32_e64 s[50:51], s98, v88
	v_nop
	v_cndmask_b32_e64 v44, 0, v44, s[30:31]
	v_cndmask_b32_e64 v45, 0, v45, s[36:37]
	v_cndmask_b32_e64 v46, 0, v46, s[78:79]
	v_cndmask_b32_e64 v47, 0, v47, s[50:51]
	v_cvt_pk_bf16_f32 v64, v32, v33
	v_cvt_pk_bf16_f32 v65, v34, v35
	v_cvt_pk_bf16_f32 v66, v36, v37
	v_cvt_pk_bf16_f32 v67, v38, v39
	v_cvt_pk_bf16_f32 v68, v40, v41
	v_cvt_pk_bf16_f32 v69, v42, v43
	v_cvt_pk_bf16_f32 v70, v44, v45
	v_cvt_pk_bf16_f32 v71, v46, v47
	v_pk_add_f32 v[232:233], v[232:233], v[32:33]
	v_pk_add_f32 v[232:233], v[232:233], v[34:35]
	v_pk_add_f32 v[232:233], v[232:233], v[36:37]
	v_pk_add_f32 v[232:233], v[232:233], v[38:39]
	v_pk_add_f32 v[232:233], v[232:233], v[40:41]
	v_pk_add_f32 v[232:233], v[232:233], v[42:43]
	v_pk_add_f32 v[232:233], v[232:233], v[44:45]
	v_pk_add_f32 v[232:233], v[232:233], v[46:47]
	s_waitcnt lgkmcnt(12)
	v_mfma_f32_32x32x16_bf16 v[0:15], v[64:67], v[72:75], v[0:15]
	v_mfma_f32_32x32x16_bf16 v[16:31], v[64:67], v[76:79], v[16:31]
	v_mfma_f32_32x32x16_bf16 v[0:15], v[68:71], v[220:223], v[0:15]
	v_mfma_f32_32x32x16_bf16 v[16:31], v[68:71], v[224:227], v[16:31]
	s_add_i32 s90, s67, 0
	v_add_u32_e32 v80, s90, v239
	v_add_u32_e32 v83, s90, v240
	v_add_u32_e32 v99, s90, v241
	v_add_u32_e32 v253, s90, v242
	v_add_u32_e32 v254, s90, v101
	v_add_u32_e32 v255, s90, v150
	v_med3_i32 v80, v80, 0, s99
	v_med3_i32 v83, v83, 0, s99
	v_med3_i32 v99, v99, 0, s99
	v_med3_i32 v253, v253, 0, s99
	v_med3_i32 v254, v254, 0, s99
	v_med3_i32 v255, v255, 0, s99
	v_mad_u32_u24 v80, v80, s100, v252
	v_mad_u32_u24 v83, v83, s100, v252
	v_mad_u32_u24 v99, v99, s100, v252
	v_mad_u32_u24 v253, v253, s100, v252
	v_mad_u32_u24 v254, v254, s100, v153
	v_mad_u32_u24 v255, v255, s100, v153
	global_load_dwordx4 v[156:159], v80, s[82:83]
	global_load_dwordx4 v[160:163], v83, s[82:83]
	global_load_dwordx4 v[164:167], v99, s[82:83]
	global_load_dwordx4 v[168:171], v253, s[82:83]
	global_load_dwordx4 v[172:175], v254, s[82:83] offset:768
	global_load_dwordx4 v[176:179], v255, s[82:83] offset:768
	global_load_dwordx4 v[180:183], v254, s[82:83] offset:832
	global_load_dwordx4 v[184:187], v255, s[82:83] offset:832
	v_mov_b32_e32 v115, v229
	ds_read2_b32 v[32:33], v115 offset0:0 offset1:1
	ds_read2_b32 v[34:35], v115 offset0:2 offset1:3
	ds_read2_b32 v[36:37], v115 offset0:8 offset1:9
	ds_read2_b32 v[38:39], v115 offset0:10 offset1:11
	ds_read2_b32 v[40:41], v115 offset0:16 offset1:17
	ds_read2_b32 v[42:43], v115 offset0:18 offset1:19
	ds_read2_b32 v[44:45], v115 offset0:24 offset1:25
	ds_read2_b32 v[46:47], v115 offset0:26 offset1:27
	s_waitcnt lgkmcnt(0)
	v_mfma_f32_32x32x16_bf16 v[32:47], v[188:191], v[48:51], v[32:47]
	ds_read_b64_tr_b16 v[72:73], v231
	ds_read_b64_tr_b16 v[74:75], v231 offset:512
	ds_read_b64_tr_b16 v[76:77], v231 offset:2048
	ds_read_b64_tr_b16 v[78:79], v231 offset:2560
	ds_read_b64_tr_b16 v[220:221], v231 offset:1024
	ds_read_b64_tr_b16 v[222:223], v231 offset:1536
	ds_read_b64_tr_b16 v[224:225], v231 offset:3072
	ds_read_b64_tr_b16 v[226:227], v231 offset:3584
	s_waitcnt vmcnt(8)
	ds_write_b128 v247, v[116:119]
	ds_write_b128 v247, v[120:123] offset:1024
	ds_write_b128 v247, v[124:127] offset:2048
	ds_write_b128 v247, v[128:131] offset:3072
	ds_read_b128 v[116:119], v248
	ds_read_b128 v[120:123], v249
	ds_read_b128 v[124:127], v250
	ds_read_b128 v[128:131], v251
	ds_write_b128 v112, v[132:135]
	ds_write_b128 v112, v[136:139] offset:1024
	ds_write_b128 v112, v[140:143] offset:2048
	ds_write_b128 v112, v[144:147] offset:3072
	v_mfma_f32_32x32x16_bf16 v[32:47], v[192:195], v[52:55], v[32:47]
	v_mfma_f32_32x32x16_bf16 v[32:47], v[196:199], v[56:59], v[32:47]
	v_mfma_f32_32x32x16_bf16 v[32:47], v[200:203], v[60:63], v[32:47]
	s_nop 11
	v_exp_f32_e32 v32, v32
	v_exp_f32_e32 v33, v33
	v_exp_f32_e32 v34, v34
	v_exp_f32_e32 v35, v35
	v_exp_f32_e32 v36, v36
	v_exp_f32_e32 v37, v37
	v_exp_f32_e32 v38, v38
	v_exp_f32_e32 v39, v39
	v_exp_f32_e32 v40, v40
	v_exp_f32_e32 v41, v41
	v_exp_f32_e32 v42, v42
	v_exp_f32_e32 v43, v43
	v_exp_f32_e32 v44, v44
	v_exp_f32_e32 v45, v45
	v_exp_f32_e32 v46, v46
	v_exp_f32_e32 v47, v47
	s_add_i32 s90, s67, -256
	v_lshlrev_b32_e32 v84, 2, v107
	v_add_u32_e32 v84, s90, v84
	v_add_u32_e32 v85, 0, v84
	v_add_u32_e32 v86, 4, v84
	v_add_u32_e32 v87, 8, v84
	v_add_u32_e32 v88, 12, v84
	v_cmp_gt_u32_e64 s[30:31], s98, v85
	v_cmp_gt_u32_e64 s[36:37], s98, v86
	v_cmp_gt_u32_e64 s[78:79], s98, v87
	v_cmp_gt_u32_e64 s[50:51], s98, v88
	v_cndmask_b32_e64 v32, 0, v32, s[30:31]
	v_add_u32_e32 v85, 32, v84
	v_cmp_gt_u32_e64 s[30:31], s98, v85
	v_cndmask_b32_e64 v33, 0, v33, s[36:37]
	v_add_u32_e32 v86, 36, v84
	v_cmp_gt_u32_e64 s[36:37], s98, v86
	v_cndmask_b32_e64 v34, 0, v34, s[78:79]
	v_add_u32_e32 v87, 40, v84
	v_cmp_gt_u32_e64 s[78:79], s98, v87
	v_cndmask_b32_e64 v35, 0, v35, s[50:51]
	v_add_u32_e32 v88, 44, v84
	v_cmp_gt_u32_e64 s[50:51], s98, v88
	v_cndmask_b32_e64 v36, 0, v36, s[30:31]
	v_add_u32_e32 v85, 64, v84
	v_cmp_gt_u32_e64 s[30:31], s98, v85
	v_cndmask_b32_e64 v37, 0, v37, s[36:37]
	v_add_u32_e32 v86, 68, v84
	v_cmp_gt_u32_e64 s[36:37], s98, v86
	v_cndmask_b32_e64 v38, 0, v38, s[78:79]
	v_add_u32_e32 v87, 72, v84
	v_cmp_gt_u32_e64 s[78:79], s98, v87
	v_cndmask_b32_e64 v39, 0, v39, s[50:51]
	v_add_u32_e32 v88, 76, v84
	v_cmp_gt_u32_e64 s[50:51], s98, v88
	v_cndmask_b32_e64 v40, 0, v40, s[30:31]
	v_add_u32_e32 v85, 96, v84
	v_cmp_gt_u32_e64 s[30:31], s98, v85
	v_cndmask_b32_e64 v41, 0, v41, s[36:37]
	v_add_u32_e32 v86, 100, v84
	v_cmp_gt_u32_e64 s[36:37], s98, v86
	v_cndmask_b32_e64 v42, 0, v42, s[78:79]
	v_add_u32_e32 v87, 104, v84
	v_cmp_gt_u32_e64 s[78:79], s98, v87
	v_cndmask_b32_e64 v43, 0, v43, s[50:51]
	v_add_u32_e32 v88, 108, v84
	v_cmp_gt_u32_e64 s[50:51], s98, v88
	v_nop
	v_cndmask_b32_e64 v44, 0, v44, s[30:31]
	v_cndmask_b32_e64 v45, 0, v45, s[36:37]
	v_cndmask_b32_e64 v46, 0, v46, s[78:79]
	v_cndmask_b32_e64 v47, 0, v47, s[50:51]
	v_cvt_pk_bf16_f32 v64, v32, v33
	v_cvt_pk_bf16_f32 v65, v34, v35
	v_cvt_pk_bf16_f32 v66, v36, v37
	v_cvt_pk_bf16_f32 v67, v38, v39
	v_cvt_pk_bf16_f32 v68, v40, v41
	v_cvt_pk_bf16_f32 v69, v42, v43
	v_cvt_pk_bf16_f32 v70, v44, v45
	v_cvt_pk_bf16_f32 v71, v46, v47
	v_pk_add_f32 v[232:233], v[232:233], v[32:33]
	v_pk_add_f32 v[232:233], v[232:233], v[34:35]
	v_pk_add_f32 v[232:233], v[232:233], v[36:37]
	v_pk_add_f32 v[232:233], v[232:233], v[38:39]
	v_pk_add_f32 v[232:233], v[232:233], v[40:41]
	v_pk_add_f32 v[232:233], v[232:233], v[42:43]
	v_pk_add_f32 v[232:233], v[232:233], v[44:45]
	v_pk_add_f32 v[232:233], v[232:233], v[46:47]
	s_waitcnt lgkmcnt(12)
	v_mfma_f32_32x32x16_bf16 v[0:15], v[64:67], v[72:75], v[0:15]
	v_mfma_f32_32x32x16_bf16 v[16:31], v[64:67], v[76:79], v[16:31]
	v_mfma_f32_32x32x16_bf16 v[0:15], v[68:71], v[220:223], v[0:15]
	v_mfma_f32_32x32x16_bf16 v[16:31], v[68:71], v[224:227], v[16:31]
	s_add_i32 s90, s67, 128
	v_add_u32_e32 v80, s90, v239
	v_add_u32_e32 v83, s90, v240
	v_add_u32_e32 v99, s90, v241
	v_add_u32_e32 v253, s90, v242
	v_add_u32_e32 v254, s90, v101
	v_add_u32_e32 v255, s90, v150
	v_med3_i32 v80, v80, 0, s99
	v_med3_i32 v83, v83, 0, s99
	v_med3_i32 v99, v99, 0, s99
	v_med3_i32 v253, v253, 0, s99
	v_med3_i32 v254, v254, 0, s99
	v_med3_i32 v255, v255, 0, s99
	v_mad_u32_u24 v80, v80, s100, v252
	v_mad_u32_u24 v83, v83, s100, v252
	v_mad_u32_u24 v99, v99, s100, v252
	v_mad_u32_u24 v253, v253, s100, v252
	v_mad_u32_u24 v254, v254, s100, v153
	v_mad_u32_u24 v255, v255, s100, v153
	global_load_dwordx4 v[188:191], v80, s[82:83]
	global_load_dwordx4 v[192:195], v83, s[82:83]
	global_load_dwordx4 v[196:199], v99, s[82:83]
	global_load_dwordx4 v[200:203], v253, s[82:83]
	global_load_dwordx4 v[204:207], v254, s[82:83] offset:768
	global_load_dwordx4 v[208:211], v255, s[82:83] offset:768
	global_load_dwordx4 v[212:215], v254, s[82:83] offset:832
	global_load_dwordx4 v[216:219], v255, s[82:83] offset:832
	ds_read2_b32 v[32:33], v115 offset0:32 offset1:33
	ds_read2_b32 v[34:35], v115 offset0:34 offset1:35
	ds_read2_b32 v[36:37], v115 offset0:40 offset1:41
	ds_read2_b32 v[38:39], v115 offset0:42 offset1:43
	ds_read2_b32 v[40:41], v115 offset0:48 offset1:49
	ds_read2_b32 v[42:43], v115 offset0:50 offset1:51
	ds_read2_b32 v[44:45], v115 offset0:56 offset1:57
	ds_read2_b32 v[46:47], v115 offset0:58 offset1:59
	s_waitcnt lgkmcnt(0)
	v_mfma_f32_32x32x16_bf16 v[32:47], v[116:119], v[48:51], v[32:47]
	ds_read_b64_tr_b16 v[72:73], v231
	ds_read_b64_tr_b16 v[74:75], v231 offset:512
	ds_read_b64_tr_b16 v[76:77], v231 offset:2048
	ds_read_b64_tr_b16 v[78:79], v231 offset:2560
	ds_read_b64_tr_b16 v[220:221], v231 offset:1024
	ds_read_b64_tr_b16 v[222:223], v231 offset:1536
	ds_read_b64_tr_b16 v[224:225], v231 offset:3072
	ds_read_b64_tr_b16 v[226:227], v231 offset:3584
	s_waitcnt vmcnt(8)
	ds_write_b128 v247, v[156:159]
	ds_write_b128 v247, v[160:163] offset:1024
	ds_write_b128 v247, v[164:167] offset:2048
	ds_write_b128 v247, v[168:171] offset:3072
	ds_read_b128 v[156:159], v248
	ds_read_b128 v[160:163], v249
	ds_read_b128 v[164:167], v250
	ds_read_b128 v[168:171], v251
	ds_write_b128 v112, v[172:175]
	ds_write_b128 v112, v[176:179] offset:1024
	ds_write_b128 v112, v[180:183] offset:2048
	ds_write_b128 v112, v[184:187] offset:3072
	v_mfma_f32_32x32x16_bf16 v[32:47], v[120:123], v[52:55], v[32:47]
	v_mfma_f32_32x32x16_bf16 v[32:47], v[124:127], v[56:59], v[32:47]
	v_mfma_f32_32x32x16_bf16 v[32:47], v[128:131], v[60:63], v[32:47]
	s_nop 11
	v_exp_f32_e32 v32, v32
	v_exp_f32_e32 v33, v33
	v_exp_f32_e32 v34, v34
	v_exp_f32_e32 v35, v35
	v_exp_f32_e32 v36, v36
	v_exp_f32_e32 v37, v37
	v_exp_f32_e32 v38, v38
	v_exp_f32_e32 v39, v39
	v_exp_f32_e32 v40, v40
	v_exp_f32_e32 v41, v41
	v_exp_f32_e32 v42, v42
	v_exp_f32_e32 v43, v43
	v_exp_f32_e32 v44, v44
	v_exp_f32_e32 v45, v45
	v_exp_f32_e32 v46, v46
	v_exp_f32_e32 v47, v47
	s_add_i32 s90, s67, -128
	v_lshlrev_b32_e32 v84, 2, v107
	v_add_u32_e32 v84, s90, v84
	v_add_u32_e32 v85, 0, v84
	v_add_u32_e32 v86, 4, v84
	v_add_u32_e32 v87, 8, v84
	v_add_u32_e32 v88, 12, v84
	v_cmp_gt_u32_e64 s[30:31], s98, v85
	v_cmp_gt_u32_e64 s[36:37], s98, v86
	v_cmp_gt_u32_e64 s[78:79], s98, v87
	v_cmp_gt_u32_e64 s[50:51], s98, v88
	v_cndmask_b32_e64 v32, 0, v32, s[30:31]
	v_add_u32_e32 v85, 32, v84
	v_cmp_gt_u32_e64 s[30:31], s98, v85
	v_cndmask_b32_e64 v33, 0, v33, s[36:37]
	v_add_u32_e32 v86, 36, v84
	v_cmp_gt_u32_e64 s[36:37], s98, v86
	v_cndmask_b32_e64 v34, 0, v34, s[78:79]
	v_add_u32_e32 v87, 40, v84
	v_cmp_gt_u32_e64 s[78:79], s98, v87
	v_cndmask_b32_e64 v35, 0, v35, s[50:51]
	v_add_u32_e32 v88, 44, v84
	v_cmp_gt_u32_e64 s[50:51], s98, v88
	v_cndmask_b32_e64 v36, 0, v36, s[30:31]
	v_add_u32_e32 v85, 64, v84
	v_cmp_gt_u32_e64 s[30:31], s98, v85
	v_cndmask_b32_e64 v37, 0, v37, s[36:37]
	v_add_u32_e32 v86, 68, v84
	v_cmp_gt_u32_e64 s[36:37], s98, v86
	v_cndmask_b32_e64 v38, 0, v38, s[78:79]
	v_add_u32_e32 v87, 72, v84
	v_cmp_gt_u32_e64 s[78:79], s98, v87
	v_cndmask_b32_e64 v39, 0, v39, s[50:51]
	v_add_u32_e32 v88, 76, v84
	v_cmp_gt_u32_e64 s[50:51], s98, v88
	v_cndmask_b32_e64 v40, 0, v40, s[30:31]
	v_add_u32_e32 v85, 96, v84
	v_cmp_gt_u32_e64 s[30:31], s98, v85
	v_cndmask_b32_e64 v41, 0, v41, s[36:37]
	v_add_u32_e32 v86, 100, v84
	v_cmp_gt_u32_e64 s[36:37], s98, v86
	v_cndmask_b32_e64 v42, 0, v42, s[78:79]
	v_add_u32_e32 v87, 104, v84
	v_cmp_gt_u32_e64 s[78:79], s98, v87
	v_cndmask_b32_e64 v43, 0, v43, s[50:51]
	v_add_u32_e32 v88, 108, v84
	v_cmp_gt_u32_e64 s[50:51], s98, v88
	v_nop
	v_cndmask_b32_e64 v44, 0, v44, s[30:31]
	v_cndmask_b32_e64 v45, 0, v45, s[36:37]
	v_cndmask_b32_e64 v46, 0, v46, s[78:79]
	v_cndmask_b32_e64 v47, 0, v47, s[50:51]
	v_cvt_pk_bf16_f32 v64, v32, v33
	v_cvt_pk_bf16_f32 v65, v34, v35
	v_cvt_pk_bf16_f32 v66, v36, v37
	v_cvt_pk_bf16_f32 v67, v38, v39
	v_cvt_pk_bf16_f32 v68, v40, v41
	v_cvt_pk_bf16_f32 v69, v42, v43
	v_cvt_pk_bf16_f32 v70, v44, v45
	v_cvt_pk_bf16_f32 v71, v46, v47
	v_pk_add_f32 v[232:233], v[232:233], v[32:33]
	v_pk_add_f32 v[232:233], v[232:233], v[34:35]
	v_pk_add_f32 v[232:233], v[232:233], v[36:37]
	v_pk_add_f32 v[232:233], v[232:233], v[38:39]
	v_pk_add_f32 v[232:233], v[232:233], v[40:41]
	v_pk_add_f32 v[232:233], v[232:233], v[42:43]
	v_pk_add_f32 v[232:233], v[232:233], v[44:45]
	v_pk_add_f32 v[232:233], v[232:233], v[46:47]
	s_waitcnt lgkmcnt(12)
	v_mfma_f32_32x32x16_bf16 v[0:15], v[64:67], v[72:75], v[0:15]
	v_mfma_f32_32x32x16_bf16 v[16:31], v[64:67], v[76:79], v[16:31]
	v_mfma_f32_32x32x16_bf16 v[0:15], v[68:71], v[220:223], v[0:15]
	v_mfma_f32_32x32x16_bf16 v[16:31], v[68:71], v[224:227], v[16:31]
	s_add_i32 s90, s67, 256
	v_add_u32_e32 v80, s90, v239
	v_add_u32_e32 v83, s90, v240
	v_add_u32_e32 v99, s90, v241
	v_add_u32_e32 v253, s90, v242
	v_add_u32_e32 v254, s90, v101
	v_add_u32_e32 v255, s90, v150
	v_med3_i32 v80, v80, 0, s99
	v_med3_i32 v83, v83, 0, s99
	v_med3_i32 v99, v99, 0, s99
	v_med3_i32 v253, v253, 0, s99
	v_med3_i32 v254, v254, 0, s99
	v_med3_i32 v255, v255, 0, s99
	v_mad_u32_u24 v80, v80, s100, v252
	v_mad_u32_u24 v83, v83, s100, v252
	v_mad_u32_u24 v99, v99, s100, v252
	v_mad_u32_u24 v253, v253, s100, v252
	v_mad_u32_u24 v254, v254, s100, v153
	v_mad_u32_u24 v255, v255, s100, v153
	global_load_dwordx4 v[116:119], v80, s[82:83]
	global_load_dwordx4 v[120:123], v83, s[82:83]
	global_load_dwordx4 v[124:127], v99, s[82:83]
	global_load_dwordx4 v[128:131], v253, s[82:83]
	global_load_dwordx4 v[132:135], v254, s[82:83] offset:768
	global_load_dwordx4 v[136:139], v255, s[82:83] offset:768
	global_load_dwordx4 v[140:143], v254, s[82:83] offset:832
	global_load_dwordx4 v[144:147], v255, s[82:83] offset:832
	ds_read2_b32 v[32:33], v115 offset0:64 offset1:65
	ds_read2_b32 v[34:35], v115 offset0:66 offset1:67
	ds_read2_b32 v[36:37], v115 offset0:72 offset1:73
	ds_read2_b32 v[38:39], v115 offset0:74 offset1:75
	ds_read2_b32 v[40:41], v115 offset0:80 offset1:81
	ds_read2_b32 v[42:43], v115 offset0:82 offset1:83
	ds_read2_b32 v[44:45], v115 offset0:88 offset1:89
	ds_read2_b32 v[46:47], v115 offset0:90 offset1:91
	s_waitcnt lgkmcnt(0)
	v_mfma_f32_32x32x16_bf16 v[32:47], v[156:159], v[48:51], v[32:47]
	ds_read_b64_tr_b16 v[72:73], v231
	ds_read_b64_tr_b16 v[74:75], v231 offset:512
	ds_read_b64_tr_b16 v[76:77], v231 offset:2048
	ds_read_b64_tr_b16 v[78:79], v231 offset:2560
	ds_read_b64_tr_b16 v[220:221], v231 offset:1024
	ds_read_b64_tr_b16 v[222:223], v231 offset:1536
	ds_read_b64_tr_b16 v[224:225], v231 offset:3072
	ds_read_b64_tr_b16 v[226:227], v231 offset:3584
	s_waitcnt vmcnt(8)
	ds_write_b128 v247, v[188:191]
	ds_write_b128 v247, v[192:195] offset:1024
	ds_write_b128 v247, v[196:199] offset:2048
	ds_write_b128 v247, v[200:203] offset:3072
	ds_read_b128 v[188:191], v248
	ds_read_b128 v[192:195], v249
	ds_read_b128 v[196:199], v250
	ds_read_b128 v[200:203], v251
	ds_write_b128 v112, v[204:207]
	ds_write_b128 v112, v[208:211] offset:1024
	ds_write_b128 v112, v[212:215] offset:2048
	ds_write_b128 v112, v[216:219] offset:3072
	v_mfma_f32_32x32x16_bf16 v[32:47], v[160:163], v[52:55], v[32:47]
	v_mfma_f32_32x32x16_bf16 v[32:47], v[164:167], v[56:59], v[32:47]
	v_mfma_f32_32x32x16_bf16 v[32:47], v[168:171], v[60:63], v[32:47]
	s_nop 11
	v_exp_f32_e32 v32, v32
	v_exp_f32_e32 v33, v33
	v_exp_f32_e32 v34, v34
	v_exp_f32_e32 v35, v35
	v_exp_f32_e32 v36, v36
	v_exp_f32_e32 v37, v37
	v_exp_f32_e32 v38, v38
	v_exp_f32_e32 v39, v39
	v_exp_f32_e32 v40, v40
	v_exp_f32_e32 v41, v41
	v_exp_f32_e32 v42, v42
	v_exp_f32_e32 v43, v43
	v_exp_f32_e32 v44, v44
	v_exp_f32_e32 v45, v45
	v_exp_f32_e32 v46, v46
	v_exp_f32_e32 v47, v47
	s_add_i32 s90, s67, 0
	v_lshlrev_b32_e32 v84, 2, v107
	v_add_u32_e32 v84, s90, v84
	v_add_u32_e32 v85, 0, v84
	v_add_u32_e32 v86, 4, v84
	v_add_u32_e32 v87, 8, v84
	v_add_u32_e32 v88, 12, v84
	v_cmp_gt_u32_e64 s[30:31], s98, v85
	v_cmp_gt_u32_e64 s[36:37], s98, v86
	v_cmp_gt_u32_e64 s[78:79], s98, v87
	v_cmp_gt_u32_e64 s[50:51], s98, v88
	v_cndmask_b32_e64 v32, 0, v32, s[30:31]
	v_add_u32_e32 v85, 32, v84
	v_cmp_gt_u32_e64 s[30:31], s98, v85
	v_cndmask_b32_e64 v33, 0, v33, s[36:37]
	v_add_u32_e32 v86, 36, v84
	v_cmp_gt_u32_e64 s[36:37], s98, v86
	v_cndmask_b32_e64 v34, 0, v34, s[78:79]
	v_add_u32_e32 v87, 40, v84
	v_cmp_gt_u32_e64 s[78:79], s98, v87
	v_cndmask_b32_e64 v35, 0, v35, s[50:51]
	v_add_u32_e32 v88, 44, v84
	v_cmp_gt_u32_e64 s[50:51], s98, v88
	v_cndmask_b32_e64 v36, 0, v36, s[30:31]
	v_add_u32_e32 v85, 64, v84
	v_cmp_gt_u32_e64 s[30:31], s98, v85
	v_cndmask_b32_e64 v37, 0, v37, s[36:37]
	v_add_u32_e32 v86, 68, v84
	v_cmp_gt_u32_e64 s[36:37], s98, v86
	v_cndmask_b32_e64 v38, 0, v38, s[78:79]
	v_add_u32_e32 v87, 72, v84
	v_cmp_gt_u32_e64 s[78:79], s98, v87
	v_cndmask_b32_e64 v39, 0, v39, s[50:51]
	v_add_u32_e32 v88, 76, v84
	v_cmp_gt_u32_e64 s[50:51], s98, v88
	v_cndmask_b32_e64 v40, 0, v40, s[30:31]
	v_add_u32_e32 v85, 96, v84
	v_cmp_gt_u32_e64 s[30:31], s98, v85
	v_cndmask_b32_e64 v41, 0, v41, s[36:37]
	v_add_u32_e32 v86, 100, v84
	v_cmp_gt_u32_e64 s[36:37], s98, v86
	v_cndmask_b32_e64 v42, 0, v42, s[78:79]
	v_add_u32_e32 v87, 104, v84
	v_cmp_gt_u32_e64 s[78:79], s98, v87
	v_cndmask_b32_e64 v43, 0, v43, s[50:51]
	v_add_u32_e32 v88, 108, v84
	v_cmp_gt_u32_e64 s[50:51], s98, v88
	v_nop
	v_cndmask_b32_e64 v44, 0, v44, s[30:31]
	v_cndmask_b32_e64 v45, 0, v45, s[36:37]
	v_cndmask_b32_e64 v46, 0, v46, s[78:79]
	v_cndmask_b32_e64 v47, 0, v47, s[50:51]
	v_cvt_pk_bf16_f32 v64, v32, v33
	v_cvt_pk_bf16_f32 v65, v34, v35
	v_cvt_pk_bf16_f32 v66, v36, v37
	v_cvt_pk_bf16_f32 v67, v38, v39
	v_cvt_pk_bf16_f32 v68, v40, v41
	v_cvt_pk_bf16_f32 v69, v42, v43
	v_cvt_pk_bf16_f32 v70, v44, v45
	v_cvt_pk_bf16_f32 v71, v46, v47
	v_pk_add_f32 v[232:233], v[232:233], v[32:33]
	v_pk_add_f32 v[232:233], v[232:233], v[34:35]
	v_pk_add_f32 v[232:233], v[232:233], v[36:37]
	v_pk_add_f32 v[232:233], v[232:233], v[38:39]
	v_pk_add_f32 v[232:233], v[232:233], v[40:41]
	v_pk_add_f32 v[232:233], v[232:233], v[42:43]
	v_pk_add_f32 v[232:233], v[232:233], v[44:45]
	v_pk_add_f32 v[232:233], v[232:233], v[46:47]
	s_waitcnt lgkmcnt(12)
	v_mfma_f32_32x32x16_bf16 v[0:15], v[64:67], v[72:75], v[0:15]
	v_mfma_f32_32x32x16_bf16 v[16:31], v[64:67], v[76:79], v[16:31]
	v_mfma_f32_32x32x16_bf16 v[0:15], v[68:71], v[220:223], v[0:15]
	v_mfma_f32_32x32x16_bf16 v[16:31], v[68:71], v[224:227], v[16:31]
	s_add_i32 s90, s67, 384
	v_add_u32_e32 v80, s90, v239
	v_add_u32_e32 v83, s90, v240
	v_add_u32_e32 v99, s90, v241
	v_add_u32_e32 v253, s90, v242
	v_add_u32_e32 v254, s90, v101
	v_add_u32_e32 v255, s90, v150
	v_med3_i32 v80, v80, 0, s99
	v_med3_i32 v83, v83, 0, s99
	v_med3_i32 v99, v99, 0, s99
	v_med3_i32 v253, v253, 0, s99
	v_med3_i32 v254, v254, 0, s99
	v_med3_i32 v255, v255, 0, s99
	v_mad_u32_u24 v80, v80, s100, v252
	v_mad_u32_u24 v83, v83, s100, v252
	v_mad_u32_u24 v99, v99, s100, v252
	v_mad_u32_u24 v253, v253, s100, v252
	v_mad_u32_u24 v254, v254, s100, v153
	v_mad_u32_u24 v255, v255, s100, v153
	global_load_dwordx4 v[156:159], v80, s[82:83]
	global_load_dwordx4 v[160:163], v83, s[82:83]
	global_load_dwordx4 v[164:167], v99, s[82:83]
	global_load_dwordx4 v[168:171], v253, s[82:83]
	global_load_dwordx4 v[172:175], v254, s[82:83] offset:768
	global_load_dwordx4 v[176:179], v255, s[82:83] offset:768
	global_load_dwordx4 v[180:183], v254, s[82:83] offset:832
	global_load_dwordx4 v[184:187], v255, s[82:83] offset:832
	ds_read2_b32 v[32:33], v115 offset0:96 offset1:97
	ds_read2_b32 v[34:35], v115 offset0:98 offset1:99
	ds_read2_b32 v[36:37], v115 offset0:104 offset1:105
	ds_read2_b32 v[38:39], v115 offset0:106 offset1:107
	ds_read2_b32 v[40:41], v115 offset0:112 offset1:113
	ds_read2_b32 v[42:43], v115 offset0:114 offset1:115
	ds_read2_b32 v[44:45], v115 offset0:120 offset1:121
	ds_read2_b32 v[46:47], v115 offset0:122 offset1:123
	s_waitcnt lgkmcnt(0)
	v_mfma_f32_32x32x16_bf16 v[32:47], v[188:191], v[48:51], v[32:47]
	ds_read_b64_tr_b16 v[72:73], v231
	ds_read_b64_tr_b16 v[74:75], v231 offset:512
	ds_read_b64_tr_b16 v[76:77], v231 offset:2048
	ds_read_b64_tr_b16 v[78:79], v231 offset:2560
	ds_read_b64_tr_b16 v[220:221], v231 offset:1024
	ds_read_b64_tr_b16 v[222:223], v231 offset:1536
	ds_read_b64_tr_b16 v[224:225], v231 offset:3072
	ds_read_b64_tr_b16 v[226:227], v231 offset:3584
	s_waitcnt vmcnt(8)
	ds_write_b128 v247, v[116:119]
	ds_write_b128 v247, v[120:123] offset:1024
	ds_write_b128 v247, v[124:127] offset:2048
	ds_write_b128 v247, v[128:131] offset:3072
	ds_read_b128 v[116:119], v248
	ds_read_b128 v[120:123], v249
	ds_read_b128 v[124:127], v250
	ds_read_b128 v[128:131], v251
	ds_write_b128 v112, v[132:135]
	ds_write_b128 v112, v[136:139] offset:1024
	ds_write_b128 v112, v[140:143] offset:2048
	ds_write_b128 v112, v[144:147] offset:3072
	v_mfma_f32_32x32x16_bf16 v[32:47], v[192:195], v[52:55], v[32:47]
	v_mfma_f32_32x32x16_bf16 v[32:47], v[196:199], v[56:59], v[32:47]
	v_mfma_f32_32x32x16_bf16 v[32:47], v[200:203], v[60:63], v[32:47]
	s_nop 11
	v_exp_f32_e32 v32, v32
	v_exp_f32_e32 v33, v33
	v_exp_f32_e32 v34, v34
	v_exp_f32_e32 v35, v35
	v_exp_f32_e32 v36, v36
	v_exp_f32_e32 v37, v37
	v_exp_f32_e32 v38, v38
	v_exp_f32_e32 v39, v39
	v_exp_f32_e32 v40, v40
	v_exp_f32_e32 v41, v41
	v_exp_f32_e32 v42, v42
	v_exp_f32_e32 v43, v43
	v_exp_f32_e32 v44, v44
	v_exp_f32_e32 v45, v45
	v_exp_f32_e32 v46, v46
	v_exp_f32_e32 v47, v47
	s_add_i32 s90, s67, 128
	v_lshlrev_b32_e32 v84, 2, v107
	v_add_u32_e32 v84, s90, v84
	v_add_u32_e32 v85, 0, v84
	v_add_u32_e32 v86, 4, v84
	v_add_u32_e32 v87, 8, v84
	v_add_u32_e32 v88, 12, v84
	v_cmp_gt_u32_e64 s[30:31], s98, v85
	v_cmp_gt_u32_e64 s[36:37], s98, v86
	v_cmp_gt_u32_e64 s[78:79], s98, v87
	v_cmp_gt_u32_e64 s[50:51], s98, v88
	v_cndmask_b32_e64 v32, 0, v32, s[30:31]
	v_add_u32_e32 v85, 32, v84
	v_cmp_gt_u32_e64 s[30:31], s98, v85
	v_cndmask_b32_e64 v33, 0, v33, s[36:37]
	v_add_u32_e32 v86, 36, v84
	v_cmp_gt_u32_e64 s[36:37], s98, v86
	v_cndmask_b32_e64 v34, 0, v34, s[78:79]
	v_add_u32_e32 v87, 40, v84
	v_cmp_gt_u32_e64 s[78:79], s98, v87
	v_cndmask_b32_e64 v35, 0, v35, s[50:51]
	v_add_u32_e32 v88, 44, v84
	v_cmp_gt_u32_e64 s[50:51], s98, v88
	v_cndmask_b32_e64 v36, 0, v36, s[30:31]
	v_add_u32_e32 v85, 64, v84
	v_cmp_gt_u32_e64 s[30:31], s98, v85
	v_cndmask_b32_e64 v37, 0, v37, s[36:37]
	v_add_u32_e32 v86, 68, v84
	v_cmp_gt_u32_e64 s[36:37], s98, v86
	v_cndmask_b32_e64 v38, 0, v38, s[78:79]
	v_add_u32_e32 v87, 72, v84
	v_cmp_gt_u32_e64 s[78:79], s98, v87
	v_cndmask_b32_e64 v39, 0, v39, s[50:51]
	v_add_u32_e32 v88, 76, v84
	v_cmp_gt_u32_e64 s[50:51], s98, v88
	v_cndmask_b32_e64 v40, 0, v40, s[30:31]
	v_add_u32_e32 v85, 96, v84
	v_cmp_gt_u32_e64 s[30:31], s98, v85
	v_cndmask_b32_e64 v41, 0, v41, s[36:37]
	v_add_u32_e32 v86, 100, v84
	v_cmp_gt_u32_e64 s[36:37], s98, v86
	v_cndmask_b32_e64 v42, 0, v42, s[78:79]
	v_add_u32_e32 v87, 104, v84
	v_cmp_gt_u32_e64 s[78:79], s98, v87
	v_cndmask_b32_e64 v43, 0, v43, s[50:51]
	v_add_u32_e32 v88, 108, v84
	v_cmp_gt_u32_e64 s[50:51], s98, v88
	v_nop
	v_cndmask_b32_e64 v44, 0, v44, s[30:31]
	v_cndmask_b32_e64 v45, 0, v45, s[36:37]
	v_cndmask_b32_e64 v46, 0, v46, s[78:79]
	v_cndmask_b32_e64 v47, 0, v47, s[50:51]
	v_cvt_pk_bf16_f32 v64, v32, v33
	v_cvt_pk_bf16_f32 v65, v34, v35
	v_cvt_pk_bf16_f32 v66, v36, v37
	v_cvt_pk_bf16_f32 v67, v38, v39
	v_cvt_pk_bf16_f32 v68, v40, v41
	v_cvt_pk_bf16_f32 v69, v42, v43
	v_cvt_pk_bf16_f32 v70, v44, v45
	v_cvt_pk_bf16_f32 v71, v46, v47
	v_pk_add_f32 v[232:233], v[232:233], v[32:33]
	v_pk_add_f32 v[232:233], v[232:233], v[34:35]
	v_pk_add_f32 v[232:233], v[232:233], v[36:37]
	v_pk_add_f32 v[232:233], v[232:233], v[38:39]
	v_pk_add_f32 v[232:233], v[232:233], v[40:41]
	v_pk_add_f32 v[232:233], v[232:233], v[42:43]
	v_pk_add_f32 v[232:233], v[232:233], v[44:45]
	v_pk_add_f32 v[232:233], v[232:233], v[46:47]
	s_waitcnt lgkmcnt(12)
	v_mfma_f32_32x32x16_bf16 v[0:15], v[64:67], v[72:75], v[0:15]
	v_mfma_f32_32x32x16_bf16 v[16:31], v[64:67], v[76:79], v[16:31]
	v_mfma_f32_32x32x16_bf16 v[0:15], v[68:71], v[220:223], v[0:15]
	v_mfma_f32_32x32x16_bf16 v[16:31], v[68:71], v[224:227], v[16:31]
	s_add_i32 s90, s67, 512
	v_add_u32_e32 v80, s90, v239
	v_add_u32_e32 v83, s90, v240
	v_add_u32_e32 v99, s90, v241
	v_add_u32_e32 v253, s90, v242
	v_add_u32_e32 v254, s90, v101
	v_add_u32_e32 v255, s90, v150
	v_med3_i32 v80, v80, 0, s99
	v_med3_i32 v83, v83, 0, s99
	v_med3_i32 v99, v99, 0, s99
	v_med3_i32 v253, v253, 0, s99
	v_med3_i32 v254, v254, 0, s99
	v_med3_i32 v255, v255, 0, s99
	v_mad_u32_u24 v80, v80, s100, v252
	v_mad_u32_u24 v83, v83, s100, v252
	v_mad_u32_u24 v99, v99, s100, v252
	v_mad_u32_u24 v253, v253, s100, v252
	v_mad_u32_u24 v254, v254, s100, v153
	v_mad_u32_u24 v255, v255, s100, v153
	global_load_dwordx4 v[188:191], v80, s[82:83]
	global_load_dwordx4 v[192:195], v83, s[82:83]
	global_load_dwordx4 v[196:199], v99, s[82:83]
	global_load_dwordx4 v[200:203], v253, s[82:83]
	global_load_dwordx4 v[204:207], v254, s[82:83] offset:768
	global_load_dwordx4 v[208:211], v255, s[82:83] offset:768
	global_load_dwordx4 v[212:215], v254, s[82:83] offset:832
	global_load_dwordx4 v[216:219], v255, s[82:83] offset:832
	ds_read2_b32 v[32:33], v115 offset0:128 offset1:129
	ds_read2_b32 v[34:35], v115 offset0:130 offset1:131
	ds_read2_b32 v[36:37], v115 offset0:136 offset1:137
	ds_read2_b32 v[38:39], v115 offset0:138 offset1:139
	ds_read2_b32 v[40:41], v115 offset0:144 offset1:145
	ds_read2_b32 v[42:43], v115 offset0:146 offset1:147
	ds_read2_b32 v[44:45], v115 offset0:152 offset1:153
	ds_read2_b32 v[46:47], v115 offset0:154 offset1:155
	s_waitcnt lgkmcnt(0)
	v_mfma_f32_32x32x16_bf16 v[32:47], v[116:119], v[48:51], v[32:47]
	ds_read_b64_tr_b16 v[72:73], v231
	ds_read_b64_tr_b16 v[74:75], v231 offset:512
	ds_read_b64_tr_b16 v[76:77], v231 offset:2048
	ds_read_b64_tr_b16 v[78:79], v231 offset:2560
	ds_read_b64_tr_b16 v[220:221], v231 offset:1024
	ds_read_b64_tr_b16 v[222:223], v231 offset:1536
	ds_read_b64_tr_b16 v[224:225], v231 offset:3072
	ds_read_b64_tr_b16 v[226:227], v231 offset:3584
	s_waitcnt vmcnt(8)
	ds_write_b128 v247, v[156:159]
	ds_write_b128 v247, v[160:163] offset:1024
	ds_write_b128 v247, v[164:167] offset:2048
	ds_write_b128 v247, v[168:171] offset:3072
	ds_read_b128 v[156:159], v248
	ds_read_b128 v[160:163], v249
	ds_read_b128 v[164:167], v250
	ds_read_b128 v[168:171], v251
	ds_write_b128 v112, v[172:175]
	ds_write_b128 v112, v[176:179] offset:1024
	ds_write_b128 v112, v[180:183] offset:2048
	ds_write_b128 v112, v[184:187] offset:3072
	v_mfma_f32_32x32x16_bf16 v[32:47], v[120:123], v[52:55], v[32:47]
	v_mfma_f32_32x32x16_bf16 v[32:47], v[124:127], v[56:59], v[32:47]
	v_mfma_f32_32x32x16_bf16 v[32:47], v[128:131], v[60:63], v[32:47]
	s_nop 11
	v_exp_f32_e32 v32, v32
	v_exp_f32_e32 v33, v33
	v_exp_f32_e32 v34, v34
	v_exp_f32_e32 v35, v35
	v_exp_f32_e32 v36, v36
	v_exp_f32_e32 v37, v37
	v_exp_f32_e32 v38, v38
	v_exp_f32_e32 v39, v39
	v_exp_f32_e32 v40, v40
	v_exp_f32_e32 v41, v41
	v_exp_f32_e32 v42, v42
	v_exp_f32_e32 v43, v43
	v_exp_f32_e32 v44, v44
	v_exp_f32_e32 v45, v45
	v_exp_f32_e32 v46, v46
	v_exp_f32_e32 v47, v47
	s_add_i32 s90, s67, 256
	v_lshlrev_b32_e32 v84, 2, v107
	v_add_u32_e32 v84, s90, v84
	v_add_u32_e32 v85, 0, v84
	v_add_u32_e32 v86, 4, v84
	v_add_u32_e32 v87, 8, v84
	v_add_u32_e32 v88, 12, v84
	v_cmp_gt_u32_e64 s[30:31], s98, v85
	v_cmp_gt_u32_e64 s[36:37], s98, v86
	v_cmp_gt_u32_e64 s[78:79], s98, v87
	v_cmp_gt_u32_e64 s[50:51], s98, v88
	v_cndmask_b32_e64 v32, 0, v32, s[30:31]
	v_add_u32_e32 v85, 32, v84
	v_cmp_gt_u32_e64 s[30:31], s98, v85
	v_cndmask_b32_e64 v33, 0, v33, s[36:37]
	v_add_u32_e32 v86, 36, v84
	v_cmp_gt_u32_e64 s[36:37], s98, v86
	v_cndmask_b32_e64 v34, 0, v34, s[78:79]
	v_add_u32_e32 v87, 40, v84
	v_cmp_gt_u32_e64 s[78:79], s98, v87
	v_cndmask_b32_e64 v35, 0, v35, s[50:51]
	v_add_u32_e32 v88, 44, v84
	v_cmp_gt_u32_e64 s[50:51], s98, v88
	v_cndmask_b32_e64 v36, 0, v36, s[30:31]
	v_add_u32_e32 v85, 64, v84
	v_cmp_gt_u32_e64 s[30:31], s98, v85
	v_cndmask_b32_e64 v37, 0, v37, s[36:37]
	v_add_u32_e32 v86, 68, v84
	v_cmp_gt_u32_e64 s[36:37], s98, v86
	v_cndmask_b32_e64 v38, 0, v38, s[78:79]
	v_add_u32_e32 v87, 72, v84
	v_cmp_gt_u32_e64 s[78:79], s98, v87
	v_cndmask_b32_e64 v39, 0, v39, s[50:51]
	v_add_u32_e32 v88, 76, v84
	v_cmp_gt_u32_e64 s[50:51], s98, v88
	v_cndmask_b32_e64 v40, 0, v40, s[30:31]
	v_add_u32_e32 v85, 96, v84
	v_cmp_gt_u32_e64 s[30:31], s98, v85
	v_cndmask_b32_e64 v41, 0, v41, s[36:37]
	v_add_u32_e32 v86, 100, v84
	v_cmp_gt_u32_e64 s[36:37], s98, v86
	v_cndmask_b32_e64 v42, 0, v42, s[78:79]
	v_add_u32_e32 v87, 104, v84
	v_cmp_gt_u32_e64 s[78:79], s98, v87
	v_cndmask_b32_e64 v43, 0, v43, s[50:51]
	v_add_u32_e32 v88, 108, v84
	v_cmp_gt_u32_e64 s[50:51], s98, v88
	v_nop
	v_cndmask_b32_e64 v44, 0, v44, s[30:31]
	v_cndmask_b32_e64 v45, 0, v45, s[36:37]
	v_cndmask_b32_e64 v46, 0, v46, s[78:79]
	v_cndmask_b32_e64 v47, 0, v47, s[50:51]
	v_cvt_pk_bf16_f32 v64, v32, v33
	v_cvt_pk_bf16_f32 v65, v34, v35
	v_cvt_pk_bf16_f32 v66, v36, v37
	v_cvt_pk_bf16_f32 v67, v38, v39
	v_cvt_pk_bf16_f32 v68, v40, v41
	v_cvt_pk_bf16_f32 v69, v42, v43
	v_cvt_pk_bf16_f32 v70, v44, v45
	v_cvt_pk_bf16_f32 v71, v46, v47
	v_pk_add_f32 v[232:233], v[232:233], v[32:33]
	v_pk_add_f32 v[232:233], v[232:233], v[34:35]
	v_pk_add_f32 v[232:233], v[232:233], v[36:37]
	v_pk_add_f32 v[232:233], v[232:233], v[38:39]
	v_pk_add_f32 v[232:233], v[232:233], v[40:41]
	v_pk_add_f32 v[232:233], v[232:233], v[42:43]
	v_pk_add_f32 v[232:233], v[232:233], v[44:45]
	v_pk_add_f32 v[232:233], v[232:233], v[46:47]
	s_waitcnt lgkmcnt(12)
	v_mfma_f32_32x32x16_bf16 v[0:15], v[64:67], v[72:75], v[0:15]
	v_mfma_f32_32x32x16_bf16 v[16:31], v[64:67], v[76:79], v[16:31]
	v_mfma_f32_32x32x16_bf16 v[0:15], v[68:71], v[220:223], v[0:15]
	v_mfma_f32_32x32x16_bf16 v[16:31], v[68:71], v[224:227], v[16:31]
	s_add_i32 s90, s67, 640
	v_add_u32_e32 v80, s90, v239
	v_add_u32_e32 v83, s90, v240
	v_add_u32_e32 v99, s90, v241
	v_add_u32_e32 v253, s90, v242
	v_add_u32_e32 v254, s90, v101
	v_add_u32_e32 v255, s90, v150
	v_med3_i32 v80, v80, 0, s99
	v_med3_i32 v83, v83, 0, s99
	v_med3_i32 v99, v99, 0, s99
	v_med3_i32 v253, v253, 0, s99
	v_med3_i32 v254, v254, 0, s99
	v_med3_i32 v255, v255, 0, s99
	v_mad_u32_u24 v80, v80, s100, v252
	v_mad_u32_u24 v83, v83, s100, v252
	v_mad_u32_u24 v99, v99, s100, v252
	v_mad_u32_u24 v253, v253, s100, v252
	v_mad_u32_u24 v254, v254, s100, v153
	v_mad_u32_u24 v255, v255, s100, v153
	global_load_dwordx4 v[116:119], v80, s[82:83]
	global_load_dwordx4 v[120:123], v83, s[82:83]
	global_load_dwordx4 v[124:127], v99, s[82:83]
	global_load_dwordx4 v[128:131], v253, s[82:83]
	global_load_dwordx4 v[132:135], v254, s[82:83] offset:768
	global_load_dwordx4 v[136:139], v255, s[82:83] offset:768
	global_load_dwordx4 v[140:143], v254, s[82:83] offset:832
	global_load_dwordx4 v[144:147], v255, s[82:83] offset:832
	ds_read2_b32 v[32:33], v115 offset0:160 offset1:161
	ds_read2_b32 v[34:35], v115 offset0:162 offset1:163
	ds_read2_b32 v[36:37], v115 offset0:168 offset1:169
	ds_read2_b32 v[38:39], v115 offset0:170 offset1:171
	ds_read2_b32 v[40:41], v115 offset0:176 offset1:177
	ds_read2_b32 v[42:43], v115 offset0:178 offset1:179
	ds_read2_b32 v[44:45], v115 offset0:184 offset1:185
	ds_read2_b32 v[46:47], v115 offset0:186 offset1:187
	s_waitcnt lgkmcnt(0)
	v_mfma_f32_32x32x16_bf16 v[32:47], v[156:159], v[48:51], v[32:47]
	ds_read_b64_tr_b16 v[72:73], v231
	ds_read_b64_tr_b16 v[74:75], v231 offset:512
	ds_read_b64_tr_b16 v[76:77], v231 offset:2048
	ds_read_b64_tr_b16 v[78:79], v231 offset:2560
	ds_read_b64_tr_b16 v[220:221], v231 offset:1024
	ds_read_b64_tr_b16 v[222:223], v231 offset:1536
	ds_read_b64_tr_b16 v[224:225], v231 offset:3072
	ds_read_b64_tr_b16 v[226:227], v231 offset:3584
	s_waitcnt vmcnt(8)
	ds_write_b128 v247, v[188:191]
	ds_write_b128 v247, v[192:195] offset:1024
	ds_write_b128 v247, v[196:199] offset:2048
	ds_write_b128 v247, v[200:203] offset:3072
	ds_read_b128 v[188:191], v248
	ds_read_b128 v[192:195], v249
	ds_read_b128 v[196:199], v250
	ds_read_b128 v[200:203], v251
	ds_write_b128 v112, v[204:207]
	ds_write_b128 v112, v[208:211] offset:1024
	ds_write_b128 v112, v[212:215] offset:2048
	ds_write_b128 v112, v[216:219] offset:3072
	v_mfma_f32_32x32x16_bf16 v[32:47], v[160:163], v[52:55], v[32:47]
	v_mfma_f32_32x32x16_bf16 v[32:47], v[164:167], v[56:59], v[32:47]
	v_mfma_f32_32x32x16_bf16 v[32:47], v[168:171], v[60:63], v[32:47]
	s_nop 11
	v_exp_f32_e32 v32, v32
	v_exp_f32_e32 v33, v33
	v_exp_f32_e32 v34, v34
	v_exp_f32_e32 v35, v35
	v_exp_f32_e32 v36, v36
	v_exp_f32_e32 v37, v37
	v_exp_f32_e32 v38, v38
	v_exp_f32_e32 v39, v39
	v_exp_f32_e32 v40, v40
	v_exp_f32_e32 v41, v41
	v_exp_f32_e32 v42, v42
	v_exp_f32_e32 v43, v43
	v_exp_f32_e32 v44, v44
	v_exp_f32_e32 v45, v45
	v_exp_f32_e32 v46, v46
	v_exp_f32_e32 v47, v47
	s_add_i32 s90, s67, 384
	v_lshlrev_b32_e32 v84, 2, v107
	v_add_u32_e32 v84, s90, v84
	v_add_u32_e32 v85, 0, v84
	v_add_u32_e32 v86, 4, v84
	v_add_u32_e32 v87, 8, v84
	v_add_u32_e32 v88, 12, v84
	v_cmp_gt_u32_e64 s[30:31], s98, v85
	v_cmp_gt_u32_e64 s[36:37], s98, v86
	v_cmp_gt_u32_e64 s[78:79], s98, v87
	v_cmp_gt_u32_e64 s[50:51], s98, v88
	v_cndmask_b32_e64 v32, 0, v32, s[30:31]
	v_add_u32_e32 v85, 32, v84
	v_cmp_gt_u32_e64 s[30:31], s98, v85
	v_cndmask_b32_e64 v33, 0, v33, s[36:37]
	v_add_u32_e32 v86, 36, v84
	v_cmp_gt_u32_e64 s[36:37], s98, v86
	v_cndmask_b32_e64 v34, 0, v34, s[78:79]
	v_add_u32_e32 v87, 40, v84
	v_cmp_gt_u32_e64 s[78:79], s98, v87
	v_cndmask_b32_e64 v35, 0, v35, s[50:51]
	v_add_u32_e32 v88, 44, v84
	v_cmp_gt_u32_e64 s[50:51], s98, v88
	v_cndmask_b32_e64 v36, 0, v36, s[30:31]
	v_add_u32_e32 v85, 64, v84
	v_cmp_gt_u32_e64 s[30:31], s98, v85
	v_cndmask_b32_e64 v37, 0, v37, s[36:37]
	v_add_u32_e32 v86, 68, v84
	v_cmp_gt_u32_e64 s[36:37], s98, v86
	v_cndmask_b32_e64 v38, 0, v38, s[78:79]
	v_add_u32_e32 v87, 72, v84
	v_cmp_gt_u32_e64 s[78:79], s98, v87
	v_cndmask_b32_e64 v39, 0, v39, s[50:51]
	v_add_u32_e32 v88, 76, v84
	v_cmp_gt_u32_e64 s[50:51], s98, v88
	v_cndmask_b32_e64 v40, 0, v40, s[30:31]
	v_add_u32_e32 v85, 96, v84
	v_cmp_gt_u32_e64 s[30:31], s98, v85
	v_cndmask_b32_e64 v41, 0, v41, s[36:37]
	v_add_u32_e32 v86, 100, v84
	v_cmp_gt_u32_e64 s[36:37], s98, v86
	v_cndmask_b32_e64 v42, 0, v42, s[78:79]
	v_add_u32_e32 v87, 104, v84
	v_cmp_gt_u32_e64 s[78:79], s98, v87
	v_cndmask_b32_e64 v43, 0, v43, s[50:51]
	v_add_u32_e32 v88, 108, v84
	v_cmp_gt_u32_e64 s[50:51], s98, v88
	v_nop
	v_cndmask_b32_e64 v44, 0, v44, s[30:31]
	v_cndmask_b32_e64 v45, 0, v45, s[36:37]
	v_cndmask_b32_e64 v46, 0, v46, s[78:79]
	v_cndmask_b32_e64 v47, 0, v47, s[50:51]
	v_cvt_pk_bf16_f32 v64, v32, v33
	v_cvt_pk_bf16_f32 v65, v34, v35
	v_cvt_pk_bf16_f32 v66, v36, v37
	v_cvt_pk_bf16_f32 v67, v38, v39
	v_cvt_pk_bf16_f32 v68, v40, v41
	v_cvt_pk_bf16_f32 v69, v42, v43
	v_cvt_pk_bf16_f32 v70, v44, v45
	v_cvt_pk_bf16_f32 v71, v46, v47
	v_pk_add_f32 v[232:233], v[232:233], v[32:33]
	v_pk_add_f32 v[232:233], v[232:233], v[34:35]
	v_pk_add_f32 v[232:233], v[232:233], v[36:37]
	v_pk_add_f32 v[232:233], v[232:233], v[38:39]
	v_pk_add_f32 v[232:233], v[232:233], v[40:41]
	v_pk_add_f32 v[232:233], v[232:233], v[42:43]
	v_pk_add_f32 v[232:233], v[232:233], v[44:45]
	v_pk_add_f32 v[232:233], v[232:233], v[46:47]
	s_waitcnt lgkmcnt(12)
	v_mfma_f32_32x32x16_bf16 v[0:15], v[64:67], v[72:75], v[0:15]
	v_mfma_f32_32x32x16_bf16 v[16:31], v[64:67], v[76:79], v[16:31]
	v_mfma_f32_32x32x16_bf16 v[0:15], v[68:71], v[220:223], v[0:15]
	v_mfma_f32_32x32x16_bf16 v[16:31], v[68:71], v[224:227], v[16:31]
	s_add_i32 s90, s67, -1024
	v_add_u32_e32 v80, s90, v243
	v_add_u32_e32 v83, s90, v244
	v_add_u32_e32 v99, s90, v245
	v_add_u32_e32 v253, s90, v246
	v_add_u32_e32 v254, s90, v148
	v_add_u32_e32 v255, s90, v151
	v_med3_i32 v80, v80, 0, s99
	v_med3_i32 v83, v83, 0, s99
	v_med3_i32 v99, v99, 0, s99
	v_med3_i32 v253, v253, 0, s99
	v_med3_i32 v254, v254, 0, s99
	v_med3_i32 v255, v255, 0, s99
	v_mad_u32_u24 v80, v80, s100, v252
	v_mad_u32_u24 v83, v83, s100, v252
	v_mad_u32_u24 v99, v99, s100, v252
	v_mad_u32_u24 v253, v253, s100, v252
	v_mad_u32_u24 v254, v254, s100, v153
	v_mad_u32_u24 v255, v255, s100, v153
	global_load_dwordx4 v[156:159], v80, s[82:83]
	global_load_dwordx4 v[160:163], v83, s[82:83]
	global_load_dwordx4 v[164:167], v99, s[82:83]
	global_load_dwordx4 v[168:171], v253, s[82:83]
	global_load_dwordx4 v[172:175], v254, s[82:83] offset:768
	global_load_dwordx4 v[176:179], v255, s[82:83] offset:768
	global_load_dwordx4 v[180:183], v254, s[82:83] offset:832
	global_load_dwordx4 v[184:187], v255, s[82:83] offset:832
	ds_read2_b32 v[32:33], v115 offset0:192 offset1:193
	ds_read2_b32 v[34:35], v115 offset0:194 offset1:195
	ds_read2_b32 v[36:37], v115 offset0:200 offset1:201
	ds_read2_b32 v[38:39], v115 offset0:202 offset1:203
	ds_read2_b32 v[40:41], v115 offset0:208 offset1:209
	ds_read2_b32 v[42:43], v115 offset0:210 offset1:211
	ds_read2_b32 v[44:45], v115 offset0:216 offset1:217
	ds_read2_b32 v[46:47], v115 offset0:218 offset1:219
	s_waitcnt lgkmcnt(0)
	v_mfma_f32_32x32x16_bf16 v[32:47], v[188:191], v[48:51], v[32:47]
	ds_read_b64_tr_b16 v[72:73], v231
	ds_read_b64_tr_b16 v[74:75], v231 offset:512
	ds_read_b64_tr_b16 v[76:77], v231 offset:2048
	ds_read_b64_tr_b16 v[78:79], v231 offset:2560
	ds_read_b64_tr_b16 v[220:221], v231 offset:1024
	ds_read_b64_tr_b16 v[222:223], v231 offset:1536
	ds_read_b64_tr_b16 v[224:225], v231 offset:3072
	ds_read_b64_tr_b16 v[226:227], v231 offset:3584
	s_waitcnt vmcnt(8)
	ds_write_b128 v247, v[116:119]
	ds_write_b128 v247, v[120:123] offset:1024
	ds_write_b128 v247, v[124:127] offset:2048
	ds_write_b128 v247, v[128:131] offset:3072
	ds_read_b128 v[116:119], v248
	ds_read_b128 v[120:123], v249
	ds_read_b128 v[124:127], v250
	ds_read_b128 v[128:131], v251
	ds_write_b128 v112, v[132:135]
	ds_write_b128 v112, v[136:139] offset:1024
	ds_write_b128 v112, v[140:143] offset:2048
	ds_write_b128 v112, v[144:147] offset:3072
	v_mfma_f32_32x32x16_bf16 v[32:47], v[192:195], v[52:55], v[32:47]
	v_mfma_f32_32x32x16_bf16 v[32:47], v[196:199], v[56:59], v[32:47]
	v_mfma_f32_32x32x16_bf16 v[32:47], v[200:203], v[60:63], v[32:47]
	s_nop 11
	v_exp_f32_e32 v32, v32
	v_exp_f32_e32 v33, v33
	v_exp_f32_e32 v34, v34
	v_exp_f32_e32 v35, v35
	v_exp_f32_e32 v36, v36
	v_exp_f32_e32 v37, v37
	v_exp_f32_e32 v38, v38
	v_exp_f32_e32 v39, v39
	v_exp_f32_e32 v40, v40
	v_exp_f32_e32 v41, v41
	v_exp_f32_e32 v42, v42
	v_exp_f32_e32 v43, v43
	v_exp_f32_e32 v44, v44
	v_exp_f32_e32 v45, v45
	v_exp_f32_e32 v46, v46
	v_exp_f32_e32 v47, v47
	s_add_i32 s90, s67, 512
	v_lshlrev_b32_e32 v84, 2, v107
	v_add_u32_e32 v84, s90, v84
	v_add_u32_e32 v85, 0, v84
	v_add_u32_e32 v86, 4, v84
	v_add_u32_e32 v87, 8, v84
	v_add_u32_e32 v88, 12, v84
	v_cmp_gt_u32_e64 s[30:31], s98, v85
	v_cmp_gt_u32_e64 s[36:37], s98, v86
	v_cmp_gt_u32_e64 s[78:79], s98, v87
	v_cmp_gt_u32_e64 s[50:51], s98, v88
	v_cndmask_b32_e64 v32, 0, v32, s[30:31]
	v_add_u32_e32 v85, 32, v84
	v_cmp_gt_u32_e64 s[30:31], s98, v85
	v_cndmask_b32_e64 v33, 0, v33, s[36:37]
	v_add_u32_e32 v86, 36, v84
	v_cmp_gt_u32_e64 s[36:37], s98, v86
	v_cndmask_b32_e64 v34, 0, v34, s[78:79]
	v_add_u32_e32 v87, 40, v84
	v_cmp_gt_u32_e64 s[78:79], s98, v87
	v_cndmask_b32_e64 v35, 0, v35, s[50:51]
	v_add_u32_e32 v88, 44, v84
	v_cmp_gt_u32_e64 s[50:51], s98, v88
	v_cndmask_b32_e64 v36, 0, v36, s[30:31]
	v_add_u32_e32 v85, 64, v84
	v_cmp_gt_u32_e64 s[30:31], s98, v85
	v_cndmask_b32_e64 v37, 0, v37, s[36:37]
	v_add_u32_e32 v86, 68, v84
	v_cmp_gt_u32_e64 s[36:37], s98, v86
	v_cndmask_b32_e64 v38, 0, v38, s[78:79]
	v_add_u32_e32 v87, 72, v84
	v_cmp_gt_u32_e64 s[78:79], s98, v87
	v_cndmask_b32_e64 v39, 0, v39, s[50:51]
	v_add_u32_e32 v88, 76, v84
	v_cmp_gt_u32_e64 s[50:51], s98, v88
	v_cndmask_b32_e64 v40, 0, v40, s[30:31]
	v_add_u32_e32 v85, 96, v84
	v_cmp_gt_u32_e64 s[30:31], s98, v85
	v_cndmask_b32_e64 v41, 0, v41, s[36:37]
	v_add_u32_e32 v86, 100, v84
	v_cmp_gt_u32_e64 s[36:37], s98, v86
	v_cndmask_b32_e64 v42, 0, v42, s[78:79]
	v_add_u32_e32 v87, 104, v84
	v_cmp_gt_u32_e64 s[78:79], s98, v87
	v_cndmask_b32_e64 v43, 0, v43, s[50:51]
	v_add_u32_e32 v88, 108, v84
	v_cmp_gt_u32_e64 s[50:51], s98, v88
	v_nop
	v_cndmask_b32_e64 v44, 0, v44, s[30:31]
	v_cndmask_b32_e64 v45, 0, v45, s[36:37]
	v_cndmask_b32_e64 v46, 0, v46, s[78:79]
	v_cndmask_b32_e64 v47, 0, v47, s[50:51]
	v_cvt_pk_bf16_f32 v64, v32, v33
	v_cvt_pk_bf16_f32 v65, v34, v35
	v_cvt_pk_bf16_f32 v66, v36, v37
	v_cvt_pk_bf16_f32 v67, v38, v39
	v_cvt_pk_bf16_f32 v68, v40, v41
	v_cvt_pk_bf16_f32 v69, v42, v43
	v_cvt_pk_bf16_f32 v70, v44, v45
	v_cvt_pk_bf16_f32 v71, v46, v47
	v_pk_add_f32 v[232:233], v[232:233], v[32:33]
	v_pk_add_f32 v[232:233], v[232:233], v[34:35]
	v_pk_add_f32 v[232:233], v[232:233], v[36:37]
	v_pk_add_f32 v[232:233], v[232:233], v[38:39]
	v_pk_add_f32 v[232:233], v[232:233], v[40:41]
	v_pk_add_f32 v[232:233], v[232:233], v[42:43]
	v_pk_add_f32 v[232:233], v[232:233], v[44:45]
	v_pk_add_f32 v[232:233], v[232:233], v[46:47]
	s_waitcnt lgkmcnt(12)
	v_mfma_f32_32x32x16_bf16 v[0:15], v[64:67], v[72:75], v[0:15]
	v_mfma_f32_32x32x16_bf16 v[16:31], v[64:67], v[76:79], v[16:31]
	v_mfma_f32_32x32x16_bf16 v[0:15], v[68:71], v[220:223], v[0:15]
	v_mfma_f32_32x32x16_bf16 v[16:31], v[68:71], v[224:227], v[16:31]
	s_add_i32 s90, s67, -512
	v_add_u32_e32 v80, s90, v243
	v_add_u32_e32 v83, s90, v244
	v_add_u32_e32 v99, s90, v245
	v_add_u32_e32 v253, s90, v246
	v_add_u32_e32 v254, s90, v148
	v_add_u32_e32 v255, s90, v151
	v_med3_i32 v80, v80, 0, s99
	v_med3_i32 v83, v83, 0, s99
	v_med3_i32 v99, v99, 0, s99
	v_med3_i32 v253, v253, 0, s99
	v_med3_i32 v254, v254, 0, s99
	v_med3_i32 v255, v255, 0, s99
	v_mad_u32_u24 v80, v80, s100, v252
	v_mad_u32_u24 v83, v83, s100, v252
	v_mad_u32_u24 v99, v99, s100, v252
	v_mad_u32_u24 v253, v253, s100, v252
	v_mad_u32_u24 v254, v254, s100, v153
	v_mad_u32_u24 v255, v255, s100, v153
	global_load_dwordx4 v[188:191], v80, s[82:83]
	global_load_dwordx4 v[192:195], v83, s[82:83]
	global_load_dwordx4 v[196:199], v99, s[82:83]
	global_load_dwordx4 v[200:203], v253, s[82:83]
	global_load_dwordx4 v[204:207], v254, s[82:83] offset:768
	global_load_dwordx4 v[208:211], v255, s[82:83] offset:768
	global_load_dwordx4 v[212:215], v254, s[82:83] offset:832
	global_load_dwordx4 v[216:219], v255, s[82:83] offset:832
	ds_read2_b32 v[32:33], v115 offset0:224 offset1:225
	ds_read2_b32 v[34:35], v115 offset0:226 offset1:227
	ds_read2_b32 v[36:37], v115 offset0:232 offset1:233
	ds_read2_b32 v[38:39], v115 offset0:234 offset1:235
	ds_read2_b32 v[40:41], v115 offset0:240 offset1:241
	ds_read2_b32 v[42:43], v115 offset0:242 offset1:243
	ds_read2_b32 v[44:45], v115 offset0:248 offset1:249
	ds_read2_b32 v[46:47], v115 offset0:250 offset1:251
	s_waitcnt lgkmcnt(0)
	v_mfma_f32_32x32x16_bf16 v[32:47], v[116:119], v[48:51], v[32:47]
	ds_read_b64_tr_b16 v[72:73], v231
	ds_read_b64_tr_b16 v[74:75], v231 offset:512
	ds_read_b64_tr_b16 v[76:77], v231 offset:2048
	ds_read_b64_tr_b16 v[78:79], v231 offset:2560
	ds_read_b64_tr_b16 v[220:221], v231 offset:1024
	ds_read_b64_tr_b16 v[222:223], v231 offset:1536
	ds_read_b64_tr_b16 v[224:225], v231 offset:3072
	ds_read_b64_tr_b16 v[226:227], v231 offset:3584
	s_waitcnt vmcnt(8)
	ds_write_b128 v247, v[156:159]
	ds_write_b128 v247, v[160:163] offset:1024
	ds_write_b128 v247, v[164:167] offset:2048
	ds_write_b128 v247, v[168:171] offset:3072
	ds_read_b128 v[156:159], v248
	ds_read_b128 v[160:163], v249
	ds_read_b128 v[164:167], v250
	ds_read_b128 v[168:171], v251
	ds_write_b128 v112, v[172:175]
	ds_write_b128 v112, v[176:179] offset:1024
	ds_write_b128 v112, v[180:183] offset:2048
	ds_write_b128 v112, v[184:187] offset:3072
	v_mfma_f32_32x32x16_bf16 v[32:47], v[120:123], v[52:55], v[32:47]
	v_mfma_f32_32x32x16_bf16 v[32:47], v[124:127], v[56:59], v[32:47]
	v_mfma_f32_32x32x16_bf16 v[32:47], v[128:131], v[60:63], v[32:47]
	s_nop 11
	v_exp_f32_e32 v32, v32
	v_exp_f32_e32 v33, v33
	v_exp_f32_e32 v34, v34
	v_exp_f32_e32 v35, v35
	v_exp_f32_e32 v36, v36
	v_exp_f32_e32 v37, v37
	v_exp_f32_e32 v38, v38
	v_exp_f32_e32 v39, v39
	v_exp_f32_e32 v40, v40
	v_exp_f32_e32 v41, v41
	v_exp_f32_e32 v42, v42
	v_exp_f32_e32 v43, v43
	v_exp_f32_e32 v44, v44
	v_exp_f32_e32 v45, v45
	v_exp_f32_e32 v46, v46
	v_exp_f32_e32 v47, v47
	s_add_i32 s90, s67, 640
	v_lshlrev_b32_e32 v84, 2, v107
	v_add_u32_e32 v84, s90, v84
	v_add_u32_e32 v85, 0, v84
	v_add_u32_e32 v86, 4, v84
	v_add_u32_e32 v87, 8, v84
	v_add_u32_e32 v88, 12, v84
	v_cmp_gt_u32_e64 s[30:31], s98, v85
	v_cmp_gt_u32_e64 s[36:37], s98, v86
	v_cmp_gt_u32_e64 s[78:79], s98, v87
	v_cmp_gt_u32_e64 s[50:51], s98, v88
	v_cndmask_b32_e64 v32, 0, v32, s[30:31]
	v_add_u32_e32 v85, 32, v84
	v_cmp_gt_u32_e64 s[30:31], s98, v85
	v_cndmask_b32_e64 v33, 0, v33, s[36:37]
	v_add_u32_e32 v86, 36, v84
	v_cmp_gt_u32_e64 s[36:37], s98, v86
	v_cndmask_b32_e64 v34, 0, v34, s[78:79]
	v_add_u32_e32 v87, 40, v84
	v_cmp_gt_u32_e64 s[78:79], s98, v87
	v_cndmask_b32_e64 v35, 0, v35, s[50:51]
	v_add_u32_e32 v88, 44, v84
	v_cmp_gt_u32_e64 s[50:51], s98, v88
	v_cndmask_b32_e64 v36, 0, v36, s[30:31]
	v_add_u32_e32 v85, 64, v84
	v_cmp_gt_u32_e64 s[30:31], s98, v85
	v_cndmask_b32_e64 v37, 0, v37, s[36:37]
	v_add_u32_e32 v86, 68, v84
	v_cmp_gt_u32_e64 s[36:37], s98, v86
	v_cndmask_b32_e64 v38, 0, v38, s[78:79]
	v_add_u32_e32 v87, 72, v84
	v_cmp_gt_u32_e64 s[78:79], s98, v87
	v_cndmask_b32_e64 v39, 0, v39, s[50:51]
	v_add_u32_e32 v88, 76, v84
	v_cmp_gt_u32_e64 s[50:51], s98, v88
	v_cndmask_b32_e64 v40, 0, v40, s[30:31]
	v_add_u32_e32 v85, 96, v84
	v_cmp_gt_u32_e64 s[30:31], s98, v85
	v_cndmask_b32_e64 v41, 0, v41, s[36:37]
	v_add_u32_e32 v86, 100, v84
	v_cmp_gt_u32_e64 s[36:37], s98, v86
	v_cndmask_b32_e64 v42, 0, v42, s[78:79]
	v_add_u32_e32 v87, 104, v84
	v_cmp_gt_u32_e64 s[78:79], s98, v87
	v_cndmask_b32_e64 v43, 0, v43, s[50:51]
	v_add_u32_e32 v88, 108, v84
	v_cmp_gt_u32_e64 s[50:51], s98, v88
	v_nop
	v_cndmask_b32_e64 v44, 0, v44, s[30:31]
	v_cndmask_b32_e64 v45, 0, v45, s[36:37]
	v_cndmask_b32_e64 v46, 0, v46, s[78:79]
	v_cndmask_b32_e64 v47, 0, v47, s[50:51]
	v_cvt_pk_bf16_f32 v64, v32, v33
	v_cvt_pk_bf16_f32 v65, v34, v35
	v_cvt_pk_bf16_f32 v66, v36, v37
	v_cvt_pk_bf16_f32 v67, v38, v39
	v_cvt_pk_bf16_f32 v68, v40, v41
	v_cvt_pk_bf16_f32 v69, v42, v43
	v_cvt_pk_bf16_f32 v70, v44, v45
	v_cvt_pk_bf16_f32 v71, v46, v47
	v_pk_add_f32 v[232:233], v[232:233], v[32:33]
	v_pk_add_f32 v[232:233], v[232:233], v[34:35]
	v_pk_add_f32 v[232:233], v[232:233], v[36:37]
	v_pk_add_f32 v[232:233], v[232:233], v[38:39]
	v_pk_add_f32 v[232:233], v[232:233], v[40:41]
	v_pk_add_f32 v[232:233], v[232:233], v[42:43]
	v_pk_add_f32 v[232:233], v[232:233], v[44:45]
	v_pk_add_f32 v[232:233], v[232:233], v[46:47]
	s_waitcnt lgkmcnt(12)
	v_mfma_f32_32x32x16_bf16 v[0:15], v[64:67], v[72:75], v[0:15]
	v_mfma_f32_32x32x16_bf16 v[16:31], v[64:67], v[76:79], v[16:31]
	v_mfma_f32_32x32x16_bf16 v[0:15], v[68:71], v[220:223], v[0:15]
	v_mfma_f32_32x32x16_bf16 v[16:31], v[68:71], v[224:227], v[16:31]
	s_add_i32 s90, s67, 0
	v_add_u32_e32 v80, s90, v243
	v_add_u32_e32 v83, s90, v244
	v_add_u32_e32 v99, s90, v245
	v_add_u32_e32 v253, s90, v246
	v_add_u32_e32 v254, s90, v148
	v_add_u32_e32 v255, s90, v151
	v_med3_i32 v80, v80, 0, s99
	v_med3_i32 v83, v83, 0, s99
	v_med3_i32 v99, v99, 0, s99
	v_med3_i32 v253, v253, 0, s99
	v_med3_i32 v254, v254, 0, s99
	v_med3_i32 v255, v255, 0, s99
	v_mad_u32_u24 v80, v80, s100, v252
	v_mad_u32_u24 v83, v83, s100, v252
	v_mad_u32_u24 v99, v99, s100, v252
	v_mad_u32_u24 v253, v253, s100, v252
	v_mad_u32_u24 v254, v254, s100, v153
	v_mad_u32_u24 v255, v255, s100, v153
	global_load_dwordx4 v[116:119], v80, s[82:83]
	global_load_dwordx4 v[120:123], v83, s[82:83]
	global_load_dwordx4 v[124:127], v99, s[82:83]
	global_load_dwordx4 v[128:131], v253, s[82:83]
	global_load_dwordx4 v[132:135], v254, s[82:83] offset:768
	global_load_dwordx4 v[136:139], v255, s[82:83] offset:768
	global_load_dwordx4 v[140:143], v254, s[82:83] offset:832
	global_load_dwordx4 v[144:147], v255, s[82:83] offset:832
	v_mov_b32_e32 v115, v230
	ds_read2_b32 v[32:33], v115 offset0:0 offset1:1
	ds_read2_b32 v[34:35], v115 offset0:2 offset1:3
	ds_read2_b32 v[36:37], v115 offset0:8 offset1:9
	ds_read2_b32 v[38:39], v115 offset0:10 offset1:11
	ds_read2_b32 v[40:41], v115 offset0:16 offset1:17
	ds_read2_b32 v[42:43], v115 offset0:18 offset1:19
	ds_read2_b32 v[44:45], v115 offset0:24 offset1:25
	ds_read2_b32 v[46:47], v115 offset0:26 offset1:27
	s_waitcnt lgkmcnt(0)
	v_mfma_f32_32x32x16_bf16 v[32:47], v[156:159], v[48:51], v[32:47]
	ds_read_b64_tr_b16 v[72:73], v231
	ds_read_b64_tr_b16 v[74:75], v231 offset:512
	ds_read_b64_tr_b16 v[76:77], v231 offset:2048
	ds_read_b64_tr_b16 v[78:79], v231 offset:2560
	ds_read_b64_tr_b16 v[220:221], v231 offset:1024
	ds_read_b64_tr_b16 v[222:223], v231 offset:1536
	ds_read_b64_tr_b16 v[224:225], v231 offset:3072
	ds_read_b64_tr_b16 v[226:227], v231 offset:3584
	s_waitcnt vmcnt(8)
	ds_write_b128 v247, v[188:191]
	ds_write_b128 v247, v[192:195] offset:1024
	ds_write_b128 v247, v[196:199] offset:2048
	ds_write_b128 v247, v[200:203] offset:3072
	ds_read_b128 v[188:191], v248
	ds_read_b128 v[192:195], v249
	ds_read_b128 v[196:199], v250
	ds_read_b128 v[200:203], v251
	ds_write_b128 v112, v[204:207]
	ds_write_b128 v112, v[208:211] offset:1024
	ds_write_b128 v112, v[212:215] offset:2048
	ds_write_b128 v112, v[216:219] offset:3072
	v_mfma_f32_32x32x16_bf16 v[32:47], v[160:163], v[52:55], v[32:47]
	v_mfma_f32_32x32x16_bf16 v[32:47], v[164:167], v[56:59], v[32:47]
	v_mfma_f32_32x32x16_bf16 v[32:47], v[168:171], v[60:63], v[32:47]
	s_nop 11
	v_exp_f32_e32 v32, v32
	v_exp_f32_e32 v33, v33
	v_exp_f32_e32 v34, v34
	v_exp_f32_e32 v35, v35
	v_exp_f32_e32 v36, v36
	v_exp_f32_e32 v37, v37
	v_exp_f32_e32 v38, v38
	v_exp_f32_e32 v39, v39
	v_exp_f32_e32 v40, v40
	v_exp_f32_e32 v41, v41
	v_exp_f32_e32 v42, v42
	v_exp_f32_e32 v43, v43
	v_exp_f32_e32 v44, v44
	v_exp_f32_e32 v45, v45
	v_exp_f32_e32 v46, v46
	v_exp_f32_e32 v47, v47
	s_add_i32 s90, s67, -1024
	v_lshlrev_b32_e32 v84, 4, v107
	v_add_u32_e32 v84, s90, v84
	v_add_u32_e32 v85, 0, v84
	v_add_u32_e32 v86, 16, v84
	v_add_u32_e32 v87, 32, v84
	v_add_u32_e32 v88, 48, v84
	v_cmp_gt_u32_e64 s[30:31], s98, v85
	v_cmp_gt_u32_e64 s[36:37], s98, v86
	v_cmp_gt_u32_e64 s[78:79], s98, v87
	v_cmp_gt_u32_e64 s[50:51], s98, v88
	v_cndmask_b32_e64 v32, 0, v32, s[30:31]
	v_add_u32_e32 v85, 128, v84
	v_cmp_gt_u32_e64 s[30:31], s98, v85
	v_cndmask_b32_e64 v33, 0, v33, s[36:37]
	v_add_u32_e32 v86, 144, v84
	v_cmp_gt_u32_e64 s[36:37], s98, v86
	v_cndmask_b32_e64 v34, 0, v34, s[78:79]
	v_add_u32_e32 v87, 160, v84
	v_cmp_gt_u32_e64 s[78:79], s98, v87
	v_cndmask_b32_e64 v35, 0, v35, s[50:51]
	v_add_u32_e32 v88, 176, v84
	v_cmp_gt_u32_e64 s[50:51], s98, v88
	v_cndmask_b32_e64 v36, 0, v36, s[30:31]
	v_add_u32_e32 v85, 256, v84
	v_cmp_gt_u32_e64 s[30:31], s98, v85
	v_cndmask_b32_e64 v37, 0, v37, s[36:37]
	v_add_u32_e32 v86, 272, v84
	v_cmp_gt_u32_e64 s[36:37], s98, v86
	v_cndmask_b32_e64 v38, 0, v38, s[78:79]
	v_add_u32_e32 v87, 288, v84
	v_cmp_gt_u32_e64 s[78:79], s98, v87
	v_cndmask_b32_e64 v39, 0, v39, s[50:51]
	v_add_u32_e32 v88, 304, v84
	v_cmp_gt_u32_e64 s[50:51], s98, v88
	v_cndmask_b32_e64 v40, 0, v40, s[30:31]
	v_add_u32_e32 v85, 384, v84
	v_cmp_gt_u32_e64 s[30:31], s98, v85
	v_cndmask_b32_e64 v41, 0, v41, s[36:37]
	v_add_u32_e32 v86, 400, v84
	v_cmp_gt_u32_e64 s[36:37], s98, v86
	v_cndmask_b32_e64 v42, 0, v42, s[78:79]
	v_add_u32_e32 v87, 416, v84
	v_cmp_gt_u32_e64 s[78:79], s98, v87
	v_cndmask_b32_e64 v43, 0, v43, s[50:51]
	v_add_u32_e32 v88, 432, v84
	v_cmp_gt_u32_e64 s[50:51], s98, v88
	v_nop
	v_cndmask_b32_e64 v44, 0, v44, s[30:31]
	v_cndmask_b32_e64 v45, 0, v45, s[36:37]
	v_cndmask_b32_e64 v46, 0, v46, s[78:79]
	v_cndmask_b32_e64 v47, 0, v47, s[50:51]
	v_cvt_pk_bf16_f32 v64, v32, v33
	v_cvt_pk_bf16_f32 v65, v34, v35
	v_cvt_pk_bf16_f32 v66, v36, v37
	v_cvt_pk_bf16_f32 v67, v38, v39
	v_cvt_pk_bf16_f32 v68, v40, v41
	v_cvt_pk_bf16_f32 v69, v42, v43
	v_cvt_pk_bf16_f32 v70, v44, v45
	v_cvt_pk_bf16_f32 v71, v46, v47
	v_pk_add_f32 v[232:233], v[232:233], v[32:33]
	v_pk_add_f32 v[232:233], v[232:233], v[34:35]
	v_pk_add_f32 v[232:233], v[232:233], v[36:37]
	v_pk_add_f32 v[232:233], v[232:233], v[38:39]
	v_pk_add_f32 v[232:233], v[232:233], v[40:41]
	v_pk_add_f32 v[232:233], v[232:233], v[42:43]
	v_pk_add_f32 v[232:233], v[232:233], v[44:45]
	v_pk_add_f32 v[232:233], v[232:233], v[46:47]
	s_waitcnt lgkmcnt(12)
	v_mfma_f32_32x32x16_bf16 v[0:15], v[64:67], v[72:75], v[0:15]
	v_mfma_f32_32x32x16_bf16 v[16:31], v[64:67], v[76:79], v[16:31]
	v_mfma_f32_32x32x16_bf16 v[0:15], v[68:71], v[220:223], v[0:15]
	v_mfma_f32_32x32x16_bf16 v[16:31], v[68:71], v[224:227], v[16:31]
	s_add_i32 s90, s67, 512
	v_add_u32_e32 v80, s90, v243
	v_add_u32_e32 v83, s90, v244
	v_add_u32_e32 v99, s90, v245
	v_add_u32_e32 v253, s90, v246
	v_add_u32_e32 v254, s90, v148
	v_add_u32_e32 v255, s90, v151
	v_med3_i32 v80, v80, 0, s99
	v_med3_i32 v83, v83, 0, s99
	v_med3_i32 v99, v99, 0, s99
	v_med3_i32 v253, v253, 0, s99
	v_med3_i32 v254, v254, 0, s99
	v_med3_i32 v255, v255, 0, s99
	v_mad_u32_u24 v80, v80, s100, v252
	v_mad_u32_u24 v83, v83, s100, v252
	v_mad_u32_u24 v99, v99, s100, v252
	v_mad_u32_u24 v253, v253, s100, v252
	v_mad_u32_u24 v254, v254, s100, v153
	v_mad_u32_u24 v255, v255, s100, v153
	global_load_dwordx4 v[156:159], v80, s[82:83]
	global_load_dwordx4 v[160:163], v83, s[82:83]
	global_load_dwordx4 v[164:167], v99, s[82:83]
	global_load_dwordx4 v[168:171], v253, s[82:83]
	global_load_dwordx4 v[172:175], v254, s[82:83] offset:768
	global_load_dwordx4 v[176:179], v255, s[82:83] offset:768
	global_load_dwordx4 v[180:183], v254, s[82:83] offset:832
	global_load_dwordx4 v[184:187], v255, s[82:83] offset:832
	ds_read2_b32 v[32:33], v115 offset0:32 offset1:33
	ds_read2_b32 v[34:35], v115 offset0:34 offset1:35
	ds_read2_b32 v[36:37], v115 offset0:40 offset1:41
	ds_read2_b32 v[38:39], v115 offset0:42 offset1:43
	ds_read2_b32 v[40:41], v115 offset0:48 offset1:49
	ds_read2_b32 v[42:43], v115 offset0:50 offset1:51
	ds_read2_b32 v[44:45], v115 offset0:56 offset1:57
	ds_read2_b32 v[46:47], v115 offset0:58 offset1:59
	s_waitcnt lgkmcnt(0)
	v_mfma_f32_32x32x16_bf16 v[32:47], v[188:191], v[48:51], v[32:47]
	ds_read_b64_tr_b16 v[72:73], v231
	ds_read_b64_tr_b16 v[74:75], v231 offset:512
	ds_read_b64_tr_b16 v[76:77], v231 offset:2048
	ds_read_b64_tr_b16 v[78:79], v231 offset:2560
	ds_read_b64_tr_b16 v[220:221], v231 offset:1024
	ds_read_b64_tr_b16 v[222:223], v231 offset:1536
	ds_read_b64_tr_b16 v[224:225], v231 offset:3072
	ds_read_b64_tr_b16 v[226:227], v231 offset:3584
	s_waitcnt vmcnt(8)
	ds_write_b128 v247, v[116:119]
	ds_write_b128 v247, v[120:123] offset:1024
	ds_write_b128 v247, v[124:127] offset:2048
	ds_write_b128 v247, v[128:131] offset:3072
	ds_read_b128 v[116:119], v248
	ds_read_b128 v[120:123], v249
	ds_read_b128 v[124:127], v250
	ds_read_b128 v[128:131], v251
	ds_write_b128 v112, v[132:135]
	ds_write_b128 v112, v[136:139] offset:1024
	ds_write_b128 v112, v[140:143] offset:2048
	ds_write_b128 v112, v[144:147] offset:3072
	v_mfma_f32_32x32x16_bf16 v[32:47], v[192:195], v[52:55], v[32:47]
	v_mfma_f32_32x32x16_bf16 v[32:47], v[196:199], v[56:59], v[32:47]
	v_mfma_f32_32x32x16_bf16 v[32:47], v[200:203], v[60:63], v[32:47]
	s_nop 11
	v_exp_f32_e32 v32, v32
	v_exp_f32_e32 v33, v33
	v_exp_f32_e32 v34, v34
	v_exp_f32_e32 v35, v35
	v_exp_f32_e32 v36, v36
	v_exp_f32_e32 v37, v37
	v_exp_f32_e32 v38, v38
	v_exp_f32_e32 v39, v39
	v_exp_f32_e32 v40, v40
	v_exp_f32_e32 v41, v41
	v_exp_f32_e32 v42, v42
	v_exp_f32_e32 v43, v43
	v_exp_f32_e32 v44, v44
	v_exp_f32_e32 v45, v45
	v_exp_f32_e32 v46, v46
	v_exp_f32_e32 v47, v47
	s_add_i32 s90, s67, -512
	v_lshlrev_b32_e32 v84, 4, v107
	v_add_u32_e32 v84, s90, v84
	v_add_u32_e32 v85, 0, v84
	v_add_u32_e32 v86, 16, v84
	v_add_u32_e32 v87, 32, v84
	v_add_u32_e32 v88, 48, v84
	v_cmp_gt_u32_e64 s[30:31], s98, v85
	v_cmp_gt_u32_e64 s[36:37], s98, v86
	v_cmp_gt_u32_e64 s[78:79], s98, v87
	v_cmp_gt_u32_e64 s[50:51], s98, v88
	v_cndmask_b32_e64 v32, 0, v32, s[30:31]
	v_add_u32_e32 v85, 128, v84
	v_cmp_gt_u32_e64 s[30:31], s98, v85
	v_cndmask_b32_e64 v33, 0, v33, s[36:37]
	v_add_u32_e32 v86, 144, v84
	v_cmp_gt_u32_e64 s[36:37], s98, v86
	v_cndmask_b32_e64 v34, 0, v34, s[78:79]
	v_add_u32_e32 v87, 160, v84
	v_cmp_gt_u32_e64 s[78:79], s98, v87
	v_cndmask_b32_e64 v35, 0, v35, s[50:51]
	v_add_u32_e32 v88, 176, v84
	v_cmp_gt_u32_e64 s[50:51], s98, v88
	v_cndmask_b32_e64 v36, 0, v36, s[30:31]
	v_add_u32_e32 v85, 256, v84
	v_cmp_gt_u32_e64 s[30:31], s98, v85
	v_cndmask_b32_e64 v37, 0, v37, s[36:37]
	v_add_u32_e32 v86, 272, v84
	v_cmp_gt_u32_e64 s[36:37], s98, v86
	v_cndmask_b32_e64 v38, 0, v38, s[78:79]
	v_add_u32_e32 v87, 288, v84
	v_cmp_gt_u32_e64 s[78:79], s98, v87
	v_cndmask_b32_e64 v39, 0, v39, s[50:51]
	v_add_u32_e32 v88, 304, v84
	v_cmp_gt_u32_e64 s[50:51], s98, v88
	v_cndmask_b32_e64 v40, 0, v40, s[30:31]
	v_add_u32_e32 v85, 384, v84
	v_cmp_gt_u32_e64 s[30:31], s98, v85
	v_cndmask_b32_e64 v41, 0, v41, s[36:37]
	v_add_u32_e32 v86, 400, v84
	v_cmp_gt_u32_e64 s[36:37], s98, v86
	v_cndmask_b32_e64 v42, 0, v42, s[78:79]
	v_add_u32_e32 v87, 416, v84
	v_cmp_gt_u32_e64 s[78:79], s98, v87
	v_cndmask_b32_e64 v43, 0, v43, s[50:51]
	v_add_u32_e32 v88, 432, v84
	v_cmp_gt_u32_e64 s[50:51], s98, v88
	v_nop
	v_cndmask_b32_e64 v44, 0, v44, s[30:31]
	v_cndmask_b32_e64 v45, 0, v45, s[36:37]
	v_cndmask_b32_e64 v46, 0, v46, s[78:79]
	v_cndmask_b32_e64 v47, 0, v47, s[50:51]
	v_cvt_pk_bf16_f32 v64, v32, v33
	v_cvt_pk_bf16_f32 v65, v34, v35
	v_cvt_pk_bf16_f32 v66, v36, v37
	v_cvt_pk_bf16_f32 v67, v38, v39
	v_cvt_pk_bf16_f32 v68, v40, v41
	v_cvt_pk_bf16_f32 v69, v42, v43
	v_cvt_pk_bf16_f32 v70, v44, v45
	v_cvt_pk_bf16_f32 v71, v46, v47
	v_pk_add_f32 v[232:233], v[232:233], v[32:33]
	v_pk_add_f32 v[232:233], v[232:233], v[34:35]
	v_pk_add_f32 v[232:233], v[232:233], v[36:37]
	v_pk_add_f32 v[232:233], v[232:233], v[38:39]
	v_pk_add_f32 v[232:233], v[232:233], v[40:41]
	v_pk_add_f32 v[232:233], v[232:233], v[42:43]
	v_pk_add_f32 v[232:233], v[232:233], v[44:45]
	v_pk_add_f32 v[232:233], v[232:233], v[46:47]
	s_waitcnt lgkmcnt(12)
	v_mfma_f32_32x32x16_bf16 v[0:15], v[64:67], v[72:75], v[0:15]
	v_mfma_f32_32x32x16_bf16 v[16:31], v[64:67], v[76:79], v[16:31]
	v_mfma_f32_32x32x16_bf16 v[0:15], v[68:71], v[220:223], v[0:15]
	v_mfma_f32_32x32x16_bf16 v[16:31], v[68:71], v[224:227], v[16:31]
	s_add_i32 s90, s67, 1024
	v_add_u32_e32 v80, s90, v243
	v_add_u32_e32 v83, s90, v244
	v_add_u32_e32 v99, s90, v245
	v_add_u32_e32 v253, s90, v246
	v_add_u32_e32 v254, s90, v148
	v_add_u32_e32 v255, s90, v151
	v_med3_i32 v80, v80, 0, s99
	v_med3_i32 v83, v83, 0, s99
	v_med3_i32 v99, v99, 0, s99
	v_med3_i32 v253, v253, 0, s99
	v_med3_i32 v254, v254, 0, s99
	v_med3_i32 v255, v255, 0, s99
	v_mad_u32_u24 v80, v80, s100, v252
	v_mad_u32_u24 v83, v83, s100, v252
	v_mad_u32_u24 v99, v99, s100, v252
	v_mad_u32_u24 v253, v253, s100, v252
	v_mad_u32_u24 v254, v254, s100, v153
	v_mad_u32_u24 v255, v255, s100, v153
	global_load_dwordx4 v[188:191], v80, s[82:83]
	global_load_dwordx4 v[192:195], v83, s[82:83]
	global_load_dwordx4 v[196:199], v99, s[82:83]
	global_load_dwordx4 v[200:203], v253, s[82:83]
	global_load_dwordx4 v[204:207], v254, s[82:83] offset:768
	global_load_dwordx4 v[208:211], v255, s[82:83] offset:768
	global_load_dwordx4 v[212:215], v254, s[82:83] offset:832
	global_load_dwordx4 v[216:219], v255, s[82:83] offset:832
	ds_read2_b32 v[32:33], v115 offset0:64 offset1:65
	ds_read2_b32 v[34:35], v115 offset0:66 offset1:67
	ds_read2_b32 v[36:37], v115 offset0:72 offset1:73
	ds_read2_b32 v[38:39], v115 offset0:74 offset1:75
	ds_read2_b32 v[40:41], v115 offset0:80 offset1:81
	ds_read2_b32 v[42:43], v115 offset0:82 offset1:83
	ds_read2_b32 v[44:45], v115 offset0:88 offset1:89
	ds_read2_b32 v[46:47], v115 offset0:90 offset1:91
	s_waitcnt lgkmcnt(0)
	v_mfma_f32_32x32x16_bf16 v[32:47], v[116:119], v[48:51], v[32:47]
	ds_read_b64_tr_b16 v[72:73], v231
	ds_read_b64_tr_b16 v[74:75], v231 offset:512
	ds_read_b64_tr_b16 v[76:77], v231 offset:2048
	ds_read_b64_tr_b16 v[78:79], v231 offset:2560
	ds_read_b64_tr_b16 v[220:221], v231 offset:1024
	ds_read_b64_tr_b16 v[222:223], v231 offset:1536
	ds_read_b64_tr_b16 v[224:225], v231 offset:3072
	ds_read_b64_tr_b16 v[226:227], v231 offset:3584
	s_waitcnt vmcnt(8)
	ds_write_b128 v247, v[156:159]
	ds_write_b128 v247, v[160:163] offset:1024
	ds_write_b128 v247, v[164:167] offset:2048
	ds_write_b128 v247, v[168:171] offset:3072
	ds_read_b128 v[156:159], v248
	ds_read_b128 v[160:163], v249
	ds_read_b128 v[164:167], v250
	ds_read_b128 v[168:171], v251
	ds_write_b128 v112, v[172:175]
	ds_write_b128 v112, v[176:179] offset:1024
	ds_write_b128 v112, v[180:183] offset:2048
	ds_write_b128 v112, v[184:187] offset:3072
	v_mfma_f32_32x32x16_bf16 v[32:47], v[120:123], v[52:55], v[32:47]
	v_mfma_f32_32x32x16_bf16 v[32:47], v[124:127], v[56:59], v[32:47]
	v_mfma_f32_32x32x16_bf16 v[32:47], v[128:131], v[60:63], v[32:47]
	s_nop 11
	v_exp_f32_e32 v32, v32
	v_exp_f32_e32 v33, v33
	v_exp_f32_e32 v34, v34
	v_exp_f32_e32 v35, v35
	v_exp_f32_e32 v36, v36
	v_exp_f32_e32 v37, v37
	v_exp_f32_e32 v38, v38
	v_exp_f32_e32 v39, v39
	v_exp_f32_e32 v40, v40
	v_exp_f32_e32 v41, v41
	v_exp_f32_e32 v42, v42
	v_exp_f32_e32 v43, v43
	v_exp_f32_e32 v44, v44
	v_exp_f32_e32 v45, v45
	v_exp_f32_e32 v46, v46
	v_exp_f32_e32 v47, v47
	s_add_i32 s90, s67, 0
	v_lshlrev_b32_e32 v84, 4, v107
	v_add_u32_e32 v84, s90, v84
	v_add_u32_e32 v85, 0, v84
	v_add_u32_e32 v86, 16, v84
	v_add_u32_e32 v87, 32, v84
	v_add_u32_e32 v88, 48, v84
	v_cmp_gt_u32_e64 s[30:31], s98, v85
	v_cmp_gt_u32_e64 s[36:37], s98, v86
	v_cmp_gt_u32_e64 s[78:79], s98, v87
	v_cmp_gt_u32_e64 s[50:51], s98, v88
	v_cndmask_b32_e64 v32, 0, v32, s[30:31]
	v_add_u32_e32 v85, 128, v84
	v_cmp_gt_u32_e64 s[30:31], s98, v85
	v_cndmask_b32_e64 v33, 0, v33, s[36:37]
	v_add_u32_e32 v86, 144, v84
	v_cmp_gt_u32_e64 s[36:37], s98, v86
	v_cndmask_b32_e64 v34, 0, v34, s[78:79]
	v_add_u32_e32 v87, 160, v84
	v_cmp_gt_u32_e64 s[78:79], s98, v87
	v_cndmask_b32_e64 v35, 0, v35, s[50:51]
	v_add_u32_e32 v88, 176, v84
	v_cmp_gt_u32_e64 s[50:51], s98, v88
	v_cndmask_b32_e64 v36, 0, v36, s[30:31]
	v_add_u32_e32 v85, 256, v84
	v_cmp_gt_u32_e64 s[30:31], s98, v85
	v_cndmask_b32_e64 v37, 0, v37, s[36:37]
	v_add_u32_e32 v86, 272, v84
	v_cmp_gt_u32_e64 s[36:37], s98, v86
	v_cndmask_b32_e64 v38, 0, v38, s[78:79]
	v_add_u32_e32 v87, 288, v84
	v_cmp_gt_u32_e64 s[78:79], s98, v87
	v_cndmask_b32_e64 v39, 0, v39, s[50:51]
	v_add_u32_e32 v88, 304, v84
	v_cmp_gt_u32_e64 s[50:51], s98, v88
	v_cndmask_b32_e64 v40, 0, v40, s[30:31]
	v_add_u32_e32 v85, 384, v84
	v_cmp_gt_u32_e64 s[30:31], s98, v85
	v_cndmask_b32_e64 v41, 0, v41, s[36:37]
	v_add_u32_e32 v86, 400, v84
	v_cmp_gt_u32_e64 s[36:37], s98, v86
	v_cndmask_b32_e64 v42, 0, v42, s[78:79]
	v_add_u32_e32 v87, 416, v84
	v_cmp_gt_u32_e64 s[78:79], s98, v87
	v_cndmask_b32_e64 v43, 0, v43, s[50:51]
	v_add_u32_e32 v88, 432, v84
	v_cmp_gt_u32_e64 s[50:51], s98, v88
	v_nop
	v_cndmask_b32_e64 v44, 0, v44, s[30:31]
	v_cndmask_b32_e64 v45, 0, v45, s[36:37]
	v_cndmask_b32_e64 v46, 0, v46, s[78:79]
	v_cndmask_b32_e64 v47, 0, v47, s[50:51]
	v_cvt_pk_bf16_f32 v64, v32, v33
	v_cvt_pk_bf16_f32 v65, v34, v35
	v_cvt_pk_bf16_f32 v66, v36, v37
	v_cvt_pk_bf16_f32 v67, v38, v39
	v_cvt_pk_bf16_f32 v68, v40, v41
	v_cvt_pk_bf16_f32 v69, v42, v43
	v_cvt_pk_bf16_f32 v70, v44, v45
	v_cvt_pk_bf16_f32 v71, v46, v47
	v_pk_add_f32 v[232:233], v[232:233], v[32:33]
	v_pk_add_f32 v[232:233], v[232:233], v[34:35]
	v_pk_add_f32 v[232:233], v[232:233], v[36:37]
	v_pk_add_f32 v[232:233], v[232:233], v[38:39]
	v_pk_add_f32 v[232:233], v[232:233], v[40:41]
	v_pk_add_f32 v[232:233], v[232:233], v[42:43]
	v_pk_add_f32 v[232:233], v[232:233], v[44:45]
	v_pk_add_f32 v[232:233], v[232:233], v[46:47]
	s_waitcnt lgkmcnt(12)
	v_mfma_f32_32x32x16_bf16 v[0:15], v[64:67], v[72:75], v[0:15]
	v_mfma_f32_32x32x16_bf16 v[16:31], v[64:67], v[76:79], v[16:31]
	v_mfma_f32_32x32x16_bf16 v[0:15], v[68:71], v[220:223], v[0:15]
	v_mfma_f32_32x32x16_bf16 v[16:31], v[68:71], v[224:227], v[16:31]
	ds_read2_b32 v[32:33], v115 offset0:96 offset1:97
	ds_read2_b32 v[34:35], v115 offset0:98 offset1:99
	ds_read2_b32 v[36:37], v115 offset0:104 offset1:105
	ds_read2_b32 v[38:39], v115 offset0:106 offset1:107
	ds_read2_b32 v[40:41], v115 offset0:112 offset1:113
	ds_read2_b32 v[42:43], v115 offset0:114 offset1:115
	ds_read2_b32 v[44:45], v115 offset0:120 offset1:121
	ds_read2_b32 v[46:47], v115 offset0:122 offset1:123
	s_waitcnt lgkmcnt(0)
	v_mfma_f32_32x32x16_bf16 v[32:47], v[156:159], v[48:51], v[32:47]
	ds_read_b64_tr_b16 v[72:73], v231
	ds_read_b64_tr_b16 v[74:75], v231 offset:512
	ds_read_b64_tr_b16 v[76:77], v231 offset:2048
	ds_read_b64_tr_b16 v[78:79], v231 offset:2560
	ds_read_b64_tr_b16 v[220:221], v231 offset:1024
	ds_read_b64_tr_b16 v[222:223], v231 offset:1536
	ds_read_b64_tr_b16 v[224:225], v231 offset:3072
	ds_read_b64_tr_b16 v[226:227], v231 offset:3584
	s_waitcnt vmcnt(0)
	ds_write_b128 v247, v[188:191]
	ds_write_b128 v247, v[192:195] offset:1024
	ds_write_b128 v247, v[196:199] offset:2048
	ds_write_b128 v247, v[200:203] offset:3072
	ds_read_b128 v[188:191], v248
	ds_read_b128 v[192:195], v249
	ds_read_b128 v[196:199], v250
	ds_read_b128 v[200:203], v251
	ds_write_b128 v112, v[204:207]
	ds_write_b128 v112, v[208:211] offset:1024
	ds_write_b128 v112, v[212:215] offset:2048
	ds_write_b128 v112, v[216:219] offset:3072
	v_mfma_f32_32x32x16_bf16 v[32:47], v[160:163], v[52:55], v[32:47]
	v_mfma_f32_32x32x16_bf16 v[32:47], v[164:167], v[56:59], v[32:47]
	v_mfma_f32_32x32x16_bf16 v[32:47], v[168:171], v[60:63], v[32:47]
	s_nop 11
	v_exp_f32_e32 v32, v32
	v_exp_f32_e32 v33, v33
	v_exp_f32_e32 v34, v34
	v_exp_f32_e32 v35, v35
	v_exp_f32_e32 v36, v36
	v_exp_f32_e32 v37, v37
	v_exp_f32_e32 v38, v38
	v_exp_f32_e32 v39, v39
	v_exp_f32_e32 v40, v40
	v_exp_f32_e32 v41, v41
	v_exp_f32_e32 v42, v42
	v_exp_f32_e32 v43, v43
	v_exp_f32_e32 v44, v44
	v_exp_f32_e32 v45, v45
	v_exp_f32_e32 v46, v46
	v_exp_f32_e32 v47, v47
	s_add_i32 s90, s67, 512
	v_lshlrev_b32_e32 v84, 4, v107
	v_add_u32_e32 v84, s90, v84
	v_add_u32_e32 v85, 0, v84
	v_add_u32_e32 v86, 16, v84
	v_add_u32_e32 v87, 32, v84
	v_add_u32_e32 v88, 48, v84
	v_cmp_gt_u32_e64 s[30:31], s98, v85
	v_cmp_gt_u32_e64 s[36:37], s98, v86
	v_cmp_gt_u32_e64 s[78:79], s98, v87
	v_cmp_gt_u32_e64 s[50:51], s98, v88
	v_cndmask_b32_e64 v32, 0, v32, s[30:31]
	v_add_u32_e32 v85, 128, v84
	v_cmp_gt_u32_e64 s[30:31], s98, v85
	v_cndmask_b32_e64 v33, 0, v33, s[36:37]
	v_add_u32_e32 v86, 144, v84
	v_cmp_gt_u32_e64 s[36:37], s98, v86
	v_cndmask_b32_e64 v34, 0, v34, s[78:79]
	v_add_u32_e32 v87, 160, v84
	v_cmp_gt_u32_e64 s[78:79], s98, v87
	v_cndmask_b32_e64 v35, 0, v35, s[50:51]
	v_add_u32_e32 v88, 176, v84
	v_cmp_gt_u32_e64 s[50:51], s98, v88
	v_cndmask_b32_e64 v36, 0, v36, s[30:31]
	v_add_u32_e32 v85, 256, v84
	v_cmp_gt_u32_e64 s[30:31], s98, v85
	v_cndmask_b32_e64 v37, 0, v37, s[36:37]
	v_add_u32_e32 v86, 272, v84
	v_cmp_gt_u32_e64 s[36:37], s98, v86
	v_cndmask_b32_e64 v38, 0, v38, s[78:79]
	v_add_u32_e32 v87, 288, v84
	v_cmp_gt_u32_e64 s[78:79], s98, v87
	v_cndmask_b32_e64 v39, 0, v39, s[50:51]
	v_add_u32_e32 v88, 304, v84
	v_cmp_gt_u32_e64 s[50:51], s98, v88
	v_cndmask_b32_e64 v40, 0, v40, s[30:31]
	v_add_u32_e32 v85, 384, v84
	v_cmp_gt_u32_e64 s[30:31], s98, v85
	v_cndmask_b32_e64 v41, 0, v41, s[36:37]
	v_add_u32_e32 v86, 400, v84
	v_cmp_gt_u32_e64 s[36:37], s98, v86
	v_cndmask_b32_e64 v42, 0, v42, s[78:79]
	v_add_u32_e32 v87, 416, v84
	v_cmp_gt_u32_e64 s[78:79], s98, v87
	v_cndmask_b32_e64 v43, 0, v43, s[50:51]
	v_add_u32_e32 v88, 432, v84
	v_cmp_gt_u32_e64 s[50:51], s98, v88
	v_nop
	v_cndmask_b32_e64 v44, 0, v44, s[30:31]
	v_cndmask_b32_e64 v45, 0, v45, s[36:37]
	v_cndmask_b32_e64 v46, 0, v46, s[78:79]
	v_cndmask_b32_e64 v47, 0, v47, s[50:51]
	v_cvt_pk_bf16_f32 v64, v32, v33
	v_cvt_pk_bf16_f32 v65, v34, v35
	v_cvt_pk_bf16_f32 v66, v36, v37
	v_cvt_pk_bf16_f32 v67, v38, v39
	v_cvt_pk_bf16_f32 v68, v40, v41
	v_cvt_pk_bf16_f32 v69, v42, v43
	v_cvt_pk_bf16_f32 v70, v44, v45
	v_cvt_pk_bf16_f32 v71, v46, v47
	v_pk_add_f32 v[232:233], v[232:233], v[32:33]
	v_pk_add_f32 v[232:233], v[232:233], v[34:35]
	v_pk_add_f32 v[232:233], v[232:233], v[36:37]
	v_pk_add_f32 v[232:233], v[232:233], v[38:39]
	v_pk_add_f32 v[232:233], v[232:233], v[40:41]
	v_pk_add_f32 v[232:233], v[232:233], v[42:43]
	v_pk_add_f32 v[232:233], v[232:233], v[44:45]
	v_pk_add_f32 v[232:233], v[232:233], v[46:47]
	s_waitcnt lgkmcnt(12)
	v_mfma_f32_32x32x16_bf16 v[0:15], v[64:67], v[72:75], v[0:15]
	v_mfma_f32_32x32x16_bf16 v[16:31], v[64:67], v[76:79], v[16:31]
	v_mfma_f32_32x32x16_bf16 v[0:15], v[68:71], v[220:223], v[0:15]
	v_mfma_f32_32x32x16_bf16 v[16:31], v[68:71], v[224:227], v[16:31]
	ds_read2_b32 v[32:33], v115 offset0:128 offset1:129
	ds_read2_b32 v[34:35], v115 offset0:130 offset1:131
	ds_read2_b32 v[36:37], v115 offset0:136 offset1:137
	ds_read2_b32 v[38:39], v115 offset0:138 offset1:139
	ds_read2_b32 v[40:41], v115 offset0:144 offset1:145
	ds_read2_b32 v[42:43], v115 offset0:146 offset1:147
	ds_read2_b32 v[44:45], v115 offset0:152 offset1:153
	ds_read2_b32 v[46:47], v115 offset0:154 offset1:155
	s_waitcnt lgkmcnt(0)
; __device__ __forceinline__ int crow(int r, int hi) { return (r & 3) + 8 * (r >> 2) + 4 * hi; }
; __device__ __forceinline__ void dil_unit(LAS unsigned char* lds, bf16_t* proj, int seq, int hd, int T0, int rho) {
;     ...
;     l += __shfl_xor(l, 32);
; #pragma unroll
;     for (int rr = 0; rr < 16; ++rr) {
;         const int j = crow(rr, hi);
	v_mfma_f32_32x32x16_bf16 v[32:47], v[188:191], v[48:51], v[32:47]
	ds_read_b64_tr_b16 v[72:73], v231
	ds_read_b64_tr_b16 v[74:75], v231 offset:512
	ds_read_b64_tr_b16 v[76:77], v231 offset:2048
	ds_read_b64_tr_b16 v[78:79], v231 offset:2560
	ds_read_b64_tr_b16 v[220:221], v231 offset:1024
	ds_read_b64_tr_b16 v[222:223], v231 offset:1536
	ds_read_b64_tr_b16 v[224:225], v231 offset:3072
	ds_read_b64_tr_b16 v[226:227], v231 offset:3584
	v_mfma_f32_32x32x16_bf16 v[32:47], v[192:195], v[52:55], v[32:47]
	v_mfma_f32_32x32x16_bf16 v[32:47], v[196:199], v[56:59], v[32:47]
	v_mfma_f32_32x32x16_bf16 v[32:47], v[200:203], v[60:63], v[32:47]
	s_nop 11
	v_exp_f32_e32 v32, v32
	v_exp_f32_e32 v33, v33
	v_exp_f32_e32 v34, v34
	v_exp_f32_e32 v35, v35
	v_exp_f32_e32 v36, v36
	v_exp_f32_e32 v37, v37
	v_exp_f32_e32 v38, v38
	v_exp_f32_e32 v39, v39
	v_exp_f32_e32 v40, v40
	v_exp_f32_e32 v41, v41
	v_exp_f32_e32 v42, v42
	v_exp_f32_e32 v43, v43
	v_exp_f32_e32 v44, v44
	v_exp_f32_e32 v45, v45
	v_exp_f32_e32 v46, v46
	v_exp_f32_e32 v47, v47
	s_add_i32 s90, s67, 1024
	v_lshlrev_b32_e32 v84, 4, v107
	v_add_u32_e32 v84, s90, v84
	v_add_u32_e32 v85, 0, v84
	v_add_u32_e32 v86, 16, v84
	v_add_u32_e32 v87, 32, v84
	v_add_u32_e32 v88, 48, v84
	v_cmp_gt_u32_e64 s[30:31], s98, v85
	v_cmp_gt_u32_e64 s[36:37], s98, v86
	v_cmp_gt_u32_e64 s[78:79], s98, v87
	v_cmp_gt_u32_e64 s[50:51], s98, v88
	v_cndmask_b32_e64 v32, 0, v32, s[30:31]
	v_add_u32_e32 v85, 128, v84
	v_cmp_gt_u32_e64 s[30:31], s98, v85
	v_cndmask_b32_e64 v33, 0, v33, s[36:37]
	v_add_u32_e32 v86, 144, v84
	v_cmp_gt_u32_e64 s[36:37], s98, v86
	v_cndmask_b32_e64 v34, 0, v34, s[78:79]
	v_add_u32_e32 v87, 160, v84
	v_cmp_gt_u32_e64 s[78:79], s98, v87
	v_cndmask_b32_e64 v35, 0, v35, s[50:51]
	v_add_u32_e32 v88, 176, v84
	v_cmp_gt_u32_e64 s[50:51], s98, v88
	v_cndmask_b32_e64 v36, 0, v36, s[30:31]
	v_add_u32_e32 v85, 256, v84
	v_cmp_gt_u32_e64 s[30:31], s98, v85
	v_cndmask_b32_e64 v37, 0, v37, s[36:37]
	v_add_u32_e32 v86, 272, v84
	v_cmp_gt_u32_e64 s[36:37], s98, v86
	v_cndmask_b32_e64 v38, 0, v38, s[78:79]
	v_add_u32_e32 v87, 288, v84
	v_cmp_gt_u32_e64 s[78:79], s98, v87
	v_cndmask_b32_e64 v39, 0, v39, s[50:51]
	v_add_u32_e32 v88, 304, v84
	v_cmp_gt_u32_e64 s[50:51], s98, v88
	v_cndmask_b32_e64 v40, 0, v40, s[30:31]
	v_add_u32_e32 v85, 384, v84
	v_cmp_gt_u32_e64 s[30:31], s98, v85
	v_cndmask_b32_e64 v41, 0, v41, s[36:37]
	v_add_u32_e32 v86, 400, v84
	v_cmp_gt_u32_e64 s[36:37], s98, v86
	v_cndmask_b32_e64 v42, 0, v42, s[78:79]
	v_add_u32_e32 v87, 416, v84
	v_cmp_gt_u32_e64 s[78:79], s98, v87
	v_cndmask_b32_e64 v43, 0, v43, s[50:51]
	v_add_u32_e32 v88, 432, v84
	v_cmp_gt_u32_e64 s[50:51], s98, v88
	v_nop
	v_cndmask_b32_e64 v44, 0, v44, s[30:31]
	v_cndmask_b32_e64 v45, 0, v45, s[36:37]
	v_cndmask_b32_e64 v46, 0, v46, s[78:79]
	v_cndmask_b32_e64 v47, 0, v47, s[50:51]
	v_cvt_pk_bf16_f32 v64, v32, v33
	v_cvt_pk_bf16_f32 v65, v34, v35
	v_cvt_pk_bf16_f32 v66, v36, v37
	v_cvt_pk_bf16_f32 v67, v38, v39
	v_cvt_pk_bf16_f32 v68, v40, v41
	v_cvt_pk_bf16_f32 v69, v42, v43
	v_cvt_pk_bf16_f32 v70, v44, v45
	v_cvt_pk_bf16_f32 v71, v46, v47
	v_pk_add_f32 v[232:233], v[232:233], v[32:33]
	v_pk_add_f32 v[232:233], v[232:233], v[34:35]
	v_pk_add_f32 v[232:233], v[232:233], v[36:37]
	v_pk_add_f32 v[232:233], v[232:233], v[38:39]
	v_pk_add_f32 v[232:233], v[232:233], v[40:41]
	v_pk_add_f32 v[232:233], v[232:233], v[42:43]
	v_pk_add_f32 v[232:233], v[232:233], v[44:45]
	v_pk_add_f32 v[232:233], v[232:233], v[46:47]
	s_waitcnt lgkmcnt(0)
	v_mfma_f32_32x32x16_bf16 v[0:15], v[64:67], v[72:75], v[0:15]
	v_mfma_f32_32x32x16_bf16 v[16:31], v[64:67], v[76:79], v[16:31]
	v_mfma_f32_32x32x16_bf16 v[0:15], v[68:71], v[220:223], v[0:15]
	v_mfma_f32_32x32x16_bf16 v[16:31], v[68:71], v[224:227], v[16:31]
	v_add_f32_e32 v113, v232, v233
	v_or_b32_e32 v114, 1, v107
	v_or_b32_e32 v97, 2, v107
	v_or_b32_e32 v96, 3, v107
	v_or_b32_e32 v95, 8, v107
	v_or_b32_e32 v94, 9, v107
	v_or_b32_e32 v93, 10, v107
	v_or_b32_e32 v92, 11, v107
	v_or_b32_e32 v91, 16, v107
	v_or_b32_e32 v90, 17, v107
	v_or_b32_e32 v89, 18, v107
	v_or_b32_e32 v88, 19, v107
	v_or_b32_e32 v87, 24, v107
	v_or_b32_e32 v86, 25, v107
	v_or_b32_e32 v85, 26, v107
	v_or_b32_e32 v84, 27, v107
	s_nop 11
	s_branch .LBB0_1265
